# plus: software pipelining applied per k-step pair (8 more k-iterations near tile ends covered)
# baseline (speedup 1.0000x reference)
; template <bool trans>
; DI void gemm_core(const GTile& tl, const GTile& nx, bool has_next  , bool chain  , bool pre, u32x4 (&ra)[4], u32x4 (&rb)[4], char* smem, f32x16 (&acc)[2][4]) {
;     ...
;   const int nk = K / 64;
;   if (!pre) { G_LOAD(0); G_STORE(0); G_LOAD(1); }
;   for (int kt = 0; kt < nk; ++kt) {
;     __syncthreads();
;     G_COMPUTE(kt & 1, kt);
;   }
.LBB0_103:
	v_lshl_add_u64 v[190:191], s[0:1], 0, v[192:193]
	v_lshl_add_u64 v[188:189], s[6:7], 0, v[192:193]
	s_waitcnt lgkmcnt(0)
	s_barrier
	global_load_dwordx4 v[218:221], v[190:191], off offset:256
	global_load_dwordx4 v[222:225], v[188:189], off offset:256
	s_lshr_b32 s1, s33, 1
	s_and_b32 s0, s33, 0xc0
	v_and_b32_e32 v10, 31, v8
	s_and_b32 s1, s1, 0xfffff80
	v_or_b32_e32 v12, s1, v10
	v_or_b32_e32 v10, s0, v10
	v_add3_u32 v215, 16, v11, v9
	v_lshrrev_b32_e32 v8, 1, v8
	v_mul_u32_u24_e32 v242, 0x90, v10
	v_and_b32_e32 v243, 16, v8
	v_add_u32_e32 v209, 0x12000, v215
	v_mul_lo_u32 v208, v12, s45
	v_add3_u32 v205, 16, v242, v243
	v_add_u32_e32 v210, 0x1b000, v215
	ds_write_b128 v209, v[0:3]
	s_waitcnt vmcnt(6)
	ds_write_b128 v210, v[4:7]
	v_add3_u32 v204, 16, v208, v243
	ds_read_b128 v[0:3], v205 offset:36864
	ds_read_b128 v[4:7], v205 offset:41472
	ds_read_b128 v[8:11], v204
	ds_read_b128 v[12:15], v204 offset:4608
	v_lshl_add_u64 v[184:185], v[190:191], 0, s[42:43]
	v_lshl_add_u64 v[186:187], s[28:29], 0, v[192:193]
	v_lshl_add_u64 v[194:195], v[190:191], 0, s[34:35]
	v_lshl_add_u64 v[196:197], s[26:27], 0, v[192:193]
	s_setprio 1
	s_waitcnt lgkmcnt(1)
	v_mfma_f32_32x32x16_bf16 v[112:127], v[8:11], v[0:3], 0
	v_mfma_f32_32x32x16_bf16 v[48:63], v[8:11], v[4:7], 0
	s_waitcnt lgkmcnt(0)
	v_mfma_f32_32x32x16_bf16 v[96:111], v[12:15], v[0:3], 0
	v_mfma_f32_32x32x16_bf16 v[32:47], v[12:15], v[4:7], 0
	ds_read_b128 v[8:11], v204 offset:9216
	ds_read_b128 v[12:15], v204 offset:13824
	s_waitcnt lgkmcnt(1)
	v_mfma_f32_32x32x16_bf16 v[80:95], v[8:11], v[0:3], 0
	v_mfma_f32_32x32x16_bf16 v[16:31], v[8:11], v[4:7], 0
	s_waitcnt lgkmcnt(0)
	v_mfma_f32_32x32x16_bf16 v[64:79], v[12:15], v[0:3], 0
	v_mfma_f32_32x32x16_bf16 v[0:15], v[12:15], v[4:7], 0
	s_setprio 0
	global_load_dwordx4 v[226:229], v[194:195], off offset:256
	global_load_dwordx4 v[230:233], v[196:197], off offset:256
	v_add_u32_e32 v212, 0x14400, v215
	v_add_u32_e32 v211, 0x1d400, v215
	ds_write_b128 v212, v[176:179]
	s_waitcnt vmcnt(7)
	ds_write_b128 v211, v[180:183]
	ds_read_b128 v[176:179], v205 offset:36896
	ds_read_b128 v[180:183], v205 offset:41504
	ds_read_b128 v[198:201], v204 offset:32
	ds_read_b128 v[234:237], v204 offset:4640
	s_setprio 1
	s_waitcnt lgkmcnt(1)
	v_mfma_f32_32x32x16_bf16 v[112:127], v[198:201], v[176:179], v[112:127]
	v_mfma_f32_32x32x16_bf16 v[48:63], v[198:201], v[180:183], v[48:63]
	s_waitcnt lgkmcnt(0)
	v_mfma_f32_32x32x16_bf16 v[96:111], v[234:237], v[176:179], v[96:111]
	v_mfma_f32_32x32x16_bf16 v[32:47], v[234:237], v[180:183], v[32:47]
	ds_read_b128 v[198:201], v204 offset:9248
	ds_read_b128 v[234:237], v204 offset:13856
	s_waitcnt lgkmcnt(1)
	v_mfma_f32_32x32x16_bf16 v[80:95], v[198:201], v[176:179], v[80:95]
	v_mfma_f32_32x32x16_bf16 v[16:31], v[198:201], v[180:183], v[16:31]
	s_waitcnt lgkmcnt(0)
	v_mfma_f32_32x32x16_bf16 v[64:79], v[234:237], v[176:179], v[64:79]
	v_mfma_f32_32x32x16_bf16 v[0:15], v[234:237], v[180:183], v[0:15]
	s_setprio 0
	global_load_dwordx4 v[176:179], v[184:185], off offset:256
	global_load_dwordx4 v[180:183], v[186:187], off offset:256
	v_add_u32_e32 v214, 0x16800, v215
	v_add_u32_e32 v213, 0x1f800, v215
	ds_write_b128 v214, v[168:171]
	s_waitcnt vmcnt(8)
	ds_write_b128 v213, v[172:175]
	ds_read_b128 v[168:171], v205 offset:36928
	ds_read_b128 v[172:175], v205 offset:41536
	ds_read_b128 v[198:201], v204 offset:64
	ds_read_b128 v[234:237], v204 offset:4672
	s_setprio 1
	s_waitcnt lgkmcnt(1)
	v_mfma_f32_32x32x16_bf16 v[112:127], v[198:201], v[168:171], v[112:127]
	v_mfma_f32_32x32x16_bf16 v[48:63], v[198:201], v[172:175], v[48:63]
	s_waitcnt lgkmcnt(0)
	v_mfma_f32_32x32x16_bf16 v[96:111], v[234:237], v[168:171], v[96:111]
	v_mfma_f32_32x32x16_bf16 v[32:47], v[234:237], v[172:175], v[32:47]
	ds_read_b128 v[198:201], v204 offset:9280
	ds_read_b128 v[234:237], v204 offset:13888
	s_waitcnt lgkmcnt(1)
	v_mfma_f32_32x32x16_bf16 v[80:95], v[198:201], v[168:171], v[80:95]
	v_mfma_f32_32x32x16_bf16 v[16:31], v[198:201], v[172:175], v[16:31]
	s_waitcnt lgkmcnt(0)
	v_mfma_f32_32x32x16_bf16 v[64:79], v[234:237], v[168:171], v[64:79]
	v_mfma_f32_32x32x16_bf16 v[0:15], v[234:237], v[172:175], v[0:15]
	s_setprio 0
	v_add_co_u32_e32 v198, vcc, s44, v190
	v_add_u32_e32 v217, 0x18c00, v215
	s_nop 0
	v_addc_co_u32_e32 v199, vcc, 0, v191, vcc
	v_add_co_u32_e32 v200, vcc, s44, v188
	v_add_u32_e32 v216, 0x21c00, v215
	s_nop 0
	v_addc_co_u32_e32 v201, vcc, 0, v189, vcc
	global_load_dwordx4 v[168:171], v[198:199], off offset:256
	global_load_dwordx4 v[172:175], v[200:201], off offset:256
	s_waitcnt vmcnt(8)
	ds_write_b128 v217, v[164:167]
	ds_write_b128 v216, v[160:163]
	ds_read_b128 v[160:163], v205 offset:36960
	ds_read_b128 v[164:167], v205 offset:41568
	ds_read_b128 v[234:237], v204 offset:96
	ds_read_b128 v[238:241], v204 offset:4704
	s_setprio 1
	s_waitcnt lgkmcnt(1)
	v_mfma_f32_32x32x16_bf16 v[112:127], v[234:237], v[160:163], v[112:127]
	v_mfma_f32_32x32x16_bf16 v[48:63], v[234:237], v[164:167], v[48:63]
	s_waitcnt lgkmcnt(0)
	v_mfma_f32_32x32x16_bf16 v[96:111], v[238:241], v[160:163], v[96:111]
	v_mfma_f32_32x32x16_bf16 v[32:47], v[238:241], v[164:167], v[32:47]
	ds_read_b128 v[234:237], v204 offset:9312
	ds_read_b128 v[238:241], v204 offset:13920
	s_waitcnt lgkmcnt(1)
	v_mfma_f32_32x32x16_bf16 v[80:95], v[234:237], v[160:163], v[80:95]
	v_mfma_f32_32x32x16_bf16 v[16:31], v[234:237], v[164:167], v[16:31]
	s_waitcnt lgkmcnt(0)
	v_mfma_f32_32x32x16_bf16 v[64:79], v[238:241], v[160:163], v[64:79]
	v_mfma_f32_32x32x16_bf16 v[0:15], v[238:241], v[164:167], v[0:15]
	s_setprio 0
	global_load_dwordx4 v[160:163], v[190:191], off offset:384
	global_load_dwordx4 v[164:167], v[188:189], off offset:384
	s_barrier
; template <bool trans>
; DI void gemm_core(const GTile& tl, const GTile& nx, bool has_next  , bool chain  , bool pre, u32x4 (&ra)[4], u32x4 (&rb)[4], char* smem, f32x16 (&acc)[2][4]) {
;     ...
;   const int nk = K / 64;
;   if (!pre) { G_LOAD(0); G_STORE(0); G_LOAD(1); }
;   for (int kt = 0; kt < nk; ++kt) {
;     __syncthreads();
;     G_COMPUTE(kt & 1, kt);
;   }
	s_add_i32 s0, 16, 0x12000
	v_add3_u32 v192, s0, v208, v243
	s_add_i32 s0, 16, 0x1b000
	v_add3_u32 v208, s0, v242, v243
	s_waitcnt vmcnt(9)
	ds_write_b128 v215, v[218:221]
	s_waitcnt vmcnt(8)
	ds_write_b128 v215, v[222:225] offset:36864
	ds_read_b128 v[218:221], v208
	ds_read_b128 v[222:225], v208 offset:4608
	ds_read_b128 v[234:237], v192
	ds_read_b128 v[238:241], v192 offset:4608
	s_setprio 1
	s_waitcnt lgkmcnt(1)
	v_mfma_f32_32x32x16_bf16 v[112:127], v[234:237], v[218:221], v[112:127]
	v_mfma_f32_32x32x16_bf16 v[48:63], v[234:237], v[222:225], v[48:63]
	s_waitcnt lgkmcnt(0)
	v_mfma_f32_32x32x16_bf16 v[96:111], v[238:241], v[218:221], v[96:111]
	v_mfma_f32_32x32x16_bf16 v[32:47], v[238:241], v[222:225], v[32:47]
	ds_read_b128 v[234:237], v192 offset:9216
	ds_read_b128 v[238:241], v192 offset:13824
	s_waitcnt lgkmcnt(1)
	v_mfma_f32_32x32x16_bf16 v[80:95], v[234:237], v[218:221], v[80:95]
	v_mfma_f32_32x32x16_bf16 v[16:31], v[234:237], v[222:225], v[16:31]
	s_waitcnt lgkmcnt(0)
	v_mfma_f32_32x32x16_bf16 v[64:79], v[238:241], v[218:221], v[64:79]
	v_mfma_f32_32x32x16_bf16 v[0:15], v[238:241], v[222:225], v[0:15]
	s_setprio 0
	global_load_dwordx4 v[218:221], v[194:195], off offset:384
	global_load_dwordx4 v[222:225], v[196:197], off offset:384
	s_waitcnt vmcnt(9)
	ds_write_b128 v215, v[226:229] offset:9216
	s_waitcnt vmcnt(8)
	ds_write_b128 v215, v[230:233] offset:46080
	ds_read_b128 v[226:229], v208 offset:32
	ds_read_b128 v[230:233], v208 offset:4640
	ds_read_b128 v[234:237], v192 offset:32
	ds_read_b128 v[238:241], v192 offset:4640
	s_setprio 1
	s_waitcnt lgkmcnt(1)
	v_mfma_f32_32x32x16_bf16 v[112:127], v[234:237], v[226:229], v[112:127]
	v_mfma_f32_32x32x16_bf16 v[48:63], v[234:237], v[230:233], v[48:63]
	s_waitcnt lgkmcnt(0)
	v_mfma_f32_32x32x16_bf16 v[96:111], v[238:241], v[226:229], v[96:111]
	v_mfma_f32_32x32x16_bf16 v[32:47], v[238:241], v[230:233], v[32:47]
	ds_read_b128 v[234:237], v192 offset:9248
	ds_read_b128 v[238:241], v192 offset:13856
	s_waitcnt lgkmcnt(1)
	v_mfma_f32_32x32x16_bf16 v[80:95], v[234:237], v[226:229], v[80:95]
	v_mfma_f32_32x32x16_bf16 v[16:31], v[234:237], v[230:233], v[16:31]
	s_waitcnt lgkmcnt(0)
	v_mfma_f32_32x32x16_bf16 v[64:79], v[238:241], v[226:229], v[64:79]
	v_mfma_f32_32x32x16_bf16 v[0:15], v[238:241], v[230:233], v[0:15]
	s_setprio 0
	global_load_dwordx4 v[226:229], v[184:185], off offset:384
	global_load_dwordx4 v[230:233], v[186:187], off offset:384
	s_waitcnt vmcnt(9)
	ds_write_b128 v215, v[176:179] offset:18432
	s_waitcnt vmcnt(8)
	ds_write_b128 v215, v[180:183] offset:55296
	ds_read_b128 v[176:179], v208 offset:64
	ds_read_b128 v[180:183], v208 offset:4672
	ds_read_b128 v[234:237], v192 offset:64
	ds_read_b128 v[238:241], v192 offset:4672
	s_setprio 1
	s_waitcnt lgkmcnt(1)
	v_mfma_f32_32x32x16_bf16 v[112:127], v[234:237], v[176:179], v[112:127]
	v_mfma_f32_32x32x16_bf16 v[48:63], v[234:237], v[180:183], v[48:63]
	s_waitcnt lgkmcnt(0)
	v_mfma_f32_32x32x16_bf16 v[96:111], v[238:241], v[176:179], v[96:111]
	v_mfma_f32_32x32x16_bf16 v[32:47], v[238:241], v[180:183], v[32:47]
	ds_read_b128 v[234:237], v192 offset:9280
	ds_read_b128 v[238:241], v192 offset:13888
	s_waitcnt lgkmcnt(1)
	v_mfma_f32_32x32x16_bf16 v[80:95], v[234:237], v[176:179], v[80:95]
	v_mfma_f32_32x32x16_bf16 v[16:31], v[234:237], v[180:183], v[16:31]
	s_waitcnt lgkmcnt(0)
	v_mfma_f32_32x32x16_bf16 v[64:79], v[238:241], v[176:179], v[64:79]
	v_mfma_f32_32x32x16_bf16 v[0:15], v[238:241], v[180:183], v[0:15]
	s_setprio 0
	global_load_dwordx4 v[176:179], v[198:199], off offset:384
	global_load_dwordx4 v[180:183], v[200:201], off offset:384
	s_waitcnt vmcnt(9)
	ds_write_b128 v215, v[168:171] offset:27648
	s_waitcnt vmcnt(8)
	ds_write_b128 v215, v[172:175] offset:64512
	ds_read_b128 v[168:171], v208 offset:96
	ds_read_b128 v[172:175], v208 offset:4704
	ds_read_b128 v[234:237], v192 offset:96
	ds_read_b128 v[238:241], v192 offset:4704
	s_setprio 1
	s_waitcnt lgkmcnt(1)
	v_mfma_f32_32x32x16_bf16 v[112:127], v[234:237], v[168:171], v[112:127]
	v_mfma_f32_32x32x16_bf16 v[48:63], v[234:237], v[172:175], v[48:63]
	s_waitcnt lgkmcnt(0)
	v_mfma_f32_32x32x16_bf16 v[96:111], v[238:241], v[168:171], v[96:111]
	v_mfma_f32_32x32x16_bf16 v[32:47], v[238:241], v[172:175], v[32:47]
	ds_read_b128 v[234:237], v192 offset:9312
	ds_read_b128 v[238:241], v192 offset:13920
	s_waitcnt lgkmcnt(1)
	v_mfma_f32_32x32x16_bf16 v[80:95], v[234:237], v[168:171], v[80:95]
	v_mfma_f32_32x32x16_bf16 v[16:31], v[234:237], v[172:175], v[16:31]
	s_waitcnt lgkmcnt(0)
	v_mfma_f32_32x32x16_bf16 v[64:79], v[238:241], v[168:171], v[64:79]
	v_mfma_f32_32x32x16_bf16 v[0:15], v[238:241], v[172:175], v[0:15]
	s_setprio 0
	global_load_dwordx4 v[168:171], v[190:191], off offset:512
	global_load_dwordx4 v[172:175], v[188:189], off offset:512
	s_barrier
; template <bool trans>
; DI void gemm_core(const GTile& tl, const GTile& nx, bool has_next  , bool chain  , bool pre, u32x4 (&ra)[4], u32x4 (&rb)[4], char* smem, f32x16 (&acc)[2][4]) {
;     ...
;   const int nk = K / 64;
;   if (!pre) { G_LOAD(0); G_STORE(0); G_LOAD(1); }
;   for (int kt = 0; kt < nk; ++kt) {
;     __syncthreads();
;     G_COMPUTE(kt & 1, kt);
;   }
	s_waitcnt vmcnt(9)
	ds_write_b128 v209, v[160:163]
	s_waitcnt vmcnt(8)
	ds_write_b128 v210, v[164:167]
	ds_read_b128 v[160:163], v205 offset:36864
	ds_read_b128 v[164:167], v205 offset:41472
	ds_read_b128 v[234:237], v204
	ds_read_b128 v[238:241], v204 offset:4608
	s_setprio 1
	s_waitcnt lgkmcnt(1)
	v_mfma_f32_32x32x16_bf16 v[112:127], v[234:237], v[160:163], v[112:127]
	v_mfma_f32_32x32x16_bf16 v[48:63], v[234:237], v[164:167], v[48:63]
	s_waitcnt lgkmcnt(0)
	v_mfma_f32_32x32x16_bf16 v[96:111], v[238:241], v[160:163], v[96:111]
	v_mfma_f32_32x32x16_bf16 v[32:47], v[238:241], v[164:167], v[32:47]
	ds_read_b128 v[234:237], v204 offset:9216
	ds_read_b128 v[238:241], v204 offset:13824
	s_waitcnt vmcnt(7)
	ds_write_b128 v212, v[218:221]
	s_waitcnt vmcnt(6)
	ds_write_b128 v211, v[222:225]
	ds_read_b128 v[218:221], v205 offset:36896
	ds_read_b128 v[222:225], v205 offset:41504
	s_waitcnt lgkmcnt(5)
	v_mfma_f32_32x32x16_bf16 v[80:95], v[234:237], v[160:163], v[80:95]
	v_mfma_f32_32x32x16_bf16 v[16:31], v[234:237], v[164:167], v[16:31]
	ds_read_b128 v[234:237], v204 offset:32
	s_waitcnt lgkmcnt(5)
	v_mfma_f32_32x32x16_bf16 v[64:79], v[238:241], v[160:163], v[64:79]
	v_mfma_f32_32x32x16_bf16 v[0:15], v[238:241], v[164:167], v[0:15]
	ds_read_b128 v[238:241], v204 offset:4640
	s_setprio 0
	global_load_dwordx4 v[160:163], v[194:195], off offset:512
	global_load_dwordx4 v[164:167], v[196:197], off offset:512
	s_setprio 1
	s_waitcnt lgkmcnt(1)
	v_mfma_f32_32x32x16_bf16 v[112:127], v[234:237], v[218:221], v[112:127]
	v_mfma_f32_32x32x16_bf16 v[48:63], v[234:237], v[222:225], v[48:63]
	s_waitcnt lgkmcnt(0)
	v_mfma_f32_32x32x16_bf16 v[96:111], v[238:241], v[218:221], v[96:111]
	v_mfma_f32_32x32x16_bf16 v[32:47], v[238:241], v[222:225], v[32:47]
	ds_read_b128 v[234:237], v204 offset:9248
	ds_read_b128 v[238:241], v204 offset:13856
	s_waitcnt vmcnt(7)
	ds_write_b128 v214, v[226:229]
	s_waitcnt vmcnt(6)
	ds_write_b128 v213, v[230:233]
	ds_read_b128 v[226:229], v205 offset:36928
	ds_read_b128 v[230:233], v205 offset:41536
	s_waitcnt lgkmcnt(5)
	v_mfma_f32_32x32x16_bf16 v[80:95], v[234:237], v[218:221], v[80:95]
	v_mfma_f32_32x32x16_bf16 v[16:31], v[234:237], v[222:225], v[16:31]
	ds_read_b128 v[234:237], v204 offset:64
	s_waitcnt lgkmcnt(5)
	v_mfma_f32_32x32x16_bf16 v[64:79], v[238:241], v[218:221], v[64:79]
	v_mfma_f32_32x32x16_bf16 v[0:15], v[238:241], v[222:225], v[0:15]
	ds_read_b128 v[238:241], v204 offset:4672
	s_setprio 0
	global_load_dwordx4 v[218:221], v[184:185], off offset:512
	global_load_dwordx4 v[222:225], v[186:187], off offset:512
	s_setprio 1
	s_waitcnt lgkmcnt(1)
	v_mfma_f32_32x32x16_bf16 v[112:127], v[234:237], v[226:229], v[112:127]
	v_mfma_f32_32x32x16_bf16 v[48:63], v[234:237], v[230:233], v[48:63]
	s_waitcnt lgkmcnt(0)
	v_mfma_f32_32x32x16_bf16 v[96:111], v[238:241], v[226:229], v[96:111]
	v_mfma_f32_32x32x16_bf16 v[32:47], v[238:241], v[230:233], v[32:47]
	ds_read_b128 v[234:237], v204 offset:9280
	ds_read_b128 v[238:241], v204 offset:13888
	s_waitcnt vmcnt(7)
	ds_write_b128 v217, v[176:179]
	s_waitcnt vmcnt(6)
	ds_write_b128 v216, v[180:183]
	ds_read_b128 v[176:179], v205 offset:36960
	ds_read_b128 v[180:183], v205 offset:41568
	s_waitcnt lgkmcnt(5)
	v_mfma_f32_32x32x16_bf16 v[80:95], v[234:237], v[226:229], v[80:95]
	v_mfma_f32_32x32x16_bf16 v[16:31], v[234:237], v[230:233], v[16:31]
	ds_read_b128 v[234:237], v204 offset:96
	s_waitcnt lgkmcnt(5)
	v_mfma_f32_32x32x16_bf16 v[64:79], v[238:241], v[226:229], v[64:79]
	v_mfma_f32_32x32x16_bf16 v[0:15], v[238:241], v[230:233], v[0:15]
	ds_read_b128 v[238:241], v204 offset:4704
	s_setprio 0
	global_load_dwordx4 v[226:229], v[198:199], off offset:512
	global_load_dwordx4 v[230:233], v[200:201], off offset:512
	s_setprio 1
	s_waitcnt lgkmcnt(1)
	v_mfma_f32_32x32x16_bf16 v[112:127], v[234:237], v[176:179], v[112:127]
	v_mfma_f32_32x32x16_bf16 v[48:63], v[234:237], v[180:183], v[48:63]
	s_waitcnt lgkmcnt(0)
	v_mfma_f32_32x32x16_bf16 v[96:111], v[238:241], v[176:179], v[96:111]
	v_mfma_f32_32x32x16_bf16 v[32:47], v[238:241], v[180:183], v[32:47]
	ds_read_b128 v[234:237], v204 offset:9312
	ds_read_b128 v[238:241], v204 offset:13920
	s_waitcnt lgkmcnt(0)
	s_barrier
	s_waitcnt vmcnt(7)
	ds_write_b128 v215, v[168:171]
	s_waitcnt vmcnt(6)
	ds_write_b128 v215, v[172:175] offset:36864
	ds_read_b128 v[168:171], v208
	ds_read_b128 v[172:175], v208 offset:4608
	v_mfma_f32_32x32x16_bf16 v[80:95], v[234:237], v[176:179], v[80:95]
	v_mfma_f32_32x32x16_bf16 v[16:31], v[234:237], v[180:183], v[16:31]
	ds_read_b128 v[234:237], v192
	v_mfma_f32_32x32x16_bf16 v[64:79], v[238:241], v[176:179], v[64:79]
	v_mfma_f32_32x32x16_bf16 v[0:15], v[238:241], v[180:183], v[0:15]
	ds_read_b128 v[238:241], v192 offset:4608
	s_setprio 0
	global_load_dwordx4 v[176:179], v[190:191], off offset:640
	global_load_dwordx4 v[180:183], v[188:189], off offset:640
	s_setprio 1
	s_waitcnt lgkmcnt(1)
	v_mfma_f32_32x32x16_bf16 v[112:127], v[234:237], v[168:171], v[112:127]
	v_mfma_f32_32x32x16_bf16 v[48:63], v[234:237], v[172:175], v[48:63]
	s_waitcnt lgkmcnt(0)
	v_mfma_f32_32x32x16_bf16 v[96:111], v[238:241], v[168:171], v[96:111]
	v_mfma_f32_32x32x16_bf16 v[32:47], v[238:241], v[172:175], v[32:47]
	ds_read_b128 v[234:237], v192 offset:9216
	ds_read_b128 v[238:241], v192 offset:13824
	s_waitcnt vmcnt(7)
	ds_write_b128 v215, v[160:163] offset:9216
	s_waitcnt vmcnt(6)
	ds_write_b128 v215, v[164:167] offset:46080
	ds_read_b128 v[160:163], v208 offset:32
	ds_read_b128 v[164:167], v208 offset:4640
	s_waitcnt lgkmcnt(5)
	v_mfma_f32_32x32x16_bf16 v[80:95], v[234:237], v[168:171], v[80:95]
	v_mfma_f32_32x32x16_bf16 v[16:31], v[234:237], v[172:175], v[16:31]
	ds_read_b128 v[234:237], v192 offset:32
	s_waitcnt lgkmcnt(5)
; template <bool trans>
; DI void gemm_core(const GTile& tl, const GTile& nx, bool has_next  , bool chain  , bool pre, u32x4 (&ra)[4], u32x4 (&rb)[4], char* smem, f32x16 (&acc)[2][4]) {
;     ...
;   const int nk = K / 64;
;   if (!pre) { G_LOAD(0); G_STORE(0); G_LOAD(1); }
;   for (int kt = 0; kt < nk; ++kt) {
;     __syncthreads();
;     G_COMPUTE(kt & 1, kt);
;   }
	v_mfma_f32_32x32x16_bf16 v[64:79], v[238:241], v[168:171], v[64:79]
	v_mfma_f32_32x32x16_bf16 v[0:15], v[238:241], v[172:175], v[0:15]
	ds_read_b128 v[238:241], v192 offset:4640
	s_setprio 0
	global_load_dwordx4 v[168:171], v[194:195], off offset:640
	global_load_dwordx4 v[172:175], v[196:197], off offset:640
	s_setprio 1
	s_waitcnt lgkmcnt(1)
	v_mfma_f32_32x32x16_bf16 v[112:127], v[234:237], v[160:163], v[112:127]
	v_mfma_f32_32x32x16_bf16 v[48:63], v[234:237], v[164:167], v[48:63]
	s_waitcnt lgkmcnt(0)
	v_mfma_f32_32x32x16_bf16 v[96:111], v[238:241], v[160:163], v[96:111]
	v_mfma_f32_32x32x16_bf16 v[32:47], v[238:241], v[164:167], v[32:47]
	ds_read_b128 v[234:237], v192 offset:9248
	ds_read_b128 v[238:241], v192 offset:13856
	s_waitcnt vmcnt(7)
	ds_write_b128 v215, v[218:221] offset:18432
	s_waitcnt vmcnt(6)
	ds_write_b128 v215, v[222:225] offset:55296
	ds_read_b128 v[218:221], v208 offset:64
	ds_read_b128 v[222:225], v208 offset:4672
	s_waitcnt lgkmcnt(5)
	v_mfma_f32_32x32x16_bf16 v[80:95], v[234:237], v[160:163], v[80:95]
	v_mfma_f32_32x32x16_bf16 v[16:31], v[234:237], v[164:167], v[16:31]
	ds_read_b128 v[234:237], v192 offset:64
	s_waitcnt lgkmcnt(5)
	v_mfma_f32_32x32x16_bf16 v[64:79], v[238:241], v[160:163], v[64:79]
	v_mfma_f32_32x32x16_bf16 v[0:15], v[238:241], v[164:167], v[0:15]
	ds_read_b128 v[238:241], v192 offset:4672
	s_setprio 0
	global_load_dwordx4 v[160:163], v[184:185], off offset:640
	global_load_dwordx4 v[164:167], v[186:187], off offset:640
	s_setprio 1
	s_waitcnt lgkmcnt(1)
	v_mfma_f32_32x32x16_bf16 v[112:127], v[234:237], v[218:221], v[112:127]
	v_mfma_f32_32x32x16_bf16 v[48:63], v[234:237], v[222:225], v[48:63]
	s_waitcnt lgkmcnt(0)
	v_mfma_f32_32x32x16_bf16 v[96:111], v[238:241], v[218:221], v[96:111]
	v_mfma_f32_32x32x16_bf16 v[32:47], v[238:241], v[222:225], v[32:47]
	ds_read_b128 v[234:237], v192 offset:9280
	ds_read_b128 v[238:241], v192 offset:13888
	s_waitcnt vmcnt(7)
	ds_write_b128 v215, v[226:229] offset:27648
	s_waitcnt vmcnt(6)
	ds_write_b128 v215, v[230:233] offset:64512
	ds_read_b128 v[226:229], v208 offset:96
	ds_read_b128 v[230:233], v208 offset:4704
	s_waitcnt lgkmcnt(5)
	v_mfma_f32_32x32x16_bf16 v[80:95], v[234:237], v[218:221], v[80:95]
	v_mfma_f32_32x32x16_bf16 v[16:31], v[234:237], v[222:225], v[16:31]
	ds_read_b128 v[234:237], v192 offset:96
	s_waitcnt lgkmcnt(5)
	v_mfma_f32_32x32x16_bf16 v[64:79], v[238:241], v[218:221], v[64:79]
	v_mfma_f32_32x32x16_bf16 v[0:15], v[238:241], v[222:225], v[0:15]
	ds_read_b128 v[238:241], v192 offset:4704
	s_setprio 0
	global_load_dwordx4 v[218:221], v[198:199], off offset:640
	global_load_dwordx4 v[222:225], v[200:201], off offset:640
	s_setprio 1
	s_waitcnt lgkmcnt(1)
	v_mfma_f32_32x32x16_bf16 v[112:127], v[234:237], v[226:229], v[112:127]
	v_mfma_f32_32x32x16_bf16 v[48:63], v[234:237], v[230:233], v[48:63]
	s_waitcnt lgkmcnt(0)
	v_mfma_f32_32x32x16_bf16 v[96:111], v[238:241], v[226:229], v[96:111]
	v_mfma_f32_32x32x16_bf16 v[32:47], v[238:241], v[230:233], v[32:47]
	ds_read_b128 v[234:237], v192 offset:9312
	ds_read_b128 v[238:241], v192 offset:13920
	s_waitcnt lgkmcnt(0)
	s_barrier
	s_waitcnt vmcnt(7)
	ds_write_b128 v209, v[176:179]
	s_waitcnt vmcnt(6)
	ds_write_b128 v210, v[180:183]
	ds_read_b128 v[176:179], v205 offset:36864
	ds_read_b128 v[180:183], v205 offset:41472
	v_mfma_f32_32x32x16_bf16 v[80:95], v[234:237], v[226:229], v[80:95]
	v_mfma_f32_32x32x16_bf16 v[16:31], v[234:237], v[230:233], v[16:31]
	ds_read_b128 v[234:237], v204
	v_mfma_f32_32x32x16_bf16 v[64:79], v[238:241], v[226:229], v[64:79]
	v_mfma_f32_32x32x16_bf16 v[0:15], v[238:241], v[230:233], v[0:15]
	ds_read_b128 v[238:241], v204 offset:4608
	s_setprio 0
	global_load_dwordx4 v[226:229], v[190:191], off offset:768
	global_load_dwordx4 v[230:233], v[188:189], off offset:768
	s_setprio 1
	s_waitcnt lgkmcnt(1)
	v_mfma_f32_32x32x16_bf16 v[112:127], v[234:237], v[176:179], v[112:127]
	v_mfma_f32_32x32x16_bf16 v[48:63], v[234:237], v[180:183], v[48:63]
	s_waitcnt lgkmcnt(0)
	v_mfma_f32_32x32x16_bf16 v[96:111], v[238:241], v[176:179], v[96:111]
	v_mfma_f32_32x32x16_bf16 v[32:47], v[238:241], v[180:183], v[32:47]
	ds_read_b128 v[234:237], v204 offset:9216
	ds_read_b128 v[238:241], v204 offset:13824
	s_waitcnt vmcnt(7)
	ds_write_b128 v212, v[168:171]
	s_waitcnt vmcnt(6)
	ds_write_b128 v211, v[172:175]
	ds_read_b128 v[168:171], v205 offset:36896
	ds_read_b128 v[172:175], v205 offset:41504
	s_waitcnt lgkmcnt(5)
	v_mfma_f32_32x32x16_bf16 v[80:95], v[234:237], v[176:179], v[80:95]
	v_mfma_f32_32x32x16_bf16 v[16:31], v[234:237], v[180:183], v[16:31]
	ds_read_b128 v[234:237], v204 offset:32
	s_waitcnt lgkmcnt(5)
	v_mfma_f32_32x32x16_bf16 v[64:79], v[238:241], v[176:179], v[64:79]
	v_mfma_f32_32x32x16_bf16 v[0:15], v[238:241], v[180:183], v[0:15]
	ds_read_b128 v[238:241], v204 offset:4640
	s_setprio 0
	global_load_dwordx4 v[176:179], v[194:195], off offset:768
	global_load_dwordx4 v[180:183], v[196:197], off offset:768
	s_setprio 1
	s_waitcnt lgkmcnt(1)
	v_mfma_f32_32x32x16_bf16 v[112:127], v[234:237], v[168:171], v[112:127]
	v_mfma_f32_32x32x16_bf16 v[48:63], v[234:237], v[172:175], v[48:63]
	s_waitcnt lgkmcnt(0)
	v_mfma_f32_32x32x16_bf16 v[96:111], v[238:241], v[168:171], v[96:111]
	v_mfma_f32_32x32x16_bf16 v[32:47], v[238:241], v[172:175], v[32:47]
	ds_read_b128 v[234:237], v204 offset:9248
	ds_read_b128 v[238:241], v204 offset:13856
	s_waitcnt vmcnt(7)
	ds_write_b128 v214, v[160:163]
	s_waitcnt vmcnt(6)
	ds_write_b128 v213, v[164:167]
	ds_read_b128 v[160:163], v205 offset:36928
	ds_read_b128 v[164:167], v205 offset:41536
	s_waitcnt lgkmcnt(5)
; template <bool trans>
; DI void gemm_core(const GTile& tl, const GTile& nx, bool has_next  , bool chain  , bool pre, u32x4 (&ra)[4], u32x4 (&rb)[4], char* smem, f32x16 (&acc)[2][4]) {
;     ...
;   const int nk = K / 64;
;   if (!pre) { G_LOAD(0); G_STORE(0); G_LOAD(1); }
;   for (int kt = 0; kt < nk; ++kt) {
;     __syncthreads();
;     G_COMPUTE(kt & 1, kt);
;   }
	v_mfma_f32_32x32x16_bf16 v[80:95], v[234:237], v[168:171], v[80:95]
	v_mfma_f32_32x32x16_bf16 v[16:31], v[234:237], v[172:175], v[16:31]
	ds_read_b128 v[234:237], v204 offset:64
	s_waitcnt lgkmcnt(5)
	v_mfma_f32_32x32x16_bf16 v[64:79], v[238:241], v[168:171], v[64:79]
	v_mfma_f32_32x32x16_bf16 v[0:15], v[238:241], v[172:175], v[0:15]
	ds_read_b128 v[238:241], v204 offset:4672
	s_setprio 0
	global_load_dwordx4 v[168:171], v[184:185], off offset:768
	global_load_dwordx4 v[172:175], v[186:187], off offset:768
	s_setprio 1
	s_waitcnt lgkmcnt(1)
	v_mfma_f32_32x32x16_bf16 v[112:127], v[234:237], v[160:163], v[112:127]
	v_mfma_f32_32x32x16_bf16 v[48:63], v[234:237], v[164:167], v[48:63]
	s_waitcnt lgkmcnt(0)
	v_mfma_f32_32x32x16_bf16 v[96:111], v[238:241], v[160:163], v[96:111]
	v_mfma_f32_32x32x16_bf16 v[32:47], v[238:241], v[164:167], v[32:47]
	ds_read_b128 v[234:237], v204 offset:9280
	ds_read_b128 v[238:241], v204 offset:13888
	s_waitcnt vmcnt(7)
	ds_write_b128 v217, v[218:221]
	s_waitcnt vmcnt(6)
	ds_write_b128 v216, v[222:225]
	ds_read_b128 v[218:221], v205 offset:36960
	ds_read_b128 v[222:225], v205 offset:41568
	s_waitcnt lgkmcnt(5)
	v_mfma_f32_32x32x16_bf16 v[80:95], v[234:237], v[160:163], v[80:95]
	v_mfma_f32_32x32x16_bf16 v[16:31], v[234:237], v[164:167], v[16:31]
	ds_read_b128 v[234:237], v204 offset:96
	s_waitcnt lgkmcnt(5)
	v_mfma_f32_32x32x16_bf16 v[64:79], v[238:241], v[160:163], v[64:79]
	v_mfma_f32_32x32x16_bf16 v[0:15], v[238:241], v[164:167], v[0:15]
	ds_read_b128 v[238:241], v204 offset:4704
	s_setprio 0
	global_load_dwordx4 v[160:163], v[198:199], off offset:768
	global_load_dwordx4 v[164:167], v[200:201], off offset:768
	s_setprio 1
	s_waitcnt lgkmcnt(1)
	v_mfma_f32_32x32x16_bf16 v[112:127], v[234:237], v[218:221], v[112:127]
	v_mfma_f32_32x32x16_bf16 v[48:63], v[234:237], v[222:225], v[48:63]
	s_waitcnt lgkmcnt(0)
	v_mfma_f32_32x32x16_bf16 v[96:111], v[238:241], v[218:221], v[96:111]
	v_mfma_f32_32x32x16_bf16 v[32:47], v[238:241], v[222:225], v[32:47]
	ds_read_b128 v[234:237], v204 offset:9312
	ds_read_b128 v[238:241], v204 offset:13920
	s_waitcnt lgkmcnt(0)
	s_barrier
	s_waitcnt vmcnt(7)
	ds_write_b128 v215, v[226:229]
	s_waitcnt vmcnt(6)
	ds_write_b128 v215, v[230:233] offset:36864
	ds_read_b128 v[226:229], v208
	ds_read_b128 v[230:233], v208 offset:4608
	v_mfma_f32_32x32x16_bf16 v[80:95], v[234:237], v[218:221], v[80:95]
	v_mfma_f32_32x32x16_bf16 v[16:31], v[234:237], v[222:225], v[16:31]
	ds_read_b128 v[234:237], v192
	v_mfma_f32_32x32x16_bf16 v[64:79], v[238:241], v[218:221], v[64:79]
	v_mfma_f32_32x32x16_bf16 v[0:15], v[238:241], v[222:225], v[0:15]
	ds_read_b128 v[238:241], v192 offset:4608
	s_setprio 0
	global_load_dwordx4 v[218:221], v[190:191], off offset:896
	global_load_dwordx4 v[222:225], v[188:189], off offset:896
	s_setprio 1
	s_waitcnt lgkmcnt(1)
	v_mfma_f32_32x32x16_bf16 v[112:127], v[234:237], v[226:229], v[112:127]
	v_mfma_f32_32x32x16_bf16 v[48:63], v[234:237], v[230:233], v[48:63]
	s_waitcnt lgkmcnt(0)
	v_mfma_f32_32x32x16_bf16 v[96:111], v[238:241], v[226:229], v[96:111]
	v_mfma_f32_32x32x16_bf16 v[32:47], v[238:241], v[230:233], v[32:47]
	ds_read_b128 v[234:237], v192 offset:9216
	ds_read_b128 v[238:241], v192 offset:13824
	s_waitcnt vmcnt(7)
	ds_write_b128 v215, v[176:179] offset:9216
	s_waitcnt vmcnt(6)
	ds_write_b128 v215, v[180:183] offset:46080
	ds_read_b128 v[176:179], v208 offset:32
	ds_read_b128 v[180:183], v208 offset:4640
	s_waitcnt lgkmcnt(5)
	v_mfma_f32_32x32x16_bf16 v[80:95], v[234:237], v[226:229], v[80:95]
	v_mfma_f32_32x32x16_bf16 v[16:31], v[234:237], v[230:233], v[16:31]
	ds_read_b128 v[234:237], v192 offset:32
	s_waitcnt lgkmcnt(5)
	v_mfma_f32_32x32x16_bf16 v[64:79], v[238:241], v[226:229], v[64:79]
	v_mfma_f32_32x32x16_bf16 v[0:15], v[238:241], v[230:233], v[0:15]
	ds_read_b128 v[238:241], v192 offset:4640
	s_setprio 0
	global_load_dwordx4 v[226:229], v[194:195], off offset:896
	global_load_dwordx4 v[230:233], v[196:197], off offset:896
	s_setprio 1
	s_waitcnt lgkmcnt(1)
	v_mfma_f32_32x32x16_bf16 v[112:127], v[234:237], v[176:179], v[112:127]
	v_mfma_f32_32x32x16_bf16 v[48:63], v[234:237], v[180:183], v[48:63]
	s_waitcnt lgkmcnt(0)
	v_mfma_f32_32x32x16_bf16 v[96:111], v[238:241], v[176:179], v[96:111]
	v_mfma_f32_32x32x16_bf16 v[32:47], v[238:241], v[180:183], v[32:47]
	ds_read_b128 v[234:237], v192 offset:9248
	ds_read_b128 v[238:241], v192 offset:13856
	s_waitcnt vmcnt(7)
	ds_write_b128 v215, v[168:171] offset:18432
	s_waitcnt vmcnt(6)
	ds_write_b128 v215, v[172:175] offset:55296
	ds_read_b128 v[168:171], v208 offset:64
	ds_read_b128 v[172:175], v208 offset:4672
	s_waitcnt lgkmcnt(5)
	v_mfma_f32_32x32x16_bf16 v[80:95], v[234:237], v[176:179], v[80:95]
	v_mfma_f32_32x32x16_bf16 v[16:31], v[234:237], v[180:183], v[16:31]
	ds_read_b128 v[234:237], v192 offset:64
	s_waitcnt lgkmcnt(5)
	v_mfma_f32_32x32x16_bf16 v[64:79], v[238:241], v[176:179], v[64:79]
	v_mfma_f32_32x32x16_bf16 v[0:15], v[238:241], v[180:183], v[0:15]
	ds_read_b128 v[238:241], v192 offset:4672
	s_setprio 0
	global_load_dwordx4 v[176:179], v[184:185], off offset:896
	global_load_dwordx4 v[180:183], v[186:187], off offset:896
	s_setprio 1
	s_waitcnt lgkmcnt(1)
	v_mfma_f32_32x32x16_bf16 v[112:127], v[234:237], v[168:171], v[112:127]
	v_mfma_f32_32x32x16_bf16 v[48:63], v[234:237], v[172:175], v[48:63]
	s_waitcnt lgkmcnt(0)
	v_mfma_f32_32x32x16_bf16 v[96:111], v[238:241], v[168:171], v[96:111]
	v_mfma_f32_32x32x16_bf16 v[32:47], v[238:241], v[172:175], v[32:47]
	ds_read_b128 v[234:237], v192 offset:9280
	ds_read_b128 v[238:241], v192 offset:13888
	s_waitcnt vmcnt(7)
	ds_write_b128 v215, v[160:163] offset:27648
	s_waitcnt vmcnt(6)
	ds_write_b128 v215, v[164:167] offset:64512
	ds_read_b128 v[160:163], v208 offset:96
	ds_read_b128 v[164:167], v208 offset:4704
	s_waitcnt lgkmcnt(5)
	v_mfma_f32_32x32x16_bf16 v[80:95], v[234:237], v[168:171], v[80:95]
	v_mfma_f32_32x32x16_bf16 v[16:31], v[234:237], v[172:175], v[16:31]
	ds_read_b128 v[234:237], v192 offset:96
	s_waitcnt lgkmcnt(5)
	v_mfma_f32_32x32x16_bf16 v[64:79], v[238:241], v[168:171], v[64:79]
	v_mfma_f32_32x32x16_bf16 v[0:15], v[238:241], v[172:175], v[0:15]
	ds_read_b128 v[238:241], v192 offset:4704
	s_setprio 0
	global_load_dwordx4 v[168:171], v[198:199], off offset:896
	global_load_dwordx4 v[172:175], v[200:201], off offset:896
	s_setprio 1
	s_waitcnt lgkmcnt(1)
	v_mfma_f32_32x32x16_bf16 v[112:127], v[234:237], v[160:163], v[112:127]
	v_mfma_f32_32x32x16_bf16 v[48:63], v[234:237], v[164:167], v[48:63]
	s_waitcnt lgkmcnt(0)
	v_mfma_f32_32x32x16_bf16 v[96:111], v[238:241], v[160:163], v[96:111]
	v_mfma_f32_32x32x16_bf16 v[32:47], v[238:241], v[164:167], v[32:47]
	ds_read_b128 v[234:237], v192 offset:9312
	ds_read_b128 v[238:241], v192 offset:13920
	s_waitcnt lgkmcnt(0)
	s_barrier
; template <bool trans>
; DI void gemm_core(const GTile& tl, const GTile& nx, bool has_next  , bool chain  , bool pre, u32x4 (&ra)[4], u32x4 (&rb)[4], char* smem, f32x16 (&acc)[2][4]) {
;     ...
;   const int nk = K / 64;
;   if (!pre) { G_LOAD(0); G_STORE(0); G_LOAD(1); }
;   for (int kt = 0; kt < nk; ++kt) {
;     __syncthreads();
;     G_COMPUTE(kt & 1, kt);
;   }
	s_waitcnt vmcnt(7)
	ds_write_b128 v209, v[218:221]
	s_waitcnt vmcnt(6)
	ds_write_b128 v210, v[222:225]
	ds_read_b128 v[218:221], v205 offset:36864
	ds_read_b128 v[222:225], v205 offset:41472
	v_mfma_f32_32x32x16_bf16 v[80:95], v[234:237], v[160:163], v[80:95]
	v_mfma_f32_32x32x16_bf16 v[16:31], v[234:237], v[164:167], v[16:31]
	ds_read_b128 v[234:237], v204
	v_mfma_f32_32x32x16_bf16 v[64:79], v[238:241], v[160:163], v[64:79]
	v_mfma_f32_32x32x16_bf16 v[0:15], v[238:241], v[164:167], v[0:15]
	ds_read_b128 v[238:241], v204 offset:4608
	s_setprio 0
	global_load_dwordx4 v[160:163], v[190:191], off offset:1024
	global_load_dwordx4 v[164:167], v[188:189], off offset:1024
	s_setprio 1
	s_waitcnt lgkmcnt(1)
	v_mfma_f32_32x32x16_bf16 v[112:127], v[234:237], v[218:221], v[112:127]
	v_mfma_f32_32x32x16_bf16 v[48:63], v[234:237], v[222:225], v[48:63]
	s_waitcnt lgkmcnt(0)
	v_mfma_f32_32x32x16_bf16 v[96:111], v[238:241], v[218:221], v[96:111]
	v_mfma_f32_32x32x16_bf16 v[32:47], v[238:241], v[222:225], v[32:47]
	ds_read_b128 v[234:237], v204 offset:9216
	ds_read_b128 v[238:241], v204 offset:13824
	s_waitcnt vmcnt(7)
	ds_write_b128 v212, v[226:229]
	s_waitcnt vmcnt(6)
	ds_write_b128 v211, v[230:233]
	ds_read_b128 v[226:229], v205 offset:36896
	ds_read_b128 v[230:233], v205 offset:41504
	s_waitcnt lgkmcnt(5)
	v_mfma_f32_32x32x16_bf16 v[80:95], v[234:237], v[218:221], v[80:95]
	v_mfma_f32_32x32x16_bf16 v[16:31], v[234:237], v[222:225], v[16:31]
	ds_read_b128 v[234:237], v204 offset:32
	s_waitcnt lgkmcnt(5)
	v_mfma_f32_32x32x16_bf16 v[64:79], v[238:241], v[218:221], v[64:79]
	v_mfma_f32_32x32x16_bf16 v[0:15], v[238:241], v[222:225], v[0:15]
	ds_read_b128 v[238:241], v204 offset:4640
	s_setprio 0
	global_load_dwordx4 v[218:221], v[194:195], off offset:1024
	global_load_dwordx4 v[222:225], v[196:197], off offset:1024
	s_setprio 1
	s_waitcnt lgkmcnt(1)
	v_mfma_f32_32x32x16_bf16 v[112:127], v[234:237], v[226:229], v[112:127]
	v_mfma_f32_32x32x16_bf16 v[48:63], v[234:237], v[230:233], v[48:63]
	s_waitcnt lgkmcnt(0)
	v_mfma_f32_32x32x16_bf16 v[96:111], v[238:241], v[226:229], v[96:111]
	v_mfma_f32_32x32x16_bf16 v[32:47], v[238:241], v[230:233], v[32:47]
	ds_read_b128 v[234:237], v204 offset:9248
	ds_read_b128 v[238:241], v204 offset:13856
	s_waitcnt vmcnt(7)
	ds_write_b128 v214, v[176:179]
	s_waitcnt vmcnt(6)
	ds_write_b128 v213, v[180:183]
	ds_read_b128 v[176:179], v205 offset:36928
	ds_read_b128 v[180:183], v205 offset:41536
	s_waitcnt lgkmcnt(5)
	v_mfma_f32_32x32x16_bf16 v[80:95], v[234:237], v[226:229], v[80:95]
	v_mfma_f32_32x32x16_bf16 v[16:31], v[234:237], v[230:233], v[16:31]
	ds_read_b128 v[234:237], v204 offset:64
	s_waitcnt lgkmcnt(5)
	v_mfma_f32_32x32x16_bf16 v[64:79], v[238:241], v[226:229], v[64:79]
	v_mfma_f32_32x32x16_bf16 v[0:15], v[238:241], v[230:233], v[0:15]
	ds_read_b128 v[238:241], v204 offset:4672
	s_setprio 0
	global_load_dwordx4 v[226:229], v[184:185], off offset:1024
	global_load_dwordx4 v[230:233], v[186:187], off offset:1024
	s_setprio 1
	s_waitcnt lgkmcnt(1)
	v_mfma_f32_32x32x16_bf16 v[112:127], v[234:237], v[176:179], v[112:127]
	v_mfma_f32_32x32x16_bf16 v[48:63], v[234:237], v[180:183], v[48:63]
	s_waitcnt lgkmcnt(0)
	v_mfma_f32_32x32x16_bf16 v[96:111], v[238:241], v[176:179], v[96:111]
	v_mfma_f32_32x32x16_bf16 v[32:47], v[238:241], v[180:183], v[32:47]
	ds_read_b128 v[234:237], v204 offset:9280
	ds_read_b128 v[238:241], v204 offset:13888
	s_waitcnt vmcnt(7)
	ds_write_b128 v217, v[168:171]
	s_waitcnt vmcnt(6)
	ds_write_b128 v216, v[172:175]
	ds_read_b128 v[168:171], v205 offset:36960
	ds_read_b128 v[172:175], v205 offset:41568
	s_waitcnt lgkmcnt(5)
	v_mfma_f32_32x32x16_bf16 v[80:95], v[234:237], v[176:179], v[80:95]
	v_mfma_f32_32x32x16_bf16 v[16:31], v[234:237], v[180:183], v[16:31]
	ds_read_b128 v[234:237], v204 offset:96
	s_waitcnt lgkmcnt(5)
	v_mfma_f32_32x32x16_bf16 v[64:79], v[238:241], v[176:179], v[64:79]
	v_mfma_f32_32x32x16_bf16 v[0:15], v[238:241], v[180:183], v[0:15]
	ds_read_b128 v[238:241], v204 offset:4704
	s_setprio 0
	global_load_dwordx4 v[176:179], v[198:199], off offset:1024
	global_load_dwordx4 v[180:183], v[200:201], off offset:1024
	s_setprio 1
	s_waitcnt lgkmcnt(1)
	v_mfma_f32_32x32x16_bf16 v[112:127], v[234:237], v[168:171], v[112:127]
	v_mfma_f32_32x32x16_bf16 v[48:63], v[234:237], v[172:175], v[48:63]
	s_waitcnt lgkmcnt(0)
	v_mfma_f32_32x32x16_bf16 v[96:111], v[238:241], v[168:171], v[96:111]
	v_mfma_f32_32x32x16_bf16 v[32:47], v[238:241], v[172:175], v[32:47]
	ds_read_b128 v[234:237], v204 offset:9312
	ds_read_b128 v[238:241], v204 offset:13920
	s_waitcnt lgkmcnt(0)
	s_barrier
; template <bool trans>
; DI void gemm_core(const GTile& tl, const GTile& nx, bool has_next  , bool chain  , bool pre, u32x4 (&ra)[4], u32x4 (&rb)[4], char* smem, f32x16 (&acc)[2][4]) {
;     ...
;   const int nk = K / 64;
;   if (!pre) { G_LOAD(0); G_STORE(0); G_LOAD(1); }
;   for (int kt = 0; kt < nk; ++kt) {
;     __syncthreads();
;     G_COMPUTE(kt & 1, kt);
;   }
	s_waitcnt vmcnt(7)
	ds_write_b128 v215, v[160:163]
	s_waitcnt vmcnt(6)
	ds_write_b128 v215, v[164:167] offset:36864
	ds_read_b128 v[160:163], v208
	ds_read_b128 v[164:167], v208 offset:4608
	v_mfma_f32_32x32x16_bf16 v[80:95], v[234:237], v[168:171], v[80:95]
	v_mfma_f32_32x32x16_bf16 v[16:31], v[234:237], v[172:175], v[16:31]
	ds_read_b128 v[234:237], v192
	v_mfma_f32_32x32x16_bf16 v[64:79], v[238:241], v[168:171], v[64:79]
	v_mfma_f32_32x32x16_bf16 v[0:15], v[238:241], v[172:175], v[0:15]
	ds_read_b128 v[238:241], v192 offset:4608
	s_setprio 0
	global_load_dwordx4 v[168:171], v[190:191], off offset:1152
	global_load_dwordx4 v[172:175], v[188:189], off offset:1152
	s_setprio 1
	s_waitcnt lgkmcnt(1)
	v_mfma_f32_32x32x16_bf16 v[112:127], v[234:237], v[160:163], v[112:127]
	v_mfma_f32_32x32x16_bf16 v[48:63], v[234:237], v[164:167], v[48:63]
	s_waitcnt lgkmcnt(0)
	v_mfma_f32_32x32x16_bf16 v[96:111], v[238:241], v[160:163], v[96:111]
	v_mfma_f32_32x32x16_bf16 v[32:47], v[238:241], v[164:167], v[32:47]
	ds_read_b128 v[234:237], v192 offset:9216
	ds_read_b128 v[238:241], v192 offset:13824
	s_waitcnt vmcnt(7)
	ds_write_b128 v215, v[218:221] offset:9216
	s_waitcnt vmcnt(6)
	ds_write_b128 v215, v[222:225] offset:46080
	ds_read_b128 v[218:221], v208 offset:32
	ds_read_b128 v[222:225], v208 offset:4640
	s_waitcnt lgkmcnt(5)
	v_mfma_f32_32x32x16_bf16 v[80:95], v[234:237], v[160:163], v[80:95]
	v_mfma_f32_32x32x16_bf16 v[16:31], v[234:237], v[164:167], v[16:31]
	ds_read_b128 v[234:237], v192 offset:32
	s_waitcnt lgkmcnt(5)
	v_mfma_f32_32x32x16_bf16 v[64:79], v[238:241], v[160:163], v[64:79]
	v_mfma_f32_32x32x16_bf16 v[0:15], v[238:241], v[164:167], v[0:15]
	ds_read_b128 v[238:241], v192 offset:4640
	s_setprio 0
	global_load_dwordx4 v[160:163], v[194:195], off offset:1152
	global_load_dwordx4 v[164:167], v[196:197], off offset:1152
	s_setprio 1
	s_waitcnt lgkmcnt(1)
	v_mfma_f32_32x32x16_bf16 v[112:127], v[234:237], v[218:221], v[112:127]
	v_mfma_f32_32x32x16_bf16 v[48:63], v[234:237], v[222:225], v[48:63]
	s_waitcnt lgkmcnt(0)
	v_mfma_f32_32x32x16_bf16 v[96:111], v[238:241], v[218:221], v[96:111]
	v_mfma_f32_32x32x16_bf16 v[32:47], v[238:241], v[222:225], v[32:47]
	ds_read_b128 v[234:237], v192 offset:9248
	ds_read_b128 v[238:241], v192 offset:13856
	s_waitcnt vmcnt(7)
	ds_write_b128 v215, v[226:229] offset:18432
	s_waitcnt vmcnt(6)
	ds_write_b128 v215, v[230:233] offset:55296
	ds_read_b128 v[226:229], v208 offset:64
	ds_read_b128 v[230:233], v208 offset:4672
	s_waitcnt lgkmcnt(5)
	v_mfma_f32_32x32x16_bf16 v[80:95], v[234:237], v[218:221], v[80:95]
	v_mfma_f32_32x32x16_bf16 v[16:31], v[234:237], v[222:225], v[16:31]
	ds_read_b128 v[234:237], v192 offset:64
	s_waitcnt lgkmcnt(5)
	v_mfma_f32_32x32x16_bf16 v[64:79], v[238:241], v[218:221], v[64:79]
	v_mfma_f32_32x32x16_bf16 v[0:15], v[238:241], v[222:225], v[0:15]
	ds_read_b128 v[238:241], v192 offset:4672
	s_setprio 0
	global_load_dwordx4 v[218:221], v[184:185], off offset:1152
	global_load_dwordx4 v[222:225], v[186:187], off offset:1152
	s_setprio 1
	s_waitcnt lgkmcnt(1)
	v_mfma_f32_32x32x16_bf16 v[112:127], v[234:237], v[226:229], v[112:127]
	v_mfma_f32_32x32x16_bf16 v[48:63], v[234:237], v[230:233], v[48:63]
	s_waitcnt lgkmcnt(0)
	v_mfma_f32_32x32x16_bf16 v[96:111], v[238:241], v[226:229], v[96:111]
	v_mfma_f32_32x32x16_bf16 v[32:47], v[238:241], v[230:233], v[32:47]
	ds_read_b128 v[234:237], v192 offset:9280
	ds_read_b128 v[238:241], v192 offset:13888
	s_waitcnt vmcnt(7)
	ds_write_b128 v215, v[176:179] offset:27648
	s_waitcnt vmcnt(6)
	ds_write_b128 v215, v[180:183] offset:64512
	ds_read_b128 v[176:179], v208 offset:96
	ds_read_b128 v[180:183], v208 offset:4704
	s_waitcnt lgkmcnt(5)
	v_mfma_f32_32x32x16_bf16 v[80:95], v[234:237], v[226:229], v[80:95]
	v_mfma_f32_32x32x16_bf16 v[16:31], v[234:237], v[230:233], v[16:31]
	ds_read_b128 v[234:237], v192 offset:96
	s_waitcnt lgkmcnt(5)
	v_mfma_f32_32x32x16_bf16 v[64:79], v[238:241], v[226:229], v[64:79]
	v_mfma_f32_32x32x16_bf16 v[0:15], v[238:241], v[230:233], v[0:15]
	ds_read_b128 v[238:241], v192 offset:4704
	s_setprio 0
	global_load_dwordx4 v[226:229], v[198:199], off offset:1152
	global_load_dwordx4 v[230:233], v[200:201], off offset:1152
	s_setprio 1
	s_waitcnt lgkmcnt(1)
	v_mfma_f32_32x32x16_bf16 v[112:127], v[234:237], v[176:179], v[112:127]
	v_mfma_f32_32x32x16_bf16 v[48:63], v[234:237], v[180:183], v[48:63]
	s_waitcnt lgkmcnt(0)
	v_mfma_f32_32x32x16_bf16 v[96:111], v[238:241], v[176:179], v[96:111]
	v_mfma_f32_32x32x16_bf16 v[32:47], v[238:241], v[180:183], v[32:47]
	ds_read_b128 v[234:237], v192 offset:9312
	ds_read_b128 v[238:241], v192 offset:13920
	s_waitcnt lgkmcnt(0)
	s_barrier
; template <bool trans>
; DI void gemm_core(const GTile& tl, const GTile& nx, bool has_next  , bool chain  , bool pre, u32x4 (&ra)[4], u32x4 (&rb)[4], char* smem, f32x16 (&acc)[2][4]) {
;     ...
;   const int nk = K / 64;
;   if (!pre) { G_LOAD(0); G_STORE(0); G_LOAD(1); }
;   for (int kt = 0; kt < nk; ++kt) {
;     __syncthreads();
;     G_COMPUTE(kt & 1, kt);
;   }
	s_waitcnt vmcnt(7)
	ds_write_b128 v209, v[168:171]
	s_waitcnt vmcnt(6)
	ds_write_b128 v210, v[172:175]
	ds_read_b128 v[168:171], v205 offset:36864
	ds_read_b128 v[172:175], v205 offset:41472
	v_mfma_f32_32x32x16_bf16 v[80:95], v[234:237], v[176:179], v[80:95]
	v_mfma_f32_32x32x16_bf16 v[16:31], v[234:237], v[180:183], v[16:31]
	ds_read_b128 v[234:237], v204
	v_mfma_f32_32x32x16_bf16 v[64:79], v[238:241], v[176:179], v[64:79]
	v_mfma_f32_32x32x16_bf16 v[0:15], v[238:241], v[180:183], v[0:15]
	ds_read_b128 v[238:241], v204 offset:4608
	s_setprio 0
	global_load_dwordx4 v[176:179], v[190:191], off offset:1280
	global_load_dwordx4 v[180:183], v[188:189], off offset:1280
	s_setprio 1
	s_waitcnt lgkmcnt(1)
	v_mfma_f32_32x32x16_bf16 v[112:127], v[234:237], v[168:171], v[112:127]
	v_mfma_f32_32x32x16_bf16 v[48:63], v[234:237], v[172:175], v[48:63]
	s_waitcnt lgkmcnt(0)
	v_mfma_f32_32x32x16_bf16 v[96:111], v[238:241], v[168:171], v[96:111]
	v_mfma_f32_32x32x16_bf16 v[32:47], v[238:241], v[172:175], v[32:47]
	ds_read_b128 v[234:237], v204 offset:9216
	ds_read_b128 v[238:241], v204 offset:13824
	s_waitcnt vmcnt(7)
	ds_write_b128 v212, v[160:163]
	s_waitcnt vmcnt(6)
	ds_write_b128 v211, v[164:167]
	ds_read_b128 v[160:163], v205 offset:36896
	ds_read_b128 v[164:167], v205 offset:41504
	s_waitcnt lgkmcnt(5)
	v_mfma_f32_32x32x16_bf16 v[80:95], v[234:237], v[168:171], v[80:95]
	v_mfma_f32_32x32x16_bf16 v[16:31], v[234:237], v[172:175], v[16:31]
	ds_read_b128 v[234:237], v204 offset:32
	s_waitcnt lgkmcnt(5)
	v_mfma_f32_32x32x16_bf16 v[64:79], v[238:241], v[168:171], v[64:79]
	v_mfma_f32_32x32x16_bf16 v[0:15], v[238:241], v[172:175], v[0:15]
	ds_read_b128 v[238:241], v204 offset:4640
	s_setprio 0
	global_load_dwordx4 v[168:171], v[194:195], off offset:1280
	global_load_dwordx4 v[172:175], v[196:197], off offset:1280
	s_setprio 1
	s_waitcnt lgkmcnt(1)
	v_mfma_f32_32x32x16_bf16 v[112:127], v[234:237], v[160:163], v[112:127]
	v_mfma_f32_32x32x16_bf16 v[48:63], v[234:237], v[164:167], v[48:63]
	s_waitcnt lgkmcnt(0)
	v_mfma_f32_32x32x16_bf16 v[96:111], v[238:241], v[160:163], v[96:111]
	v_mfma_f32_32x32x16_bf16 v[32:47], v[238:241], v[164:167], v[32:47]
	ds_read_b128 v[234:237], v204 offset:9248
	ds_read_b128 v[238:241], v204 offset:13856
	s_waitcnt vmcnt(7)
	ds_write_b128 v214, v[218:221]
	s_waitcnt vmcnt(6)
	ds_write_b128 v213, v[222:225]
	ds_read_b128 v[218:221], v205 offset:36928
	ds_read_b128 v[222:225], v205 offset:41536
	s_waitcnt lgkmcnt(5)
	v_mfma_f32_32x32x16_bf16 v[80:95], v[234:237], v[160:163], v[80:95]
	v_mfma_f32_32x32x16_bf16 v[16:31], v[234:237], v[164:167], v[16:31]
	ds_read_b128 v[234:237], v204 offset:64
	s_waitcnt lgkmcnt(5)
	v_mfma_f32_32x32x16_bf16 v[64:79], v[238:241], v[160:163], v[64:79]
	v_mfma_f32_32x32x16_bf16 v[0:15], v[238:241], v[164:167], v[0:15]
	ds_read_b128 v[238:241], v204 offset:4672
	s_setprio 0
	global_load_dwordx4 v[160:163], v[184:185], off offset:1280
	global_load_dwordx4 v[164:167], v[186:187], off offset:1280
	s_setprio 1
	s_waitcnt lgkmcnt(1)
	v_mfma_f32_32x32x16_bf16 v[112:127], v[234:237], v[218:221], v[112:127]
	v_mfma_f32_32x32x16_bf16 v[48:63], v[234:237], v[222:225], v[48:63]
	s_waitcnt lgkmcnt(0)
	v_mfma_f32_32x32x16_bf16 v[96:111], v[238:241], v[218:221], v[96:111]
	v_mfma_f32_32x32x16_bf16 v[32:47], v[238:241], v[222:225], v[32:47]
	ds_read_b128 v[234:237], v204 offset:9280
	ds_read_b128 v[238:241], v204 offset:13888
	s_waitcnt vmcnt(7)
	ds_write_b128 v217, v[226:229]
	s_waitcnt vmcnt(6)
	ds_write_b128 v216, v[230:233]
	ds_read_b128 v[226:229], v205 offset:36960
	ds_read_b128 v[230:233], v205 offset:41568
	s_waitcnt lgkmcnt(5)
	v_mfma_f32_32x32x16_bf16 v[80:95], v[234:237], v[218:221], v[80:95]
	v_mfma_f32_32x32x16_bf16 v[16:31], v[234:237], v[222:225], v[16:31]
	ds_read_b128 v[234:237], v204 offset:96
	s_waitcnt lgkmcnt(5)
	v_mfma_f32_32x32x16_bf16 v[64:79], v[238:241], v[218:221], v[64:79]
	v_mfma_f32_32x32x16_bf16 v[0:15], v[238:241], v[222:225], v[0:15]
	ds_read_b128 v[238:241], v204 offset:4704
	s_setprio 0
	global_load_dwordx4 v[218:221], v[198:199], off offset:1280
	global_load_dwordx4 v[222:225], v[200:201], off offset:1280
	s_setprio 1
	s_waitcnt lgkmcnt(1)
	v_mfma_f32_32x32x16_bf16 v[112:127], v[234:237], v[226:229], v[112:127]
	v_mfma_f32_32x32x16_bf16 v[48:63], v[234:237], v[230:233], v[48:63]
	s_waitcnt lgkmcnt(0)
	v_mfma_f32_32x32x16_bf16 v[96:111], v[238:241], v[226:229], v[96:111]
	v_mfma_f32_32x32x16_bf16 v[32:47], v[238:241], v[230:233], v[32:47]
	ds_read_b128 v[234:237], v204 offset:9312
	ds_read_b128 v[238:241], v204 offset:13920
	s_waitcnt lgkmcnt(0)
	s_barrier
; template <bool trans>
; DI void gemm_core(const GTile& tl, const GTile& nx, bool has_next  , bool chain  , bool pre, u32x4 (&ra)[4], u32x4 (&rb)[4], char* smem, f32x16 (&acc)[2][4]) {
;     ...
;   const int nk = K / 64;
;   if (!pre) { G_LOAD(0); G_STORE(0); G_LOAD(1); }
;   for (int kt = 0; kt < nk; ++kt) {
;     __syncthreads();
;     G_COMPUTE(kt & 1, kt);
;   }
	s_waitcnt vmcnt(7)
	ds_write_b128 v215, v[176:179]
	s_waitcnt vmcnt(6)
	ds_write_b128 v215, v[180:183] offset:36864
	ds_read_b128 v[176:179], v208
	ds_read_b128 v[180:183], v208 offset:4608
	v_mfma_f32_32x32x16_bf16 v[80:95], v[234:237], v[226:229], v[80:95]
	v_mfma_f32_32x32x16_bf16 v[16:31], v[234:237], v[230:233], v[16:31]
	ds_read_b128 v[234:237], v192
	v_mfma_f32_32x32x16_bf16 v[64:79], v[238:241], v[226:229], v[64:79]
	v_mfma_f32_32x32x16_bf16 v[0:15], v[238:241], v[230:233], v[0:15]
	ds_read_b128 v[238:241], v192 offset:4608
	s_setprio 0
	global_load_dwordx4 v[226:229], v[190:191], off offset:1408
	global_load_dwordx4 v[230:233], v[188:189], off offset:1408
	s_setprio 1
	s_waitcnt lgkmcnt(1)
	v_mfma_f32_32x32x16_bf16 v[112:127], v[234:237], v[176:179], v[112:127]
	v_mfma_f32_32x32x16_bf16 v[48:63], v[234:237], v[180:183], v[48:63]
	s_waitcnt lgkmcnt(0)
	v_mfma_f32_32x32x16_bf16 v[96:111], v[238:241], v[176:179], v[96:111]
	v_mfma_f32_32x32x16_bf16 v[32:47], v[238:241], v[180:183], v[32:47]
	ds_read_b128 v[234:237], v192 offset:9216
	ds_read_b128 v[238:241], v192 offset:13824
	s_waitcnt vmcnt(7)
	ds_write_b128 v215, v[168:171] offset:9216
	s_waitcnt vmcnt(6)
	ds_write_b128 v215, v[172:175] offset:46080
	ds_read_b128 v[168:171], v208 offset:32
	ds_read_b128 v[172:175], v208 offset:4640
	s_waitcnt lgkmcnt(5)
	v_mfma_f32_32x32x16_bf16 v[80:95], v[234:237], v[176:179], v[80:95]
	v_mfma_f32_32x32x16_bf16 v[16:31], v[234:237], v[180:183], v[16:31]
	ds_read_b128 v[234:237], v192 offset:32
	s_waitcnt lgkmcnt(5)
	v_mfma_f32_32x32x16_bf16 v[64:79], v[238:241], v[176:179], v[64:79]
	v_mfma_f32_32x32x16_bf16 v[0:15], v[238:241], v[180:183], v[0:15]
	ds_read_b128 v[238:241], v192 offset:4640
	s_setprio 0
	global_load_dwordx4 v[176:179], v[194:195], off offset:1408
	global_load_dwordx4 v[180:183], v[196:197], off offset:1408
	s_setprio 1
	s_waitcnt lgkmcnt(1)
	v_mfma_f32_32x32x16_bf16 v[112:127], v[234:237], v[168:171], v[112:127]
	v_mfma_f32_32x32x16_bf16 v[48:63], v[234:237], v[172:175], v[48:63]
	s_waitcnt lgkmcnt(0)
	v_mfma_f32_32x32x16_bf16 v[96:111], v[238:241], v[168:171], v[96:111]
	v_mfma_f32_32x32x16_bf16 v[32:47], v[238:241], v[172:175], v[32:47]
	ds_read_b128 v[234:237], v192 offset:9248
	ds_read_b128 v[238:241], v192 offset:13856
	s_waitcnt vmcnt(7)
	ds_write_b128 v215, v[160:163] offset:18432
	s_waitcnt vmcnt(6)
	ds_write_b128 v215, v[164:167] offset:55296
	ds_read_b128 v[160:163], v208 offset:64
	ds_read_b128 v[164:167], v208 offset:4672
	s_waitcnt lgkmcnt(5)
	v_mfma_f32_32x32x16_bf16 v[80:95], v[234:237], v[168:171], v[80:95]
	v_mfma_f32_32x32x16_bf16 v[16:31], v[234:237], v[172:175], v[16:31]
	ds_read_b128 v[234:237], v192 offset:64
	s_waitcnt lgkmcnt(5)
	v_mfma_f32_32x32x16_bf16 v[64:79], v[238:241], v[168:171], v[64:79]
	v_mfma_f32_32x32x16_bf16 v[0:15], v[238:241], v[172:175], v[0:15]
	ds_read_b128 v[238:241], v192 offset:4672
	s_setprio 0
	global_load_dwordx4 v[168:171], v[184:185], off offset:1408
	global_load_dwordx4 v[172:175], v[186:187], off offset:1408
	s_setprio 1
	s_waitcnt lgkmcnt(1)
	v_mfma_f32_32x32x16_bf16 v[112:127], v[234:237], v[160:163], v[112:127]
	v_mfma_f32_32x32x16_bf16 v[48:63], v[234:237], v[164:167], v[48:63]
	s_waitcnt lgkmcnt(0)
	v_mfma_f32_32x32x16_bf16 v[96:111], v[238:241], v[160:163], v[96:111]
	v_mfma_f32_32x32x16_bf16 v[32:47], v[238:241], v[164:167], v[32:47]
	ds_read_b128 v[234:237], v192 offset:9280
	ds_read_b128 v[238:241], v192 offset:13888
	s_waitcnt vmcnt(7)
	ds_write_b128 v215, v[218:221] offset:27648
	s_waitcnt vmcnt(6)
	ds_write_b128 v215, v[222:225] offset:64512
	ds_read_b128 v[218:221], v208 offset:96
	ds_read_b128 v[222:225], v208 offset:4704
	s_waitcnt lgkmcnt(5)
	v_mfma_f32_32x32x16_bf16 v[80:95], v[234:237], v[160:163], v[80:95]
	v_mfma_f32_32x32x16_bf16 v[16:31], v[234:237], v[164:167], v[16:31]
	ds_read_b128 v[234:237], v192 offset:96
	s_waitcnt lgkmcnt(5)
	v_mfma_f32_32x32x16_bf16 v[64:79], v[238:241], v[160:163], v[64:79]
	v_mfma_f32_32x32x16_bf16 v[0:15], v[238:241], v[164:167], v[0:15]
	ds_read_b128 v[238:241], v192 offset:4704
	s_setprio 0
	global_load_dwordx4 v[160:163], v[198:199], off offset:1408
	global_load_dwordx4 v[164:167], v[200:201], off offset:1408
	s_setprio 1
	s_waitcnt lgkmcnt(1)
	v_mfma_f32_32x32x16_bf16 v[112:127], v[234:237], v[218:221], v[112:127]
	v_mfma_f32_32x32x16_bf16 v[48:63], v[234:237], v[222:225], v[48:63]
	s_waitcnt lgkmcnt(0)
	v_mfma_f32_32x32x16_bf16 v[96:111], v[238:241], v[218:221], v[96:111]
	v_mfma_f32_32x32x16_bf16 v[32:47], v[238:241], v[222:225], v[32:47]
	ds_read_b128 v[234:237], v192 offset:9312
	ds_read_b128 v[238:241], v192 offset:13920
	s_waitcnt lgkmcnt(0)
	s_barrier
; template <bool trans>
; DI void gemm_core(const GTile& tl, const GTile& nx, bool has_next  , bool chain  , bool pre, u32x4 (&ra)[4], u32x4 (&rb)[4], char* smem, f32x16 (&acc)[2][4]) {
;     ...
;   const int nk = K / 64;
;   if (!pre) { G_LOAD(0); G_STORE(0); G_LOAD(1); }
;   for (int kt = 0; kt < nk; ++kt) {
;     __syncthreads();
;     G_COMPUTE(kt & 1, kt);
;   }
	s_waitcnt vmcnt(7)
	ds_write_b128 v209, v[226:229]
	s_waitcnt vmcnt(6)
	ds_write_b128 v210, v[230:233]
	ds_read_b128 v[226:229], v205 offset:36864
	ds_read_b128 v[230:233], v205 offset:41472
	v_mfma_f32_32x32x16_bf16 v[80:95], v[234:237], v[218:221], v[80:95]
	v_mfma_f32_32x32x16_bf16 v[16:31], v[234:237], v[222:225], v[16:31]
	ds_read_b128 v[234:237], v204
	v_mfma_f32_32x32x16_bf16 v[64:79], v[238:241], v[218:221], v[64:79]
	v_mfma_f32_32x32x16_bf16 v[0:15], v[238:241], v[222:225], v[0:15]
	ds_read_b128 v[238:241], v204 offset:4608
	s_setprio 0
	global_load_dwordx4 v[218:221], v[190:191], off offset:1536
	global_load_dwordx4 v[222:225], v[188:189], off offset:1536
	s_setprio 1
	s_waitcnt lgkmcnt(1)
	v_mfma_f32_32x32x16_bf16 v[112:127], v[234:237], v[226:229], v[112:127]
	v_mfma_f32_32x32x16_bf16 v[48:63], v[234:237], v[230:233], v[48:63]
	s_waitcnt lgkmcnt(0)
	v_mfma_f32_32x32x16_bf16 v[96:111], v[238:241], v[226:229], v[96:111]
	v_mfma_f32_32x32x16_bf16 v[32:47], v[238:241], v[230:233], v[32:47]
	ds_read_b128 v[234:237], v204 offset:9216
	ds_read_b128 v[238:241], v204 offset:13824
	s_waitcnt vmcnt(7)
	ds_write_b128 v212, v[176:179]
	s_waitcnt vmcnt(6)
	ds_write_b128 v211, v[180:183]
	ds_read_b128 v[176:179], v205 offset:36896
	ds_read_b128 v[180:183], v205 offset:41504
	s_waitcnt lgkmcnt(5)
	v_mfma_f32_32x32x16_bf16 v[80:95], v[234:237], v[226:229], v[80:95]
	v_mfma_f32_32x32x16_bf16 v[16:31], v[234:237], v[230:233], v[16:31]
	ds_read_b128 v[234:237], v204 offset:32
	s_waitcnt lgkmcnt(5)
	v_mfma_f32_32x32x16_bf16 v[64:79], v[238:241], v[226:229], v[64:79]
	v_mfma_f32_32x32x16_bf16 v[0:15], v[238:241], v[230:233], v[0:15]
	ds_read_b128 v[238:241], v204 offset:4640
	s_setprio 0
	global_load_dwordx4 v[226:229], v[194:195], off offset:1536
	global_load_dwordx4 v[230:233], v[196:197], off offset:1536
	s_setprio 1
	s_waitcnt lgkmcnt(1)
	v_mfma_f32_32x32x16_bf16 v[112:127], v[234:237], v[176:179], v[112:127]
	v_mfma_f32_32x32x16_bf16 v[48:63], v[234:237], v[180:183], v[48:63]
	s_waitcnt lgkmcnt(0)
	v_mfma_f32_32x32x16_bf16 v[96:111], v[238:241], v[176:179], v[96:111]
	v_mfma_f32_32x32x16_bf16 v[32:47], v[238:241], v[180:183], v[32:47]
	ds_read_b128 v[234:237], v204 offset:9248
	ds_read_b128 v[238:241], v204 offset:13856
	s_waitcnt vmcnt(7)
	ds_write_b128 v214, v[168:171]
	s_waitcnt vmcnt(6)
	ds_write_b128 v213, v[172:175]
	ds_read_b128 v[168:171], v205 offset:36928
	ds_read_b128 v[172:175], v205 offset:41536
	s_waitcnt lgkmcnt(5)
	v_mfma_f32_32x32x16_bf16 v[80:95], v[234:237], v[176:179], v[80:95]
	v_mfma_f32_32x32x16_bf16 v[16:31], v[234:237], v[180:183], v[16:31]
	ds_read_b128 v[234:237], v204 offset:64
	s_waitcnt lgkmcnt(5)
	v_mfma_f32_32x32x16_bf16 v[64:79], v[238:241], v[176:179], v[64:79]
	v_mfma_f32_32x32x16_bf16 v[0:15], v[238:241], v[180:183], v[0:15]
	ds_read_b128 v[238:241], v204 offset:4672
	s_setprio 0
	global_load_dwordx4 v[176:179], v[184:185], off offset:1536
	global_load_dwordx4 v[180:183], v[186:187], off offset:1536
	s_setprio 1
	s_waitcnt lgkmcnt(1)
	v_mfma_f32_32x32x16_bf16 v[112:127], v[234:237], v[168:171], v[112:127]
	v_mfma_f32_32x32x16_bf16 v[48:63], v[234:237], v[172:175], v[48:63]
	s_waitcnt lgkmcnt(0)
	v_mfma_f32_32x32x16_bf16 v[96:111], v[238:241], v[168:171], v[96:111]
	v_mfma_f32_32x32x16_bf16 v[32:47], v[238:241], v[172:175], v[32:47]
	ds_read_b128 v[234:237], v204 offset:9280
	ds_read_b128 v[238:241], v204 offset:13888
	s_waitcnt vmcnt(7)
	ds_write_b128 v217, v[160:163]
	s_waitcnt vmcnt(6)
	ds_write_b128 v216, v[164:167]
	ds_read_b128 v[160:163], v205 offset:36960
	ds_read_b128 v[164:167], v205 offset:41568
	s_waitcnt lgkmcnt(5)
	v_mfma_f32_32x32x16_bf16 v[80:95], v[234:237], v[168:171], v[80:95]
	v_mfma_f32_32x32x16_bf16 v[16:31], v[234:237], v[172:175], v[16:31]
	ds_read_b128 v[234:237], v204 offset:96
	s_waitcnt lgkmcnt(5)
	v_mfma_f32_32x32x16_bf16 v[64:79], v[238:241], v[168:171], v[64:79]
	v_mfma_f32_32x32x16_bf16 v[0:15], v[238:241], v[172:175], v[0:15]
	ds_read_b128 v[238:241], v204 offset:4704
	s_setprio 0
	global_load_dwordx4 v[168:171], v[198:199], off offset:1536
	global_load_dwordx4 v[172:175], v[200:201], off offset:1536
	s_setprio 1
	s_waitcnt lgkmcnt(1)
	v_mfma_f32_32x32x16_bf16 v[112:127], v[234:237], v[160:163], v[112:127]
	v_mfma_f32_32x32x16_bf16 v[48:63], v[234:237], v[164:167], v[48:63]
	s_waitcnt lgkmcnt(0)
	v_mfma_f32_32x32x16_bf16 v[96:111], v[238:241], v[160:163], v[96:111]
	v_mfma_f32_32x32x16_bf16 v[32:47], v[238:241], v[164:167], v[32:47]
	ds_read_b128 v[234:237], v204 offset:9312
	ds_read_b128 v[238:241], v204 offset:13920
	s_waitcnt lgkmcnt(0)
	s_barrier
; template <bool trans>
; DI void gemm_core(const GTile& tl, const GTile& nx, bool has_next  , bool chain  , bool pre, u32x4 (&ra)[4], u32x4 (&rb)[4], char* smem, f32x16 (&acc)[2][4]) {
;     ...
;   const int nk = K / 64;
;   if (!pre) { G_LOAD(0); G_STORE(0); G_LOAD(1); }
;   for (int kt = 0; kt < nk; ++kt) {
;     __syncthreads();
;     G_COMPUTE(kt & 1, kt);
;   }
	s_waitcnt vmcnt(7)
	ds_write_b128 v215, v[218:221]
	s_waitcnt vmcnt(6)
	ds_write_b128 v215, v[222:225] offset:36864
	ds_read_b128 v[218:221], v208
	ds_read_b128 v[222:225], v208 offset:4608
	v_mfma_f32_32x32x16_bf16 v[80:95], v[234:237], v[160:163], v[80:95]
	v_mfma_f32_32x32x16_bf16 v[16:31], v[234:237], v[164:167], v[16:31]
	ds_read_b128 v[234:237], v192
	v_mfma_f32_32x32x16_bf16 v[64:79], v[238:241], v[160:163], v[64:79]
	v_mfma_f32_32x32x16_bf16 v[0:15], v[238:241], v[164:167], v[0:15]
	ds_read_b128 v[238:241], v192 offset:4608
	s_setprio 0
	global_load_dwordx4 v[160:163], v[190:191], off offset:1664
	global_load_dwordx4 v[164:167], v[188:189], off offset:1664
	s_setprio 1
	s_waitcnt lgkmcnt(1)
	v_mfma_f32_32x32x16_bf16 v[112:127], v[234:237], v[218:221], v[112:127]
	v_mfma_f32_32x32x16_bf16 v[48:63], v[234:237], v[222:225], v[48:63]
	s_waitcnt lgkmcnt(0)
	v_mfma_f32_32x32x16_bf16 v[96:111], v[238:241], v[218:221], v[96:111]
	v_mfma_f32_32x32x16_bf16 v[32:47], v[238:241], v[222:225], v[32:47]
	ds_read_b128 v[234:237], v192 offset:9216
	ds_read_b128 v[238:241], v192 offset:13824
	s_waitcnt vmcnt(7)
	ds_write_b128 v215, v[226:229] offset:9216
	s_waitcnt vmcnt(6)
	ds_write_b128 v215, v[230:233] offset:46080
	ds_read_b128 v[226:229], v208 offset:32
	ds_read_b128 v[230:233], v208 offset:4640
	s_waitcnt lgkmcnt(5)
	v_mfma_f32_32x32x16_bf16 v[80:95], v[234:237], v[218:221], v[80:95]
	v_mfma_f32_32x32x16_bf16 v[16:31], v[234:237], v[222:225], v[16:31]
	ds_read_b128 v[234:237], v192 offset:32
	s_waitcnt lgkmcnt(5)
	v_mfma_f32_32x32x16_bf16 v[64:79], v[238:241], v[218:221], v[64:79]
	v_mfma_f32_32x32x16_bf16 v[0:15], v[238:241], v[222:225], v[0:15]
	ds_read_b128 v[238:241], v192 offset:4640
	s_setprio 0
	global_load_dwordx4 v[218:221], v[194:195], off offset:1664
	global_load_dwordx4 v[222:225], v[196:197], off offset:1664
	s_setprio 1
	s_waitcnt lgkmcnt(1)
	v_mfma_f32_32x32x16_bf16 v[112:127], v[234:237], v[226:229], v[112:127]
	v_mfma_f32_32x32x16_bf16 v[48:63], v[234:237], v[230:233], v[48:63]
	s_waitcnt lgkmcnt(0)
	v_mfma_f32_32x32x16_bf16 v[96:111], v[238:241], v[226:229], v[96:111]
	v_mfma_f32_32x32x16_bf16 v[32:47], v[238:241], v[230:233], v[32:47]
	ds_read_b128 v[234:237], v192 offset:9248
	ds_read_b128 v[238:241], v192 offset:13856
	s_waitcnt vmcnt(7)
	ds_write_b128 v215, v[176:179] offset:18432
	s_waitcnt vmcnt(6)
	ds_write_b128 v215, v[180:183] offset:55296
	ds_read_b128 v[176:179], v208 offset:64
	ds_read_b128 v[180:183], v208 offset:4672
	s_waitcnt lgkmcnt(5)
	v_mfma_f32_32x32x16_bf16 v[80:95], v[234:237], v[226:229], v[80:95]
	v_mfma_f32_32x32x16_bf16 v[16:31], v[234:237], v[230:233], v[16:31]
	ds_read_b128 v[234:237], v192 offset:64
	s_waitcnt lgkmcnt(5)
	v_mfma_f32_32x32x16_bf16 v[64:79], v[238:241], v[226:229], v[64:79]
	v_mfma_f32_32x32x16_bf16 v[0:15], v[238:241], v[230:233], v[0:15]
	ds_read_b128 v[238:241], v192 offset:4672
	s_setprio 0
	global_load_dwordx4 v[226:229], v[184:185], off offset:1664
	global_load_dwordx4 v[230:233], v[186:187], off offset:1664
	s_setprio 1
	s_waitcnt lgkmcnt(1)
	v_mfma_f32_32x32x16_bf16 v[112:127], v[234:237], v[176:179], v[112:127]
	v_mfma_f32_32x32x16_bf16 v[48:63], v[234:237], v[180:183], v[48:63]
	s_waitcnt lgkmcnt(0)
	v_mfma_f32_32x32x16_bf16 v[96:111], v[238:241], v[176:179], v[96:111]
	v_mfma_f32_32x32x16_bf16 v[32:47], v[238:241], v[180:183], v[32:47]
	ds_read_b128 v[234:237], v192 offset:9280
	ds_read_b128 v[238:241], v192 offset:13888
	s_waitcnt vmcnt(7)
	ds_write_b128 v215, v[168:171] offset:27648
	s_waitcnt vmcnt(6)
	ds_write_b128 v215, v[172:175] offset:64512
	ds_read_b128 v[168:171], v208 offset:96
	ds_read_b128 v[172:175], v208 offset:4704
	s_waitcnt lgkmcnt(5)
	v_mfma_f32_32x32x16_bf16 v[80:95], v[234:237], v[176:179], v[80:95]
	v_mfma_f32_32x32x16_bf16 v[16:31], v[234:237], v[180:183], v[16:31]
	ds_read_b128 v[234:237], v192 offset:96
	s_waitcnt lgkmcnt(5)
	v_mfma_f32_32x32x16_bf16 v[64:79], v[238:241], v[176:179], v[64:79]
	v_mfma_f32_32x32x16_bf16 v[0:15], v[238:241], v[180:183], v[0:15]
	ds_read_b128 v[238:241], v192 offset:4704
	s_setprio 0
	global_load_dwordx4 v[176:179], v[198:199], off offset:1664
	global_load_dwordx4 v[180:183], v[200:201], off offset:1664
	s_setprio 1
	s_waitcnt lgkmcnt(1)
	v_mfma_f32_32x32x16_bf16 v[112:127], v[234:237], v[168:171], v[112:127]
	v_mfma_f32_32x32x16_bf16 v[48:63], v[234:237], v[172:175], v[48:63]
	s_waitcnt lgkmcnt(0)
	v_mfma_f32_32x32x16_bf16 v[96:111], v[238:241], v[168:171], v[96:111]
	v_mfma_f32_32x32x16_bf16 v[32:47], v[238:241], v[172:175], v[32:47]
	ds_read_b128 v[234:237], v192 offset:9312
	ds_read_b128 v[238:241], v192 offset:13920
	s_waitcnt lgkmcnt(0)
	s_barrier
; template <bool trans>
; DI void gemm_core(const GTile& tl, const GTile& nx, bool has_next  , bool chain  , bool pre, u32x4 (&ra)[4], u32x4 (&rb)[4], char* smem, f32x16 (&acc)[2][4]) {
;     ...
;   const int nk = K / 64;
;   if (!pre) { G_LOAD(0); G_STORE(0); G_LOAD(1); }
;   for (int kt = 0; kt < nk; ++kt) {
;     __syncthreads();
;     G_COMPUTE(kt & 1, kt);
;   }
	s_waitcnt vmcnt(7)
	ds_write_b128 v209, v[160:163]
	s_waitcnt vmcnt(6)
	ds_write_b128 v210, v[164:167]
	ds_read_b128 v[160:163], v205 offset:36864
	ds_read_b128 v[164:167], v205 offset:41472
	v_mfma_f32_32x32x16_bf16 v[80:95], v[234:237], v[168:171], v[80:95]
	v_mfma_f32_32x32x16_bf16 v[16:31], v[234:237], v[172:175], v[16:31]
	ds_read_b128 v[234:237], v204
	v_mfma_f32_32x32x16_bf16 v[64:79], v[238:241], v[168:171], v[64:79]
	v_mfma_f32_32x32x16_bf16 v[0:15], v[238:241], v[172:175], v[0:15]
	ds_read_b128 v[238:241], v204 offset:4608
	s_setprio 0
	global_load_dwordx4 v[168:171], v[190:191], off offset:1792
	global_load_dwordx4 v[172:175], v[188:189], off offset:1792
	s_setprio 1
	s_waitcnt lgkmcnt(1)
	v_mfma_f32_32x32x16_bf16 v[112:127], v[234:237], v[160:163], v[112:127]
	v_mfma_f32_32x32x16_bf16 v[48:63], v[234:237], v[164:167], v[48:63]
	s_waitcnt lgkmcnt(0)
	v_mfma_f32_32x32x16_bf16 v[96:111], v[238:241], v[160:163], v[96:111]
	v_mfma_f32_32x32x16_bf16 v[32:47], v[238:241], v[164:167], v[32:47]
	ds_read_b128 v[234:237], v204 offset:9216
	ds_read_b128 v[238:241], v204 offset:13824
	s_waitcnt vmcnt(7)
	ds_write_b128 v212, v[218:221]
	s_waitcnt vmcnt(6)
	ds_write_b128 v211, v[222:225]
	ds_read_b128 v[218:221], v205 offset:36896
	ds_read_b128 v[222:225], v205 offset:41504
	s_waitcnt lgkmcnt(5)
	v_mfma_f32_32x32x16_bf16 v[80:95], v[234:237], v[160:163], v[80:95]
	v_mfma_f32_32x32x16_bf16 v[16:31], v[234:237], v[164:167], v[16:31]
	ds_read_b128 v[234:237], v204 offset:32
	s_waitcnt lgkmcnt(5)
	v_mfma_f32_32x32x16_bf16 v[64:79], v[238:241], v[160:163], v[64:79]
	v_mfma_f32_32x32x16_bf16 v[0:15], v[238:241], v[164:167], v[0:15]
	ds_read_b128 v[238:241], v204 offset:4640
	s_setprio 0
	global_load_dwordx4 v[160:163], v[194:195], off offset:1792
	global_load_dwordx4 v[164:167], v[196:197], off offset:1792
	s_setprio 1
	s_waitcnt lgkmcnt(1)
	v_mfma_f32_32x32x16_bf16 v[112:127], v[234:237], v[218:221], v[112:127]
	v_mfma_f32_32x32x16_bf16 v[48:63], v[234:237], v[222:225], v[48:63]
	s_waitcnt lgkmcnt(0)
	v_mfma_f32_32x32x16_bf16 v[96:111], v[238:241], v[218:221], v[96:111]
	v_mfma_f32_32x32x16_bf16 v[32:47], v[238:241], v[222:225], v[32:47]
	ds_read_b128 v[234:237], v204 offset:9248
	ds_read_b128 v[238:241], v204 offset:13856
	s_waitcnt vmcnt(7)
	ds_write_b128 v214, v[226:229]
	s_waitcnt vmcnt(6)
	ds_write_b128 v213, v[230:233]
	ds_read_b128 v[226:229], v205 offset:36928
	ds_read_b128 v[230:233], v205 offset:41536
	s_waitcnt lgkmcnt(5)
	v_mfma_f32_32x32x16_bf16 v[80:95], v[234:237], v[218:221], v[80:95]
	v_mfma_f32_32x32x16_bf16 v[16:31], v[234:237], v[222:225], v[16:31]
	ds_read_b128 v[234:237], v204 offset:64
	s_waitcnt lgkmcnt(5)
	v_mfma_f32_32x32x16_bf16 v[64:79], v[238:241], v[218:221], v[64:79]
	v_mfma_f32_32x32x16_bf16 v[0:15], v[238:241], v[222:225], v[0:15]
	ds_read_b128 v[238:241], v204 offset:4672
	s_setprio 0
	global_load_dwordx4 v[218:221], v[184:185], off offset:1792
	global_load_dwordx4 v[222:225], v[186:187], off offset:1792
	s_setprio 1
	s_waitcnt lgkmcnt(1)
	v_mfma_f32_32x32x16_bf16 v[112:127], v[234:237], v[226:229], v[112:127]
	v_mfma_f32_32x32x16_bf16 v[48:63], v[234:237], v[230:233], v[48:63]
	s_waitcnt lgkmcnt(0)
	v_mfma_f32_32x32x16_bf16 v[96:111], v[238:241], v[226:229], v[96:111]
	v_mfma_f32_32x32x16_bf16 v[32:47], v[238:241], v[230:233], v[32:47]
	ds_read_b128 v[234:237], v204 offset:9280
	ds_read_b128 v[238:241], v204 offset:13888
	s_waitcnt vmcnt(7)
	ds_write_b128 v217, v[176:179]
	s_waitcnt vmcnt(6)
	ds_write_b128 v216, v[180:183]
	ds_read_b128 v[176:179], v205 offset:36960
	ds_read_b128 v[180:183], v205 offset:41568
	s_waitcnt lgkmcnt(5)
	v_mfma_f32_32x32x16_bf16 v[80:95], v[234:237], v[226:229], v[80:95]
	v_mfma_f32_32x32x16_bf16 v[16:31], v[234:237], v[230:233], v[16:31]
	ds_read_b128 v[234:237], v204 offset:96
	s_waitcnt lgkmcnt(5)
	v_mfma_f32_32x32x16_bf16 v[64:79], v[238:241], v[226:229], v[64:79]
	v_mfma_f32_32x32x16_bf16 v[0:15], v[238:241], v[230:233], v[0:15]
	ds_read_b128 v[238:241], v204 offset:4704
	s_setprio 0
	global_load_dwordx4 v[226:229], v[198:199], off offset:1792
	global_load_dwordx4 v[230:233], v[200:201], off offset:1792
	s_setprio 1
	s_waitcnt lgkmcnt(1)
	v_mfma_f32_32x32x16_bf16 v[112:127], v[234:237], v[176:179], v[112:127]
	v_mfma_f32_32x32x16_bf16 v[48:63], v[234:237], v[180:183], v[48:63]
	s_waitcnt lgkmcnt(0)
	v_mfma_f32_32x32x16_bf16 v[96:111], v[238:241], v[176:179], v[96:111]
	v_mfma_f32_32x32x16_bf16 v[32:47], v[238:241], v[180:183], v[32:47]
	ds_read_b128 v[234:237], v204 offset:9312
	ds_read_b128 v[238:241], v204 offset:13920
	s_waitcnt lgkmcnt(0)
	s_barrier
; template <bool trans>
; DI void gemm_core(const GTile& tl, const GTile& nx, bool has_next  , bool chain  , bool pre, u32x4 (&ra)[4], u32x4 (&rb)[4], char* smem, f32x16 (&acc)[2][4]) {
;     ...
;   const int nk = K / 64;
;   if (!pre) { G_LOAD(0); G_STORE(0); G_LOAD(1); }
;   for (int kt = 0; kt < nk; ++kt) {
;     __syncthreads();
;     G_COMPUTE(kt & 1, kt);
;   }
	s_waitcnt vmcnt(7)
	ds_write_b128 v215, v[168:171]
	s_waitcnt vmcnt(6)
	ds_write_b128 v215, v[172:175] offset:36864
	ds_read_b128 v[168:171], v208
	ds_read_b128 v[172:175], v208 offset:4608
	v_mfma_f32_32x32x16_bf16 v[80:95], v[234:237], v[176:179], v[80:95]
	v_mfma_f32_32x32x16_bf16 v[16:31], v[234:237], v[180:183], v[16:31]
	ds_read_b128 v[234:237], v192
	v_mfma_f32_32x32x16_bf16 v[64:79], v[238:241], v[176:179], v[64:79]
	v_mfma_f32_32x32x16_bf16 v[0:15], v[238:241], v[180:183], v[0:15]
	ds_read_b128 v[238:241], v192 offset:4608
	s_setprio 0
	global_load_dwordx4 v[176:179], v[190:191], off offset:1920
	global_load_dwordx4 v[180:183], v[188:189], off offset:1920
	s_setprio 1
	s_waitcnt lgkmcnt(1)
	v_mfma_f32_32x32x16_bf16 v[112:127], v[234:237], v[168:171], v[112:127]
	v_mfma_f32_32x32x16_bf16 v[48:63], v[234:237], v[172:175], v[48:63]
	s_waitcnt lgkmcnt(0)
	v_mfma_f32_32x32x16_bf16 v[96:111], v[238:241], v[168:171], v[96:111]
	v_mfma_f32_32x32x16_bf16 v[32:47], v[238:241], v[172:175], v[32:47]
	ds_read_b128 v[234:237], v192 offset:9216
	ds_read_b128 v[238:241], v192 offset:13824
	s_waitcnt vmcnt(7)
	ds_write_b128 v215, v[160:163] offset:9216
	s_waitcnt vmcnt(6)
	ds_write_b128 v215, v[164:167] offset:46080
	ds_read_b128 v[160:163], v208 offset:32
	ds_read_b128 v[164:167], v208 offset:4640
	s_waitcnt lgkmcnt(5)
	v_mfma_f32_32x32x16_bf16 v[80:95], v[234:237], v[168:171], v[80:95]
	v_mfma_f32_32x32x16_bf16 v[16:31], v[234:237], v[172:175], v[16:31]
	ds_read_b128 v[234:237], v192 offset:32
	s_waitcnt lgkmcnt(5)
	v_mfma_f32_32x32x16_bf16 v[64:79], v[238:241], v[168:171], v[64:79]
	v_mfma_f32_32x32x16_bf16 v[0:15], v[238:241], v[172:175], v[0:15]
	ds_read_b128 v[238:241], v192 offset:4640
	s_setprio 0
	global_load_dwordx4 v[168:171], v[194:195], off offset:1920
	global_load_dwordx4 v[172:175], v[196:197], off offset:1920
	s_setprio 1
	s_waitcnt lgkmcnt(1)
	v_mfma_f32_32x32x16_bf16 v[112:127], v[234:237], v[160:163], v[112:127]
	v_mfma_f32_32x32x16_bf16 v[48:63], v[234:237], v[164:167], v[48:63]
	s_waitcnt lgkmcnt(0)
	v_mfma_f32_32x32x16_bf16 v[96:111], v[238:241], v[160:163], v[96:111]
	v_mfma_f32_32x32x16_bf16 v[32:47], v[238:241], v[164:167], v[32:47]
	ds_read_b128 v[234:237], v192 offset:9248
	ds_read_b128 v[238:241], v192 offset:13856
	s_waitcnt vmcnt(7)
	ds_write_b128 v215, v[218:221] offset:18432
	s_waitcnt vmcnt(6)
	ds_write_b128 v215, v[222:225] offset:55296
	ds_read_b128 v[218:221], v208 offset:64
	ds_read_b128 v[222:225], v208 offset:4672
	s_waitcnt lgkmcnt(5)
	v_mfma_f32_32x32x16_bf16 v[80:95], v[234:237], v[160:163], v[80:95]
	v_mfma_f32_32x32x16_bf16 v[16:31], v[234:237], v[164:167], v[16:31]
	ds_read_b128 v[234:237], v192 offset:64
	s_waitcnt lgkmcnt(5)
	v_mfma_f32_32x32x16_bf16 v[64:79], v[238:241], v[160:163], v[64:79]
	v_mfma_f32_32x32x16_bf16 v[0:15], v[238:241], v[164:167], v[0:15]
	ds_read_b128 v[238:241], v192 offset:4672
	s_setprio 0
	global_load_dwordx4 v[160:163], v[184:185], off offset:1920
	global_load_dwordx4 v[164:167], v[186:187], off offset:1920
	s_setprio 1
	s_waitcnt lgkmcnt(1)
	v_mfma_f32_32x32x16_bf16 v[112:127], v[234:237], v[218:221], v[112:127]
	v_mfma_f32_32x32x16_bf16 v[48:63], v[234:237], v[222:225], v[48:63]
	s_waitcnt lgkmcnt(0)
	v_mfma_f32_32x32x16_bf16 v[96:111], v[238:241], v[218:221], v[96:111]
	v_mfma_f32_32x32x16_bf16 v[32:47], v[238:241], v[222:225], v[32:47]
	ds_read_b128 v[234:237], v192 offset:9280
	ds_read_b128 v[238:241], v192 offset:13888
	s_waitcnt vmcnt(7)
	ds_write_b128 v215, v[226:229] offset:27648
	s_waitcnt vmcnt(6)
	ds_write_b128 v215, v[230:233] offset:64512
	ds_read_b128 v[226:229], v208 offset:96
	ds_read_b128 v[230:233], v208 offset:4704
	s_waitcnt lgkmcnt(5)
	v_mfma_f32_32x32x16_bf16 v[80:95], v[234:237], v[218:221], v[80:95]
	v_mfma_f32_32x32x16_bf16 v[16:31], v[234:237], v[222:225], v[16:31]
	ds_read_b128 v[234:237], v192 offset:96
	s_waitcnt lgkmcnt(5)
	v_mfma_f32_32x32x16_bf16 v[64:79], v[238:241], v[218:221], v[64:79]
	v_mfma_f32_32x32x16_bf16 v[0:15], v[238:241], v[222:225], v[0:15]
	ds_read_b128 v[238:241], v192 offset:4704
	s_setprio 0
	global_load_dwordx4 v[218:221], v[198:199], off offset:1920
	global_load_dwordx4 v[222:225], v[200:201], off offset:1920
	s_setprio 1
	s_waitcnt lgkmcnt(1)
	v_mfma_f32_32x32x16_bf16 v[112:127], v[234:237], v[226:229], v[112:127]
	v_mfma_f32_32x32x16_bf16 v[48:63], v[234:237], v[230:233], v[48:63]
	s_waitcnt lgkmcnt(0)
	v_mfma_f32_32x32x16_bf16 v[96:111], v[238:241], v[226:229], v[96:111]
	v_mfma_f32_32x32x16_bf16 v[32:47], v[238:241], v[230:233], v[32:47]
	ds_read_b128 v[234:237], v192 offset:9312
	ds_read_b128 v[238:241], v192 offset:13920
	s_waitcnt lgkmcnt(0)
	s_barrier
; template <bool trans>
; DI void gemm_core(const GTile& tl, const GTile& nx, bool has_next  , bool chain  , bool pre, u32x4 (&ra)[4], u32x4 (&rb)[4], char* smem, f32x16 (&acc)[2][4]) {
;     ...
;   const int nk = K / 64;
;   if (!pre) { G_LOAD(0); G_STORE(0); G_LOAD(1); }
;   for (int kt = 0; kt < nk; ++kt) {
;     __syncthreads();
;     G_COMPUTE(kt & 1, kt);
;   }
	s_waitcnt vmcnt(7)
	ds_write_b128 v209, v[176:179]
	s_waitcnt vmcnt(6)
	ds_write_b128 v210, v[180:183]
	ds_read_b128 v[176:179], v205 offset:36864
	ds_read_b128 v[180:183], v205 offset:41472
	v_mfma_f32_32x32x16_bf16 v[80:95], v[234:237], v[226:229], v[80:95]
	v_mfma_f32_32x32x16_bf16 v[16:31], v[234:237], v[230:233], v[16:31]
	ds_read_b128 v[234:237], v204
	v_mfma_f32_32x32x16_bf16 v[64:79], v[238:241], v[226:229], v[64:79]
	v_mfma_f32_32x32x16_bf16 v[0:15], v[238:241], v[230:233], v[0:15]
	ds_read_b128 v[238:241], v204 offset:4608
	s_setprio 0
	global_load_dwordx4 v[226:229], v[190:191], off offset:2048
	global_load_dwordx4 v[230:233], v[188:189], off offset:2048
	s_setprio 1
	s_waitcnt lgkmcnt(1)
	v_mfma_f32_32x32x16_bf16 v[112:127], v[234:237], v[176:179], v[112:127]
	v_mfma_f32_32x32x16_bf16 v[48:63], v[234:237], v[180:183], v[48:63]
	s_waitcnt lgkmcnt(0)
	v_mfma_f32_32x32x16_bf16 v[96:111], v[238:241], v[176:179], v[96:111]
	v_mfma_f32_32x32x16_bf16 v[32:47], v[238:241], v[180:183], v[32:47]
	ds_read_b128 v[234:237], v204 offset:9216
	ds_read_b128 v[238:241], v204 offset:13824
	s_waitcnt vmcnt(7)
	ds_write_b128 v212, v[168:171]
	s_waitcnt vmcnt(6)
	ds_write_b128 v211, v[172:175]
	ds_read_b128 v[168:171], v205 offset:36896
	ds_read_b128 v[172:175], v205 offset:41504
	s_waitcnt lgkmcnt(5)
	v_mfma_f32_32x32x16_bf16 v[80:95], v[234:237], v[176:179], v[80:95]
	v_mfma_f32_32x32x16_bf16 v[16:31], v[234:237], v[180:183], v[16:31]
	ds_read_b128 v[234:237], v204 offset:32
	s_waitcnt lgkmcnt(5)
	v_mfma_f32_32x32x16_bf16 v[64:79], v[238:241], v[176:179], v[64:79]
	v_mfma_f32_32x32x16_bf16 v[0:15], v[238:241], v[180:183], v[0:15]
	ds_read_b128 v[238:241], v204 offset:4640
	s_setprio 0
	global_load_dwordx4 v[176:179], v[194:195], off offset:2048
	global_load_dwordx4 v[180:183], v[196:197], off offset:2048
	s_setprio 1
	s_waitcnt lgkmcnt(1)
	v_mfma_f32_32x32x16_bf16 v[112:127], v[234:237], v[168:171], v[112:127]
	v_mfma_f32_32x32x16_bf16 v[48:63], v[234:237], v[172:175], v[48:63]
	s_waitcnt lgkmcnt(0)
	v_mfma_f32_32x32x16_bf16 v[96:111], v[238:241], v[168:171], v[96:111]
	v_mfma_f32_32x32x16_bf16 v[32:47], v[238:241], v[172:175], v[32:47]
	ds_read_b128 v[234:237], v204 offset:9248
	ds_read_b128 v[238:241], v204 offset:13856
	s_waitcnt vmcnt(7)
	ds_write_b128 v214, v[160:163]
	s_waitcnt vmcnt(6)
	ds_write_b128 v213, v[164:167]
	ds_read_b128 v[160:163], v205 offset:36928
	ds_read_b128 v[164:167], v205 offset:41536
	s_waitcnt lgkmcnt(5)
	v_mfma_f32_32x32x16_bf16 v[80:95], v[234:237], v[168:171], v[80:95]
	v_mfma_f32_32x32x16_bf16 v[16:31], v[234:237], v[172:175], v[16:31]
	ds_read_b128 v[234:237], v204 offset:64
	s_waitcnt lgkmcnt(5)
	v_mfma_f32_32x32x16_bf16 v[64:79], v[238:241], v[168:171], v[64:79]
	v_mfma_f32_32x32x16_bf16 v[0:15], v[238:241], v[172:175], v[0:15]
	ds_read_b128 v[238:241], v204 offset:4672
	s_setprio 0
	global_load_dwordx4 v[168:171], v[184:185], off offset:2048
	global_load_dwordx4 v[172:175], v[186:187], off offset:2048
	s_setprio 1
	s_waitcnt lgkmcnt(1)
	v_mfma_f32_32x32x16_bf16 v[112:127], v[234:237], v[160:163], v[112:127]
	v_mfma_f32_32x32x16_bf16 v[48:63], v[234:237], v[164:167], v[48:63]
	s_waitcnt lgkmcnt(0)
	v_mfma_f32_32x32x16_bf16 v[96:111], v[238:241], v[160:163], v[96:111]
	v_mfma_f32_32x32x16_bf16 v[32:47], v[238:241], v[164:167], v[32:47]
	ds_read_b128 v[234:237], v204 offset:9280
	ds_read_b128 v[238:241], v204 offset:13888
	s_waitcnt vmcnt(7)
	ds_write_b128 v217, v[218:221]
	s_waitcnt vmcnt(6)
	ds_write_b128 v216, v[222:225]
	ds_read_b128 v[218:221], v205 offset:36960
	ds_read_b128 v[222:225], v205 offset:41568
	s_waitcnt lgkmcnt(5)
	v_mfma_f32_32x32x16_bf16 v[80:95], v[234:237], v[160:163], v[80:95]
	v_mfma_f32_32x32x16_bf16 v[16:31], v[234:237], v[164:167], v[16:31]
	ds_read_b128 v[234:237], v204 offset:96
	s_waitcnt lgkmcnt(5)
	v_mfma_f32_32x32x16_bf16 v[64:79], v[238:241], v[160:163], v[64:79]
	v_mfma_f32_32x32x16_bf16 v[0:15], v[238:241], v[164:167], v[0:15]
	ds_read_b128 v[238:241], v204 offset:4704
	s_setprio 0
	global_load_dwordx4 v[160:163], v[198:199], off offset:2048
	global_load_dwordx4 v[164:167], v[200:201], off offset:2048
	s_setprio 1
	s_waitcnt lgkmcnt(1)
	v_mfma_f32_32x32x16_bf16 v[112:127], v[234:237], v[218:221], v[112:127]
	v_mfma_f32_32x32x16_bf16 v[48:63], v[234:237], v[222:225], v[48:63]
	s_waitcnt lgkmcnt(0)
	v_mfma_f32_32x32x16_bf16 v[96:111], v[238:241], v[218:221], v[96:111]
	v_mfma_f32_32x32x16_bf16 v[32:47], v[238:241], v[222:225], v[32:47]
	ds_read_b128 v[234:237], v204 offset:9312
	ds_read_b128 v[238:241], v204 offset:13920
	s_waitcnt lgkmcnt(0)
	s_barrier
; template <bool trans>
; DI void gemm_core(const GTile& tl, const GTile& nx, bool has_next  , bool chain  , bool pre, u32x4 (&ra)[4], u32x4 (&rb)[4], char* smem, f32x16 (&acc)[2][4]) {
;     ...
;   const int nk = K / 64;
;   if (!pre) { G_LOAD(0); G_STORE(0); G_LOAD(1); }
;   for (int kt = 0; kt < nk; ++kt) {
;     __syncthreads();
;     G_COMPUTE(kt & 1, kt);
;   }
	s_waitcnt vmcnt(7)
	ds_write_b128 v215, v[226:229]
	s_waitcnt vmcnt(6)
	ds_write_b128 v215, v[230:233] offset:36864
	ds_read_b128 v[226:229], v208
	ds_read_b128 v[230:233], v208 offset:4608
	v_mfma_f32_32x32x16_bf16 v[80:95], v[234:237], v[218:221], v[80:95]
	v_mfma_f32_32x32x16_bf16 v[16:31], v[234:237], v[222:225], v[16:31]
	ds_read_b128 v[234:237], v192
	v_mfma_f32_32x32x16_bf16 v[64:79], v[238:241], v[218:221], v[64:79]
	v_mfma_f32_32x32x16_bf16 v[0:15], v[238:241], v[222:225], v[0:15]
	ds_read_b128 v[238:241], v192 offset:4608
	s_setprio 0
	global_load_dwordx4 v[218:221], v[190:191], off offset:2176
	global_load_dwordx4 v[222:225], v[188:189], off offset:2176
	s_setprio 1
	s_waitcnt lgkmcnt(1)
	v_mfma_f32_32x32x16_bf16 v[112:127], v[234:237], v[226:229], v[112:127]
	v_mfma_f32_32x32x16_bf16 v[48:63], v[234:237], v[230:233], v[48:63]
	s_waitcnt lgkmcnt(0)
	v_mfma_f32_32x32x16_bf16 v[96:111], v[238:241], v[226:229], v[96:111]
	v_mfma_f32_32x32x16_bf16 v[32:47], v[238:241], v[230:233], v[32:47]
	ds_read_b128 v[234:237], v192 offset:9216
	ds_read_b128 v[238:241], v192 offset:13824
	s_waitcnt vmcnt(7)
	ds_write_b128 v215, v[176:179] offset:9216
	s_waitcnt vmcnt(6)
	ds_write_b128 v215, v[180:183] offset:46080
	ds_read_b128 v[176:179], v208 offset:32
	ds_read_b128 v[180:183], v208 offset:4640
	s_waitcnt lgkmcnt(5)
	v_mfma_f32_32x32x16_bf16 v[80:95], v[234:237], v[226:229], v[80:95]
	v_mfma_f32_32x32x16_bf16 v[16:31], v[234:237], v[230:233], v[16:31]
	ds_read_b128 v[234:237], v192 offset:32
	s_waitcnt lgkmcnt(5)
	v_mfma_f32_32x32x16_bf16 v[64:79], v[238:241], v[226:229], v[64:79]
	v_mfma_f32_32x32x16_bf16 v[0:15], v[238:241], v[230:233], v[0:15]
	ds_read_b128 v[238:241], v192 offset:4640
	s_setprio 0
	global_load_dwordx4 v[226:229], v[194:195], off offset:2176
	global_load_dwordx4 v[230:233], v[196:197], off offset:2176
	s_setprio 1
	s_waitcnt lgkmcnt(1)
	v_mfma_f32_32x32x16_bf16 v[112:127], v[234:237], v[176:179], v[112:127]
	v_mfma_f32_32x32x16_bf16 v[48:63], v[234:237], v[180:183], v[48:63]
	s_waitcnt lgkmcnt(0)
	v_mfma_f32_32x32x16_bf16 v[96:111], v[238:241], v[176:179], v[96:111]
	v_mfma_f32_32x32x16_bf16 v[32:47], v[238:241], v[180:183], v[32:47]
	ds_read_b128 v[234:237], v192 offset:9248
	ds_read_b128 v[238:241], v192 offset:13856
	s_waitcnt vmcnt(7)
	ds_write_b128 v215, v[168:171] offset:18432
	s_waitcnt vmcnt(6)
	ds_write_b128 v215, v[172:175] offset:55296
	ds_read_b128 v[168:171], v208 offset:64
	ds_read_b128 v[172:175], v208 offset:4672
	s_waitcnt lgkmcnt(5)
	v_mfma_f32_32x32x16_bf16 v[80:95], v[234:237], v[176:179], v[80:95]
	v_mfma_f32_32x32x16_bf16 v[16:31], v[234:237], v[180:183], v[16:31]
	ds_read_b128 v[234:237], v192 offset:64
	s_waitcnt lgkmcnt(5)
	v_mfma_f32_32x32x16_bf16 v[64:79], v[238:241], v[176:179], v[64:79]
	v_mfma_f32_32x32x16_bf16 v[0:15], v[238:241], v[180:183], v[0:15]
	ds_read_b128 v[238:241], v192 offset:4672
	s_setprio 0
	global_load_dwordx4 v[176:179], v[184:185], off offset:2176
	global_load_dwordx4 v[180:183], v[186:187], off offset:2176
	s_setprio 1
	s_waitcnt lgkmcnt(1)
	v_mfma_f32_32x32x16_bf16 v[112:127], v[234:237], v[168:171], v[112:127]
	v_mfma_f32_32x32x16_bf16 v[48:63], v[234:237], v[172:175], v[48:63]
	s_waitcnt lgkmcnt(0)
	v_mfma_f32_32x32x16_bf16 v[96:111], v[238:241], v[168:171], v[96:111]
	v_mfma_f32_32x32x16_bf16 v[32:47], v[238:241], v[172:175], v[32:47]
	ds_read_b128 v[234:237], v192 offset:9280
	ds_read_b128 v[238:241], v192 offset:13888
	s_waitcnt vmcnt(7)
	ds_write_b128 v215, v[160:163] offset:27648
	s_waitcnt vmcnt(6)
	ds_write_b128 v215, v[164:167] offset:64512
	ds_read_b128 v[160:163], v208 offset:96
	ds_read_b128 v[164:167], v208 offset:4704
	s_waitcnt lgkmcnt(5)
	v_mfma_f32_32x32x16_bf16 v[80:95], v[234:237], v[168:171], v[80:95]
	v_mfma_f32_32x32x16_bf16 v[16:31], v[234:237], v[172:175], v[16:31]
	ds_read_b128 v[234:237], v192 offset:96
	s_waitcnt lgkmcnt(5)
	v_mfma_f32_32x32x16_bf16 v[64:79], v[238:241], v[168:171], v[64:79]
	v_mfma_f32_32x32x16_bf16 v[0:15], v[238:241], v[172:175], v[0:15]
	ds_read_b128 v[238:241], v192 offset:4704
	s_setprio 0
	global_load_dwordx4 v[168:171], v[198:199], off offset:2176
	global_load_dwordx4 v[172:175], v[200:201], off offset:2176
	s_setprio 1
	s_waitcnt lgkmcnt(1)
	v_mfma_f32_32x32x16_bf16 v[112:127], v[234:237], v[160:163], v[112:127]
	v_mfma_f32_32x32x16_bf16 v[48:63], v[234:237], v[164:167], v[48:63]
	s_waitcnt lgkmcnt(0)
	v_mfma_f32_32x32x16_bf16 v[96:111], v[238:241], v[160:163], v[96:111]
	v_mfma_f32_32x32x16_bf16 v[32:47], v[238:241], v[164:167], v[32:47]
	ds_read_b128 v[234:237], v192 offset:9312
	ds_read_b128 v[238:241], v192 offset:13920
	s_waitcnt lgkmcnt(0)
	s_barrier
; template <bool trans>
; DI void gemm_core(const GTile& tl, const GTile& nx, bool has_next  , bool chain  , bool pre, u32x4 (&ra)[4], u32x4 (&rb)[4], char* smem, f32x16 (&acc)[2][4]) {
;     ...
;   const int nk = K / 64;
;   if (!pre) { G_LOAD(0); G_STORE(0); G_LOAD(1); }
;   for (int kt = 0; kt < nk; ++kt) {
;     __syncthreads();
;     G_COMPUTE(kt & 1, kt);
;   }
	s_waitcnt vmcnt(7)
	ds_write_b128 v209, v[218:221]
	s_waitcnt vmcnt(6)
	ds_write_b128 v210, v[222:225]
	ds_read_b128 v[218:221], v205 offset:36864
	ds_read_b128 v[222:225], v205 offset:41472
	v_mfma_f32_32x32x16_bf16 v[80:95], v[234:237], v[160:163], v[80:95]
	v_mfma_f32_32x32x16_bf16 v[16:31], v[234:237], v[164:167], v[16:31]
	ds_read_b128 v[234:237], v204
	v_mfma_f32_32x32x16_bf16 v[64:79], v[238:241], v[160:163], v[64:79]
	v_mfma_f32_32x32x16_bf16 v[0:15], v[238:241], v[164:167], v[0:15]
	ds_read_b128 v[238:241], v204 offset:4608
	s_setprio 0
	global_load_dwordx4 v[160:163], v[190:191], off offset:2304
	global_load_dwordx4 v[164:167], v[188:189], off offset:2304
	s_setprio 1
	s_waitcnt lgkmcnt(1)
	v_mfma_f32_32x32x16_bf16 v[112:127], v[234:237], v[218:221], v[112:127]
	v_mfma_f32_32x32x16_bf16 v[48:63], v[234:237], v[222:225], v[48:63]
	s_waitcnt lgkmcnt(0)
	v_mfma_f32_32x32x16_bf16 v[96:111], v[238:241], v[218:221], v[96:111]
	v_mfma_f32_32x32x16_bf16 v[32:47], v[238:241], v[222:225], v[32:47]
	ds_read_b128 v[234:237], v204 offset:9216
	ds_read_b128 v[238:241], v204 offset:13824
	s_waitcnt vmcnt(7)
	ds_write_b128 v212, v[226:229]
	s_waitcnt vmcnt(6)
	ds_write_b128 v211, v[230:233]
	ds_read_b128 v[226:229], v205 offset:36896
	ds_read_b128 v[230:233], v205 offset:41504
	s_waitcnt lgkmcnt(5)
	v_mfma_f32_32x32x16_bf16 v[80:95], v[234:237], v[218:221], v[80:95]
	v_mfma_f32_32x32x16_bf16 v[16:31], v[234:237], v[222:225], v[16:31]
	ds_read_b128 v[234:237], v204 offset:32
	s_waitcnt lgkmcnt(5)
	v_mfma_f32_32x32x16_bf16 v[64:79], v[238:241], v[218:221], v[64:79]
	v_mfma_f32_32x32x16_bf16 v[0:15], v[238:241], v[222:225], v[0:15]
	ds_read_b128 v[238:241], v204 offset:4640
	s_setprio 0
	global_load_dwordx4 v[218:221], v[194:195], off offset:2304
	global_load_dwordx4 v[222:225], v[196:197], off offset:2304
	s_setprio 1
	s_waitcnt lgkmcnt(1)
	v_mfma_f32_32x32x16_bf16 v[112:127], v[234:237], v[226:229], v[112:127]
	v_mfma_f32_32x32x16_bf16 v[48:63], v[234:237], v[230:233], v[48:63]
	s_waitcnt lgkmcnt(0)
	v_mfma_f32_32x32x16_bf16 v[96:111], v[238:241], v[226:229], v[96:111]
	v_mfma_f32_32x32x16_bf16 v[32:47], v[238:241], v[230:233], v[32:47]
	ds_read_b128 v[234:237], v204 offset:9248
	ds_read_b128 v[238:241], v204 offset:13856
	s_waitcnt vmcnt(7)
	ds_write_b128 v214, v[176:179]
	s_waitcnt vmcnt(6)
	ds_write_b128 v213, v[180:183]
	ds_read_b128 v[176:179], v205 offset:36928
	ds_read_b128 v[180:183], v205 offset:41536
	s_waitcnt lgkmcnt(5)
	v_mfma_f32_32x32x16_bf16 v[80:95], v[234:237], v[226:229], v[80:95]
	v_mfma_f32_32x32x16_bf16 v[16:31], v[234:237], v[230:233], v[16:31]
	ds_read_b128 v[234:237], v204 offset:64
	s_waitcnt lgkmcnt(5)
	v_mfma_f32_32x32x16_bf16 v[64:79], v[238:241], v[226:229], v[64:79]
	v_mfma_f32_32x32x16_bf16 v[0:15], v[238:241], v[230:233], v[0:15]
	ds_read_b128 v[238:241], v204 offset:4672
	s_setprio 0
	global_load_dwordx4 v[226:229], v[184:185], off offset:2304
	global_load_dwordx4 v[230:233], v[186:187], off offset:2304
	s_setprio 1
	s_waitcnt lgkmcnt(1)
	v_mfma_f32_32x32x16_bf16 v[112:127], v[234:237], v[176:179], v[112:127]
	v_mfma_f32_32x32x16_bf16 v[48:63], v[234:237], v[180:183], v[48:63]
	s_waitcnt lgkmcnt(0)
	v_mfma_f32_32x32x16_bf16 v[96:111], v[238:241], v[176:179], v[96:111]
	v_mfma_f32_32x32x16_bf16 v[32:47], v[238:241], v[180:183], v[32:47]
	ds_read_b128 v[234:237], v204 offset:9280
	ds_read_b128 v[238:241], v204 offset:13888
	s_waitcnt vmcnt(7)
	ds_write_b128 v217, v[168:171]
	s_waitcnt vmcnt(6)
	ds_write_b128 v216, v[172:175]
	ds_read_b128 v[168:171], v205 offset:36960
	ds_read_b128 v[172:175], v205 offset:41568
	s_waitcnt lgkmcnt(5)
	v_mfma_f32_32x32x16_bf16 v[80:95], v[234:237], v[176:179], v[80:95]
	v_mfma_f32_32x32x16_bf16 v[16:31], v[234:237], v[180:183], v[16:31]
	ds_read_b128 v[234:237], v204 offset:96
	s_waitcnt lgkmcnt(5)
	v_mfma_f32_32x32x16_bf16 v[64:79], v[238:241], v[176:179], v[64:79]
	v_mfma_f32_32x32x16_bf16 v[0:15], v[238:241], v[180:183], v[0:15]
	ds_read_b128 v[238:241], v204 offset:4704
	s_setprio 0
	global_load_dwordx4 v[176:179], v[198:199], off offset:2304
	global_load_dwordx4 v[180:183], v[200:201], off offset:2304
	s_setprio 1
	s_waitcnt lgkmcnt(1)
	v_mfma_f32_32x32x16_bf16 v[112:127], v[234:237], v[168:171], v[112:127]
	v_mfma_f32_32x32x16_bf16 v[48:63], v[234:237], v[172:175], v[48:63]
	s_waitcnt lgkmcnt(0)
	v_mfma_f32_32x32x16_bf16 v[96:111], v[238:241], v[168:171], v[96:111]
	v_mfma_f32_32x32x16_bf16 v[32:47], v[238:241], v[172:175], v[32:47]
	ds_read_b128 v[234:237], v204 offset:9312
	ds_read_b128 v[238:241], v204 offset:13920
	s_waitcnt lgkmcnt(0)
	s_barrier
; template <bool trans>
; DI void gemm_core(const GTile& tl, const GTile& nx, bool has_next  , bool chain  , bool pre, u32x4 (&ra)[4], u32x4 (&rb)[4], char* smem, f32x16 (&acc)[2][4]) {
;     ...
;   const int nk = K / 64;
;   if (!pre) { G_LOAD(0); G_STORE(0); G_LOAD(1); }
;   for (int kt = 0; kt < nk; ++kt) {
;     __syncthreads();
;     G_COMPUTE(kt & 1, kt);
;   }
	s_waitcnt vmcnt(7)
	ds_write_b128 v215, v[160:163]
	s_waitcnt vmcnt(6)
	ds_write_b128 v215, v[164:167] offset:36864
	ds_read_b128 v[160:163], v208
	ds_read_b128 v[164:167], v208 offset:4608
	v_mfma_f32_32x32x16_bf16 v[80:95], v[234:237], v[168:171], v[80:95]
	v_mfma_f32_32x32x16_bf16 v[16:31], v[234:237], v[172:175], v[16:31]
	ds_read_b128 v[234:237], v192
	v_mfma_f32_32x32x16_bf16 v[64:79], v[238:241], v[168:171], v[64:79]
	v_mfma_f32_32x32x16_bf16 v[0:15], v[238:241], v[172:175], v[0:15]
	ds_read_b128 v[238:241], v192 offset:4608
	s_setprio 0
	global_load_dwordx4 v[168:171], v[190:191], off offset:2432
	global_load_dwordx4 v[172:175], v[188:189], off offset:2432
	s_setprio 1
	s_waitcnt lgkmcnt(1)
	v_mfma_f32_32x32x16_bf16 v[112:127], v[234:237], v[160:163], v[112:127]
	v_mfma_f32_32x32x16_bf16 v[48:63], v[234:237], v[164:167], v[48:63]
	s_waitcnt lgkmcnt(0)
	v_mfma_f32_32x32x16_bf16 v[96:111], v[238:241], v[160:163], v[96:111]
	v_mfma_f32_32x32x16_bf16 v[32:47], v[238:241], v[164:167], v[32:47]
	ds_read_b128 v[234:237], v192 offset:9216
	ds_read_b128 v[238:241], v192 offset:13824
	s_waitcnt vmcnt(7)
	ds_write_b128 v215, v[218:221] offset:9216
	s_waitcnt vmcnt(6)
	ds_write_b128 v215, v[222:225] offset:46080
	ds_read_b128 v[218:221], v208 offset:32
	ds_read_b128 v[222:225], v208 offset:4640
	s_waitcnt lgkmcnt(5)
	v_mfma_f32_32x32x16_bf16 v[80:95], v[234:237], v[160:163], v[80:95]
	v_mfma_f32_32x32x16_bf16 v[16:31], v[234:237], v[164:167], v[16:31]
	ds_read_b128 v[234:237], v192 offset:32
	s_waitcnt lgkmcnt(5)
	v_mfma_f32_32x32x16_bf16 v[64:79], v[238:241], v[160:163], v[64:79]
	v_mfma_f32_32x32x16_bf16 v[0:15], v[238:241], v[164:167], v[0:15]
	ds_read_b128 v[238:241], v192 offset:4640
	s_setprio 0
	global_load_dwordx4 v[160:163], v[194:195], off offset:2432
	global_load_dwordx4 v[164:167], v[196:197], off offset:2432
	s_setprio 1
	s_waitcnt lgkmcnt(1)
	v_mfma_f32_32x32x16_bf16 v[112:127], v[234:237], v[218:221], v[112:127]
	v_mfma_f32_32x32x16_bf16 v[48:63], v[234:237], v[222:225], v[48:63]
	s_waitcnt lgkmcnt(0)
	v_mfma_f32_32x32x16_bf16 v[96:111], v[238:241], v[218:221], v[96:111]
	v_mfma_f32_32x32x16_bf16 v[32:47], v[238:241], v[222:225], v[32:47]
	ds_read_b128 v[234:237], v192 offset:9248
	ds_read_b128 v[238:241], v192 offset:13856
	s_waitcnt vmcnt(7)
	ds_write_b128 v215, v[226:229] offset:18432
	s_waitcnt vmcnt(6)
	ds_write_b128 v215, v[230:233] offset:55296
	ds_read_b128 v[226:229], v208 offset:64
	ds_read_b128 v[230:233], v208 offset:4672
	s_waitcnt lgkmcnt(5)
	v_mfma_f32_32x32x16_bf16 v[80:95], v[234:237], v[218:221], v[80:95]
	v_mfma_f32_32x32x16_bf16 v[16:31], v[234:237], v[222:225], v[16:31]
	ds_read_b128 v[234:237], v192 offset:64
	s_waitcnt lgkmcnt(5)
	v_mfma_f32_32x32x16_bf16 v[64:79], v[238:241], v[218:221], v[64:79]
	v_mfma_f32_32x32x16_bf16 v[0:15], v[238:241], v[222:225], v[0:15]
	ds_read_b128 v[238:241], v192 offset:4672
	s_setprio 0
	global_load_dwordx4 v[218:221], v[184:185], off offset:2432
	global_load_dwordx4 v[222:225], v[186:187], off offset:2432
	s_setprio 1
	s_waitcnt lgkmcnt(1)
	v_mfma_f32_32x32x16_bf16 v[112:127], v[234:237], v[226:229], v[112:127]
	v_mfma_f32_32x32x16_bf16 v[48:63], v[234:237], v[230:233], v[48:63]
	s_waitcnt lgkmcnt(0)
	v_mfma_f32_32x32x16_bf16 v[96:111], v[238:241], v[226:229], v[96:111]
	v_mfma_f32_32x32x16_bf16 v[32:47], v[238:241], v[230:233], v[32:47]
	ds_read_b128 v[234:237], v192 offset:9280
	ds_read_b128 v[238:241], v192 offset:13888
	s_waitcnt vmcnt(7)
	ds_write_b128 v215, v[176:179] offset:27648
	s_waitcnt vmcnt(6)
	ds_write_b128 v215, v[180:183] offset:64512
	ds_read_b128 v[176:179], v208 offset:96
	ds_read_b128 v[180:183], v208 offset:4704
	s_waitcnt lgkmcnt(5)
	v_mfma_f32_32x32x16_bf16 v[80:95], v[234:237], v[226:229], v[80:95]
	v_mfma_f32_32x32x16_bf16 v[16:31], v[234:237], v[230:233], v[16:31]
	ds_read_b128 v[234:237], v192 offset:96
	s_waitcnt lgkmcnt(5)
	v_mfma_f32_32x32x16_bf16 v[64:79], v[238:241], v[226:229], v[64:79]
	v_mfma_f32_32x32x16_bf16 v[0:15], v[238:241], v[230:233], v[0:15]
	ds_read_b128 v[238:241], v192 offset:4704
	s_setprio 0
	global_load_dwordx4 v[226:229], v[198:199], off offset:2432
	global_load_dwordx4 v[230:233], v[200:201], off offset:2432
	s_setprio 1
	s_waitcnt lgkmcnt(1)
	v_mfma_f32_32x32x16_bf16 v[112:127], v[234:237], v[176:179], v[112:127]
	v_mfma_f32_32x32x16_bf16 v[48:63], v[234:237], v[180:183], v[48:63]
	s_waitcnt lgkmcnt(0)
	v_mfma_f32_32x32x16_bf16 v[96:111], v[238:241], v[176:179], v[96:111]
	v_mfma_f32_32x32x16_bf16 v[32:47], v[238:241], v[180:183], v[32:47]
	ds_read_b128 v[234:237], v192 offset:9312
	ds_read_b128 v[238:241], v192 offset:13920
	s_waitcnt lgkmcnt(0)
	s_barrier
; template <bool trans>
; DI void gemm_core(const GTile& tl, const GTile& nx, bool has_next  , bool chain  , bool pre, u32x4 (&ra)[4], u32x4 (&rb)[4], char* smem, f32x16 (&acc)[2][4]) {
;     ...
;   const int nk = K / 64;
;   if (!pre) { G_LOAD(0); G_STORE(0); G_LOAD(1); }
;   for (int kt = 0; kt < nk; ++kt) {
;     __syncthreads();
;     G_COMPUTE(kt & 1, kt);
;   }
	s_waitcnt vmcnt(7)
	ds_write_b128 v209, v[168:171]
	s_waitcnt vmcnt(6)
	ds_write_b128 v210, v[172:175]
	ds_read_b128 v[168:171], v205 offset:36864
	ds_read_b128 v[172:175], v205 offset:41472
	v_mfma_f32_32x32x16_bf16 v[80:95], v[234:237], v[176:179], v[80:95]
	v_mfma_f32_32x32x16_bf16 v[16:31], v[234:237], v[180:183], v[16:31]
	ds_read_b128 v[234:237], v204
	v_mfma_f32_32x32x16_bf16 v[64:79], v[238:241], v[176:179], v[64:79]
	v_mfma_f32_32x32x16_bf16 v[0:15], v[238:241], v[180:183], v[0:15]
	ds_read_b128 v[238:241], v204 offset:4608
	s_setprio 0
	global_load_dwordx4 v[176:179], v[190:191], off offset:2560
	global_load_dwordx4 v[180:183], v[188:189], off offset:2560
	s_setprio 1
	s_waitcnt lgkmcnt(1)
	v_mfma_f32_32x32x16_bf16 v[112:127], v[234:237], v[168:171], v[112:127]
	v_mfma_f32_32x32x16_bf16 v[48:63], v[234:237], v[172:175], v[48:63]
	s_waitcnt lgkmcnt(0)
	v_mfma_f32_32x32x16_bf16 v[96:111], v[238:241], v[168:171], v[96:111]
	v_mfma_f32_32x32x16_bf16 v[32:47], v[238:241], v[172:175], v[32:47]
	ds_read_b128 v[234:237], v204 offset:9216
	ds_read_b128 v[238:241], v204 offset:13824
	s_waitcnt vmcnt(7)
	ds_write_b128 v212, v[160:163]
	s_waitcnt vmcnt(6)
	ds_write_b128 v211, v[164:167]
	ds_read_b128 v[160:163], v205 offset:36896
	ds_read_b128 v[164:167], v205 offset:41504
	s_waitcnt lgkmcnt(5)
	v_mfma_f32_32x32x16_bf16 v[80:95], v[234:237], v[168:171], v[80:95]
	v_mfma_f32_32x32x16_bf16 v[16:31], v[234:237], v[172:175], v[16:31]
	ds_read_b128 v[234:237], v204 offset:32
	s_waitcnt lgkmcnt(5)
	v_mfma_f32_32x32x16_bf16 v[64:79], v[238:241], v[168:171], v[64:79]
	v_mfma_f32_32x32x16_bf16 v[0:15], v[238:241], v[172:175], v[0:15]
	ds_read_b128 v[238:241], v204 offset:4640
	s_setprio 0
	global_load_dwordx4 v[168:171], v[194:195], off offset:2560
	global_load_dwordx4 v[172:175], v[196:197], off offset:2560
	s_setprio 1
	s_waitcnt lgkmcnt(1)
	v_mfma_f32_32x32x16_bf16 v[112:127], v[234:237], v[160:163], v[112:127]
	v_mfma_f32_32x32x16_bf16 v[48:63], v[234:237], v[164:167], v[48:63]
	s_waitcnt lgkmcnt(0)
	v_mfma_f32_32x32x16_bf16 v[96:111], v[238:241], v[160:163], v[96:111]
	v_mfma_f32_32x32x16_bf16 v[32:47], v[238:241], v[164:167], v[32:47]
	ds_read_b128 v[234:237], v204 offset:9248
	ds_read_b128 v[238:241], v204 offset:13856
	s_waitcnt vmcnt(7)
	ds_write_b128 v214, v[218:221]
	s_waitcnt vmcnt(6)
	ds_write_b128 v213, v[222:225]
	ds_read_b128 v[218:221], v205 offset:36928
	ds_read_b128 v[222:225], v205 offset:41536
	s_waitcnt lgkmcnt(5)
	v_mfma_f32_32x32x16_bf16 v[80:95], v[234:237], v[160:163], v[80:95]
	v_mfma_f32_32x32x16_bf16 v[16:31], v[234:237], v[164:167], v[16:31]
	ds_read_b128 v[234:237], v204 offset:64
	s_waitcnt lgkmcnt(5)
	v_mfma_f32_32x32x16_bf16 v[64:79], v[238:241], v[160:163], v[64:79]
	v_mfma_f32_32x32x16_bf16 v[0:15], v[238:241], v[164:167], v[0:15]
	ds_read_b128 v[238:241], v204 offset:4672
	s_setprio 0
	global_load_dwordx4 v[160:163], v[184:185], off offset:2560
	global_load_dwordx4 v[164:167], v[186:187], off offset:2560
	s_setprio 1
	s_waitcnt lgkmcnt(1)
	v_mfma_f32_32x32x16_bf16 v[112:127], v[234:237], v[218:221], v[112:127]
	v_mfma_f32_32x32x16_bf16 v[48:63], v[234:237], v[222:225], v[48:63]
	s_waitcnt lgkmcnt(0)
	v_mfma_f32_32x32x16_bf16 v[96:111], v[238:241], v[218:221], v[96:111]
	v_mfma_f32_32x32x16_bf16 v[32:47], v[238:241], v[222:225], v[32:47]
	ds_read_b128 v[234:237], v204 offset:9280
	ds_read_b128 v[238:241], v204 offset:13888
	s_waitcnt vmcnt(7)
	ds_write_b128 v217, v[226:229]
	s_waitcnt vmcnt(6)
	ds_write_b128 v216, v[230:233]
	ds_read_b128 v[226:229], v205 offset:36960
	ds_read_b128 v[230:233], v205 offset:41568
	s_waitcnt lgkmcnt(5)
	v_mfma_f32_32x32x16_bf16 v[80:95], v[234:237], v[218:221], v[80:95]
	v_mfma_f32_32x32x16_bf16 v[16:31], v[234:237], v[222:225], v[16:31]
	ds_read_b128 v[234:237], v204 offset:96
	s_waitcnt lgkmcnt(5)
	v_mfma_f32_32x32x16_bf16 v[64:79], v[238:241], v[218:221], v[64:79]
	v_mfma_f32_32x32x16_bf16 v[0:15], v[238:241], v[222:225], v[0:15]
	ds_read_b128 v[238:241], v204 offset:4704
	s_setprio 0
	global_load_dwordx4 v[218:221], v[198:199], off offset:2560
	global_load_dwordx4 v[222:225], v[200:201], off offset:2560
	s_setprio 1
	s_waitcnt lgkmcnt(1)
	v_mfma_f32_32x32x16_bf16 v[112:127], v[234:237], v[226:229], v[112:127]
	v_mfma_f32_32x32x16_bf16 v[48:63], v[234:237], v[230:233], v[48:63]
	s_waitcnt lgkmcnt(0)
	v_mfma_f32_32x32x16_bf16 v[96:111], v[238:241], v[226:229], v[96:111]
	v_mfma_f32_32x32x16_bf16 v[32:47], v[238:241], v[230:233], v[32:47]
	ds_read_b128 v[234:237], v204 offset:9312
	ds_read_b128 v[238:241], v204 offset:13920
	s_waitcnt lgkmcnt(0)
	s_barrier
; template <bool trans>
; DI void gemm_core(const GTile& tl, const GTile& nx, bool has_next  , bool chain  , bool pre, u32x4 (&ra)[4], u32x4 (&rb)[4], char* smem, f32x16 (&acc)[2][4]) {
;     ...
;   const int nk = K / 64;
;   if (!pre) { G_LOAD(0); G_STORE(0); G_LOAD(1); }
;   for (int kt = 0; kt < nk; ++kt) {
;     __syncthreads();
;     G_COMPUTE(kt & 1, kt);
;   }
	s_waitcnt vmcnt(7)
	ds_write_b128 v215, v[176:179]
	s_waitcnt vmcnt(6)
	ds_write_b128 v215, v[180:183] offset:36864
	ds_read_b128 v[176:179], v208
	ds_read_b128 v[180:183], v208 offset:4608
	v_mfma_f32_32x32x16_bf16 v[80:95], v[234:237], v[226:229], v[80:95]
	v_mfma_f32_32x32x16_bf16 v[16:31], v[234:237], v[230:233], v[16:31]
	ds_read_b128 v[234:237], v192
	v_mfma_f32_32x32x16_bf16 v[64:79], v[238:241], v[226:229], v[64:79]
	v_mfma_f32_32x32x16_bf16 v[0:15], v[238:241], v[230:233], v[0:15]
	ds_read_b128 v[238:241], v192 offset:4608
	s_setprio 0
	global_load_dwordx4 v[226:229], v[190:191], off offset:2688
	global_load_dwordx4 v[230:233], v[188:189], off offset:2688
	s_setprio 1
	s_waitcnt lgkmcnt(1)
	v_mfma_f32_32x32x16_bf16 v[112:127], v[234:237], v[176:179], v[112:127]
	v_mfma_f32_32x32x16_bf16 v[48:63], v[234:237], v[180:183], v[48:63]
	s_waitcnt lgkmcnt(0)
	v_mfma_f32_32x32x16_bf16 v[96:111], v[238:241], v[176:179], v[96:111]
	v_mfma_f32_32x32x16_bf16 v[32:47], v[238:241], v[180:183], v[32:47]
	ds_read_b128 v[234:237], v192 offset:9216
	ds_read_b128 v[238:241], v192 offset:13824
	s_waitcnt vmcnt(7)
	ds_write_b128 v215, v[168:171] offset:9216
	s_waitcnt vmcnt(6)
	ds_write_b128 v215, v[172:175] offset:46080
	ds_read_b128 v[168:171], v208 offset:32
	ds_read_b128 v[172:175], v208 offset:4640
	s_waitcnt lgkmcnt(5)
	v_mfma_f32_32x32x16_bf16 v[80:95], v[234:237], v[176:179], v[80:95]
	v_mfma_f32_32x32x16_bf16 v[16:31], v[234:237], v[180:183], v[16:31]
	ds_read_b128 v[234:237], v192 offset:32
	s_waitcnt lgkmcnt(5)
	v_mfma_f32_32x32x16_bf16 v[64:79], v[238:241], v[176:179], v[64:79]
	v_mfma_f32_32x32x16_bf16 v[0:15], v[238:241], v[180:183], v[0:15]
	ds_read_b128 v[238:241], v192 offset:4640
	s_setprio 0
	global_load_dwordx4 v[176:179], v[194:195], off offset:2688
	global_load_dwordx4 v[180:183], v[196:197], off offset:2688
	s_setprio 1
	s_waitcnt lgkmcnt(1)
	v_mfma_f32_32x32x16_bf16 v[112:127], v[234:237], v[168:171], v[112:127]
	v_mfma_f32_32x32x16_bf16 v[48:63], v[234:237], v[172:175], v[48:63]
	s_waitcnt lgkmcnt(0)
	v_mfma_f32_32x32x16_bf16 v[96:111], v[238:241], v[168:171], v[96:111]
	v_mfma_f32_32x32x16_bf16 v[32:47], v[238:241], v[172:175], v[32:47]
	ds_read_b128 v[234:237], v192 offset:9248
	ds_read_b128 v[238:241], v192 offset:13856
	s_waitcnt vmcnt(7)
	ds_write_b128 v215, v[160:163] offset:18432
	s_waitcnt vmcnt(6)
	ds_write_b128 v215, v[164:167] offset:55296
	ds_read_b128 v[160:163], v208 offset:64
	ds_read_b128 v[164:167], v208 offset:4672
	s_waitcnt lgkmcnt(5)
	v_mfma_f32_32x32x16_bf16 v[80:95], v[234:237], v[168:171], v[80:95]
	v_mfma_f32_32x32x16_bf16 v[16:31], v[234:237], v[172:175], v[16:31]
	ds_read_b128 v[234:237], v192 offset:64
	s_waitcnt lgkmcnt(5)
	v_mfma_f32_32x32x16_bf16 v[64:79], v[238:241], v[168:171], v[64:79]
	v_mfma_f32_32x32x16_bf16 v[0:15], v[238:241], v[172:175], v[0:15]
	ds_read_b128 v[238:241], v192 offset:4672
	s_setprio 0
	global_load_dwordx4 v[168:171], v[184:185], off offset:2688
	global_load_dwordx4 v[172:175], v[186:187], off offset:2688
	s_setprio 1
	s_waitcnt lgkmcnt(1)
	v_mfma_f32_32x32x16_bf16 v[112:127], v[234:237], v[160:163], v[112:127]
	v_mfma_f32_32x32x16_bf16 v[48:63], v[234:237], v[164:167], v[48:63]
	s_waitcnt lgkmcnt(0)
	v_mfma_f32_32x32x16_bf16 v[96:111], v[238:241], v[160:163], v[96:111]
	v_mfma_f32_32x32x16_bf16 v[32:47], v[238:241], v[164:167], v[32:47]
	ds_read_b128 v[234:237], v192 offset:9280
	ds_read_b128 v[238:241], v192 offset:13888
	s_waitcnt vmcnt(7)
	ds_write_b128 v215, v[218:221] offset:27648
	s_waitcnt vmcnt(6)
	ds_write_b128 v215, v[222:225] offset:64512
	ds_read_b128 v[218:221], v208 offset:96
	ds_read_b128 v[222:225], v208 offset:4704
	s_waitcnt lgkmcnt(5)
	v_mfma_f32_32x32x16_bf16 v[80:95], v[234:237], v[160:163], v[80:95]
	v_mfma_f32_32x32x16_bf16 v[16:31], v[234:237], v[164:167], v[16:31]
	ds_read_b128 v[234:237], v192 offset:96
	s_waitcnt lgkmcnt(5)
	v_mfma_f32_32x32x16_bf16 v[64:79], v[238:241], v[160:163], v[64:79]
	v_mfma_f32_32x32x16_bf16 v[0:15], v[238:241], v[164:167], v[0:15]
	ds_read_b128 v[238:241], v192 offset:4704
	s_setprio 0
	global_load_dwordx4 v[160:163], v[198:199], off offset:2688
	global_load_dwordx4 v[164:167], v[200:201], off offset:2688
	s_setprio 1
	s_waitcnt lgkmcnt(1)
	v_mfma_f32_32x32x16_bf16 v[112:127], v[234:237], v[218:221], v[112:127]
	v_mfma_f32_32x32x16_bf16 v[48:63], v[234:237], v[222:225], v[48:63]
	s_waitcnt lgkmcnt(0)
	v_mfma_f32_32x32x16_bf16 v[96:111], v[238:241], v[218:221], v[96:111]
	v_mfma_f32_32x32x16_bf16 v[32:47], v[238:241], v[222:225], v[32:47]
	ds_read_b128 v[234:237], v192 offset:9312
	ds_read_b128 v[238:241], v192 offset:13920
	s_waitcnt lgkmcnt(0)
	s_barrier
; template <bool trans>
; DI void gemm_core(const GTile& tl, const GTile& nx, bool has_next  , bool chain  , bool pre, u32x4 (&ra)[4], u32x4 (&rb)[4], char* smem, f32x16 (&acc)[2][4]) {
;     ...
;   const int nk = K / 64;
;   if (!pre) { G_LOAD(0); G_STORE(0); G_LOAD(1); }
;   for (int kt = 0; kt < nk; ++kt) {
;     __syncthreads();
;     G_COMPUTE(kt & 1, kt);
;   }
	s_waitcnt vmcnt(7)
	ds_write_b128 v209, v[226:229]
	s_waitcnt vmcnt(6)
	ds_write_b128 v210, v[230:233]
	ds_read_b128 v[226:229], v205 offset:36864
	ds_read_b128 v[230:233], v205 offset:41472
	v_mfma_f32_32x32x16_bf16 v[80:95], v[234:237], v[218:221], v[80:95]
	v_mfma_f32_32x32x16_bf16 v[16:31], v[234:237], v[222:225], v[16:31]
	ds_read_b128 v[234:237], v204
	v_mfma_f32_32x32x16_bf16 v[64:79], v[238:241], v[218:221], v[64:79]
	v_mfma_f32_32x32x16_bf16 v[0:15], v[238:241], v[222:225], v[0:15]
	ds_read_b128 v[238:241], v204 offset:4608
	s_setprio 0
	global_load_dwordx4 v[218:221], v[190:191], off offset:2816
	global_load_dwordx4 v[222:225], v[188:189], off offset:2816
	s_setprio 1
	s_waitcnt lgkmcnt(1)
	v_mfma_f32_32x32x16_bf16 v[112:127], v[234:237], v[226:229], v[112:127]
	v_mfma_f32_32x32x16_bf16 v[48:63], v[234:237], v[230:233], v[48:63]
	s_waitcnt lgkmcnt(0)
	v_mfma_f32_32x32x16_bf16 v[96:111], v[238:241], v[226:229], v[96:111]
	v_mfma_f32_32x32x16_bf16 v[32:47], v[238:241], v[230:233], v[32:47]
	ds_read_b128 v[234:237], v204 offset:9216
	ds_read_b128 v[238:241], v204 offset:13824
	s_waitcnt vmcnt(7)
	ds_write_b128 v212, v[176:179]
	s_waitcnt vmcnt(6)
	ds_write_b128 v211, v[180:183]
	ds_read_b128 v[176:179], v205 offset:36896
	ds_read_b128 v[180:183], v205 offset:41504
	s_waitcnt lgkmcnt(5)
	v_mfma_f32_32x32x16_bf16 v[80:95], v[234:237], v[226:229], v[80:95]
	v_mfma_f32_32x32x16_bf16 v[16:31], v[234:237], v[230:233], v[16:31]
	ds_read_b128 v[234:237], v204 offset:32
	s_waitcnt lgkmcnt(5)
	v_mfma_f32_32x32x16_bf16 v[64:79], v[238:241], v[226:229], v[64:79]
	v_mfma_f32_32x32x16_bf16 v[0:15], v[238:241], v[230:233], v[0:15]
	ds_read_b128 v[238:241], v204 offset:4640
	s_setprio 0
	global_load_dwordx4 v[226:229], v[194:195], off offset:2816
	global_load_dwordx4 v[230:233], v[196:197], off offset:2816
	s_setprio 1
	s_waitcnt lgkmcnt(1)
	v_mfma_f32_32x32x16_bf16 v[112:127], v[234:237], v[176:179], v[112:127]
	v_mfma_f32_32x32x16_bf16 v[48:63], v[234:237], v[180:183], v[48:63]
	s_waitcnt lgkmcnt(0)
	v_mfma_f32_32x32x16_bf16 v[96:111], v[238:241], v[176:179], v[96:111]
	v_mfma_f32_32x32x16_bf16 v[32:47], v[238:241], v[180:183], v[32:47]
	ds_read_b128 v[234:237], v204 offset:9248
	ds_read_b128 v[238:241], v204 offset:13856
	s_waitcnt vmcnt(7)
	ds_write_b128 v214, v[168:171]
	s_waitcnt vmcnt(6)
	ds_write_b128 v213, v[172:175]
	ds_read_b128 v[168:171], v205 offset:36928
	ds_read_b128 v[172:175], v205 offset:41536
	s_waitcnt lgkmcnt(5)
	v_mfma_f32_32x32x16_bf16 v[80:95], v[234:237], v[176:179], v[80:95]
	v_mfma_f32_32x32x16_bf16 v[16:31], v[234:237], v[180:183], v[16:31]
	ds_read_b128 v[234:237], v204 offset:64
	s_waitcnt lgkmcnt(5)
	v_mfma_f32_32x32x16_bf16 v[64:79], v[238:241], v[176:179], v[64:79]
	v_mfma_f32_32x32x16_bf16 v[0:15], v[238:241], v[180:183], v[0:15]
	ds_read_b128 v[238:241], v204 offset:4672
	s_setprio 0
	global_load_dwordx4 v[176:179], v[184:185], off offset:2816
	global_load_dwordx4 v[180:183], v[186:187], off offset:2816
	s_setprio 1
	s_waitcnt lgkmcnt(1)
	v_mfma_f32_32x32x16_bf16 v[112:127], v[234:237], v[168:171], v[112:127]
	v_mfma_f32_32x32x16_bf16 v[48:63], v[234:237], v[172:175], v[48:63]
	s_waitcnt lgkmcnt(0)
	v_mfma_f32_32x32x16_bf16 v[96:111], v[238:241], v[168:171], v[96:111]
	v_mfma_f32_32x32x16_bf16 v[32:47], v[238:241], v[172:175], v[32:47]
	ds_read_b128 v[234:237], v204 offset:9280
	ds_read_b128 v[238:241], v204 offset:13888
	s_waitcnt vmcnt(7)
	ds_write_b128 v217, v[160:163]
	s_waitcnt vmcnt(6)
	ds_write_b128 v216, v[164:167]
	ds_read_b128 v[160:163], v205 offset:36960
	ds_read_b128 v[164:167], v205 offset:41568
	s_waitcnt lgkmcnt(5)
	v_mfma_f32_32x32x16_bf16 v[80:95], v[234:237], v[168:171], v[80:95]
	v_mfma_f32_32x32x16_bf16 v[16:31], v[234:237], v[172:175], v[16:31]
	ds_read_b128 v[234:237], v204 offset:96
	s_waitcnt lgkmcnt(5)
	v_mfma_f32_32x32x16_bf16 v[64:79], v[238:241], v[168:171], v[64:79]
	v_mfma_f32_32x32x16_bf16 v[0:15], v[238:241], v[172:175], v[0:15]
	ds_read_b128 v[238:241], v204 offset:4704
	s_setprio 0
	global_load_dwordx4 v[168:171], v[198:199], off offset:2816
	global_load_dwordx4 v[172:175], v[200:201], off offset:2816
	s_setprio 1
	s_waitcnt lgkmcnt(1)
	v_mfma_f32_32x32x16_bf16 v[112:127], v[234:237], v[160:163], v[112:127]
	v_mfma_f32_32x32x16_bf16 v[48:63], v[234:237], v[164:167], v[48:63]
	s_waitcnt lgkmcnt(0)
	v_mfma_f32_32x32x16_bf16 v[96:111], v[238:241], v[160:163], v[96:111]
	v_mfma_f32_32x32x16_bf16 v[32:47], v[238:241], v[164:167], v[32:47]
	ds_read_b128 v[234:237], v204 offset:9312
	ds_read_b128 v[238:241], v204 offset:13920
	s_waitcnt lgkmcnt(0)
	s_barrier
; template <bool trans>
; DI void gemm_core(const GTile& tl, const GTile& nx, bool has_next  , bool chain  , bool pre, u32x4 (&ra)[4], u32x4 (&rb)[4], char* smem, f32x16 (&acc)[2][4]) {
;     ...
;   const int nk = K / 64;
;   if (!pre) { G_LOAD(0); G_STORE(0); G_LOAD(1); }
;   for (int kt = 0; kt < nk; ++kt) {
;     __syncthreads();
;     G_COMPUTE(kt & 1, kt);
;   }
	s_waitcnt vmcnt(7)
	ds_write_b128 v215, v[218:221]
	s_waitcnt vmcnt(6)
	ds_write_b128 v215, v[222:225] offset:36864
	ds_read_b128 v[218:221], v208
	ds_read_b128 v[222:225], v208 offset:4608
	v_mfma_f32_32x32x16_bf16 v[80:95], v[234:237], v[160:163], v[80:95]
	v_mfma_f32_32x32x16_bf16 v[16:31], v[234:237], v[164:167], v[16:31]
	ds_read_b128 v[234:237], v192
	v_mfma_f32_32x32x16_bf16 v[64:79], v[238:241], v[160:163], v[64:79]
	v_mfma_f32_32x32x16_bf16 v[0:15], v[238:241], v[164:167], v[0:15]
	ds_read_b128 v[238:241], v192 offset:4608
	s_setprio 0
	global_load_dwordx4 v[160:163], v[190:191], off offset:2944
	global_load_dwordx4 v[164:167], v[188:189], off offset:2944
	s_setprio 1
	s_waitcnt lgkmcnt(1)
	v_mfma_f32_32x32x16_bf16 v[112:127], v[234:237], v[218:221], v[112:127]
	v_mfma_f32_32x32x16_bf16 v[48:63], v[234:237], v[222:225], v[48:63]
	s_waitcnt lgkmcnt(0)
	v_mfma_f32_32x32x16_bf16 v[96:111], v[238:241], v[218:221], v[96:111]
	v_mfma_f32_32x32x16_bf16 v[32:47], v[238:241], v[222:225], v[32:47]
	ds_read_b128 v[234:237], v192 offset:9216
	ds_read_b128 v[238:241], v192 offset:13824
	s_waitcnt vmcnt(7)
	ds_write_b128 v215, v[226:229] offset:9216
	s_waitcnt vmcnt(6)
	ds_write_b128 v215, v[230:233] offset:46080
	ds_read_b128 v[226:229], v208 offset:32
	ds_read_b128 v[230:233], v208 offset:4640
	s_waitcnt lgkmcnt(5)
	v_mfma_f32_32x32x16_bf16 v[80:95], v[234:237], v[218:221], v[80:95]
	v_mfma_f32_32x32x16_bf16 v[16:31], v[234:237], v[222:225], v[16:31]
	ds_read_b128 v[234:237], v192 offset:32
	s_waitcnt lgkmcnt(5)
	v_mfma_f32_32x32x16_bf16 v[64:79], v[238:241], v[218:221], v[64:79]
	v_mfma_f32_32x32x16_bf16 v[0:15], v[238:241], v[222:225], v[0:15]
	ds_read_b128 v[238:241], v192 offset:4640
	s_setprio 0
	global_load_dwordx4 v[218:221], v[194:195], off offset:2944
	global_load_dwordx4 v[222:225], v[196:197], off offset:2944
	s_setprio 1
	s_waitcnt lgkmcnt(1)
	v_mfma_f32_32x32x16_bf16 v[112:127], v[234:237], v[226:229], v[112:127]
	v_mfma_f32_32x32x16_bf16 v[48:63], v[234:237], v[230:233], v[48:63]
	s_waitcnt lgkmcnt(0)
	v_mfma_f32_32x32x16_bf16 v[96:111], v[238:241], v[226:229], v[96:111]
	v_mfma_f32_32x32x16_bf16 v[32:47], v[238:241], v[230:233], v[32:47]
	ds_read_b128 v[234:237], v192 offset:9248
	ds_read_b128 v[238:241], v192 offset:13856
	s_waitcnt vmcnt(7)
	ds_write_b128 v215, v[176:179] offset:18432
	s_waitcnt vmcnt(6)
	ds_write_b128 v215, v[180:183] offset:55296
	ds_read_b128 v[176:179], v208 offset:64
	ds_read_b128 v[180:183], v208 offset:4672
	s_waitcnt lgkmcnt(5)
	v_mfma_f32_32x32x16_bf16 v[80:95], v[234:237], v[226:229], v[80:95]
	v_mfma_f32_32x32x16_bf16 v[16:31], v[234:237], v[230:233], v[16:31]
	ds_read_b128 v[234:237], v192 offset:64
	s_waitcnt lgkmcnt(5)
	v_mfma_f32_32x32x16_bf16 v[64:79], v[238:241], v[226:229], v[64:79]
	v_mfma_f32_32x32x16_bf16 v[0:15], v[238:241], v[230:233], v[0:15]
	ds_read_b128 v[238:241], v192 offset:4672
	s_setprio 0
	global_load_dwordx4 v[226:229], v[184:185], off offset:2944
	global_load_dwordx4 v[230:233], v[186:187], off offset:2944
	s_setprio 1
	s_waitcnt lgkmcnt(1)
	v_mfma_f32_32x32x16_bf16 v[112:127], v[234:237], v[176:179], v[112:127]
	v_mfma_f32_32x32x16_bf16 v[48:63], v[234:237], v[180:183], v[48:63]
	s_waitcnt lgkmcnt(0)
	v_mfma_f32_32x32x16_bf16 v[96:111], v[238:241], v[176:179], v[96:111]
	v_mfma_f32_32x32x16_bf16 v[32:47], v[238:241], v[180:183], v[32:47]
	ds_read_b128 v[234:237], v192 offset:9280
	ds_read_b128 v[238:241], v192 offset:13888
	s_waitcnt vmcnt(7)
	ds_write_b128 v215, v[168:171] offset:27648
	s_waitcnt vmcnt(6)
	ds_write_b128 v215, v[172:175] offset:64512
	ds_read_b128 v[168:171], v208 offset:96
	ds_read_b128 v[172:175], v208 offset:4704
	s_waitcnt lgkmcnt(5)
	v_mfma_f32_32x32x16_bf16 v[80:95], v[234:237], v[176:179], v[80:95]
	v_mfma_f32_32x32x16_bf16 v[16:31], v[234:237], v[180:183], v[16:31]
	ds_read_b128 v[234:237], v192 offset:96
	s_waitcnt lgkmcnt(5)
	v_mfma_f32_32x32x16_bf16 v[64:79], v[238:241], v[176:179], v[64:79]
	v_mfma_f32_32x32x16_bf16 v[0:15], v[238:241], v[180:183], v[0:15]
	ds_read_b128 v[238:241], v192 offset:4704
	s_setprio 0
	global_load_dwordx4 v[176:179], v[198:199], off offset:2944
	global_load_dwordx4 v[180:183], v[200:201], off offset:2944
	s_setprio 1
	s_waitcnt lgkmcnt(1)
	v_mfma_f32_32x32x16_bf16 v[112:127], v[234:237], v[168:171], v[112:127]
	v_mfma_f32_32x32x16_bf16 v[48:63], v[234:237], v[172:175], v[48:63]
	s_waitcnt lgkmcnt(0)
	v_mfma_f32_32x32x16_bf16 v[96:111], v[238:241], v[168:171], v[96:111]
	v_mfma_f32_32x32x16_bf16 v[32:47], v[238:241], v[172:175], v[32:47]
	ds_read_b128 v[234:237], v192 offset:9312
	ds_read_b128 v[238:241], v192 offset:13920
	s_waitcnt lgkmcnt(0)
	s_barrier
; template <bool trans>
; DI void gemm_core(const GTile& tl, const GTile& nx, bool has_next  , bool chain  , bool pre, u32x4 (&ra)[4], u32x4 (&rb)[4], char* smem, f32x16 (&acc)[2][4]) {
;     ...
;   const int nk = K / 64;
;   if (!pre) { G_LOAD(0); G_STORE(0); G_LOAD(1); }
;   for (int kt = 0; kt < nk; ++kt) {
;     __syncthreads();
;     G_COMPUTE(kt & 1, kt);
;   }
	s_waitcnt vmcnt(7)
	ds_write_b128 v209, v[160:163]
	s_waitcnt vmcnt(6)
	ds_write_b128 v210, v[164:167]
	ds_read_b128 v[160:163], v205 offset:36864
	ds_read_b128 v[164:167], v205 offset:41472
	v_mfma_f32_32x32x16_bf16 v[80:95], v[234:237], v[168:171], v[80:95]
	v_mfma_f32_32x32x16_bf16 v[16:31], v[234:237], v[172:175], v[16:31]
	ds_read_b128 v[234:237], v204
	v_mfma_f32_32x32x16_bf16 v[64:79], v[238:241], v[168:171], v[64:79]
	v_mfma_f32_32x32x16_bf16 v[0:15], v[238:241], v[172:175], v[0:15]
	ds_read_b128 v[238:241], v204 offset:4608
	s_setprio 0
	global_load_dwordx4 v[168:171], v[190:191], off offset:3072
	global_load_dwordx4 v[172:175], v[188:189], off offset:3072
	s_setprio 1
	s_waitcnt lgkmcnt(1)
	v_mfma_f32_32x32x16_bf16 v[112:127], v[234:237], v[160:163], v[112:127]
	v_mfma_f32_32x32x16_bf16 v[48:63], v[234:237], v[164:167], v[48:63]
	s_waitcnt lgkmcnt(0)
	v_mfma_f32_32x32x16_bf16 v[96:111], v[238:241], v[160:163], v[96:111]
	v_mfma_f32_32x32x16_bf16 v[32:47], v[238:241], v[164:167], v[32:47]
	ds_read_b128 v[234:237], v204 offset:9216
	ds_read_b128 v[238:241], v204 offset:13824
	s_waitcnt vmcnt(7)
	ds_write_b128 v212, v[218:221]
	s_waitcnt vmcnt(6)
	ds_write_b128 v211, v[222:225]
	ds_read_b128 v[218:221], v205 offset:36896
	ds_read_b128 v[222:225], v205 offset:41504
	s_waitcnt lgkmcnt(5)
	v_mfma_f32_32x32x16_bf16 v[80:95], v[234:237], v[160:163], v[80:95]
	v_mfma_f32_32x32x16_bf16 v[16:31], v[234:237], v[164:167], v[16:31]
	ds_read_b128 v[234:237], v204 offset:32
	s_waitcnt lgkmcnt(5)
	v_mfma_f32_32x32x16_bf16 v[64:79], v[238:241], v[160:163], v[64:79]
	v_mfma_f32_32x32x16_bf16 v[0:15], v[238:241], v[164:167], v[0:15]
	ds_read_b128 v[238:241], v204 offset:4640
	s_setprio 0
	global_load_dwordx4 v[160:163], v[194:195], off offset:3072
	global_load_dwordx4 v[164:167], v[196:197], off offset:3072
	s_setprio 1
	s_waitcnt lgkmcnt(1)
	v_mfma_f32_32x32x16_bf16 v[112:127], v[234:237], v[218:221], v[112:127]
	v_mfma_f32_32x32x16_bf16 v[48:63], v[234:237], v[222:225], v[48:63]
	s_waitcnt lgkmcnt(0)
	v_mfma_f32_32x32x16_bf16 v[96:111], v[238:241], v[218:221], v[96:111]
	v_mfma_f32_32x32x16_bf16 v[32:47], v[238:241], v[222:225], v[32:47]
	ds_read_b128 v[234:237], v204 offset:9248
	ds_read_b128 v[238:241], v204 offset:13856
	s_waitcnt vmcnt(7)
	ds_write_b128 v214, v[226:229]
	s_waitcnt vmcnt(6)
	ds_write_b128 v213, v[230:233]
	ds_read_b128 v[226:229], v205 offset:36928
	ds_read_b128 v[230:233], v205 offset:41536
	s_waitcnt lgkmcnt(5)
	v_mfma_f32_32x32x16_bf16 v[80:95], v[234:237], v[218:221], v[80:95]
	v_mfma_f32_32x32x16_bf16 v[16:31], v[234:237], v[222:225], v[16:31]
	ds_read_b128 v[234:237], v204 offset:64
	s_waitcnt lgkmcnt(5)
	v_mfma_f32_32x32x16_bf16 v[64:79], v[238:241], v[218:221], v[64:79]
	v_mfma_f32_32x32x16_bf16 v[0:15], v[238:241], v[222:225], v[0:15]
	ds_read_b128 v[238:241], v204 offset:4672
	s_setprio 0
	global_load_dwordx4 v[218:221], v[184:185], off offset:3072
	global_load_dwordx4 v[222:225], v[186:187], off offset:3072
	s_setprio 1
	s_waitcnt lgkmcnt(1)
	v_mfma_f32_32x32x16_bf16 v[112:127], v[234:237], v[226:229], v[112:127]
	v_mfma_f32_32x32x16_bf16 v[48:63], v[234:237], v[230:233], v[48:63]
	s_waitcnt lgkmcnt(0)
	v_mfma_f32_32x32x16_bf16 v[96:111], v[238:241], v[226:229], v[96:111]
	v_mfma_f32_32x32x16_bf16 v[32:47], v[238:241], v[230:233], v[32:47]
	ds_read_b128 v[234:237], v204 offset:9280
	ds_read_b128 v[238:241], v204 offset:13888
	s_waitcnt vmcnt(7)
	ds_write_b128 v217, v[176:179]
	s_waitcnt vmcnt(6)
	ds_write_b128 v216, v[180:183]
	ds_read_b128 v[176:179], v205 offset:36960
	ds_read_b128 v[180:183], v205 offset:41568
	s_waitcnt lgkmcnt(5)
	v_mfma_f32_32x32x16_bf16 v[80:95], v[234:237], v[226:229], v[80:95]
	v_mfma_f32_32x32x16_bf16 v[16:31], v[234:237], v[230:233], v[16:31]
	ds_read_b128 v[234:237], v204 offset:96
	s_waitcnt lgkmcnt(5)
	v_mfma_f32_32x32x16_bf16 v[64:79], v[238:241], v[226:229], v[64:79]
	v_mfma_f32_32x32x16_bf16 v[0:15], v[238:241], v[230:233], v[0:15]
	ds_read_b128 v[238:241], v204 offset:4704
	s_setprio 0
	global_load_dwordx4 v[226:229], v[198:199], off offset:3072
	global_load_dwordx4 v[230:233], v[200:201], off offset:3072
	s_setprio 1
	s_waitcnt lgkmcnt(1)
	v_mfma_f32_32x32x16_bf16 v[112:127], v[234:237], v[176:179], v[112:127]
	v_mfma_f32_32x32x16_bf16 v[48:63], v[234:237], v[180:183], v[48:63]
	s_waitcnt lgkmcnt(0)
	v_mfma_f32_32x32x16_bf16 v[96:111], v[238:241], v[176:179], v[96:111]
	v_mfma_f32_32x32x16_bf16 v[32:47], v[238:241], v[180:183], v[32:47]
	ds_read_b128 v[234:237], v204 offset:9312
	ds_read_b128 v[238:241], v204 offset:13920
	s_waitcnt lgkmcnt(0)
	s_barrier
; template <bool trans>
; DI void gemm_core(const GTile& tl, const GTile& nx, bool has_next  , bool chain  , bool pre, u32x4 (&ra)[4], u32x4 (&rb)[4], char* smem, f32x16 (&acc)[2][4]) {
;     ...
;   const int nk = K / 64;
;   if (!pre) { G_LOAD(0); G_STORE(0); G_LOAD(1); }
;   for (int kt = 0; kt < nk; ++kt) {
;     __syncthreads();
;     G_COMPUTE(kt & 1, kt);
;   }
	s_waitcnt vmcnt(7)
	ds_write_b128 v215, v[168:171]
	s_waitcnt vmcnt(6)
	ds_write_b128 v215, v[172:175] offset:36864
	ds_read_b128 v[168:171], v208
	ds_read_b128 v[172:175], v208 offset:4608
	v_mfma_f32_32x32x16_bf16 v[80:95], v[234:237], v[176:179], v[80:95]
	v_mfma_f32_32x32x16_bf16 v[16:31], v[234:237], v[180:183], v[16:31]
	ds_read_b128 v[234:237], v192
	v_mfma_f32_32x32x16_bf16 v[64:79], v[238:241], v[176:179], v[64:79]
	v_mfma_f32_32x32x16_bf16 v[0:15], v[238:241], v[180:183], v[0:15]
	ds_read_b128 v[238:241], v192 offset:4608
	s_setprio 0
	global_load_dwordx4 v[176:179], v[190:191], off offset:3200
	global_load_dwordx4 v[180:183], v[188:189], off offset:3200
	s_setprio 1
	s_waitcnt lgkmcnt(1)
	v_mfma_f32_32x32x16_bf16 v[112:127], v[234:237], v[168:171], v[112:127]
	v_mfma_f32_32x32x16_bf16 v[48:63], v[234:237], v[172:175], v[48:63]
	s_waitcnt lgkmcnt(0)
	v_mfma_f32_32x32x16_bf16 v[96:111], v[238:241], v[168:171], v[96:111]
	v_mfma_f32_32x32x16_bf16 v[32:47], v[238:241], v[172:175], v[32:47]
	ds_read_b128 v[234:237], v192 offset:9216
	ds_read_b128 v[238:241], v192 offset:13824
	s_waitcnt vmcnt(7)
	ds_write_b128 v215, v[160:163] offset:9216
	s_waitcnt vmcnt(6)
	ds_write_b128 v215, v[164:167] offset:46080
	ds_read_b128 v[160:163], v208 offset:32
	ds_read_b128 v[164:167], v208 offset:4640
	s_waitcnt lgkmcnt(5)
	v_mfma_f32_32x32x16_bf16 v[80:95], v[234:237], v[168:171], v[80:95]
	v_mfma_f32_32x32x16_bf16 v[16:31], v[234:237], v[172:175], v[16:31]
	ds_read_b128 v[234:237], v192 offset:32
	s_waitcnt lgkmcnt(5)
	v_mfma_f32_32x32x16_bf16 v[64:79], v[238:241], v[168:171], v[64:79]
	v_mfma_f32_32x32x16_bf16 v[0:15], v[238:241], v[172:175], v[0:15]
	ds_read_b128 v[238:241], v192 offset:4640
	s_setprio 0
	global_load_dwordx4 v[168:171], v[194:195], off offset:3200
	global_load_dwordx4 v[172:175], v[196:197], off offset:3200
	s_setprio 1
	s_waitcnt lgkmcnt(1)
	v_mfma_f32_32x32x16_bf16 v[112:127], v[234:237], v[160:163], v[112:127]
	v_mfma_f32_32x32x16_bf16 v[48:63], v[234:237], v[164:167], v[48:63]
	s_waitcnt lgkmcnt(0)
	v_mfma_f32_32x32x16_bf16 v[96:111], v[238:241], v[160:163], v[96:111]
	v_mfma_f32_32x32x16_bf16 v[32:47], v[238:241], v[164:167], v[32:47]
	ds_read_b128 v[234:237], v192 offset:9248
	ds_read_b128 v[238:241], v192 offset:13856
	s_waitcnt vmcnt(7)
	ds_write_b128 v215, v[218:221] offset:18432
	s_waitcnt vmcnt(6)
	ds_write_b128 v215, v[222:225] offset:55296
	ds_read_b128 v[218:221], v208 offset:64
	ds_read_b128 v[222:225], v208 offset:4672
	s_waitcnt lgkmcnt(5)
	v_mfma_f32_32x32x16_bf16 v[80:95], v[234:237], v[160:163], v[80:95]
	v_mfma_f32_32x32x16_bf16 v[16:31], v[234:237], v[164:167], v[16:31]
	ds_read_b128 v[234:237], v192 offset:64
	s_waitcnt lgkmcnt(5)
	v_mfma_f32_32x32x16_bf16 v[64:79], v[238:241], v[160:163], v[64:79]
	v_mfma_f32_32x32x16_bf16 v[0:15], v[238:241], v[164:167], v[0:15]
	ds_read_b128 v[238:241], v192 offset:4672
	s_setprio 0
	global_load_dwordx4 v[160:163], v[184:185], off offset:3200
	global_load_dwordx4 v[164:167], v[186:187], off offset:3200
	s_setprio 1
	s_waitcnt lgkmcnt(1)
	v_mfma_f32_32x32x16_bf16 v[112:127], v[234:237], v[218:221], v[112:127]
	v_mfma_f32_32x32x16_bf16 v[48:63], v[234:237], v[222:225], v[48:63]
	s_waitcnt lgkmcnt(0)
	v_mfma_f32_32x32x16_bf16 v[96:111], v[238:241], v[218:221], v[96:111]
	v_mfma_f32_32x32x16_bf16 v[32:47], v[238:241], v[222:225], v[32:47]
	ds_read_b128 v[234:237], v192 offset:9280
	ds_read_b128 v[238:241], v192 offset:13888
	s_waitcnt vmcnt(7)
	ds_write_b128 v215, v[226:229] offset:27648
	s_waitcnt vmcnt(6)
	ds_write_b128 v215, v[230:233] offset:64512
	ds_read_b128 v[226:229], v208 offset:96
	ds_read_b128 v[230:233], v208 offset:4704
	s_waitcnt lgkmcnt(5)
	v_mfma_f32_32x32x16_bf16 v[80:95], v[234:237], v[218:221], v[80:95]
	v_mfma_f32_32x32x16_bf16 v[16:31], v[234:237], v[222:225], v[16:31]
	ds_read_b128 v[234:237], v192 offset:96
	s_waitcnt lgkmcnt(5)
	v_mfma_f32_32x32x16_bf16 v[64:79], v[238:241], v[218:221], v[64:79]
	v_mfma_f32_32x32x16_bf16 v[0:15], v[238:241], v[222:225], v[0:15]
	ds_read_b128 v[238:241], v192 offset:4704
	s_setprio 0
	global_load_dwordx4 v[218:221], v[198:199], off offset:3200
	global_load_dwordx4 v[222:225], v[200:201], off offset:3200
	s_setprio 1
	s_waitcnt lgkmcnt(1)
	v_mfma_f32_32x32x16_bf16 v[112:127], v[234:237], v[226:229], v[112:127]
	v_mfma_f32_32x32x16_bf16 v[48:63], v[234:237], v[230:233], v[48:63]
	s_waitcnt lgkmcnt(0)
	v_mfma_f32_32x32x16_bf16 v[96:111], v[238:241], v[226:229], v[96:111]
	v_mfma_f32_32x32x16_bf16 v[32:47], v[238:241], v[230:233], v[32:47]
	ds_read_b128 v[234:237], v192 offset:9312
	ds_read_b128 v[238:241], v192 offset:13920
	s_waitcnt lgkmcnt(0)
	s_barrier
; template <bool trans>
; DI void gemm_core(const GTile& tl, const GTile& nx, bool has_next  , bool chain  , bool pre, u32x4 (&ra)[4], u32x4 (&rb)[4], char* smem, f32x16 (&acc)[2][4]) {
;     ...
;   const int nk = K / 64;
;   if (!pre) { G_LOAD(0); G_STORE(0); G_LOAD(1); }
;   for (int kt = 0; kt < nk; ++kt) {
;     __syncthreads();
;     G_COMPUTE(kt & 1, kt);
;   }
	s_waitcnt vmcnt(7)
	ds_write_b128 v209, v[176:179]
	s_waitcnt vmcnt(6)
	ds_write_b128 v210, v[180:183]
	ds_read_b128 v[176:179], v205 offset:36864
	ds_read_b128 v[180:183], v205 offset:41472
	v_mfma_f32_32x32x16_bf16 v[80:95], v[234:237], v[226:229], v[80:95]
	v_mfma_f32_32x32x16_bf16 v[16:31], v[234:237], v[230:233], v[16:31]
	ds_read_b128 v[234:237], v204
	v_mfma_f32_32x32x16_bf16 v[64:79], v[238:241], v[226:229], v[64:79]
	v_mfma_f32_32x32x16_bf16 v[0:15], v[238:241], v[230:233], v[0:15]
	ds_read_b128 v[238:241], v204 offset:4608
	s_setprio 0
	global_load_dwordx4 v[226:229], v[190:191], off offset:3328
	global_load_dwordx4 v[230:233], v[188:189], off offset:3328
	s_setprio 1
	s_waitcnt lgkmcnt(1)
	v_mfma_f32_32x32x16_bf16 v[112:127], v[234:237], v[176:179], v[112:127]
	v_mfma_f32_32x32x16_bf16 v[48:63], v[234:237], v[180:183], v[48:63]
	s_waitcnt lgkmcnt(0)
	v_mfma_f32_32x32x16_bf16 v[96:111], v[238:241], v[176:179], v[96:111]
	v_mfma_f32_32x32x16_bf16 v[32:47], v[238:241], v[180:183], v[32:47]
	ds_read_b128 v[234:237], v204 offset:9216
	ds_read_b128 v[238:241], v204 offset:13824
	s_waitcnt vmcnt(7)
	ds_write_b128 v212, v[168:171]
	s_waitcnt vmcnt(6)
	ds_write_b128 v211, v[172:175]
	ds_read_b128 v[168:171], v205 offset:36896
	ds_read_b128 v[172:175], v205 offset:41504
	s_waitcnt lgkmcnt(5)
	v_mfma_f32_32x32x16_bf16 v[80:95], v[234:237], v[176:179], v[80:95]
	v_mfma_f32_32x32x16_bf16 v[16:31], v[234:237], v[180:183], v[16:31]
	ds_read_b128 v[234:237], v204 offset:32
	s_waitcnt lgkmcnt(5)
	v_mfma_f32_32x32x16_bf16 v[64:79], v[238:241], v[176:179], v[64:79]
	v_mfma_f32_32x32x16_bf16 v[0:15], v[238:241], v[180:183], v[0:15]
	ds_read_b128 v[238:241], v204 offset:4640
	s_setprio 0
	global_load_dwordx4 v[176:179], v[194:195], off offset:3328
	global_load_dwordx4 v[180:183], v[196:197], off offset:3328
	s_setprio 1
	s_waitcnt lgkmcnt(1)
	v_mfma_f32_32x32x16_bf16 v[112:127], v[234:237], v[168:171], v[112:127]
	v_mfma_f32_32x32x16_bf16 v[48:63], v[234:237], v[172:175], v[48:63]
	s_waitcnt lgkmcnt(0)
	v_mfma_f32_32x32x16_bf16 v[96:111], v[238:241], v[168:171], v[96:111]
	v_mfma_f32_32x32x16_bf16 v[32:47], v[238:241], v[172:175], v[32:47]
	ds_read_b128 v[234:237], v204 offset:9248
	ds_read_b128 v[238:241], v204 offset:13856
	s_waitcnt vmcnt(7)
	ds_write_b128 v214, v[160:163]
	s_waitcnt vmcnt(6)
	ds_write_b128 v213, v[164:167]
	ds_read_b128 v[160:163], v205 offset:36928
	ds_read_b128 v[164:167], v205 offset:41536
	s_waitcnt lgkmcnt(5)
	v_mfma_f32_32x32x16_bf16 v[80:95], v[234:237], v[168:171], v[80:95]
	v_mfma_f32_32x32x16_bf16 v[16:31], v[234:237], v[172:175], v[16:31]
	ds_read_b128 v[234:237], v204 offset:64
	s_waitcnt lgkmcnt(5)
	v_mfma_f32_32x32x16_bf16 v[64:79], v[238:241], v[168:171], v[64:79]
	v_mfma_f32_32x32x16_bf16 v[0:15], v[238:241], v[172:175], v[0:15]
	ds_read_b128 v[238:241], v204 offset:4672
	s_setprio 0
	global_load_dwordx4 v[168:171], v[184:185], off offset:3328
	global_load_dwordx4 v[172:175], v[186:187], off offset:3328
	s_setprio 1
	s_waitcnt lgkmcnt(1)
	v_mfma_f32_32x32x16_bf16 v[112:127], v[234:237], v[160:163], v[112:127]
	v_mfma_f32_32x32x16_bf16 v[48:63], v[234:237], v[164:167], v[48:63]
	s_waitcnt lgkmcnt(0)
	v_mfma_f32_32x32x16_bf16 v[96:111], v[238:241], v[160:163], v[96:111]
	v_mfma_f32_32x32x16_bf16 v[32:47], v[238:241], v[164:167], v[32:47]
	ds_read_b128 v[234:237], v204 offset:9280
	ds_read_b128 v[238:241], v204 offset:13888
	s_waitcnt vmcnt(7)
	ds_write_b128 v217, v[218:221]
	s_waitcnt vmcnt(6)
	ds_write_b128 v216, v[222:225]
	ds_read_b128 v[218:221], v205 offset:36960
	ds_read_b128 v[222:225], v205 offset:41568
	s_waitcnt lgkmcnt(5)
	v_mfma_f32_32x32x16_bf16 v[80:95], v[234:237], v[160:163], v[80:95]
	v_mfma_f32_32x32x16_bf16 v[16:31], v[234:237], v[164:167], v[16:31]
	ds_read_b128 v[234:237], v204 offset:96
	s_waitcnt lgkmcnt(5)
	v_mfma_f32_32x32x16_bf16 v[64:79], v[238:241], v[160:163], v[64:79]
	v_mfma_f32_32x32x16_bf16 v[0:15], v[238:241], v[164:167], v[0:15]
	ds_read_b128 v[238:241], v204 offset:4704
	s_setprio 0
	global_load_dwordx4 v[160:163], v[198:199], off offset:3328
	global_load_dwordx4 v[164:167], v[200:201], off offset:3328
	s_setprio 1
	s_waitcnt lgkmcnt(1)
	v_mfma_f32_32x32x16_bf16 v[112:127], v[234:237], v[218:221], v[112:127]
	v_mfma_f32_32x32x16_bf16 v[48:63], v[234:237], v[222:225], v[48:63]
	s_waitcnt lgkmcnt(0)
	v_mfma_f32_32x32x16_bf16 v[96:111], v[238:241], v[218:221], v[96:111]
	v_mfma_f32_32x32x16_bf16 v[32:47], v[238:241], v[222:225], v[32:47]
	ds_read_b128 v[234:237], v204 offset:9312
	ds_read_b128 v[238:241], v204 offset:13920
	s_waitcnt lgkmcnt(0)
	s_barrier
; template <bool trans>
; DI void gemm_core(const GTile& tl, const GTile& nx, bool has_next  , bool chain  , bool pre, u32x4 (&ra)[4], u32x4 (&rb)[4], char* smem, f32x16 (&acc)[2][4]) {
;     ...
;   const int nk = K / 64;
;   if (!pre) { G_LOAD(0); G_STORE(0); G_LOAD(1); }
;   for (int kt = 0; kt < nk; ++kt) {
;     __syncthreads();
;     G_COMPUTE(kt & 1, kt);
;   }
	s_waitcnt vmcnt(7)
	ds_write_b128 v215, v[226:229]
	s_waitcnt vmcnt(6)
	ds_write_b128 v215, v[230:233] offset:36864
	ds_read_b128 v[226:229], v208
	ds_read_b128 v[230:233], v208 offset:4608
	v_mfma_f32_32x32x16_bf16 v[80:95], v[234:237], v[218:221], v[80:95]
	v_mfma_f32_32x32x16_bf16 v[16:31], v[234:237], v[222:225], v[16:31]
	ds_read_b128 v[234:237], v192
	v_mfma_f32_32x32x16_bf16 v[64:79], v[238:241], v[218:221], v[64:79]
	v_mfma_f32_32x32x16_bf16 v[0:15], v[238:241], v[222:225], v[0:15]
	ds_read_b128 v[238:241], v192 offset:4608
	s_setprio 0
	global_load_dwordx4 v[218:221], v[190:191], off offset:3456
	global_load_dwordx4 v[222:225], v[188:189], off offset:3456
	s_setprio 1
	s_waitcnt lgkmcnt(1)
	v_mfma_f32_32x32x16_bf16 v[112:127], v[234:237], v[226:229], v[112:127]
	v_mfma_f32_32x32x16_bf16 v[48:63], v[234:237], v[230:233], v[48:63]
	s_waitcnt lgkmcnt(0)
	v_mfma_f32_32x32x16_bf16 v[96:111], v[238:241], v[226:229], v[96:111]
	v_mfma_f32_32x32x16_bf16 v[32:47], v[238:241], v[230:233], v[32:47]
	ds_read_b128 v[234:237], v192 offset:9216
	ds_read_b128 v[238:241], v192 offset:13824
	s_waitcnt vmcnt(7)
	ds_write_b128 v215, v[176:179] offset:9216
	s_waitcnt vmcnt(6)
	ds_write_b128 v215, v[180:183] offset:46080
	ds_read_b128 v[176:179], v208 offset:32
	ds_read_b128 v[180:183], v208 offset:4640
	s_waitcnt lgkmcnt(5)
	v_mfma_f32_32x32x16_bf16 v[80:95], v[234:237], v[226:229], v[80:95]
	v_mfma_f32_32x32x16_bf16 v[16:31], v[234:237], v[230:233], v[16:31]
	ds_read_b128 v[234:237], v192 offset:32
	s_waitcnt lgkmcnt(5)
	v_mfma_f32_32x32x16_bf16 v[64:79], v[238:241], v[226:229], v[64:79]
	v_mfma_f32_32x32x16_bf16 v[0:15], v[238:241], v[230:233], v[0:15]
	ds_read_b128 v[238:241], v192 offset:4640
	s_setprio 0
	global_load_dwordx4 v[226:229], v[194:195], off offset:3456
	global_load_dwordx4 v[230:233], v[196:197], off offset:3456
	s_setprio 1
	s_waitcnt lgkmcnt(1)
	v_mfma_f32_32x32x16_bf16 v[112:127], v[234:237], v[176:179], v[112:127]
	v_mfma_f32_32x32x16_bf16 v[48:63], v[234:237], v[180:183], v[48:63]
	s_waitcnt lgkmcnt(0)
	v_mfma_f32_32x32x16_bf16 v[96:111], v[238:241], v[176:179], v[96:111]
	v_mfma_f32_32x32x16_bf16 v[32:47], v[238:241], v[180:183], v[32:47]
	ds_read_b128 v[234:237], v192 offset:9248
	ds_read_b128 v[238:241], v192 offset:13856
	s_waitcnt vmcnt(7)
	ds_write_b128 v215, v[168:171] offset:18432
	s_waitcnt vmcnt(6)
	ds_write_b128 v215, v[172:175] offset:55296
	ds_read_b128 v[168:171], v208 offset:64
	ds_read_b128 v[172:175], v208 offset:4672
	s_waitcnt lgkmcnt(5)
	v_mfma_f32_32x32x16_bf16 v[80:95], v[234:237], v[176:179], v[80:95]
	v_mfma_f32_32x32x16_bf16 v[16:31], v[234:237], v[180:183], v[16:31]
	ds_read_b128 v[234:237], v192 offset:64
	s_waitcnt lgkmcnt(5)
	v_mfma_f32_32x32x16_bf16 v[64:79], v[238:241], v[176:179], v[64:79]
	v_mfma_f32_32x32x16_bf16 v[0:15], v[238:241], v[180:183], v[0:15]
	ds_read_b128 v[238:241], v192 offset:4672
	s_setprio 0
	global_load_dwordx4 v[176:179], v[184:185], off offset:3456
	global_load_dwordx4 v[180:183], v[186:187], off offset:3456
	s_setprio 1
	s_waitcnt lgkmcnt(1)
	v_mfma_f32_32x32x16_bf16 v[112:127], v[234:237], v[168:171], v[112:127]
	v_mfma_f32_32x32x16_bf16 v[48:63], v[234:237], v[172:175], v[48:63]
	s_waitcnt lgkmcnt(0)
	v_mfma_f32_32x32x16_bf16 v[96:111], v[238:241], v[168:171], v[96:111]
	v_mfma_f32_32x32x16_bf16 v[32:47], v[238:241], v[172:175], v[32:47]
	ds_read_b128 v[234:237], v192 offset:9280
	ds_read_b128 v[238:241], v192 offset:13888
	s_waitcnt vmcnt(7)
	ds_write_b128 v215, v[160:163] offset:27648
	s_waitcnt vmcnt(6)
	ds_write_b128 v215, v[164:167] offset:64512
	ds_read_b128 v[160:163], v208 offset:96
	ds_read_b128 v[164:167], v208 offset:4704
	s_waitcnt lgkmcnt(5)
	v_mfma_f32_32x32x16_bf16 v[80:95], v[234:237], v[168:171], v[80:95]
	v_mfma_f32_32x32x16_bf16 v[16:31], v[234:237], v[172:175], v[16:31]
	ds_read_b128 v[234:237], v192 offset:96
	s_waitcnt lgkmcnt(5)
	v_mfma_f32_32x32x16_bf16 v[64:79], v[238:241], v[168:171], v[64:79]
	v_mfma_f32_32x32x16_bf16 v[0:15], v[238:241], v[172:175], v[0:15]
	ds_read_b128 v[238:241], v192 offset:4704
	s_setprio 0
	global_load_dwordx4 v[168:171], v[198:199], off offset:3456
	global_load_dwordx4 v[172:175], v[200:201], off offset:3456
	s_setprio 1
	s_waitcnt lgkmcnt(1)
	v_mfma_f32_32x32x16_bf16 v[112:127], v[234:237], v[160:163], v[112:127]
	v_mfma_f32_32x32x16_bf16 v[48:63], v[234:237], v[164:167], v[48:63]
	s_waitcnt lgkmcnt(0)
	v_mfma_f32_32x32x16_bf16 v[96:111], v[238:241], v[160:163], v[96:111]
	v_mfma_f32_32x32x16_bf16 v[32:47], v[238:241], v[164:167], v[32:47]
	ds_read_b128 v[234:237], v192 offset:9312
	ds_read_b128 v[238:241], v192 offset:13920
	s_waitcnt lgkmcnt(0)
	s_barrier
; template <bool trans>
; DI void gemm_core(const GTile& tl, const GTile& nx, bool has_next  , bool chain  , bool pre, u32x4 (&ra)[4], u32x4 (&rb)[4], char* smem, f32x16 (&acc)[2][4]) {
;     ...
;   const int nk = K / 64;
;   if (!pre) { G_LOAD(0); G_STORE(0); G_LOAD(1); }
;   for (int kt = 0; kt < nk; ++kt) {
;     __syncthreads();
;     G_COMPUTE(kt & 1, kt);
;   }
	s_waitcnt vmcnt(7)
	ds_write_b128 v209, v[218:221]
	s_waitcnt vmcnt(6)
	ds_write_b128 v210, v[222:225]
	ds_read_b128 v[218:221], v205 offset:36864
	ds_read_b128 v[222:225], v205 offset:41472
	v_mfma_f32_32x32x16_bf16 v[80:95], v[234:237], v[160:163], v[80:95]
	v_mfma_f32_32x32x16_bf16 v[16:31], v[234:237], v[164:167], v[16:31]
	ds_read_b128 v[234:237], v204
	v_mfma_f32_32x32x16_bf16 v[64:79], v[238:241], v[160:163], v[64:79]
	v_mfma_f32_32x32x16_bf16 v[0:15], v[238:241], v[164:167], v[0:15]
	ds_read_b128 v[238:241], v204 offset:4608
	s_setprio 0
	global_load_dwordx4 v[160:163], v[190:191], off offset:3584
	global_load_dwordx4 v[164:167], v[188:189], off offset:3584
	s_setprio 1
	s_waitcnt lgkmcnt(1)
	v_mfma_f32_32x32x16_bf16 v[112:127], v[234:237], v[218:221], v[112:127]
	v_mfma_f32_32x32x16_bf16 v[48:63], v[234:237], v[222:225], v[48:63]
	s_waitcnt lgkmcnt(0)
	v_mfma_f32_32x32x16_bf16 v[96:111], v[238:241], v[218:221], v[96:111]
	v_mfma_f32_32x32x16_bf16 v[32:47], v[238:241], v[222:225], v[32:47]
	ds_read_b128 v[234:237], v204 offset:9216
	ds_read_b128 v[238:241], v204 offset:13824
	s_waitcnt vmcnt(7)
	ds_write_b128 v212, v[226:229]
	s_waitcnt vmcnt(6)
	ds_write_b128 v211, v[230:233]
	ds_read_b128 v[226:229], v205 offset:36896
	ds_read_b128 v[230:233], v205 offset:41504
	s_waitcnt lgkmcnt(5)
	v_mfma_f32_32x32x16_bf16 v[80:95], v[234:237], v[218:221], v[80:95]
	v_mfma_f32_32x32x16_bf16 v[16:31], v[234:237], v[222:225], v[16:31]
	ds_read_b128 v[234:237], v204 offset:32
	s_waitcnt lgkmcnt(5)
	v_mfma_f32_32x32x16_bf16 v[64:79], v[238:241], v[218:221], v[64:79]
	v_mfma_f32_32x32x16_bf16 v[0:15], v[238:241], v[222:225], v[0:15]
	ds_read_b128 v[238:241], v204 offset:4640
	s_setprio 0
	global_load_dwordx4 v[218:221], v[194:195], off offset:3584
	global_load_dwordx4 v[222:225], v[196:197], off offset:3584
	s_setprio 1
	s_waitcnt lgkmcnt(1)
	v_mfma_f32_32x32x16_bf16 v[112:127], v[234:237], v[226:229], v[112:127]
	v_mfma_f32_32x32x16_bf16 v[48:63], v[234:237], v[230:233], v[48:63]
	s_waitcnt lgkmcnt(0)
	v_mfma_f32_32x32x16_bf16 v[96:111], v[238:241], v[226:229], v[96:111]
	v_mfma_f32_32x32x16_bf16 v[32:47], v[238:241], v[230:233], v[32:47]
	ds_read_b128 v[234:237], v204 offset:9248
	ds_read_b128 v[238:241], v204 offset:13856
	s_waitcnt vmcnt(7)
	ds_write_b128 v214, v[176:179]
	s_waitcnt vmcnt(6)
	ds_write_b128 v213, v[180:183]
	ds_read_b128 v[176:179], v205 offset:36928
	ds_read_b128 v[180:183], v205 offset:41536
	s_waitcnt lgkmcnt(5)
	v_mfma_f32_32x32x16_bf16 v[80:95], v[234:237], v[226:229], v[80:95]
	v_mfma_f32_32x32x16_bf16 v[16:31], v[234:237], v[230:233], v[16:31]
	ds_read_b128 v[234:237], v204 offset:64
	s_waitcnt lgkmcnt(5)
	v_mfma_f32_32x32x16_bf16 v[64:79], v[238:241], v[226:229], v[64:79]
	v_mfma_f32_32x32x16_bf16 v[0:15], v[238:241], v[230:233], v[0:15]
	ds_read_b128 v[238:241], v204 offset:4672
	s_setprio 0
	global_load_dwordx4 v[226:229], v[184:185], off offset:3584
	global_load_dwordx4 v[230:233], v[186:187], off offset:3584
	s_setprio 1
	s_waitcnt lgkmcnt(1)
	v_mfma_f32_32x32x16_bf16 v[112:127], v[234:237], v[176:179], v[112:127]
	v_mfma_f32_32x32x16_bf16 v[48:63], v[234:237], v[180:183], v[48:63]
	s_waitcnt lgkmcnt(0)
	v_mfma_f32_32x32x16_bf16 v[96:111], v[238:241], v[176:179], v[96:111]
	v_mfma_f32_32x32x16_bf16 v[32:47], v[238:241], v[180:183], v[32:47]
	ds_read_b128 v[234:237], v204 offset:9280
	ds_read_b128 v[238:241], v204 offset:13888
	s_waitcnt vmcnt(7)
	ds_write_b128 v217, v[168:171]
	s_waitcnt vmcnt(6)
	ds_write_b128 v216, v[172:175]
	ds_read_b128 v[168:171], v205 offset:36960
	ds_read_b128 v[172:175], v205 offset:41568
	s_waitcnt lgkmcnt(5)
	v_mfma_f32_32x32x16_bf16 v[80:95], v[234:237], v[176:179], v[80:95]
	v_mfma_f32_32x32x16_bf16 v[16:31], v[234:237], v[180:183], v[16:31]
	ds_read_b128 v[234:237], v204 offset:96
	s_waitcnt lgkmcnt(5)
	v_mfma_f32_32x32x16_bf16 v[64:79], v[238:241], v[176:179], v[64:79]
	v_mfma_f32_32x32x16_bf16 v[0:15], v[238:241], v[180:183], v[0:15]
	ds_read_b128 v[238:241], v204 offset:4704
	s_setprio 0
	global_load_dwordx4 v[176:179], v[198:199], off offset:3584
	global_load_dwordx4 v[180:183], v[200:201], off offset:3584
	s_setprio 1
	s_waitcnt lgkmcnt(1)
	v_mfma_f32_32x32x16_bf16 v[112:127], v[234:237], v[168:171], v[112:127]
	v_mfma_f32_32x32x16_bf16 v[48:63], v[234:237], v[172:175], v[48:63]
	s_waitcnt lgkmcnt(0)
	v_mfma_f32_32x32x16_bf16 v[96:111], v[238:241], v[168:171], v[96:111]
	v_mfma_f32_32x32x16_bf16 v[32:47], v[238:241], v[172:175], v[32:47]
	ds_read_b128 v[234:237], v204 offset:9312
	ds_read_b128 v[238:241], v204 offset:13920
	s_waitcnt lgkmcnt(0)
	s_barrier
; template <bool trans>
; DI void gemm_core(const GTile& tl, const GTile& nx, bool has_next  , bool chain  , bool pre, u32x4 (&ra)[4], u32x4 (&rb)[4], char* smem, f32x16 (&acc)[2][4]) {
;     ...
;   const int nk = K / 64;
;   if (!pre) { G_LOAD(0); G_STORE(0); G_LOAD(1); }
;   for (int kt = 0; kt < nk; ++kt) {
;     __syncthreads();
;     G_COMPUTE(kt & 1, kt);
;   }
	s_waitcnt vmcnt(7)
	ds_write_b128 v215, v[160:163]
	s_waitcnt vmcnt(6)
	ds_write_b128 v215, v[164:167] offset:36864
	ds_read_b128 v[160:163], v208
	ds_read_b128 v[164:167], v208 offset:4608
	v_mfma_f32_32x32x16_bf16 v[80:95], v[234:237], v[168:171], v[80:95]
	v_mfma_f32_32x32x16_bf16 v[16:31], v[234:237], v[172:175], v[16:31]
	ds_read_b128 v[234:237], v192
	v_mfma_f32_32x32x16_bf16 v[64:79], v[238:241], v[168:171], v[64:79]
	v_mfma_f32_32x32x16_bf16 v[0:15], v[238:241], v[172:175], v[0:15]
	ds_read_b128 v[238:241], v192 offset:4608
	s_setprio 0
	global_load_dwordx4 v[168:171], v[190:191], off offset:3712
	global_load_dwordx4 v[172:175], v[188:189], off offset:3712
	s_setprio 1
	s_waitcnt lgkmcnt(1)
	v_mfma_f32_32x32x16_bf16 v[112:127], v[234:237], v[160:163], v[112:127]
	v_mfma_f32_32x32x16_bf16 v[48:63], v[234:237], v[164:167], v[48:63]
	s_waitcnt lgkmcnt(0)
	v_mfma_f32_32x32x16_bf16 v[96:111], v[238:241], v[160:163], v[96:111]
	v_mfma_f32_32x32x16_bf16 v[32:47], v[238:241], v[164:167], v[32:47]
	ds_read_b128 v[234:237], v192 offset:9216
	ds_read_b128 v[238:241], v192 offset:13824
	s_waitcnt vmcnt(7)
	ds_write_b128 v215, v[218:221] offset:9216
	s_waitcnt vmcnt(6)
	ds_write_b128 v215, v[222:225] offset:46080
	ds_read_b128 v[218:221], v208 offset:32
	ds_read_b128 v[222:225], v208 offset:4640
	s_waitcnt lgkmcnt(5)
	v_mfma_f32_32x32x16_bf16 v[80:95], v[234:237], v[160:163], v[80:95]
	v_mfma_f32_32x32x16_bf16 v[16:31], v[234:237], v[164:167], v[16:31]
	ds_read_b128 v[234:237], v192 offset:32
	s_waitcnt lgkmcnt(5)
	v_mfma_f32_32x32x16_bf16 v[64:79], v[238:241], v[160:163], v[64:79]
	v_mfma_f32_32x32x16_bf16 v[0:15], v[238:241], v[164:167], v[0:15]
	ds_read_b128 v[238:241], v192 offset:4640
	s_setprio 0
	global_load_dwordx4 v[160:163], v[194:195], off offset:3712
	global_load_dwordx4 v[164:167], v[196:197], off offset:3712
	s_setprio 1
	s_waitcnt lgkmcnt(1)
	v_mfma_f32_32x32x16_bf16 v[112:127], v[234:237], v[218:221], v[112:127]
	v_mfma_f32_32x32x16_bf16 v[48:63], v[234:237], v[222:225], v[48:63]
	s_waitcnt lgkmcnt(0)
	v_mfma_f32_32x32x16_bf16 v[96:111], v[238:241], v[218:221], v[96:111]
	v_mfma_f32_32x32x16_bf16 v[32:47], v[238:241], v[222:225], v[32:47]
	ds_read_b128 v[234:237], v192 offset:9248
	ds_read_b128 v[238:241], v192 offset:13856
	s_waitcnt vmcnt(7)
	ds_write_b128 v215, v[226:229] offset:18432
	s_waitcnt vmcnt(6)
	ds_write_b128 v215, v[230:233] offset:55296
	ds_read_b128 v[226:229], v208 offset:64
	ds_read_b128 v[230:233], v208 offset:4672
	s_waitcnt lgkmcnt(5)
	v_mfma_f32_32x32x16_bf16 v[80:95], v[234:237], v[218:221], v[80:95]
	v_mfma_f32_32x32x16_bf16 v[16:31], v[234:237], v[222:225], v[16:31]
	ds_read_b128 v[234:237], v192 offset:64
	s_waitcnt lgkmcnt(5)
	v_mfma_f32_32x32x16_bf16 v[64:79], v[238:241], v[218:221], v[64:79]
	v_mfma_f32_32x32x16_bf16 v[0:15], v[238:241], v[222:225], v[0:15]
	ds_read_b128 v[238:241], v192 offset:4672
	s_setprio 0
	global_load_dwordx4 v[218:221], v[184:185], off offset:3712
	global_load_dwordx4 v[222:225], v[186:187], off offset:3712
	s_setprio 1
	s_waitcnt lgkmcnt(1)
	v_mfma_f32_32x32x16_bf16 v[112:127], v[234:237], v[226:229], v[112:127]
	v_mfma_f32_32x32x16_bf16 v[48:63], v[234:237], v[230:233], v[48:63]
	s_waitcnt lgkmcnt(0)
	v_mfma_f32_32x32x16_bf16 v[96:111], v[238:241], v[226:229], v[96:111]
	v_mfma_f32_32x32x16_bf16 v[32:47], v[238:241], v[230:233], v[32:47]
	ds_read_b128 v[234:237], v192 offset:9280
	ds_read_b128 v[238:241], v192 offset:13888
	s_waitcnt vmcnt(7)
	ds_write_b128 v215, v[176:179] offset:27648
	s_waitcnt vmcnt(6)
	ds_write_b128 v215, v[180:183] offset:64512
	ds_read_b128 v[176:179], v208 offset:96
	ds_read_b128 v[180:183], v208 offset:4704
	s_waitcnt lgkmcnt(5)
	v_mfma_f32_32x32x16_bf16 v[80:95], v[234:237], v[226:229], v[80:95]
	v_mfma_f32_32x32x16_bf16 v[16:31], v[234:237], v[230:233], v[16:31]
	ds_read_b128 v[234:237], v192 offset:96
	s_waitcnt lgkmcnt(5)
	v_mfma_f32_32x32x16_bf16 v[64:79], v[238:241], v[226:229], v[64:79]
	v_mfma_f32_32x32x16_bf16 v[0:15], v[238:241], v[230:233], v[0:15]
	ds_read_b128 v[238:241], v192 offset:4704
	s_setprio 0
	global_load_dwordx4 v[226:229], v[198:199], off offset:3712
	global_load_dwordx4 v[230:233], v[200:201], off offset:3712
	s_setprio 1
	s_waitcnt lgkmcnt(1)
	v_mfma_f32_32x32x16_bf16 v[112:127], v[234:237], v[176:179], v[112:127]
	v_mfma_f32_32x32x16_bf16 v[48:63], v[234:237], v[180:183], v[48:63]
	s_waitcnt lgkmcnt(0)
	v_mfma_f32_32x32x16_bf16 v[96:111], v[238:241], v[176:179], v[96:111]
	v_mfma_f32_32x32x16_bf16 v[32:47], v[238:241], v[180:183], v[32:47]
	ds_read_b128 v[234:237], v192 offset:9312
	ds_read_b128 v[238:241], v192 offset:13920
	s_waitcnt lgkmcnt(0)
	s_barrier
; template <bool trans>
; DI void gemm_core(const GTile& tl, const GTile& nx, bool has_next  , bool chain  , bool pre, u32x4 (&ra)[4], u32x4 (&rb)[4], char* smem, f32x16 (&acc)[2][4]) {
;     ...
;   const int nk = K / 64;
;   if (!pre) { G_LOAD(0); G_STORE(0); G_LOAD(1); }
;   for (int kt = 0; kt < nk; ++kt) {
;     __syncthreads();
;     G_COMPUTE(kt & 1, kt);
;   }
	s_waitcnt vmcnt(7)
	ds_write_b128 v209, v[168:171]
	s_waitcnt vmcnt(6)
	ds_write_b128 v210, v[172:175]
	ds_read_b128 v[168:171], v205 offset:36864
	ds_read_b128 v[172:175], v205 offset:41472
	v_mfma_f32_32x32x16_bf16 v[80:95], v[234:237], v[176:179], v[80:95]
	v_mfma_f32_32x32x16_bf16 v[16:31], v[234:237], v[180:183], v[16:31]
	ds_read_b128 v[234:237], v204
	v_mfma_f32_32x32x16_bf16 v[64:79], v[238:241], v[176:179], v[64:79]
	v_mfma_f32_32x32x16_bf16 v[0:15], v[238:241], v[180:183], v[0:15]
	ds_read_b128 v[238:241], v204 offset:4608
	s_setprio 0
	global_load_dwordx4 v[176:179], v[190:191], off offset:3840
	global_load_dwordx4 v[180:183], v[188:189], off offset:3840
	s_setprio 1
	s_waitcnt lgkmcnt(1)
	v_mfma_f32_32x32x16_bf16 v[112:127], v[234:237], v[168:171], v[112:127]
	v_mfma_f32_32x32x16_bf16 v[48:63], v[234:237], v[172:175], v[48:63]
	s_waitcnt lgkmcnt(0)
	v_mfma_f32_32x32x16_bf16 v[96:111], v[238:241], v[168:171], v[96:111]
	v_mfma_f32_32x32x16_bf16 v[32:47], v[238:241], v[172:175], v[32:47]
	ds_read_b128 v[234:237], v204 offset:9216
	ds_read_b128 v[238:241], v204 offset:13824
	s_waitcnt lgkmcnt(1)
	v_mfma_f32_32x32x16_bf16 v[80:95], v[234:237], v[168:171], v[80:95]
	v_mfma_f32_32x32x16_bf16 v[16:31], v[234:237], v[172:175], v[16:31]
	s_waitcnt lgkmcnt(0)
	v_mfma_f32_32x32x16_bf16 v[64:79], v[238:241], v[168:171], v[64:79]
	v_mfma_f32_32x32x16_bf16 v[0:15], v[238:241], v[172:175], v[0:15]
	s_setprio 0
	global_load_dwordx4 v[234:237], v[194:195], off offset:3840
	global_load_dwordx4 v[238:241], v[196:197], off offset:3840
	s_waitcnt vmcnt(9)
	ds_write_b128 v212, v[160:163]
	s_waitcnt vmcnt(8)
	ds_write_b128 v211, v[164:167]
	ds_read_b128 v[160:163], v205 offset:36896
	ds_read_b128 v[164:167], v205 offset:41504
	ds_read_b128 v[168:171], v204 offset:32
	ds_read_b128 v[172:175], v204 offset:4640
	s_setprio 1
	s_waitcnt lgkmcnt(1)
	v_mfma_f32_32x32x16_bf16 v[112:127], v[168:171], v[160:163], v[112:127]
	v_mfma_f32_32x32x16_bf16 v[48:63], v[168:171], v[164:167], v[48:63]
	s_waitcnt lgkmcnt(0)
	v_mfma_f32_32x32x16_bf16 v[96:111], v[172:175], v[160:163], v[96:111]
	v_mfma_f32_32x32x16_bf16 v[32:47], v[172:175], v[164:167], v[32:47]
	ds_read_b128 v[168:171], v204 offset:9248
	ds_read_b128 v[172:175], v204 offset:13856
	s_waitcnt lgkmcnt(1)
	v_mfma_f32_32x32x16_bf16 v[80:95], v[168:171], v[160:163], v[80:95]
	v_mfma_f32_32x32x16_bf16 v[16:31], v[168:171], v[164:167], v[16:31]
	s_waitcnt lgkmcnt(0)
	v_mfma_f32_32x32x16_bf16 v[64:79], v[172:175], v[160:163], v[64:79]
	v_mfma_f32_32x32x16_bf16 v[0:15], v[172:175], v[164:167], v[0:15]
	s_setprio 0
	global_load_dwordx4 v[242:245], v[184:185], off offset:3840
	global_load_dwordx4 v[246:249], v[186:187], off offset:3840
	s_waitcnt vmcnt(9)
	ds_write_b128 v214, v[218:221]
	s_waitcnt vmcnt(8)
	ds_write_b128 v213, v[222:225]
	ds_read_b128 v[160:163], v205 offset:36928
	ds_read_b128 v[164:167], v205 offset:41536
	ds_read_b128 v[168:171], v204 offset:64
	ds_read_b128 v[172:175], v204 offset:4672
	s_setprio 1
	s_waitcnt lgkmcnt(1)
	v_mfma_f32_32x32x16_bf16 v[112:127], v[168:171], v[160:163], v[112:127]
	v_mfma_f32_32x32x16_bf16 v[48:63], v[168:171], v[164:167], v[48:63]
	s_waitcnt lgkmcnt(0)
	v_mfma_f32_32x32x16_bf16 v[96:111], v[172:175], v[160:163], v[96:111]
	v_mfma_f32_32x32x16_bf16 v[32:47], v[172:175], v[164:167], v[32:47]
	ds_read_b128 v[168:171], v204 offset:9280
	ds_read_b128 v[172:175], v204 offset:13888
	s_waitcnt lgkmcnt(1)
	v_mfma_f32_32x32x16_bf16 v[80:95], v[168:171], v[160:163], v[80:95]
	v_mfma_f32_32x32x16_bf16 v[16:31], v[168:171], v[164:167], v[16:31]
	s_waitcnt lgkmcnt(0)
	v_mfma_f32_32x32x16_bf16 v[64:79], v[172:175], v[160:163], v[64:79]
	v_mfma_f32_32x32x16_bf16 v[0:15], v[172:175], v[164:167], v[0:15]
	s_setprio 0
	global_load_dwordx4 v[218:221], v[198:199], off offset:3840
	global_load_dwordx4 v[222:225], v[200:201], off offset:3840
	s_waitcnt vmcnt(9)
	ds_write_b128 v217, v[226:229]
	s_waitcnt vmcnt(8)
	ds_write_b128 v216, v[230:233]
	ds_read_b128 v[160:163], v205 offset:36960
	ds_read_b128 v[164:167], v205 offset:41568
	ds_read_b128 v[168:171], v204 offset:96
	ds_read_b128 v[172:175], v204 offset:4704
	s_setprio 1
	s_waitcnt lgkmcnt(1)
	v_mfma_f32_32x32x16_bf16 v[112:127], v[168:171], v[160:163], v[112:127]
	v_mfma_f32_32x32x16_bf16 v[48:63], v[168:171], v[164:167], v[48:63]
	s_waitcnt lgkmcnt(0)
	v_mfma_f32_32x32x16_bf16 v[96:111], v[172:175], v[160:163], v[96:111]
	v_mfma_f32_32x32x16_bf16 v[32:47], v[172:175], v[164:167], v[32:47]
	ds_read_b128 v[168:171], v204 offset:9312
	ds_read_b128 v[172:175], v204 offset:13920
	s_waitcnt lgkmcnt(1)
	v_mfma_f32_32x32x16_bf16 v[80:95], v[168:171], v[160:163], v[80:95]
	v_mfma_f32_32x32x16_bf16 v[16:31], v[168:171], v[164:167], v[16:31]
	s_waitcnt lgkmcnt(0)
	v_mfma_f32_32x32x16_bf16 v[64:79], v[172:175], v[160:163], v[64:79]
	v_mfma_f32_32x32x16_bf16 v[0:15], v[172:175], v[164:167], v[0:15]
	s_setprio 0
	global_load_dwordx4 v[160:163], v[190:191], off offset:3968
	global_load_dwordx4 v[164:167], v[188:189], off offset:3968
	s_barrier
; template <bool trans>
; DI void gemm_core(const GTile& tl, const GTile& nx, bool has_next  , bool chain  , bool pre, u32x4 (&ra)[4], u32x4 (&rb)[4], char* smem, f32x16 (&acc)[2][4]) {
;     ...
;   const int nk = K / 64;
;   if (!pre) { G_LOAD(0); G_STORE(0); G_LOAD(1); }
;   for (int kt = 0; kt < nk; ++kt) {
;     __syncthreads();
;     G_COMPUTE(kt & 1, kt);
;   }
	s_waitcnt vmcnt(9)
	ds_write_b128 v215, v[176:179]
	s_waitcnt vmcnt(8)
	ds_write_b128 v215, v[180:183] offset:36864
	ds_read_b128 v[168:171], v208
	ds_read_b128 v[172:175], v208 offset:4608
	ds_read_b128 v[176:179], v192
	ds_read_b128 v[180:183], v192 offset:4608
	s_setprio 1
	s_waitcnt lgkmcnt(1)
	v_mfma_f32_32x32x16_bf16 v[112:127], v[176:179], v[168:171], v[112:127]
	v_mfma_f32_32x32x16_bf16 v[48:63], v[176:179], v[172:175], v[48:63]
	s_waitcnt lgkmcnt(0)
	v_mfma_f32_32x32x16_bf16 v[96:111], v[180:183], v[168:171], v[96:111]
	v_mfma_f32_32x32x16_bf16 v[32:47], v[180:183], v[172:175], v[32:47]
	ds_read_b128 v[176:179], v192 offset:9216
	ds_read_b128 v[180:183], v192 offset:13824
	s_waitcnt lgkmcnt(1)
	v_mfma_f32_32x32x16_bf16 v[80:95], v[176:179], v[168:171], v[80:95]
	v_mfma_f32_32x32x16_bf16 v[16:31], v[176:179], v[172:175], v[16:31]
	s_waitcnt lgkmcnt(0)
	v_mfma_f32_32x32x16_bf16 v[64:79], v[180:183], v[168:171], v[64:79]
	v_mfma_f32_32x32x16_bf16 v[0:15], v[180:183], v[172:175], v[0:15]
	s_setprio 0
	global_load_dwordx4 v[168:171], v[194:195], off offset:3968
	global_load_dwordx4 v[172:175], v[196:197], off offset:3968
	s_waitcnt vmcnt(9)
	ds_write_b128 v215, v[234:237] offset:9216
	s_waitcnt vmcnt(8)
	ds_write_b128 v215, v[238:241] offset:46080
	ds_read_b128 v[176:179], v208 offset:32
	ds_read_b128 v[180:183], v208 offset:4640
	ds_read_b128 v[188:191], v192 offset:32
	ds_read_b128 v[194:197], v192 offset:4640
	s_setprio 1
	s_waitcnt lgkmcnt(1)
	v_mfma_f32_32x32x16_bf16 v[112:127], v[188:191], v[176:179], v[112:127]
	v_mfma_f32_32x32x16_bf16 v[48:63], v[188:191], v[180:183], v[48:63]
	s_waitcnt lgkmcnt(0)
	v_mfma_f32_32x32x16_bf16 v[96:111], v[194:197], v[176:179], v[96:111]
	v_mfma_f32_32x32x16_bf16 v[32:47], v[194:197], v[180:183], v[32:47]
	ds_read_b128 v[188:191], v192 offset:9248
	ds_read_b128 v[194:197], v192 offset:13856
	s_waitcnt lgkmcnt(1)
	v_mfma_f32_32x32x16_bf16 v[80:95], v[188:191], v[176:179], v[80:95]
	v_mfma_f32_32x32x16_bf16 v[16:31], v[188:191], v[180:183], v[16:31]
	s_waitcnt lgkmcnt(0)
	v_mfma_f32_32x32x16_bf16 v[64:79], v[194:197], v[176:179], v[64:79]
	v_mfma_f32_32x32x16_bf16 v[0:15], v[194:197], v[180:183], v[0:15]
	s_setprio 0
	global_load_dwordx4 v[176:179], v[184:185], off offset:3968
	global_load_dwordx4 v[180:183], v[186:187], off offset:3968
	s_waitcnt vmcnt(9)
	ds_write_b128 v215, v[242:245] offset:18432
	s_waitcnt vmcnt(8)
	ds_write_b128 v215, v[246:249] offset:55296
	ds_read_b128 v[184:187], v208 offset:64
	ds_read_b128 v[188:191], v208 offset:4672
	ds_read_b128 v[194:197], v192 offset:64
	ds_read_b128 v[226:229], v192 offset:4672
	s_setprio 1
	s_waitcnt lgkmcnt(1)
	v_mfma_f32_32x32x16_bf16 v[112:127], v[194:197], v[184:187], v[112:127]
	v_mfma_f32_32x32x16_bf16 v[48:63], v[194:197], v[188:191], v[48:63]
	s_waitcnt lgkmcnt(0)
	v_mfma_f32_32x32x16_bf16 v[96:111], v[226:229], v[184:187], v[96:111]
	v_mfma_f32_32x32x16_bf16 v[32:47], v[226:229], v[188:191], v[32:47]
	ds_read_b128 v[194:197], v192 offset:9280
	ds_read_b128 v[226:229], v192 offset:13888
	s_waitcnt lgkmcnt(1)
	v_mfma_f32_32x32x16_bf16 v[80:95], v[194:197], v[184:187], v[80:95]
	v_mfma_f32_32x32x16_bf16 v[16:31], v[194:197], v[188:191], v[16:31]
	s_waitcnt lgkmcnt(0)
	v_mfma_f32_32x32x16_bf16 v[64:79], v[226:229], v[184:187], v[64:79]
	v_mfma_f32_32x32x16_bf16 v[0:15], v[226:229], v[188:191], v[0:15]
	s_setprio 0
	global_load_dwordx4 v[184:187], v[198:199], off offset:3968
	global_load_dwordx4 v[188:191], v[200:201], off offset:3968
	s_waitcnt vmcnt(9)
	ds_write_b128 v215, v[218:221] offset:27648
	s_waitcnt vmcnt(8)
	ds_write_b128 v215, v[222:225] offset:64512
	ds_read_b128 v[194:197], v208 offset:96
	ds_read_b128 v[198:201], v208 offset:4704
	ds_read_b128 v[218:221], v192 offset:96
	ds_read_b128 v[222:225], v192 offset:4704
	s_setprio 1
	s_waitcnt lgkmcnt(1)
	v_mfma_f32_32x32x16_bf16 v[112:127], v[218:221], v[194:197], v[112:127]
	v_mfma_f32_32x32x16_bf16 v[48:63], v[218:221], v[198:201], v[48:63]
	s_waitcnt lgkmcnt(0)
	v_mfma_f32_32x32x16_bf16 v[96:111], v[222:225], v[194:197], v[96:111]
	v_mfma_f32_32x32x16_bf16 v[32:47], v[222:225], v[198:201], v[32:47]
	ds_read_b128 v[218:221], v192 offset:9312
	ds_read_b128 v[222:225], v192 offset:13920
	s_waitcnt lgkmcnt(1)
	v_mfma_f32_32x32x16_bf16 v[80:95], v[218:221], v[194:197], v[80:95]
	v_mfma_f32_32x32x16_bf16 v[16:31], v[218:221], v[198:201], v[16:31]
	s_waitcnt lgkmcnt(0)
	v_mfma_f32_32x32x16_bf16 v[64:79], v[222:225], v[194:197], v[64:79]
	v_mfma_f32_32x32x16_bf16 v[0:15], v[222:225], v[198:201], v[0:15]
	s_setprio 0
	s_barrier
; template <bool trans>
; DI void gemm_core(const GTile& tl, const GTile& nx, bool has_next  , bool chain  , bool pre, u32x4 (&ra)[4], u32x4 (&rb)[4], char* smem, f32x16 (&acc)[2][4]) {
;     ...
;   const int nk = K / 64;
;   if (!pre) { G_LOAD(0); G_STORE(0); G_LOAD(1); }
;   for (int kt = 0; kt < nk; ++kt) {
;     __syncthreads();
;     G_COMPUTE(kt & 1, kt);
;   }
	s_waitcnt vmcnt(7)
	ds_write_b128 v209, v[160:163]
	s_waitcnt vmcnt(6)
	ds_write_b128 v210, v[164:167]
	ds_read_b128 v[194:197], v205 offset:36864
	ds_read_b128 v[198:201], v205 offset:41472
	ds_read_b128 v[218:221], v204
	ds_read_b128 v[222:225], v204 offset:4608
	s_setprio 1
	s_waitcnt lgkmcnt(1)
	v_mfma_f32_32x32x16_bf16 v[112:127], v[218:221], v[194:197], v[112:127]
	v_mfma_f32_32x32x16_bf16 v[48:63], v[218:221], v[198:201], v[48:63]
	s_waitcnt lgkmcnt(0)
	v_mfma_f32_32x32x16_bf16 v[96:111], v[222:225], v[194:197], v[96:111]
	v_mfma_f32_32x32x16_bf16 v[32:47], v[222:225], v[198:201], v[32:47]
	ds_read_b128 v[218:221], v204 offset:9216
	ds_read_b128 v[222:225], v204 offset:13824
	s_waitcnt lgkmcnt(1)
	v_mfma_f32_32x32x16_bf16 v[80:95], v[218:221], v[194:197], v[80:95]
	v_mfma_f32_32x32x16_bf16 v[16:31], v[218:221], v[198:201], v[16:31]
	s_waitcnt lgkmcnt(0)
	v_mfma_f32_32x32x16_bf16 v[64:79], v[222:225], v[194:197], v[64:79]
	v_mfma_f32_32x32x16_bf16 v[0:15], v[222:225], v[198:201], v[0:15]
	s_setprio 0
	s_waitcnt vmcnt(5)
	ds_write_b128 v212, v[168:171]
	s_waitcnt vmcnt(4)
	ds_write_b128 v211, v[172:175]
	ds_read_b128 v[194:197], v205 offset:36896
	ds_read_b128 v[198:201], v205 offset:41504
	ds_read_b128 v[218:221], v204 offset:32
	ds_read_b128 v[222:225], v204 offset:4640
	s_setprio 1
	s_waitcnt lgkmcnt(1)
	v_mfma_f32_32x32x16_bf16 v[112:127], v[218:221], v[194:197], v[112:127]
	v_mfma_f32_32x32x16_bf16 v[48:63], v[218:221], v[198:201], v[48:63]
	s_waitcnt lgkmcnt(0)
	v_mfma_f32_32x32x16_bf16 v[96:111], v[222:225], v[194:197], v[96:111]
	v_mfma_f32_32x32x16_bf16 v[32:47], v[222:225], v[198:201], v[32:47]
	ds_read_b128 v[218:221], v204 offset:9248
	ds_read_b128 v[222:225], v204 offset:13856
	s_waitcnt lgkmcnt(1)
	v_mfma_f32_32x32x16_bf16 v[80:95], v[218:221], v[194:197], v[80:95]
	v_mfma_f32_32x32x16_bf16 v[16:31], v[218:221], v[198:201], v[16:31]
	s_waitcnt lgkmcnt(0)
	v_mfma_f32_32x32x16_bf16 v[64:79], v[222:225], v[194:197], v[64:79]
	v_mfma_f32_32x32x16_bf16 v[0:15], v[222:225], v[198:201], v[0:15]
	s_setprio 0
	s_waitcnt vmcnt(3)
	ds_write_b128 v214, v[176:179]
	s_waitcnt vmcnt(2)
	ds_write_b128 v213, v[180:183]
	ds_read_b128 v[194:197], v205 offset:36928
	ds_read_b128 v[198:201], v205 offset:41536
	ds_read_b128 v[210:213], v204 offset:64
	ds_read_b128 v[218:221], v204 offset:4672
	s_setprio 1
	s_waitcnt lgkmcnt(1)
	v_mfma_f32_32x32x16_bf16 v[112:127], v[210:213], v[194:197], v[112:127]
	v_mfma_f32_32x32x16_bf16 v[48:63], v[210:213], v[198:201], v[48:63]
	s_waitcnt lgkmcnt(0)
	v_mfma_f32_32x32x16_bf16 v[96:111], v[218:221], v[194:197], v[96:111]
	v_mfma_f32_32x32x16_bf16 v[32:47], v[218:221], v[198:201], v[32:47]
	ds_read_b128 v[210:213], v204 offset:9280
	ds_read_b128 v[218:221], v204 offset:13888
	s_waitcnt lgkmcnt(1)
	v_mfma_f32_32x32x16_bf16 v[80:95], v[210:213], v[194:197], v[80:95]
	v_mfma_f32_32x32x16_bf16 v[16:31], v[210:213], v[198:201], v[16:31]
	s_waitcnt lgkmcnt(0)
	v_mfma_f32_32x32x16_bf16 v[64:79], v[218:221], v[194:197], v[64:79]
	v_mfma_f32_32x32x16_bf16 v[0:15], v[218:221], v[198:201], v[0:15]
	s_setprio 0
	s_waitcnt vmcnt(1)
	ds_write_b128 v217, v[184:187]
	s_waitcnt vmcnt(0)
	ds_write_b128 v216, v[188:191]
	ds_read_b128 v[194:197], v205 offset:36960
	ds_read_b128 v[198:201], v205 offset:41568
	ds_read_b128 v[210:213], v204 offset:96
	ds_read_b128 v[214:217], v204 offset:4704
	s_setprio 1
	s_waitcnt lgkmcnt(1)
	v_mfma_f32_32x32x16_bf16 v[112:127], v[210:213], v[194:197], v[112:127]
	v_mfma_f32_32x32x16_bf16 v[48:63], v[210:213], v[198:201], v[48:63]
	s_waitcnt lgkmcnt(0)
	v_mfma_f32_32x32x16_bf16 v[96:111], v[214:217], v[194:197], v[96:111]
	v_mfma_f32_32x32x16_bf16 v[32:47], v[214:217], v[198:201], v[32:47]
	ds_read_b128 v[210:213], v204 offset:9312
	ds_read_b128 v[214:217], v204 offset:13920
	s_waitcnt lgkmcnt(1)
	v_mfma_f32_32x32x16_bf16 v[80:95], v[210:213], v[194:197], v[80:95]
	v_mfma_f32_32x32x16_bf16 v[16:31], v[210:213], v[198:201], v[16:31]
	s_waitcnt lgkmcnt(0)
	v_mfma_f32_32x32x16_bf16 v[64:79], v[214:217], v[194:197], v[64:79]
	v_mfma_f32_32x32x16_bf16 v[0:15], v[214:217], v[198:201], v[0:15]
	s_setprio 0
	s_barrier
; template <bool trans>
; DI void gemm_core(const GTile& tl, const GTile& nx, bool has_next  , bool chain  , bool pre, u32x4 (&ra)[4], u32x4 (&rb)[4], char* smem, f32x16 (&acc)[2][4]) {
;     ...
;   for (int kt = 0; kt < nk; ++kt) {
;     __syncthreads();
;     G_COMPUTE(kt & 1, kt);
;   }
;   if (!has_next) __syncthreads();
	ds_read_b128 v[194:197], v208
	ds_read_b128 v[198:201], v208 offset:4608
	ds_read_b128 v[210:213], v192
	ds_read_b128 v[214:217], v192 offset:4608
	s_setprio 1
	s_waitcnt lgkmcnt(1)
	v_mfma_f32_32x32x16_bf16 v[112:127], v[210:213], v[194:197], v[112:127]
	v_mfma_f32_32x32x16_bf16 v[48:63], v[210:213], v[198:201], v[48:63]
	s_waitcnt lgkmcnt(0)
	v_mfma_f32_32x32x16_bf16 v[96:111], v[214:217], v[194:197], v[96:111]
	v_mfma_f32_32x32x16_bf16 v[32:47], v[214:217], v[198:201], v[32:47]
	ds_read_b128 v[210:213], v192 offset:9216
	ds_read_b128 v[214:217], v192 offset:13824
	s_waitcnt lgkmcnt(1)
	v_mfma_f32_32x32x16_bf16 v[80:95], v[210:213], v[194:197], v[80:95]
	v_mfma_f32_32x32x16_bf16 v[16:31], v[210:213], v[198:201], v[16:31]
	s_waitcnt lgkmcnt(0)
	v_mfma_f32_32x32x16_bf16 v[64:79], v[214:217], v[194:197], v[64:79]
	v_mfma_f32_32x32x16_bf16 v[0:15], v[214:217], v[198:201], v[0:15]
	s_setprio 0
	ds_read_b128 v[194:197], v208 offset:32
	ds_read_b128 v[198:201], v208 offset:4640
	ds_read_b128 v[210:213], v192 offset:32
	ds_read_b128 v[214:217], v192 offset:4640
	s_setprio 1
	s_waitcnt lgkmcnt(1)
	v_mfma_f32_32x32x16_bf16 v[112:127], v[210:213], v[194:197], v[112:127]
	v_mfma_f32_32x32x16_bf16 v[48:63], v[210:213], v[198:201], v[48:63]
	s_waitcnt lgkmcnt(0)
	v_mfma_f32_32x32x16_bf16 v[96:111], v[214:217], v[194:197], v[96:111]
	v_mfma_f32_32x32x16_bf16 v[32:47], v[214:217], v[198:201], v[32:47]
	ds_read_b128 v[210:213], v192 offset:9248
	ds_read_b128 v[214:217], v192 offset:13856
	s_waitcnt lgkmcnt(1)
	v_mfma_f32_32x32x16_bf16 v[80:95], v[210:213], v[194:197], v[80:95]
	v_mfma_f32_32x32x16_bf16 v[16:31], v[210:213], v[198:201], v[16:31]
	s_waitcnt lgkmcnt(0)
	v_mfma_f32_32x32x16_bf16 v[64:79], v[214:217], v[194:197], v[64:79]
	v_mfma_f32_32x32x16_bf16 v[0:15], v[214:217], v[198:201], v[0:15]
	s_setprio 0
	ds_read_b128 v[194:197], v208 offset:64
	ds_read_b128 v[198:201], v208 offset:4672
	ds_read_b128 v[210:213], v192 offset:64
	ds_read_b128 v[214:217], v192 offset:4672
	s_setprio 1
	s_waitcnt lgkmcnt(1)
	v_mfma_f32_32x32x16_bf16 v[112:127], v[210:213], v[194:197], v[112:127]
	v_mfma_f32_32x32x16_bf16 v[48:63], v[210:213], v[198:201], v[48:63]
	s_waitcnt lgkmcnt(0)
	v_mfma_f32_32x32x16_bf16 v[96:111], v[214:217], v[194:197], v[96:111]
	v_mfma_f32_32x32x16_bf16 v[32:47], v[214:217], v[198:201], v[32:47]
	ds_read_b128 v[210:213], v192 offset:9280
	ds_read_b128 v[214:217], v192 offset:13888
	s_waitcnt lgkmcnt(1)
	v_mfma_f32_32x32x16_bf16 v[80:95], v[210:213], v[194:197], v[80:95]
	v_mfma_f32_32x32x16_bf16 v[16:31], v[210:213], v[198:201], v[16:31]
	s_waitcnt lgkmcnt(0)
	v_mfma_f32_32x32x16_bf16 v[64:79], v[214:217], v[194:197], v[64:79]
	v_mfma_f32_32x32x16_bf16 v[0:15], v[214:217], v[198:201], v[0:15]
	s_setprio 0
	ds_read_b128 v[194:197], v208 offset:96
	ds_read_b128 v[198:201], v208 offset:4704
	ds_read_b128 v[208:211], v192 offset:96
	ds_read_b128 v[212:215], v192 offset:4704
	s_setprio 1
	s_waitcnt lgkmcnt(1)
	v_mfma_f32_32x32x16_bf16 v[112:127], v[208:211], v[194:197], v[112:127]
	v_mfma_f32_32x32x16_bf16 v[48:63], v[208:211], v[198:201], v[48:63]
	s_waitcnt lgkmcnt(0)
	v_mfma_f32_32x32x16_bf16 v[96:111], v[212:215], v[194:197], v[96:111]
	v_mfma_f32_32x32x16_bf16 v[32:47], v[212:215], v[198:201], v[32:47]
	ds_read_b128 v[208:211], v192 offset:9312
	ds_read_b128 v[212:215], v192 offset:13920
	s_waitcnt lgkmcnt(1)
	v_mfma_f32_32x32x16_bf16 v[80:95], v[208:211], v[194:197], v[80:95]
	v_mfma_f32_32x32x16_bf16 v[16:31], v[208:211], v[198:201], v[16:31]
	s_waitcnt lgkmcnt(0)
	v_mfma_f32_32x32x16_bf16 v[64:79], v[212:215], v[194:197], v[64:79]
	v_mfma_f32_32x32x16_bf16 v[0:15], v[212:215], v[198:201], v[0:15]
	s_setprio 0
	s_andn2_b64 vcc, exec, s[48:49]
	s_cbranch_vccnz .LBB0_105
	s_barrier

; template <bool trans>
; DI void gemm_core(const GTile& tl, const GTile& nx, bool has_next  , bool chain  , bool pre, u32x4 (&ra)[4], u32x4 (&rb)[4], char* smem, f32x16 (&acc)[2][4]) {
;     ...
;   const int lrow = tid >> 3, kc = tid & 7;
;   const unsigned aoff = (unsigned)(lrow * lda + kc * 8) * 2u, boff = (unsigned)(lrow * ldb + kc * 8) * 2u;
;   const char* ag = (const char*)(A + (size_t)m0 * lda);
;   const char* bg = (const char*)(Bt + (size_t)n0 * ldb);
;   const unsigned aoffn = (unsigned)(lrow * nx.lda + kc * 8) * 2u, boffn = (unsigned)(lrow * nx.ldb + kc * 8) * 2u;
;   const char* agn = (const char*)(nx.A + (size_t)nx.m0 * nx.lda);
;   const char* bgn = (const char*)(nx.Bt + (size_t)nx.n0 * nx.ldb);
;     ...
;   const int nk = K / 64;
;   if (!pre) { G_LOAD(0); G_STORE(0); G_LOAD(1); }
;   for (int kt = 0; kt < nk; ++kt) {
;     __syncthreads();
;     G_COMPUTE(kt & 1, kt);
;   }
.LBB0_111:
	v_lshl_add_u64 v[136:137], s[0:1], 0, v[192:193]
	v_lshl_add_u64 v[138:139], s[2:3], 0, v[192:193]
	s_waitcnt lgkmcnt(0)
	s_barrier
	global_load_dwordx4 v[184:187], v[136:137], off offset:256
	global_load_dwordx4 v[188:191], v[138:139], off offset:256
	s_and_b32 s1, s36, 0x1f80000
	s_and_b32 s0, s38, 0xffffff00
	s_and_b32 s4, s33, 0xc0
	s_lshl_b32 s1, s1, 1
	s_add_u32 s2, s16, s1
	s_addc_u32 s3, s17, 0
	s_ashr_i32 s1, s0, 31
	s_lshl_b64 s[0:1], s[0:1], 12
	s_add_u32 s0, s22, s0
	s_addc_u32 s1, s23, s1
	s_lshr_b32 s5, s33, 1
	v_and_b32_e32 v11, 31, v8
	s_and_b32 s5, s5, 0xfffff80
	v_or_b32_e32 v12, s5, v11
	v_or_b32_e32 v11, s4, v11
	v_add3_u32 v148, 16, v10, v9
	v_lshrrev_b32_e32 v8, 1, v8
	v_mul_u32_u24_e32 v150, 0x90, v11
	v_lshl_add_u64 v[130:131], s[2:3], 0, v[192:193]
	v_lshl_add_u64 v[128:129], s[0:1], 0, v[192:193]
	v_and_b32_e32 v204, 16, v8
	v_add_u32_e32 v192, 0x12000, v148
	v_mul_lo_u32 v149, v12, s45
	v_add3_u32 v152, 16, v150, v204
	v_add_u32_e32 v159, 0x1b000, v148
	ds_write_b128 v192, v[0:3]
	s_waitcnt vmcnt(5)
	ds_write_b128 v159, v[4:7]
	v_add3_u32 v151, 16, v149, v204
	ds_read_b128 v[0:3], v152 offset:36864
	ds_read_b128 v[4:7], v152 offset:41472
	ds_read_b128 v[8:11], v151
	ds_read_b128 v[12:15], v151 offset:4608
	v_lshl_add_u64 v[140:141], v[136:137], 0, s[34:35]
	v_lshl_add_u64 v[142:143], v[138:139], 0, s[34:35]
	v_lshl_add_u64 v[132:133], v[136:137], 0, s[42:43]
	v_lshl_add_u64 v[134:135], v[138:139], 0, s[42:43]
	s_setprio 1
	s_waitcnt lgkmcnt(1)
	v_mfma_f32_32x32x16_bf16 v[112:127], v[0:3], v[8:11], 0
	v_mfma_f32_32x32x16_bf16 v[48:63], v[4:7], v[8:11], 0
	s_waitcnt lgkmcnt(0)
	v_mfma_f32_32x32x16_bf16 v[96:111], v[0:3], v[12:15], 0
	v_mfma_f32_32x32x16_bf16 v[32:47], v[4:7], v[12:15], 0
	ds_read_b128 v[8:11], v151 offset:9216
	ds_read_b128 v[12:15], v151 offset:13824
	s_waitcnt lgkmcnt(1)
	v_mfma_f32_32x32x16_bf16 v[80:95], v[0:3], v[8:11], 0
	v_mfma_f32_32x32x16_bf16 v[16:31], v[4:7], v[8:11], 0
	s_waitcnt lgkmcnt(0)
	v_mfma_f32_32x32x16_bf16 v[64:79], v[0:3], v[12:15], 0
	v_mfma_f32_32x32x16_bf16 v[0:15], v[4:7], v[12:15], 0
	s_setprio 0
	global_load_dwordx4 v[194:197], v[140:141], off offset:256
	global_load_dwordx4 v[198:201], v[142:143], off offset:256
	v_add_u32_e32 v158, 0x14400, v148
	v_add_u32_e32 v157, 0x1d400, v148
	ds_write_b128 v158, v[176:179]
	s_waitcnt vmcnt(6)
	ds_write_b128 v157, v[180:183]
	ds_read_b128 v[144:147], v152 offset:36896
	ds_read_b128 v[176:179], v152 offset:41504
	ds_read_b128 v[180:183], v151 offset:32
	ds_read_b128 v[208:211], v151 offset:4640
	s_setprio 1
	s_waitcnt lgkmcnt(1)
	v_mfma_f32_32x32x16_bf16 v[112:127], v[144:147], v[180:183], v[112:127]
	v_mfma_f32_32x32x16_bf16 v[48:63], v[176:179], v[180:183], v[48:63]
	s_waitcnt lgkmcnt(0)
	v_mfma_f32_32x32x16_bf16 v[96:111], v[144:147], v[208:211], v[96:111]
	v_mfma_f32_32x32x16_bf16 v[32:47], v[176:179], v[208:211], v[32:47]
	ds_read_b128 v[180:183], v151 offset:9248
	ds_read_b128 v[208:211], v151 offset:13856
	s_waitcnt lgkmcnt(1)
	v_mfma_f32_32x32x16_bf16 v[80:95], v[144:147], v[180:183], v[80:95]
	v_mfma_f32_32x32x16_bf16 v[16:31], v[176:179], v[180:183], v[16:31]
	s_waitcnt lgkmcnt(0)
	v_mfma_f32_32x32x16_bf16 v[64:79], v[144:147], v[208:211], v[64:79]
	v_mfma_f32_32x32x16_bf16 v[0:15], v[176:179], v[208:211], v[0:15]
	s_setprio 0
	global_load_dwordx4 v[176:179], v[132:133], off offset:256
	global_load_dwordx4 v[180:183], v[134:135], off offset:256
	v_add_u32_e32 v154, 0x16800, v148
	v_add_u32_e32 v153, 0x1f800, v148
	ds_write_b128 v154, v[168:171]
	s_waitcnt vmcnt(7)
	ds_write_b128 v153, v[172:175]
	ds_read_b128 v[144:147], v152 offset:36928
	ds_read_b128 v[168:171], v152 offset:41536
	ds_read_b128 v[172:175], v151 offset:64
	ds_read_b128 v[208:211], v151 offset:4672
	s_setprio 1
	s_waitcnt lgkmcnt(1)
	v_mfma_f32_32x32x16_bf16 v[112:127], v[144:147], v[172:175], v[112:127]
	v_mfma_f32_32x32x16_bf16 v[48:63], v[168:171], v[172:175], v[48:63]
	s_waitcnt lgkmcnt(0)
	v_mfma_f32_32x32x16_bf16 v[96:111], v[144:147], v[208:211], v[96:111]
	v_mfma_f32_32x32x16_bf16 v[32:47], v[168:171], v[208:211], v[32:47]
	ds_read_b128 v[172:175], v151 offset:9280
	ds_read_b128 v[208:211], v151 offset:13888
	s_waitcnt lgkmcnt(1)
	v_mfma_f32_32x32x16_bf16 v[80:95], v[144:147], v[172:175], v[80:95]
	v_mfma_f32_32x32x16_bf16 v[16:31], v[168:171], v[172:175], v[16:31]
	s_waitcnt lgkmcnt(0)
	v_mfma_f32_32x32x16_bf16 v[64:79], v[144:147], v[208:211], v[64:79]
	v_mfma_f32_32x32x16_bf16 v[0:15], v[168:171], v[208:211], v[0:15]
	s_setprio 0
	v_add_co_u32_e32 v144, vcc, s44, v136
	v_add_u32_e32 v156, 0x18c00, v148
	s_nop 0
	v_addc_co_u32_e32 v145, vcc, 0, v137, vcc
	v_add_co_u32_e32 v146, vcc, s44, v138
	v_add_u32_e32 v155, 0x21c00, v148
	s_nop 0
	v_addc_co_u32_e32 v147, vcc, 0, v139, vcc
	global_load_dwordx4 v[168:171], v[144:145], off offset:256
	global_load_dwordx4 v[172:175], v[146:147], off offset:256
	ds_write_b128 v156, v[160:163]
	s_waitcnt vmcnt(8)
	ds_write_b128 v155, v[164:167]
	ds_read_b128 v[160:163], v152 offset:36960
	ds_read_b128 v[164:167], v152 offset:41568
	ds_read_b128 v[208:211], v151 offset:96
	ds_read_b128 v[212:215], v151 offset:4704
	s_setprio 1
	s_waitcnt lgkmcnt(1)
	v_mfma_f32_32x32x16_bf16 v[112:127], v[160:163], v[208:211], v[112:127]
	v_mfma_f32_32x32x16_bf16 v[48:63], v[164:167], v[208:211], v[48:63]
	s_waitcnt lgkmcnt(0)
	v_mfma_f32_32x32x16_bf16 v[96:111], v[160:163], v[212:215], v[96:111]
	v_mfma_f32_32x32x16_bf16 v[32:47], v[164:167], v[212:215], v[32:47]
	ds_read_b128 v[208:211], v151 offset:9312
	ds_read_b128 v[212:215], v151 offset:13920
	s_waitcnt lgkmcnt(1)
	v_mfma_f32_32x32x16_bf16 v[80:95], v[160:163], v[208:211], v[80:95]
	v_mfma_f32_32x32x16_bf16 v[16:31], v[164:167], v[208:211], v[16:31]
	s_waitcnt lgkmcnt(0)
	v_mfma_f32_32x32x16_bf16 v[64:79], v[160:163], v[212:215], v[64:79]
	v_mfma_f32_32x32x16_bf16 v[0:15], v[164:167], v[212:215], v[0:15]
	s_setprio 0
	global_load_dwordx4 v[160:163], v[136:137], off offset:384
	global_load_dwordx4 v[164:167], v[138:139], off offset:384
	s_barrier
; template <bool trans>
; DI void gemm_core(const GTile& tl, const GTile& nx, bool has_next  , bool chain  , bool pre, u32x4 (&ra)[4], u32x4 (&rb)[4], char* smem, f32x16 (&acc)[2][4]) {
;     ...
;   const int nk = K / 64;
;   if (!pre) { G_LOAD(0); G_STORE(0); G_LOAD(1); }
;   for (int kt = 0; kt < nk; ++kt) {
;     __syncthreads();
;     G_COMPUTE(kt & 1, kt);
;   }
	s_add_i32 s0, 16, 0x12000
	v_add3_u32 v149, s0, v149, v204
	s_add_i32 s0, 16, 0x1b000
	v_add3_u32 v150, s0, v150, v204
	s_waitcnt vmcnt(9)
	ds_write_b128 v148, v[184:187]
	s_waitcnt vmcnt(8)
	ds_write_b128 v148, v[188:191] offset:36864
	ds_read_b128 v[184:187], v150
	ds_read_b128 v[188:191], v150 offset:4608
	ds_read_b128 v[208:211], v149
	ds_read_b128 v[212:215], v149 offset:4608
	s_setprio 1
	s_waitcnt lgkmcnt(1)
	v_mfma_f32_32x32x16_bf16 v[112:127], v[184:187], v[208:211], v[112:127]
	v_mfma_f32_32x32x16_bf16 v[48:63], v[188:191], v[208:211], v[48:63]
	s_waitcnt lgkmcnt(0)
	v_mfma_f32_32x32x16_bf16 v[96:111], v[184:187], v[212:215], v[96:111]
	v_mfma_f32_32x32x16_bf16 v[32:47], v[188:191], v[212:215], v[32:47]
	ds_read_b128 v[208:211], v149 offset:9216
	ds_read_b128 v[212:215], v149 offset:13824
	s_waitcnt lgkmcnt(1)
	v_mfma_f32_32x32x16_bf16 v[80:95], v[184:187], v[208:211], v[80:95]
	v_mfma_f32_32x32x16_bf16 v[16:31], v[188:191], v[208:211], v[16:31]
	s_waitcnt lgkmcnt(0)
	v_mfma_f32_32x32x16_bf16 v[64:79], v[184:187], v[212:215], v[64:79]
	v_mfma_f32_32x32x16_bf16 v[0:15], v[188:191], v[212:215], v[0:15]
	s_setprio 0
	global_load_dwordx4 v[184:187], v[140:141], off offset:384
	global_load_dwordx4 v[188:191], v[142:143], off offset:384
	s_waitcnt vmcnt(9)
	ds_write_b128 v148, v[194:197] offset:9216
	s_waitcnt vmcnt(8)
	ds_write_b128 v148, v[198:201] offset:46080
	ds_read_b128 v[194:197], v150 offset:32
	ds_read_b128 v[198:201], v150 offset:4640
	ds_read_b128 v[208:211], v149 offset:32
	ds_read_b128 v[212:215], v149 offset:4640
	s_setprio 1
	s_waitcnt lgkmcnt(1)
	v_mfma_f32_32x32x16_bf16 v[112:127], v[194:197], v[208:211], v[112:127]
	v_mfma_f32_32x32x16_bf16 v[48:63], v[198:201], v[208:211], v[48:63]
	s_waitcnt lgkmcnt(0)
	v_mfma_f32_32x32x16_bf16 v[96:111], v[194:197], v[212:215], v[96:111]
	v_mfma_f32_32x32x16_bf16 v[32:47], v[198:201], v[212:215], v[32:47]
	ds_read_b128 v[208:211], v149 offset:9248
	ds_read_b128 v[212:215], v149 offset:13856
	s_waitcnt lgkmcnt(1)
	v_mfma_f32_32x32x16_bf16 v[80:95], v[194:197], v[208:211], v[80:95]
	v_mfma_f32_32x32x16_bf16 v[16:31], v[198:201], v[208:211], v[16:31]
	s_waitcnt lgkmcnt(0)
	v_mfma_f32_32x32x16_bf16 v[64:79], v[194:197], v[212:215], v[64:79]
	v_mfma_f32_32x32x16_bf16 v[0:15], v[198:201], v[212:215], v[0:15]
	s_setprio 0
	global_load_dwordx4 v[194:197], v[132:133], off offset:384
	global_load_dwordx4 v[198:201], v[134:135], off offset:384
	s_waitcnt vmcnt(9)
	ds_write_b128 v148, v[176:179] offset:18432
	s_waitcnt vmcnt(8)
	ds_write_b128 v148, v[180:183] offset:55296
	ds_read_b128 v[176:179], v150 offset:64
	ds_read_b128 v[180:183], v150 offset:4672
	ds_read_b128 v[208:211], v149 offset:64
	ds_read_b128 v[212:215], v149 offset:4672
	s_setprio 1
	s_waitcnt lgkmcnt(1)
	v_mfma_f32_32x32x16_bf16 v[112:127], v[176:179], v[208:211], v[112:127]
	v_mfma_f32_32x32x16_bf16 v[48:63], v[180:183], v[208:211], v[48:63]
	s_waitcnt lgkmcnt(0)
	v_mfma_f32_32x32x16_bf16 v[96:111], v[176:179], v[212:215], v[96:111]
	v_mfma_f32_32x32x16_bf16 v[32:47], v[180:183], v[212:215], v[32:47]
	ds_read_b128 v[208:211], v149 offset:9280
	ds_read_b128 v[212:215], v149 offset:13888
	s_waitcnt lgkmcnt(1)
	v_mfma_f32_32x32x16_bf16 v[80:95], v[176:179], v[208:211], v[80:95]
	v_mfma_f32_32x32x16_bf16 v[16:31], v[180:183], v[208:211], v[16:31]
	s_waitcnt lgkmcnt(0)
	v_mfma_f32_32x32x16_bf16 v[64:79], v[176:179], v[212:215], v[64:79]
	v_mfma_f32_32x32x16_bf16 v[0:15], v[180:183], v[212:215], v[0:15]
	s_setprio 0
	global_load_dwordx4 v[176:179], v[144:145], off offset:384
	global_load_dwordx4 v[180:183], v[146:147], off offset:384
	s_waitcnt vmcnt(9)
	ds_write_b128 v148, v[168:171] offset:27648
	s_waitcnt vmcnt(8)
	ds_write_b128 v148, v[172:175] offset:64512
	ds_read_b128 v[168:171], v150 offset:96
	ds_read_b128 v[172:175], v150 offset:4704
	ds_read_b128 v[208:211], v149 offset:96
	ds_read_b128 v[212:215], v149 offset:4704
	s_setprio 1
	s_waitcnt lgkmcnt(1)
	v_mfma_f32_32x32x16_bf16 v[112:127], v[168:171], v[208:211], v[112:127]
	v_mfma_f32_32x32x16_bf16 v[48:63], v[172:175], v[208:211], v[48:63]
	s_waitcnt lgkmcnt(0)
	v_mfma_f32_32x32x16_bf16 v[96:111], v[168:171], v[212:215], v[96:111]
	v_mfma_f32_32x32x16_bf16 v[32:47], v[172:175], v[212:215], v[32:47]
	ds_read_b128 v[208:211], v149 offset:9312
	ds_read_b128 v[212:215], v149 offset:13920
	s_waitcnt lgkmcnt(1)
	v_mfma_f32_32x32x16_bf16 v[80:95], v[168:171], v[208:211], v[80:95]
	v_mfma_f32_32x32x16_bf16 v[16:31], v[172:175], v[208:211], v[16:31]
	s_waitcnt lgkmcnt(0)
	v_mfma_f32_32x32x16_bf16 v[64:79], v[168:171], v[212:215], v[64:79]
	v_mfma_f32_32x32x16_bf16 v[0:15], v[172:175], v[212:215], v[0:15]
	s_setprio 0
	global_load_dwordx4 v[168:171], v[136:137], off offset:512
	global_load_dwordx4 v[172:175], v[138:139], off offset:512
	s_barrier
; template <bool trans>
; DI void gemm_core(const GTile& tl, const GTile& nx, bool has_next  , bool chain  , bool pre, u32x4 (&ra)[4], u32x4 (&rb)[4], char* smem, f32x16 (&acc)[2][4]) {
;     ...
;   const int nk = K / 64;
;   if (!pre) { G_LOAD(0); G_STORE(0); G_LOAD(1); }
;   for (int kt = 0; kt < nk; ++kt) {
;     __syncthreads();
;     G_COMPUTE(kt & 1, kt);
;   }
	s_waitcnt vmcnt(9)
	ds_write_b128 v192, v[160:163]
	s_waitcnt vmcnt(8)
	ds_write_b128 v159, v[164:167]
	ds_read_b128 v[160:163], v152 offset:36864
	ds_read_b128 v[164:167], v152 offset:41472
	ds_read_b128 v[208:211], v151
	ds_read_b128 v[212:215], v151 offset:4608
	s_setprio 1
	s_waitcnt lgkmcnt(1)
	v_mfma_f32_32x32x16_bf16 v[112:127], v[160:163], v[208:211], v[112:127]
	v_mfma_f32_32x32x16_bf16 v[48:63], v[164:167], v[208:211], v[48:63]
	s_waitcnt lgkmcnt(0)
	v_mfma_f32_32x32x16_bf16 v[96:111], v[160:163], v[212:215], v[96:111]
	v_mfma_f32_32x32x16_bf16 v[32:47], v[164:167], v[212:215], v[32:47]
	ds_read_b128 v[208:211], v151 offset:9216
	ds_read_b128 v[212:215], v151 offset:13824
	s_waitcnt vmcnt(7)
	ds_write_b128 v158, v[184:187]
	s_waitcnt vmcnt(6)
	ds_write_b128 v157, v[188:191]
	ds_read_b128 v[184:187], v152 offset:36896
	ds_read_b128 v[188:191], v152 offset:41504
	s_waitcnt lgkmcnt(5)
	v_mfma_f32_32x32x16_bf16 v[80:95], v[160:163], v[208:211], v[80:95]
	v_mfma_f32_32x32x16_bf16 v[16:31], v[164:167], v[208:211], v[16:31]
	ds_read_b128 v[208:211], v151 offset:32
	s_waitcnt lgkmcnt(5)
	v_mfma_f32_32x32x16_bf16 v[64:79], v[160:163], v[212:215], v[64:79]
	v_mfma_f32_32x32x16_bf16 v[0:15], v[164:167], v[212:215], v[0:15]
	ds_read_b128 v[212:215], v151 offset:4640
	s_setprio 0
	global_load_dwordx4 v[160:163], v[140:141], off offset:512
	global_load_dwordx4 v[164:167], v[142:143], off offset:512
	s_setprio 1
	s_waitcnt lgkmcnt(1)
	v_mfma_f32_32x32x16_bf16 v[112:127], v[184:187], v[208:211], v[112:127]
	v_mfma_f32_32x32x16_bf16 v[48:63], v[188:191], v[208:211], v[48:63]
	s_waitcnt lgkmcnt(0)
	v_mfma_f32_32x32x16_bf16 v[96:111], v[184:187], v[212:215], v[96:111]
	v_mfma_f32_32x32x16_bf16 v[32:47], v[188:191], v[212:215], v[32:47]
	ds_read_b128 v[208:211], v151 offset:9248
	ds_read_b128 v[212:215], v151 offset:13856
	s_waitcnt vmcnt(7)
	ds_write_b128 v154, v[194:197]
	s_waitcnt vmcnt(6)
	ds_write_b128 v153, v[198:201]
	ds_read_b128 v[194:197], v152 offset:36928
	ds_read_b128 v[198:201], v152 offset:41536
	s_waitcnt lgkmcnt(5)
	v_mfma_f32_32x32x16_bf16 v[80:95], v[184:187], v[208:211], v[80:95]
	v_mfma_f32_32x32x16_bf16 v[16:31], v[188:191], v[208:211], v[16:31]
	ds_read_b128 v[208:211], v151 offset:64
	s_waitcnt lgkmcnt(5)
	v_mfma_f32_32x32x16_bf16 v[64:79], v[184:187], v[212:215], v[64:79]
	v_mfma_f32_32x32x16_bf16 v[0:15], v[188:191], v[212:215], v[0:15]
	ds_read_b128 v[212:215], v151 offset:4672
	s_setprio 0
	global_load_dwordx4 v[184:187], v[132:133], off offset:512
	global_load_dwordx4 v[188:191], v[134:135], off offset:512
	s_setprio 1
	s_waitcnt lgkmcnt(1)
	v_mfma_f32_32x32x16_bf16 v[112:127], v[194:197], v[208:211], v[112:127]
	v_mfma_f32_32x32x16_bf16 v[48:63], v[198:201], v[208:211], v[48:63]
	s_waitcnt lgkmcnt(0)
	v_mfma_f32_32x32x16_bf16 v[96:111], v[194:197], v[212:215], v[96:111]
	v_mfma_f32_32x32x16_bf16 v[32:47], v[198:201], v[212:215], v[32:47]
	ds_read_b128 v[208:211], v151 offset:9280
	ds_read_b128 v[212:215], v151 offset:13888
	s_waitcnt vmcnt(7)
	ds_write_b128 v156, v[176:179]
	s_waitcnt vmcnt(6)
	ds_write_b128 v155, v[180:183]
	ds_read_b128 v[176:179], v152 offset:36960
	ds_read_b128 v[180:183], v152 offset:41568
	s_waitcnt lgkmcnt(5)
	v_mfma_f32_32x32x16_bf16 v[80:95], v[194:197], v[208:211], v[80:95]
	v_mfma_f32_32x32x16_bf16 v[16:31], v[198:201], v[208:211], v[16:31]
	ds_read_b128 v[208:211], v151 offset:96
	s_waitcnt lgkmcnt(5)
	v_mfma_f32_32x32x16_bf16 v[64:79], v[194:197], v[212:215], v[64:79]
	v_mfma_f32_32x32x16_bf16 v[0:15], v[198:201], v[212:215], v[0:15]
	ds_read_b128 v[212:215], v151 offset:4704
	s_setprio 0
	global_load_dwordx4 v[194:197], v[144:145], off offset:512
	global_load_dwordx4 v[198:201], v[146:147], off offset:512
	s_setprio 1
	s_waitcnt lgkmcnt(1)
	v_mfma_f32_32x32x16_bf16 v[112:127], v[176:179], v[208:211], v[112:127]
	v_mfma_f32_32x32x16_bf16 v[48:63], v[180:183], v[208:211], v[48:63]
	s_waitcnt lgkmcnt(0)
	v_mfma_f32_32x32x16_bf16 v[96:111], v[176:179], v[212:215], v[96:111]
	v_mfma_f32_32x32x16_bf16 v[32:47], v[180:183], v[212:215], v[32:47]
	ds_read_b128 v[208:211], v151 offset:9312
	ds_read_b128 v[212:215], v151 offset:13920
	s_waitcnt lgkmcnt(0)
	s_barrier
	s_waitcnt vmcnt(7)
	ds_write_b128 v148, v[168:171]
	s_waitcnt vmcnt(6)
	ds_write_b128 v148, v[172:175] offset:36864
	ds_read_b128 v[168:171], v150
	ds_read_b128 v[172:175], v150 offset:4608
	v_mfma_f32_32x32x16_bf16 v[80:95], v[176:179], v[208:211], v[80:95]
	v_mfma_f32_32x32x16_bf16 v[16:31], v[180:183], v[208:211], v[16:31]
	ds_read_b128 v[208:211], v149
	v_mfma_f32_32x32x16_bf16 v[64:79], v[176:179], v[212:215], v[64:79]
	v_mfma_f32_32x32x16_bf16 v[0:15], v[180:183], v[212:215], v[0:15]
	ds_read_b128 v[212:215], v149 offset:4608
	s_setprio 0
	global_load_dwordx4 v[176:179], v[136:137], off offset:640
	global_load_dwordx4 v[180:183], v[138:139], off offset:640
	s_setprio 1
	s_waitcnt lgkmcnt(1)
	v_mfma_f32_32x32x16_bf16 v[112:127], v[168:171], v[208:211], v[112:127]
	v_mfma_f32_32x32x16_bf16 v[48:63], v[172:175], v[208:211], v[48:63]
	s_waitcnt lgkmcnt(0)
	v_mfma_f32_32x32x16_bf16 v[96:111], v[168:171], v[212:215], v[96:111]
	v_mfma_f32_32x32x16_bf16 v[32:47], v[172:175], v[212:215], v[32:47]
	ds_read_b128 v[208:211], v149 offset:9216
	ds_read_b128 v[212:215], v149 offset:13824
	s_waitcnt vmcnt(7)
	ds_write_b128 v148, v[160:163] offset:9216
	s_waitcnt vmcnt(6)
	ds_write_b128 v148, v[164:167] offset:46080
	ds_read_b128 v[160:163], v150 offset:32
	ds_read_b128 v[164:167], v150 offset:4640
	s_waitcnt lgkmcnt(5)
	v_mfma_f32_32x32x16_bf16 v[80:95], v[168:171], v[208:211], v[80:95]
	v_mfma_f32_32x32x16_bf16 v[16:31], v[172:175], v[208:211], v[16:31]
	ds_read_b128 v[208:211], v149 offset:32
	s_waitcnt lgkmcnt(5)
; template <bool trans>
; DI void gemm_core(const GTile& tl, const GTile& nx, bool has_next  , bool chain  , bool pre, u32x4 (&ra)[4], u32x4 (&rb)[4], char* smem, f32x16 (&acc)[2][4]) {
;     ...
;   const int nk = K / 64;
;   if (!pre) { G_LOAD(0); G_STORE(0); G_LOAD(1); }
;   for (int kt = 0; kt < nk; ++kt) {
;     __syncthreads();
;     G_COMPUTE(kt & 1, kt);
;   }
	v_mfma_f32_32x32x16_bf16 v[64:79], v[168:171], v[212:215], v[64:79]
	v_mfma_f32_32x32x16_bf16 v[0:15], v[172:175], v[212:215], v[0:15]
	ds_read_b128 v[212:215], v149 offset:4640
	s_setprio 0
	global_load_dwordx4 v[168:171], v[140:141], off offset:640
	global_load_dwordx4 v[172:175], v[142:143], off offset:640
	s_setprio 1
	s_waitcnt lgkmcnt(1)
	v_mfma_f32_32x32x16_bf16 v[112:127], v[160:163], v[208:211], v[112:127]
	v_mfma_f32_32x32x16_bf16 v[48:63], v[164:167], v[208:211], v[48:63]
	s_waitcnt lgkmcnt(0)
	v_mfma_f32_32x32x16_bf16 v[96:111], v[160:163], v[212:215], v[96:111]
	v_mfma_f32_32x32x16_bf16 v[32:47], v[164:167], v[212:215], v[32:47]
	ds_read_b128 v[208:211], v149 offset:9248
	ds_read_b128 v[212:215], v149 offset:13856
	s_waitcnt vmcnt(7)
	ds_write_b128 v148, v[184:187] offset:18432
	s_waitcnt vmcnt(6)
	ds_write_b128 v148, v[188:191] offset:55296
	ds_read_b128 v[184:187], v150 offset:64
	ds_read_b128 v[188:191], v150 offset:4672
	s_waitcnt lgkmcnt(5)
	v_mfma_f32_32x32x16_bf16 v[80:95], v[160:163], v[208:211], v[80:95]
	v_mfma_f32_32x32x16_bf16 v[16:31], v[164:167], v[208:211], v[16:31]
	ds_read_b128 v[208:211], v149 offset:64
	s_waitcnt lgkmcnt(5)
	v_mfma_f32_32x32x16_bf16 v[64:79], v[160:163], v[212:215], v[64:79]
	v_mfma_f32_32x32x16_bf16 v[0:15], v[164:167], v[212:215], v[0:15]
	ds_read_b128 v[212:215], v149 offset:4672
	s_setprio 0
	global_load_dwordx4 v[160:163], v[132:133], off offset:640
	global_load_dwordx4 v[164:167], v[134:135], off offset:640
	s_setprio 1
	s_waitcnt lgkmcnt(1)
	v_mfma_f32_32x32x16_bf16 v[112:127], v[184:187], v[208:211], v[112:127]
	v_mfma_f32_32x32x16_bf16 v[48:63], v[188:191], v[208:211], v[48:63]
	s_waitcnt lgkmcnt(0)
	v_mfma_f32_32x32x16_bf16 v[96:111], v[184:187], v[212:215], v[96:111]
	v_mfma_f32_32x32x16_bf16 v[32:47], v[188:191], v[212:215], v[32:47]
	ds_read_b128 v[208:211], v149 offset:9280
	ds_read_b128 v[212:215], v149 offset:13888
	s_waitcnt vmcnt(7)
	ds_write_b128 v148, v[194:197] offset:27648
	s_waitcnt vmcnt(6)
	ds_write_b128 v148, v[198:201] offset:64512
	ds_read_b128 v[194:197], v150 offset:96
	ds_read_b128 v[198:201], v150 offset:4704
	s_waitcnt lgkmcnt(5)
	v_mfma_f32_32x32x16_bf16 v[80:95], v[184:187], v[208:211], v[80:95]
	v_mfma_f32_32x32x16_bf16 v[16:31], v[188:191], v[208:211], v[16:31]
	ds_read_b128 v[208:211], v149 offset:96
	s_waitcnt lgkmcnt(5)
	v_mfma_f32_32x32x16_bf16 v[64:79], v[184:187], v[212:215], v[64:79]
	v_mfma_f32_32x32x16_bf16 v[0:15], v[188:191], v[212:215], v[0:15]
	ds_read_b128 v[212:215], v149 offset:4704
	s_setprio 0
	global_load_dwordx4 v[184:187], v[144:145], off offset:640
	global_load_dwordx4 v[188:191], v[146:147], off offset:640
	s_setprio 1
	s_waitcnt lgkmcnt(1)
	v_mfma_f32_32x32x16_bf16 v[112:127], v[194:197], v[208:211], v[112:127]
	v_mfma_f32_32x32x16_bf16 v[48:63], v[198:201], v[208:211], v[48:63]
	s_waitcnt lgkmcnt(0)
	v_mfma_f32_32x32x16_bf16 v[96:111], v[194:197], v[212:215], v[96:111]
	v_mfma_f32_32x32x16_bf16 v[32:47], v[198:201], v[212:215], v[32:47]
	ds_read_b128 v[208:211], v149 offset:9312
	ds_read_b128 v[212:215], v149 offset:13920
	s_waitcnt lgkmcnt(0)
	s_barrier
	s_waitcnt vmcnt(7)
	ds_write_b128 v192, v[176:179]
	s_waitcnt vmcnt(6)
	ds_write_b128 v159, v[180:183]
	ds_read_b128 v[176:179], v152 offset:36864
	ds_read_b128 v[180:183], v152 offset:41472
	v_mfma_f32_32x32x16_bf16 v[80:95], v[194:197], v[208:211], v[80:95]
	v_mfma_f32_32x32x16_bf16 v[16:31], v[198:201], v[208:211], v[16:31]
	ds_read_b128 v[208:211], v151
	v_mfma_f32_32x32x16_bf16 v[64:79], v[194:197], v[212:215], v[64:79]
	v_mfma_f32_32x32x16_bf16 v[0:15], v[198:201], v[212:215], v[0:15]
	ds_read_b128 v[212:215], v151 offset:4608
	s_setprio 0
	global_load_dwordx4 v[194:197], v[136:137], off offset:768
	global_load_dwordx4 v[198:201], v[138:139], off offset:768
	s_setprio 1
	s_waitcnt lgkmcnt(1)
	v_mfma_f32_32x32x16_bf16 v[112:127], v[176:179], v[208:211], v[112:127]
	v_mfma_f32_32x32x16_bf16 v[48:63], v[180:183], v[208:211], v[48:63]
	s_waitcnt lgkmcnt(0)
	v_mfma_f32_32x32x16_bf16 v[96:111], v[176:179], v[212:215], v[96:111]
	v_mfma_f32_32x32x16_bf16 v[32:47], v[180:183], v[212:215], v[32:47]
	ds_read_b128 v[208:211], v151 offset:9216
	ds_read_b128 v[212:215], v151 offset:13824
	s_waitcnt vmcnt(7)
	ds_write_b128 v158, v[168:171]
	s_waitcnt vmcnt(6)
	ds_write_b128 v157, v[172:175]
	ds_read_b128 v[168:171], v152 offset:36896
	ds_read_b128 v[172:175], v152 offset:41504
	s_waitcnt lgkmcnt(5)
	v_mfma_f32_32x32x16_bf16 v[80:95], v[176:179], v[208:211], v[80:95]
	v_mfma_f32_32x32x16_bf16 v[16:31], v[180:183], v[208:211], v[16:31]
	ds_read_b128 v[208:211], v151 offset:32
	s_waitcnt lgkmcnt(5)
	v_mfma_f32_32x32x16_bf16 v[64:79], v[176:179], v[212:215], v[64:79]
	v_mfma_f32_32x32x16_bf16 v[0:15], v[180:183], v[212:215], v[0:15]
	ds_read_b128 v[212:215], v151 offset:4640
	s_setprio 0
	global_load_dwordx4 v[176:179], v[140:141], off offset:768
	global_load_dwordx4 v[180:183], v[142:143], off offset:768
	s_setprio 1
	s_waitcnt lgkmcnt(1)
	v_mfma_f32_32x32x16_bf16 v[112:127], v[168:171], v[208:211], v[112:127]
	v_mfma_f32_32x32x16_bf16 v[48:63], v[172:175], v[208:211], v[48:63]
	s_waitcnt lgkmcnt(0)
	v_mfma_f32_32x32x16_bf16 v[96:111], v[168:171], v[212:215], v[96:111]
	v_mfma_f32_32x32x16_bf16 v[32:47], v[172:175], v[212:215], v[32:47]
	ds_read_b128 v[208:211], v151 offset:9248
	ds_read_b128 v[212:215], v151 offset:13856
	s_waitcnt vmcnt(7)
	ds_write_b128 v154, v[160:163]
	s_waitcnt vmcnt(6)
	ds_write_b128 v153, v[164:167]
	ds_read_b128 v[160:163], v152 offset:36928
	ds_read_b128 v[164:167], v152 offset:41536
	s_waitcnt lgkmcnt(5)
; template <bool trans>
; DI void gemm_core(const GTile& tl, const GTile& nx, bool has_next  , bool chain  , bool pre, u32x4 (&ra)[4], u32x4 (&rb)[4], char* smem, f32x16 (&acc)[2][4]) {
;     ...
;   const int nk = K / 64;
;   if (!pre) { G_LOAD(0); G_STORE(0); G_LOAD(1); }
;   for (int kt = 0; kt < nk; ++kt) {
;     __syncthreads();
;     G_COMPUTE(kt & 1, kt);
;   }
	v_mfma_f32_32x32x16_bf16 v[80:95], v[168:171], v[208:211], v[80:95]
	v_mfma_f32_32x32x16_bf16 v[16:31], v[172:175], v[208:211], v[16:31]
	ds_read_b128 v[208:211], v151 offset:64
	s_waitcnt lgkmcnt(5)
	v_mfma_f32_32x32x16_bf16 v[64:79], v[168:171], v[212:215], v[64:79]
	v_mfma_f32_32x32x16_bf16 v[0:15], v[172:175], v[212:215], v[0:15]
	ds_read_b128 v[212:215], v151 offset:4672
	s_setprio 0
	global_load_dwordx4 v[168:171], v[132:133], off offset:768
	global_load_dwordx4 v[172:175], v[134:135], off offset:768
	s_setprio 1
	s_waitcnt lgkmcnt(1)
	v_mfma_f32_32x32x16_bf16 v[112:127], v[160:163], v[208:211], v[112:127]
	v_mfma_f32_32x32x16_bf16 v[48:63], v[164:167], v[208:211], v[48:63]
	s_waitcnt lgkmcnt(0)
	v_mfma_f32_32x32x16_bf16 v[96:111], v[160:163], v[212:215], v[96:111]
	v_mfma_f32_32x32x16_bf16 v[32:47], v[164:167], v[212:215], v[32:47]
	ds_read_b128 v[208:211], v151 offset:9280
	ds_read_b128 v[212:215], v151 offset:13888
	s_waitcnt vmcnt(7)
	ds_write_b128 v156, v[184:187]
	s_waitcnt vmcnt(6)
	ds_write_b128 v155, v[188:191]
	ds_read_b128 v[184:187], v152 offset:36960
	ds_read_b128 v[188:191], v152 offset:41568
	s_waitcnt lgkmcnt(5)
	v_mfma_f32_32x32x16_bf16 v[80:95], v[160:163], v[208:211], v[80:95]
	v_mfma_f32_32x32x16_bf16 v[16:31], v[164:167], v[208:211], v[16:31]
	ds_read_b128 v[208:211], v151 offset:96
	s_waitcnt lgkmcnt(5)
	v_mfma_f32_32x32x16_bf16 v[64:79], v[160:163], v[212:215], v[64:79]
	v_mfma_f32_32x32x16_bf16 v[0:15], v[164:167], v[212:215], v[0:15]
	ds_read_b128 v[212:215], v151 offset:4704
	s_setprio 0
	global_load_dwordx4 v[160:163], v[144:145], off offset:768
	global_load_dwordx4 v[164:167], v[146:147], off offset:768
	s_setprio 1
	s_waitcnt lgkmcnt(1)
	v_mfma_f32_32x32x16_bf16 v[112:127], v[184:187], v[208:211], v[112:127]
	v_mfma_f32_32x32x16_bf16 v[48:63], v[188:191], v[208:211], v[48:63]
	s_waitcnt lgkmcnt(0)
	v_mfma_f32_32x32x16_bf16 v[96:111], v[184:187], v[212:215], v[96:111]
	v_mfma_f32_32x32x16_bf16 v[32:47], v[188:191], v[212:215], v[32:47]
	ds_read_b128 v[208:211], v151 offset:9312
	ds_read_b128 v[212:215], v151 offset:13920
	s_waitcnt lgkmcnt(0)
	s_barrier
	s_waitcnt vmcnt(7)
	ds_write_b128 v148, v[194:197]
	s_waitcnt vmcnt(6)
	ds_write_b128 v148, v[198:201] offset:36864
	ds_read_b128 v[194:197], v150
	ds_read_b128 v[198:201], v150 offset:4608
	v_mfma_f32_32x32x16_bf16 v[80:95], v[184:187], v[208:211], v[80:95]
	v_mfma_f32_32x32x16_bf16 v[16:31], v[188:191], v[208:211], v[16:31]
	ds_read_b128 v[208:211], v149
	v_mfma_f32_32x32x16_bf16 v[64:79], v[184:187], v[212:215], v[64:79]
	v_mfma_f32_32x32x16_bf16 v[0:15], v[188:191], v[212:215], v[0:15]
	ds_read_b128 v[212:215], v149 offset:4608
	s_setprio 0
	global_load_dwordx4 v[184:187], v[136:137], off offset:896
	global_load_dwordx4 v[188:191], v[138:139], off offset:896
	s_setprio 1
	s_waitcnt lgkmcnt(1)
	v_mfma_f32_32x32x16_bf16 v[112:127], v[194:197], v[208:211], v[112:127]
	v_mfma_f32_32x32x16_bf16 v[48:63], v[198:201], v[208:211], v[48:63]
	s_waitcnt lgkmcnt(0)
	v_mfma_f32_32x32x16_bf16 v[96:111], v[194:197], v[212:215], v[96:111]
	v_mfma_f32_32x32x16_bf16 v[32:47], v[198:201], v[212:215], v[32:47]
	ds_read_b128 v[208:211], v149 offset:9216
	ds_read_b128 v[212:215], v149 offset:13824
	s_waitcnt vmcnt(7)
	ds_write_b128 v148, v[176:179] offset:9216
	s_waitcnt vmcnt(6)
	ds_write_b128 v148, v[180:183] offset:46080
	ds_read_b128 v[176:179], v150 offset:32
	ds_read_b128 v[180:183], v150 offset:4640
	s_waitcnt lgkmcnt(5)
	v_mfma_f32_32x32x16_bf16 v[80:95], v[194:197], v[208:211], v[80:95]
	v_mfma_f32_32x32x16_bf16 v[16:31], v[198:201], v[208:211], v[16:31]
	ds_read_b128 v[208:211], v149 offset:32
	s_waitcnt lgkmcnt(5)
	v_mfma_f32_32x32x16_bf16 v[64:79], v[194:197], v[212:215], v[64:79]
	v_mfma_f32_32x32x16_bf16 v[0:15], v[198:201], v[212:215], v[0:15]
	ds_read_b128 v[212:215], v149 offset:4640
	s_setprio 0
	global_load_dwordx4 v[194:197], v[140:141], off offset:896
	global_load_dwordx4 v[198:201], v[142:143], off offset:896
	s_setprio 1
	s_waitcnt lgkmcnt(1)
	v_mfma_f32_32x32x16_bf16 v[112:127], v[176:179], v[208:211], v[112:127]
	v_mfma_f32_32x32x16_bf16 v[48:63], v[180:183], v[208:211], v[48:63]
	s_waitcnt lgkmcnt(0)
	v_mfma_f32_32x32x16_bf16 v[96:111], v[176:179], v[212:215], v[96:111]
	v_mfma_f32_32x32x16_bf16 v[32:47], v[180:183], v[212:215], v[32:47]
	ds_read_b128 v[208:211], v149 offset:9248
	ds_read_b128 v[212:215], v149 offset:13856
	s_waitcnt vmcnt(7)
	ds_write_b128 v148, v[168:171] offset:18432
	s_waitcnt vmcnt(6)
	ds_write_b128 v148, v[172:175] offset:55296
	ds_read_b128 v[168:171], v150 offset:64
	ds_read_b128 v[172:175], v150 offset:4672
	s_waitcnt lgkmcnt(5)
	v_mfma_f32_32x32x16_bf16 v[80:95], v[176:179], v[208:211], v[80:95]
	v_mfma_f32_32x32x16_bf16 v[16:31], v[180:183], v[208:211], v[16:31]
	ds_read_b128 v[208:211], v149 offset:64
	s_waitcnt lgkmcnt(5)
	v_mfma_f32_32x32x16_bf16 v[64:79], v[176:179], v[212:215], v[64:79]
	v_mfma_f32_32x32x16_bf16 v[0:15], v[180:183], v[212:215], v[0:15]
	ds_read_b128 v[212:215], v149 offset:4672
	s_setprio 0
	global_load_dwordx4 v[176:179], v[132:133], off offset:896
	global_load_dwordx4 v[180:183], v[134:135], off offset:896
	s_setprio 1
	s_waitcnt lgkmcnt(1)
	v_mfma_f32_32x32x16_bf16 v[112:127], v[168:171], v[208:211], v[112:127]
	v_mfma_f32_32x32x16_bf16 v[48:63], v[172:175], v[208:211], v[48:63]
	s_waitcnt lgkmcnt(0)
	v_mfma_f32_32x32x16_bf16 v[96:111], v[168:171], v[212:215], v[96:111]
	v_mfma_f32_32x32x16_bf16 v[32:47], v[172:175], v[212:215], v[32:47]
	ds_read_b128 v[208:211], v149 offset:9280
	ds_read_b128 v[212:215], v149 offset:13888
	s_waitcnt vmcnt(7)
	ds_write_b128 v148, v[160:163] offset:27648
	s_waitcnt vmcnt(6)
	ds_write_b128 v148, v[164:167] offset:64512
	ds_read_b128 v[160:163], v150 offset:96
	ds_read_b128 v[164:167], v150 offset:4704
	s_waitcnt lgkmcnt(5)
	v_mfma_f32_32x32x16_bf16 v[80:95], v[168:171], v[208:211], v[80:95]
	v_mfma_f32_32x32x16_bf16 v[16:31], v[172:175], v[208:211], v[16:31]
	ds_read_b128 v[208:211], v149 offset:96
	s_waitcnt lgkmcnt(5)
	v_mfma_f32_32x32x16_bf16 v[64:79], v[168:171], v[212:215], v[64:79]
	v_mfma_f32_32x32x16_bf16 v[0:15], v[172:175], v[212:215], v[0:15]
	ds_read_b128 v[212:215], v149 offset:4704
	s_setprio 0
	global_load_dwordx4 v[168:171], v[144:145], off offset:896
	global_load_dwordx4 v[172:175], v[146:147], off offset:896
	s_setprio 1
	s_waitcnt lgkmcnt(1)
	v_mfma_f32_32x32x16_bf16 v[112:127], v[160:163], v[208:211], v[112:127]
	v_mfma_f32_32x32x16_bf16 v[48:63], v[164:167], v[208:211], v[48:63]
	s_waitcnt lgkmcnt(0)
	v_mfma_f32_32x32x16_bf16 v[96:111], v[160:163], v[212:215], v[96:111]
	v_mfma_f32_32x32x16_bf16 v[32:47], v[164:167], v[212:215], v[32:47]
	ds_read_b128 v[208:211], v149 offset:9312
	ds_read_b128 v[212:215], v149 offset:13920
	s_waitcnt lgkmcnt(0)
	s_barrier
; template <bool trans>
; DI void gemm_core(const GTile& tl, const GTile& nx, bool has_next  , bool chain  , bool pre, u32x4 (&ra)[4], u32x4 (&rb)[4], char* smem, f32x16 (&acc)[2][4]) {
;     ...
;   const int nk = K / 64;
;   if (!pre) { G_LOAD(0); G_STORE(0); G_LOAD(1); }
;   for (int kt = 0; kt < nk; ++kt) {
;     __syncthreads();
;     G_COMPUTE(kt & 1, kt);
;   }
	s_waitcnt vmcnt(7)
	ds_write_b128 v192, v[184:187]
	s_waitcnt vmcnt(6)
	ds_write_b128 v159, v[188:191]
	ds_read_b128 v[184:187], v152 offset:36864
	ds_read_b128 v[188:191], v152 offset:41472
	v_mfma_f32_32x32x16_bf16 v[80:95], v[160:163], v[208:211], v[80:95]
	v_mfma_f32_32x32x16_bf16 v[16:31], v[164:167], v[208:211], v[16:31]
	ds_read_b128 v[208:211], v151
	v_mfma_f32_32x32x16_bf16 v[64:79], v[160:163], v[212:215], v[64:79]
	v_mfma_f32_32x32x16_bf16 v[0:15], v[164:167], v[212:215], v[0:15]
	ds_read_b128 v[212:215], v151 offset:4608
	s_setprio 0
	global_load_dwordx4 v[160:163], v[136:137], off offset:1024
	global_load_dwordx4 v[164:167], v[138:139], off offset:1024
	s_setprio 1
	s_waitcnt lgkmcnt(1)
	v_mfma_f32_32x32x16_bf16 v[112:127], v[184:187], v[208:211], v[112:127]
	v_mfma_f32_32x32x16_bf16 v[48:63], v[188:191], v[208:211], v[48:63]
	s_waitcnt lgkmcnt(0)
	v_mfma_f32_32x32x16_bf16 v[96:111], v[184:187], v[212:215], v[96:111]
	v_mfma_f32_32x32x16_bf16 v[32:47], v[188:191], v[212:215], v[32:47]
	ds_read_b128 v[208:211], v151 offset:9216
	ds_read_b128 v[212:215], v151 offset:13824
	s_waitcnt vmcnt(7)
	ds_write_b128 v158, v[194:197]
	s_waitcnt vmcnt(6)
	ds_write_b128 v157, v[198:201]
	ds_read_b128 v[194:197], v152 offset:36896
	ds_read_b128 v[198:201], v152 offset:41504
	s_waitcnt lgkmcnt(5)
	v_mfma_f32_32x32x16_bf16 v[80:95], v[184:187], v[208:211], v[80:95]
	v_mfma_f32_32x32x16_bf16 v[16:31], v[188:191], v[208:211], v[16:31]
	ds_read_b128 v[208:211], v151 offset:32
	s_waitcnt lgkmcnt(5)
	v_mfma_f32_32x32x16_bf16 v[64:79], v[184:187], v[212:215], v[64:79]
	v_mfma_f32_32x32x16_bf16 v[0:15], v[188:191], v[212:215], v[0:15]
	ds_read_b128 v[212:215], v151 offset:4640
	s_setprio 0
	global_load_dwordx4 v[184:187], v[140:141], off offset:1024
	global_load_dwordx4 v[188:191], v[142:143], off offset:1024
	s_setprio 1
	s_waitcnt lgkmcnt(1)
	v_mfma_f32_32x32x16_bf16 v[112:127], v[194:197], v[208:211], v[112:127]
	v_mfma_f32_32x32x16_bf16 v[48:63], v[198:201], v[208:211], v[48:63]
	s_waitcnt lgkmcnt(0)
	v_mfma_f32_32x32x16_bf16 v[96:111], v[194:197], v[212:215], v[96:111]
	v_mfma_f32_32x32x16_bf16 v[32:47], v[198:201], v[212:215], v[32:47]
	ds_read_b128 v[208:211], v151 offset:9248
	ds_read_b128 v[212:215], v151 offset:13856
	s_waitcnt vmcnt(7)
	ds_write_b128 v154, v[176:179]
	s_waitcnt vmcnt(6)
	ds_write_b128 v153, v[180:183]
	ds_read_b128 v[176:179], v152 offset:36928
	ds_read_b128 v[180:183], v152 offset:41536
	s_waitcnt lgkmcnt(5)
	v_mfma_f32_32x32x16_bf16 v[80:95], v[194:197], v[208:211], v[80:95]
	v_mfma_f32_32x32x16_bf16 v[16:31], v[198:201], v[208:211], v[16:31]
	ds_read_b128 v[208:211], v151 offset:64
	s_waitcnt lgkmcnt(5)
	v_mfma_f32_32x32x16_bf16 v[64:79], v[194:197], v[212:215], v[64:79]
	v_mfma_f32_32x32x16_bf16 v[0:15], v[198:201], v[212:215], v[0:15]
	ds_read_b128 v[212:215], v151 offset:4672
	s_setprio 0
	global_load_dwordx4 v[194:197], v[132:133], off offset:1024
	global_load_dwordx4 v[198:201], v[134:135], off offset:1024
	s_setprio 1
	s_waitcnt lgkmcnt(1)
	v_mfma_f32_32x32x16_bf16 v[112:127], v[176:179], v[208:211], v[112:127]
	v_mfma_f32_32x32x16_bf16 v[48:63], v[180:183], v[208:211], v[48:63]
	s_waitcnt lgkmcnt(0)
	v_mfma_f32_32x32x16_bf16 v[96:111], v[176:179], v[212:215], v[96:111]
	v_mfma_f32_32x32x16_bf16 v[32:47], v[180:183], v[212:215], v[32:47]
	ds_read_b128 v[208:211], v151 offset:9280
	ds_read_b128 v[212:215], v151 offset:13888
	s_waitcnt vmcnt(7)
	ds_write_b128 v156, v[168:171]
	s_waitcnt vmcnt(6)
	ds_write_b128 v155, v[172:175]
	ds_read_b128 v[168:171], v152 offset:36960
	ds_read_b128 v[172:175], v152 offset:41568
	s_waitcnt lgkmcnt(5)
	v_mfma_f32_32x32x16_bf16 v[80:95], v[176:179], v[208:211], v[80:95]
	v_mfma_f32_32x32x16_bf16 v[16:31], v[180:183], v[208:211], v[16:31]
	ds_read_b128 v[208:211], v151 offset:96
	s_waitcnt lgkmcnt(5)
	v_mfma_f32_32x32x16_bf16 v[64:79], v[176:179], v[212:215], v[64:79]
	v_mfma_f32_32x32x16_bf16 v[0:15], v[180:183], v[212:215], v[0:15]
	ds_read_b128 v[212:215], v151 offset:4704
	s_setprio 0
	global_load_dwordx4 v[176:179], v[144:145], off offset:1024
	global_load_dwordx4 v[180:183], v[146:147], off offset:1024
	s_setprio 1
	s_waitcnt lgkmcnt(1)
	v_mfma_f32_32x32x16_bf16 v[112:127], v[168:171], v[208:211], v[112:127]
	v_mfma_f32_32x32x16_bf16 v[48:63], v[172:175], v[208:211], v[48:63]
	s_waitcnt lgkmcnt(0)
	v_mfma_f32_32x32x16_bf16 v[96:111], v[168:171], v[212:215], v[96:111]
	v_mfma_f32_32x32x16_bf16 v[32:47], v[172:175], v[212:215], v[32:47]
	ds_read_b128 v[208:211], v151 offset:9312
	ds_read_b128 v[212:215], v151 offset:13920
	s_waitcnt lgkmcnt(0)
	s_barrier
; template <bool trans>
; DI void gemm_core(const GTile& tl, const GTile& nx, bool has_next  , bool chain  , bool pre, u32x4 (&ra)[4], u32x4 (&rb)[4], char* smem, f32x16 (&acc)[2][4]) {
;     ...
;   const int nk = K / 64;
;   if (!pre) { G_LOAD(0); G_STORE(0); G_LOAD(1); }
;   for (int kt = 0; kt < nk; ++kt) {
;     __syncthreads();
;     G_COMPUTE(kt & 1, kt);
;   }
	s_waitcnt vmcnt(7)
	ds_write_b128 v148, v[160:163]
	s_waitcnt vmcnt(6)
	ds_write_b128 v148, v[164:167] offset:36864
	ds_read_b128 v[160:163], v150
	ds_read_b128 v[164:167], v150 offset:4608
	v_mfma_f32_32x32x16_bf16 v[80:95], v[168:171], v[208:211], v[80:95]
	v_mfma_f32_32x32x16_bf16 v[16:31], v[172:175], v[208:211], v[16:31]
	ds_read_b128 v[208:211], v149
	v_mfma_f32_32x32x16_bf16 v[64:79], v[168:171], v[212:215], v[64:79]
	v_mfma_f32_32x32x16_bf16 v[0:15], v[172:175], v[212:215], v[0:15]
	ds_read_b128 v[212:215], v149 offset:4608
	s_setprio 0
	global_load_dwordx4 v[168:171], v[136:137], off offset:1152
	global_load_dwordx4 v[172:175], v[138:139], off offset:1152
	s_setprio 1
	s_waitcnt lgkmcnt(1)
	v_mfma_f32_32x32x16_bf16 v[112:127], v[160:163], v[208:211], v[112:127]
	v_mfma_f32_32x32x16_bf16 v[48:63], v[164:167], v[208:211], v[48:63]
	s_waitcnt lgkmcnt(0)
	v_mfma_f32_32x32x16_bf16 v[96:111], v[160:163], v[212:215], v[96:111]
	v_mfma_f32_32x32x16_bf16 v[32:47], v[164:167], v[212:215], v[32:47]
	ds_read_b128 v[208:211], v149 offset:9216
	ds_read_b128 v[212:215], v149 offset:13824
	s_waitcnt vmcnt(7)
	ds_write_b128 v148, v[184:187] offset:9216
	s_waitcnt vmcnt(6)
	ds_write_b128 v148, v[188:191] offset:46080
	ds_read_b128 v[184:187], v150 offset:32
	ds_read_b128 v[188:191], v150 offset:4640
	s_waitcnt lgkmcnt(5)
	v_mfma_f32_32x32x16_bf16 v[80:95], v[160:163], v[208:211], v[80:95]
	v_mfma_f32_32x32x16_bf16 v[16:31], v[164:167], v[208:211], v[16:31]
	ds_read_b128 v[208:211], v149 offset:32
	s_waitcnt lgkmcnt(5)
	v_mfma_f32_32x32x16_bf16 v[64:79], v[160:163], v[212:215], v[64:79]
	v_mfma_f32_32x32x16_bf16 v[0:15], v[164:167], v[212:215], v[0:15]
	ds_read_b128 v[212:215], v149 offset:4640
	s_setprio 0
	global_load_dwordx4 v[160:163], v[140:141], off offset:1152
	global_load_dwordx4 v[164:167], v[142:143], off offset:1152
	s_setprio 1
	s_waitcnt lgkmcnt(1)
	v_mfma_f32_32x32x16_bf16 v[112:127], v[184:187], v[208:211], v[112:127]
	v_mfma_f32_32x32x16_bf16 v[48:63], v[188:191], v[208:211], v[48:63]
	s_waitcnt lgkmcnt(0)
	v_mfma_f32_32x32x16_bf16 v[96:111], v[184:187], v[212:215], v[96:111]
	v_mfma_f32_32x32x16_bf16 v[32:47], v[188:191], v[212:215], v[32:47]
	ds_read_b128 v[208:211], v149 offset:9248
	ds_read_b128 v[212:215], v149 offset:13856
	s_waitcnt vmcnt(7)
	ds_write_b128 v148, v[194:197] offset:18432
	s_waitcnt vmcnt(6)
	ds_write_b128 v148, v[198:201] offset:55296
	ds_read_b128 v[194:197], v150 offset:64
	ds_read_b128 v[198:201], v150 offset:4672
	s_waitcnt lgkmcnt(5)
	v_mfma_f32_32x32x16_bf16 v[80:95], v[184:187], v[208:211], v[80:95]
	v_mfma_f32_32x32x16_bf16 v[16:31], v[188:191], v[208:211], v[16:31]
	ds_read_b128 v[208:211], v149 offset:64
	s_waitcnt lgkmcnt(5)
	v_mfma_f32_32x32x16_bf16 v[64:79], v[184:187], v[212:215], v[64:79]
	v_mfma_f32_32x32x16_bf16 v[0:15], v[188:191], v[212:215], v[0:15]
	ds_read_b128 v[212:215], v149 offset:4672
	s_setprio 0
	global_load_dwordx4 v[184:187], v[132:133], off offset:1152
	global_load_dwordx4 v[188:191], v[134:135], off offset:1152
	s_setprio 1
	s_waitcnt lgkmcnt(1)
	v_mfma_f32_32x32x16_bf16 v[112:127], v[194:197], v[208:211], v[112:127]
	v_mfma_f32_32x32x16_bf16 v[48:63], v[198:201], v[208:211], v[48:63]
	s_waitcnt lgkmcnt(0)
	v_mfma_f32_32x32x16_bf16 v[96:111], v[194:197], v[212:215], v[96:111]
	v_mfma_f32_32x32x16_bf16 v[32:47], v[198:201], v[212:215], v[32:47]
	ds_read_b128 v[208:211], v149 offset:9280
	ds_read_b128 v[212:215], v149 offset:13888
	s_waitcnt vmcnt(7)
	ds_write_b128 v148, v[176:179] offset:27648
	s_waitcnt vmcnt(6)
	ds_write_b128 v148, v[180:183] offset:64512
	ds_read_b128 v[176:179], v150 offset:96
	ds_read_b128 v[180:183], v150 offset:4704
	s_waitcnt lgkmcnt(5)
	v_mfma_f32_32x32x16_bf16 v[80:95], v[194:197], v[208:211], v[80:95]
	v_mfma_f32_32x32x16_bf16 v[16:31], v[198:201], v[208:211], v[16:31]
	ds_read_b128 v[208:211], v149 offset:96
	s_waitcnt lgkmcnt(5)
	v_mfma_f32_32x32x16_bf16 v[64:79], v[194:197], v[212:215], v[64:79]
	v_mfma_f32_32x32x16_bf16 v[0:15], v[198:201], v[212:215], v[0:15]
	ds_read_b128 v[212:215], v149 offset:4704
	s_setprio 0
	global_load_dwordx4 v[194:197], v[144:145], off offset:1152
	global_load_dwordx4 v[198:201], v[146:147], off offset:1152
	s_setprio 1
	s_waitcnt lgkmcnt(1)
	v_mfma_f32_32x32x16_bf16 v[112:127], v[176:179], v[208:211], v[112:127]
	v_mfma_f32_32x32x16_bf16 v[48:63], v[180:183], v[208:211], v[48:63]
	s_waitcnt lgkmcnt(0)
	v_mfma_f32_32x32x16_bf16 v[96:111], v[176:179], v[212:215], v[96:111]
	v_mfma_f32_32x32x16_bf16 v[32:47], v[180:183], v[212:215], v[32:47]
	ds_read_b128 v[208:211], v149 offset:9312
	ds_read_b128 v[212:215], v149 offset:13920
	s_waitcnt lgkmcnt(0)
	s_barrier
; template <bool trans>
; DI void gemm_core(const GTile& tl, const GTile& nx, bool has_next  , bool chain  , bool pre, u32x4 (&ra)[4], u32x4 (&rb)[4], char* smem, f32x16 (&acc)[2][4]) {
;     ...
;   const int nk = K / 64;
;   if (!pre) { G_LOAD(0); G_STORE(0); G_LOAD(1); }
;   for (int kt = 0; kt < nk; ++kt) {
;     __syncthreads();
;     G_COMPUTE(kt & 1, kt);
;   }
	s_waitcnt vmcnt(7)
	ds_write_b128 v192, v[168:171]
	s_waitcnt vmcnt(6)
	ds_write_b128 v159, v[172:175]
	ds_read_b128 v[168:171], v152 offset:36864
	ds_read_b128 v[172:175], v152 offset:41472
	v_mfma_f32_32x32x16_bf16 v[80:95], v[176:179], v[208:211], v[80:95]
	v_mfma_f32_32x32x16_bf16 v[16:31], v[180:183], v[208:211], v[16:31]
	ds_read_b128 v[208:211], v151
	v_mfma_f32_32x32x16_bf16 v[64:79], v[176:179], v[212:215], v[64:79]
	v_mfma_f32_32x32x16_bf16 v[0:15], v[180:183], v[212:215], v[0:15]
	ds_read_b128 v[212:215], v151 offset:4608
	s_setprio 0
	global_load_dwordx4 v[176:179], v[136:137], off offset:1280
	global_load_dwordx4 v[180:183], v[138:139], off offset:1280
	s_setprio 1
	s_waitcnt lgkmcnt(1)
	v_mfma_f32_32x32x16_bf16 v[112:127], v[168:171], v[208:211], v[112:127]
	v_mfma_f32_32x32x16_bf16 v[48:63], v[172:175], v[208:211], v[48:63]
	s_waitcnt lgkmcnt(0)
	v_mfma_f32_32x32x16_bf16 v[96:111], v[168:171], v[212:215], v[96:111]
	v_mfma_f32_32x32x16_bf16 v[32:47], v[172:175], v[212:215], v[32:47]
	ds_read_b128 v[208:211], v151 offset:9216
	ds_read_b128 v[212:215], v151 offset:13824
	s_waitcnt vmcnt(7)
	ds_write_b128 v158, v[160:163]
	s_waitcnt vmcnt(6)
	ds_write_b128 v157, v[164:167]
	ds_read_b128 v[160:163], v152 offset:36896
	ds_read_b128 v[164:167], v152 offset:41504
	s_waitcnt lgkmcnt(5)
	v_mfma_f32_32x32x16_bf16 v[80:95], v[168:171], v[208:211], v[80:95]
	v_mfma_f32_32x32x16_bf16 v[16:31], v[172:175], v[208:211], v[16:31]
	ds_read_b128 v[208:211], v151 offset:32
	s_waitcnt lgkmcnt(5)
	v_mfma_f32_32x32x16_bf16 v[64:79], v[168:171], v[212:215], v[64:79]
	v_mfma_f32_32x32x16_bf16 v[0:15], v[172:175], v[212:215], v[0:15]
	ds_read_b128 v[212:215], v151 offset:4640
	s_setprio 0
	global_load_dwordx4 v[168:171], v[140:141], off offset:1280
	global_load_dwordx4 v[172:175], v[142:143], off offset:1280
	s_setprio 1
	s_waitcnt lgkmcnt(1)
	v_mfma_f32_32x32x16_bf16 v[112:127], v[160:163], v[208:211], v[112:127]
	v_mfma_f32_32x32x16_bf16 v[48:63], v[164:167], v[208:211], v[48:63]
	s_waitcnt lgkmcnt(0)
	v_mfma_f32_32x32x16_bf16 v[96:111], v[160:163], v[212:215], v[96:111]
	v_mfma_f32_32x32x16_bf16 v[32:47], v[164:167], v[212:215], v[32:47]
	ds_read_b128 v[208:211], v151 offset:9248
	ds_read_b128 v[212:215], v151 offset:13856
	s_waitcnt vmcnt(7)
	ds_write_b128 v154, v[184:187]
	s_waitcnt vmcnt(6)
	ds_write_b128 v153, v[188:191]
	ds_read_b128 v[184:187], v152 offset:36928
	ds_read_b128 v[188:191], v152 offset:41536
	s_waitcnt lgkmcnt(5)
	v_mfma_f32_32x32x16_bf16 v[80:95], v[160:163], v[208:211], v[80:95]
	v_mfma_f32_32x32x16_bf16 v[16:31], v[164:167], v[208:211], v[16:31]
	ds_read_b128 v[208:211], v151 offset:64
	s_waitcnt lgkmcnt(5)
	v_mfma_f32_32x32x16_bf16 v[64:79], v[160:163], v[212:215], v[64:79]
	v_mfma_f32_32x32x16_bf16 v[0:15], v[164:167], v[212:215], v[0:15]
	ds_read_b128 v[212:215], v151 offset:4672
	s_setprio 0
	global_load_dwordx4 v[160:163], v[132:133], off offset:1280
	global_load_dwordx4 v[164:167], v[134:135], off offset:1280
	s_setprio 1
	s_waitcnt lgkmcnt(1)
	v_mfma_f32_32x32x16_bf16 v[112:127], v[184:187], v[208:211], v[112:127]
	v_mfma_f32_32x32x16_bf16 v[48:63], v[188:191], v[208:211], v[48:63]
	s_waitcnt lgkmcnt(0)
	v_mfma_f32_32x32x16_bf16 v[96:111], v[184:187], v[212:215], v[96:111]
	v_mfma_f32_32x32x16_bf16 v[32:47], v[188:191], v[212:215], v[32:47]
	ds_read_b128 v[208:211], v151 offset:9280
	ds_read_b128 v[212:215], v151 offset:13888
	s_waitcnt vmcnt(7)
	ds_write_b128 v156, v[194:197]
	s_waitcnt vmcnt(6)
	ds_write_b128 v155, v[198:201]
	ds_read_b128 v[194:197], v152 offset:36960
	ds_read_b128 v[198:201], v152 offset:41568
	s_waitcnt lgkmcnt(5)
	v_mfma_f32_32x32x16_bf16 v[80:95], v[184:187], v[208:211], v[80:95]
	v_mfma_f32_32x32x16_bf16 v[16:31], v[188:191], v[208:211], v[16:31]
	ds_read_b128 v[208:211], v151 offset:96
	s_waitcnt lgkmcnt(5)
	v_mfma_f32_32x32x16_bf16 v[64:79], v[184:187], v[212:215], v[64:79]
	v_mfma_f32_32x32x16_bf16 v[0:15], v[188:191], v[212:215], v[0:15]
	ds_read_b128 v[212:215], v151 offset:4704
	s_setprio 0
	global_load_dwordx4 v[184:187], v[144:145], off offset:1280
	global_load_dwordx4 v[188:191], v[146:147], off offset:1280
	s_setprio 1
	s_waitcnt lgkmcnt(1)
	v_mfma_f32_32x32x16_bf16 v[112:127], v[194:197], v[208:211], v[112:127]
	v_mfma_f32_32x32x16_bf16 v[48:63], v[198:201], v[208:211], v[48:63]
	s_waitcnt lgkmcnt(0)
	v_mfma_f32_32x32x16_bf16 v[96:111], v[194:197], v[212:215], v[96:111]
	v_mfma_f32_32x32x16_bf16 v[32:47], v[198:201], v[212:215], v[32:47]
	ds_read_b128 v[208:211], v151 offset:9312
	ds_read_b128 v[212:215], v151 offset:13920
	s_waitcnt lgkmcnt(0)
	s_barrier
; template <bool trans>
; DI void gemm_core(const GTile& tl, const GTile& nx, bool has_next  , bool chain  , bool pre, u32x4 (&ra)[4], u32x4 (&rb)[4], char* smem, f32x16 (&acc)[2][4]) {
;     ...
;   const int nk = K / 64;
;   if (!pre) { G_LOAD(0); G_STORE(0); G_LOAD(1); }
;   for (int kt = 0; kt < nk; ++kt) {
;     __syncthreads();
;     G_COMPUTE(kt & 1, kt);
;   }
	s_waitcnt vmcnt(7)
	ds_write_b128 v148, v[176:179]
	s_waitcnt vmcnt(6)
	ds_write_b128 v148, v[180:183] offset:36864
	ds_read_b128 v[176:179], v150
	ds_read_b128 v[180:183], v150 offset:4608
	v_mfma_f32_32x32x16_bf16 v[80:95], v[194:197], v[208:211], v[80:95]
	v_mfma_f32_32x32x16_bf16 v[16:31], v[198:201], v[208:211], v[16:31]
	ds_read_b128 v[208:211], v149
	v_mfma_f32_32x32x16_bf16 v[64:79], v[194:197], v[212:215], v[64:79]
	v_mfma_f32_32x32x16_bf16 v[0:15], v[198:201], v[212:215], v[0:15]
	ds_read_b128 v[212:215], v149 offset:4608
	s_setprio 0
	global_load_dwordx4 v[194:197], v[136:137], off offset:1408
	global_load_dwordx4 v[198:201], v[138:139], off offset:1408
	s_setprio 1
	s_waitcnt lgkmcnt(1)
	v_mfma_f32_32x32x16_bf16 v[112:127], v[176:179], v[208:211], v[112:127]
	v_mfma_f32_32x32x16_bf16 v[48:63], v[180:183], v[208:211], v[48:63]
	s_waitcnt lgkmcnt(0)
	v_mfma_f32_32x32x16_bf16 v[96:111], v[176:179], v[212:215], v[96:111]
	v_mfma_f32_32x32x16_bf16 v[32:47], v[180:183], v[212:215], v[32:47]
	ds_read_b128 v[208:211], v149 offset:9216
	ds_read_b128 v[212:215], v149 offset:13824
	s_waitcnt vmcnt(7)
	ds_write_b128 v148, v[168:171] offset:9216
	s_waitcnt vmcnt(6)
	ds_write_b128 v148, v[172:175] offset:46080
	ds_read_b128 v[168:171], v150 offset:32
	ds_read_b128 v[172:175], v150 offset:4640
	s_waitcnt lgkmcnt(5)
	v_mfma_f32_32x32x16_bf16 v[80:95], v[176:179], v[208:211], v[80:95]
	v_mfma_f32_32x32x16_bf16 v[16:31], v[180:183], v[208:211], v[16:31]
	ds_read_b128 v[208:211], v149 offset:32
	s_waitcnt lgkmcnt(5)
	v_mfma_f32_32x32x16_bf16 v[64:79], v[176:179], v[212:215], v[64:79]
	v_mfma_f32_32x32x16_bf16 v[0:15], v[180:183], v[212:215], v[0:15]
	ds_read_b128 v[212:215], v149 offset:4640
	s_setprio 0
	global_load_dwordx4 v[176:179], v[140:141], off offset:1408
	global_load_dwordx4 v[180:183], v[142:143], off offset:1408
	s_setprio 1
	s_waitcnt lgkmcnt(1)
	v_mfma_f32_32x32x16_bf16 v[112:127], v[168:171], v[208:211], v[112:127]
	v_mfma_f32_32x32x16_bf16 v[48:63], v[172:175], v[208:211], v[48:63]
	s_waitcnt lgkmcnt(0)
	v_mfma_f32_32x32x16_bf16 v[96:111], v[168:171], v[212:215], v[96:111]
	v_mfma_f32_32x32x16_bf16 v[32:47], v[172:175], v[212:215], v[32:47]
	ds_read_b128 v[208:211], v149 offset:9248
	ds_read_b128 v[212:215], v149 offset:13856
	s_waitcnt vmcnt(7)
	ds_write_b128 v148, v[160:163] offset:18432
	s_waitcnt vmcnt(6)
	ds_write_b128 v148, v[164:167] offset:55296
	ds_read_b128 v[160:163], v150 offset:64
	ds_read_b128 v[164:167], v150 offset:4672
	s_waitcnt lgkmcnt(5)
	v_mfma_f32_32x32x16_bf16 v[80:95], v[168:171], v[208:211], v[80:95]
	v_mfma_f32_32x32x16_bf16 v[16:31], v[172:175], v[208:211], v[16:31]
	ds_read_b128 v[208:211], v149 offset:64
	s_waitcnt lgkmcnt(5)
	v_mfma_f32_32x32x16_bf16 v[64:79], v[168:171], v[212:215], v[64:79]
	v_mfma_f32_32x32x16_bf16 v[0:15], v[172:175], v[212:215], v[0:15]
	ds_read_b128 v[212:215], v149 offset:4672
	s_setprio 0
	global_load_dwordx4 v[168:171], v[132:133], off offset:1408
	global_load_dwordx4 v[172:175], v[134:135], off offset:1408
	s_setprio 1
	s_waitcnt lgkmcnt(1)
	v_mfma_f32_32x32x16_bf16 v[112:127], v[160:163], v[208:211], v[112:127]
	v_mfma_f32_32x32x16_bf16 v[48:63], v[164:167], v[208:211], v[48:63]
	s_waitcnt lgkmcnt(0)
	v_mfma_f32_32x32x16_bf16 v[96:111], v[160:163], v[212:215], v[96:111]
	v_mfma_f32_32x32x16_bf16 v[32:47], v[164:167], v[212:215], v[32:47]
	ds_read_b128 v[208:211], v149 offset:9280
	ds_read_b128 v[212:215], v149 offset:13888
	s_waitcnt vmcnt(7)
	ds_write_b128 v148, v[184:187] offset:27648
	s_waitcnt vmcnt(6)
	ds_write_b128 v148, v[188:191] offset:64512
	ds_read_b128 v[184:187], v150 offset:96
	ds_read_b128 v[188:191], v150 offset:4704
	s_waitcnt lgkmcnt(5)
	v_mfma_f32_32x32x16_bf16 v[80:95], v[160:163], v[208:211], v[80:95]
	v_mfma_f32_32x32x16_bf16 v[16:31], v[164:167], v[208:211], v[16:31]
	ds_read_b128 v[208:211], v149 offset:96
	s_waitcnt lgkmcnt(5)
	v_mfma_f32_32x32x16_bf16 v[64:79], v[160:163], v[212:215], v[64:79]
	v_mfma_f32_32x32x16_bf16 v[0:15], v[164:167], v[212:215], v[0:15]
	ds_read_b128 v[212:215], v149 offset:4704
	s_setprio 0
	global_load_dwordx4 v[160:163], v[144:145], off offset:1408
	global_load_dwordx4 v[164:167], v[146:147], off offset:1408
	s_setprio 1
	s_waitcnt lgkmcnt(1)
	v_mfma_f32_32x32x16_bf16 v[112:127], v[184:187], v[208:211], v[112:127]
	v_mfma_f32_32x32x16_bf16 v[48:63], v[188:191], v[208:211], v[48:63]
	s_waitcnt lgkmcnt(0)
	v_mfma_f32_32x32x16_bf16 v[96:111], v[184:187], v[212:215], v[96:111]
	v_mfma_f32_32x32x16_bf16 v[32:47], v[188:191], v[212:215], v[32:47]
	ds_read_b128 v[208:211], v149 offset:9312
	ds_read_b128 v[212:215], v149 offset:13920
	s_waitcnt lgkmcnt(0)
	s_barrier
; template <bool trans>
; DI void gemm_core(const GTile& tl, const GTile& nx, bool has_next  , bool chain  , bool pre, u32x4 (&ra)[4], u32x4 (&rb)[4], char* smem, f32x16 (&acc)[2][4]) {
;     ...
;   const int nk = K / 64;
;   if (!pre) { G_LOAD(0); G_STORE(0); G_LOAD(1); }
;   for (int kt = 0; kt < nk; ++kt) {
;     __syncthreads();
;     G_COMPUTE(kt & 1, kt);
;   }
	s_waitcnt vmcnt(7)
	ds_write_b128 v192, v[194:197]
	s_waitcnt vmcnt(6)
	ds_write_b128 v159, v[198:201]
	ds_read_b128 v[194:197], v152 offset:36864
	ds_read_b128 v[198:201], v152 offset:41472
	v_mfma_f32_32x32x16_bf16 v[80:95], v[184:187], v[208:211], v[80:95]
	v_mfma_f32_32x32x16_bf16 v[16:31], v[188:191], v[208:211], v[16:31]
	ds_read_b128 v[208:211], v151
	v_mfma_f32_32x32x16_bf16 v[64:79], v[184:187], v[212:215], v[64:79]
	v_mfma_f32_32x32x16_bf16 v[0:15], v[188:191], v[212:215], v[0:15]
	ds_read_b128 v[212:215], v151 offset:4608
	s_setprio 0
	global_load_dwordx4 v[184:187], v[136:137], off offset:1536
	global_load_dwordx4 v[188:191], v[138:139], off offset:1536
	s_setprio 1
	s_waitcnt lgkmcnt(1)
	v_mfma_f32_32x32x16_bf16 v[112:127], v[194:197], v[208:211], v[112:127]
	v_mfma_f32_32x32x16_bf16 v[48:63], v[198:201], v[208:211], v[48:63]
	s_waitcnt lgkmcnt(0)
	v_mfma_f32_32x32x16_bf16 v[96:111], v[194:197], v[212:215], v[96:111]
	v_mfma_f32_32x32x16_bf16 v[32:47], v[198:201], v[212:215], v[32:47]
	ds_read_b128 v[208:211], v151 offset:9216
	ds_read_b128 v[212:215], v151 offset:13824
	s_waitcnt vmcnt(7)
	ds_write_b128 v158, v[176:179]
	s_waitcnt vmcnt(6)
	ds_write_b128 v157, v[180:183]
	ds_read_b128 v[176:179], v152 offset:36896
	ds_read_b128 v[180:183], v152 offset:41504
	s_waitcnt lgkmcnt(5)
	v_mfma_f32_32x32x16_bf16 v[80:95], v[194:197], v[208:211], v[80:95]
	v_mfma_f32_32x32x16_bf16 v[16:31], v[198:201], v[208:211], v[16:31]
	ds_read_b128 v[208:211], v151 offset:32
	s_waitcnt lgkmcnt(5)
	v_mfma_f32_32x32x16_bf16 v[64:79], v[194:197], v[212:215], v[64:79]
	v_mfma_f32_32x32x16_bf16 v[0:15], v[198:201], v[212:215], v[0:15]
	ds_read_b128 v[212:215], v151 offset:4640
	s_setprio 0
	global_load_dwordx4 v[194:197], v[140:141], off offset:1536
	global_load_dwordx4 v[198:201], v[142:143], off offset:1536
	s_setprio 1
	s_waitcnt lgkmcnt(1)
	v_mfma_f32_32x32x16_bf16 v[112:127], v[176:179], v[208:211], v[112:127]
	v_mfma_f32_32x32x16_bf16 v[48:63], v[180:183], v[208:211], v[48:63]
	s_waitcnt lgkmcnt(0)
	v_mfma_f32_32x32x16_bf16 v[96:111], v[176:179], v[212:215], v[96:111]
	v_mfma_f32_32x32x16_bf16 v[32:47], v[180:183], v[212:215], v[32:47]
	ds_read_b128 v[208:211], v151 offset:9248
	ds_read_b128 v[212:215], v151 offset:13856
	s_waitcnt vmcnt(7)
	ds_write_b128 v154, v[168:171]
	s_waitcnt vmcnt(6)
	ds_write_b128 v153, v[172:175]
	ds_read_b128 v[168:171], v152 offset:36928
	ds_read_b128 v[172:175], v152 offset:41536
	s_waitcnt lgkmcnt(5)
	v_mfma_f32_32x32x16_bf16 v[80:95], v[176:179], v[208:211], v[80:95]
	v_mfma_f32_32x32x16_bf16 v[16:31], v[180:183], v[208:211], v[16:31]
	ds_read_b128 v[208:211], v151 offset:64
	s_waitcnt lgkmcnt(5)
	v_mfma_f32_32x32x16_bf16 v[64:79], v[176:179], v[212:215], v[64:79]
	v_mfma_f32_32x32x16_bf16 v[0:15], v[180:183], v[212:215], v[0:15]
	ds_read_b128 v[212:215], v151 offset:4672
	s_setprio 0
	global_load_dwordx4 v[176:179], v[132:133], off offset:1536
	global_load_dwordx4 v[180:183], v[134:135], off offset:1536
	s_setprio 1
	s_waitcnt lgkmcnt(1)
	v_mfma_f32_32x32x16_bf16 v[112:127], v[168:171], v[208:211], v[112:127]
	v_mfma_f32_32x32x16_bf16 v[48:63], v[172:175], v[208:211], v[48:63]
	s_waitcnt lgkmcnt(0)
	v_mfma_f32_32x32x16_bf16 v[96:111], v[168:171], v[212:215], v[96:111]
	v_mfma_f32_32x32x16_bf16 v[32:47], v[172:175], v[212:215], v[32:47]
	ds_read_b128 v[208:211], v151 offset:9280
	ds_read_b128 v[212:215], v151 offset:13888
	s_waitcnt vmcnt(7)
	ds_write_b128 v156, v[160:163]
	s_waitcnt vmcnt(6)
	ds_write_b128 v155, v[164:167]
	ds_read_b128 v[160:163], v152 offset:36960
	ds_read_b128 v[164:167], v152 offset:41568
	s_waitcnt lgkmcnt(5)
	v_mfma_f32_32x32x16_bf16 v[80:95], v[168:171], v[208:211], v[80:95]
	v_mfma_f32_32x32x16_bf16 v[16:31], v[172:175], v[208:211], v[16:31]
	ds_read_b128 v[208:211], v151 offset:96
	s_waitcnt lgkmcnt(5)
	v_mfma_f32_32x32x16_bf16 v[64:79], v[168:171], v[212:215], v[64:79]
	v_mfma_f32_32x32x16_bf16 v[0:15], v[172:175], v[212:215], v[0:15]
	ds_read_b128 v[212:215], v151 offset:4704
	s_setprio 0
	global_load_dwordx4 v[168:171], v[144:145], off offset:1536
	global_load_dwordx4 v[172:175], v[146:147], off offset:1536
	s_setprio 1
	s_waitcnt lgkmcnt(1)
	v_mfma_f32_32x32x16_bf16 v[112:127], v[160:163], v[208:211], v[112:127]
	v_mfma_f32_32x32x16_bf16 v[48:63], v[164:167], v[208:211], v[48:63]
	s_waitcnt lgkmcnt(0)
	v_mfma_f32_32x32x16_bf16 v[96:111], v[160:163], v[212:215], v[96:111]
	v_mfma_f32_32x32x16_bf16 v[32:47], v[164:167], v[212:215], v[32:47]
	ds_read_b128 v[208:211], v151 offset:9312
	ds_read_b128 v[212:215], v151 offset:13920
	s_waitcnt lgkmcnt(0)
	s_barrier
; template <bool trans>
; DI void gemm_core(const GTile& tl, const GTile& nx, bool has_next  , bool chain  , bool pre, u32x4 (&ra)[4], u32x4 (&rb)[4], char* smem, f32x16 (&acc)[2][4]) {
;     ...
;   const int nk = K / 64;
;   if (!pre) { G_LOAD(0); G_STORE(0); G_LOAD(1); }
;   for (int kt = 0; kt < nk; ++kt) {
;     __syncthreads();
;     G_COMPUTE(kt & 1, kt);
;   }
	s_waitcnt vmcnt(7)
	ds_write_b128 v148, v[184:187]
	s_waitcnt vmcnt(6)
	ds_write_b128 v148, v[188:191] offset:36864
	ds_read_b128 v[184:187], v150
	ds_read_b128 v[188:191], v150 offset:4608
	v_mfma_f32_32x32x16_bf16 v[80:95], v[160:163], v[208:211], v[80:95]
	v_mfma_f32_32x32x16_bf16 v[16:31], v[164:167], v[208:211], v[16:31]
	ds_read_b128 v[208:211], v149
	v_mfma_f32_32x32x16_bf16 v[64:79], v[160:163], v[212:215], v[64:79]
	v_mfma_f32_32x32x16_bf16 v[0:15], v[164:167], v[212:215], v[0:15]
	ds_read_b128 v[212:215], v149 offset:4608
	s_setprio 0
	global_load_dwordx4 v[160:163], v[136:137], off offset:1664
	global_load_dwordx4 v[164:167], v[138:139], off offset:1664
	s_setprio 1
	s_waitcnt lgkmcnt(1)
	v_mfma_f32_32x32x16_bf16 v[112:127], v[184:187], v[208:211], v[112:127]
	v_mfma_f32_32x32x16_bf16 v[48:63], v[188:191], v[208:211], v[48:63]
	s_waitcnt lgkmcnt(0)
	v_mfma_f32_32x32x16_bf16 v[96:111], v[184:187], v[212:215], v[96:111]
	v_mfma_f32_32x32x16_bf16 v[32:47], v[188:191], v[212:215], v[32:47]
	ds_read_b128 v[208:211], v149 offset:9216
	ds_read_b128 v[212:215], v149 offset:13824
	s_waitcnt vmcnt(7)
	ds_write_b128 v148, v[194:197] offset:9216
	s_waitcnt vmcnt(6)
	ds_write_b128 v148, v[198:201] offset:46080
	ds_read_b128 v[194:197], v150 offset:32
	ds_read_b128 v[198:201], v150 offset:4640
	s_waitcnt lgkmcnt(5)
	v_mfma_f32_32x32x16_bf16 v[80:95], v[184:187], v[208:211], v[80:95]
	v_mfma_f32_32x32x16_bf16 v[16:31], v[188:191], v[208:211], v[16:31]
	ds_read_b128 v[208:211], v149 offset:32
	s_waitcnt lgkmcnt(5)
	v_mfma_f32_32x32x16_bf16 v[64:79], v[184:187], v[212:215], v[64:79]
	v_mfma_f32_32x32x16_bf16 v[0:15], v[188:191], v[212:215], v[0:15]
	ds_read_b128 v[212:215], v149 offset:4640
	s_setprio 0
	global_load_dwordx4 v[184:187], v[140:141], off offset:1664
	global_load_dwordx4 v[188:191], v[142:143], off offset:1664
	s_setprio 1
	s_waitcnt lgkmcnt(1)
	v_mfma_f32_32x32x16_bf16 v[112:127], v[194:197], v[208:211], v[112:127]
	v_mfma_f32_32x32x16_bf16 v[48:63], v[198:201], v[208:211], v[48:63]
	s_waitcnt lgkmcnt(0)
	v_mfma_f32_32x32x16_bf16 v[96:111], v[194:197], v[212:215], v[96:111]
	v_mfma_f32_32x32x16_bf16 v[32:47], v[198:201], v[212:215], v[32:47]
	ds_read_b128 v[208:211], v149 offset:9248
	ds_read_b128 v[212:215], v149 offset:13856
	s_waitcnt vmcnt(7)
	ds_write_b128 v148, v[176:179] offset:18432
	s_waitcnt vmcnt(6)
	ds_write_b128 v148, v[180:183] offset:55296
	ds_read_b128 v[176:179], v150 offset:64
	ds_read_b128 v[180:183], v150 offset:4672
	s_waitcnt lgkmcnt(5)
	v_mfma_f32_32x32x16_bf16 v[80:95], v[194:197], v[208:211], v[80:95]
	v_mfma_f32_32x32x16_bf16 v[16:31], v[198:201], v[208:211], v[16:31]
	ds_read_b128 v[208:211], v149 offset:64
	s_waitcnt lgkmcnt(5)
	v_mfma_f32_32x32x16_bf16 v[64:79], v[194:197], v[212:215], v[64:79]
	v_mfma_f32_32x32x16_bf16 v[0:15], v[198:201], v[212:215], v[0:15]
	ds_read_b128 v[212:215], v149 offset:4672
	s_setprio 0
	global_load_dwordx4 v[194:197], v[132:133], off offset:1664
	global_load_dwordx4 v[198:201], v[134:135], off offset:1664
	s_setprio 1
	s_waitcnt lgkmcnt(1)
	v_mfma_f32_32x32x16_bf16 v[112:127], v[176:179], v[208:211], v[112:127]
	v_mfma_f32_32x32x16_bf16 v[48:63], v[180:183], v[208:211], v[48:63]
	s_waitcnt lgkmcnt(0)
	v_mfma_f32_32x32x16_bf16 v[96:111], v[176:179], v[212:215], v[96:111]
	v_mfma_f32_32x32x16_bf16 v[32:47], v[180:183], v[212:215], v[32:47]
	ds_read_b128 v[208:211], v149 offset:9280
	ds_read_b128 v[212:215], v149 offset:13888
	s_waitcnt vmcnt(7)
	ds_write_b128 v148, v[168:171] offset:27648
	s_waitcnt vmcnt(6)
	ds_write_b128 v148, v[172:175] offset:64512
	ds_read_b128 v[168:171], v150 offset:96
	ds_read_b128 v[172:175], v150 offset:4704
	s_waitcnt lgkmcnt(5)
	v_mfma_f32_32x32x16_bf16 v[80:95], v[176:179], v[208:211], v[80:95]
	v_mfma_f32_32x32x16_bf16 v[16:31], v[180:183], v[208:211], v[16:31]
	ds_read_b128 v[208:211], v149 offset:96
	s_waitcnt lgkmcnt(5)
	v_mfma_f32_32x32x16_bf16 v[64:79], v[176:179], v[212:215], v[64:79]
	v_mfma_f32_32x32x16_bf16 v[0:15], v[180:183], v[212:215], v[0:15]
	ds_read_b128 v[212:215], v149 offset:4704
	s_setprio 0
	global_load_dwordx4 v[176:179], v[144:145], off offset:1664
	global_load_dwordx4 v[180:183], v[146:147], off offset:1664
	s_setprio 1
	s_waitcnt lgkmcnt(1)
	v_mfma_f32_32x32x16_bf16 v[112:127], v[168:171], v[208:211], v[112:127]
	v_mfma_f32_32x32x16_bf16 v[48:63], v[172:175], v[208:211], v[48:63]
	s_waitcnt lgkmcnt(0)
	v_mfma_f32_32x32x16_bf16 v[96:111], v[168:171], v[212:215], v[96:111]
	v_mfma_f32_32x32x16_bf16 v[32:47], v[172:175], v[212:215], v[32:47]
	ds_read_b128 v[208:211], v149 offset:9312
	ds_read_b128 v[212:215], v149 offset:13920
	s_waitcnt lgkmcnt(0)
	s_barrier
; template <bool trans>
; DI void gemm_core(const GTile& tl, const GTile& nx, bool has_next  , bool chain  , bool pre, u32x4 (&ra)[4], u32x4 (&rb)[4], char* smem, f32x16 (&acc)[2][4]) {
;     ...
;   const int nk = K / 64;
;   if (!pre) { G_LOAD(0); G_STORE(0); G_LOAD(1); }
;   for (int kt = 0; kt < nk; ++kt) {
;     __syncthreads();
;     G_COMPUTE(kt & 1, kt);
;   }
	s_waitcnt vmcnt(7)
	ds_write_b128 v192, v[160:163]
	s_waitcnt vmcnt(6)
	ds_write_b128 v159, v[164:167]
	ds_read_b128 v[160:163], v152 offset:36864
	ds_read_b128 v[164:167], v152 offset:41472
	v_mfma_f32_32x32x16_bf16 v[80:95], v[168:171], v[208:211], v[80:95]
	v_mfma_f32_32x32x16_bf16 v[16:31], v[172:175], v[208:211], v[16:31]
	ds_read_b128 v[208:211], v151
	v_mfma_f32_32x32x16_bf16 v[64:79], v[168:171], v[212:215], v[64:79]
	v_mfma_f32_32x32x16_bf16 v[0:15], v[172:175], v[212:215], v[0:15]
	ds_read_b128 v[212:215], v151 offset:4608
	s_setprio 0
	global_load_dwordx4 v[168:171], v[136:137], off offset:1792
	global_load_dwordx4 v[172:175], v[138:139], off offset:1792
	s_setprio 1
	s_waitcnt lgkmcnt(1)
	v_mfma_f32_32x32x16_bf16 v[112:127], v[160:163], v[208:211], v[112:127]
	v_mfma_f32_32x32x16_bf16 v[48:63], v[164:167], v[208:211], v[48:63]
	s_waitcnt lgkmcnt(0)
	v_mfma_f32_32x32x16_bf16 v[96:111], v[160:163], v[212:215], v[96:111]
	v_mfma_f32_32x32x16_bf16 v[32:47], v[164:167], v[212:215], v[32:47]
	ds_read_b128 v[208:211], v151 offset:9216
	ds_read_b128 v[212:215], v151 offset:13824
	s_waitcnt vmcnt(7)
	ds_write_b128 v158, v[184:187]
	s_waitcnt vmcnt(6)
	ds_write_b128 v157, v[188:191]
	ds_read_b128 v[184:187], v152 offset:36896
	ds_read_b128 v[188:191], v152 offset:41504
	s_waitcnt lgkmcnt(5)
	v_mfma_f32_32x32x16_bf16 v[80:95], v[160:163], v[208:211], v[80:95]
	v_mfma_f32_32x32x16_bf16 v[16:31], v[164:167], v[208:211], v[16:31]
	ds_read_b128 v[208:211], v151 offset:32
	s_waitcnt lgkmcnt(5)
	v_mfma_f32_32x32x16_bf16 v[64:79], v[160:163], v[212:215], v[64:79]
	v_mfma_f32_32x32x16_bf16 v[0:15], v[164:167], v[212:215], v[0:15]
	ds_read_b128 v[212:215], v151 offset:4640
	s_setprio 0
	global_load_dwordx4 v[160:163], v[140:141], off offset:1792
	global_load_dwordx4 v[164:167], v[142:143], off offset:1792
	s_setprio 1
	s_waitcnt lgkmcnt(1)
	v_mfma_f32_32x32x16_bf16 v[112:127], v[184:187], v[208:211], v[112:127]
	v_mfma_f32_32x32x16_bf16 v[48:63], v[188:191], v[208:211], v[48:63]
	s_waitcnt lgkmcnt(0)
	v_mfma_f32_32x32x16_bf16 v[96:111], v[184:187], v[212:215], v[96:111]
	v_mfma_f32_32x32x16_bf16 v[32:47], v[188:191], v[212:215], v[32:47]
	ds_read_b128 v[208:211], v151 offset:9248
	ds_read_b128 v[212:215], v151 offset:13856
	s_waitcnt vmcnt(7)
	ds_write_b128 v154, v[194:197]
	s_waitcnt vmcnt(6)
	ds_write_b128 v153, v[198:201]
	ds_read_b128 v[194:197], v152 offset:36928
	ds_read_b128 v[198:201], v152 offset:41536
	s_waitcnt lgkmcnt(5)
	v_mfma_f32_32x32x16_bf16 v[80:95], v[184:187], v[208:211], v[80:95]
	v_mfma_f32_32x32x16_bf16 v[16:31], v[188:191], v[208:211], v[16:31]
	ds_read_b128 v[208:211], v151 offset:64
	s_waitcnt lgkmcnt(5)
	v_mfma_f32_32x32x16_bf16 v[64:79], v[184:187], v[212:215], v[64:79]
	v_mfma_f32_32x32x16_bf16 v[0:15], v[188:191], v[212:215], v[0:15]
	ds_read_b128 v[212:215], v151 offset:4672
	s_setprio 0
	global_load_dwordx4 v[184:187], v[132:133], off offset:1792
	global_load_dwordx4 v[188:191], v[134:135], off offset:1792
	s_setprio 1
	s_waitcnt lgkmcnt(1)
	v_mfma_f32_32x32x16_bf16 v[112:127], v[194:197], v[208:211], v[112:127]
	v_mfma_f32_32x32x16_bf16 v[48:63], v[198:201], v[208:211], v[48:63]
	s_waitcnt lgkmcnt(0)
	v_mfma_f32_32x32x16_bf16 v[96:111], v[194:197], v[212:215], v[96:111]
	v_mfma_f32_32x32x16_bf16 v[32:47], v[198:201], v[212:215], v[32:47]
	ds_read_b128 v[208:211], v151 offset:9280
	ds_read_b128 v[212:215], v151 offset:13888
	s_waitcnt vmcnt(7)
	ds_write_b128 v156, v[176:179]
	s_waitcnt vmcnt(6)
	ds_write_b128 v155, v[180:183]
	ds_read_b128 v[176:179], v152 offset:36960
	ds_read_b128 v[180:183], v152 offset:41568
	s_waitcnt lgkmcnt(5)
	v_mfma_f32_32x32x16_bf16 v[80:95], v[194:197], v[208:211], v[80:95]
	v_mfma_f32_32x32x16_bf16 v[16:31], v[198:201], v[208:211], v[16:31]
	ds_read_b128 v[208:211], v151 offset:96
	s_waitcnt lgkmcnt(5)
	v_mfma_f32_32x32x16_bf16 v[64:79], v[194:197], v[212:215], v[64:79]
	v_mfma_f32_32x32x16_bf16 v[0:15], v[198:201], v[212:215], v[0:15]
	ds_read_b128 v[212:215], v151 offset:4704
	s_setprio 0
	global_load_dwordx4 v[194:197], v[144:145], off offset:1792
	global_load_dwordx4 v[198:201], v[146:147], off offset:1792
	s_setprio 1
	s_waitcnt lgkmcnt(1)
	v_mfma_f32_32x32x16_bf16 v[112:127], v[176:179], v[208:211], v[112:127]
	v_mfma_f32_32x32x16_bf16 v[48:63], v[180:183], v[208:211], v[48:63]
	s_waitcnt lgkmcnt(0)
	v_mfma_f32_32x32x16_bf16 v[96:111], v[176:179], v[212:215], v[96:111]
	v_mfma_f32_32x32x16_bf16 v[32:47], v[180:183], v[212:215], v[32:47]
	ds_read_b128 v[208:211], v151 offset:9312
	ds_read_b128 v[212:215], v151 offset:13920
	s_waitcnt lgkmcnt(0)
	s_barrier
; template <bool trans>
; DI void gemm_core(const GTile& tl, const GTile& nx, bool has_next  , bool chain  , bool pre, u32x4 (&ra)[4], u32x4 (&rb)[4], char* smem, f32x16 (&acc)[2][4]) {
;     ...
;   const int nk = K / 64;
;   if (!pre) { G_LOAD(0); G_STORE(0); G_LOAD(1); }
;   for (int kt = 0; kt < nk; ++kt) {
;     __syncthreads();
;     G_COMPUTE(kt & 1, kt);
;   }
	s_waitcnt vmcnt(7)
	ds_write_b128 v148, v[168:171]
	s_waitcnt vmcnt(6)
	ds_write_b128 v148, v[172:175] offset:36864
	ds_read_b128 v[168:171], v150
	ds_read_b128 v[172:175], v150 offset:4608
	v_mfma_f32_32x32x16_bf16 v[80:95], v[176:179], v[208:211], v[80:95]
	v_mfma_f32_32x32x16_bf16 v[16:31], v[180:183], v[208:211], v[16:31]
	ds_read_b128 v[208:211], v149
	v_mfma_f32_32x32x16_bf16 v[64:79], v[176:179], v[212:215], v[64:79]
	v_mfma_f32_32x32x16_bf16 v[0:15], v[180:183], v[212:215], v[0:15]
	ds_read_b128 v[212:215], v149 offset:4608
	s_setprio 0
	global_load_dwordx4 v[176:179], v[136:137], off offset:1920
	global_load_dwordx4 v[180:183], v[138:139], off offset:1920
	s_setprio 1
	s_waitcnt lgkmcnt(1)
	v_mfma_f32_32x32x16_bf16 v[112:127], v[168:171], v[208:211], v[112:127]
	v_mfma_f32_32x32x16_bf16 v[48:63], v[172:175], v[208:211], v[48:63]
	s_waitcnt lgkmcnt(0)
	v_mfma_f32_32x32x16_bf16 v[96:111], v[168:171], v[212:215], v[96:111]
	v_mfma_f32_32x32x16_bf16 v[32:47], v[172:175], v[212:215], v[32:47]
	ds_read_b128 v[208:211], v149 offset:9216
	ds_read_b128 v[212:215], v149 offset:13824
	s_waitcnt vmcnt(7)
	ds_write_b128 v148, v[160:163] offset:9216
	s_waitcnt vmcnt(6)
	ds_write_b128 v148, v[164:167] offset:46080
	ds_read_b128 v[160:163], v150 offset:32
	ds_read_b128 v[164:167], v150 offset:4640
	s_waitcnt lgkmcnt(5)
	v_mfma_f32_32x32x16_bf16 v[80:95], v[168:171], v[208:211], v[80:95]
	v_mfma_f32_32x32x16_bf16 v[16:31], v[172:175], v[208:211], v[16:31]
	ds_read_b128 v[208:211], v149 offset:32
	s_waitcnt lgkmcnt(5)
	v_mfma_f32_32x32x16_bf16 v[64:79], v[168:171], v[212:215], v[64:79]
	v_mfma_f32_32x32x16_bf16 v[0:15], v[172:175], v[212:215], v[0:15]
	ds_read_b128 v[212:215], v149 offset:4640
	s_setprio 0
	global_load_dwordx4 v[168:171], v[140:141], off offset:1920
	global_load_dwordx4 v[172:175], v[142:143], off offset:1920
	s_setprio 1
	s_waitcnt lgkmcnt(1)
	v_mfma_f32_32x32x16_bf16 v[112:127], v[160:163], v[208:211], v[112:127]
	v_mfma_f32_32x32x16_bf16 v[48:63], v[164:167], v[208:211], v[48:63]
	s_waitcnt lgkmcnt(0)
	v_mfma_f32_32x32x16_bf16 v[96:111], v[160:163], v[212:215], v[96:111]
	v_mfma_f32_32x32x16_bf16 v[32:47], v[164:167], v[212:215], v[32:47]
	ds_read_b128 v[208:211], v149 offset:9248
	ds_read_b128 v[212:215], v149 offset:13856
	s_waitcnt vmcnt(7)
	ds_write_b128 v148, v[184:187] offset:18432
	s_waitcnt vmcnt(6)
	ds_write_b128 v148, v[188:191] offset:55296
	ds_read_b128 v[184:187], v150 offset:64
	ds_read_b128 v[188:191], v150 offset:4672
	s_waitcnt lgkmcnt(5)
	v_mfma_f32_32x32x16_bf16 v[80:95], v[160:163], v[208:211], v[80:95]
	v_mfma_f32_32x32x16_bf16 v[16:31], v[164:167], v[208:211], v[16:31]
	ds_read_b128 v[208:211], v149 offset:64
	s_waitcnt lgkmcnt(5)
	v_mfma_f32_32x32x16_bf16 v[64:79], v[160:163], v[212:215], v[64:79]
	v_mfma_f32_32x32x16_bf16 v[0:15], v[164:167], v[212:215], v[0:15]
	ds_read_b128 v[212:215], v149 offset:4672
	s_setprio 0
	global_load_dwordx4 v[160:163], v[132:133], off offset:1920
	global_load_dwordx4 v[164:167], v[134:135], off offset:1920
	s_setprio 1
	s_waitcnt lgkmcnt(1)
	v_mfma_f32_32x32x16_bf16 v[112:127], v[184:187], v[208:211], v[112:127]
	v_mfma_f32_32x32x16_bf16 v[48:63], v[188:191], v[208:211], v[48:63]
	s_waitcnt lgkmcnt(0)
	v_mfma_f32_32x32x16_bf16 v[96:111], v[184:187], v[212:215], v[96:111]
	v_mfma_f32_32x32x16_bf16 v[32:47], v[188:191], v[212:215], v[32:47]
	ds_read_b128 v[208:211], v149 offset:9280
	ds_read_b128 v[212:215], v149 offset:13888
	s_waitcnt vmcnt(7)
	ds_write_b128 v148, v[194:197] offset:27648
	s_waitcnt vmcnt(6)
	ds_write_b128 v148, v[198:201] offset:64512
	ds_read_b128 v[194:197], v150 offset:96
	ds_read_b128 v[198:201], v150 offset:4704
	s_waitcnt lgkmcnt(5)
	v_mfma_f32_32x32x16_bf16 v[80:95], v[184:187], v[208:211], v[80:95]
	v_mfma_f32_32x32x16_bf16 v[16:31], v[188:191], v[208:211], v[16:31]
	ds_read_b128 v[208:211], v149 offset:96
	s_waitcnt lgkmcnt(5)
	v_mfma_f32_32x32x16_bf16 v[64:79], v[184:187], v[212:215], v[64:79]
	v_mfma_f32_32x32x16_bf16 v[0:15], v[188:191], v[212:215], v[0:15]
	ds_read_b128 v[212:215], v149 offset:4704
	s_setprio 0
	global_load_dwordx4 v[184:187], v[144:145], off offset:1920
	global_load_dwordx4 v[188:191], v[146:147], off offset:1920
	s_setprio 1
	s_waitcnt lgkmcnt(1)
	v_mfma_f32_32x32x16_bf16 v[112:127], v[194:197], v[208:211], v[112:127]
	v_mfma_f32_32x32x16_bf16 v[48:63], v[198:201], v[208:211], v[48:63]
	s_waitcnt lgkmcnt(0)
	v_mfma_f32_32x32x16_bf16 v[96:111], v[194:197], v[212:215], v[96:111]
	v_mfma_f32_32x32x16_bf16 v[32:47], v[198:201], v[212:215], v[32:47]
	ds_read_b128 v[208:211], v149 offset:9312
	ds_read_b128 v[212:215], v149 offset:13920
	s_waitcnt lgkmcnt(0)
	s_barrier
; template <bool trans>
; DI void gemm_core(const GTile& tl, const GTile& nx, bool has_next  , bool chain  , bool pre, u32x4 (&ra)[4], u32x4 (&rb)[4], char* smem, f32x16 (&acc)[2][4]) {
;     ...
;   const int nk = K / 64;
;   if (!pre) { G_LOAD(0); G_STORE(0); G_LOAD(1); }
;   for (int kt = 0; kt < nk; ++kt) {
;     __syncthreads();
;     G_COMPUTE(kt & 1, kt);
;   }
	s_waitcnt vmcnt(7)
	ds_write_b128 v192, v[176:179]
	s_waitcnt vmcnt(6)
	ds_write_b128 v159, v[180:183]
	ds_read_b128 v[176:179], v152 offset:36864
	ds_read_b128 v[180:183], v152 offset:41472
	v_mfma_f32_32x32x16_bf16 v[80:95], v[194:197], v[208:211], v[80:95]
	v_mfma_f32_32x32x16_bf16 v[16:31], v[198:201], v[208:211], v[16:31]
	ds_read_b128 v[208:211], v151
	v_mfma_f32_32x32x16_bf16 v[64:79], v[194:197], v[212:215], v[64:79]
	v_mfma_f32_32x32x16_bf16 v[0:15], v[198:201], v[212:215], v[0:15]
	ds_read_b128 v[212:215], v151 offset:4608
	s_setprio 0
	global_load_dwordx4 v[194:197], v[136:137], off offset:2048
	global_load_dwordx4 v[198:201], v[138:139], off offset:2048
	s_setprio 1
	s_waitcnt lgkmcnt(1)
	v_mfma_f32_32x32x16_bf16 v[112:127], v[176:179], v[208:211], v[112:127]
	v_mfma_f32_32x32x16_bf16 v[48:63], v[180:183], v[208:211], v[48:63]
	s_waitcnt lgkmcnt(0)
	v_mfma_f32_32x32x16_bf16 v[96:111], v[176:179], v[212:215], v[96:111]
	v_mfma_f32_32x32x16_bf16 v[32:47], v[180:183], v[212:215], v[32:47]
	ds_read_b128 v[208:211], v151 offset:9216
	ds_read_b128 v[212:215], v151 offset:13824
	s_waitcnt vmcnt(7)
	ds_write_b128 v158, v[168:171]
	s_waitcnt vmcnt(6)
	ds_write_b128 v157, v[172:175]
	ds_read_b128 v[168:171], v152 offset:36896
	ds_read_b128 v[172:175], v152 offset:41504
	s_waitcnt lgkmcnt(5)
	v_mfma_f32_32x32x16_bf16 v[80:95], v[176:179], v[208:211], v[80:95]
	v_mfma_f32_32x32x16_bf16 v[16:31], v[180:183], v[208:211], v[16:31]
	ds_read_b128 v[208:211], v151 offset:32
	s_waitcnt lgkmcnt(5)
	v_mfma_f32_32x32x16_bf16 v[64:79], v[176:179], v[212:215], v[64:79]
	v_mfma_f32_32x32x16_bf16 v[0:15], v[180:183], v[212:215], v[0:15]
	ds_read_b128 v[212:215], v151 offset:4640
	s_setprio 0
	global_load_dwordx4 v[176:179], v[140:141], off offset:2048
	global_load_dwordx4 v[180:183], v[142:143], off offset:2048
	s_setprio 1
	s_waitcnt lgkmcnt(1)
	v_mfma_f32_32x32x16_bf16 v[112:127], v[168:171], v[208:211], v[112:127]
	v_mfma_f32_32x32x16_bf16 v[48:63], v[172:175], v[208:211], v[48:63]
	s_waitcnt lgkmcnt(0)
	v_mfma_f32_32x32x16_bf16 v[96:111], v[168:171], v[212:215], v[96:111]
	v_mfma_f32_32x32x16_bf16 v[32:47], v[172:175], v[212:215], v[32:47]
	ds_read_b128 v[208:211], v151 offset:9248
	ds_read_b128 v[212:215], v151 offset:13856
	s_waitcnt vmcnt(7)
	ds_write_b128 v154, v[160:163]
	s_waitcnt vmcnt(6)
	ds_write_b128 v153, v[164:167]
	ds_read_b128 v[160:163], v152 offset:36928
	ds_read_b128 v[164:167], v152 offset:41536
	s_waitcnt lgkmcnt(5)
	v_mfma_f32_32x32x16_bf16 v[80:95], v[168:171], v[208:211], v[80:95]
	v_mfma_f32_32x32x16_bf16 v[16:31], v[172:175], v[208:211], v[16:31]
	ds_read_b128 v[208:211], v151 offset:64
	s_waitcnt lgkmcnt(5)
	v_mfma_f32_32x32x16_bf16 v[64:79], v[168:171], v[212:215], v[64:79]
	v_mfma_f32_32x32x16_bf16 v[0:15], v[172:175], v[212:215], v[0:15]
	ds_read_b128 v[212:215], v151 offset:4672
	s_setprio 0
	global_load_dwordx4 v[168:171], v[132:133], off offset:2048
	global_load_dwordx4 v[172:175], v[134:135], off offset:2048
	s_setprio 1
	s_waitcnt lgkmcnt(1)
	v_mfma_f32_32x32x16_bf16 v[112:127], v[160:163], v[208:211], v[112:127]
	v_mfma_f32_32x32x16_bf16 v[48:63], v[164:167], v[208:211], v[48:63]
	s_waitcnt lgkmcnt(0)
	v_mfma_f32_32x32x16_bf16 v[96:111], v[160:163], v[212:215], v[96:111]
	v_mfma_f32_32x32x16_bf16 v[32:47], v[164:167], v[212:215], v[32:47]
	ds_read_b128 v[208:211], v151 offset:9280
	ds_read_b128 v[212:215], v151 offset:13888
	s_waitcnt vmcnt(7)
	ds_write_b128 v156, v[184:187]
	s_waitcnt vmcnt(6)
	ds_write_b128 v155, v[188:191]
	ds_read_b128 v[184:187], v152 offset:36960
	ds_read_b128 v[188:191], v152 offset:41568
	s_waitcnt lgkmcnt(5)
	v_mfma_f32_32x32x16_bf16 v[80:95], v[160:163], v[208:211], v[80:95]
	v_mfma_f32_32x32x16_bf16 v[16:31], v[164:167], v[208:211], v[16:31]
	ds_read_b128 v[208:211], v151 offset:96
	s_waitcnt lgkmcnt(5)
	v_mfma_f32_32x32x16_bf16 v[64:79], v[160:163], v[212:215], v[64:79]
	v_mfma_f32_32x32x16_bf16 v[0:15], v[164:167], v[212:215], v[0:15]
	ds_read_b128 v[212:215], v151 offset:4704
	s_setprio 0
	global_load_dwordx4 v[160:163], v[144:145], off offset:2048
	global_load_dwordx4 v[164:167], v[146:147], off offset:2048
	s_setprio 1
	s_waitcnt lgkmcnt(1)
	v_mfma_f32_32x32x16_bf16 v[112:127], v[184:187], v[208:211], v[112:127]
	v_mfma_f32_32x32x16_bf16 v[48:63], v[188:191], v[208:211], v[48:63]
	s_waitcnt lgkmcnt(0)
	v_mfma_f32_32x32x16_bf16 v[96:111], v[184:187], v[212:215], v[96:111]
	v_mfma_f32_32x32x16_bf16 v[32:47], v[188:191], v[212:215], v[32:47]
	ds_read_b128 v[208:211], v151 offset:9312
	ds_read_b128 v[212:215], v151 offset:13920
	s_waitcnt lgkmcnt(0)
	s_barrier
; template <bool trans>
; DI void gemm_core(const GTile& tl, const GTile& nx, bool has_next  , bool chain  , bool pre, u32x4 (&ra)[4], u32x4 (&rb)[4], char* smem, f32x16 (&acc)[2][4]) {
;     ...
;   const int nk = K / 64;
;   if (!pre) { G_LOAD(0); G_STORE(0); G_LOAD(1); }
;   for (int kt = 0; kt < nk; ++kt) {
;     __syncthreads();
;     G_COMPUTE(kt & 1, kt);
;   }
	s_waitcnt vmcnt(7)
	ds_write_b128 v148, v[194:197]
	s_waitcnt vmcnt(6)
	ds_write_b128 v148, v[198:201] offset:36864
	ds_read_b128 v[194:197], v150
	ds_read_b128 v[198:201], v150 offset:4608
	v_mfma_f32_32x32x16_bf16 v[80:95], v[184:187], v[208:211], v[80:95]
	v_mfma_f32_32x32x16_bf16 v[16:31], v[188:191], v[208:211], v[16:31]
	ds_read_b128 v[208:211], v149
	v_mfma_f32_32x32x16_bf16 v[64:79], v[184:187], v[212:215], v[64:79]
	v_mfma_f32_32x32x16_bf16 v[0:15], v[188:191], v[212:215], v[0:15]
	ds_read_b128 v[212:215], v149 offset:4608
	s_setprio 0
	global_load_dwordx4 v[184:187], v[136:137], off offset:2176
	global_load_dwordx4 v[188:191], v[138:139], off offset:2176
	s_setprio 1
	s_waitcnt lgkmcnt(1)
	v_mfma_f32_32x32x16_bf16 v[112:127], v[194:197], v[208:211], v[112:127]
	v_mfma_f32_32x32x16_bf16 v[48:63], v[198:201], v[208:211], v[48:63]
	s_waitcnt lgkmcnt(0)
	v_mfma_f32_32x32x16_bf16 v[96:111], v[194:197], v[212:215], v[96:111]
	v_mfma_f32_32x32x16_bf16 v[32:47], v[198:201], v[212:215], v[32:47]
	ds_read_b128 v[208:211], v149 offset:9216
	ds_read_b128 v[212:215], v149 offset:13824
	s_waitcnt vmcnt(7)
	ds_write_b128 v148, v[176:179] offset:9216
	s_waitcnt vmcnt(6)
	ds_write_b128 v148, v[180:183] offset:46080
	ds_read_b128 v[176:179], v150 offset:32
	ds_read_b128 v[180:183], v150 offset:4640
	s_waitcnt lgkmcnt(5)
	v_mfma_f32_32x32x16_bf16 v[80:95], v[194:197], v[208:211], v[80:95]
	v_mfma_f32_32x32x16_bf16 v[16:31], v[198:201], v[208:211], v[16:31]
	ds_read_b128 v[208:211], v149 offset:32
	s_waitcnt lgkmcnt(5)
	v_mfma_f32_32x32x16_bf16 v[64:79], v[194:197], v[212:215], v[64:79]
	v_mfma_f32_32x32x16_bf16 v[0:15], v[198:201], v[212:215], v[0:15]
	ds_read_b128 v[212:215], v149 offset:4640
	s_setprio 0
	global_load_dwordx4 v[194:197], v[140:141], off offset:2176
	global_load_dwordx4 v[198:201], v[142:143], off offset:2176
	s_setprio 1
	s_waitcnt lgkmcnt(1)
	v_mfma_f32_32x32x16_bf16 v[112:127], v[176:179], v[208:211], v[112:127]
	v_mfma_f32_32x32x16_bf16 v[48:63], v[180:183], v[208:211], v[48:63]
	s_waitcnt lgkmcnt(0)
	v_mfma_f32_32x32x16_bf16 v[96:111], v[176:179], v[212:215], v[96:111]
	v_mfma_f32_32x32x16_bf16 v[32:47], v[180:183], v[212:215], v[32:47]
	ds_read_b128 v[208:211], v149 offset:9248
	ds_read_b128 v[212:215], v149 offset:13856
	s_waitcnt vmcnt(7)
	ds_write_b128 v148, v[168:171] offset:18432
	s_waitcnt vmcnt(6)
	ds_write_b128 v148, v[172:175] offset:55296
	ds_read_b128 v[168:171], v150 offset:64
	ds_read_b128 v[172:175], v150 offset:4672
	s_waitcnt lgkmcnt(5)
	v_mfma_f32_32x32x16_bf16 v[80:95], v[176:179], v[208:211], v[80:95]
	v_mfma_f32_32x32x16_bf16 v[16:31], v[180:183], v[208:211], v[16:31]
	ds_read_b128 v[208:211], v149 offset:64
	s_waitcnt lgkmcnt(5)
	v_mfma_f32_32x32x16_bf16 v[64:79], v[176:179], v[212:215], v[64:79]
	v_mfma_f32_32x32x16_bf16 v[0:15], v[180:183], v[212:215], v[0:15]
	ds_read_b128 v[212:215], v149 offset:4672
	s_setprio 0
	global_load_dwordx4 v[176:179], v[132:133], off offset:2176
	global_load_dwordx4 v[180:183], v[134:135], off offset:2176
	s_setprio 1
	s_waitcnt lgkmcnt(1)
	v_mfma_f32_32x32x16_bf16 v[112:127], v[168:171], v[208:211], v[112:127]
	v_mfma_f32_32x32x16_bf16 v[48:63], v[172:175], v[208:211], v[48:63]
	s_waitcnt lgkmcnt(0)
	v_mfma_f32_32x32x16_bf16 v[96:111], v[168:171], v[212:215], v[96:111]
	v_mfma_f32_32x32x16_bf16 v[32:47], v[172:175], v[212:215], v[32:47]
	ds_read_b128 v[208:211], v149 offset:9280
	ds_read_b128 v[212:215], v149 offset:13888
	s_waitcnt vmcnt(7)
	ds_write_b128 v148, v[160:163] offset:27648
	s_waitcnt vmcnt(6)
	ds_write_b128 v148, v[164:167] offset:64512
	ds_read_b128 v[160:163], v150 offset:96
	ds_read_b128 v[164:167], v150 offset:4704
	s_waitcnt lgkmcnt(5)
	v_mfma_f32_32x32x16_bf16 v[80:95], v[168:171], v[208:211], v[80:95]
	v_mfma_f32_32x32x16_bf16 v[16:31], v[172:175], v[208:211], v[16:31]
	ds_read_b128 v[208:211], v149 offset:96
	s_waitcnt lgkmcnt(5)
	v_mfma_f32_32x32x16_bf16 v[64:79], v[168:171], v[212:215], v[64:79]
	v_mfma_f32_32x32x16_bf16 v[0:15], v[172:175], v[212:215], v[0:15]
	ds_read_b128 v[212:215], v149 offset:4704
	s_setprio 0
	global_load_dwordx4 v[168:171], v[144:145], off offset:2176
	global_load_dwordx4 v[172:175], v[146:147], off offset:2176
	s_setprio 1
	s_waitcnt lgkmcnt(1)
	v_mfma_f32_32x32x16_bf16 v[112:127], v[160:163], v[208:211], v[112:127]
	v_mfma_f32_32x32x16_bf16 v[48:63], v[164:167], v[208:211], v[48:63]
	s_waitcnt lgkmcnt(0)
	v_mfma_f32_32x32x16_bf16 v[96:111], v[160:163], v[212:215], v[96:111]
	v_mfma_f32_32x32x16_bf16 v[32:47], v[164:167], v[212:215], v[32:47]
	ds_read_b128 v[208:211], v149 offset:9312
	ds_read_b128 v[212:215], v149 offset:13920
	s_waitcnt lgkmcnt(0)
	s_barrier
; template <bool trans>
; DI void gemm_core(const GTile& tl, const GTile& nx, bool has_next  , bool chain  , bool pre, u32x4 (&ra)[4], u32x4 (&rb)[4], char* smem, f32x16 (&acc)[2][4]) {
;     ...
;   const int nk = K / 64;
;   if (!pre) { G_LOAD(0); G_STORE(0); G_LOAD(1); }
;   for (int kt = 0; kt < nk; ++kt) {
;     __syncthreads();
;     G_COMPUTE(kt & 1, kt);
;   }
	s_waitcnt vmcnt(7)
	ds_write_b128 v192, v[184:187]
	s_waitcnt vmcnt(6)
	ds_write_b128 v159, v[188:191]
	ds_read_b128 v[184:187], v152 offset:36864
	ds_read_b128 v[188:191], v152 offset:41472
	v_mfma_f32_32x32x16_bf16 v[80:95], v[160:163], v[208:211], v[80:95]
	v_mfma_f32_32x32x16_bf16 v[16:31], v[164:167], v[208:211], v[16:31]
	ds_read_b128 v[208:211], v151
	v_mfma_f32_32x32x16_bf16 v[64:79], v[160:163], v[212:215], v[64:79]
	v_mfma_f32_32x32x16_bf16 v[0:15], v[164:167], v[212:215], v[0:15]
	ds_read_b128 v[212:215], v151 offset:4608
	s_setprio 0
	global_load_dwordx4 v[160:163], v[136:137], off offset:2304
	global_load_dwordx4 v[164:167], v[138:139], off offset:2304
	s_setprio 1
	s_waitcnt lgkmcnt(1)
	v_mfma_f32_32x32x16_bf16 v[112:127], v[184:187], v[208:211], v[112:127]
	v_mfma_f32_32x32x16_bf16 v[48:63], v[188:191], v[208:211], v[48:63]
	s_waitcnt lgkmcnt(0)
	v_mfma_f32_32x32x16_bf16 v[96:111], v[184:187], v[212:215], v[96:111]
	v_mfma_f32_32x32x16_bf16 v[32:47], v[188:191], v[212:215], v[32:47]
	ds_read_b128 v[208:211], v151 offset:9216
	ds_read_b128 v[212:215], v151 offset:13824
	s_waitcnt vmcnt(7)
	ds_write_b128 v158, v[194:197]
	s_waitcnt vmcnt(6)
	ds_write_b128 v157, v[198:201]
	ds_read_b128 v[194:197], v152 offset:36896
	ds_read_b128 v[198:201], v152 offset:41504
	s_waitcnt lgkmcnt(5)
	v_mfma_f32_32x32x16_bf16 v[80:95], v[184:187], v[208:211], v[80:95]
	v_mfma_f32_32x32x16_bf16 v[16:31], v[188:191], v[208:211], v[16:31]
	ds_read_b128 v[208:211], v151 offset:32
	s_waitcnt lgkmcnt(5)
	v_mfma_f32_32x32x16_bf16 v[64:79], v[184:187], v[212:215], v[64:79]
	v_mfma_f32_32x32x16_bf16 v[0:15], v[188:191], v[212:215], v[0:15]
	ds_read_b128 v[212:215], v151 offset:4640
	s_setprio 0
	global_load_dwordx4 v[184:187], v[140:141], off offset:2304
	global_load_dwordx4 v[188:191], v[142:143], off offset:2304
	s_setprio 1
	s_waitcnt lgkmcnt(1)
	v_mfma_f32_32x32x16_bf16 v[112:127], v[194:197], v[208:211], v[112:127]
	v_mfma_f32_32x32x16_bf16 v[48:63], v[198:201], v[208:211], v[48:63]
	s_waitcnt lgkmcnt(0)
	v_mfma_f32_32x32x16_bf16 v[96:111], v[194:197], v[212:215], v[96:111]
	v_mfma_f32_32x32x16_bf16 v[32:47], v[198:201], v[212:215], v[32:47]
	ds_read_b128 v[208:211], v151 offset:9248
	ds_read_b128 v[212:215], v151 offset:13856
	s_waitcnt vmcnt(7)
	ds_write_b128 v154, v[176:179]
	s_waitcnt vmcnt(6)
	ds_write_b128 v153, v[180:183]
	ds_read_b128 v[176:179], v152 offset:36928
	ds_read_b128 v[180:183], v152 offset:41536
	s_waitcnt lgkmcnt(5)
	v_mfma_f32_32x32x16_bf16 v[80:95], v[194:197], v[208:211], v[80:95]
	v_mfma_f32_32x32x16_bf16 v[16:31], v[198:201], v[208:211], v[16:31]
	ds_read_b128 v[208:211], v151 offset:64
	s_waitcnt lgkmcnt(5)
	v_mfma_f32_32x32x16_bf16 v[64:79], v[194:197], v[212:215], v[64:79]
	v_mfma_f32_32x32x16_bf16 v[0:15], v[198:201], v[212:215], v[0:15]
	ds_read_b128 v[212:215], v151 offset:4672
	s_setprio 0
	global_load_dwordx4 v[194:197], v[132:133], off offset:2304
	global_load_dwordx4 v[198:201], v[134:135], off offset:2304
	s_setprio 1
	s_waitcnt lgkmcnt(1)
	v_mfma_f32_32x32x16_bf16 v[112:127], v[176:179], v[208:211], v[112:127]
	v_mfma_f32_32x32x16_bf16 v[48:63], v[180:183], v[208:211], v[48:63]
	s_waitcnt lgkmcnt(0)
	v_mfma_f32_32x32x16_bf16 v[96:111], v[176:179], v[212:215], v[96:111]
	v_mfma_f32_32x32x16_bf16 v[32:47], v[180:183], v[212:215], v[32:47]
	ds_read_b128 v[208:211], v151 offset:9280
	ds_read_b128 v[212:215], v151 offset:13888
	s_waitcnt vmcnt(7)
	ds_write_b128 v156, v[168:171]
	s_waitcnt vmcnt(6)
	ds_write_b128 v155, v[172:175]
	ds_read_b128 v[168:171], v152 offset:36960
	ds_read_b128 v[172:175], v152 offset:41568
	s_waitcnt lgkmcnt(5)
	v_mfma_f32_32x32x16_bf16 v[80:95], v[176:179], v[208:211], v[80:95]
	v_mfma_f32_32x32x16_bf16 v[16:31], v[180:183], v[208:211], v[16:31]
	ds_read_b128 v[208:211], v151 offset:96
	s_waitcnt lgkmcnt(5)
	v_mfma_f32_32x32x16_bf16 v[64:79], v[176:179], v[212:215], v[64:79]
	v_mfma_f32_32x32x16_bf16 v[0:15], v[180:183], v[212:215], v[0:15]
	ds_read_b128 v[212:215], v151 offset:4704
	s_setprio 0
	global_load_dwordx4 v[176:179], v[144:145], off offset:2304
	global_load_dwordx4 v[180:183], v[146:147], off offset:2304
	s_setprio 1
	s_waitcnt lgkmcnt(1)
	v_mfma_f32_32x32x16_bf16 v[112:127], v[168:171], v[208:211], v[112:127]
	v_mfma_f32_32x32x16_bf16 v[48:63], v[172:175], v[208:211], v[48:63]
	s_waitcnt lgkmcnt(0)
	v_mfma_f32_32x32x16_bf16 v[96:111], v[168:171], v[212:215], v[96:111]
	v_mfma_f32_32x32x16_bf16 v[32:47], v[172:175], v[212:215], v[32:47]
	ds_read_b128 v[208:211], v151 offset:9312
	ds_read_b128 v[212:215], v151 offset:13920
	s_waitcnt lgkmcnt(0)
	s_barrier
; template <bool trans>
; DI void gemm_core(const GTile& tl, const GTile& nx, bool has_next  , bool chain  , bool pre, u32x4 (&ra)[4], u32x4 (&rb)[4], char* smem, f32x16 (&acc)[2][4]) {
;     ...
;   const int nk = K / 64;
;   if (!pre) { G_LOAD(0); G_STORE(0); G_LOAD(1); }
;   for (int kt = 0; kt < nk; ++kt) {
;     __syncthreads();
;     G_COMPUTE(kt & 1, kt);
;   }
	s_waitcnt vmcnt(7)
	ds_write_b128 v148, v[160:163]
	s_waitcnt vmcnt(6)
	ds_write_b128 v148, v[164:167] offset:36864
	ds_read_b128 v[160:163], v150
	ds_read_b128 v[164:167], v150 offset:4608
	v_mfma_f32_32x32x16_bf16 v[80:95], v[168:171], v[208:211], v[80:95]
	v_mfma_f32_32x32x16_bf16 v[16:31], v[172:175], v[208:211], v[16:31]
	ds_read_b128 v[208:211], v149
	v_mfma_f32_32x32x16_bf16 v[64:79], v[168:171], v[212:215], v[64:79]
	v_mfma_f32_32x32x16_bf16 v[0:15], v[172:175], v[212:215], v[0:15]
	ds_read_b128 v[212:215], v149 offset:4608
	s_setprio 0
	global_load_dwordx4 v[168:171], v[136:137], off offset:2432
	global_load_dwordx4 v[172:175], v[138:139], off offset:2432
	s_setprio 1
	s_waitcnt lgkmcnt(1)
	v_mfma_f32_32x32x16_bf16 v[112:127], v[160:163], v[208:211], v[112:127]
	v_mfma_f32_32x32x16_bf16 v[48:63], v[164:167], v[208:211], v[48:63]
	s_waitcnt lgkmcnt(0)
	v_mfma_f32_32x32x16_bf16 v[96:111], v[160:163], v[212:215], v[96:111]
	v_mfma_f32_32x32x16_bf16 v[32:47], v[164:167], v[212:215], v[32:47]
	ds_read_b128 v[208:211], v149 offset:9216
	ds_read_b128 v[212:215], v149 offset:13824
	s_waitcnt vmcnt(7)
	ds_write_b128 v148, v[184:187] offset:9216
	s_waitcnt vmcnt(6)
	ds_write_b128 v148, v[188:191] offset:46080
	ds_read_b128 v[184:187], v150 offset:32
	ds_read_b128 v[188:191], v150 offset:4640
	s_waitcnt lgkmcnt(5)
	v_mfma_f32_32x32x16_bf16 v[80:95], v[160:163], v[208:211], v[80:95]
	v_mfma_f32_32x32x16_bf16 v[16:31], v[164:167], v[208:211], v[16:31]
	ds_read_b128 v[208:211], v149 offset:32
	s_waitcnt lgkmcnt(5)
	v_mfma_f32_32x32x16_bf16 v[64:79], v[160:163], v[212:215], v[64:79]
	v_mfma_f32_32x32x16_bf16 v[0:15], v[164:167], v[212:215], v[0:15]
	ds_read_b128 v[212:215], v149 offset:4640
	s_setprio 0
	global_load_dwordx4 v[160:163], v[140:141], off offset:2432
	global_load_dwordx4 v[164:167], v[142:143], off offset:2432
	s_setprio 1
	s_waitcnt lgkmcnt(1)
	v_mfma_f32_32x32x16_bf16 v[112:127], v[184:187], v[208:211], v[112:127]
	v_mfma_f32_32x32x16_bf16 v[48:63], v[188:191], v[208:211], v[48:63]
	s_waitcnt lgkmcnt(0)
	v_mfma_f32_32x32x16_bf16 v[96:111], v[184:187], v[212:215], v[96:111]
	v_mfma_f32_32x32x16_bf16 v[32:47], v[188:191], v[212:215], v[32:47]
	ds_read_b128 v[208:211], v149 offset:9248
	ds_read_b128 v[212:215], v149 offset:13856
	s_waitcnt vmcnt(7)
	ds_write_b128 v148, v[194:197] offset:18432
	s_waitcnt vmcnt(6)
	ds_write_b128 v148, v[198:201] offset:55296
	ds_read_b128 v[194:197], v150 offset:64
	ds_read_b128 v[198:201], v150 offset:4672
	s_waitcnt lgkmcnt(5)
	v_mfma_f32_32x32x16_bf16 v[80:95], v[184:187], v[208:211], v[80:95]
	v_mfma_f32_32x32x16_bf16 v[16:31], v[188:191], v[208:211], v[16:31]
	ds_read_b128 v[208:211], v149 offset:64
	s_waitcnt lgkmcnt(5)
	v_mfma_f32_32x32x16_bf16 v[64:79], v[184:187], v[212:215], v[64:79]
	v_mfma_f32_32x32x16_bf16 v[0:15], v[188:191], v[212:215], v[0:15]
	ds_read_b128 v[212:215], v149 offset:4672
	s_setprio 0
	global_load_dwordx4 v[184:187], v[132:133], off offset:2432
	global_load_dwordx4 v[188:191], v[134:135], off offset:2432
	s_setprio 1
	s_waitcnt lgkmcnt(1)
	v_mfma_f32_32x32x16_bf16 v[112:127], v[194:197], v[208:211], v[112:127]
	v_mfma_f32_32x32x16_bf16 v[48:63], v[198:201], v[208:211], v[48:63]
	s_waitcnt lgkmcnt(0)
	v_mfma_f32_32x32x16_bf16 v[96:111], v[194:197], v[212:215], v[96:111]
	v_mfma_f32_32x32x16_bf16 v[32:47], v[198:201], v[212:215], v[32:47]
	ds_read_b128 v[208:211], v149 offset:9280
	ds_read_b128 v[212:215], v149 offset:13888
	s_waitcnt vmcnt(7)
	ds_write_b128 v148, v[176:179] offset:27648
	s_waitcnt vmcnt(6)
	ds_write_b128 v148, v[180:183] offset:64512
	ds_read_b128 v[176:179], v150 offset:96
	ds_read_b128 v[180:183], v150 offset:4704
	s_waitcnt lgkmcnt(5)
	v_mfma_f32_32x32x16_bf16 v[80:95], v[194:197], v[208:211], v[80:95]
	v_mfma_f32_32x32x16_bf16 v[16:31], v[198:201], v[208:211], v[16:31]
	ds_read_b128 v[208:211], v149 offset:96
	s_waitcnt lgkmcnt(5)
	v_mfma_f32_32x32x16_bf16 v[64:79], v[194:197], v[212:215], v[64:79]
	v_mfma_f32_32x32x16_bf16 v[0:15], v[198:201], v[212:215], v[0:15]
	ds_read_b128 v[212:215], v149 offset:4704
	s_setprio 0
	global_load_dwordx4 v[194:197], v[144:145], off offset:2432
	global_load_dwordx4 v[198:201], v[146:147], off offset:2432
	s_setprio 1
	s_waitcnt lgkmcnt(1)
	v_mfma_f32_32x32x16_bf16 v[112:127], v[176:179], v[208:211], v[112:127]
	v_mfma_f32_32x32x16_bf16 v[48:63], v[180:183], v[208:211], v[48:63]
	s_waitcnt lgkmcnt(0)
	v_mfma_f32_32x32x16_bf16 v[96:111], v[176:179], v[212:215], v[96:111]
	v_mfma_f32_32x32x16_bf16 v[32:47], v[180:183], v[212:215], v[32:47]
	ds_read_b128 v[208:211], v149 offset:9312
	ds_read_b128 v[212:215], v149 offset:13920
	s_waitcnt lgkmcnt(0)
	s_barrier
; template <bool trans>
; DI void gemm_core(const GTile& tl, const GTile& nx, bool has_next  , bool chain  , bool pre, u32x4 (&ra)[4], u32x4 (&rb)[4], char* smem, f32x16 (&acc)[2][4]) {
;     ...
;   const int nk = K / 64;
;   if (!pre) { G_LOAD(0); G_STORE(0); G_LOAD(1); }
;   for (int kt = 0; kt < nk; ++kt) {
;     __syncthreads();
;     G_COMPUTE(kt & 1, kt);
;   }
	s_waitcnt vmcnt(7)
	ds_write_b128 v192, v[168:171]
	s_waitcnt vmcnt(6)
	ds_write_b128 v159, v[172:175]
	ds_read_b128 v[168:171], v152 offset:36864
	ds_read_b128 v[172:175], v152 offset:41472
	v_mfma_f32_32x32x16_bf16 v[80:95], v[176:179], v[208:211], v[80:95]
	v_mfma_f32_32x32x16_bf16 v[16:31], v[180:183], v[208:211], v[16:31]
	ds_read_b128 v[208:211], v151
	v_mfma_f32_32x32x16_bf16 v[64:79], v[176:179], v[212:215], v[64:79]
	v_mfma_f32_32x32x16_bf16 v[0:15], v[180:183], v[212:215], v[0:15]
	ds_read_b128 v[212:215], v151 offset:4608
	s_setprio 0
	global_load_dwordx4 v[176:179], v[136:137], off offset:2560
	global_load_dwordx4 v[180:183], v[138:139], off offset:2560
	s_setprio 1
	s_waitcnt lgkmcnt(1)
	v_mfma_f32_32x32x16_bf16 v[112:127], v[168:171], v[208:211], v[112:127]
	v_mfma_f32_32x32x16_bf16 v[48:63], v[172:175], v[208:211], v[48:63]
	s_waitcnt lgkmcnt(0)
	v_mfma_f32_32x32x16_bf16 v[96:111], v[168:171], v[212:215], v[96:111]
	v_mfma_f32_32x32x16_bf16 v[32:47], v[172:175], v[212:215], v[32:47]
	ds_read_b128 v[208:211], v151 offset:9216
	ds_read_b128 v[212:215], v151 offset:13824
	s_waitcnt vmcnt(7)
	ds_write_b128 v158, v[160:163]
	s_waitcnt vmcnt(6)
	ds_write_b128 v157, v[164:167]
	ds_read_b128 v[160:163], v152 offset:36896
	ds_read_b128 v[164:167], v152 offset:41504
	s_waitcnt lgkmcnt(5)
	v_mfma_f32_32x32x16_bf16 v[80:95], v[168:171], v[208:211], v[80:95]
	v_mfma_f32_32x32x16_bf16 v[16:31], v[172:175], v[208:211], v[16:31]
	ds_read_b128 v[208:211], v151 offset:32
	s_waitcnt lgkmcnt(5)
	v_mfma_f32_32x32x16_bf16 v[64:79], v[168:171], v[212:215], v[64:79]
	v_mfma_f32_32x32x16_bf16 v[0:15], v[172:175], v[212:215], v[0:15]
	ds_read_b128 v[212:215], v151 offset:4640
	s_setprio 0
	global_load_dwordx4 v[168:171], v[140:141], off offset:2560
	global_load_dwordx4 v[172:175], v[142:143], off offset:2560
	s_setprio 1
	s_waitcnt lgkmcnt(1)
	v_mfma_f32_32x32x16_bf16 v[112:127], v[160:163], v[208:211], v[112:127]
	v_mfma_f32_32x32x16_bf16 v[48:63], v[164:167], v[208:211], v[48:63]
	s_waitcnt lgkmcnt(0)
	v_mfma_f32_32x32x16_bf16 v[96:111], v[160:163], v[212:215], v[96:111]
	v_mfma_f32_32x32x16_bf16 v[32:47], v[164:167], v[212:215], v[32:47]
	ds_read_b128 v[208:211], v151 offset:9248
	ds_read_b128 v[212:215], v151 offset:13856
	s_waitcnt vmcnt(7)
	ds_write_b128 v154, v[184:187]
	s_waitcnt vmcnt(6)
	ds_write_b128 v153, v[188:191]
	ds_read_b128 v[184:187], v152 offset:36928
	ds_read_b128 v[188:191], v152 offset:41536
	s_waitcnt lgkmcnt(5)
	v_mfma_f32_32x32x16_bf16 v[80:95], v[160:163], v[208:211], v[80:95]
	v_mfma_f32_32x32x16_bf16 v[16:31], v[164:167], v[208:211], v[16:31]
	ds_read_b128 v[208:211], v151 offset:64
	s_waitcnt lgkmcnt(5)
	v_mfma_f32_32x32x16_bf16 v[64:79], v[160:163], v[212:215], v[64:79]
	v_mfma_f32_32x32x16_bf16 v[0:15], v[164:167], v[212:215], v[0:15]
	ds_read_b128 v[212:215], v151 offset:4672
	s_setprio 0
	global_load_dwordx4 v[160:163], v[132:133], off offset:2560
	global_load_dwordx4 v[164:167], v[134:135], off offset:2560
	s_setprio 1
	s_waitcnt lgkmcnt(1)
	v_mfma_f32_32x32x16_bf16 v[112:127], v[184:187], v[208:211], v[112:127]
	v_mfma_f32_32x32x16_bf16 v[48:63], v[188:191], v[208:211], v[48:63]
	s_waitcnt lgkmcnt(0)
	v_mfma_f32_32x32x16_bf16 v[96:111], v[184:187], v[212:215], v[96:111]
	v_mfma_f32_32x32x16_bf16 v[32:47], v[188:191], v[212:215], v[32:47]
	ds_read_b128 v[208:211], v151 offset:9280
	ds_read_b128 v[212:215], v151 offset:13888
	s_waitcnt vmcnt(7)
	ds_write_b128 v156, v[194:197]
	s_waitcnt vmcnt(6)
	ds_write_b128 v155, v[198:201]
	ds_read_b128 v[194:197], v152 offset:36960
	ds_read_b128 v[198:201], v152 offset:41568
	s_waitcnt lgkmcnt(5)
	v_mfma_f32_32x32x16_bf16 v[80:95], v[184:187], v[208:211], v[80:95]
	v_mfma_f32_32x32x16_bf16 v[16:31], v[188:191], v[208:211], v[16:31]
	ds_read_b128 v[208:211], v151 offset:96
	s_waitcnt lgkmcnt(5)
	v_mfma_f32_32x32x16_bf16 v[64:79], v[184:187], v[212:215], v[64:79]
	v_mfma_f32_32x32x16_bf16 v[0:15], v[188:191], v[212:215], v[0:15]
	ds_read_b128 v[212:215], v151 offset:4704
	s_setprio 0
	global_load_dwordx4 v[184:187], v[144:145], off offset:2560
	global_load_dwordx4 v[188:191], v[146:147], off offset:2560
	s_setprio 1
	s_waitcnt lgkmcnt(1)
	v_mfma_f32_32x32x16_bf16 v[112:127], v[194:197], v[208:211], v[112:127]
	v_mfma_f32_32x32x16_bf16 v[48:63], v[198:201], v[208:211], v[48:63]
	s_waitcnt lgkmcnt(0)
	v_mfma_f32_32x32x16_bf16 v[96:111], v[194:197], v[212:215], v[96:111]
	v_mfma_f32_32x32x16_bf16 v[32:47], v[198:201], v[212:215], v[32:47]
	ds_read_b128 v[208:211], v151 offset:9312
	ds_read_b128 v[212:215], v151 offset:13920
	s_waitcnt lgkmcnt(0)
	s_barrier
; template <bool trans>
; DI void gemm_core(const GTile& tl, const GTile& nx, bool has_next  , bool chain  , bool pre, u32x4 (&ra)[4], u32x4 (&rb)[4], char* smem, f32x16 (&acc)[2][4]) {
;     ...
;   const int nk = K / 64;
;   if (!pre) { G_LOAD(0); G_STORE(0); G_LOAD(1); }
;   for (int kt = 0; kt < nk; ++kt) {
;     __syncthreads();
;     G_COMPUTE(kt & 1, kt);
;   }
	s_waitcnt vmcnt(7)
	ds_write_b128 v148, v[176:179]
	s_waitcnt vmcnt(6)
	ds_write_b128 v148, v[180:183] offset:36864
	ds_read_b128 v[176:179], v150
	ds_read_b128 v[180:183], v150 offset:4608
	v_mfma_f32_32x32x16_bf16 v[80:95], v[194:197], v[208:211], v[80:95]
	v_mfma_f32_32x32x16_bf16 v[16:31], v[198:201], v[208:211], v[16:31]
	ds_read_b128 v[208:211], v149
	v_mfma_f32_32x32x16_bf16 v[64:79], v[194:197], v[212:215], v[64:79]
	v_mfma_f32_32x32x16_bf16 v[0:15], v[198:201], v[212:215], v[0:15]
	ds_read_b128 v[212:215], v149 offset:4608
	s_setprio 0
	global_load_dwordx4 v[194:197], v[136:137], off offset:2688
	global_load_dwordx4 v[198:201], v[138:139], off offset:2688
	s_setprio 1
	s_waitcnt lgkmcnt(1)
	v_mfma_f32_32x32x16_bf16 v[112:127], v[176:179], v[208:211], v[112:127]
	v_mfma_f32_32x32x16_bf16 v[48:63], v[180:183], v[208:211], v[48:63]
	s_waitcnt lgkmcnt(0)
	v_mfma_f32_32x32x16_bf16 v[96:111], v[176:179], v[212:215], v[96:111]
	v_mfma_f32_32x32x16_bf16 v[32:47], v[180:183], v[212:215], v[32:47]
	ds_read_b128 v[208:211], v149 offset:9216
	ds_read_b128 v[212:215], v149 offset:13824
	s_waitcnt vmcnt(7)
	ds_write_b128 v148, v[168:171] offset:9216
	s_waitcnt vmcnt(6)
	ds_write_b128 v148, v[172:175] offset:46080
	ds_read_b128 v[168:171], v150 offset:32
	ds_read_b128 v[172:175], v150 offset:4640
	s_waitcnt lgkmcnt(5)
	v_mfma_f32_32x32x16_bf16 v[80:95], v[176:179], v[208:211], v[80:95]
	v_mfma_f32_32x32x16_bf16 v[16:31], v[180:183], v[208:211], v[16:31]
	ds_read_b128 v[208:211], v149 offset:32
	s_waitcnt lgkmcnt(5)
	v_mfma_f32_32x32x16_bf16 v[64:79], v[176:179], v[212:215], v[64:79]
	v_mfma_f32_32x32x16_bf16 v[0:15], v[180:183], v[212:215], v[0:15]
	ds_read_b128 v[212:215], v149 offset:4640
	s_setprio 0
	global_load_dwordx4 v[176:179], v[140:141], off offset:2688
	global_load_dwordx4 v[180:183], v[142:143], off offset:2688
	s_setprio 1
	s_waitcnt lgkmcnt(1)
	v_mfma_f32_32x32x16_bf16 v[112:127], v[168:171], v[208:211], v[112:127]
	v_mfma_f32_32x32x16_bf16 v[48:63], v[172:175], v[208:211], v[48:63]
	s_waitcnt lgkmcnt(0)
	v_mfma_f32_32x32x16_bf16 v[96:111], v[168:171], v[212:215], v[96:111]
	v_mfma_f32_32x32x16_bf16 v[32:47], v[172:175], v[212:215], v[32:47]
	ds_read_b128 v[208:211], v149 offset:9248
	ds_read_b128 v[212:215], v149 offset:13856
	s_waitcnt vmcnt(7)
	ds_write_b128 v148, v[160:163] offset:18432
	s_waitcnt vmcnt(6)
	ds_write_b128 v148, v[164:167] offset:55296
	ds_read_b128 v[160:163], v150 offset:64
	ds_read_b128 v[164:167], v150 offset:4672
	s_waitcnt lgkmcnt(5)
	v_mfma_f32_32x32x16_bf16 v[80:95], v[168:171], v[208:211], v[80:95]
	v_mfma_f32_32x32x16_bf16 v[16:31], v[172:175], v[208:211], v[16:31]
	ds_read_b128 v[208:211], v149 offset:64
	s_waitcnt lgkmcnt(5)
	v_mfma_f32_32x32x16_bf16 v[64:79], v[168:171], v[212:215], v[64:79]
	v_mfma_f32_32x32x16_bf16 v[0:15], v[172:175], v[212:215], v[0:15]
	ds_read_b128 v[212:215], v149 offset:4672
	s_setprio 0
	global_load_dwordx4 v[168:171], v[132:133], off offset:2688
	global_load_dwordx4 v[172:175], v[134:135], off offset:2688
	s_setprio 1
	s_waitcnt lgkmcnt(1)
	v_mfma_f32_32x32x16_bf16 v[112:127], v[160:163], v[208:211], v[112:127]
	v_mfma_f32_32x32x16_bf16 v[48:63], v[164:167], v[208:211], v[48:63]
	s_waitcnt lgkmcnt(0)
	v_mfma_f32_32x32x16_bf16 v[96:111], v[160:163], v[212:215], v[96:111]
	v_mfma_f32_32x32x16_bf16 v[32:47], v[164:167], v[212:215], v[32:47]
	ds_read_b128 v[208:211], v149 offset:9280
	ds_read_b128 v[212:215], v149 offset:13888
	s_waitcnt vmcnt(7)
	ds_write_b128 v148, v[184:187] offset:27648
	s_waitcnt vmcnt(6)
	ds_write_b128 v148, v[188:191] offset:64512
	ds_read_b128 v[184:187], v150 offset:96
	ds_read_b128 v[188:191], v150 offset:4704
	s_waitcnt lgkmcnt(5)
	v_mfma_f32_32x32x16_bf16 v[80:95], v[160:163], v[208:211], v[80:95]
	v_mfma_f32_32x32x16_bf16 v[16:31], v[164:167], v[208:211], v[16:31]
	ds_read_b128 v[208:211], v149 offset:96
	s_waitcnt lgkmcnt(5)
	v_mfma_f32_32x32x16_bf16 v[64:79], v[160:163], v[212:215], v[64:79]
	v_mfma_f32_32x32x16_bf16 v[0:15], v[164:167], v[212:215], v[0:15]
	ds_read_b128 v[212:215], v149 offset:4704
	s_setprio 0
	global_load_dwordx4 v[160:163], v[144:145], off offset:2688
	global_load_dwordx4 v[164:167], v[146:147], off offset:2688
	s_setprio 1
	s_waitcnt lgkmcnt(1)
	v_mfma_f32_32x32x16_bf16 v[112:127], v[184:187], v[208:211], v[112:127]
	v_mfma_f32_32x32x16_bf16 v[48:63], v[188:191], v[208:211], v[48:63]
	s_waitcnt lgkmcnt(0)
	v_mfma_f32_32x32x16_bf16 v[96:111], v[184:187], v[212:215], v[96:111]
	v_mfma_f32_32x32x16_bf16 v[32:47], v[188:191], v[212:215], v[32:47]
	ds_read_b128 v[208:211], v149 offset:9312
	ds_read_b128 v[212:215], v149 offset:13920
	s_waitcnt lgkmcnt(0)
	s_barrier
; template <bool trans>
; DI void gemm_core(const GTile& tl, const GTile& nx, bool has_next  , bool chain  , bool pre, u32x4 (&ra)[4], u32x4 (&rb)[4], char* smem, f32x16 (&acc)[2][4]) {
;     ...
;   const int nk = K / 64;
;   if (!pre) { G_LOAD(0); G_STORE(0); G_LOAD(1); }
;   for (int kt = 0; kt < nk; ++kt) {
;     __syncthreads();
;     G_COMPUTE(kt & 1, kt);
;   }
	s_waitcnt vmcnt(7)
	ds_write_b128 v192, v[194:197]
	s_waitcnt vmcnt(6)
	ds_write_b128 v159, v[198:201]
	ds_read_b128 v[194:197], v152 offset:36864
	ds_read_b128 v[198:201], v152 offset:41472
	v_mfma_f32_32x32x16_bf16 v[80:95], v[184:187], v[208:211], v[80:95]
	v_mfma_f32_32x32x16_bf16 v[16:31], v[188:191], v[208:211], v[16:31]
	ds_read_b128 v[208:211], v151
	v_mfma_f32_32x32x16_bf16 v[64:79], v[184:187], v[212:215], v[64:79]
	v_mfma_f32_32x32x16_bf16 v[0:15], v[188:191], v[212:215], v[0:15]
	ds_read_b128 v[212:215], v151 offset:4608
	s_setprio 0
	global_load_dwordx4 v[184:187], v[136:137], off offset:2816
	global_load_dwordx4 v[188:191], v[138:139], off offset:2816
	s_setprio 1
	s_waitcnt lgkmcnt(1)
	v_mfma_f32_32x32x16_bf16 v[112:127], v[194:197], v[208:211], v[112:127]
	v_mfma_f32_32x32x16_bf16 v[48:63], v[198:201], v[208:211], v[48:63]
	s_waitcnt lgkmcnt(0)
	v_mfma_f32_32x32x16_bf16 v[96:111], v[194:197], v[212:215], v[96:111]
	v_mfma_f32_32x32x16_bf16 v[32:47], v[198:201], v[212:215], v[32:47]
	ds_read_b128 v[208:211], v151 offset:9216
	ds_read_b128 v[212:215], v151 offset:13824
	s_waitcnt vmcnt(7)
	ds_write_b128 v158, v[176:179]
	s_waitcnt vmcnt(6)
	ds_write_b128 v157, v[180:183]
	ds_read_b128 v[176:179], v152 offset:36896
	ds_read_b128 v[180:183], v152 offset:41504
	s_waitcnt lgkmcnt(5)
	v_mfma_f32_32x32x16_bf16 v[80:95], v[194:197], v[208:211], v[80:95]
	v_mfma_f32_32x32x16_bf16 v[16:31], v[198:201], v[208:211], v[16:31]
	ds_read_b128 v[208:211], v151 offset:32
	s_waitcnt lgkmcnt(5)
	v_mfma_f32_32x32x16_bf16 v[64:79], v[194:197], v[212:215], v[64:79]
	v_mfma_f32_32x32x16_bf16 v[0:15], v[198:201], v[212:215], v[0:15]
	ds_read_b128 v[212:215], v151 offset:4640
	s_setprio 0
	global_load_dwordx4 v[194:197], v[140:141], off offset:2816
	global_load_dwordx4 v[198:201], v[142:143], off offset:2816
	s_setprio 1
	s_waitcnt lgkmcnt(1)
	v_mfma_f32_32x32x16_bf16 v[112:127], v[176:179], v[208:211], v[112:127]
	v_mfma_f32_32x32x16_bf16 v[48:63], v[180:183], v[208:211], v[48:63]
	s_waitcnt lgkmcnt(0)
	v_mfma_f32_32x32x16_bf16 v[96:111], v[176:179], v[212:215], v[96:111]
	v_mfma_f32_32x32x16_bf16 v[32:47], v[180:183], v[212:215], v[32:47]
	ds_read_b128 v[208:211], v151 offset:9248
	ds_read_b128 v[212:215], v151 offset:13856
	s_waitcnt vmcnt(7)
	ds_write_b128 v154, v[168:171]
	s_waitcnt vmcnt(6)
	ds_write_b128 v153, v[172:175]
	ds_read_b128 v[168:171], v152 offset:36928
	ds_read_b128 v[172:175], v152 offset:41536
	s_waitcnt lgkmcnt(5)
	v_mfma_f32_32x32x16_bf16 v[80:95], v[176:179], v[208:211], v[80:95]
	v_mfma_f32_32x32x16_bf16 v[16:31], v[180:183], v[208:211], v[16:31]
	ds_read_b128 v[208:211], v151 offset:64
	s_waitcnt lgkmcnt(5)
	v_mfma_f32_32x32x16_bf16 v[64:79], v[176:179], v[212:215], v[64:79]
	v_mfma_f32_32x32x16_bf16 v[0:15], v[180:183], v[212:215], v[0:15]
	ds_read_b128 v[212:215], v151 offset:4672
	s_setprio 0
	global_load_dwordx4 v[176:179], v[132:133], off offset:2816
	global_load_dwordx4 v[180:183], v[134:135], off offset:2816
	s_setprio 1
	s_waitcnt lgkmcnt(1)
	v_mfma_f32_32x32x16_bf16 v[112:127], v[168:171], v[208:211], v[112:127]
	v_mfma_f32_32x32x16_bf16 v[48:63], v[172:175], v[208:211], v[48:63]
	s_waitcnt lgkmcnt(0)
	v_mfma_f32_32x32x16_bf16 v[96:111], v[168:171], v[212:215], v[96:111]
	v_mfma_f32_32x32x16_bf16 v[32:47], v[172:175], v[212:215], v[32:47]
	ds_read_b128 v[208:211], v151 offset:9280
	ds_read_b128 v[212:215], v151 offset:13888
	s_waitcnt vmcnt(7)
	ds_write_b128 v156, v[160:163]
	s_waitcnt vmcnt(6)
	ds_write_b128 v155, v[164:167]
	ds_read_b128 v[160:163], v152 offset:36960
	ds_read_b128 v[164:167], v152 offset:41568
	s_waitcnt lgkmcnt(5)
	v_mfma_f32_32x32x16_bf16 v[80:95], v[168:171], v[208:211], v[80:95]
	v_mfma_f32_32x32x16_bf16 v[16:31], v[172:175], v[208:211], v[16:31]
	ds_read_b128 v[208:211], v151 offset:96
	s_waitcnt lgkmcnt(5)
	v_mfma_f32_32x32x16_bf16 v[64:79], v[168:171], v[212:215], v[64:79]
	v_mfma_f32_32x32x16_bf16 v[0:15], v[172:175], v[212:215], v[0:15]
	ds_read_b128 v[212:215], v151 offset:4704
	s_setprio 0
	global_load_dwordx4 v[168:171], v[144:145], off offset:2816
	global_load_dwordx4 v[172:175], v[146:147], off offset:2816
	s_setprio 1
	s_waitcnt lgkmcnt(1)
	v_mfma_f32_32x32x16_bf16 v[112:127], v[160:163], v[208:211], v[112:127]
	v_mfma_f32_32x32x16_bf16 v[48:63], v[164:167], v[208:211], v[48:63]
	s_waitcnt lgkmcnt(0)
	v_mfma_f32_32x32x16_bf16 v[96:111], v[160:163], v[212:215], v[96:111]
	v_mfma_f32_32x32x16_bf16 v[32:47], v[164:167], v[212:215], v[32:47]
	ds_read_b128 v[208:211], v151 offset:9312
	ds_read_b128 v[212:215], v151 offset:13920
	s_waitcnt lgkmcnt(0)
	s_barrier
; template <bool trans>
; DI void gemm_core(const GTile& tl, const GTile& nx, bool has_next  , bool chain  , bool pre, u32x4 (&ra)[4], u32x4 (&rb)[4], char* smem, f32x16 (&acc)[2][4]) {
;     ...
;   const int nk = K / 64;
;   if (!pre) { G_LOAD(0); G_STORE(0); G_LOAD(1); }
;   for (int kt = 0; kt < nk; ++kt) {
;     __syncthreads();
;     G_COMPUTE(kt & 1, kt);
;   }
	s_waitcnt vmcnt(7)
	ds_write_b128 v148, v[184:187]
	s_waitcnt vmcnt(6)
	ds_write_b128 v148, v[188:191] offset:36864
	ds_read_b128 v[184:187], v150
	ds_read_b128 v[188:191], v150 offset:4608
	v_mfma_f32_32x32x16_bf16 v[80:95], v[160:163], v[208:211], v[80:95]
	v_mfma_f32_32x32x16_bf16 v[16:31], v[164:167], v[208:211], v[16:31]
	ds_read_b128 v[208:211], v149
	v_mfma_f32_32x32x16_bf16 v[64:79], v[160:163], v[212:215], v[64:79]
	v_mfma_f32_32x32x16_bf16 v[0:15], v[164:167], v[212:215], v[0:15]
	ds_read_b128 v[212:215], v149 offset:4608
	s_setprio 0
	global_load_dwordx4 v[160:163], v[136:137], off offset:2944
	global_load_dwordx4 v[164:167], v[138:139], off offset:2944
	s_setprio 1
	s_waitcnt lgkmcnt(1)
	v_mfma_f32_32x32x16_bf16 v[112:127], v[184:187], v[208:211], v[112:127]
	v_mfma_f32_32x32x16_bf16 v[48:63], v[188:191], v[208:211], v[48:63]
	s_waitcnt lgkmcnt(0)
	v_mfma_f32_32x32x16_bf16 v[96:111], v[184:187], v[212:215], v[96:111]
	v_mfma_f32_32x32x16_bf16 v[32:47], v[188:191], v[212:215], v[32:47]
	ds_read_b128 v[208:211], v149 offset:9216
	ds_read_b128 v[212:215], v149 offset:13824
	s_waitcnt vmcnt(7)
	ds_write_b128 v148, v[194:197] offset:9216
	s_waitcnt vmcnt(6)
	ds_write_b128 v148, v[198:201] offset:46080
	ds_read_b128 v[194:197], v150 offset:32
	ds_read_b128 v[198:201], v150 offset:4640
	s_waitcnt lgkmcnt(5)
	v_mfma_f32_32x32x16_bf16 v[80:95], v[184:187], v[208:211], v[80:95]
	v_mfma_f32_32x32x16_bf16 v[16:31], v[188:191], v[208:211], v[16:31]
	ds_read_b128 v[208:211], v149 offset:32
	s_waitcnt lgkmcnt(5)
	v_mfma_f32_32x32x16_bf16 v[64:79], v[184:187], v[212:215], v[64:79]
	v_mfma_f32_32x32x16_bf16 v[0:15], v[188:191], v[212:215], v[0:15]
	ds_read_b128 v[212:215], v149 offset:4640
	s_setprio 0
	global_load_dwordx4 v[184:187], v[140:141], off offset:2944
	global_load_dwordx4 v[188:191], v[142:143], off offset:2944
	s_setprio 1
	s_waitcnt lgkmcnt(1)
	v_mfma_f32_32x32x16_bf16 v[112:127], v[194:197], v[208:211], v[112:127]
	v_mfma_f32_32x32x16_bf16 v[48:63], v[198:201], v[208:211], v[48:63]
	s_waitcnt lgkmcnt(0)
	v_mfma_f32_32x32x16_bf16 v[96:111], v[194:197], v[212:215], v[96:111]
	v_mfma_f32_32x32x16_bf16 v[32:47], v[198:201], v[212:215], v[32:47]
	ds_read_b128 v[208:211], v149 offset:9248
	ds_read_b128 v[212:215], v149 offset:13856
	s_waitcnt vmcnt(7)
	ds_write_b128 v148, v[176:179] offset:18432
	s_waitcnt vmcnt(6)
	ds_write_b128 v148, v[180:183] offset:55296
	ds_read_b128 v[176:179], v150 offset:64
	ds_read_b128 v[180:183], v150 offset:4672
	s_waitcnt lgkmcnt(5)
	v_mfma_f32_32x32x16_bf16 v[80:95], v[194:197], v[208:211], v[80:95]
	v_mfma_f32_32x32x16_bf16 v[16:31], v[198:201], v[208:211], v[16:31]
	ds_read_b128 v[208:211], v149 offset:64
	s_waitcnt lgkmcnt(5)
	v_mfma_f32_32x32x16_bf16 v[64:79], v[194:197], v[212:215], v[64:79]
	v_mfma_f32_32x32x16_bf16 v[0:15], v[198:201], v[212:215], v[0:15]
	ds_read_b128 v[212:215], v149 offset:4672
	s_setprio 0
	global_load_dwordx4 v[194:197], v[132:133], off offset:2944
	global_load_dwordx4 v[198:201], v[134:135], off offset:2944
	s_setprio 1
	s_waitcnt lgkmcnt(1)
	v_mfma_f32_32x32x16_bf16 v[112:127], v[176:179], v[208:211], v[112:127]
	v_mfma_f32_32x32x16_bf16 v[48:63], v[180:183], v[208:211], v[48:63]
	s_waitcnt lgkmcnt(0)
	v_mfma_f32_32x32x16_bf16 v[96:111], v[176:179], v[212:215], v[96:111]
	v_mfma_f32_32x32x16_bf16 v[32:47], v[180:183], v[212:215], v[32:47]
	ds_read_b128 v[208:211], v149 offset:9280
	ds_read_b128 v[212:215], v149 offset:13888
	s_waitcnt vmcnt(7)
	ds_write_b128 v148, v[168:171] offset:27648
	s_waitcnt vmcnt(6)
	ds_write_b128 v148, v[172:175] offset:64512
	ds_read_b128 v[168:171], v150 offset:96
	ds_read_b128 v[172:175], v150 offset:4704
	s_waitcnt lgkmcnt(5)
	v_mfma_f32_32x32x16_bf16 v[80:95], v[176:179], v[208:211], v[80:95]
	v_mfma_f32_32x32x16_bf16 v[16:31], v[180:183], v[208:211], v[16:31]
	ds_read_b128 v[208:211], v149 offset:96
	s_waitcnt lgkmcnt(5)
	v_mfma_f32_32x32x16_bf16 v[64:79], v[176:179], v[212:215], v[64:79]
	v_mfma_f32_32x32x16_bf16 v[0:15], v[180:183], v[212:215], v[0:15]
	ds_read_b128 v[212:215], v149 offset:4704
	s_setprio 0
	global_load_dwordx4 v[176:179], v[144:145], off offset:2944
	global_load_dwordx4 v[180:183], v[146:147], off offset:2944
	s_setprio 1
	s_waitcnt lgkmcnt(1)
	v_mfma_f32_32x32x16_bf16 v[112:127], v[168:171], v[208:211], v[112:127]
	v_mfma_f32_32x32x16_bf16 v[48:63], v[172:175], v[208:211], v[48:63]
	s_waitcnt lgkmcnt(0)
	v_mfma_f32_32x32x16_bf16 v[96:111], v[168:171], v[212:215], v[96:111]
	v_mfma_f32_32x32x16_bf16 v[32:47], v[172:175], v[212:215], v[32:47]
	ds_read_b128 v[208:211], v149 offset:9312
	ds_read_b128 v[212:215], v149 offset:13920
	s_waitcnt lgkmcnt(0)
	s_barrier
; template <bool trans>
; DI void gemm_core(const GTile& tl, const GTile& nx, bool has_next  , bool chain  , bool pre, u32x4 (&ra)[4], u32x4 (&rb)[4], char* smem, f32x16 (&acc)[2][4]) {
;     ...
;   const int nk = K / 64;
;   if (!pre) { G_LOAD(0); G_STORE(0); G_LOAD(1); }
;   for (int kt = 0; kt < nk; ++kt) {
;     __syncthreads();
;     G_COMPUTE(kt & 1, kt);
;   }
	s_waitcnt vmcnt(7)
	ds_write_b128 v192, v[160:163]
	s_waitcnt vmcnt(6)
	ds_write_b128 v159, v[164:167]
	ds_read_b128 v[160:163], v152 offset:36864
	ds_read_b128 v[164:167], v152 offset:41472
	v_mfma_f32_32x32x16_bf16 v[80:95], v[168:171], v[208:211], v[80:95]
	v_mfma_f32_32x32x16_bf16 v[16:31], v[172:175], v[208:211], v[16:31]
	ds_read_b128 v[208:211], v151
	v_mfma_f32_32x32x16_bf16 v[64:79], v[168:171], v[212:215], v[64:79]
	v_mfma_f32_32x32x16_bf16 v[0:15], v[172:175], v[212:215], v[0:15]
	ds_read_b128 v[212:215], v151 offset:4608
	s_setprio 0
	global_load_dwordx4 v[168:171], v[136:137], off offset:3072
	global_load_dwordx4 v[172:175], v[138:139], off offset:3072
	s_setprio 1
	s_waitcnt lgkmcnt(1)
	v_mfma_f32_32x32x16_bf16 v[112:127], v[160:163], v[208:211], v[112:127]
	v_mfma_f32_32x32x16_bf16 v[48:63], v[164:167], v[208:211], v[48:63]
	s_waitcnt lgkmcnt(0)
	v_mfma_f32_32x32x16_bf16 v[96:111], v[160:163], v[212:215], v[96:111]
	v_mfma_f32_32x32x16_bf16 v[32:47], v[164:167], v[212:215], v[32:47]
	ds_read_b128 v[208:211], v151 offset:9216
	ds_read_b128 v[212:215], v151 offset:13824
	s_waitcnt vmcnt(7)
	ds_write_b128 v158, v[184:187]
	s_waitcnt vmcnt(6)
	ds_write_b128 v157, v[188:191]
	ds_read_b128 v[184:187], v152 offset:36896
	ds_read_b128 v[188:191], v152 offset:41504
	s_waitcnt lgkmcnt(5)
	v_mfma_f32_32x32x16_bf16 v[80:95], v[160:163], v[208:211], v[80:95]
	v_mfma_f32_32x32x16_bf16 v[16:31], v[164:167], v[208:211], v[16:31]
	ds_read_b128 v[208:211], v151 offset:32
	s_waitcnt lgkmcnt(5)
	v_mfma_f32_32x32x16_bf16 v[64:79], v[160:163], v[212:215], v[64:79]
	v_mfma_f32_32x32x16_bf16 v[0:15], v[164:167], v[212:215], v[0:15]
	ds_read_b128 v[212:215], v151 offset:4640
	s_setprio 0
	global_load_dwordx4 v[160:163], v[140:141], off offset:3072
	global_load_dwordx4 v[164:167], v[142:143], off offset:3072
	s_setprio 1
	s_waitcnt lgkmcnt(1)
	v_mfma_f32_32x32x16_bf16 v[112:127], v[184:187], v[208:211], v[112:127]
	v_mfma_f32_32x32x16_bf16 v[48:63], v[188:191], v[208:211], v[48:63]
	s_waitcnt lgkmcnt(0)
	v_mfma_f32_32x32x16_bf16 v[96:111], v[184:187], v[212:215], v[96:111]
	v_mfma_f32_32x32x16_bf16 v[32:47], v[188:191], v[212:215], v[32:47]
	ds_read_b128 v[208:211], v151 offset:9248
	ds_read_b128 v[212:215], v151 offset:13856
	s_waitcnt vmcnt(7)
	ds_write_b128 v154, v[194:197]
	s_waitcnt vmcnt(6)
	ds_write_b128 v153, v[198:201]
	ds_read_b128 v[194:197], v152 offset:36928
	ds_read_b128 v[198:201], v152 offset:41536
	s_waitcnt lgkmcnt(5)
	v_mfma_f32_32x32x16_bf16 v[80:95], v[184:187], v[208:211], v[80:95]
	v_mfma_f32_32x32x16_bf16 v[16:31], v[188:191], v[208:211], v[16:31]
	ds_read_b128 v[208:211], v151 offset:64
	s_waitcnt lgkmcnt(5)
	v_mfma_f32_32x32x16_bf16 v[64:79], v[184:187], v[212:215], v[64:79]
	v_mfma_f32_32x32x16_bf16 v[0:15], v[188:191], v[212:215], v[0:15]
	ds_read_b128 v[212:215], v151 offset:4672
	s_setprio 0
	global_load_dwordx4 v[184:187], v[132:133], off offset:3072
	global_load_dwordx4 v[188:191], v[134:135], off offset:3072
	s_setprio 1
	s_waitcnt lgkmcnt(1)
	v_mfma_f32_32x32x16_bf16 v[112:127], v[194:197], v[208:211], v[112:127]
	v_mfma_f32_32x32x16_bf16 v[48:63], v[198:201], v[208:211], v[48:63]
	s_waitcnt lgkmcnt(0)
	v_mfma_f32_32x32x16_bf16 v[96:111], v[194:197], v[212:215], v[96:111]
	v_mfma_f32_32x32x16_bf16 v[32:47], v[198:201], v[212:215], v[32:47]
	ds_read_b128 v[208:211], v151 offset:9280
	ds_read_b128 v[212:215], v151 offset:13888
	s_waitcnt vmcnt(7)
	ds_write_b128 v156, v[176:179]
	s_waitcnt vmcnt(6)
	ds_write_b128 v155, v[180:183]
	ds_read_b128 v[176:179], v152 offset:36960
	ds_read_b128 v[180:183], v152 offset:41568
	s_waitcnt lgkmcnt(5)
	v_mfma_f32_32x32x16_bf16 v[80:95], v[194:197], v[208:211], v[80:95]
	v_mfma_f32_32x32x16_bf16 v[16:31], v[198:201], v[208:211], v[16:31]
	ds_read_b128 v[208:211], v151 offset:96
	s_waitcnt lgkmcnt(5)
	v_mfma_f32_32x32x16_bf16 v[64:79], v[194:197], v[212:215], v[64:79]
	v_mfma_f32_32x32x16_bf16 v[0:15], v[198:201], v[212:215], v[0:15]
	ds_read_b128 v[212:215], v151 offset:4704
	s_setprio 0
	global_load_dwordx4 v[194:197], v[144:145], off offset:3072
	global_load_dwordx4 v[198:201], v[146:147], off offset:3072
	s_setprio 1
	s_waitcnt lgkmcnt(1)
	v_mfma_f32_32x32x16_bf16 v[112:127], v[176:179], v[208:211], v[112:127]
	v_mfma_f32_32x32x16_bf16 v[48:63], v[180:183], v[208:211], v[48:63]
	s_waitcnt lgkmcnt(0)
	v_mfma_f32_32x32x16_bf16 v[96:111], v[176:179], v[212:215], v[96:111]
	v_mfma_f32_32x32x16_bf16 v[32:47], v[180:183], v[212:215], v[32:47]
	ds_read_b128 v[208:211], v151 offset:9312
	ds_read_b128 v[212:215], v151 offset:13920
	s_waitcnt lgkmcnt(0)
	s_barrier
; template <bool trans>
; DI void gemm_core(const GTile& tl, const GTile& nx, bool has_next  , bool chain  , bool pre, u32x4 (&ra)[4], u32x4 (&rb)[4], char* smem, f32x16 (&acc)[2][4]) {
;     ...
;   const int nk = K / 64;
;   if (!pre) { G_LOAD(0); G_STORE(0); G_LOAD(1); }
;   for (int kt = 0; kt < nk; ++kt) {
;     __syncthreads();
;     G_COMPUTE(kt & 1, kt);
;   }
	s_waitcnt vmcnt(7)
	ds_write_b128 v148, v[168:171]
	s_waitcnt vmcnt(6)
	ds_write_b128 v148, v[172:175] offset:36864
	ds_read_b128 v[168:171], v150
	ds_read_b128 v[172:175], v150 offset:4608
	v_mfma_f32_32x32x16_bf16 v[80:95], v[176:179], v[208:211], v[80:95]
	v_mfma_f32_32x32x16_bf16 v[16:31], v[180:183], v[208:211], v[16:31]
	ds_read_b128 v[208:211], v149
	v_mfma_f32_32x32x16_bf16 v[64:79], v[176:179], v[212:215], v[64:79]
	v_mfma_f32_32x32x16_bf16 v[0:15], v[180:183], v[212:215], v[0:15]
	ds_read_b128 v[212:215], v149 offset:4608
	s_setprio 0
	global_load_dwordx4 v[176:179], v[136:137], off offset:3200
	global_load_dwordx4 v[180:183], v[138:139], off offset:3200
	s_setprio 1
	s_waitcnt lgkmcnt(1)
	v_mfma_f32_32x32x16_bf16 v[112:127], v[168:171], v[208:211], v[112:127]
	v_mfma_f32_32x32x16_bf16 v[48:63], v[172:175], v[208:211], v[48:63]
	s_waitcnt lgkmcnt(0)
	v_mfma_f32_32x32x16_bf16 v[96:111], v[168:171], v[212:215], v[96:111]
	v_mfma_f32_32x32x16_bf16 v[32:47], v[172:175], v[212:215], v[32:47]
	ds_read_b128 v[208:211], v149 offset:9216
	ds_read_b128 v[212:215], v149 offset:13824
	s_waitcnt vmcnt(7)
	ds_write_b128 v148, v[160:163] offset:9216
	s_waitcnt vmcnt(6)
	ds_write_b128 v148, v[164:167] offset:46080
	ds_read_b128 v[160:163], v150 offset:32
	ds_read_b128 v[164:167], v150 offset:4640
	s_waitcnt lgkmcnt(5)
	v_mfma_f32_32x32x16_bf16 v[80:95], v[168:171], v[208:211], v[80:95]
	v_mfma_f32_32x32x16_bf16 v[16:31], v[172:175], v[208:211], v[16:31]
	ds_read_b128 v[208:211], v149 offset:32
	s_waitcnt lgkmcnt(5)
	v_mfma_f32_32x32x16_bf16 v[64:79], v[168:171], v[212:215], v[64:79]
	v_mfma_f32_32x32x16_bf16 v[0:15], v[172:175], v[212:215], v[0:15]
	ds_read_b128 v[212:215], v149 offset:4640
	s_setprio 0
	global_load_dwordx4 v[168:171], v[140:141], off offset:3200
	global_load_dwordx4 v[172:175], v[142:143], off offset:3200
	s_setprio 1
	s_waitcnt lgkmcnt(1)
	v_mfma_f32_32x32x16_bf16 v[112:127], v[160:163], v[208:211], v[112:127]
	v_mfma_f32_32x32x16_bf16 v[48:63], v[164:167], v[208:211], v[48:63]
	s_waitcnt lgkmcnt(0)
	v_mfma_f32_32x32x16_bf16 v[96:111], v[160:163], v[212:215], v[96:111]
	v_mfma_f32_32x32x16_bf16 v[32:47], v[164:167], v[212:215], v[32:47]
	ds_read_b128 v[208:211], v149 offset:9248
	ds_read_b128 v[212:215], v149 offset:13856
	s_waitcnt vmcnt(7)
	ds_write_b128 v148, v[184:187] offset:18432
	s_waitcnt vmcnt(6)
	ds_write_b128 v148, v[188:191] offset:55296
	ds_read_b128 v[184:187], v150 offset:64
	ds_read_b128 v[188:191], v150 offset:4672
	s_waitcnt lgkmcnt(5)
	v_mfma_f32_32x32x16_bf16 v[80:95], v[160:163], v[208:211], v[80:95]
	v_mfma_f32_32x32x16_bf16 v[16:31], v[164:167], v[208:211], v[16:31]
	ds_read_b128 v[208:211], v149 offset:64
	s_waitcnt lgkmcnt(5)
	v_mfma_f32_32x32x16_bf16 v[64:79], v[160:163], v[212:215], v[64:79]
	v_mfma_f32_32x32x16_bf16 v[0:15], v[164:167], v[212:215], v[0:15]
	ds_read_b128 v[212:215], v149 offset:4672
	s_setprio 0
	global_load_dwordx4 v[160:163], v[132:133], off offset:3200
	global_load_dwordx4 v[164:167], v[134:135], off offset:3200
	s_setprio 1
	s_waitcnt lgkmcnt(1)
	v_mfma_f32_32x32x16_bf16 v[112:127], v[184:187], v[208:211], v[112:127]
	v_mfma_f32_32x32x16_bf16 v[48:63], v[188:191], v[208:211], v[48:63]
	s_waitcnt lgkmcnt(0)
	v_mfma_f32_32x32x16_bf16 v[96:111], v[184:187], v[212:215], v[96:111]
	v_mfma_f32_32x32x16_bf16 v[32:47], v[188:191], v[212:215], v[32:47]
	ds_read_b128 v[208:211], v149 offset:9280
	ds_read_b128 v[212:215], v149 offset:13888
	s_waitcnt vmcnt(7)
	ds_write_b128 v148, v[194:197] offset:27648
	s_waitcnt vmcnt(6)
	ds_write_b128 v148, v[198:201] offset:64512
	ds_read_b128 v[194:197], v150 offset:96
	ds_read_b128 v[198:201], v150 offset:4704
	s_waitcnt lgkmcnt(5)
	v_mfma_f32_32x32x16_bf16 v[80:95], v[184:187], v[208:211], v[80:95]
	v_mfma_f32_32x32x16_bf16 v[16:31], v[188:191], v[208:211], v[16:31]
	ds_read_b128 v[208:211], v149 offset:96
	s_waitcnt lgkmcnt(5)
	v_mfma_f32_32x32x16_bf16 v[64:79], v[184:187], v[212:215], v[64:79]
	v_mfma_f32_32x32x16_bf16 v[0:15], v[188:191], v[212:215], v[0:15]
	ds_read_b128 v[212:215], v149 offset:4704
	s_setprio 0
	global_load_dwordx4 v[184:187], v[144:145], off offset:3200
	global_load_dwordx4 v[188:191], v[146:147], off offset:3200
	s_setprio 1
	s_waitcnt lgkmcnt(1)
	v_mfma_f32_32x32x16_bf16 v[112:127], v[194:197], v[208:211], v[112:127]
	v_mfma_f32_32x32x16_bf16 v[48:63], v[198:201], v[208:211], v[48:63]
	s_waitcnt lgkmcnt(0)
	v_mfma_f32_32x32x16_bf16 v[96:111], v[194:197], v[212:215], v[96:111]
	v_mfma_f32_32x32x16_bf16 v[32:47], v[198:201], v[212:215], v[32:47]
	ds_read_b128 v[208:211], v149 offset:9312
	ds_read_b128 v[212:215], v149 offset:13920
	s_waitcnt lgkmcnt(0)
	s_barrier
; template <bool trans>
; DI void gemm_core(const GTile& tl, const GTile& nx, bool has_next  , bool chain  , bool pre, u32x4 (&ra)[4], u32x4 (&rb)[4], char* smem, f32x16 (&acc)[2][4]) {
;     ...
;   const int nk = K / 64;
;   if (!pre) { G_LOAD(0); G_STORE(0); G_LOAD(1); }
;   for (int kt = 0; kt < nk; ++kt) {
;     __syncthreads();
;     G_COMPUTE(kt & 1, kt);
;   }
	s_waitcnt vmcnt(7)
	ds_write_b128 v192, v[176:179]
	s_waitcnt vmcnt(6)
	ds_write_b128 v159, v[180:183]
	ds_read_b128 v[176:179], v152 offset:36864
	ds_read_b128 v[180:183], v152 offset:41472
	v_mfma_f32_32x32x16_bf16 v[80:95], v[194:197], v[208:211], v[80:95]
	v_mfma_f32_32x32x16_bf16 v[16:31], v[198:201], v[208:211], v[16:31]
	ds_read_b128 v[208:211], v151
	v_mfma_f32_32x32x16_bf16 v[64:79], v[194:197], v[212:215], v[64:79]
	v_mfma_f32_32x32x16_bf16 v[0:15], v[198:201], v[212:215], v[0:15]
	ds_read_b128 v[212:215], v151 offset:4608
	s_setprio 0
	global_load_dwordx4 v[194:197], v[136:137], off offset:3328
	global_load_dwordx4 v[198:201], v[138:139], off offset:3328
	s_setprio 1
	s_waitcnt lgkmcnt(1)
	v_mfma_f32_32x32x16_bf16 v[112:127], v[176:179], v[208:211], v[112:127]
	v_mfma_f32_32x32x16_bf16 v[48:63], v[180:183], v[208:211], v[48:63]
	s_waitcnt lgkmcnt(0)
	v_mfma_f32_32x32x16_bf16 v[96:111], v[176:179], v[212:215], v[96:111]
	v_mfma_f32_32x32x16_bf16 v[32:47], v[180:183], v[212:215], v[32:47]
	ds_read_b128 v[208:211], v151 offset:9216
	ds_read_b128 v[212:215], v151 offset:13824
	s_waitcnt vmcnt(7)
	ds_write_b128 v158, v[168:171]
	s_waitcnt vmcnt(6)
	ds_write_b128 v157, v[172:175]
	ds_read_b128 v[168:171], v152 offset:36896
	ds_read_b128 v[172:175], v152 offset:41504
	s_waitcnt lgkmcnt(5)
	v_mfma_f32_32x32x16_bf16 v[80:95], v[176:179], v[208:211], v[80:95]
	v_mfma_f32_32x32x16_bf16 v[16:31], v[180:183], v[208:211], v[16:31]
	ds_read_b128 v[208:211], v151 offset:32
	s_waitcnt lgkmcnt(5)
	v_mfma_f32_32x32x16_bf16 v[64:79], v[176:179], v[212:215], v[64:79]
	v_mfma_f32_32x32x16_bf16 v[0:15], v[180:183], v[212:215], v[0:15]
	ds_read_b128 v[212:215], v151 offset:4640
	s_setprio 0
	global_load_dwordx4 v[176:179], v[140:141], off offset:3328
	global_load_dwordx4 v[180:183], v[142:143], off offset:3328
	s_setprio 1
	s_waitcnt lgkmcnt(1)
	v_mfma_f32_32x32x16_bf16 v[112:127], v[168:171], v[208:211], v[112:127]
	v_mfma_f32_32x32x16_bf16 v[48:63], v[172:175], v[208:211], v[48:63]
	s_waitcnt lgkmcnt(0)
	v_mfma_f32_32x32x16_bf16 v[96:111], v[168:171], v[212:215], v[96:111]
	v_mfma_f32_32x32x16_bf16 v[32:47], v[172:175], v[212:215], v[32:47]
	ds_read_b128 v[208:211], v151 offset:9248
	ds_read_b128 v[212:215], v151 offset:13856
	s_waitcnt vmcnt(7)
	ds_write_b128 v154, v[160:163]
	s_waitcnt vmcnt(6)
	ds_write_b128 v153, v[164:167]
	ds_read_b128 v[160:163], v152 offset:36928
	ds_read_b128 v[164:167], v152 offset:41536
	s_waitcnt lgkmcnt(5)
	v_mfma_f32_32x32x16_bf16 v[80:95], v[168:171], v[208:211], v[80:95]
	v_mfma_f32_32x32x16_bf16 v[16:31], v[172:175], v[208:211], v[16:31]
	ds_read_b128 v[208:211], v151 offset:64
	s_waitcnt lgkmcnt(5)
	v_mfma_f32_32x32x16_bf16 v[64:79], v[168:171], v[212:215], v[64:79]
	v_mfma_f32_32x32x16_bf16 v[0:15], v[172:175], v[212:215], v[0:15]
	ds_read_b128 v[212:215], v151 offset:4672
	s_setprio 0
	global_load_dwordx4 v[168:171], v[132:133], off offset:3328
	global_load_dwordx4 v[172:175], v[134:135], off offset:3328
	s_setprio 1
	s_waitcnt lgkmcnt(1)
	v_mfma_f32_32x32x16_bf16 v[112:127], v[160:163], v[208:211], v[112:127]
	v_mfma_f32_32x32x16_bf16 v[48:63], v[164:167], v[208:211], v[48:63]
	s_waitcnt lgkmcnt(0)
	v_mfma_f32_32x32x16_bf16 v[96:111], v[160:163], v[212:215], v[96:111]
	v_mfma_f32_32x32x16_bf16 v[32:47], v[164:167], v[212:215], v[32:47]
	ds_read_b128 v[208:211], v151 offset:9280
	ds_read_b128 v[212:215], v151 offset:13888
	s_waitcnt vmcnt(7)
	ds_write_b128 v156, v[184:187]
	s_waitcnt vmcnt(6)
	ds_write_b128 v155, v[188:191]
	ds_read_b128 v[184:187], v152 offset:36960
	ds_read_b128 v[188:191], v152 offset:41568
	s_waitcnt lgkmcnt(5)
	v_mfma_f32_32x32x16_bf16 v[80:95], v[160:163], v[208:211], v[80:95]
	v_mfma_f32_32x32x16_bf16 v[16:31], v[164:167], v[208:211], v[16:31]
	ds_read_b128 v[208:211], v151 offset:96
	s_waitcnt lgkmcnt(5)
	v_mfma_f32_32x32x16_bf16 v[64:79], v[160:163], v[212:215], v[64:79]
	v_mfma_f32_32x32x16_bf16 v[0:15], v[164:167], v[212:215], v[0:15]
	ds_read_b128 v[212:215], v151 offset:4704
	s_setprio 0
	global_load_dwordx4 v[160:163], v[144:145], off offset:3328
	global_load_dwordx4 v[164:167], v[146:147], off offset:3328
	s_setprio 1
	s_waitcnt lgkmcnt(1)
	v_mfma_f32_32x32x16_bf16 v[112:127], v[184:187], v[208:211], v[112:127]
	v_mfma_f32_32x32x16_bf16 v[48:63], v[188:191], v[208:211], v[48:63]
	s_waitcnt lgkmcnt(0)
	v_mfma_f32_32x32x16_bf16 v[96:111], v[184:187], v[212:215], v[96:111]
	v_mfma_f32_32x32x16_bf16 v[32:47], v[188:191], v[212:215], v[32:47]
	ds_read_b128 v[208:211], v151 offset:9312
	ds_read_b128 v[212:215], v151 offset:13920
	s_waitcnt lgkmcnt(0)
	s_barrier
; template <bool trans>
; DI void gemm_core(const GTile& tl, const GTile& nx, bool has_next  , bool chain  , bool pre, u32x4 (&ra)[4], u32x4 (&rb)[4], char* smem, f32x16 (&acc)[2][4]) {
;     ...
;   const int nk = K / 64;
;   if (!pre) { G_LOAD(0); G_STORE(0); G_LOAD(1); }
;   for (int kt = 0; kt < nk; ++kt) {
;     __syncthreads();
;     G_COMPUTE(kt & 1, kt);
;   }
	s_waitcnt vmcnt(7)
	ds_write_b128 v148, v[194:197]
	s_waitcnt vmcnt(6)
	ds_write_b128 v148, v[198:201] offset:36864
	ds_read_b128 v[194:197], v150
	ds_read_b128 v[198:201], v150 offset:4608
	v_mfma_f32_32x32x16_bf16 v[80:95], v[184:187], v[208:211], v[80:95]
	v_mfma_f32_32x32x16_bf16 v[16:31], v[188:191], v[208:211], v[16:31]
	ds_read_b128 v[208:211], v149
	v_mfma_f32_32x32x16_bf16 v[64:79], v[184:187], v[212:215], v[64:79]
	v_mfma_f32_32x32x16_bf16 v[0:15], v[188:191], v[212:215], v[0:15]
	ds_read_b128 v[212:215], v149 offset:4608
	s_setprio 0
	global_load_dwordx4 v[184:187], v[136:137], off offset:3456
	global_load_dwordx4 v[188:191], v[138:139], off offset:3456
	s_setprio 1
	s_waitcnt lgkmcnt(1)
	v_mfma_f32_32x32x16_bf16 v[112:127], v[194:197], v[208:211], v[112:127]
	v_mfma_f32_32x32x16_bf16 v[48:63], v[198:201], v[208:211], v[48:63]
	s_waitcnt lgkmcnt(0)
	v_mfma_f32_32x32x16_bf16 v[96:111], v[194:197], v[212:215], v[96:111]
	v_mfma_f32_32x32x16_bf16 v[32:47], v[198:201], v[212:215], v[32:47]
	ds_read_b128 v[208:211], v149 offset:9216
	ds_read_b128 v[212:215], v149 offset:13824
	s_waitcnt vmcnt(7)
	ds_write_b128 v148, v[176:179] offset:9216
	s_waitcnt vmcnt(6)
	ds_write_b128 v148, v[180:183] offset:46080
	ds_read_b128 v[176:179], v150 offset:32
	ds_read_b128 v[180:183], v150 offset:4640
	s_waitcnt lgkmcnt(5)
	v_mfma_f32_32x32x16_bf16 v[80:95], v[194:197], v[208:211], v[80:95]
	v_mfma_f32_32x32x16_bf16 v[16:31], v[198:201], v[208:211], v[16:31]
	ds_read_b128 v[208:211], v149 offset:32
	s_waitcnt lgkmcnt(5)
	v_mfma_f32_32x32x16_bf16 v[64:79], v[194:197], v[212:215], v[64:79]
	v_mfma_f32_32x32x16_bf16 v[0:15], v[198:201], v[212:215], v[0:15]
	ds_read_b128 v[212:215], v149 offset:4640
	s_setprio 0
	global_load_dwordx4 v[194:197], v[140:141], off offset:3456
	global_load_dwordx4 v[198:201], v[142:143], off offset:3456
	s_setprio 1
	s_waitcnt lgkmcnt(1)
	v_mfma_f32_32x32x16_bf16 v[112:127], v[176:179], v[208:211], v[112:127]
	v_mfma_f32_32x32x16_bf16 v[48:63], v[180:183], v[208:211], v[48:63]
	s_waitcnt lgkmcnt(0)
	v_mfma_f32_32x32x16_bf16 v[96:111], v[176:179], v[212:215], v[96:111]
	v_mfma_f32_32x32x16_bf16 v[32:47], v[180:183], v[212:215], v[32:47]
	ds_read_b128 v[208:211], v149 offset:9248
	ds_read_b128 v[212:215], v149 offset:13856
	s_waitcnt vmcnt(7)
	ds_write_b128 v148, v[168:171] offset:18432
	s_waitcnt vmcnt(6)
	ds_write_b128 v148, v[172:175] offset:55296
	ds_read_b128 v[168:171], v150 offset:64
	ds_read_b128 v[172:175], v150 offset:4672
	s_waitcnt lgkmcnt(5)
	v_mfma_f32_32x32x16_bf16 v[80:95], v[176:179], v[208:211], v[80:95]
	v_mfma_f32_32x32x16_bf16 v[16:31], v[180:183], v[208:211], v[16:31]
	ds_read_b128 v[208:211], v149 offset:64
	s_waitcnt lgkmcnt(5)
	v_mfma_f32_32x32x16_bf16 v[64:79], v[176:179], v[212:215], v[64:79]
	v_mfma_f32_32x32x16_bf16 v[0:15], v[180:183], v[212:215], v[0:15]
	ds_read_b128 v[212:215], v149 offset:4672
	s_setprio 0
	global_load_dwordx4 v[176:179], v[132:133], off offset:3456
	global_load_dwordx4 v[180:183], v[134:135], off offset:3456
	s_setprio 1
	s_waitcnt lgkmcnt(1)
	v_mfma_f32_32x32x16_bf16 v[112:127], v[168:171], v[208:211], v[112:127]
	v_mfma_f32_32x32x16_bf16 v[48:63], v[172:175], v[208:211], v[48:63]
	s_waitcnt lgkmcnt(0)
	v_mfma_f32_32x32x16_bf16 v[96:111], v[168:171], v[212:215], v[96:111]
	v_mfma_f32_32x32x16_bf16 v[32:47], v[172:175], v[212:215], v[32:47]
	ds_read_b128 v[208:211], v149 offset:9280
	ds_read_b128 v[212:215], v149 offset:13888
	s_waitcnt vmcnt(7)
	ds_write_b128 v148, v[160:163] offset:27648
	s_waitcnt vmcnt(6)
	ds_write_b128 v148, v[164:167] offset:64512
	ds_read_b128 v[160:163], v150 offset:96
	ds_read_b128 v[164:167], v150 offset:4704
	s_waitcnt lgkmcnt(5)
	v_mfma_f32_32x32x16_bf16 v[80:95], v[168:171], v[208:211], v[80:95]
	v_mfma_f32_32x32x16_bf16 v[16:31], v[172:175], v[208:211], v[16:31]
	ds_read_b128 v[208:211], v149 offset:96
	s_waitcnt lgkmcnt(5)
	v_mfma_f32_32x32x16_bf16 v[64:79], v[168:171], v[212:215], v[64:79]
	v_mfma_f32_32x32x16_bf16 v[0:15], v[172:175], v[212:215], v[0:15]
	ds_read_b128 v[212:215], v149 offset:4704
	s_setprio 0
	global_load_dwordx4 v[168:171], v[144:145], off offset:3456
	global_load_dwordx4 v[172:175], v[146:147], off offset:3456
	s_setprio 1
	s_waitcnt lgkmcnt(1)
	v_mfma_f32_32x32x16_bf16 v[112:127], v[160:163], v[208:211], v[112:127]
	v_mfma_f32_32x32x16_bf16 v[48:63], v[164:167], v[208:211], v[48:63]
	s_waitcnt lgkmcnt(0)
	v_mfma_f32_32x32x16_bf16 v[96:111], v[160:163], v[212:215], v[96:111]
	v_mfma_f32_32x32x16_bf16 v[32:47], v[164:167], v[212:215], v[32:47]
	ds_read_b128 v[208:211], v149 offset:9312
	ds_read_b128 v[212:215], v149 offset:13920
	s_waitcnt lgkmcnt(0)
	s_barrier
; template <bool trans>
; DI void gemm_core(const GTile& tl, const GTile& nx, bool has_next  , bool chain  , bool pre, u32x4 (&ra)[4], u32x4 (&rb)[4], char* smem, f32x16 (&acc)[2][4]) {
;     ...
;   const int nk = K / 64;
;   if (!pre) { G_LOAD(0); G_STORE(0); G_LOAD(1); }
;   for (int kt = 0; kt < nk; ++kt) {
;     __syncthreads();
;     G_COMPUTE(kt & 1, kt);
;   }
	s_waitcnt vmcnt(7)
	ds_write_b128 v192, v[184:187]
	s_waitcnt vmcnt(6)
	ds_write_b128 v159, v[188:191]
	ds_read_b128 v[184:187], v152 offset:36864
	ds_read_b128 v[188:191], v152 offset:41472
	v_mfma_f32_32x32x16_bf16 v[80:95], v[160:163], v[208:211], v[80:95]
	v_mfma_f32_32x32x16_bf16 v[16:31], v[164:167], v[208:211], v[16:31]
	ds_read_b128 v[208:211], v151
	v_mfma_f32_32x32x16_bf16 v[64:79], v[160:163], v[212:215], v[64:79]
	v_mfma_f32_32x32x16_bf16 v[0:15], v[164:167], v[212:215], v[0:15]
	ds_read_b128 v[212:215], v151 offset:4608
	s_setprio 0
	global_load_dwordx4 v[160:163], v[136:137], off offset:3584
	global_load_dwordx4 v[164:167], v[138:139], off offset:3584
	s_setprio 1
	s_waitcnt lgkmcnt(1)
	v_mfma_f32_32x32x16_bf16 v[112:127], v[184:187], v[208:211], v[112:127]
	v_mfma_f32_32x32x16_bf16 v[48:63], v[188:191], v[208:211], v[48:63]
	s_waitcnt lgkmcnt(0)
	v_mfma_f32_32x32x16_bf16 v[96:111], v[184:187], v[212:215], v[96:111]
	v_mfma_f32_32x32x16_bf16 v[32:47], v[188:191], v[212:215], v[32:47]
	ds_read_b128 v[208:211], v151 offset:9216
	ds_read_b128 v[212:215], v151 offset:13824
	s_waitcnt vmcnt(7)
	ds_write_b128 v158, v[194:197]
	s_waitcnt vmcnt(6)
	ds_write_b128 v157, v[198:201]
	ds_read_b128 v[194:197], v152 offset:36896
	ds_read_b128 v[198:201], v152 offset:41504
	s_waitcnt lgkmcnt(5)
	v_mfma_f32_32x32x16_bf16 v[80:95], v[184:187], v[208:211], v[80:95]
	v_mfma_f32_32x32x16_bf16 v[16:31], v[188:191], v[208:211], v[16:31]
	ds_read_b128 v[208:211], v151 offset:32
	s_waitcnt lgkmcnt(5)
	v_mfma_f32_32x32x16_bf16 v[64:79], v[184:187], v[212:215], v[64:79]
	v_mfma_f32_32x32x16_bf16 v[0:15], v[188:191], v[212:215], v[0:15]
	ds_read_b128 v[212:215], v151 offset:4640
	s_setprio 0
	global_load_dwordx4 v[184:187], v[140:141], off offset:3584
	global_load_dwordx4 v[188:191], v[142:143], off offset:3584
	s_setprio 1
	s_waitcnt lgkmcnt(1)
	v_mfma_f32_32x32x16_bf16 v[112:127], v[194:197], v[208:211], v[112:127]
	v_mfma_f32_32x32x16_bf16 v[48:63], v[198:201], v[208:211], v[48:63]
	s_waitcnt lgkmcnt(0)
	v_mfma_f32_32x32x16_bf16 v[96:111], v[194:197], v[212:215], v[96:111]
	v_mfma_f32_32x32x16_bf16 v[32:47], v[198:201], v[212:215], v[32:47]
	ds_read_b128 v[208:211], v151 offset:9248
	ds_read_b128 v[212:215], v151 offset:13856
	s_waitcnt vmcnt(7)
	ds_write_b128 v154, v[176:179]
	s_waitcnt vmcnt(6)
	ds_write_b128 v153, v[180:183]
	ds_read_b128 v[176:179], v152 offset:36928
	ds_read_b128 v[180:183], v152 offset:41536
	s_waitcnt lgkmcnt(5)
	v_mfma_f32_32x32x16_bf16 v[80:95], v[194:197], v[208:211], v[80:95]
	v_mfma_f32_32x32x16_bf16 v[16:31], v[198:201], v[208:211], v[16:31]
	ds_read_b128 v[208:211], v151 offset:64
	s_waitcnt lgkmcnt(5)
	v_mfma_f32_32x32x16_bf16 v[64:79], v[194:197], v[212:215], v[64:79]
	v_mfma_f32_32x32x16_bf16 v[0:15], v[198:201], v[212:215], v[0:15]
	ds_read_b128 v[212:215], v151 offset:4672
	s_setprio 0
	global_load_dwordx4 v[194:197], v[132:133], off offset:3584
	global_load_dwordx4 v[198:201], v[134:135], off offset:3584
	s_setprio 1
	s_waitcnt lgkmcnt(1)
	v_mfma_f32_32x32x16_bf16 v[112:127], v[176:179], v[208:211], v[112:127]
	v_mfma_f32_32x32x16_bf16 v[48:63], v[180:183], v[208:211], v[48:63]
	s_waitcnt lgkmcnt(0)
	v_mfma_f32_32x32x16_bf16 v[96:111], v[176:179], v[212:215], v[96:111]
	v_mfma_f32_32x32x16_bf16 v[32:47], v[180:183], v[212:215], v[32:47]
	ds_read_b128 v[208:211], v151 offset:9280
	ds_read_b128 v[212:215], v151 offset:13888
	s_waitcnt vmcnt(7)
	ds_write_b128 v156, v[168:171]
	s_waitcnt vmcnt(6)
	ds_write_b128 v155, v[172:175]
	ds_read_b128 v[168:171], v152 offset:36960
	ds_read_b128 v[172:175], v152 offset:41568
	s_waitcnt lgkmcnt(5)
	v_mfma_f32_32x32x16_bf16 v[80:95], v[176:179], v[208:211], v[80:95]
	v_mfma_f32_32x32x16_bf16 v[16:31], v[180:183], v[208:211], v[16:31]
	ds_read_b128 v[208:211], v151 offset:96
	s_waitcnt lgkmcnt(5)
	v_mfma_f32_32x32x16_bf16 v[64:79], v[176:179], v[212:215], v[64:79]
	v_mfma_f32_32x32x16_bf16 v[0:15], v[180:183], v[212:215], v[0:15]
	ds_read_b128 v[212:215], v151 offset:4704
	s_setprio 0
	global_load_dwordx4 v[176:179], v[144:145], off offset:3584
	global_load_dwordx4 v[180:183], v[146:147], off offset:3584
	s_setprio 1
	s_waitcnt lgkmcnt(1)
	v_mfma_f32_32x32x16_bf16 v[112:127], v[168:171], v[208:211], v[112:127]
	v_mfma_f32_32x32x16_bf16 v[48:63], v[172:175], v[208:211], v[48:63]
	s_waitcnt lgkmcnt(0)
	v_mfma_f32_32x32x16_bf16 v[96:111], v[168:171], v[212:215], v[96:111]
	v_mfma_f32_32x32x16_bf16 v[32:47], v[172:175], v[212:215], v[32:47]
	ds_read_b128 v[208:211], v151 offset:9312
	ds_read_b128 v[212:215], v151 offset:13920
	s_waitcnt lgkmcnt(0)
	s_barrier
; template <bool trans>
; DI void gemm_core(const GTile& tl, const GTile& nx, bool has_next  , bool chain  , bool pre, u32x4 (&ra)[4], u32x4 (&rb)[4], char* smem, f32x16 (&acc)[2][4]) {
;     ...
;   const int nk = K / 64;
;   if (!pre) { G_LOAD(0); G_STORE(0); G_LOAD(1); }
;   for (int kt = 0; kt < nk; ++kt) {
;     __syncthreads();
;     G_COMPUTE(kt & 1, kt);
;   }
	s_waitcnt vmcnt(7)
	ds_write_b128 v148, v[160:163]
	s_waitcnt vmcnt(6)
	ds_write_b128 v148, v[164:167] offset:36864
	ds_read_b128 v[160:163], v150
	ds_read_b128 v[164:167], v150 offset:4608
	v_mfma_f32_32x32x16_bf16 v[80:95], v[168:171], v[208:211], v[80:95]
	v_mfma_f32_32x32x16_bf16 v[16:31], v[172:175], v[208:211], v[16:31]
	ds_read_b128 v[208:211], v149
	v_mfma_f32_32x32x16_bf16 v[64:79], v[168:171], v[212:215], v[64:79]
	v_mfma_f32_32x32x16_bf16 v[0:15], v[172:175], v[212:215], v[0:15]
	ds_read_b128 v[212:215], v149 offset:4608
	s_setprio 0
	global_load_dwordx4 v[168:171], v[136:137], off offset:3712
	global_load_dwordx4 v[172:175], v[138:139], off offset:3712
	s_setprio 1
	s_waitcnt lgkmcnt(1)
	v_mfma_f32_32x32x16_bf16 v[112:127], v[160:163], v[208:211], v[112:127]
	v_mfma_f32_32x32x16_bf16 v[48:63], v[164:167], v[208:211], v[48:63]
	s_waitcnt lgkmcnt(0)
	v_mfma_f32_32x32x16_bf16 v[96:111], v[160:163], v[212:215], v[96:111]
	v_mfma_f32_32x32x16_bf16 v[32:47], v[164:167], v[212:215], v[32:47]
	ds_read_b128 v[208:211], v149 offset:9216
	ds_read_b128 v[212:215], v149 offset:13824
	s_waitcnt vmcnt(7)
	ds_write_b128 v148, v[184:187] offset:9216
	s_waitcnt vmcnt(6)
	ds_write_b128 v148, v[188:191] offset:46080
	ds_read_b128 v[184:187], v150 offset:32
	ds_read_b128 v[188:191], v150 offset:4640
	s_waitcnt lgkmcnt(5)
	v_mfma_f32_32x32x16_bf16 v[80:95], v[160:163], v[208:211], v[80:95]
	v_mfma_f32_32x32x16_bf16 v[16:31], v[164:167], v[208:211], v[16:31]
	ds_read_b128 v[208:211], v149 offset:32
	s_waitcnt lgkmcnt(5)
	v_mfma_f32_32x32x16_bf16 v[64:79], v[160:163], v[212:215], v[64:79]
	v_mfma_f32_32x32x16_bf16 v[0:15], v[164:167], v[212:215], v[0:15]
	ds_read_b128 v[212:215], v149 offset:4640
	s_setprio 0
	global_load_dwordx4 v[160:163], v[140:141], off offset:3712
	global_load_dwordx4 v[164:167], v[142:143], off offset:3712
	s_setprio 1
	s_waitcnt lgkmcnt(1)
	v_mfma_f32_32x32x16_bf16 v[112:127], v[184:187], v[208:211], v[112:127]
	v_mfma_f32_32x32x16_bf16 v[48:63], v[188:191], v[208:211], v[48:63]
	s_waitcnt lgkmcnt(0)
	v_mfma_f32_32x32x16_bf16 v[96:111], v[184:187], v[212:215], v[96:111]
	v_mfma_f32_32x32x16_bf16 v[32:47], v[188:191], v[212:215], v[32:47]
	ds_read_b128 v[208:211], v149 offset:9248
	ds_read_b128 v[212:215], v149 offset:13856
	s_waitcnt vmcnt(7)
	ds_write_b128 v148, v[194:197] offset:18432
	s_waitcnt vmcnt(6)
	ds_write_b128 v148, v[198:201] offset:55296
	ds_read_b128 v[194:197], v150 offset:64
	ds_read_b128 v[198:201], v150 offset:4672
	s_waitcnt lgkmcnt(5)
	v_mfma_f32_32x32x16_bf16 v[80:95], v[184:187], v[208:211], v[80:95]
	v_mfma_f32_32x32x16_bf16 v[16:31], v[188:191], v[208:211], v[16:31]
	ds_read_b128 v[208:211], v149 offset:64
	s_waitcnt lgkmcnt(5)
	v_mfma_f32_32x32x16_bf16 v[64:79], v[184:187], v[212:215], v[64:79]
	v_mfma_f32_32x32x16_bf16 v[0:15], v[188:191], v[212:215], v[0:15]
	ds_read_b128 v[212:215], v149 offset:4672
	s_setprio 0
	global_load_dwordx4 v[184:187], v[132:133], off offset:3712
	global_load_dwordx4 v[188:191], v[134:135], off offset:3712
	s_setprio 1
	s_waitcnt lgkmcnt(1)
	v_mfma_f32_32x32x16_bf16 v[112:127], v[194:197], v[208:211], v[112:127]
	v_mfma_f32_32x32x16_bf16 v[48:63], v[198:201], v[208:211], v[48:63]
	s_waitcnt lgkmcnt(0)
	v_mfma_f32_32x32x16_bf16 v[96:111], v[194:197], v[212:215], v[96:111]
	v_mfma_f32_32x32x16_bf16 v[32:47], v[198:201], v[212:215], v[32:47]
	ds_read_b128 v[208:211], v149 offset:9280
	ds_read_b128 v[212:215], v149 offset:13888
	s_waitcnt vmcnt(7)
	ds_write_b128 v148, v[176:179] offset:27648
	s_waitcnt vmcnt(6)
	ds_write_b128 v148, v[180:183] offset:64512
	ds_read_b128 v[176:179], v150 offset:96
	ds_read_b128 v[180:183], v150 offset:4704
	s_waitcnt lgkmcnt(5)
	v_mfma_f32_32x32x16_bf16 v[80:95], v[194:197], v[208:211], v[80:95]
	v_mfma_f32_32x32x16_bf16 v[16:31], v[198:201], v[208:211], v[16:31]
	ds_read_b128 v[208:211], v149 offset:96
	s_waitcnt lgkmcnt(5)
	v_mfma_f32_32x32x16_bf16 v[64:79], v[194:197], v[212:215], v[64:79]
	v_mfma_f32_32x32x16_bf16 v[0:15], v[198:201], v[212:215], v[0:15]
	ds_read_b128 v[212:215], v149 offset:4704
	s_setprio 0
	global_load_dwordx4 v[194:197], v[144:145], off offset:3712
	global_load_dwordx4 v[198:201], v[146:147], off offset:3712
	s_setprio 1
	s_waitcnt lgkmcnt(1)
	v_mfma_f32_32x32x16_bf16 v[112:127], v[176:179], v[208:211], v[112:127]
	v_mfma_f32_32x32x16_bf16 v[48:63], v[180:183], v[208:211], v[48:63]
	s_waitcnt lgkmcnt(0)
	v_mfma_f32_32x32x16_bf16 v[96:111], v[176:179], v[212:215], v[96:111]
	v_mfma_f32_32x32x16_bf16 v[32:47], v[180:183], v[212:215], v[32:47]
	ds_read_b128 v[208:211], v149 offset:9312
	ds_read_b128 v[212:215], v149 offset:13920
	s_waitcnt lgkmcnt(0)
	s_barrier
; template <bool trans>
; DI void gemm_core(const GTile& tl, const GTile& nx, bool has_next  , bool chain  , bool pre, u32x4 (&ra)[4], u32x4 (&rb)[4], char* smem, f32x16 (&acc)[2][4]) {
;     ...
;   const int nk = K / 64;
;   if (!pre) { G_LOAD(0); G_STORE(0); G_LOAD(1); }
;   for (int kt = 0; kt < nk; ++kt) {
;     __syncthreads();
;     G_COMPUTE(kt & 1, kt);
;   }
	s_waitcnt vmcnt(7)
	ds_write_b128 v192, v[168:171]
	s_waitcnt vmcnt(6)
	ds_write_b128 v159, v[172:175]
	ds_read_b128 v[168:171], v152 offset:36864
	ds_read_b128 v[172:175], v152 offset:41472
	v_mfma_f32_32x32x16_bf16 v[80:95], v[176:179], v[208:211], v[80:95]
	v_mfma_f32_32x32x16_bf16 v[16:31], v[180:183], v[208:211], v[16:31]
	ds_read_b128 v[208:211], v151
	v_mfma_f32_32x32x16_bf16 v[64:79], v[176:179], v[212:215], v[64:79]
	v_mfma_f32_32x32x16_bf16 v[0:15], v[180:183], v[212:215], v[0:15]
	ds_read_b128 v[212:215], v151 offset:4608
	s_setprio 0
	global_load_dwordx4 v[176:179], v[136:137], off offset:3840
	global_load_dwordx4 v[180:183], v[138:139], off offset:3840
	s_setprio 1
	s_waitcnt lgkmcnt(1)
	v_mfma_f32_32x32x16_bf16 v[112:127], v[168:171], v[208:211], v[112:127]
	v_mfma_f32_32x32x16_bf16 v[48:63], v[172:175], v[208:211], v[48:63]
	s_waitcnt lgkmcnt(0)
	v_mfma_f32_32x32x16_bf16 v[96:111], v[168:171], v[212:215], v[96:111]
	v_mfma_f32_32x32x16_bf16 v[32:47], v[172:175], v[212:215], v[32:47]
	ds_read_b128 v[208:211], v151 offset:9216
	ds_read_b128 v[212:215], v151 offset:13824
	s_waitcnt lgkmcnt(1)
	v_mfma_f32_32x32x16_bf16 v[80:95], v[168:171], v[208:211], v[80:95]
	v_mfma_f32_32x32x16_bf16 v[16:31], v[172:175], v[208:211], v[16:31]
	s_waitcnt lgkmcnt(0)
	v_mfma_f32_32x32x16_bf16 v[64:79], v[168:171], v[212:215], v[64:79]
	v_mfma_f32_32x32x16_bf16 v[0:15], v[172:175], v[212:215], v[0:15]
	s_setprio 0
	global_load_dwordx4 v[208:211], v[140:141], off offset:3840
	global_load_dwordx4 v[212:215], v[142:143], off offset:3840
	s_waitcnt vmcnt(9)
	ds_write_b128 v158, v[160:163]
	s_waitcnt vmcnt(8)
	ds_write_b128 v157, v[164:167]
	ds_read_b128 v[160:163], v152 offset:36896
	ds_read_b128 v[164:167], v152 offset:41504
	ds_read_b128 v[168:171], v151 offset:32
	ds_read_b128 v[172:175], v151 offset:4640
	s_setprio 1
	s_waitcnt lgkmcnt(1)
	v_mfma_f32_32x32x16_bf16 v[112:127], v[160:163], v[168:171], v[112:127]
	v_mfma_f32_32x32x16_bf16 v[48:63], v[164:167], v[168:171], v[48:63]
	s_waitcnt lgkmcnt(0)
	v_mfma_f32_32x32x16_bf16 v[96:111], v[160:163], v[172:175], v[96:111]
	v_mfma_f32_32x32x16_bf16 v[32:47], v[164:167], v[172:175], v[32:47]
	ds_read_b128 v[168:171], v151 offset:9248
	ds_read_b128 v[172:175], v151 offset:13856
	s_waitcnt lgkmcnt(1)
	v_mfma_f32_32x32x16_bf16 v[80:95], v[160:163], v[168:171], v[80:95]
	v_mfma_f32_32x32x16_bf16 v[16:31], v[164:167], v[168:171], v[16:31]
	s_waitcnt lgkmcnt(0)
	v_mfma_f32_32x32x16_bf16 v[64:79], v[160:163], v[172:175], v[64:79]
	v_mfma_f32_32x32x16_bf16 v[0:15], v[164:167], v[172:175], v[0:15]
	s_setprio 0
	global_load_dwordx4 v[216:219], v[132:133], off offset:3840
	global_load_dwordx4 v[220:223], v[134:135], off offset:3840
	s_waitcnt vmcnt(9)
	ds_write_b128 v154, v[184:187]
	s_waitcnt vmcnt(8)
	ds_write_b128 v153, v[188:191]
	ds_read_b128 v[160:163], v152 offset:36928
	ds_read_b128 v[164:167], v152 offset:41536
	ds_read_b128 v[168:171], v151 offset:64
	ds_read_b128 v[172:175], v151 offset:4672
	s_setprio 1
	s_waitcnt lgkmcnt(1)
	v_mfma_f32_32x32x16_bf16 v[112:127], v[160:163], v[168:171], v[112:127]
	v_mfma_f32_32x32x16_bf16 v[48:63], v[164:167], v[168:171], v[48:63]
	s_waitcnt lgkmcnt(0)
	v_mfma_f32_32x32x16_bf16 v[96:111], v[160:163], v[172:175], v[96:111]
	v_mfma_f32_32x32x16_bf16 v[32:47], v[164:167], v[172:175], v[32:47]
	ds_read_b128 v[168:171], v151 offset:9280
	ds_read_b128 v[172:175], v151 offset:13888
	s_waitcnt lgkmcnt(1)
	v_mfma_f32_32x32x16_bf16 v[80:95], v[160:163], v[168:171], v[80:95]
	v_mfma_f32_32x32x16_bf16 v[16:31], v[164:167], v[168:171], v[16:31]
	s_waitcnt lgkmcnt(0)
	v_mfma_f32_32x32x16_bf16 v[64:79], v[160:163], v[172:175], v[64:79]
	v_mfma_f32_32x32x16_bf16 v[0:15], v[164:167], v[172:175], v[0:15]
	s_setprio 0
	global_load_dwordx4 v[224:227], v[144:145], off offset:3840
	global_load_dwordx4 v[228:231], v[146:147], off offset:3840
	s_waitcnt vmcnt(9)
	ds_write_b128 v156, v[194:197]
	s_waitcnt vmcnt(8)
	ds_write_b128 v155, v[198:201]
	ds_read_b128 v[160:163], v152 offset:36960
	ds_read_b128 v[164:167], v152 offset:41568
	ds_read_b128 v[168:171], v151 offset:96
	ds_read_b128 v[172:175], v151 offset:4704
	s_setprio 1
	s_waitcnt lgkmcnt(1)
	v_mfma_f32_32x32x16_bf16 v[112:127], v[160:163], v[168:171], v[112:127]
	v_mfma_f32_32x32x16_bf16 v[48:63], v[164:167], v[168:171], v[48:63]
	s_waitcnt lgkmcnt(0)
	v_mfma_f32_32x32x16_bf16 v[96:111], v[160:163], v[172:175], v[96:111]
	v_mfma_f32_32x32x16_bf16 v[32:47], v[164:167], v[172:175], v[32:47]
	ds_read_b128 v[168:171], v151 offset:9312
	ds_read_b128 v[172:175], v151 offset:13920
	s_waitcnt lgkmcnt(1)
	v_mfma_f32_32x32x16_bf16 v[80:95], v[160:163], v[168:171], v[80:95]
	v_mfma_f32_32x32x16_bf16 v[16:31], v[164:167], v[168:171], v[16:31]
	s_waitcnt lgkmcnt(0)
	v_mfma_f32_32x32x16_bf16 v[64:79], v[160:163], v[172:175], v[64:79]
	v_mfma_f32_32x32x16_bf16 v[0:15], v[164:167], v[172:175], v[0:15]
	s_setprio 0
	global_load_dwordx4 v[160:163], v[136:137], off offset:3968
	global_load_dwordx4 v[164:167], v[138:139], off offset:3968
	s_barrier
; template <bool trans>
; DI void gemm_core(const GTile& tl, const GTile& nx, bool has_next  , bool chain  , bool pre, u32x4 (&ra)[4], u32x4 (&rb)[4], char* smem, f32x16 (&acc)[2][4]) {
;     ...
;   const int nk = K / 64;
;   if (!pre) { G_LOAD(0); G_STORE(0); G_LOAD(1); }
;   for (int kt = 0; kt < nk; ++kt) {
;     __syncthreads();
;     G_COMPUTE(kt & 1, kt);
;   }
	s_waitcnt vmcnt(9)
	ds_write_b128 v148, v[176:179]
	s_waitcnt vmcnt(8)
	ds_write_b128 v148, v[180:183] offset:36864
	ds_read_b128 v[136:139], v150
	ds_read_b128 v[168:171], v150 offset:4608
	ds_read_b128 v[172:175], v149
	ds_read_b128 v[176:179], v149 offset:4608
	s_setprio 1
	s_waitcnt lgkmcnt(1)
	v_mfma_f32_32x32x16_bf16 v[112:127], v[136:139], v[172:175], v[112:127]
	v_mfma_f32_32x32x16_bf16 v[48:63], v[168:171], v[172:175], v[48:63]
	s_waitcnt lgkmcnt(0)
	v_mfma_f32_32x32x16_bf16 v[96:111], v[136:139], v[176:179], v[96:111]
	v_mfma_f32_32x32x16_bf16 v[32:47], v[168:171], v[176:179], v[32:47]
	ds_read_b128 v[172:175], v149 offset:9216
	ds_read_b128 v[176:179], v149 offset:13824
	s_waitcnt lgkmcnt(1)
	v_mfma_f32_32x32x16_bf16 v[80:95], v[136:139], v[172:175], v[80:95]
	v_mfma_f32_32x32x16_bf16 v[16:31], v[168:171], v[172:175], v[16:31]
	s_waitcnt lgkmcnt(0)
	v_mfma_f32_32x32x16_bf16 v[64:79], v[136:139], v[176:179], v[64:79]
	v_mfma_f32_32x32x16_bf16 v[0:15], v[168:171], v[176:179], v[0:15]
	s_setprio 0
	global_load_dwordx4 v[168:171], v[140:141], off offset:3968
	global_load_dwordx4 v[172:175], v[142:143], off offset:3968
	s_waitcnt vmcnt(9)
	ds_write_b128 v148, v[208:211] offset:9216
	s_waitcnt vmcnt(8)
	ds_write_b128 v148, v[212:215] offset:46080
	ds_read_b128 v[136:139], v150 offset:32
	ds_read_b128 v[140:143], v150 offset:4640
	ds_read_b128 v[176:179], v149 offset:32
	ds_read_b128 v[180:183], v149 offset:4640
	s_setprio 1
	s_waitcnt lgkmcnt(1)
	v_mfma_f32_32x32x16_bf16 v[112:127], v[136:139], v[176:179], v[112:127]
	v_mfma_f32_32x32x16_bf16 v[48:63], v[140:143], v[176:179], v[48:63]
	s_waitcnt lgkmcnt(0)
	v_mfma_f32_32x32x16_bf16 v[96:111], v[136:139], v[180:183], v[96:111]
	v_mfma_f32_32x32x16_bf16 v[32:47], v[140:143], v[180:183], v[32:47]
	ds_read_b128 v[176:179], v149 offset:9248
	ds_read_b128 v[180:183], v149 offset:13856
	s_waitcnt lgkmcnt(1)
	v_mfma_f32_32x32x16_bf16 v[80:95], v[136:139], v[176:179], v[80:95]
	v_mfma_f32_32x32x16_bf16 v[16:31], v[140:143], v[176:179], v[16:31]
	s_waitcnt lgkmcnt(0)
	v_mfma_f32_32x32x16_bf16 v[64:79], v[136:139], v[180:183], v[64:79]
	v_mfma_f32_32x32x16_bf16 v[0:15], v[140:143], v[180:183], v[0:15]
	s_setprio 0
	global_load_dwordx4 v[176:179], v[132:133], off offset:3968
	global_load_dwordx4 v[180:183], v[134:135], off offset:3968
	s_waitcnt vmcnt(9)
	ds_write_b128 v148, v[216:219] offset:18432
	s_waitcnt vmcnt(8)
	ds_write_b128 v148, v[220:223] offset:55296
	ds_read_b128 v[132:135], v150 offset:64
	ds_read_b128 v[136:139], v150 offset:4672
	ds_read_b128 v[140:143], v149 offset:64
	ds_read_b128 v[184:187], v149 offset:4672
	s_setprio 1
	s_waitcnt lgkmcnt(1)
	v_mfma_f32_32x32x16_bf16 v[112:127], v[132:135], v[140:143], v[112:127]
	v_mfma_f32_32x32x16_bf16 v[48:63], v[136:139], v[140:143], v[48:63]
	s_waitcnt lgkmcnt(0)
	v_mfma_f32_32x32x16_bf16 v[96:111], v[132:135], v[184:187], v[96:111]
	v_mfma_f32_32x32x16_bf16 v[32:47], v[136:139], v[184:187], v[32:47]
	ds_read_b128 v[140:143], v149 offset:9280
	ds_read_b128 v[184:187], v149 offset:13888
	s_waitcnt lgkmcnt(1)
	v_mfma_f32_32x32x16_bf16 v[80:95], v[132:135], v[140:143], v[80:95]
	v_mfma_f32_32x32x16_bf16 v[16:31], v[136:139], v[140:143], v[16:31]
	s_waitcnt lgkmcnt(0)
	v_mfma_f32_32x32x16_bf16 v[64:79], v[132:135], v[184:187], v[64:79]
	v_mfma_f32_32x32x16_bf16 v[0:15], v[136:139], v[184:187], v[0:15]
	s_setprio 0
	global_load_dwordx4 v[184:187], v[144:145], off offset:3968
	global_load_dwordx4 v[188:191], v[146:147], off offset:3968
	s_waitcnt vmcnt(9)
	ds_write_b128 v148, v[224:227] offset:27648
	s_waitcnt vmcnt(8)
	ds_write_b128 v148, v[228:231] offset:64512
	ds_read_b128 v[132:135], v150 offset:96
	ds_read_b128 v[136:139], v150 offset:4704
	ds_read_b128 v[140:143], v149 offset:96
	ds_read_b128 v[144:147], v149 offset:4704
	s_setprio 1
	s_waitcnt lgkmcnt(1)
	v_mfma_f32_32x32x16_bf16 v[112:127], v[132:135], v[140:143], v[112:127]
	v_mfma_f32_32x32x16_bf16 v[48:63], v[136:139], v[140:143], v[48:63]
	s_waitcnt lgkmcnt(0)
	v_mfma_f32_32x32x16_bf16 v[96:111], v[132:135], v[144:147], v[96:111]
	v_mfma_f32_32x32x16_bf16 v[32:47], v[136:139], v[144:147], v[32:47]
	ds_read_b128 v[140:143], v149 offset:9312
	ds_read_b128 v[144:147], v149 offset:13920
	s_waitcnt lgkmcnt(1)
	v_mfma_f32_32x32x16_bf16 v[80:95], v[132:135], v[140:143], v[80:95]
	v_mfma_f32_32x32x16_bf16 v[16:31], v[136:139], v[140:143], v[16:31]
	s_waitcnt lgkmcnt(0)
	v_mfma_f32_32x32x16_bf16 v[64:79], v[132:135], v[144:147], v[64:79]
	v_mfma_f32_32x32x16_bf16 v[0:15], v[136:139], v[144:147], v[0:15]
	s_setprio 0
	v_cndmask_b32_e64 v132, 0, 1, s[52:53]
	v_cmp_ne_u32_e64 s[4:5], 1, v132
	s_andn2_b64 vcc, exec, s[52:53]
	s_barrier
	s_waitcnt vmcnt(7)
	ds_write_b128 v192, v[160:163]
	s_waitcnt vmcnt(6)
	ds_write_b128 v159, v[164:167]
	s_cbranch_vccnz .LBB0_113
	global_load_dwordx4 v[160:163], v[130:131], off
	global_load_dwordx4 v[164:167], v[128:129], off

; template <bool trans>
; DI void gemm_core(const GTile& tl, const GTile& nx, bool has_next  , bool chain  , bool pre, u32x4 (&ra)[4], u32x4 (&rb)[4], char* smem, f32x16 (&acc)[2][4]) {
;     ...
;   const int lrow = tid >> 3, kc = tid & 7;
;   const unsigned aoff = (unsigned)(lrow * lda + kc * 8) * 2u, boff = (unsigned)(lrow * ldb + kc * 8) * 2u;
;   const char* ag = (const char*)(A + (size_t)m0 * lda);
;   const char* bg = (const char*)(Bt + (size_t)n0 * ldb);
;   const unsigned aoffn = (unsigned)(lrow * nx.lda + kc * 8) * 2u, boffn = (unsigned)(lrow * nx.ldb + kc * 8) * 2u;
;   const char* agn = (const char*)(nx.A + (size_t)nx.m0 * nx.lda);
;   const char* bgn = (const char*)(nx.Bt + (size_t)nx.n0 * nx.ldb);
;     ...
;   const int nk = K / 64;
;   if (!pre) { G_LOAD(0); G_STORE(0); G_LOAD(1); }
;   for (int kt = 0; kt < nk; ++kt) {
;     __syncthreads();
;     G_COMPUTE(kt & 1, kt);
.LBB0_882:
	v_lshl_add_u64 v[190:191], s[2:3], 0, v[192:193]
	v_lshl_add_u64 v[188:189], s[16:17], 0, v[192:193]
	s_waitcnt lgkmcnt(0)
	s_barrier
	global_load_dwordx4 v[218:221], v[190:191], off offset:256
	global_load_dwordx4 v[222:225], v[188:189], off offset:256
	s_lshr_b32 s3, s33, 1
	s_and_b32 s2, s33, 0xc0
	v_and_b32_e32 v10, 31, v8
	s_and_b32 s3, s3, 0xfffff80
	v_or_b32_e32 v12, s3, v10
	v_or_b32_e32 v10, s2, v10
	v_add3_u32 v215, 16, v11, v9
	v_lshrrev_b32_e32 v8, 1, v8
	v_mul_u32_u24_e32 v208, 0x90, v10
	v_and_b32_e32 v242, 16, v8
	v_add_u32_e32 v209, 0x12000, v215
	v_mul_lo_u32 v205, v12, s54
	v_add3_u32 v204, 16, v208, v242
	v_add_u32_e32 v210, 0x1b000, v215
	ds_write_b128 v209, v[0:3]
	s_waitcnt vmcnt(5)
	ds_write_b128 v210, v[4:7]
	v_add3_u32 v192, 16, v205, v242
	ds_read_b128 v[0:3], v204 offset:36864
	ds_read_b128 v[4:7], v204 offset:41472
	ds_read_b128 v[8:11], v192
	ds_read_b128 v[12:15], v192 offset:4608
	v_lshl_add_u64 v[184:185], v[190:191], 0, s[14:15]
	v_lshl_add_u64 v[186:187], v[188:189], 0, s[14:15]
	v_lshl_add_u64 v[194:195], v[190:191], 0, s[12:13]
	v_lshl_add_u64 v[196:197], v[188:189], 0, s[12:13]
	s_setprio 1
	s_waitcnt lgkmcnt(1)
	v_mfma_f32_32x32x16_bf16 v[112:127], v[8:11], v[0:3], 0
	v_mfma_f32_32x32x16_bf16 v[48:63], v[8:11], v[4:7], 0
	s_waitcnt lgkmcnt(0)
	v_mfma_f32_32x32x16_bf16 v[96:111], v[12:15], v[0:3], 0
	v_mfma_f32_32x32x16_bf16 v[32:47], v[12:15], v[4:7], 0
	ds_read_b128 v[8:11], v192 offset:9216
	ds_read_b128 v[12:15], v192 offset:13824
	s_waitcnt lgkmcnt(1)
	v_mfma_f32_32x32x16_bf16 v[80:95], v[8:11], v[0:3], 0
	v_mfma_f32_32x32x16_bf16 v[16:31], v[8:11], v[4:7], 0
	s_waitcnt lgkmcnt(0)
	v_mfma_f32_32x32x16_bf16 v[64:79], v[12:15], v[0:3], 0
	v_mfma_f32_32x32x16_bf16 v[0:15], v[12:15], v[4:7], 0
	s_setprio 0
	global_load_dwordx4 v[226:229], v[194:195], off offset:256
	global_load_dwordx4 v[230:233], v[196:197], off offset:256
	v_add_u32_e32 v212, 0x14400, v215
	v_add_u32_e32 v211, 0x1d400, v215
	ds_write_b128 v212, v[176:179]
	s_waitcnt vmcnt(6)
	ds_write_b128 v211, v[180:183]
	ds_read_b128 v[176:179], v204 offset:36896
	ds_read_b128 v[180:183], v204 offset:41504
	ds_read_b128 v[198:201], v192 offset:32
	ds_read_b128 v[234:237], v192 offset:4640
	s_setprio 1
	s_waitcnt lgkmcnt(1)
	v_mfma_f32_32x32x16_bf16 v[112:127], v[198:201], v[176:179], v[112:127]
	v_mfma_f32_32x32x16_bf16 v[48:63], v[198:201], v[180:183], v[48:63]
	s_waitcnt lgkmcnt(0)
	v_mfma_f32_32x32x16_bf16 v[96:111], v[234:237], v[176:179], v[96:111]
	v_mfma_f32_32x32x16_bf16 v[32:47], v[234:237], v[180:183], v[32:47]
	ds_read_b128 v[198:201], v192 offset:9248
	ds_read_b128 v[234:237], v192 offset:13856
	s_waitcnt lgkmcnt(1)
	v_mfma_f32_32x32x16_bf16 v[80:95], v[198:201], v[176:179], v[80:95]
	v_mfma_f32_32x32x16_bf16 v[16:31], v[198:201], v[180:183], v[16:31]
	s_waitcnt lgkmcnt(0)
	v_mfma_f32_32x32x16_bf16 v[64:79], v[234:237], v[176:179], v[64:79]
	v_mfma_f32_32x32x16_bf16 v[0:15], v[234:237], v[180:183], v[0:15]
	s_setprio 0
	global_load_dwordx4 v[176:179], v[184:185], off offset:256
	global_load_dwordx4 v[180:183], v[186:187], off offset:256
	v_add_u32_e32 v214, 0x16800, v215
	v_add_u32_e32 v213, 0x1f800, v215
	ds_write_b128 v214, v[168:171]
	s_waitcnt vmcnt(7)
	ds_write_b128 v213, v[172:175]
	ds_read_b128 v[168:171], v204 offset:36928
	ds_read_b128 v[172:175], v204 offset:41536
	ds_read_b128 v[198:201], v192 offset:64
	ds_read_b128 v[234:237], v192 offset:4672
	s_setprio 1
	s_waitcnt lgkmcnt(1)
	v_mfma_f32_32x32x16_bf16 v[112:127], v[198:201], v[168:171], v[112:127]
	v_mfma_f32_32x32x16_bf16 v[48:63], v[198:201], v[172:175], v[48:63]
	s_waitcnt lgkmcnt(0)
	v_mfma_f32_32x32x16_bf16 v[96:111], v[234:237], v[168:171], v[96:111]
	v_mfma_f32_32x32x16_bf16 v[32:47], v[234:237], v[172:175], v[32:47]
	ds_read_b128 v[198:201], v192 offset:9280
	ds_read_b128 v[234:237], v192 offset:13888
	s_waitcnt lgkmcnt(1)
	v_mfma_f32_32x32x16_bf16 v[80:95], v[198:201], v[168:171], v[80:95]
	v_mfma_f32_32x32x16_bf16 v[16:31], v[198:201], v[172:175], v[16:31]
	s_waitcnt lgkmcnt(0)
	v_mfma_f32_32x32x16_bf16 v[64:79], v[234:237], v[168:171], v[64:79]
	v_mfma_f32_32x32x16_bf16 v[0:15], v[234:237], v[172:175], v[0:15]
	s_setprio 0
	v_add_co_u32_e32 v198, vcc, s53, v190
	v_add_u32_e32 v217, 0x18c00, v215
	s_nop 0
	v_addc_co_u32_e32 v199, vcc, 0, v191, vcc
	v_add_co_u32_e32 v200, vcc, s53, v188
	v_add_u32_e32 v216, 0x21c00, v215
	s_nop 0
	v_addc_co_u32_e32 v201, vcc, 0, v189, vcc
	global_load_dwordx4 v[168:171], v[198:199], off offset:256
	global_load_dwordx4 v[172:175], v[200:201], off offset:256
	ds_write_b128 v217, v[160:163]
	s_waitcnt vmcnt(8)
	ds_write_b128 v216, v[164:167]
	ds_read_b128 v[160:163], v204 offset:36960
	ds_read_b128 v[164:167], v204 offset:41568
	ds_read_b128 v[234:237], v192 offset:96
	ds_read_b128 v[238:241], v192 offset:4704
	s_setprio 1
	s_waitcnt lgkmcnt(1)
	v_mfma_f32_32x32x16_bf16 v[112:127], v[234:237], v[160:163], v[112:127]
	v_mfma_f32_32x32x16_bf16 v[48:63], v[234:237], v[164:167], v[48:63]
	s_waitcnt lgkmcnt(0)
	v_mfma_f32_32x32x16_bf16 v[96:111], v[238:241], v[160:163], v[96:111]
	v_mfma_f32_32x32x16_bf16 v[32:47], v[238:241], v[164:167], v[32:47]
	ds_read_b128 v[234:237], v192 offset:9312
	ds_read_b128 v[238:241], v192 offset:13920
	s_waitcnt lgkmcnt(1)
	v_mfma_f32_32x32x16_bf16 v[80:95], v[234:237], v[160:163], v[80:95]
	v_mfma_f32_32x32x16_bf16 v[16:31], v[234:237], v[164:167], v[16:31]
	s_waitcnt lgkmcnt(0)
	v_mfma_f32_32x32x16_bf16 v[64:79], v[238:241], v[160:163], v[64:79]
	v_mfma_f32_32x32x16_bf16 v[0:15], v[238:241], v[164:167], v[0:15]
	s_setprio 0
	global_load_dwordx4 v[160:163], v[190:191], off offset:384
	global_load_dwordx4 v[164:167], v[188:189], off offset:384
	s_barrier
; template <bool trans>
; DI void gemm_core(const GTile& tl, const GTile& nx, bool has_next  , bool chain  , bool pre, u32x4 (&ra)[4], u32x4 (&rb)[4], char* smem, f32x16 (&acc)[2][4]) {
;     ...
;   const int nk = K / 64;
;   if (!pre) { G_LOAD(0); G_STORE(0); G_LOAD(1); }
;   for (int kt = 0; kt < nk; ++kt) {
;     __syncthreads();
;     G_COMPUTE(kt & 1, kt);
;   }
	s_add_i32 s2, 16, 0x12000
	v_add3_u32 v205, s2, v205, v242
	s_add_i32 s2, 16, 0x1b000
	v_add3_u32 v208, s2, v208, v242
	s_waitcnt vmcnt(9)
	ds_write_b128 v215, v[218:221]
	s_waitcnt vmcnt(8)
	ds_write_b128 v215, v[222:225] offset:36864
	ds_read_b128 v[218:221], v208
	ds_read_b128 v[222:225], v208 offset:4608
	ds_read_b128 v[234:237], v205
	ds_read_b128 v[238:241], v205 offset:4608
	s_setprio 1
	s_waitcnt lgkmcnt(1)
	v_mfma_f32_32x32x16_bf16 v[112:127], v[234:237], v[218:221], v[112:127]
	v_mfma_f32_32x32x16_bf16 v[48:63], v[234:237], v[222:225], v[48:63]
	s_waitcnt lgkmcnt(0)
	v_mfma_f32_32x32x16_bf16 v[96:111], v[238:241], v[218:221], v[96:111]
	v_mfma_f32_32x32x16_bf16 v[32:47], v[238:241], v[222:225], v[32:47]
	ds_read_b128 v[234:237], v205 offset:9216
	ds_read_b128 v[238:241], v205 offset:13824
	s_waitcnt lgkmcnt(1)
	v_mfma_f32_32x32x16_bf16 v[80:95], v[234:237], v[218:221], v[80:95]
	v_mfma_f32_32x32x16_bf16 v[16:31], v[234:237], v[222:225], v[16:31]
	s_waitcnt lgkmcnt(0)
	v_mfma_f32_32x32x16_bf16 v[64:79], v[238:241], v[218:221], v[64:79]
	v_mfma_f32_32x32x16_bf16 v[0:15], v[238:241], v[222:225], v[0:15]
	s_setprio 0
	global_load_dwordx4 v[218:221], v[194:195], off offset:384
	global_load_dwordx4 v[222:225], v[196:197], off offset:384
	s_waitcnt vmcnt(9)
	ds_write_b128 v215, v[226:229] offset:9216
	s_waitcnt vmcnt(8)
	ds_write_b128 v215, v[230:233] offset:46080
	ds_read_b128 v[226:229], v208 offset:32
	ds_read_b128 v[230:233], v208 offset:4640
	ds_read_b128 v[234:237], v205 offset:32
	ds_read_b128 v[238:241], v205 offset:4640
	s_setprio 1
	s_waitcnt lgkmcnt(1)
	v_mfma_f32_32x32x16_bf16 v[112:127], v[234:237], v[226:229], v[112:127]
	v_mfma_f32_32x32x16_bf16 v[48:63], v[234:237], v[230:233], v[48:63]
	s_waitcnt lgkmcnt(0)
	v_mfma_f32_32x32x16_bf16 v[96:111], v[238:241], v[226:229], v[96:111]
	v_mfma_f32_32x32x16_bf16 v[32:47], v[238:241], v[230:233], v[32:47]
	ds_read_b128 v[234:237], v205 offset:9248
	ds_read_b128 v[238:241], v205 offset:13856
	s_waitcnt lgkmcnt(1)
	v_mfma_f32_32x32x16_bf16 v[80:95], v[234:237], v[226:229], v[80:95]
	v_mfma_f32_32x32x16_bf16 v[16:31], v[234:237], v[230:233], v[16:31]
	s_waitcnt lgkmcnt(0)
	v_mfma_f32_32x32x16_bf16 v[64:79], v[238:241], v[226:229], v[64:79]
	v_mfma_f32_32x32x16_bf16 v[0:15], v[238:241], v[230:233], v[0:15]
	s_setprio 0
	global_load_dwordx4 v[226:229], v[184:185], off offset:384
	global_load_dwordx4 v[230:233], v[186:187], off offset:384
	s_waitcnt vmcnt(9)
	ds_write_b128 v215, v[176:179] offset:18432
	s_waitcnt vmcnt(8)
	ds_write_b128 v215, v[180:183] offset:55296
	ds_read_b128 v[176:179], v208 offset:64
	ds_read_b128 v[180:183], v208 offset:4672
	ds_read_b128 v[234:237], v205 offset:64
	ds_read_b128 v[238:241], v205 offset:4672
	s_setprio 1
	s_waitcnt lgkmcnt(1)
	v_mfma_f32_32x32x16_bf16 v[112:127], v[234:237], v[176:179], v[112:127]
	v_mfma_f32_32x32x16_bf16 v[48:63], v[234:237], v[180:183], v[48:63]
	s_waitcnt lgkmcnt(0)
	v_mfma_f32_32x32x16_bf16 v[96:111], v[238:241], v[176:179], v[96:111]
	v_mfma_f32_32x32x16_bf16 v[32:47], v[238:241], v[180:183], v[32:47]
	ds_read_b128 v[234:237], v205 offset:9280
	ds_read_b128 v[238:241], v205 offset:13888
	s_waitcnt lgkmcnt(1)
	v_mfma_f32_32x32x16_bf16 v[80:95], v[234:237], v[176:179], v[80:95]
	v_mfma_f32_32x32x16_bf16 v[16:31], v[234:237], v[180:183], v[16:31]
	s_waitcnt lgkmcnt(0)
	v_mfma_f32_32x32x16_bf16 v[64:79], v[238:241], v[176:179], v[64:79]
	v_mfma_f32_32x32x16_bf16 v[0:15], v[238:241], v[180:183], v[0:15]
	s_setprio 0
	global_load_dwordx4 v[176:179], v[198:199], off offset:384
	global_load_dwordx4 v[180:183], v[200:201], off offset:384
	s_waitcnt vmcnt(9)
	ds_write_b128 v215, v[168:171] offset:27648
	s_waitcnt vmcnt(8)
	ds_write_b128 v215, v[172:175] offset:64512
	ds_read_b128 v[168:171], v208 offset:96
	ds_read_b128 v[172:175], v208 offset:4704
	ds_read_b128 v[234:237], v205 offset:96
	ds_read_b128 v[238:241], v205 offset:4704
	s_setprio 1
	s_waitcnt lgkmcnt(1)
	v_mfma_f32_32x32x16_bf16 v[112:127], v[234:237], v[168:171], v[112:127]
	v_mfma_f32_32x32x16_bf16 v[48:63], v[234:237], v[172:175], v[48:63]
	s_waitcnt lgkmcnt(0)
	v_mfma_f32_32x32x16_bf16 v[96:111], v[238:241], v[168:171], v[96:111]
	v_mfma_f32_32x32x16_bf16 v[32:47], v[238:241], v[172:175], v[32:47]
	ds_read_b128 v[234:237], v205 offset:9312
	ds_read_b128 v[238:241], v205 offset:13920
	s_waitcnt lgkmcnt(1)
	v_mfma_f32_32x32x16_bf16 v[80:95], v[234:237], v[168:171], v[80:95]
	v_mfma_f32_32x32x16_bf16 v[16:31], v[234:237], v[172:175], v[16:31]
	s_waitcnt lgkmcnt(0)
	v_mfma_f32_32x32x16_bf16 v[64:79], v[238:241], v[168:171], v[64:79]
	v_mfma_f32_32x32x16_bf16 v[0:15], v[238:241], v[172:175], v[0:15]
	s_setprio 0
	global_load_dwordx4 v[168:171], v[190:191], off offset:512
	global_load_dwordx4 v[172:175], v[188:189], off offset:512
	s_barrier
; template <bool trans>
; DI void gemm_core(const GTile& tl, const GTile& nx, bool has_next  , bool chain  , bool pre, u32x4 (&ra)[4], u32x4 (&rb)[4], char* smem, f32x16 (&acc)[2][4]) {
;     ...
;   const int nk = K / 64;
;   if (!pre) { G_LOAD(0); G_STORE(0); G_LOAD(1); }
;   for (int kt = 0; kt < nk; ++kt) {
;     __syncthreads();
;     G_COMPUTE(kt & 1, kt);
;   }
	s_waitcnt vmcnt(9)
	ds_write_b128 v209, v[160:163]
	s_waitcnt vmcnt(8)
	ds_write_b128 v210, v[164:167]
	ds_read_b128 v[160:163], v204 offset:36864
	ds_read_b128 v[164:167], v204 offset:41472
	ds_read_b128 v[234:237], v192
	ds_read_b128 v[238:241], v192 offset:4608
	s_setprio 1
	s_waitcnt lgkmcnt(1)
	v_mfma_f32_32x32x16_bf16 v[112:127], v[234:237], v[160:163], v[112:127]
	v_mfma_f32_32x32x16_bf16 v[48:63], v[234:237], v[164:167], v[48:63]
	s_waitcnt lgkmcnt(0)
	v_mfma_f32_32x32x16_bf16 v[96:111], v[238:241], v[160:163], v[96:111]
	v_mfma_f32_32x32x16_bf16 v[32:47], v[238:241], v[164:167], v[32:47]
	ds_read_b128 v[234:237], v192 offset:9216
	ds_read_b128 v[238:241], v192 offset:13824
	s_waitcnt vmcnt(7)
	ds_write_b128 v212, v[218:221]
	s_waitcnt vmcnt(6)
	ds_write_b128 v211, v[222:225]
	ds_read_b128 v[218:221], v204 offset:36896
	ds_read_b128 v[222:225], v204 offset:41504
	s_waitcnt lgkmcnt(5)
	v_mfma_f32_32x32x16_bf16 v[80:95], v[234:237], v[160:163], v[80:95]
	v_mfma_f32_32x32x16_bf16 v[16:31], v[234:237], v[164:167], v[16:31]
	ds_read_b128 v[234:237], v192 offset:32
	s_waitcnt lgkmcnt(5)
	v_mfma_f32_32x32x16_bf16 v[64:79], v[238:241], v[160:163], v[64:79]
	v_mfma_f32_32x32x16_bf16 v[0:15], v[238:241], v[164:167], v[0:15]
	ds_read_b128 v[238:241], v192 offset:4640
	s_setprio 0
	global_load_dwordx4 v[160:163], v[194:195], off offset:512
	global_load_dwordx4 v[164:167], v[196:197], off offset:512
	s_setprio 1
	s_waitcnt lgkmcnt(1)
	v_mfma_f32_32x32x16_bf16 v[112:127], v[234:237], v[218:221], v[112:127]
	v_mfma_f32_32x32x16_bf16 v[48:63], v[234:237], v[222:225], v[48:63]
	s_waitcnt lgkmcnt(0)
	v_mfma_f32_32x32x16_bf16 v[96:111], v[238:241], v[218:221], v[96:111]
	v_mfma_f32_32x32x16_bf16 v[32:47], v[238:241], v[222:225], v[32:47]
	ds_read_b128 v[234:237], v192 offset:9248
	ds_read_b128 v[238:241], v192 offset:13856
	s_waitcnt vmcnt(7)
	ds_write_b128 v214, v[226:229]
	s_waitcnt vmcnt(6)
	ds_write_b128 v213, v[230:233]
	ds_read_b128 v[226:229], v204 offset:36928
	ds_read_b128 v[230:233], v204 offset:41536
	s_waitcnt lgkmcnt(5)
	v_mfma_f32_32x32x16_bf16 v[80:95], v[234:237], v[218:221], v[80:95]
	v_mfma_f32_32x32x16_bf16 v[16:31], v[234:237], v[222:225], v[16:31]
	ds_read_b128 v[234:237], v192 offset:64
	s_waitcnt lgkmcnt(5)
	v_mfma_f32_32x32x16_bf16 v[64:79], v[238:241], v[218:221], v[64:79]
	v_mfma_f32_32x32x16_bf16 v[0:15], v[238:241], v[222:225], v[0:15]
	ds_read_b128 v[238:241], v192 offset:4672
	s_setprio 0
	global_load_dwordx4 v[218:221], v[184:185], off offset:512
	global_load_dwordx4 v[222:225], v[186:187], off offset:512
	s_setprio 1
	s_waitcnt lgkmcnt(1)
	v_mfma_f32_32x32x16_bf16 v[112:127], v[234:237], v[226:229], v[112:127]
	v_mfma_f32_32x32x16_bf16 v[48:63], v[234:237], v[230:233], v[48:63]
	s_waitcnt lgkmcnt(0)
	v_mfma_f32_32x32x16_bf16 v[96:111], v[238:241], v[226:229], v[96:111]
	v_mfma_f32_32x32x16_bf16 v[32:47], v[238:241], v[230:233], v[32:47]
	ds_read_b128 v[234:237], v192 offset:9280
	ds_read_b128 v[238:241], v192 offset:13888
	s_waitcnt vmcnt(7)
	ds_write_b128 v217, v[176:179]
	s_waitcnt vmcnt(6)
	ds_write_b128 v216, v[180:183]
	ds_read_b128 v[176:179], v204 offset:36960
	ds_read_b128 v[180:183], v204 offset:41568
	s_waitcnt lgkmcnt(5)
	v_mfma_f32_32x32x16_bf16 v[80:95], v[234:237], v[226:229], v[80:95]
	v_mfma_f32_32x32x16_bf16 v[16:31], v[234:237], v[230:233], v[16:31]
	ds_read_b128 v[234:237], v192 offset:96
	s_waitcnt lgkmcnt(5)
	v_mfma_f32_32x32x16_bf16 v[64:79], v[238:241], v[226:229], v[64:79]
	v_mfma_f32_32x32x16_bf16 v[0:15], v[238:241], v[230:233], v[0:15]
	ds_read_b128 v[238:241], v192 offset:4704
	s_setprio 0
	global_load_dwordx4 v[226:229], v[198:199], off offset:512
	global_load_dwordx4 v[230:233], v[200:201], off offset:512
	s_setprio 1
	s_waitcnt lgkmcnt(1)
	v_mfma_f32_32x32x16_bf16 v[112:127], v[234:237], v[176:179], v[112:127]
	v_mfma_f32_32x32x16_bf16 v[48:63], v[234:237], v[180:183], v[48:63]
	s_waitcnt lgkmcnt(0)
	v_mfma_f32_32x32x16_bf16 v[96:111], v[238:241], v[176:179], v[96:111]
	v_mfma_f32_32x32x16_bf16 v[32:47], v[238:241], v[180:183], v[32:47]
	ds_read_b128 v[234:237], v192 offset:9312
	ds_read_b128 v[238:241], v192 offset:13920
	s_waitcnt lgkmcnt(0)
	s_barrier
	s_waitcnt vmcnt(7)
	ds_write_b128 v215, v[168:171]
	s_waitcnt vmcnt(6)
	ds_write_b128 v215, v[172:175] offset:36864
	ds_read_b128 v[168:171], v208
	ds_read_b128 v[172:175], v208 offset:4608
	v_mfma_f32_32x32x16_bf16 v[80:95], v[234:237], v[176:179], v[80:95]
	v_mfma_f32_32x32x16_bf16 v[16:31], v[234:237], v[180:183], v[16:31]
	ds_read_b128 v[234:237], v205
	v_mfma_f32_32x32x16_bf16 v[64:79], v[238:241], v[176:179], v[64:79]
	v_mfma_f32_32x32x16_bf16 v[0:15], v[238:241], v[180:183], v[0:15]
	ds_read_b128 v[238:241], v205 offset:4608
	s_setprio 0
	global_load_dwordx4 v[176:179], v[190:191], off offset:640
	global_load_dwordx4 v[180:183], v[188:189], off offset:640
	s_setprio 1
	s_waitcnt lgkmcnt(1)
	v_mfma_f32_32x32x16_bf16 v[112:127], v[234:237], v[168:171], v[112:127]
	v_mfma_f32_32x32x16_bf16 v[48:63], v[234:237], v[172:175], v[48:63]
	s_waitcnt lgkmcnt(0)
	v_mfma_f32_32x32x16_bf16 v[96:111], v[238:241], v[168:171], v[96:111]
	v_mfma_f32_32x32x16_bf16 v[32:47], v[238:241], v[172:175], v[32:47]
	ds_read_b128 v[234:237], v205 offset:9216
	ds_read_b128 v[238:241], v205 offset:13824
	s_waitcnt vmcnt(7)
	ds_write_b128 v215, v[160:163] offset:9216
	s_waitcnt vmcnt(6)
	ds_write_b128 v215, v[164:167] offset:46080
	ds_read_b128 v[160:163], v208 offset:32
	ds_read_b128 v[164:167], v208 offset:4640
	s_waitcnt lgkmcnt(5)
	v_mfma_f32_32x32x16_bf16 v[80:95], v[234:237], v[168:171], v[80:95]
	v_mfma_f32_32x32x16_bf16 v[16:31], v[234:237], v[172:175], v[16:31]
	ds_read_b128 v[234:237], v205 offset:32
	s_waitcnt lgkmcnt(5)
; template <bool trans>
; DI void gemm_core(const GTile& tl, const GTile& nx, bool has_next  , bool chain  , bool pre, u32x4 (&ra)[4], u32x4 (&rb)[4], char* smem, f32x16 (&acc)[2][4]) {
;     ...
;   const int nk = K / 64;
;   if (!pre) { G_LOAD(0); G_STORE(0); G_LOAD(1); }
;   for (int kt = 0; kt < nk; ++kt) {
;     __syncthreads();
;     G_COMPUTE(kt & 1, kt);
;   }
	v_mfma_f32_32x32x16_bf16 v[64:79], v[238:241], v[168:171], v[64:79]
	v_mfma_f32_32x32x16_bf16 v[0:15], v[238:241], v[172:175], v[0:15]
	ds_read_b128 v[238:241], v205 offset:4640
	s_setprio 0
	global_load_dwordx4 v[168:171], v[194:195], off offset:640
	global_load_dwordx4 v[172:175], v[196:197], off offset:640
	s_setprio 1
	s_waitcnt lgkmcnt(1)
	v_mfma_f32_32x32x16_bf16 v[112:127], v[234:237], v[160:163], v[112:127]
	v_mfma_f32_32x32x16_bf16 v[48:63], v[234:237], v[164:167], v[48:63]
	s_waitcnt lgkmcnt(0)
	v_mfma_f32_32x32x16_bf16 v[96:111], v[238:241], v[160:163], v[96:111]
	v_mfma_f32_32x32x16_bf16 v[32:47], v[238:241], v[164:167], v[32:47]
	ds_read_b128 v[234:237], v205 offset:9248
	ds_read_b128 v[238:241], v205 offset:13856
	s_waitcnt vmcnt(7)
	ds_write_b128 v215, v[218:221] offset:18432
	s_waitcnt vmcnt(6)
	ds_write_b128 v215, v[222:225] offset:55296
	ds_read_b128 v[218:221], v208 offset:64
	ds_read_b128 v[222:225], v208 offset:4672
	s_waitcnt lgkmcnt(5)
	v_mfma_f32_32x32x16_bf16 v[80:95], v[234:237], v[160:163], v[80:95]
	v_mfma_f32_32x32x16_bf16 v[16:31], v[234:237], v[164:167], v[16:31]
	ds_read_b128 v[234:237], v205 offset:64
	s_waitcnt lgkmcnt(5)
	v_mfma_f32_32x32x16_bf16 v[64:79], v[238:241], v[160:163], v[64:79]
	v_mfma_f32_32x32x16_bf16 v[0:15], v[238:241], v[164:167], v[0:15]
	ds_read_b128 v[238:241], v205 offset:4672
	s_setprio 0
	global_load_dwordx4 v[160:163], v[184:185], off offset:640
	global_load_dwordx4 v[164:167], v[186:187], off offset:640
	s_setprio 1
	s_waitcnt lgkmcnt(1)
	v_mfma_f32_32x32x16_bf16 v[112:127], v[234:237], v[218:221], v[112:127]
	v_mfma_f32_32x32x16_bf16 v[48:63], v[234:237], v[222:225], v[48:63]
	s_waitcnt lgkmcnt(0)
	v_mfma_f32_32x32x16_bf16 v[96:111], v[238:241], v[218:221], v[96:111]
	v_mfma_f32_32x32x16_bf16 v[32:47], v[238:241], v[222:225], v[32:47]
	ds_read_b128 v[234:237], v205 offset:9280
	ds_read_b128 v[238:241], v205 offset:13888
	s_waitcnt vmcnt(7)
	ds_write_b128 v215, v[226:229] offset:27648
	s_waitcnt vmcnt(6)
	ds_write_b128 v215, v[230:233] offset:64512
	ds_read_b128 v[226:229], v208 offset:96
	ds_read_b128 v[230:233], v208 offset:4704
	s_waitcnt lgkmcnt(5)
	v_mfma_f32_32x32x16_bf16 v[80:95], v[234:237], v[218:221], v[80:95]
	v_mfma_f32_32x32x16_bf16 v[16:31], v[234:237], v[222:225], v[16:31]
	ds_read_b128 v[234:237], v205 offset:96
	s_waitcnt lgkmcnt(5)
	v_mfma_f32_32x32x16_bf16 v[64:79], v[238:241], v[218:221], v[64:79]
	v_mfma_f32_32x32x16_bf16 v[0:15], v[238:241], v[222:225], v[0:15]
	ds_read_b128 v[238:241], v205 offset:4704
	s_setprio 0
	global_load_dwordx4 v[218:221], v[198:199], off offset:640
	global_load_dwordx4 v[222:225], v[200:201], off offset:640
	s_setprio 1
	s_waitcnt lgkmcnt(1)
	v_mfma_f32_32x32x16_bf16 v[112:127], v[234:237], v[226:229], v[112:127]
	v_mfma_f32_32x32x16_bf16 v[48:63], v[234:237], v[230:233], v[48:63]
	s_waitcnt lgkmcnt(0)
	v_mfma_f32_32x32x16_bf16 v[96:111], v[238:241], v[226:229], v[96:111]
	v_mfma_f32_32x32x16_bf16 v[32:47], v[238:241], v[230:233], v[32:47]
	ds_read_b128 v[234:237], v205 offset:9312
	ds_read_b128 v[238:241], v205 offset:13920
	s_waitcnt lgkmcnt(0)
	s_barrier
	s_waitcnt vmcnt(7)
	ds_write_b128 v209, v[176:179]
	s_waitcnt vmcnt(6)
	ds_write_b128 v210, v[180:183]
	ds_read_b128 v[176:179], v204 offset:36864
	ds_read_b128 v[180:183], v204 offset:41472
	v_mfma_f32_32x32x16_bf16 v[80:95], v[234:237], v[226:229], v[80:95]
	v_mfma_f32_32x32x16_bf16 v[16:31], v[234:237], v[230:233], v[16:31]
	ds_read_b128 v[234:237], v192
	v_mfma_f32_32x32x16_bf16 v[64:79], v[238:241], v[226:229], v[64:79]
	v_mfma_f32_32x32x16_bf16 v[0:15], v[238:241], v[230:233], v[0:15]
	ds_read_b128 v[238:241], v192 offset:4608
	s_setprio 0
	global_load_dwordx4 v[226:229], v[190:191], off offset:768
	global_load_dwordx4 v[230:233], v[188:189], off offset:768
	s_setprio 1
	s_waitcnt lgkmcnt(1)
	v_mfma_f32_32x32x16_bf16 v[112:127], v[234:237], v[176:179], v[112:127]
	v_mfma_f32_32x32x16_bf16 v[48:63], v[234:237], v[180:183], v[48:63]
	s_waitcnt lgkmcnt(0)
	v_mfma_f32_32x32x16_bf16 v[96:111], v[238:241], v[176:179], v[96:111]
	v_mfma_f32_32x32x16_bf16 v[32:47], v[238:241], v[180:183], v[32:47]
	ds_read_b128 v[234:237], v192 offset:9216
	ds_read_b128 v[238:241], v192 offset:13824
	s_waitcnt vmcnt(7)
	ds_write_b128 v212, v[168:171]
	s_waitcnt vmcnt(6)
	ds_write_b128 v211, v[172:175]
	ds_read_b128 v[168:171], v204 offset:36896
	ds_read_b128 v[172:175], v204 offset:41504
	s_waitcnt lgkmcnt(5)
	v_mfma_f32_32x32x16_bf16 v[80:95], v[234:237], v[176:179], v[80:95]
	v_mfma_f32_32x32x16_bf16 v[16:31], v[234:237], v[180:183], v[16:31]
	ds_read_b128 v[234:237], v192 offset:32
	s_waitcnt lgkmcnt(5)
	v_mfma_f32_32x32x16_bf16 v[64:79], v[238:241], v[176:179], v[64:79]
	v_mfma_f32_32x32x16_bf16 v[0:15], v[238:241], v[180:183], v[0:15]
	ds_read_b128 v[238:241], v192 offset:4640
	s_setprio 0
	global_load_dwordx4 v[176:179], v[194:195], off offset:768
	global_load_dwordx4 v[180:183], v[196:197], off offset:768
	s_setprio 1
	s_waitcnt lgkmcnt(1)
	v_mfma_f32_32x32x16_bf16 v[112:127], v[234:237], v[168:171], v[112:127]
	v_mfma_f32_32x32x16_bf16 v[48:63], v[234:237], v[172:175], v[48:63]
	s_waitcnt lgkmcnt(0)
	v_mfma_f32_32x32x16_bf16 v[96:111], v[238:241], v[168:171], v[96:111]
	v_mfma_f32_32x32x16_bf16 v[32:47], v[238:241], v[172:175], v[32:47]
	ds_read_b128 v[234:237], v192 offset:9248
	ds_read_b128 v[238:241], v192 offset:13856
	s_waitcnt vmcnt(7)
	ds_write_b128 v214, v[160:163]
	s_waitcnt vmcnt(6)
	ds_write_b128 v213, v[164:167]
	ds_read_b128 v[160:163], v204 offset:36928
	ds_read_b128 v[164:167], v204 offset:41536
	s_waitcnt lgkmcnt(5)
; template <bool trans>
; DI void gemm_core(const GTile& tl, const GTile& nx, bool has_next  , bool chain  , bool pre, u32x4 (&ra)[4], u32x4 (&rb)[4], char* smem, f32x16 (&acc)[2][4]) {
;     ...
;   const int nk = K / 64;
;   if (!pre) { G_LOAD(0); G_STORE(0); G_LOAD(1); }
;   for (int kt = 0; kt < nk; ++kt) {
;     __syncthreads();
;     G_COMPUTE(kt & 1, kt);
;   }
	v_mfma_f32_32x32x16_bf16 v[80:95], v[234:237], v[168:171], v[80:95]
	v_mfma_f32_32x32x16_bf16 v[16:31], v[234:237], v[172:175], v[16:31]
	ds_read_b128 v[234:237], v192 offset:64
	s_waitcnt lgkmcnt(5)
	v_mfma_f32_32x32x16_bf16 v[64:79], v[238:241], v[168:171], v[64:79]
	v_mfma_f32_32x32x16_bf16 v[0:15], v[238:241], v[172:175], v[0:15]
	ds_read_b128 v[238:241], v192 offset:4672
	s_setprio 0
	global_load_dwordx4 v[168:171], v[184:185], off offset:768
	global_load_dwordx4 v[172:175], v[186:187], off offset:768
	s_setprio 1
	s_waitcnt lgkmcnt(1)
	v_mfma_f32_32x32x16_bf16 v[112:127], v[234:237], v[160:163], v[112:127]
	v_mfma_f32_32x32x16_bf16 v[48:63], v[234:237], v[164:167], v[48:63]
	s_waitcnt lgkmcnt(0)
	v_mfma_f32_32x32x16_bf16 v[96:111], v[238:241], v[160:163], v[96:111]
	v_mfma_f32_32x32x16_bf16 v[32:47], v[238:241], v[164:167], v[32:47]
	ds_read_b128 v[234:237], v192 offset:9280
	ds_read_b128 v[238:241], v192 offset:13888
	s_waitcnt vmcnt(7)
	ds_write_b128 v217, v[218:221]
	s_waitcnt vmcnt(6)
	ds_write_b128 v216, v[222:225]
	ds_read_b128 v[218:221], v204 offset:36960
	ds_read_b128 v[222:225], v204 offset:41568
	s_waitcnt lgkmcnt(5)
	v_mfma_f32_32x32x16_bf16 v[80:95], v[234:237], v[160:163], v[80:95]
	v_mfma_f32_32x32x16_bf16 v[16:31], v[234:237], v[164:167], v[16:31]
	ds_read_b128 v[234:237], v192 offset:96
	s_waitcnt lgkmcnt(5)
	v_mfma_f32_32x32x16_bf16 v[64:79], v[238:241], v[160:163], v[64:79]
	v_mfma_f32_32x32x16_bf16 v[0:15], v[238:241], v[164:167], v[0:15]
	ds_read_b128 v[238:241], v192 offset:4704
	s_setprio 0
	global_load_dwordx4 v[160:163], v[198:199], off offset:768
	global_load_dwordx4 v[164:167], v[200:201], off offset:768
	s_setprio 1
	s_waitcnt lgkmcnt(1)
	v_mfma_f32_32x32x16_bf16 v[112:127], v[234:237], v[218:221], v[112:127]
	v_mfma_f32_32x32x16_bf16 v[48:63], v[234:237], v[222:225], v[48:63]
	s_waitcnt lgkmcnt(0)
	v_mfma_f32_32x32x16_bf16 v[96:111], v[238:241], v[218:221], v[96:111]
	v_mfma_f32_32x32x16_bf16 v[32:47], v[238:241], v[222:225], v[32:47]
	ds_read_b128 v[234:237], v192 offset:9312
	ds_read_b128 v[238:241], v192 offset:13920
	s_waitcnt lgkmcnt(0)
	s_barrier
	s_waitcnt vmcnt(7)
	ds_write_b128 v215, v[226:229]
	s_waitcnt vmcnt(6)
	ds_write_b128 v215, v[230:233] offset:36864
	ds_read_b128 v[226:229], v208
	ds_read_b128 v[230:233], v208 offset:4608
	v_mfma_f32_32x32x16_bf16 v[80:95], v[234:237], v[218:221], v[80:95]
	v_mfma_f32_32x32x16_bf16 v[16:31], v[234:237], v[222:225], v[16:31]
	ds_read_b128 v[234:237], v205
	v_mfma_f32_32x32x16_bf16 v[64:79], v[238:241], v[218:221], v[64:79]
	v_mfma_f32_32x32x16_bf16 v[0:15], v[238:241], v[222:225], v[0:15]
	ds_read_b128 v[238:241], v205 offset:4608
	s_setprio 0
	global_load_dwordx4 v[218:221], v[190:191], off offset:896
	global_load_dwordx4 v[222:225], v[188:189], off offset:896
	s_setprio 1
	s_waitcnt lgkmcnt(1)
	v_mfma_f32_32x32x16_bf16 v[112:127], v[234:237], v[226:229], v[112:127]
	v_mfma_f32_32x32x16_bf16 v[48:63], v[234:237], v[230:233], v[48:63]
	s_waitcnt lgkmcnt(0)
	v_mfma_f32_32x32x16_bf16 v[96:111], v[238:241], v[226:229], v[96:111]
	v_mfma_f32_32x32x16_bf16 v[32:47], v[238:241], v[230:233], v[32:47]
	ds_read_b128 v[234:237], v205 offset:9216
	ds_read_b128 v[238:241], v205 offset:13824
	s_waitcnt vmcnt(7)
	ds_write_b128 v215, v[176:179] offset:9216
	s_waitcnt vmcnt(6)
	ds_write_b128 v215, v[180:183] offset:46080
	ds_read_b128 v[176:179], v208 offset:32
	ds_read_b128 v[180:183], v208 offset:4640
	s_waitcnt lgkmcnt(5)
	v_mfma_f32_32x32x16_bf16 v[80:95], v[234:237], v[226:229], v[80:95]
	v_mfma_f32_32x32x16_bf16 v[16:31], v[234:237], v[230:233], v[16:31]
	ds_read_b128 v[234:237], v205 offset:32
	s_waitcnt lgkmcnt(5)
	v_mfma_f32_32x32x16_bf16 v[64:79], v[238:241], v[226:229], v[64:79]
	v_mfma_f32_32x32x16_bf16 v[0:15], v[238:241], v[230:233], v[0:15]
	ds_read_b128 v[238:241], v205 offset:4640
	s_setprio 0
	global_load_dwordx4 v[226:229], v[194:195], off offset:896
	global_load_dwordx4 v[230:233], v[196:197], off offset:896
	s_setprio 1
	s_waitcnt lgkmcnt(1)
	v_mfma_f32_32x32x16_bf16 v[112:127], v[234:237], v[176:179], v[112:127]
	v_mfma_f32_32x32x16_bf16 v[48:63], v[234:237], v[180:183], v[48:63]
	s_waitcnt lgkmcnt(0)
	v_mfma_f32_32x32x16_bf16 v[96:111], v[238:241], v[176:179], v[96:111]
	v_mfma_f32_32x32x16_bf16 v[32:47], v[238:241], v[180:183], v[32:47]
	ds_read_b128 v[234:237], v205 offset:9248
	ds_read_b128 v[238:241], v205 offset:13856
	s_waitcnt vmcnt(7)
	ds_write_b128 v215, v[168:171] offset:18432
	s_waitcnt vmcnt(6)
	ds_write_b128 v215, v[172:175] offset:55296
	ds_read_b128 v[168:171], v208 offset:64
	ds_read_b128 v[172:175], v208 offset:4672
	s_waitcnt lgkmcnt(5)
	v_mfma_f32_32x32x16_bf16 v[80:95], v[234:237], v[176:179], v[80:95]
	v_mfma_f32_32x32x16_bf16 v[16:31], v[234:237], v[180:183], v[16:31]
	ds_read_b128 v[234:237], v205 offset:64
	s_waitcnt lgkmcnt(5)
	v_mfma_f32_32x32x16_bf16 v[64:79], v[238:241], v[176:179], v[64:79]
	v_mfma_f32_32x32x16_bf16 v[0:15], v[238:241], v[180:183], v[0:15]
	ds_read_b128 v[238:241], v205 offset:4672
	s_setprio 0
	global_load_dwordx4 v[176:179], v[184:185], off offset:896
	global_load_dwordx4 v[180:183], v[186:187], off offset:896
	s_setprio 1
	s_waitcnt lgkmcnt(1)
	v_mfma_f32_32x32x16_bf16 v[112:127], v[234:237], v[168:171], v[112:127]
	v_mfma_f32_32x32x16_bf16 v[48:63], v[234:237], v[172:175], v[48:63]
	s_waitcnt lgkmcnt(0)
	v_mfma_f32_32x32x16_bf16 v[96:111], v[238:241], v[168:171], v[96:111]
	v_mfma_f32_32x32x16_bf16 v[32:47], v[238:241], v[172:175], v[32:47]
	ds_read_b128 v[234:237], v205 offset:9280
	ds_read_b128 v[238:241], v205 offset:13888
	s_waitcnt vmcnt(7)
	ds_write_b128 v215, v[160:163] offset:27648
	s_waitcnt vmcnt(6)
	ds_write_b128 v215, v[164:167] offset:64512
	ds_read_b128 v[160:163], v208 offset:96
	ds_read_b128 v[164:167], v208 offset:4704
	s_waitcnt lgkmcnt(5)
	v_mfma_f32_32x32x16_bf16 v[80:95], v[234:237], v[168:171], v[80:95]
	v_mfma_f32_32x32x16_bf16 v[16:31], v[234:237], v[172:175], v[16:31]
	ds_read_b128 v[234:237], v205 offset:96
	s_waitcnt lgkmcnt(5)
	v_mfma_f32_32x32x16_bf16 v[64:79], v[238:241], v[168:171], v[64:79]
	v_mfma_f32_32x32x16_bf16 v[0:15], v[238:241], v[172:175], v[0:15]
	ds_read_b128 v[238:241], v205 offset:4704
	s_setprio 0
	global_load_dwordx4 v[168:171], v[198:199], off offset:896
	global_load_dwordx4 v[172:175], v[200:201], off offset:896
	s_setprio 1
	s_waitcnt lgkmcnt(1)
	v_mfma_f32_32x32x16_bf16 v[112:127], v[234:237], v[160:163], v[112:127]
	v_mfma_f32_32x32x16_bf16 v[48:63], v[234:237], v[164:167], v[48:63]
	s_waitcnt lgkmcnt(0)
	v_mfma_f32_32x32x16_bf16 v[96:111], v[238:241], v[160:163], v[96:111]
	v_mfma_f32_32x32x16_bf16 v[32:47], v[238:241], v[164:167], v[32:47]
	ds_read_b128 v[234:237], v205 offset:9312
	ds_read_b128 v[238:241], v205 offset:13920
	s_waitcnt lgkmcnt(0)
	s_barrier
; template <bool trans>
; DI void gemm_core(const GTile& tl, const GTile& nx, bool has_next  , bool chain  , bool pre, u32x4 (&ra)[4], u32x4 (&rb)[4], char* smem, f32x16 (&acc)[2][4]) {
;     ...
;   const int nk = K / 64;
;   if (!pre) { G_LOAD(0); G_STORE(0); G_LOAD(1); }
;   for (int kt = 0; kt < nk; ++kt) {
;     __syncthreads();
;     G_COMPUTE(kt & 1, kt);
;   }
	s_waitcnt vmcnt(7)
	ds_write_b128 v209, v[218:221]
	s_waitcnt vmcnt(6)
	ds_write_b128 v210, v[222:225]
	ds_read_b128 v[218:221], v204 offset:36864
	ds_read_b128 v[222:225], v204 offset:41472
	v_mfma_f32_32x32x16_bf16 v[80:95], v[234:237], v[160:163], v[80:95]
	v_mfma_f32_32x32x16_bf16 v[16:31], v[234:237], v[164:167], v[16:31]
	ds_read_b128 v[234:237], v192
	v_mfma_f32_32x32x16_bf16 v[64:79], v[238:241], v[160:163], v[64:79]
	v_mfma_f32_32x32x16_bf16 v[0:15], v[238:241], v[164:167], v[0:15]
	ds_read_b128 v[238:241], v192 offset:4608
	s_setprio 0
	global_load_dwordx4 v[160:163], v[190:191], off offset:1024
	global_load_dwordx4 v[164:167], v[188:189], off offset:1024
	s_setprio 1
	s_waitcnt lgkmcnt(1)
	v_mfma_f32_32x32x16_bf16 v[112:127], v[234:237], v[218:221], v[112:127]
	v_mfma_f32_32x32x16_bf16 v[48:63], v[234:237], v[222:225], v[48:63]
	s_waitcnt lgkmcnt(0)
	v_mfma_f32_32x32x16_bf16 v[96:111], v[238:241], v[218:221], v[96:111]
	v_mfma_f32_32x32x16_bf16 v[32:47], v[238:241], v[222:225], v[32:47]
	ds_read_b128 v[234:237], v192 offset:9216
	ds_read_b128 v[238:241], v192 offset:13824
	s_waitcnt vmcnt(7)
	ds_write_b128 v212, v[226:229]
	s_waitcnt vmcnt(6)
	ds_write_b128 v211, v[230:233]
	ds_read_b128 v[226:229], v204 offset:36896
	ds_read_b128 v[230:233], v204 offset:41504
	s_waitcnt lgkmcnt(5)
	v_mfma_f32_32x32x16_bf16 v[80:95], v[234:237], v[218:221], v[80:95]
	v_mfma_f32_32x32x16_bf16 v[16:31], v[234:237], v[222:225], v[16:31]
	ds_read_b128 v[234:237], v192 offset:32
	s_waitcnt lgkmcnt(5)
	v_mfma_f32_32x32x16_bf16 v[64:79], v[238:241], v[218:221], v[64:79]
	v_mfma_f32_32x32x16_bf16 v[0:15], v[238:241], v[222:225], v[0:15]
	ds_read_b128 v[238:241], v192 offset:4640
	s_setprio 0
	global_load_dwordx4 v[218:221], v[194:195], off offset:1024
	global_load_dwordx4 v[222:225], v[196:197], off offset:1024
	s_setprio 1
	s_waitcnt lgkmcnt(1)
	v_mfma_f32_32x32x16_bf16 v[112:127], v[234:237], v[226:229], v[112:127]
	v_mfma_f32_32x32x16_bf16 v[48:63], v[234:237], v[230:233], v[48:63]
	s_waitcnt lgkmcnt(0)
	v_mfma_f32_32x32x16_bf16 v[96:111], v[238:241], v[226:229], v[96:111]
	v_mfma_f32_32x32x16_bf16 v[32:47], v[238:241], v[230:233], v[32:47]
	ds_read_b128 v[234:237], v192 offset:9248
	ds_read_b128 v[238:241], v192 offset:13856
	s_waitcnt vmcnt(7)
	ds_write_b128 v214, v[176:179]
	s_waitcnt vmcnt(6)
	ds_write_b128 v213, v[180:183]
	ds_read_b128 v[176:179], v204 offset:36928
	ds_read_b128 v[180:183], v204 offset:41536
	s_waitcnt lgkmcnt(5)
	v_mfma_f32_32x32x16_bf16 v[80:95], v[234:237], v[226:229], v[80:95]
	v_mfma_f32_32x32x16_bf16 v[16:31], v[234:237], v[230:233], v[16:31]
	ds_read_b128 v[234:237], v192 offset:64
	s_waitcnt lgkmcnt(5)
	v_mfma_f32_32x32x16_bf16 v[64:79], v[238:241], v[226:229], v[64:79]
	v_mfma_f32_32x32x16_bf16 v[0:15], v[238:241], v[230:233], v[0:15]
	ds_read_b128 v[238:241], v192 offset:4672
	s_setprio 0
	global_load_dwordx4 v[226:229], v[184:185], off offset:1024
	global_load_dwordx4 v[230:233], v[186:187], off offset:1024
	s_setprio 1
	s_waitcnt lgkmcnt(1)
	v_mfma_f32_32x32x16_bf16 v[112:127], v[234:237], v[176:179], v[112:127]
	v_mfma_f32_32x32x16_bf16 v[48:63], v[234:237], v[180:183], v[48:63]
	s_waitcnt lgkmcnt(0)
	v_mfma_f32_32x32x16_bf16 v[96:111], v[238:241], v[176:179], v[96:111]
	v_mfma_f32_32x32x16_bf16 v[32:47], v[238:241], v[180:183], v[32:47]
	ds_read_b128 v[234:237], v192 offset:9280
	ds_read_b128 v[238:241], v192 offset:13888
	s_waitcnt vmcnt(7)
	ds_write_b128 v217, v[168:171]
	s_waitcnt vmcnt(6)
	ds_write_b128 v216, v[172:175]
	ds_read_b128 v[168:171], v204 offset:36960
	ds_read_b128 v[172:175], v204 offset:41568
	s_waitcnt lgkmcnt(5)
	v_mfma_f32_32x32x16_bf16 v[80:95], v[234:237], v[176:179], v[80:95]
	v_mfma_f32_32x32x16_bf16 v[16:31], v[234:237], v[180:183], v[16:31]
	ds_read_b128 v[234:237], v192 offset:96
	s_waitcnt lgkmcnt(5)
	v_mfma_f32_32x32x16_bf16 v[64:79], v[238:241], v[176:179], v[64:79]
	v_mfma_f32_32x32x16_bf16 v[0:15], v[238:241], v[180:183], v[0:15]
	ds_read_b128 v[238:241], v192 offset:4704
	s_setprio 0
	global_load_dwordx4 v[176:179], v[198:199], off offset:1024
	global_load_dwordx4 v[180:183], v[200:201], off offset:1024
	s_setprio 1
	s_waitcnt lgkmcnt(1)
	v_mfma_f32_32x32x16_bf16 v[112:127], v[234:237], v[168:171], v[112:127]
	v_mfma_f32_32x32x16_bf16 v[48:63], v[234:237], v[172:175], v[48:63]
	s_waitcnt lgkmcnt(0)
	v_mfma_f32_32x32x16_bf16 v[96:111], v[238:241], v[168:171], v[96:111]
	v_mfma_f32_32x32x16_bf16 v[32:47], v[238:241], v[172:175], v[32:47]
	ds_read_b128 v[234:237], v192 offset:9312
	ds_read_b128 v[238:241], v192 offset:13920
	s_waitcnt lgkmcnt(0)
	s_barrier
; template <bool trans>
; DI void gemm_core(const GTile& tl, const GTile& nx, bool has_next  , bool chain  , bool pre, u32x4 (&ra)[4], u32x4 (&rb)[4], char* smem, f32x16 (&acc)[2][4]) {
;     ...
;   const int nk = K / 64;
;   if (!pre) { G_LOAD(0); G_STORE(0); G_LOAD(1); }
;   for (int kt = 0; kt < nk; ++kt) {
;     __syncthreads();
;     G_COMPUTE(kt & 1, kt);
;   }
	s_waitcnt vmcnt(7)
	ds_write_b128 v215, v[160:163]
	s_waitcnt vmcnt(6)
	ds_write_b128 v215, v[164:167] offset:36864
	ds_read_b128 v[160:163], v208
	ds_read_b128 v[164:167], v208 offset:4608
	v_mfma_f32_32x32x16_bf16 v[80:95], v[234:237], v[168:171], v[80:95]
	v_mfma_f32_32x32x16_bf16 v[16:31], v[234:237], v[172:175], v[16:31]
	ds_read_b128 v[234:237], v205
	v_mfma_f32_32x32x16_bf16 v[64:79], v[238:241], v[168:171], v[64:79]
	v_mfma_f32_32x32x16_bf16 v[0:15], v[238:241], v[172:175], v[0:15]
	ds_read_b128 v[238:241], v205 offset:4608
	s_setprio 0
	global_load_dwordx4 v[168:171], v[190:191], off offset:1152
	global_load_dwordx4 v[172:175], v[188:189], off offset:1152
	s_setprio 1
	s_waitcnt lgkmcnt(1)
	v_mfma_f32_32x32x16_bf16 v[112:127], v[234:237], v[160:163], v[112:127]
	v_mfma_f32_32x32x16_bf16 v[48:63], v[234:237], v[164:167], v[48:63]
	s_waitcnt lgkmcnt(0)
	v_mfma_f32_32x32x16_bf16 v[96:111], v[238:241], v[160:163], v[96:111]
	v_mfma_f32_32x32x16_bf16 v[32:47], v[238:241], v[164:167], v[32:47]
	ds_read_b128 v[234:237], v205 offset:9216
	ds_read_b128 v[238:241], v205 offset:13824
	s_waitcnt vmcnt(7)
	ds_write_b128 v215, v[218:221] offset:9216
	s_waitcnt vmcnt(6)
	ds_write_b128 v215, v[222:225] offset:46080
	ds_read_b128 v[218:221], v208 offset:32
	ds_read_b128 v[222:225], v208 offset:4640
	s_waitcnt lgkmcnt(5)
	v_mfma_f32_32x32x16_bf16 v[80:95], v[234:237], v[160:163], v[80:95]
	v_mfma_f32_32x32x16_bf16 v[16:31], v[234:237], v[164:167], v[16:31]
	ds_read_b128 v[234:237], v205 offset:32
	s_waitcnt lgkmcnt(5)
	v_mfma_f32_32x32x16_bf16 v[64:79], v[238:241], v[160:163], v[64:79]
	v_mfma_f32_32x32x16_bf16 v[0:15], v[238:241], v[164:167], v[0:15]
	ds_read_b128 v[238:241], v205 offset:4640
	s_setprio 0
	global_load_dwordx4 v[160:163], v[194:195], off offset:1152
	global_load_dwordx4 v[164:167], v[196:197], off offset:1152
	s_setprio 1
	s_waitcnt lgkmcnt(1)
	v_mfma_f32_32x32x16_bf16 v[112:127], v[234:237], v[218:221], v[112:127]
	v_mfma_f32_32x32x16_bf16 v[48:63], v[234:237], v[222:225], v[48:63]
	s_waitcnt lgkmcnt(0)
	v_mfma_f32_32x32x16_bf16 v[96:111], v[238:241], v[218:221], v[96:111]
	v_mfma_f32_32x32x16_bf16 v[32:47], v[238:241], v[222:225], v[32:47]
	ds_read_b128 v[234:237], v205 offset:9248
	ds_read_b128 v[238:241], v205 offset:13856
	s_waitcnt vmcnt(7)
	ds_write_b128 v215, v[226:229] offset:18432
	s_waitcnt vmcnt(6)
	ds_write_b128 v215, v[230:233] offset:55296
	ds_read_b128 v[226:229], v208 offset:64
	ds_read_b128 v[230:233], v208 offset:4672
	s_waitcnt lgkmcnt(5)
	v_mfma_f32_32x32x16_bf16 v[80:95], v[234:237], v[218:221], v[80:95]
	v_mfma_f32_32x32x16_bf16 v[16:31], v[234:237], v[222:225], v[16:31]
	ds_read_b128 v[234:237], v205 offset:64
	s_waitcnt lgkmcnt(5)
	v_mfma_f32_32x32x16_bf16 v[64:79], v[238:241], v[218:221], v[64:79]
	v_mfma_f32_32x32x16_bf16 v[0:15], v[238:241], v[222:225], v[0:15]
	ds_read_b128 v[238:241], v205 offset:4672
	s_setprio 0
	global_load_dwordx4 v[218:221], v[184:185], off offset:1152
	global_load_dwordx4 v[222:225], v[186:187], off offset:1152
	s_setprio 1
	s_waitcnt lgkmcnt(1)
	v_mfma_f32_32x32x16_bf16 v[112:127], v[234:237], v[226:229], v[112:127]
	v_mfma_f32_32x32x16_bf16 v[48:63], v[234:237], v[230:233], v[48:63]
	s_waitcnt lgkmcnt(0)
	v_mfma_f32_32x32x16_bf16 v[96:111], v[238:241], v[226:229], v[96:111]
	v_mfma_f32_32x32x16_bf16 v[32:47], v[238:241], v[230:233], v[32:47]
	ds_read_b128 v[234:237], v205 offset:9280
	ds_read_b128 v[238:241], v205 offset:13888
	s_waitcnt vmcnt(7)
	ds_write_b128 v215, v[176:179] offset:27648
	s_waitcnt vmcnt(6)
	ds_write_b128 v215, v[180:183] offset:64512
	ds_read_b128 v[176:179], v208 offset:96
	ds_read_b128 v[180:183], v208 offset:4704
	s_waitcnt lgkmcnt(5)
	v_mfma_f32_32x32x16_bf16 v[80:95], v[234:237], v[226:229], v[80:95]
	v_mfma_f32_32x32x16_bf16 v[16:31], v[234:237], v[230:233], v[16:31]
	ds_read_b128 v[234:237], v205 offset:96
	s_waitcnt lgkmcnt(5)
	v_mfma_f32_32x32x16_bf16 v[64:79], v[238:241], v[226:229], v[64:79]
	v_mfma_f32_32x32x16_bf16 v[0:15], v[238:241], v[230:233], v[0:15]
	ds_read_b128 v[238:241], v205 offset:4704
	s_setprio 0
	global_load_dwordx4 v[226:229], v[198:199], off offset:1152
	global_load_dwordx4 v[230:233], v[200:201], off offset:1152
	s_setprio 1
	s_waitcnt lgkmcnt(1)
	v_mfma_f32_32x32x16_bf16 v[112:127], v[234:237], v[176:179], v[112:127]
	v_mfma_f32_32x32x16_bf16 v[48:63], v[234:237], v[180:183], v[48:63]
	s_waitcnt lgkmcnt(0)
	v_mfma_f32_32x32x16_bf16 v[96:111], v[238:241], v[176:179], v[96:111]
	v_mfma_f32_32x32x16_bf16 v[32:47], v[238:241], v[180:183], v[32:47]
	ds_read_b128 v[234:237], v205 offset:9312
	ds_read_b128 v[238:241], v205 offset:13920
	s_waitcnt lgkmcnt(0)
	s_barrier
; template <bool trans>
; DI void gemm_core(const GTile& tl, const GTile& nx, bool has_next  , bool chain  , bool pre, u32x4 (&ra)[4], u32x4 (&rb)[4], char* smem, f32x16 (&acc)[2][4]) {
;     ...
;   const int nk = K / 64;
;   if (!pre) { G_LOAD(0); G_STORE(0); G_LOAD(1); }
;   for (int kt = 0; kt < nk; ++kt) {
;     __syncthreads();
;     G_COMPUTE(kt & 1, kt);
;   }
	s_waitcnt vmcnt(7)
	ds_write_b128 v209, v[168:171]
	s_waitcnt vmcnt(6)
	ds_write_b128 v210, v[172:175]
	ds_read_b128 v[168:171], v204 offset:36864
	ds_read_b128 v[172:175], v204 offset:41472
	v_mfma_f32_32x32x16_bf16 v[80:95], v[234:237], v[176:179], v[80:95]
	v_mfma_f32_32x32x16_bf16 v[16:31], v[234:237], v[180:183], v[16:31]
	ds_read_b128 v[234:237], v192
	v_mfma_f32_32x32x16_bf16 v[64:79], v[238:241], v[176:179], v[64:79]
	v_mfma_f32_32x32x16_bf16 v[0:15], v[238:241], v[180:183], v[0:15]
	ds_read_b128 v[238:241], v192 offset:4608
	s_setprio 0
	global_load_dwordx4 v[176:179], v[190:191], off offset:1280
	global_load_dwordx4 v[180:183], v[188:189], off offset:1280
	s_setprio 1
	s_waitcnt lgkmcnt(1)
	v_mfma_f32_32x32x16_bf16 v[112:127], v[234:237], v[168:171], v[112:127]
	v_mfma_f32_32x32x16_bf16 v[48:63], v[234:237], v[172:175], v[48:63]
	s_waitcnt lgkmcnt(0)
	v_mfma_f32_32x32x16_bf16 v[96:111], v[238:241], v[168:171], v[96:111]
	v_mfma_f32_32x32x16_bf16 v[32:47], v[238:241], v[172:175], v[32:47]
	ds_read_b128 v[234:237], v192 offset:9216
	ds_read_b128 v[238:241], v192 offset:13824
	s_waitcnt vmcnt(7)
	ds_write_b128 v212, v[160:163]
	s_waitcnt vmcnt(6)
	ds_write_b128 v211, v[164:167]
	ds_read_b128 v[160:163], v204 offset:36896
	ds_read_b128 v[164:167], v204 offset:41504
	s_waitcnt lgkmcnt(5)
	v_mfma_f32_32x32x16_bf16 v[80:95], v[234:237], v[168:171], v[80:95]
	v_mfma_f32_32x32x16_bf16 v[16:31], v[234:237], v[172:175], v[16:31]
	ds_read_b128 v[234:237], v192 offset:32
	s_waitcnt lgkmcnt(5)
	v_mfma_f32_32x32x16_bf16 v[64:79], v[238:241], v[168:171], v[64:79]
	v_mfma_f32_32x32x16_bf16 v[0:15], v[238:241], v[172:175], v[0:15]
	ds_read_b128 v[238:241], v192 offset:4640
	s_setprio 0
	global_load_dwordx4 v[168:171], v[194:195], off offset:1280
	global_load_dwordx4 v[172:175], v[196:197], off offset:1280
	s_setprio 1
	s_waitcnt lgkmcnt(1)
	v_mfma_f32_32x32x16_bf16 v[112:127], v[234:237], v[160:163], v[112:127]
	v_mfma_f32_32x32x16_bf16 v[48:63], v[234:237], v[164:167], v[48:63]
	s_waitcnt lgkmcnt(0)
	v_mfma_f32_32x32x16_bf16 v[96:111], v[238:241], v[160:163], v[96:111]
	v_mfma_f32_32x32x16_bf16 v[32:47], v[238:241], v[164:167], v[32:47]
	ds_read_b128 v[234:237], v192 offset:9248
	ds_read_b128 v[238:241], v192 offset:13856
	s_waitcnt vmcnt(7)
	ds_write_b128 v214, v[218:221]
	s_waitcnt vmcnt(6)
	ds_write_b128 v213, v[222:225]
	ds_read_b128 v[218:221], v204 offset:36928
	ds_read_b128 v[222:225], v204 offset:41536
	s_waitcnt lgkmcnt(5)
	v_mfma_f32_32x32x16_bf16 v[80:95], v[234:237], v[160:163], v[80:95]
	v_mfma_f32_32x32x16_bf16 v[16:31], v[234:237], v[164:167], v[16:31]
	ds_read_b128 v[234:237], v192 offset:64
	s_waitcnt lgkmcnt(5)
	v_mfma_f32_32x32x16_bf16 v[64:79], v[238:241], v[160:163], v[64:79]
	v_mfma_f32_32x32x16_bf16 v[0:15], v[238:241], v[164:167], v[0:15]
	ds_read_b128 v[238:241], v192 offset:4672
	s_setprio 0
	global_load_dwordx4 v[160:163], v[184:185], off offset:1280
	global_load_dwordx4 v[164:167], v[186:187], off offset:1280
	s_setprio 1
	s_waitcnt lgkmcnt(1)
	v_mfma_f32_32x32x16_bf16 v[112:127], v[234:237], v[218:221], v[112:127]
	v_mfma_f32_32x32x16_bf16 v[48:63], v[234:237], v[222:225], v[48:63]
	s_waitcnt lgkmcnt(0)
	v_mfma_f32_32x32x16_bf16 v[96:111], v[238:241], v[218:221], v[96:111]
	v_mfma_f32_32x32x16_bf16 v[32:47], v[238:241], v[222:225], v[32:47]
	ds_read_b128 v[234:237], v192 offset:9280
	ds_read_b128 v[238:241], v192 offset:13888
	s_waitcnt vmcnt(7)
	ds_write_b128 v217, v[226:229]
	s_waitcnt vmcnt(6)
	ds_write_b128 v216, v[230:233]
	ds_read_b128 v[226:229], v204 offset:36960
	ds_read_b128 v[230:233], v204 offset:41568
	s_waitcnt lgkmcnt(5)
	v_mfma_f32_32x32x16_bf16 v[80:95], v[234:237], v[218:221], v[80:95]
	v_mfma_f32_32x32x16_bf16 v[16:31], v[234:237], v[222:225], v[16:31]
	ds_read_b128 v[234:237], v192 offset:96
	s_waitcnt lgkmcnt(5)
	v_mfma_f32_32x32x16_bf16 v[64:79], v[238:241], v[218:221], v[64:79]
	v_mfma_f32_32x32x16_bf16 v[0:15], v[238:241], v[222:225], v[0:15]
	ds_read_b128 v[238:241], v192 offset:4704
	s_setprio 0
	global_load_dwordx4 v[218:221], v[198:199], off offset:1280
	global_load_dwordx4 v[222:225], v[200:201], off offset:1280
	s_setprio 1
	s_waitcnt lgkmcnt(1)
	v_mfma_f32_32x32x16_bf16 v[112:127], v[234:237], v[226:229], v[112:127]
	v_mfma_f32_32x32x16_bf16 v[48:63], v[234:237], v[230:233], v[48:63]
	s_waitcnt lgkmcnt(0)
	v_mfma_f32_32x32x16_bf16 v[96:111], v[238:241], v[226:229], v[96:111]
	v_mfma_f32_32x32x16_bf16 v[32:47], v[238:241], v[230:233], v[32:47]
	ds_read_b128 v[234:237], v192 offset:9312
	ds_read_b128 v[238:241], v192 offset:13920
	s_waitcnt lgkmcnt(0)
	s_barrier
; template <bool trans>
; DI void gemm_core(const GTile& tl, const GTile& nx, bool has_next  , bool chain  , bool pre, u32x4 (&ra)[4], u32x4 (&rb)[4], char* smem, f32x16 (&acc)[2][4]) {
;     ...
;   const int nk = K / 64;
;   if (!pre) { G_LOAD(0); G_STORE(0); G_LOAD(1); }
;   for (int kt = 0; kt < nk; ++kt) {
;     __syncthreads();
;     G_COMPUTE(kt & 1, kt);
;   }
	s_waitcnt vmcnt(7)
	ds_write_b128 v215, v[176:179]
	s_waitcnt vmcnt(6)
	ds_write_b128 v215, v[180:183] offset:36864
	ds_read_b128 v[176:179], v208
	ds_read_b128 v[180:183], v208 offset:4608
	v_mfma_f32_32x32x16_bf16 v[80:95], v[234:237], v[226:229], v[80:95]
	v_mfma_f32_32x32x16_bf16 v[16:31], v[234:237], v[230:233], v[16:31]
	ds_read_b128 v[234:237], v205
	v_mfma_f32_32x32x16_bf16 v[64:79], v[238:241], v[226:229], v[64:79]
	v_mfma_f32_32x32x16_bf16 v[0:15], v[238:241], v[230:233], v[0:15]
	ds_read_b128 v[238:241], v205 offset:4608
	s_setprio 0
	global_load_dwordx4 v[226:229], v[190:191], off offset:1408
	global_load_dwordx4 v[230:233], v[188:189], off offset:1408
	s_setprio 1
	s_waitcnt lgkmcnt(1)
	v_mfma_f32_32x32x16_bf16 v[112:127], v[234:237], v[176:179], v[112:127]
	v_mfma_f32_32x32x16_bf16 v[48:63], v[234:237], v[180:183], v[48:63]
	s_waitcnt lgkmcnt(0)
	v_mfma_f32_32x32x16_bf16 v[96:111], v[238:241], v[176:179], v[96:111]
	v_mfma_f32_32x32x16_bf16 v[32:47], v[238:241], v[180:183], v[32:47]
	ds_read_b128 v[234:237], v205 offset:9216
	ds_read_b128 v[238:241], v205 offset:13824
	s_waitcnt vmcnt(7)
	ds_write_b128 v215, v[168:171] offset:9216
	s_waitcnt vmcnt(6)
	ds_write_b128 v215, v[172:175] offset:46080
	ds_read_b128 v[168:171], v208 offset:32
	ds_read_b128 v[172:175], v208 offset:4640
	s_waitcnt lgkmcnt(5)
	v_mfma_f32_32x32x16_bf16 v[80:95], v[234:237], v[176:179], v[80:95]
	v_mfma_f32_32x32x16_bf16 v[16:31], v[234:237], v[180:183], v[16:31]
	ds_read_b128 v[234:237], v205 offset:32
	s_waitcnt lgkmcnt(5)
	v_mfma_f32_32x32x16_bf16 v[64:79], v[238:241], v[176:179], v[64:79]
	v_mfma_f32_32x32x16_bf16 v[0:15], v[238:241], v[180:183], v[0:15]
	ds_read_b128 v[238:241], v205 offset:4640
	s_setprio 0
	global_load_dwordx4 v[176:179], v[194:195], off offset:1408
	global_load_dwordx4 v[180:183], v[196:197], off offset:1408
	s_setprio 1
	s_waitcnt lgkmcnt(1)
	v_mfma_f32_32x32x16_bf16 v[112:127], v[234:237], v[168:171], v[112:127]
	v_mfma_f32_32x32x16_bf16 v[48:63], v[234:237], v[172:175], v[48:63]
	s_waitcnt lgkmcnt(0)
	v_mfma_f32_32x32x16_bf16 v[96:111], v[238:241], v[168:171], v[96:111]
	v_mfma_f32_32x32x16_bf16 v[32:47], v[238:241], v[172:175], v[32:47]
	ds_read_b128 v[234:237], v205 offset:9248
	ds_read_b128 v[238:241], v205 offset:13856
	s_waitcnt vmcnt(7)
	ds_write_b128 v215, v[160:163] offset:18432
	s_waitcnt vmcnt(6)
	ds_write_b128 v215, v[164:167] offset:55296
	ds_read_b128 v[160:163], v208 offset:64
	ds_read_b128 v[164:167], v208 offset:4672
	s_waitcnt lgkmcnt(5)
	v_mfma_f32_32x32x16_bf16 v[80:95], v[234:237], v[168:171], v[80:95]
	v_mfma_f32_32x32x16_bf16 v[16:31], v[234:237], v[172:175], v[16:31]
	ds_read_b128 v[234:237], v205 offset:64
	s_waitcnt lgkmcnt(5)
	v_mfma_f32_32x32x16_bf16 v[64:79], v[238:241], v[168:171], v[64:79]
	v_mfma_f32_32x32x16_bf16 v[0:15], v[238:241], v[172:175], v[0:15]
	ds_read_b128 v[238:241], v205 offset:4672
	s_setprio 0
	global_load_dwordx4 v[168:171], v[184:185], off offset:1408
	global_load_dwordx4 v[172:175], v[186:187], off offset:1408
	s_setprio 1
	s_waitcnt lgkmcnt(1)
	v_mfma_f32_32x32x16_bf16 v[112:127], v[234:237], v[160:163], v[112:127]
	v_mfma_f32_32x32x16_bf16 v[48:63], v[234:237], v[164:167], v[48:63]
	s_waitcnt lgkmcnt(0)
	v_mfma_f32_32x32x16_bf16 v[96:111], v[238:241], v[160:163], v[96:111]
	v_mfma_f32_32x32x16_bf16 v[32:47], v[238:241], v[164:167], v[32:47]
	ds_read_b128 v[234:237], v205 offset:9280
	ds_read_b128 v[238:241], v205 offset:13888
	s_waitcnt vmcnt(7)
	ds_write_b128 v215, v[218:221] offset:27648
	s_waitcnt vmcnt(6)
	ds_write_b128 v215, v[222:225] offset:64512
	ds_read_b128 v[218:221], v208 offset:96
	ds_read_b128 v[222:225], v208 offset:4704
	s_waitcnt lgkmcnt(5)
	v_mfma_f32_32x32x16_bf16 v[80:95], v[234:237], v[160:163], v[80:95]
	v_mfma_f32_32x32x16_bf16 v[16:31], v[234:237], v[164:167], v[16:31]
	ds_read_b128 v[234:237], v205 offset:96
	s_waitcnt lgkmcnt(5)
	v_mfma_f32_32x32x16_bf16 v[64:79], v[238:241], v[160:163], v[64:79]
	v_mfma_f32_32x32x16_bf16 v[0:15], v[238:241], v[164:167], v[0:15]
	ds_read_b128 v[238:241], v205 offset:4704
	s_setprio 0
	global_load_dwordx4 v[160:163], v[198:199], off offset:1408
	global_load_dwordx4 v[164:167], v[200:201], off offset:1408
	s_setprio 1
	s_waitcnt lgkmcnt(1)
	v_mfma_f32_32x32x16_bf16 v[112:127], v[234:237], v[218:221], v[112:127]
	v_mfma_f32_32x32x16_bf16 v[48:63], v[234:237], v[222:225], v[48:63]
	s_waitcnt lgkmcnt(0)
	v_mfma_f32_32x32x16_bf16 v[96:111], v[238:241], v[218:221], v[96:111]
	v_mfma_f32_32x32x16_bf16 v[32:47], v[238:241], v[222:225], v[32:47]
	ds_read_b128 v[234:237], v205 offset:9312
	ds_read_b128 v[238:241], v205 offset:13920
	s_waitcnt lgkmcnt(0)
	s_barrier
; template <bool trans>
; DI void gemm_core(const GTile& tl, const GTile& nx, bool has_next  , bool chain  , bool pre, u32x4 (&ra)[4], u32x4 (&rb)[4], char* smem, f32x16 (&acc)[2][4]) {
;     ...
;   const int nk = K / 64;
;   if (!pre) { G_LOAD(0); G_STORE(0); G_LOAD(1); }
;   for (int kt = 0; kt < nk; ++kt) {
;     __syncthreads();
;     G_COMPUTE(kt & 1, kt);
;   }
	s_waitcnt vmcnt(7)
	ds_write_b128 v209, v[226:229]
	s_waitcnt vmcnt(6)
	ds_write_b128 v210, v[230:233]
	ds_read_b128 v[226:229], v204 offset:36864
	ds_read_b128 v[230:233], v204 offset:41472
	v_mfma_f32_32x32x16_bf16 v[80:95], v[234:237], v[218:221], v[80:95]
	v_mfma_f32_32x32x16_bf16 v[16:31], v[234:237], v[222:225], v[16:31]
	ds_read_b128 v[234:237], v192
	v_mfma_f32_32x32x16_bf16 v[64:79], v[238:241], v[218:221], v[64:79]
	v_mfma_f32_32x32x16_bf16 v[0:15], v[238:241], v[222:225], v[0:15]
	ds_read_b128 v[238:241], v192 offset:4608
	s_setprio 0
	global_load_dwordx4 v[218:221], v[190:191], off offset:1536
	global_load_dwordx4 v[222:225], v[188:189], off offset:1536
	s_setprio 1
	s_waitcnt lgkmcnt(1)
	v_mfma_f32_32x32x16_bf16 v[112:127], v[234:237], v[226:229], v[112:127]
	v_mfma_f32_32x32x16_bf16 v[48:63], v[234:237], v[230:233], v[48:63]
	s_waitcnt lgkmcnt(0)
	v_mfma_f32_32x32x16_bf16 v[96:111], v[238:241], v[226:229], v[96:111]
	v_mfma_f32_32x32x16_bf16 v[32:47], v[238:241], v[230:233], v[32:47]
	ds_read_b128 v[234:237], v192 offset:9216
	ds_read_b128 v[238:241], v192 offset:13824
	s_waitcnt vmcnt(7)
	ds_write_b128 v212, v[176:179]
	s_waitcnt vmcnt(6)
	ds_write_b128 v211, v[180:183]
	ds_read_b128 v[176:179], v204 offset:36896
	ds_read_b128 v[180:183], v204 offset:41504
	s_waitcnt lgkmcnt(5)
	v_mfma_f32_32x32x16_bf16 v[80:95], v[234:237], v[226:229], v[80:95]
	v_mfma_f32_32x32x16_bf16 v[16:31], v[234:237], v[230:233], v[16:31]
	ds_read_b128 v[234:237], v192 offset:32
	s_waitcnt lgkmcnt(5)
	v_mfma_f32_32x32x16_bf16 v[64:79], v[238:241], v[226:229], v[64:79]
	v_mfma_f32_32x32x16_bf16 v[0:15], v[238:241], v[230:233], v[0:15]
	ds_read_b128 v[238:241], v192 offset:4640
	s_setprio 0
	global_load_dwordx4 v[226:229], v[194:195], off offset:1536
	global_load_dwordx4 v[230:233], v[196:197], off offset:1536
	s_setprio 1
	s_waitcnt lgkmcnt(1)
	v_mfma_f32_32x32x16_bf16 v[112:127], v[234:237], v[176:179], v[112:127]
	v_mfma_f32_32x32x16_bf16 v[48:63], v[234:237], v[180:183], v[48:63]
	s_waitcnt lgkmcnt(0)
	v_mfma_f32_32x32x16_bf16 v[96:111], v[238:241], v[176:179], v[96:111]
	v_mfma_f32_32x32x16_bf16 v[32:47], v[238:241], v[180:183], v[32:47]
	ds_read_b128 v[234:237], v192 offset:9248
	ds_read_b128 v[238:241], v192 offset:13856
	s_waitcnt vmcnt(7)
	ds_write_b128 v214, v[168:171]
	s_waitcnt vmcnt(6)
	ds_write_b128 v213, v[172:175]
	ds_read_b128 v[168:171], v204 offset:36928
	ds_read_b128 v[172:175], v204 offset:41536
	s_waitcnt lgkmcnt(5)
	v_mfma_f32_32x32x16_bf16 v[80:95], v[234:237], v[176:179], v[80:95]
	v_mfma_f32_32x32x16_bf16 v[16:31], v[234:237], v[180:183], v[16:31]
	ds_read_b128 v[234:237], v192 offset:64
	s_waitcnt lgkmcnt(5)
	v_mfma_f32_32x32x16_bf16 v[64:79], v[238:241], v[176:179], v[64:79]
	v_mfma_f32_32x32x16_bf16 v[0:15], v[238:241], v[180:183], v[0:15]
	ds_read_b128 v[238:241], v192 offset:4672
	s_setprio 0
	global_load_dwordx4 v[176:179], v[184:185], off offset:1536
	global_load_dwordx4 v[180:183], v[186:187], off offset:1536
	s_setprio 1
	s_waitcnt lgkmcnt(1)
	v_mfma_f32_32x32x16_bf16 v[112:127], v[234:237], v[168:171], v[112:127]
	v_mfma_f32_32x32x16_bf16 v[48:63], v[234:237], v[172:175], v[48:63]
	s_waitcnt lgkmcnt(0)
	v_mfma_f32_32x32x16_bf16 v[96:111], v[238:241], v[168:171], v[96:111]
	v_mfma_f32_32x32x16_bf16 v[32:47], v[238:241], v[172:175], v[32:47]
	ds_read_b128 v[234:237], v192 offset:9280
	ds_read_b128 v[238:241], v192 offset:13888
	s_waitcnt vmcnt(7)
	ds_write_b128 v217, v[160:163]
	s_waitcnt vmcnt(6)
	ds_write_b128 v216, v[164:167]
	ds_read_b128 v[160:163], v204 offset:36960
	ds_read_b128 v[164:167], v204 offset:41568
	s_waitcnt lgkmcnt(5)
	v_mfma_f32_32x32x16_bf16 v[80:95], v[234:237], v[168:171], v[80:95]
	v_mfma_f32_32x32x16_bf16 v[16:31], v[234:237], v[172:175], v[16:31]
	ds_read_b128 v[234:237], v192 offset:96
	s_waitcnt lgkmcnt(5)
	v_mfma_f32_32x32x16_bf16 v[64:79], v[238:241], v[168:171], v[64:79]
	v_mfma_f32_32x32x16_bf16 v[0:15], v[238:241], v[172:175], v[0:15]
	ds_read_b128 v[238:241], v192 offset:4704
	s_setprio 0
	global_load_dwordx4 v[168:171], v[198:199], off offset:1536
	global_load_dwordx4 v[172:175], v[200:201], off offset:1536
	s_setprio 1
	s_waitcnt lgkmcnt(1)
	v_mfma_f32_32x32x16_bf16 v[112:127], v[234:237], v[160:163], v[112:127]
	v_mfma_f32_32x32x16_bf16 v[48:63], v[234:237], v[164:167], v[48:63]
	s_waitcnt lgkmcnt(0)
	v_mfma_f32_32x32x16_bf16 v[96:111], v[238:241], v[160:163], v[96:111]
	v_mfma_f32_32x32x16_bf16 v[32:47], v[238:241], v[164:167], v[32:47]
	ds_read_b128 v[234:237], v192 offset:9312
	ds_read_b128 v[238:241], v192 offset:13920
	s_waitcnt lgkmcnt(0)
	s_barrier
; template <bool trans>
; DI void gemm_core(const GTile& tl, const GTile& nx, bool has_next  , bool chain  , bool pre, u32x4 (&ra)[4], u32x4 (&rb)[4], char* smem, f32x16 (&acc)[2][4]) {
;     ...
;   const int nk = K / 64;
;   if (!pre) { G_LOAD(0); G_STORE(0); G_LOAD(1); }
;   for (int kt = 0; kt < nk; ++kt) {
;     __syncthreads();
;     G_COMPUTE(kt & 1, kt);
;   }
	s_waitcnt vmcnt(7)
	ds_write_b128 v215, v[218:221]
	s_waitcnt vmcnt(6)
	ds_write_b128 v215, v[222:225] offset:36864
	ds_read_b128 v[218:221], v208
	ds_read_b128 v[222:225], v208 offset:4608
	v_mfma_f32_32x32x16_bf16 v[80:95], v[234:237], v[160:163], v[80:95]
	v_mfma_f32_32x32x16_bf16 v[16:31], v[234:237], v[164:167], v[16:31]
	ds_read_b128 v[234:237], v205
	v_mfma_f32_32x32x16_bf16 v[64:79], v[238:241], v[160:163], v[64:79]
	v_mfma_f32_32x32x16_bf16 v[0:15], v[238:241], v[164:167], v[0:15]
	ds_read_b128 v[238:241], v205 offset:4608
	s_setprio 0
	global_load_dwordx4 v[160:163], v[190:191], off offset:1664
	global_load_dwordx4 v[164:167], v[188:189], off offset:1664
	s_setprio 1
	s_waitcnt lgkmcnt(1)
	v_mfma_f32_32x32x16_bf16 v[112:127], v[234:237], v[218:221], v[112:127]
	v_mfma_f32_32x32x16_bf16 v[48:63], v[234:237], v[222:225], v[48:63]
	s_waitcnt lgkmcnt(0)
	v_mfma_f32_32x32x16_bf16 v[96:111], v[238:241], v[218:221], v[96:111]
	v_mfma_f32_32x32x16_bf16 v[32:47], v[238:241], v[222:225], v[32:47]
	ds_read_b128 v[234:237], v205 offset:9216
	ds_read_b128 v[238:241], v205 offset:13824
	s_waitcnt vmcnt(7)
	ds_write_b128 v215, v[226:229] offset:9216
	s_waitcnt vmcnt(6)
	ds_write_b128 v215, v[230:233] offset:46080
	ds_read_b128 v[226:229], v208 offset:32
	ds_read_b128 v[230:233], v208 offset:4640
	s_waitcnt lgkmcnt(5)
	v_mfma_f32_32x32x16_bf16 v[80:95], v[234:237], v[218:221], v[80:95]
	v_mfma_f32_32x32x16_bf16 v[16:31], v[234:237], v[222:225], v[16:31]
	ds_read_b128 v[234:237], v205 offset:32
	s_waitcnt lgkmcnt(5)
	v_mfma_f32_32x32x16_bf16 v[64:79], v[238:241], v[218:221], v[64:79]
	v_mfma_f32_32x32x16_bf16 v[0:15], v[238:241], v[222:225], v[0:15]
	ds_read_b128 v[238:241], v205 offset:4640
	s_setprio 0
	global_load_dwordx4 v[218:221], v[194:195], off offset:1664
	global_load_dwordx4 v[222:225], v[196:197], off offset:1664
	s_setprio 1
	s_waitcnt lgkmcnt(1)
	v_mfma_f32_32x32x16_bf16 v[112:127], v[234:237], v[226:229], v[112:127]
	v_mfma_f32_32x32x16_bf16 v[48:63], v[234:237], v[230:233], v[48:63]
	s_waitcnt lgkmcnt(0)
	v_mfma_f32_32x32x16_bf16 v[96:111], v[238:241], v[226:229], v[96:111]
	v_mfma_f32_32x32x16_bf16 v[32:47], v[238:241], v[230:233], v[32:47]
	ds_read_b128 v[234:237], v205 offset:9248
	ds_read_b128 v[238:241], v205 offset:13856
	s_waitcnt vmcnt(7)
	ds_write_b128 v215, v[176:179] offset:18432
	s_waitcnt vmcnt(6)
	ds_write_b128 v215, v[180:183] offset:55296
	ds_read_b128 v[176:179], v208 offset:64
	ds_read_b128 v[180:183], v208 offset:4672
	s_waitcnt lgkmcnt(5)
	v_mfma_f32_32x32x16_bf16 v[80:95], v[234:237], v[226:229], v[80:95]
	v_mfma_f32_32x32x16_bf16 v[16:31], v[234:237], v[230:233], v[16:31]
	ds_read_b128 v[234:237], v205 offset:64
	s_waitcnt lgkmcnt(5)
	v_mfma_f32_32x32x16_bf16 v[64:79], v[238:241], v[226:229], v[64:79]
	v_mfma_f32_32x32x16_bf16 v[0:15], v[238:241], v[230:233], v[0:15]
	ds_read_b128 v[238:241], v205 offset:4672
	s_setprio 0
	global_load_dwordx4 v[226:229], v[184:185], off offset:1664
	global_load_dwordx4 v[230:233], v[186:187], off offset:1664
	s_setprio 1
	s_waitcnt lgkmcnt(1)
	v_mfma_f32_32x32x16_bf16 v[112:127], v[234:237], v[176:179], v[112:127]
	v_mfma_f32_32x32x16_bf16 v[48:63], v[234:237], v[180:183], v[48:63]
	s_waitcnt lgkmcnt(0)
	v_mfma_f32_32x32x16_bf16 v[96:111], v[238:241], v[176:179], v[96:111]
	v_mfma_f32_32x32x16_bf16 v[32:47], v[238:241], v[180:183], v[32:47]
	ds_read_b128 v[234:237], v205 offset:9280
	ds_read_b128 v[238:241], v205 offset:13888
	s_waitcnt vmcnt(7)
	ds_write_b128 v215, v[168:171] offset:27648
	s_waitcnt vmcnt(6)
	ds_write_b128 v215, v[172:175] offset:64512
	ds_read_b128 v[168:171], v208 offset:96
	ds_read_b128 v[172:175], v208 offset:4704
	s_waitcnt lgkmcnt(5)
	v_mfma_f32_32x32x16_bf16 v[80:95], v[234:237], v[176:179], v[80:95]
	v_mfma_f32_32x32x16_bf16 v[16:31], v[234:237], v[180:183], v[16:31]
	ds_read_b128 v[234:237], v205 offset:96
	s_waitcnt lgkmcnt(5)
	v_mfma_f32_32x32x16_bf16 v[64:79], v[238:241], v[176:179], v[64:79]
	v_mfma_f32_32x32x16_bf16 v[0:15], v[238:241], v[180:183], v[0:15]
	ds_read_b128 v[238:241], v205 offset:4704
	s_setprio 0
	global_load_dwordx4 v[176:179], v[198:199], off offset:1664
	global_load_dwordx4 v[180:183], v[200:201], off offset:1664
	s_setprio 1
	s_waitcnt lgkmcnt(1)
	v_mfma_f32_32x32x16_bf16 v[112:127], v[234:237], v[168:171], v[112:127]
	v_mfma_f32_32x32x16_bf16 v[48:63], v[234:237], v[172:175], v[48:63]
	s_waitcnt lgkmcnt(0)
	v_mfma_f32_32x32x16_bf16 v[96:111], v[238:241], v[168:171], v[96:111]
	v_mfma_f32_32x32x16_bf16 v[32:47], v[238:241], v[172:175], v[32:47]
	ds_read_b128 v[234:237], v205 offset:9312
	ds_read_b128 v[238:241], v205 offset:13920
	s_waitcnt lgkmcnt(0)
	s_barrier
; template <bool trans>
; DI void gemm_core(const GTile& tl, const GTile& nx, bool has_next  , bool chain  , bool pre, u32x4 (&ra)[4], u32x4 (&rb)[4], char* smem, f32x16 (&acc)[2][4]) {
;     ...
;   const int nk = K / 64;
;   if (!pre) { G_LOAD(0); G_STORE(0); G_LOAD(1); }
;   for (int kt = 0; kt < nk; ++kt) {
;     __syncthreads();
;     G_COMPUTE(kt & 1, kt);
;   }
	s_waitcnt vmcnt(7)
	ds_write_b128 v209, v[160:163]
	s_waitcnt vmcnt(6)
	ds_write_b128 v210, v[164:167]
	ds_read_b128 v[160:163], v204 offset:36864
	ds_read_b128 v[164:167], v204 offset:41472
	v_mfma_f32_32x32x16_bf16 v[80:95], v[234:237], v[168:171], v[80:95]
	v_mfma_f32_32x32x16_bf16 v[16:31], v[234:237], v[172:175], v[16:31]
	ds_read_b128 v[234:237], v192
	v_mfma_f32_32x32x16_bf16 v[64:79], v[238:241], v[168:171], v[64:79]
	v_mfma_f32_32x32x16_bf16 v[0:15], v[238:241], v[172:175], v[0:15]
	ds_read_b128 v[238:241], v192 offset:4608
	s_setprio 0
	global_load_dwordx4 v[168:171], v[190:191], off offset:1792
	global_load_dwordx4 v[172:175], v[188:189], off offset:1792
	s_setprio 1
	s_waitcnt lgkmcnt(1)
	v_mfma_f32_32x32x16_bf16 v[112:127], v[234:237], v[160:163], v[112:127]
	v_mfma_f32_32x32x16_bf16 v[48:63], v[234:237], v[164:167], v[48:63]
	s_waitcnt lgkmcnt(0)
	v_mfma_f32_32x32x16_bf16 v[96:111], v[238:241], v[160:163], v[96:111]
	v_mfma_f32_32x32x16_bf16 v[32:47], v[238:241], v[164:167], v[32:47]
	ds_read_b128 v[234:237], v192 offset:9216
	ds_read_b128 v[238:241], v192 offset:13824
	s_waitcnt vmcnt(7)
	ds_write_b128 v212, v[218:221]
	s_waitcnt vmcnt(6)
	ds_write_b128 v211, v[222:225]
	ds_read_b128 v[218:221], v204 offset:36896
	ds_read_b128 v[222:225], v204 offset:41504
	s_waitcnt lgkmcnt(5)
	v_mfma_f32_32x32x16_bf16 v[80:95], v[234:237], v[160:163], v[80:95]
	v_mfma_f32_32x32x16_bf16 v[16:31], v[234:237], v[164:167], v[16:31]
	ds_read_b128 v[234:237], v192 offset:32
	s_waitcnt lgkmcnt(5)
	v_mfma_f32_32x32x16_bf16 v[64:79], v[238:241], v[160:163], v[64:79]
	v_mfma_f32_32x32x16_bf16 v[0:15], v[238:241], v[164:167], v[0:15]
	ds_read_b128 v[238:241], v192 offset:4640
	s_setprio 0
	global_load_dwordx4 v[160:163], v[194:195], off offset:1792
	global_load_dwordx4 v[164:167], v[196:197], off offset:1792
	s_setprio 1
	s_waitcnt lgkmcnt(1)
	v_mfma_f32_32x32x16_bf16 v[112:127], v[234:237], v[218:221], v[112:127]
	v_mfma_f32_32x32x16_bf16 v[48:63], v[234:237], v[222:225], v[48:63]
	s_waitcnt lgkmcnt(0)
	v_mfma_f32_32x32x16_bf16 v[96:111], v[238:241], v[218:221], v[96:111]
	v_mfma_f32_32x32x16_bf16 v[32:47], v[238:241], v[222:225], v[32:47]
	ds_read_b128 v[234:237], v192 offset:9248
	ds_read_b128 v[238:241], v192 offset:13856
	s_waitcnt vmcnt(7)
	ds_write_b128 v214, v[226:229]
	s_waitcnt vmcnt(6)
	ds_write_b128 v213, v[230:233]
	ds_read_b128 v[226:229], v204 offset:36928
	ds_read_b128 v[230:233], v204 offset:41536
	s_waitcnt lgkmcnt(5)
	v_mfma_f32_32x32x16_bf16 v[80:95], v[234:237], v[218:221], v[80:95]
	v_mfma_f32_32x32x16_bf16 v[16:31], v[234:237], v[222:225], v[16:31]
	ds_read_b128 v[234:237], v192 offset:64
	s_waitcnt lgkmcnt(5)
	v_mfma_f32_32x32x16_bf16 v[64:79], v[238:241], v[218:221], v[64:79]
	v_mfma_f32_32x32x16_bf16 v[0:15], v[238:241], v[222:225], v[0:15]
	ds_read_b128 v[238:241], v192 offset:4672
	s_setprio 0
	global_load_dwordx4 v[218:221], v[184:185], off offset:1792
	global_load_dwordx4 v[222:225], v[186:187], off offset:1792
	s_setprio 1
	s_waitcnt lgkmcnt(1)
	v_mfma_f32_32x32x16_bf16 v[112:127], v[234:237], v[226:229], v[112:127]
	v_mfma_f32_32x32x16_bf16 v[48:63], v[234:237], v[230:233], v[48:63]
	s_waitcnt lgkmcnt(0)
	v_mfma_f32_32x32x16_bf16 v[96:111], v[238:241], v[226:229], v[96:111]
	v_mfma_f32_32x32x16_bf16 v[32:47], v[238:241], v[230:233], v[32:47]
	ds_read_b128 v[234:237], v192 offset:9280
	ds_read_b128 v[238:241], v192 offset:13888
	s_waitcnt vmcnt(7)
	ds_write_b128 v217, v[176:179]
	s_waitcnt vmcnt(6)
	ds_write_b128 v216, v[180:183]
	ds_read_b128 v[176:179], v204 offset:36960
	ds_read_b128 v[180:183], v204 offset:41568
	s_waitcnt lgkmcnt(5)
	v_mfma_f32_32x32x16_bf16 v[80:95], v[234:237], v[226:229], v[80:95]
	v_mfma_f32_32x32x16_bf16 v[16:31], v[234:237], v[230:233], v[16:31]
	ds_read_b128 v[234:237], v192 offset:96
	s_waitcnt lgkmcnt(5)
	v_mfma_f32_32x32x16_bf16 v[64:79], v[238:241], v[226:229], v[64:79]
	v_mfma_f32_32x32x16_bf16 v[0:15], v[238:241], v[230:233], v[0:15]
	ds_read_b128 v[238:241], v192 offset:4704
	s_setprio 0
	global_load_dwordx4 v[226:229], v[198:199], off offset:1792
	global_load_dwordx4 v[230:233], v[200:201], off offset:1792
	s_setprio 1
	s_waitcnt lgkmcnt(1)
	v_mfma_f32_32x32x16_bf16 v[112:127], v[234:237], v[176:179], v[112:127]
	v_mfma_f32_32x32x16_bf16 v[48:63], v[234:237], v[180:183], v[48:63]
	s_waitcnt lgkmcnt(0)
	v_mfma_f32_32x32x16_bf16 v[96:111], v[238:241], v[176:179], v[96:111]
	v_mfma_f32_32x32x16_bf16 v[32:47], v[238:241], v[180:183], v[32:47]
	ds_read_b128 v[234:237], v192 offset:9312
	ds_read_b128 v[238:241], v192 offset:13920
	s_waitcnt lgkmcnt(0)
	s_barrier
; template <bool trans>
; DI void gemm_core(const GTile& tl, const GTile& nx, bool has_next  , bool chain  , bool pre, u32x4 (&ra)[4], u32x4 (&rb)[4], char* smem, f32x16 (&acc)[2][4]) {
;     ...
;   const int nk = K / 64;
;   if (!pre) { G_LOAD(0); G_STORE(0); G_LOAD(1); }
;   for (int kt = 0; kt < nk; ++kt) {
;     __syncthreads();
;     G_COMPUTE(kt & 1, kt);
;   }
	s_waitcnt vmcnt(7)
	ds_write_b128 v215, v[168:171]
	s_waitcnt vmcnt(6)
	ds_write_b128 v215, v[172:175] offset:36864
	ds_read_b128 v[168:171], v208
	ds_read_b128 v[172:175], v208 offset:4608
	v_mfma_f32_32x32x16_bf16 v[80:95], v[234:237], v[176:179], v[80:95]
	v_mfma_f32_32x32x16_bf16 v[16:31], v[234:237], v[180:183], v[16:31]
	ds_read_b128 v[234:237], v205
	v_mfma_f32_32x32x16_bf16 v[64:79], v[238:241], v[176:179], v[64:79]
	v_mfma_f32_32x32x16_bf16 v[0:15], v[238:241], v[180:183], v[0:15]
	ds_read_b128 v[238:241], v205 offset:4608
	s_setprio 0
	global_load_dwordx4 v[176:179], v[190:191], off offset:1920
	global_load_dwordx4 v[180:183], v[188:189], off offset:1920
	s_setprio 1
	s_waitcnt lgkmcnt(1)
	v_mfma_f32_32x32x16_bf16 v[112:127], v[234:237], v[168:171], v[112:127]
	v_mfma_f32_32x32x16_bf16 v[48:63], v[234:237], v[172:175], v[48:63]
	s_waitcnt lgkmcnt(0)
	v_mfma_f32_32x32x16_bf16 v[96:111], v[238:241], v[168:171], v[96:111]
	v_mfma_f32_32x32x16_bf16 v[32:47], v[238:241], v[172:175], v[32:47]
	ds_read_b128 v[234:237], v205 offset:9216
	ds_read_b128 v[238:241], v205 offset:13824
	s_waitcnt vmcnt(7)
	ds_write_b128 v215, v[160:163] offset:9216
	s_waitcnt vmcnt(6)
	ds_write_b128 v215, v[164:167] offset:46080
	ds_read_b128 v[160:163], v208 offset:32
	ds_read_b128 v[164:167], v208 offset:4640
	s_waitcnt lgkmcnt(5)
	v_mfma_f32_32x32x16_bf16 v[80:95], v[234:237], v[168:171], v[80:95]
	v_mfma_f32_32x32x16_bf16 v[16:31], v[234:237], v[172:175], v[16:31]
	ds_read_b128 v[234:237], v205 offset:32
	s_waitcnt lgkmcnt(5)
	v_mfma_f32_32x32x16_bf16 v[64:79], v[238:241], v[168:171], v[64:79]
	v_mfma_f32_32x32x16_bf16 v[0:15], v[238:241], v[172:175], v[0:15]
	ds_read_b128 v[238:241], v205 offset:4640
	s_setprio 0
	global_load_dwordx4 v[168:171], v[194:195], off offset:1920
	global_load_dwordx4 v[172:175], v[196:197], off offset:1920
	s_setprio 1
	s_waitcnt lgkmcnt(1)
	v_mfma_f32_32x32x16_bf16 v[112:127], v[234:237], v[160:163], v[112:127]
	v_mfma_f32_32x32x16_bf16 v[48:63], v[234:237], v[164:167], v[48:63]
	s_waitcnt lgkmcnt(0)
	v_mfma_f32_32x32x16_bf16 v[96:111], v[238:241], v[160:163], v[96:111]
	v_mfma_f32_32x32x16_bf16 v[32:47], v[238:241], v[164:167], v[32:47]
	ds_read_b128 v[234:237], v205 offset:9248
	ds_read_b128 v[238:241], v205 offset:13856
	s_waitcnt vmcnt(7)
	ds_write_b128 v215, v[218:221] offset:18432
	s_waitcnt vmcnt(6)
	ds_write_b128 v215, v[222:225] offset:55296
	ds_read_b128 v[218:221], v208 offset:64
	ds_read_b128 v[222:225], v208 offset:4672
	s_waitcnt lgkmcnt(5)
	v_mfma_f32_32x32x16_bf16 v[80:95], v[234:237], v[160:163], v[80:95]
	v_mfma_f32_32x32x16_bf16 v[16:31], v[234:237], v[164:167], v[16:31]
	ds_read_b128 v[234:237], v205 offset:64
	s_waitcnt lgkmcnt(5)
	v_mfma_f32_32x32x16_bf16 v[64:79], v[238:241], v[160:163], v[64:79]
	v_mfma_f32_32x32x16_bf16 v[0:15], v[238:241], v[164:167], v[0:15]
	ds_read_b128 v[238:241], v205 offset:4672
	s_setprio 0
	global_load_dwordx4 v[160:163], v[184:185], off offset:1920
	global_load_dwordx4 v[164:167], v[186:187], off offset:1920
	s_setprio 1
	s_waitcnt lgkmcnt(1)
	v_mfma_f32_32x32x16_bf16 v[112:127], v[234:237], v[218:221], v[112:127]
	v_mfma_f32_32x32x16_bf16 v[48:63], v[234:237], v[222:225], v[48:63]
	s_waitcnt lgkmcnt(0)
	v_mfma_f32_32x32x16_bf16 v[96:111], v[238:241], v[218:221], v[96:111]
	v_mfma_f32_32x32x16_bf16 v[32:47], v[238:241], v[222:225], v[32:47]
	ds_read_b128 v[234:237], v205 offset:9280
	ds_read_b128 v[238:241], v205 offset:13888
	s_waitcnt vmcnt(7)
	ds_write_b128 v215, v[226:229] offset:27648
	s_waitcnt vmcnt(6)
	ds_write_b128 v215, v[230:233] offset:64512
	ds_read_b128 v[226:229], v208 offset:96
	ds_read_b128 v[230:233], v208 offset:4704
	s_waitcnt lgkmcnt(5)
	v_mfma_f32_32x32x16_bf16 v[80:95], v[234:237], v[218:221], v[80:95]
	v_mfma_f32_32x32x16_bf16 v[16:31], v[234:237], v[222:225], v[16:31]
	ds_read_b128 v[234:237], v205 offset:96
	s_waitcnt lgkmcnt(5)
	v_mfma_f32_32x32x16_bf16 v[64:79], v[238:241], v[218:221], v[64:79]
	v_mfma_f32_32x32x16_bf16 v[0:15], v[238:241], v[222:225], v[0:15]
	ds_read_b128 v[238:241], v205 offset:4704
	s_setprio 0
	global_load_dwordx4 v[218:221], v[198:199], off offset:1920
	global_load_dwordx4 v[222:225], v[200:201], off offset:1920
	s_setprio 1
	s_waitcnt lgkmcnt(1)
	v_mfma_f32_32x32x16_bf16 v[112:127], v[234:237], v[226:229], v[112:127]
	v_mfma_f32_32x32x16_bf16 v[48:63], v[234:237], v[230:233], v[48:63]
	s_waitcnt lgkmcnt(0)
	v_mfma_f32_32x32x16_bf16 v[96:111], v[238:241], v[226:229], v[96:111]
	v_mfma_f32_32x32x16_bf16 v[32:47], v[238:241], v[230:233], v[32:47]
	ds_read_b128 v[234:237], v205 offset:9312
	ds_read_b128 v[238:241], v205 offset:13920
	s_waitcnt lgkmcnt(0)
	s_barrier
; template <bool trans>
; DI void gemm_core(const GTile& tl, const GTile& nx, bool has_next  , bool chain  , bool pre, u32x4 (&ra)[4], u32x4 (&rb)[4], char* smem, f32x16 (&acc)[2][4]) {
;     ...
;   const int nk = K / 64;
;   if (!pre) { G_LOAD(0); G_STORE(0); G_LOAD(1); }
;   for (int kt = 0; kt < nk; ++kt) {
;     __syncthreads();
;     G_COMPUTE(kt & 1, kt);
;   }
	s_waitcnt vmcnt(7)
	ds_write_b128 v209, v[176:179]
	s_waitcnt vmcnt(6)
	ds_write_b128 v210, v[180:183]
	ds_read_b128 v[176:179], v204 offset:36864
	ds_read_b128 v[180:183], v204 offset:41472
	v_mfma_f32_32x32x16_bf16 v[80:95], v[234:237], v[226:229], v[80:95]
	v_mfma_f32_32x32x16_bf16 v[16:31], v[234:237], v[230:233], v[16:31]
	ds_read_b128 v[234:237], v192
	v_mfma_f32_32x32x16_bf16 v[64:79], v[238:241], v[226:229], v[64:79]
	v_mfma_f32_32x32x16_bf16 v[0:15], v[238:241], v[230:233], v[0:15]
	ds_read_b128 v[238:241], v192 offset:4608
	s_setprio 0
	global_load_dwordx4 v[226:229], v[190:191], off offset:2048
	global_load_dwordx4 v[230:233], v[188:189], off offset:2048
	s_setprio 1
	s_waitcnt lgkmcnt(1)
	v_mfma_f32_32x32x16_bf16 v[112:127], v[234:237], v[176:179], v[112:127]
	v_mfma_f32_32x32x16_bf16 v[48:63], v[234:237], v[180:183], v[48:63]
	s_waitcnt lgkmcnt(0)
	v_mfma_f32_32x32x16_bf16 v[96:111], v[238:241], v[176:179], v[96:111]
	v_mfma_f32_32x32x16_bf16 v[32:47], v[238:241], v[180:183], v[32:47]
	ds_read_b128 v[234:237], v192 offset:9216
	ds_read_b128 v[238:241], v192 offset:13824
	s_waitcnt vmcnt(7)
	ds_write_b128 v212, v[168:171]
	s_waitcnt vmcnt(6)
	ds_write_b128 v211, v[172:175]
	ds_read_b128 v[168:171], v204 offset:36896
	ds_read_b128 v[172:175], v204 offset:41504
	s_waitcnt lgkmcnt(5)
	v_mfma_f32_32x32x16_bf16 v[80:95], v[234:237], v[176:179], v[80:95]
	v_mfma_f32_32x32x16_bf16 v[16:31], v[234:237], v[180:183], v[16:31]
	ds_read_b128 v[234:237], v192 offset:32
	s_waitcnt lgkmcnt(5)
	v_mfma_f32_32x32x16_bf16 v[64:79], v[238:241], v[176:179], v[64:79]
	v_mfma_f32_32x32x16_bf16 v[0:15], v[238:241], v[180:183], v[0:15]
	ds_read_b128 v[238:241], v192 offset:4640
	s_setprio 0
	global_load_dwordx4 v[176:179], v[194:195], off offset:2048
	global_load_dwordx4 v[180:183], v[196:197], off offset:2048
	s_setprio 1
	s_waitcnt lgkmcnt(1)
	v_mfma_f32_32x32x16_bf16 v[112:127], v[234:237], v[168:171], v[112:127]
	v_mfma_f32_32x32x16_bf16 v[48:63], v[234:237], v[172:175], v[48:63]
	s_waitcnt lgkmcnt(0)
	v_mfma_f32_32x32x16_bf16 v[96:111], v[238:241], v[168:171], v[96:111]
	v_mfma_f32_32x32x16_bf16 v[32:47], v[238:241], v[172:175], v[32:47]
	ds_read_b128 v[234:237], v192 offset:9248
	ds_read_b128 v[238:241], v192 offset:13856
	s_waitcnt vmcnt(7)
	ds_write_b128 v214, v[160:163]
	s_waitcnt vmcnt(6)
	ds_write_b128 v213, v[164:167]
	ds_read_b128 v[160:163], v204 offset:36928
	ds_read_b128 v[164:167], v204 offset:41536
	s_waitcnt lgkmcnt(5)
	v_mfma_f32_32x32x16_bf16 v[80:95], v[234:237], v[168:171], v[80:95]
	v_mfma_f32_32x32x16_bf16 v[16:31], v[234:237], v[172:175], v[16:31]
	ds_read_b128 v[234:237], v192 offset:64
	s_waitcnt lgkmcnt(5)
	v_mfma_f32_32x32x16_bf16 v[64:79], v[238:241], v[168:171], v[64:79]
	v_mfma_f32_32x32x16_bf16 v[0:15], v[238:241], v[172:175], v[0:15]
	ds_read_b128 v[238:241], v192 offset:4672
	s_setprio 0
	global_load_dwordx4 v[168:171], v[184:185], off offset:2048
	global_load_dwordx4 v[172:175], v[186:187], off offset:2048
	s_setprio 1
	s_waitcnt lgkmcnt(1)
	v_mfma_f32_32x32x16_bf16 v[112:127], v[234:237], v[160:163], v[112:127]
	v_mfma_f32_32x32x16_bf16 v[48:63], v[234:237], v[164:167], v[48:63]
	s_waitcnt lgkmcnt(0)
	v_mfma_f32_32x32x16_bf16 v[96:111], v[238:241], v[160:163], v[96:111]
	v_mfma_f32_32x32x16_bf16 v[32:47], v[238:241], v[164:167], v[32:47]
	ds_read_b128 v[234:237], v192 offset:9280
	ds_read_b128 v[238:241], v192 offset:13888
	s_waitcnt vmcnt(7)
	ds_write_b128 v217, v[218:221]
	s_waitcnt vmcnt(6)
	ds_write_b128 v216, v[222:225]
	ds_read_b128 v[218:221], v204 offset:36960
	ds_read_b128 v[222:225], v204 offset:41568
	s_waitcnt lgkmcnt(5)
	v_mfma_f32_32x32x16_bf16 v[80:95], v[234:237], v[160:163], v[80:95]
	v_mfma_f32_32x32x16_bf16 v[16:31], v[234:237], v[164:167], v[16:31]
	ds_read_b128 v[234:237], v192 offset:96
	s_waitcnt lgkmcnt(5)
	v_mfma_f32_32x32x16_bf16 v[64:79], v[238:241], v[160:163], v[64:79]
	v_mfma_f32_32x32x16_bf16 v[0:15], v[238:241], v[164:167], v[0:15]
	ds_read_b128 v[238:241], v192 offset:4704
	s_setprio 0
	global_load_dwordx4 v[160:163], v[198:199], off offset:2048
	global_load_dwordx4 v[164:167], v[200:201], off offset:2048
	s_setprio 1
	s_waitcnt lgkmcnt(1)
	v_mfma_f32_32x32x16_bf16 v[112:127], v[234:237], v[218:221], v[112:127]
	v_mfma_f32_32x32x16_bf16 v[48:63], v[234:237], v[222:225], v[48:63]
	s_waitcnt lgkmcnt(0)
	v_mfma_f32_32x32x16_bf16 v[96:111], v[238:241], v[218:221], v[96:111]
	v_mfma_f32_32x32x16_bf16 v[32:47], v[238:241], v[222:225], v[32:47]
	ds_read_b128 v[234:237], v192 offset:9312
	ds_read_b128 v[238:241], v192 offset:13920
	s_waitcnt lgkmcnt(0)
	s_barrier
; template <bool trans>
; DI void gemm_core(const GTile& tl, const GTile& nx, bool has_next  , bool chain  , bool pre, u32x4 (&ra)[4], u32x4 (&rb)[4], char* smem, f32x16 (&acc)[2][4]) {
;     ...
;   const int nk = K / 64;
;   if (!pre) { G_LOAD(0); G_STORE(0); G_LOAD(1); }
;   for (int kt = 0; kt < nk; ++kt) {
;     __syncthreads();
;     G_COMPUTE(kt & 1, kt);
;   }
	s_waitcnt vmcnt(7)
	ds_write_b128 v215, v[226:229]
	s_waitcnt vmcnt(6)
	ds_write_b128 v215, v[230:233] offset:36864
	ds_read_b128 v[226:229], v208
	ds_read_b128 v[230:233], v208 offset:4608
	v_mfma_f32_32x32x16_bf16 v[80:95], v[234:237], v[218:221], v[80:95]
	v_mfma_f32_32x32x16_bf16 v[16:31], v[234:237], v[222:225], v[16:31]
	ds_read_b128 v[234:237], v205
	v_mfma_f32_32x32x16_bf16 v[64:79], v[238:241], v[218:221], v[64:79]
	v_mfma_f32_32x32x16_bf16 v[0:15], v[238:241], v[222:225], v[0:15]
	ds_read_b128 v[238:241], v205 offset:4608
	s_setprio 0
	global_load_dwordx4 v[218:221], v[190:191], off offset:2176
	global_load_dwordx4 v[222:225], v[188:189], off offset:2176
	s_setprio 1
	s_waitcnt lgkmcnt(1)
	v_mfma_f32_32x32x16_bf16 v[112:127], v[234:237], v[226:229], v[112:127]
	v_mfma_f32_32x32x16_bf16 v[48:63], v[234:237], v[230:233], v[48:63]
	s_waitcnt lgkmcnt(0)
	v_mfma_f32_32x32x16_bf16 v[96:111], v[238:241], v[226:229], v[96:111]
	v_mfma_f32_32x32x16_bf16 v[32:47], v[238:241], v[230:233], v[32:47]
	ds_read_b128 v[234:237], v205 offset:9216
	ds_read_b128 v[238:241], v205 offset:13824
	s_waitcnt vmcnt(7)
	ds_write_b128 v215, v[176:179] offset:9216
	s_waitcnt vmcnt(6)
	ds_write_b128 v215, v[180:183] offset:46080
	ds_read_b128 v[176:179], v208 offset:32
	ds_read_b128 v[180:183], v208 offset:4640
	s_waitcnt lgkmcnt(5)
	v_mfma_f32_32x32x16_bf16 v[80:95], v[234:237], v[226:229], v[80:95]
	v_mfma_f32_32x32x16_bf16 v[16:31], v[234:237], v[230:233], v[16:31]
	ds_read_b128 v[234:237], v205 offset:32
	s_waitcnt lgkmcnt(5)
	v_mfma_f32_32x32x16_bf16 v[64:79], v[238:241], v[226:229], v[64:79]
	v_mfma_f32_32x32x16_bf16 v[0:15], v[238:241], v[230:233], v[0:15]
	ds_read_b128 v[238:241], v205 offset:4640
	s_setprio 0
	global_load_dwordx4 v[226:229], v[194:195], off offset:2176
	global_load_dwordx4 v[230:233], v[196:197], off offset:2176
	s_setprio 1
	s_waitcnt lgkmcnt(1)
	v_mfma_f32_32x32x16_bf16 v[112:127], v[234:237], v[176:179], v[112:127]
	v_mfma_f32_32x32x16_bf16 v[48:63], v[234:237], v[180:183], v[48:63]
	s_waitcnt lgkmcnt(0)
	v_mfma_f32_32x32x16_bf16 v[96:111], v[238:241], v[176:179], v[96:111]
	v_mfma_f32_32x32x16_bf16 v[32:47], v[238:241], v[180:183], v[32:47]
	ds_read_b128 v[234:237], v205 offset:9248
	ds_read_b128 v[238:241], v205 offset:13856
	s_waitcnt vmcnt(7)
	ds_write_b128 v215, v[168:171] offset:18432
	s_waitcnt vmcnt(6)
	ds_write_b128 v215, v[172:175] offset:55296
	ds_read_b128 v[168:171], v208 offset:64
	ds_read_b128 v[172:175], v208 offset:4672
	s_waitcnt lgkmcnt(5)
	v_mfma_f32_32x32x16_bf16 v[80:95], v[234:237], v[176:179], v[80:95]
	v_mfma_f32_32x32x16_bf16 v[16:31], v[234:237], v[180:183], v[16:31]
	ds_read_b128 v[234:237], v205 offset:64
	s_waitcnt lgkmcnt(5)
	v_mfma_f32_32x32x16_bf16 v[64:79], v[238:241], v[176:179], v[64:79]
	v_mfma_f32_32x32x16_bf16 v[0:15], v[238:241], v[180:183], v[0:15]
	ds_read_b128 v[238:241], v205 offset:4672
	s_setprio 0
	global_load_dwordx4 v[176:179], v[184:185], off offset:2176
	global_load_dwordx4 v[180:183], v[186:187], off offset:2176
	s_setprio 1
	s_waitcnt lgkmcnt(1)
	v_mfma_f32_32x32x16_bf16 v[112:127], v[234:237], v[168:171], v[112:127]
	v_mfma_f32_32x32x16_bf16 v[48:63], v[234:237], v[172:175], v[48:63]
	s_waitcnt lgkmcnt(0)
	v_mfma_f32_32x32x16_bf16 v[96:111], v[238:241], v[168:171], v[96:111]
	v_mfma_f32_32x32x16_bf16 v[32:47], v[238:241], v[172:175], v[32:47]
	ds_read_b128 v[234:237], v205 offset:9280
	ds_read_b128 v[238:241], v205 offset:13888
	s_waitcnt vmcnt(7)
	ds_write_b128 v215, v[160:163] offset:27648
	s_waitcnt vmcnt(6)
	ds_write_b128 v215, v[164:167] offset:64512
	ds_read_b128 v[160:163], v208 offset:96
	ds_read_b128 v[164:167], v208 offset:4704
	s_waitcnt lgkmcnt(5)
	v_mfma_f32_32x32x16_bf16 v[80:95], v[234:237], v[168:171], v[80:95]
	v_mfma_f32_32x32x16_bf16 v[16:31], v[234:237], v[172:175], v[16:31]
	ds_read_b128 v[234:237], v205 offset:96
	s_waitcnt lgkmcnt(5)
	v_mfma_f32_32x32x16_bf16 v[64:79], v[238:241], v[168:171], v[64:79]
	v_mfma_f32_32x32x16_bf16 v[0:15], v[238:241], v[172:175], v[0:15]
	ds_read_b128 v[238:241], v205 offset:4704
	s_setprio 0
	global_load_dwordx4 v[168:171], v[198:199], off offset:2176
	global_load_dwordx4 v[172:175], v[200:201], off offset:2176
	s_setprio 1
	s_waitcnt lgkmcnt(1)
	v_mfma_f32_32x32x16_bf16 v[112:127], v[234:237], v[160:163], v[112:127]
	v_mfma_f32_32x32x16_bf16 v[48:63], v[234:237], v[164:167], v[48:63]
	s_waitcnt lgkmcnt(0)
	v_mfma_f32_32x32x16_bf16 v[96:111], v[238:241], v[160:163], v[96:111]
	v_mfma_f32_32x32x16_bf16 v[32:47], v[238:241], v[164:167], v[32:47]
	ds_read_b128 v[234:237], v205 offset:9312
	ds_read_b128 v[238:241], v205 offset:13920
	s_waitcnt lgkmcnt(0)
	s_barrier
; template <bool trans>
; DI void gemm_core(const GTile& tl, const GTile& nx, bool has_next  , bool chain  , bool pre, u32x4 (&ra)[4], u32x4 (&rb)[4], char* smem, f32x16 (&acc)[2][4]) {
;     ...
;   const int nk = K / 64;
;   if (!pre) { G_LOAD(0); G_STORE(0); G_LOAD(1); }
;   for (int kt = 0; kt < nk; ++kt) {
;     __syncthreads();
;     G_COMPUTE(kt & 1, kt);
;   }
	s_waitcnt vmcnt(7)
	ds_write_b128 v209, v[218:221]
	s_waitcnt vmcnt(6)
	ds_write_b128 v210, v[222:225]
	ds_read_b128 v[218:221], v204 offset:36864
	ds_read_b128 v[222:225], v204 offset:41472
	v_mfma_f32_32x32x16_bf16 v[80:95], v[234:237], v[160:163], v[80:95]
	v_mfma_f32_32x32x16_bf16 v[16:31], v[234:237], v[164:167], v[16:31]
	ds_read_b128 v[234:237], v192
	v_mfma_f32_32x32x16_bf16 v[64:79], v[238:241], v[160:163], v[64:79]
	v_mfma_f32_32x32x16_bf16 v[0:15], v[238:241], v[164:167], v[0:15]
	ds_read_b128 v[238:241], v192 offset:4608
	s_setprio 0
	global_load_dwordx4 v[160:163], v[190:191], off offset:2304
	global_load_dwordx4 v[164:167], v[188:189], off offset:2304
	s_setprio 1
	s_waitcnt lgkmcnt(1)
	v_mfma_f32_32x32x16_bf16 v[112:127], v[234:237], v[218:221], v[112:127]
	v_mfma_f32_32x32x16_bf16 v[48:63], v[234:237], v[222:225], v[48:63]
	s_waitcnt lgkmcnt(0)
	v_mfma_f32_32x32x16_bf16 v[96:111], v[238:241], v[218:221], v[96:111]
	v_mfma_f32_32x32x16_bf16 v[32:47], v[238:241], v[222:225], v[32:47]
	ds_read_b128 v[234:237], v192 offset:9216
	ds_read_b128 v[238:241], v192 offset:13824
	s_waitcnt vmcnt(7)
	ds_write_b128 v212, v[226:229]
	s_waitcnt vmcnt(6)
	ds_write_b128 v211, v[230:233]
	ds_read_b128 v[226:229], v204 offset:36896
	ds_read_b128 v[230:233], v204 offset:41504
	s_waitcnt lgkmcnt(5)
	v_mfma_f32_32x32x16_bf16 v[80:95], v[234:237], v[218:221], v[80:95]
	v_mfma_f32_32x32x16_bf16 v[16:31], v[234:237], v[222:225], v[16:31]
	ds_read_b128 v[234:237], v192 offset:32
	s_waitcnt lgkmcnt(5)
	v_mfma_f32_32x32x16_bf16 v[64:79], v[238:241], v[218:221], v[64:79]
	v_mfma_f32_32x32x16_bf16 v[0:15], v[238:241], v[222:225], v[0:15]
	ds_read_b128 v[238:241], v192 offset:4640
	s_setprio 0
	global_load_dwordx4 v[218:221], v[194:195], off offset:2304
	global_load_dwordx4 v[222:225], v[196:197], off offset:2304
	s_setprio 1
	s_waitcnt lgkmcnt(1)
	v_mfma_f32_32x32x16_bf16 v[112:127], v[234:237], v[226:229], v[112:127]
	v_mfma_f32_32x32x16_bf16 v[48:63], v[234:237], v[230:233], v[48:63]
	s_waitcnt lgkmcnt(0)
	v_mfma_f32_32x32x16_bf16 v[96:111], v[238:241], v[226:229], v[96:111]
	v_mfma_f32_32x32x16_bf16 v[32:47], v[238:241], v[230:233], v[32:47]
	ds_read_b128 v[234:237], v192 offset:9248
	ds_read_b128 v[238:241], v192 offset:13856
	s_waitcnt vmcnt(7)
	ds_write_b128 v214, v[176:179]
	s_waitcnt vmcnt(6)
	ds_write_b128 v213, v[180:183]
	ds_read_b128 v[176:179], v204 offset:36928
	ds_read_b128 v[180:183], v204 offset:41536
	s_waitcnt lgkmcnt(5)
	v_mfma_f32_32x32x16_bf16 v[80:95], v[234:237], v[226:229], v[80:95]
	v_mfma_f32_32x32x16_bf16 v[16:31], v[234:237], v[230:233], v[16:31]
	ds_read_b128 v[234:237], v192 offset:64
	s_waitcnt lgkmcnt(5)
	v_mfma_f32_32x32x16_bf16 v[64:79], v[238:241], v[226:229], v[64:79]
	v_mfma_f32_32x32x16_bf16 v[0:15], v[238:241], v[230:233], v[0:15]
	ds_read_b128 v[238:241], v192 offset:4672
	s_setprio 0
	global_load_dwordx4 v[226:229], v[184:185], off offset:2304
	global_load_dwordx4 v[230:233], v[186:187], off offset:2304
	s_setprio 1
	s_waitcnt lgkmcnt(1)
	v_mfma_f32_32x32x16_bf16 v[112:127], v[234:237], v[176:179], v[112:127]
	v_mfma_f32_32x32x16_bf16 v[48:63], v[234:237], v[180:183], v[48:63]
	s_waitcnt lgkmcnt(0)
	v_mfma_f32_32x32x16_bf16 v[96:111], v[238:241], v[176:179], v[96:111]
	v_mfma_f32_32x32x16_bf16 v[32:47], v[238:241], v[180:183], v[32:47]
	ds_read_b128 v[234:237], v192 offset:9280
	ds_read_b128 v[238:241], v192 offset:13888
	s_waitcnt vmcnt(7)
	ds_write_b128 v217, v[168:171]
	s_waitcnt vmcnt(6)
	ds_write_b128 v216, v[172:175]
	ds_read_b128 v[168:171], v204 offset:36960
	ds_read_b128 v[172:175], v204 offset:41568
	s_waitcnt lgkmcnt(5)
	v_mfma_f32_32x32x16_bf16 v[80:95], v[234:237], v[176:179], v[80:95]
	v_mfma_f32_32x32x16_bf16 v[16:31], v[234:237], v[180:183], v[16:31]
	ds_read_b128 v[234:237], v192 offset:96
	s_waitcnt lgkmcnt(5)
	v_mfma_f32_32x32x16_bf16 v[64:79], v[238:241], v[176:179], v[64:79]
	v_mfma_f32_32x32x16_bf16 v[0:15], v[238:241], v[180:183], v[0:15]
	ds_read_b128 v[238:241], v192 offset:4704
	s_setprio 0
	global_load_dwordx4 v[176:179], v[198:199], off offset:2304
	global_load_dwordx4 v[180:183], v[200:201], off offset:2304
	s_setprio 1
	s_waitcnt lgkmcnt(1)
	v_mfma_f32_32x32x16_bf16 v[112:127], v[234:237], v[168:171], v[112:127]
	v_mfma_f32_32x32x16_bf16 v[48:63], v[234:237], v[172:175], v[48:63]
	s_waitcnt lgkmcnt(0)
	v_mfma_f32_32x32x16_bf16 v[96:111], v[238:241], v[168:171], v[96:111]
	v_mfma_f32_32x32x16_bf16 v[32:47], v[238:241], v[172:175], v[32:47]
	ds_read_b128 v[234:237], v192 offset:9312
	ds_read_b128 v[238:241], v192 offset:13920
	s_waitcnt lgkmcnt(0)
	s_barrier
; template <bool trans>
; DI void gemm_core(const GTile& tl, const GTile& nx, bool has_next  , bool chain  , bool pre, u32x4 (&ra)[4], u32x4 (&rb)[4], char* smem, f32x16 (&acc)[2][4]) {
;     ...
;   const int nk = K / 64;
;   if (!pre) { G_LOAD(0); G_STORE(0); G_LOAD(1); }
;   for (int kt = 0; kt < nk; ++kt) {
;     __syncthreads();
;     G_COMPUTE(kt & 1, kt);
;   }
	s_waitcnt vmcnt(7)
	ds_write_b128 v215, v[160:163]
	s_waitcnt vmcnt(6)
	ds_write_b128 v215, v[164:167] offset:36864
	ds_read_b128 v[160:163], v208
	ds_read_b128 v[164:167], v208 offset:4608
	v_mfma_f32_32x32x16_bf16 v[80:95], v[234:237], v[168:171], v[80:95]
	v_mfma_f32_32x32x16_bf16 v[16:31], v[234:237], v[172:175], v[16:31]
	ds_read_b128 v[234:237], v205
	v_mfma_f32_32x32x16_bf16 v[64:79], v[238:241], v[168:171], v[64:79]
	v_mfma_f32_32x32x16_bf16 v[0:15], v[238:241], v[172:175], v[0:15]
	ds_read_b128 v[238:241], v205 offset:4608
	s_setprio 0
	global_load_dwordx4 v[168:171], v[190:191], off offset:2432
	global_load_dwordx4 v[172:175], v[188:189], off offset:2432
	s_setprio 1
	s_waitcnt lgkmcnt(1)
	v_mfma_f32_32x32x16_bf16 v[112:127], v[234:237], v[160:163], v[112:127]
	v_mfma_f32_32x32x16_bf16 v[48:63], v[234:237], v[164:167], v[48:63]
	s_waitcnt lgkmcnt(0)
	v_mfma_f32_32x32x16_bf16 v[96:111], v[238:241], v[160:163], v[96:111]
	v_mfma_f32_32x32x16_bf16 v[32:47], v[238:241], v[164:167], v[32:47]
	ds_read_b128 v[234:237], v205 offset:9216
	ds_read_b128 v[238:241], v205 offset:13824
	s_waitcnt vmcnt(7)
	ds_write_b128 v215, v[218:221] offset:9216
	s_waitcnt vmcnt(6)
	ds_write_b128 v215, v[222:225] offset:46080
	ds_read_b128 v[218:221], v208 offset:32
	ds_read_b128 v[222:225], v208 offset:4640
	s_waitcnt lgkmcnt(5)
	v_mfma_f32_32x32x16_bf16 v[80:95], v[234:237], v[160:163], v[80:95]
	v_mfma_f32_32x32x16_bf16 v[16:31], v[234:237], v[164:167], v[16:31]
	ds_read_b128 v[234:237], v205 offset:32
	s_waitcnt lgkmcnt(5)
	v_mfma_f32_32x32x16_bf16 v[64:79], v[238:241], v[160:163], v[64:79]
	v_mfma_f32_32x32x16_bf16 v[0:15], v[238:241], v[164:167], v[0:15]
	ds_read_b128 v[238:241], v205 offset:4640
	s_setprio 0
	global_load_dwordx4 v[160:163], v[194:195], off offset:2432
	global_load_dwordx4 v[164:167], v[196:197], off offset:2432
	s_setprio 1
	s_waitcnt lgkmcnt(1)
	v_mfma_f32_32x32x16_bf16 v[112:127], v[234:237], v[218:221], v[112:127]
	v_mfma_f32_32x32x16_bf16 v[48:63], v[234:237], v[222:225], v[48:63]
	s_waitcnt lgkmcnt(0)
	v_mfma_f32_32x32x16_bf16 v[96:111], v[238:241], v[218:221], v[96:111]
	v_mfma_f32_32x32x16_bf16 v[32:47], v[238:241], v[222:225], v[32:47]
	ds_read_b128 v[234:237], v205 offset:9248
	ds_read_b128 v[238:241], v205 offset:13856
	s_waitcnt vmcnt(7)
	ds_write_b128 v215, v[226:229] offset:18432
	s_waitcnt vmcnt(6)
	ds_write_b128 v215, v[230:233] offset:55296
	ds_read_b128 v[226:229], v208 offset:64
	ds_read_b128 v[230:233], v208 offset:4672
	s_waitcnt lgkmcnt(5)
	v_mfma_f32_32x32x16_bf16 v[80:95], v[234:237], v[218:221], v[80:95]
	v_mfma_f32_32x32x16_bf16 v[16:31], v[234:237], v[222:225], v[16:31]
	ds_read_b128 v[234:237], v205 offset:64
	s_waitcnt lgkmcnt(5)
	v_mfma_f32_32x32x16_bf16 v[64:79], v[238:241], v[218:221], v[64:79]
	v_mfma_f32_32x32x16_bf16 v[0:15], v[238:241], v[222:225], v[0:15]
	ds_read_b128 v[238:241], v205 offset:4672
	s_setprio 0
	global_load_dwordx4 v[218:221], v[184:185], off offset:2432
	global_load_dwordx4 v[222:225], v[186:187], off offset:2432
	s_setprio 1
	s_waitcnt lgkmcnt(1)
	v_mfma_f32_32x32x16_bf16 v[112:127], v[234:237], v[226:229], v[112:127]
	v_mfma_f32_32x32x16_bf16 v[48:63], v[234:237], v[230:233], v[48:63]
	s_waitcnt lgkmcnt(0)
	v_mfma_f32_32x32x16_bf16 v[96:111], v[238:241], v[226:229], v[96:111]
	v_mfma_f32_32x32x16_bf16 v[32:47], v[238:241], v[230:233], v[32:47]
	ds_read_b128 v[234:237], v205 offset:9280
	ds_read_b128 v[238:241], v205 offset:13888
	s_waitcnt vmcnt(7)
	ds_write_b128 v215, v[176:179] offset:27648
	s_waitcnt vmcnt(6)
	ds_write_b128 v215, v[180:183] offset:64512
	ds_read_b128 v[176:179], v208 offset:96
	ds_read_b128 v[180:183], v208 offset:4704
	s_waitcnt lgkmcnt(5)
	v_mfma_f32_32x32x16_bf16 v[80:95], v[234:237], v[226:229], v[80:95]
	v_mfma_f32_32x32x16_bf16 v[16:31], v[234:237], v[230:233], v[16:31]
	ds_read_b128 v[234:237], v205 offset:96
	s_waitcnt lgkmcnt(5)
	v_mfma_f32_32x32x16_bf16 v[64:79], v[238:241], v[226:229], v[64:79]
	v_mfma_f32_32x32x16_bf16 v[0:15], v[238:241], v[230:233], v[0:15]
	ds_read_b128 v[238:241], v205 offset:4704
	s_setprio 0
	global_load_dwordx4 v[226:229], v[198:199], off offset:2432
	global_load_dwordx4 v[230:233], v[200:201], off offset:2432
	s_setprio 1
	s_waitcnt lgkmcnt(1)
	v_mfma_f32_32x32x16_bf16 v[112:127], v[234:237], v[176:179], v[112:127]
	v_mfma_f32_32x32x16_bf16 v[48:63], v[234:237], v[180:183], v[48:63]
	s_waitcnt lgkmcnt(0)
	v_mfma_f32_32x32x16_bf16 v[96:111], v[238:241], v[176:179], v[96:111]
	v_mfma_f32_32x32x16_bf16 v[32:47], v[238:241], v[180:183], v[32:47]
	ds_read_b128 v[234:237], v205 offset:9312
	ds_read_b128 v[238:241], v205 offset:13920
	s_waitcnt lgkmcnt(0)
	s_barrier
; template <bool trans>
; DI void gemm_core(const GTile& tl, const GTile& nx, bool has_next  , bool chain  , bool pre, u32x4 (&ra)[4], u32x4 (&rb)[4], char* smem, f32x16 (&acc)[2][4]) {
;     ...
;   const int nk = K / 64;
;   if (!pre) { G_LOAD(0); G_STORE(0); G_LOAD(1); }
;   for (int kt = 0; kt < nk; ++kt) {
;     __syncthreads();
;     G_COMPUTE(kt & 1, kt);
;   }
	s_waitcnt vmcnt(7)
	ds_write_b128 v209, v[168:171]
	s_waitcnt vmcnt(6)
	ds_write_b128 v210, v[172:175]
	ds_read_b128 v[168:171], v204 offset:36864
	ds_read_b128 v[172:175], v204 offset:41472
	v_mfma_f32_32x32x16_bf16 v[80:95], v[234:237], v[176:179], v[80:95]
	v_mfma_f32_32x32x16_bf16 v[16:31], v[234:237], v[180:183], v[16:31]
	ds_read_b128 v[234:237], v192
	v_mfma_f32_32x32x16_bf16 v[64:79], v[238:241], v[176:179], v[64:79]
	v_mfma_f32_32x32x16_bf16 v[0:15], v[238:241], v[180:183], v[0:15]
	ds_read_b128 v[238:241], v192 offset:4608
	s_setprio 0
	global_load_dwordx4 v[176:179], v[190:191], off offset:2560
	global_load_dwordx4 v[180:183], v[188:189], off offset:2560
	s_setprio 1
	s_waitcnt lgkmcnt(1)
	v_mfma_f32_32x32x16_bf16 v[112:127], v[234:237], v[168:171], v[112:127]
	v_mfma_f32_32x32x16_bf16 v[48:63], v[234:237], v[172:175], v[48:63]
	s_waitcnt lgkmcnt(0)
	v_mfma_f32_32x32x16_bf16 v[96:111], v[238:241], v[168:171], v[96:111]
	v_mfma_f32_32x32x16_bf16 v[32:47], v[238:241], v[172:175], v[32:47]
	ds_read_b128 v[234:237], v192 offset:9216
	ds_read_b128 v[238:241], v192 offset:13824
	s_waitcnt vmcnt(7)
	ds_write_b128 v212, v[160:163]
	s_waitcnt vmcnt(6)
	ds_write_b128 v211, v[164:167]
	ds_read_b128 v[160:163], v204 offset:36896
	ds_read_b128 v[164:167], v204 offset:41504
	s_waitcnt lgkmcnt(5)
	v_mfma_f32_32x32x16_bf16 v[80:95], v[234:237], v[168:171], v[80:95]
	v_mfma_f32_32x32x16_bf16 v[16:31], v[234:237], v[172:175], v[16:31]
	ds_read_b128 v[234:237], v192 offset:32
	s_waitcnt lgkmcnt(5)
	v_mfma_f32_32x32x16_bf16 v[64:79], v[238:241], v[168:171], v[64:79]
	v_mfma_f32_32x32x16_bf16 v[0:15], v[238:241], v[172:175], v[0:15]
	ds_read_b128 v[238:241], v192 offset:4640
	s_setprio 0
	global_load_dwordx4 v[168:171], v[194:195], off offset:2560
	global_load_dwordx4 v[172:175], v[196:197], off offset:2560
	s_setprio 1
	s_waitcnt lgkmcnt(1)
	v_mfma_f32_32x32x16_bf16 v[112:127], v[234:237], v[160:163], v[112:127]
	v_mfma_f32_32x32x16_bf16 v[48:63], v[234:237], v[164:167], v[48:63]
	s_waitcnt lgkmcnt(0)
	v_mfma_f32_32x32x16_bf16 v[96:111], v[238:241], v[160:163], v[96:111]
	v_mfma_f32_32x32x16_bf16 v[32:47], v[238:241], v[164:167], v[32:47]
	ds_read_b128 v[234:237], v192 offset:9248
	ds_read_b128 v[238:241], v192 offset:13856
	s_waitcnt vmcnt(7)
	ds_write_b128 v214, v[218:221]
	s_waitcnt vmcnt(6)
	ds_write_b128 v213, v[222:225]
	ds_read_b128 v[218:221], v204 offset:36928
	ds_read_b128 v[222:225], v204 offset:41536
	s_waitcnt lgkmcnt(5)
	v_mfma_f32_32x32x16_bf16 v[80:95], v[234:237], v[160:163], v[80:95]
	v_mfma_f32_32x32x16_bf16 v[16:31], v[234:237], v[164:167], v[16:31]
	ds_read_b128 v[234:237], v192 offset:64
	s_waitcnt lgkmcnt(5)
	v_mfma_f32_32x32x16_bf16 v[64:79], v[238:241], v[160:163], v[64:79]
	v_mfma_f32_32x32x16_bf16 v[0:15], v[238:241], v[164:167], v[0:15]
	ds_read_b128 v[238:241], v192 offset:4672
	s_setprio 0
	global_load_dwordx4 v[160:163], v[184:185], off offset:2560
	global_load_dwordx4 v[164:167], v[186:187], off offset:2560
	s_setprio 1
	s_waitcnt lgkmcnt(1)
	v_mfma_f32_32x32x16_bf16 v[112:127], v[234:237], v[218:221], v[112:127]
	v_mfma_f32_32x32x16_bf16 v[48:63], v[234:237], v[222:225], v[48:63]
	s_waitcnt lgkmcnt(0)
	v_mfma_f32_32x32x16_bf16 v[96:111], v[238:241], v[218:221], v[96:111]
	v_mfma_f32_32x32x16_bf16 v[32:47], v[238:241], v[222:225], v[32:47]
	ds_read_b128 v[234:237], v192 offset:9280
	ds_read_b128 v[238:241], v192 offset:13888
	s_waitcnt vmcnt(7)
	ds_write_b128 v217, v[226:229]
	s_waitcnt vmcnt(6)
	ds_write_b128 v216, v[230:233]
	ds_read_b128 v[226:229], v204 offset:36960
	ds_read_b128 v[230:233], v204 offset:41568
	s_waitcnt lgkmcnt(5)
	v_mfma_f32_32x32x16_bf16 v[80:95], v[234:237], v[218:221], v[80:95]
	v_mfma_f32_32x32x16_bf16 v[16:31], v[234:237], v[222:225], v[16:31]
	ds_read_b128 v[234:237], v192 offset:96
	s_waitcnt lgkmcnt(5)
	v_mfma_f32_32x32x16_bf16 v[64:79], v[238:241], v[218:221], v[64:79]
	v_mfma_f32_32x32x16_bf16 v[0:15], v[238:241], v[222:225], v[0:15]
	ds_read_b128 v[238:241], v192 offset:4704
	s_setprio 0
	global_load_dwordx4 v[218:221], v[198:199], off offset:2560
	global_load_dwordx4 v[222:225], v[200:201], off offset:2560
	s_setprio 1
	s_waitcnt lgkmcnt(1)
	v_mfma_f32_32x32x16_bf16 v[112:127], v[234:237], v[226:229], v[112:127]
	v_mfma_f32_32x32x16_bf16 v[48:63], v[234:237], v[230:233], v[48:63]
	s_waitcnt lgkmcnt(0)
	v_mfma_f32_32x32x16_bf16 v[96:111], v[238:241], v[226:229], v[96:111]
	v_mfma_f32_32x32x16_bf16 v[32:47], v[238:241], v[230:233], v[32:47]
	ds_read_b128 v[234:237], v192 offset:9312
	ds_read_b128 v[238:241], v192 offset:13920
	s_waitcnt lgkmcnt(0)
	s_barrier
; template <bool trans>
; DI void gemm_core(const GTile& tl, const GTile& nx, bool has_next  , bool chain  , bool pre, u32x4 (&ra)[4], u32x4 (&rb)[4], char* smem, f32x16 (&acc)[2][4]) {
;     ...
;   const int nk = K / 64;
;   if (!pre) { G_LOAD(0); G_STORE(0); G_LOAD(1); }
;   for (int kt = 0; kt < nk; ++kt) {
;     __syncthreads();
;     G_COMPUTE(kt & 1, kt);
;   }
	s_waitcnt vmcnt(7)
	ds_write_b128 v215, v[176:179]
	s_waitcnt vmcnt(6)
	ds_write_b128 v215, v[180:183] offset:36864
	ds_read_b128 v[176:179], v208
	ds_read_b128 v[180:183], v208 offset:4608
	v_mfma_f32_32x32x16_bf16 v[80:95], v[234:237], v[226:229], v[80:95]
	v_mfma_f32_32x32x16_bf16 v[16:31], v[234:237], v[230:233], v[16:31]
	ds_read_b128 v[234:237], v205
	v_mfma_f32_32x32x16_bf16 v[64:79], v[238:241], v[226:229], v[64:79]
	v_mfma_f32_32x32x16_bf16 v[0:15], v[238:241], v[230:233], v[0:15]
	ds_read_b128 v[238:241], v205 offset:4608
	s_setprio 0
	global_load_dwordx4 v[226:229], v[190:191], off offset:2688
	global_load_dwordx4 v[230:233], v[188:189], off offset:2688
	s_setprio 1
	s_waitcnt lgkmcnt(1)
	v_mfma_f32_32x32x16_bf16 v[112:127], v[234:237], v[176:179], v[112:127]
	v_mfma_f32_32x32x16_bf16 v[48:63], v[234:237], v[180:183], v[48:63]
	s_waitcnt lgkmcnt(0)
	v_mfma_f32_32x32x16_bf16 v[96:111], v[238:241], v[176:179], v[96:111]
	v_mfma_f32_32x32x16_bf16 v[32:47], v[238:241], v[180:183], v[32:47]
	ds_read_b128 v[234:237], v205 offset:9216
	ds_read_b128 v[238:241], v205 offset:13824
	s_waitcnt vmcnt(7)
	ds_write_b128 v215, v[168:171] offset:9216
	s_waitcnt vmcnt(6)
	ds_write_b128 v215, v[172:175] offset:46080
	ds_read_b128 v[168:171], v208 offset:32
	ds_read_b128 v[172:175], v208 offset:4640
	s_waitcnt lgkmcnt(5)
	v_mfma_f32_32x32x16_bf16 v[80:95], v[234:237], v[176:179], v[80:95]
	v_mfma_f32_32x32x16_bf16 v[16:31], v[234:237], v[180:183], v[16:31]
	ds_read_b128 v[234:237], v205 offset:32
	s_waitcnt lgkmcnt(5)
	v_mfma_f32_32x32x16_bf16 v[64:79], v[238:241], v[176:179], v[64:79]
	v_mfma_f32_32x32x16_bf16 v[0:15], v[238:241], v[180:183], v[0:15]
	ds_read_b128 v[238:241], v205 offset:4640
	s_setprio 0
	global_load_dwordx4 v[176:179], v[194:195], off offset:2688
	global_load_dwordx4 v[180:183], v[196:197], off offset:2688
	s_setprio 1
	s_waitcnt lgkmcnt(1)
	v_mfma_f32_32x32x16_bf16 v[112:127], v[234:237], v[168:171], v[112:127]
	v_mfma_f32_32x32x16_bf16 v[48:63], v[234:237], v[172:175], v[48:63]
	s_waitcnt lgkmcnt(0)
	v_mfma_f32_32x32x16_bf16 v[96:111], v[238:241], v[168:171], v[96:111]
	v_mfma_f32_32x32x16_bf16 v[32:47], v[238:241], v[172:175], v[32:47]
	ds_read_b128 v[234:237], v205 offset:9248
	ds_read_b128 v[238:241], v205 offset:13856
	s_waitcnt vmcnt(7)
	ds_write_b128 v215, v[160:163] offset:18432
	s_waitcnt vmcnt(6)
	ds_write_b128 v215, v[164:167] offset:55296
	ds_read_b128 v[160:163], v208 offset:64
	ds_read_b128 v[164:167], v208 offset:4672
	s_waitcnt lgkmcnt(5)
	v_mfma_f32_32x32x16_bf16 v[80:95], v[234:237], v[168:171], v[80:95]
	v_mfma_f32_32x32x16_bf16 v[16:31], v[234:237], v[172:175], v[16:31]
	ds_read_b128 v[234:237], v205 offset:64
	s_waitcnt lgkmcnt(5)
	v_mfma_f32_32x32x16_bf16 v[64:79], v[238:241], v[168:171], v[64:79]
	v_mfma_f32_32x32x16_bf16 v[0:15], v[238:241], v[172:175], v[0:15]
	ds_read_b128 v[238:241], v205 offset:4672
	s_setprio 0
	global_load_dwordx4 v[168:171], v[184:185], off offset:2688
	global_load_dwordx4 v[172:175], v[186:187], off offset:2688
	s_setprio 1
	s_waitcnt lgkmcnt(1)
	v_mfma_f32_32x32x16_bf16 v[112:127], v[234:237], v[160:163], v[112:127]
	v_mfma_f32_32x32x16_bf16 v[48:63], v[234:237], v[164:167], v[48:63]
	s_waitcnt lgkmcnt(0)
	v_mfma_f32_32x32x16_bf16 v[96:111], v[238:241], v[160:163], v[96:111]
	v_mfma_f32_32x32x16_bf16 v[32:47], v[238:241], v[164:167], v[32:47]
	ds_read_b128 v[234:237], v205 offset:9280
	ds_read_b128 v[238:241], v205 offset:13888
	s_waitcnt vmcnt(7)
	ds_write_b128 v215, v[218:221] offset:27648
	s_waitcnt vmcnt(6)
	ds_write_b128 v215, v[222:225] offset:64512
	ds_read_b128 v[218:221], v208 offset:96
	ds_read_b128 v[222:225], v208 offset:4704
	s_waitcnt lgkmcnt(5)
	v_mfma_f32_32x32x16_bf16 v[80:95], v[234:237], v[160:163], v[80:95]
	v_mfma_f32_32x32x16_bf16 v[16:31], v[234:237], v[164:167], v[16:31]
	ds_read_b128 v[234:237], v205 offset:96
	s_waitcnt lgkmcnt(5)
	v_mfma_f32_32x32x16_bf16 v[64:79], v[238:241], v[160:163], v[64:79]
	v_mfma_f32_32x32x16_bf16 v[0:15], v[238:241], v[164:167], v[0:15]
	ds_read_b128 v[238:241], v205 offset:4704
	s_setprio 0
	global_load_dwordx4 v[160:163], v[198:199], off offset:2688
	global_load_dwordx4 v[164:167], v[200:201], off offset:2688
	s_setprio 1
	s_waitcnt lgkmcnt(1)
	v_mfma_f32_32x32x16_bf16 v[112:127], v[234:237], v[218:221], v[112:127]
	v_mfma_f32_32x32x16_bf16 v[48:63], v[234:237], v[222:225], v[48:63]
	s_waitcnt lgkmcnt(0)
	v_mfma_f32_32x32x16_bf16 v[96:111], v[238:241], v[218:221], v[96:111]
	v_mfma_f32_32x32x16_bf16 v[32:47], v[238:241], v[222:225], v[32:47]
	ds_read_b128 v[234:237], v205 offset:9312
	ds_read_b128 v[238:241], v205 offset:13920
	s_waitcnt lgkmcnt(0)
	s_barrier
; template <bool trans>
; DI void gemm_core(const GTile& tl, const GTile& nx, bool has_next  , bool chain  , bool pre, u32x4 (&ra)[4], u32x4 (&rb)[4], char* smem, f32x16 (&acc)[2][4]) {
;     ...
;   const int nk = K / 64;
;   if (!pre) { G_LOAD(0); G_STORE(0); G_LOAD(1); }
;   for (int kt = 0; kt < nk; ++kt) {
;     __syncthreads();
;     G_COMPUTE(kt & 1, kt);
;   }
	s_waitcnt vmcnt(7)
	ds_write_b128 v209, v[226:229]
	s_waitcnt vmcnt(6)
	ds_write_b128 v210, v[230:233]
	ds_read_b128 v[226:229], v204 offset:36864
	ds_read_b128 v[230:233], v204 offset:41472
	v_mfma_f32_32x32x16_bf16 v[80:95], v[234:237], v[218:221], v[80:95]
	v_mfma_f32_32x32x16_bf16 v[16:31], v[234:237], v[222:225], v[16:31]
	ds_read_b128 v[234:237], v192
	v_mfma_f32_32x32x16_bf16 v[64:79], v[238:241], v[218:221], v[64:79]
	v_mfma_f32_32x32x16_bf16 v[0:15], v[238:241], v[222:225], v[0:15]
	ds_read_b128 v[238:241], v192 offset:4608
	s_setprio 0
	global_load_dwordx4 v[218:221], v[190:191], off offset:2816
	global_load_dwordx4 v[222:225], v[188:189], off offset:2816
	s_setprio 1
	s_waitcnt lgkmcnt(1)
	v_mfma_f32_32x32x16_bf16 v[112:127], v[234:237], v[226:229], v[112:127]
	v_mfma_f32_32x32x16_bf16 v[48:63], v[234:237], v[230:233], v[48:63]
	s_waitcnt lgkmcnt(0)
	v_mfma_f32_32x32x16_bf16 v[96:111], v[238:241], v[226:229], v[96:111]
	v_mfma_f32_32x32x16_bf16 v[32:47], v[238:241], v[230:233], v[32:47]
	ds_read_b128 v[234:237], v192 offset:9216
	ds_read_b128 v[238:241], v192 offset:13824
	s_waitcnt vmcnt(7)
	ds_write_b128 v212, v[176:179]
	s_waitcnt vmcnt(6)
	ds_write_b128 v211, v[180:183]
	ds_read_b128 v[176:179], v204 offset:36896
	ds_read_b128 v[180:183], v204 offset:41504
	s_waitcnt lgkmcnt(5)
	v_mfma_f32_32x32x16_bf16 v[80:95], v[234:237], v[226:229], v[80:95]
	v_mfma_f32_32x32x16_bf16 v[16:31], v[234:237], v[230:233], v[16:31]
	ds_read_b128 v[234:237], v192 offset:32
	s_waitcnt lgkmcnt(5)
	v_mfma_f32_32x32x16_bf16 v[64:79], v[238:241], v[226:229], v[64:79]
	v_mfma_f32_32x32x16_bf16 v[0:15], v[238:241], v[230:233], v[0:15]
	ds_read_b128 v[238:241], v192 offset:4640
	s_setprio 0
	global_load_dwordx4 v[226:229], v[194:195], off offset:2816
	global_load_dwordx4 v[230:233], v[196:197], off offset:2816
	s_setprio 1
	s_waitcnt lgkmcnt(1)
	v_mfma_f32_32x32x16_bf16 v[112:127], v[234:237], v[176:179], v[112:127]
	v_mfma_f32_32x32x16_bf16 v[48:63], v[234:237], v[180:183], v[48:63]
	s_waitcnt lgkmcnt(0)
	v_mfma_f32_32x32x16_bf16 v[96:111], v[238:241], v[176:179], v[96:111]
	v_mfma_f32_32x32x16_bf16 v[32:47], v[238:241], v[180:183], v[32:47]
	ds_read_b128 v[234:237], v192 offset:9248
	ds_read_b128 v[238:241], v192 offset:13856
	s_waitcnt vmcnt(7)
	ds_write_b128 v214, v[168:171]
	s_waitcnt vmcnt(6)
	ds_write_b128 v213, v[172:175]
	ds_read_b128 v[168:171], v204 offset:36928
	ds_read_b128 v[172:175], v204 offset:41536
	s_waitcnt lgkmcnt(5)
	v_mfma_f32_32x32x16_bf16 v[80:95], v[234:237], v[176:179], v[80:95]
	v_mfma_f32_32x32x16_bf16 v[16:31], v[234:237], v[180:183], v[16:31]
	ds_read_b128 v[234:237], v192 offset:64
	s_waitcnt lgkmcnt(5)
	v_mfma_f32_32x32x16_bf16 v[64:79], v[238:241], v[176:179], v[64:79]
	v_mfma_f32_32x32x16_bf16 v[0:15], v[238:241], v[180:183], v[0:15]
	ds_read_b128 v[238:241], v192 offset:4672
	s_setprio 0
	global_load_dwordx4 v[176:179], v[184:185], off offset:2816
	global_load_dwordx4 v[180:183], v[186:187], off offset:2816
	s_setprio 1
	s_waitcnt lgkmcnt(1)
	v_mfma_f32_32x32x16_bf16 v[112:127], v[234:237], v[168:171], v[112:127]
	v_mfma_f32_32x32x16_bf16 v[48:63], v[234:237], v[172:175], v[48:63]
	s_waitcnt lgkmcnt(0)
	v_mfma_f32_32x32x16_bf16 v[96:111], v[238:241], v[168:171], v[96:111]
	v_mfma_f32_32x32x16_bf16 v[32:47], v[238:241], v[172:175], v[32:47]
	ds_read_b128 v[234:237], v192 offset:9280
	ds_read_b128 v[238:241], v192 offset:13888
	s_waitcnt vmcnt(7)
	ds_write_b128 v217, v[160:163]
	s_waitcnt vmcnt(6)
	ds_write_b128 v216, v[164:167]
	ds_read_b128 v[160:163], v204 offset:36960
	ds_read_b128 v[164:167], v204 offset:41568
	s_waitcnt lgkmcnt(5)
	v_mfma_f32_32x32x16_bf16 v[80:95], v[234:237], v[168:171], v[80:95]
	v_mfma_f32_32x32x16_bf16 v[16:31], v[234:237], v[172:175], v[16:31]
	ds_read_b128 v[234:237], v192 offset:96
	s_waitcnt lgkmcnt(5)
	v_mfma_f32_32x32x16_bf16 v[64:79], v[238:241], v[168:171], v[64:79]
	v_mfma_f32_32x32x16_bf16 v[0:15], v[238:241], v[172:175], v[0:15]
	ds_read_b128 v[238:241], v192 offset:4704
	s_setprio 0
	global_load_dwordx4 v[168:171], v[198:199], off offset:2816
	global_load_dwordx4 v[172:175], v[200:201], off offset:2816
	s_setprio 1
	s_waitcnt lgkmcnt(1)
	v_mfma_f32_32x32x16_bf16 v[112:127], v[234:237], v[160:163], v[112:127]
	v_mfma_f32_32x32x16_bf16 v[48:63], v[234:237], v[164:167], v[48:63]
	s_waitcnt lgkmcnt(0)
	v_mfma_f32_32x32x16_bf16 v[96:111], v[238:241], v[160:163], v[96:111]
	v_mfma_f32_32x32x16_bf16 v[32:47], v[238:241], v[164:167], v[32:47]
	ds_read_b128 v[234:237], v192 offset:9312
	ds_read_b128 v[238:241], v192 offset:13920
	s_waitcnt lgkmcnt(0)
	s_barrier
; template <bool trans>
; DI void gemm_core(const GTile& tl, const GTile& nx, bool has_next  , bool chain  , bool pre, u32x4 (&ra)[4], u32x4 (&rb)[4], char* smem, f32x16 (&acc)[2][4]) {
;     ...
;   const int nk = K / 64;
;   if (!pre) { G_LOAD(0); G_STORE(0); G_LOAD(1); }
;   for (int kt = 0; kt < nk; ++kt) {
;     __syncthreads();
;     G_COMPUTE(kt & 1, kt);
;   }
	s_waitcnt vmcnt(7)
	ds_write_b128 v215, v[218:221]
	s_waitcnt vmcnt(6)
	ds_write_b128 v215, v[222:225] offset:36864
	ds_read_b128 v[218:221], v208
	ds_read_b128 v[222:225], v208 offset:4608
	v_mfma_f32_32x32x16_bf16 v[80:95], v[234:237], v[160:163], v[80:95]
	v_mfma_f32_32x32x16_bf16 v[16:31], v[234:237], v[164:167], v[16:31]
	ds_read_b128 v[234:237], v205
	v_mfma_f32_32x32x16_bf16 v[64:79], v[238:241], v[160:163], v[64:79]
	v_mfma_f32_32x32x16_bf16 v[0:15], v[238:241], v[164:167], v[0:15]
	ds_read_b128 v[238:241], v205 offset:4608
	s_setprio 0
	global_load_dwordx4 v[160:163], v[190:191], off offset:2944
	global_load_dwordx4 v[164:167], v[188:189], off offset:2944
	s_setprio 1
	s_waitcnt lgkmcnt(1)
	v_mfma_f32_32x32x16_bf16 v[112:127], v[234:237], v[218:221], v[112:127]
	v_mfma_f32_32x32x16_bf16 v[48:63], v[234:237], v[222:225], v[48:63]
	s_waitcnt lgkmcnt(0)
	v_mfma_f32_32x32x16_bf16 v[96:111], v[238:241], v[218:221], v[96:111]
	v_mfma_f32_32x32x16_bf16 v[32:47], v[238:241], v[222:225], v[32:47]
	ds_read_b128 v[234:237], v205 offset:9216
	ds_read_b128 v[238:241], v205 offset:13824
	s_waitcnt vmcnt(7)
	ds_write_b128 v215, v[226:229] offset:9216
	s_waitcnt vmcnt(6)
	ds_write_b128 v215, v[230:233] offset:46080
	ds_read_b128 v[226:229], v208 offset:32
	ds_read_b128 v[230:233], v208 offset:4640
	s_waitcnt lgkmcnt(5)
	v_mfma_f32_32x32x16_bf16 v[80:95], v[234:237], v[218:221], v[80:95]
	v_mfma_f32_32x32x16_bf16 v[16:31], v[234:237], v[222:225], v[16:31]
	ds_read_b128 v[234:237], v205 offset:32
	s_waitcnt lgkmcnt(5)
	v_mfma_f32_32x32x16_bf16 v[64:79], v[238:241], v[218:221], v[64:79]
	v_mfma_f32_32x32x16_bf16 v[0:15], v[238:241], v[222:225], v[0:15]
	ds_read_b128 v[238:241], v205 offset:4640
	s_setprio 0
	global_load_dwordx4 v[218:221], v[194:195], off offset:2944
	global_load_dwordx4 v[222:225], v[196:197], off offset:2944
	s_setprio 1
	s_waitcnt lgkmcnt(1)
	v_mfma_f32_32x32x16_bf16 v[112:127], v[234:237], v[226:229], v[112:127]
	v_mfma_f32_32x32x16_bf16 v[48:63], v[234:237], v[230:233], v[48:63]
	s_waitcnt lgkmcnt(0)
	v_mfma_f32_32x32x16_bf16 v[96:111], v[238:241], v[226:229], v[96:111]
	v_mfma_f32_32x32x16_bf16 v[32:47], v[238:241], v[230:233], v[32:47]
	ds_read_b128 v[234:237], v205 offset:9248
	ds_read_b128 v[238:241], v205 offset:13856
	s_waitcnt vmcnt(7)
	ds_write_b128 v215, v[176:179] offset:18432
	s_waitcnt vmcnt(6)
	ds_write_b128 v215, v[180:183] offset:55296
	ds_read_b128 v[176:179], v208 offset:64
	ds_read_b128 v[180:183], v208 offset:4672
	s_waitcnt lgkmcnt(5)
	v_mfma_f32_32x32x16_bf16 v[80:95], v[234:237], v[226:229], v[80:95]
	v_mfma_f32_32x32x16_bf16 v[16:31], v[234:237], v[230:233], v[16:31]
	ds_read_b128 v[234:237], v205 offset:64
	s_waitcnt lgkmcnt(5)
	v_mfma_f32_32x32x16_bf16 v[64:79], v[238:241], v[226:229], v[64:79]
	v_mfma_f32_32x32x16_bf16 v[0:15], v[238:241], v[230:233], v[0:15]
	ds_read_b128 v[238:241], v205 offset:4672
	s_setprio 0
	global_load_dwordx4 v[226:229], v[184:185], off offset:2944
	global_load_dwordx4 v[230:233], v[186:187], off offset:2944
	s_setprio 1
	s_waitcnt lgkmcnt(1)
	v_mfma_f32_32x32x16_bf16 v[112:127], v[234:237], v[176:179], v[112:127]
	v_mfma_f32_32x32x16_bf16 v[48:63], v[234:237], v[180:183], v[48:63]
	s_waitcnt lgkmcnt(0)
	v_mfma_f32_32x32x16_bf16 v[96:111], v[238:241], v[176:179], v[96:111]
	v_mfma_f32_32x32x16_bf16 v[32:47], v[238:241], v[180:183], v[32:47]
	ds_read_b128 v[234:237], v205 offset:9280
	ds_read_b128 v[238:241], v205 offset:13888
	s_waitcnt vmcnt(7)
	ds_write_b128 v215, v[168:171] offset:27648
	s_waitcnt vmcnt(6)
	ds_write_b128 v215, v[172:175] offset:64512
	ds_read_b128 v[168:171], v208 offset:96
	ds_read_b128 v[172:175], v208 offset:4704
	s_waitcnt lgkmcnt(5)
	v_mfma_f32_32x32x16_bf16 v[80:95], v[234:237], v[176:179], v[80:95]
	v_mfma_f32_32x32x16_bf16 v[16:31], v[234:237], v[180:183], v[16:31]
	ds_read_b128 v[234:237], v205 offset:96
	s_waitcnt lgkmcnt(5)
	v_mfma_f32_32x32x16_bf16 v[64:79], v[238:241], v[176:179], v[64:79]
	v_mfma_f32_32x32x16_bf16 v[0:15], v[238:241], v[180:183], v[0:15]
	ds_read_b128 v[238:241], v205 offset:4704
	s_setprio 0
	global_load_dwordx4 v[176:179], v[198:199], off offset:2944
	global_load_dwordx4 v[180:183], v[200:201], off offset:2944
	s_setprio 1
	s_waitcnt lgkmcnt(1)
	v_mfma_f32_32x32x16_bf16 v[112:127], v[234:237], v[168:171], v[112:127]
	v_mfma_f32_32x32x16_bf16 v[48:63], v[234:237], v[172:175], v[48:63]
	s_waitcnt lgkmcnt(0)
	v_mfma_f32_32x32x16_bf16 v[96:111], v[238:241], v[168:171], v[96:111]
	v_mfma_f32_32x32x16_bf16 v[32:47], v[238:241], v[172:175], v[32:47]
	ds_read_b128 v[234:237], v205 offset:9312
	ds_read_b128 v[238:241], v205 offset:13920
	s_waitcnt lgkmcnt(0)
	s_barrier
; template <bool trans>
; DI void gemm_core(const GTile& tl, const GTile& nx, bool has_next  , bool chain  , bool pre, u32x4 (&ra)[4], u32x4 (&rb)[4], char* smem, f32x16 (&acc)[2][4]) {
;     ...
;   const int nk = K / 64;
;   if (!pre) { G_LOAD(0); G_STORE(0); G_LOAD(1); }
;   for (int kt = 0; kt < nk; ++kt) {
;     __syncthreads();
;     G_COMPUTE(kt & 1, kt);
;   }
	s_waitcnt vmcnt(7)
	ds_write_b128 v209, v[160:163]
	s_waitcnt vmcnt(6)
	ds_write_b128 v210, v[164:167]
	ds_read_b128 v[160:163], v204 offset:36864
	ds_read_b128 v[164:167], v204 offset:41472
	v_mfma_f32_32x32x16_bf16 v[80:95], v[234:237], v[168:171], v[80:95]
	v_mfma_f32_32x32x16_bf16 v[16:31], v[234:237], v[172:175], v[16:31]
	ds_read_b128 v[234:237], v192
	v_mfma_f32_32x32x16_bf16 v[64:79], v[238:241], v[168:171], v[64:79]
	v_mfma_f32_32x32x16_bf16 v[0:15], v[238:241], v[172:175], v[0:15]
	ds_read_b128 v[238:241], v192 offset:4608
	s_setprio 0
	global_load_dwordx4 v[168:171], v[190:191], off offset:3072
	global_load_dwordx4 v[172:175], v[188:189], off offset:3072
	s_setprio 1
	s_waitcnt lgkmcnt(1)
	v_mfma_f32_32x32x16_bf16 v[112:127], v[234:237], v[160:163], v[112:127]
	v_mfma_f32_32x32x16_bf16 v[48:63], v[234:237], v[164:167], v[48:63]
	s_waitcnt lgkmcnt(0)
	v_mfma_f32_32x32x16_bf16 v[96:111], v[238:241], v[160:163], v[96:111]
	v_mfma_f32_32x32x16_bf16 v[32:47], v[238:241], v[164:167], v[32:47]
	ds_read_b128 v[234:237], v192 offset:9216
	ds_read_b128 v[238:241], v192 offset:13824
	s_waitcnt vmcnt(7)
	ds_write_b128 v212, v[218:221]
	s_waitcnt vmcnt(6)
	ds_write_b128 v211, v[222:225]
	ds_read_b128 v[218:221], v204 offset:36896
	ds_read_b128 v[222:225], v204 offset:41504
	s_waitcnt lgkmcnt(5)
	v_mfma_f32_32x32x16_bf16 v[80:95], v[234:237], v[160:163], v[80:95]
	v_mfma_f32_32x32x16_bf16 v[16:31], v[234:237], v[164:167], v[16:31]
	ds_read_b128 v[234:237], v192 offset:32
	s_waitcnt lgkmcnt(5)
	v_mfma_f32_32x32x16_bf16 v[64:79], v[238:241], v[160:163], v[64:79]
	v_mfma_f32_32x32x16_bf16 v[0:15], v[238:241], v[164:167], v[0:15]
	ds_read_b128 v[238:241], v192 offset:4640
	s_setprio 0
	global_load_dwordx4 v[160:163], v[194:195], off offset:3072
	global_load_dwordx4 v[164:167], v[196:197], off offset:3072
	s_setprio 1
	s_waitcnt lgkmcnt(1)
	v_mfma_f32_32x32x16_bf16 v[112:127], v[234:237], v[218:221], v[112:127]
	v_mfma_f32_32x32x16_bf16 v[48:63], v[234:237], v[222:225], v[48:63]
	s_waitcnt lgkmcnt(0)
	v_mfma_f32_32x32x16_bf16 v[96:111], v[238:241], v[218:221], v[96:111]
	v_mfma_f32_32x32x16_bf16 v[32:47], v[238:241], v[222:225], v[32:47]
	ds_read_b128 v[234:237], v192 offset:9248
	ds_read_b128 v[238:241], v192 offset:13856
	s_waitcnt vmcnt(7)
	ds_write_b128 v214, v[226:229]
	s_waitcnt vmcnt(6)
	ds_write_b128 v213, v[230:233]
	ds_read_b128 v[226:229], v204 offset:36928
	ds_read_b128 v[230:233], v204 offset:41536
	s_waitcnt lgkmcnt(5)
	v_mfma_f32_32x32x16_bf16 v[80:95], v[234:237], v[218:221], v[80:95]
	v_mfma_f32_32x32x16_bf16 v[16:31], v[234:237], v[222:225], v[16:31]
	ds_read_b128 v[234:237], v192 offset:64
	s_waitcnt lgkmcnt(5)
	v_mfma_f32_32x32x16_bf16 v[64:79], v[238:241], v[218:221], v[64:79]
	v_mfma_f32_32x32x16_bf16 v[0:15], v[238:241], v[222:225], v[0:15]
	ds_read_b128 v[238:241], v192 offset:4672
	s_setprio 0
	global_load_dwordx4 v[218:221], v[184:185], off offset:3072
	global_load_dwordx4 v[222:225], v[186:187], off offset:3072
	s_setprio 1
	s_waitcnt lgkmcnt(1)
	v_mfma_f32_32x32x16_bf16 v[112:127], v[234:237], v[226:229], v[112:127]
	v_mfma_f32_32x32x16_bf16 v[48:63], v[234:237], v[230:233], v[48:63]
	s_waitcnt lgkmcnt(0)
	v_mfma_f32_32x32x16_bf16 v[96:111], v[238:241], v[226:229], v[96:111]
	v_mfma_f32_32x32x16_bf16 v[32:47], v[238:241], v[230:233], v[32:47]
	ds_read_b128 v[234:237], v192 offset:9280
	ds_read_b128 v[238:241], v192 offset:13888
	s_waitcnt vmcnt(7)
	ds_write_b128 v217, v[176:179]
	s_waitcnt vmcnt(6)
	ds_write_b128 v216, v[180:183]
	ds_read_b128 v[176:179], v204 offset:36960
	ds_read_b128 v[180:183], v204 offset:41568
	s_waitcnt lgkmcnt(5)
	v_mfma_f32_32x32x16_bf16 v[80:95], v[234:237], v[226:229], v[80:95]
	v_mfma_f32_32x32x16_bf16 v[16:31], v[234:237], v[230:233], v[16:31]
	ds_read_b128 v[234:237], v192 offset:96
	s_waitcnt lgkmcnt(5)
	v_mfma_f32_32x32x16_bf16 v[64:79], v[238:241], v[226:229], v[64:79]
	v_mfma_f32_32x32x16_bf16 v[0:15], v[238:241], v[230:233], v[0:15]
	ds_read_b128 v[238:241], v192 offset:4704
	s_setprio 0
	global_load_dwordx4 v[226:229], v[198:199], off offset:3072
	global_load_dwordx4 v[230:233], v[200:201], off offset:3072
	s_setprio 1
	s_waitcnt lgkmcnt(1)
	v_mfma_f32_32x32x16_bf16 v[112:127], v[234:237], v[176:179], v[112:127]
	v_mfma_f32_32x32x16_bf16 v[48:63], v[234:237], v[180:183], v[48:63]
	s_waitcnt lgkmcnt(0)
	v_mfma_f32_32x32x16_bf16 v[96:111], v[238:241], v[176:179], v[96:111]
	v_mfma_f32_32x32x16_bf16 v[32:47], v[238:241], v[180:183], v[32:47]
	ds_read_b128 v[234:237], v192 offset:9312
	ds_read_b128 v[238:241], v192 offset:13920
	s_waitcnt lgkmcnt(0)
	s_barrier
; template <bool trans>
; DI void gemm_core(const GTile& tl, const GTile& nx, bool has_next  , bool chain  , bool pre, u32x4 (&ra)[4], u32x4 (&rb)[4], char* smem, f32x16 (&acc)[2][4]) {
;     ...
;   const int nk = K / 64;
;   if (!pre) { G_LOAD(0); G_STORE(0); G_LOAD(1); }
;   for (int kt = 0; kt < nk; ++kt) {
;     __syncthreads();
;     G_COMPUTE(kt & 1, kt);
;   }
	s_waitcnt vmcnt(7)
	ds_write_b128 v215, v[168:171]
	s_waitcnt vmcnt(6)
	ds_write_b128 v215, v[172:175] offset:36864
	ds_read_b128 v[168:171], v208
	ds_read_b128 v[172:175], v208 offset:4608
	v_mfma_f32_32x32x16_bf16 v[80:95], v[234:237], v[176:179], v[80:95]
	v_mfma_f32_32x32x16_bf16 v[16:31], v[234:237], v[180:183], v[16:31]
	ds_read_b128 v[234:237], v205
	v_mfma_f32_32x32x16_bf16 v[64:79], v[238:241], v[176:179], v[64:79]
	v_mfma_f32_32x32x16_bf16 v[0:15], v[238:241], v[180:183], v[0:15]
	ds_read_b128 v[238:241], v205 offset:4608
	s_setprio 0
	global_load_dwordx4 v[176:179], v[190:191], off offset:3200
	global_load_dwordx4 v[180:183], v[188:189], off offset:3200
	s_setprio 1
	s_waitcnt lgkmcnt(1)
	v_mfma_f32_32x32x16_bf16 v[112:127], v[234:237], v[168:171], v[112:127]
	v_mfma_f32_32x32x16_bf16 v[48:63], v[234:237], v[172:175], v[48:63]
	s_waitcnt lgkmcnt(0)
	v_mfma_f32_32x32x16_bf16 v[96:111], v[238:241], v[168:171], v[96:111]
	v_mfma_f32_32x32x16_bf16 v[32:47], v[238:241], v[172:175], v[32:47]
	ds_read_b128 v[234:237], v205 offset:9216
	ds_read_b128 v[238:241], v205 offset:13824
	s_waitcnt vmcnt(7)
	ds_write_b128 v215, v[160:163] offset:9216
	s_waitcnt vmcnt(6)
	ds_write_b128 v215, v[164:167] offset:46080
	ds_read_b128 v[160:163], v208 offset:32
	ds_read_b128 v[164:167], v208 offset:4640
	s_waitcnt lgkmcnt(5)
	v_mfma_f32_32x32x16_bf16 v[80:95], v[234:237], v[168:171], v[80:95]
	v_mfma_f32_32x32x16_bf16 v[16:31], v[234:237], v[172:175], v[16:31]
	ds_read_b128 v[234:237], v205 offset:32
	s_waitcnt lgkmcnt(5)
	v_mfma_f32_32x32x16_bf16 v[64:79], v[238:241], v[168:171], v[64:79]
	v_mfma_f32_32x32x16_bf16 v[0:15], v[238:241], v[172:175], v[0:15]
	ds_read_b128 v[238:241], v205 offset:4640
	s_setprio 0
	global_load_dwordx4 v[168:171], v[194:195], off offset:3200
	global_load_dwordx4 v[172:175], v[196:197], off offset:3200
	s_setprio 1
	s_waitcnt lgkmcnt(1)
	v_mfma_f32_32x32x16_bf16 v[112:127], v[234:237], v[160:163], v[112:127]
	v_mfma_f32_32x32x16_bf16 v[48:63], v[234:237], v[164:167], v[48:63]
	s_waitcnt lgkmcnt(0)
	v_mfma_f32_32x32x16_bf16 v[96:111], v[238:241], v[160:163], v[96:111]
	v_mfma_f32_32x32x16_bf16 v[32:47], v[238:241], v[164:167], v[32:47]
	ds_read_b128 v[234:237], v205 offset:9248
	ds_read_b128 v[238:241], v205 offset:13856
	s_waitcnt vmcnt(7)
	ds_write_b128 v215, v[218:221] offset:18432
	s_waitcnt vmcnt(6)
	ds_write_b128 v215, v[222:225] offset:55296
	ds_read_b128 v[218:221], v208 offset:64
	ds_read_b128 v[222:225], v208 offset:4672
	s_waitcnt lgkmcnt(5)
	v_mfma_f32_32x32x16_bf16 v[80:95], v[234:237], v[160:163], v[80:95]
	v_mfma_f32_32x32x16_bf16 v[16:31], v[234:237], v[164:167], v[16:31]
	ds_read_b128 v[234:237], v205 offset:64
	s_waitcnt lgkmcnt(5)
	v_mfma_f32_32x32x16_bf16 v[64:79], v[238:241], v[160:163], v[64:79]
	v_mfma_f32_32x32x16_bf16 v[0:15], v[238:241], v[164:167], v[0:15]
	ds_read_b128 v[238:241], v205 offset:4672
	s_setprio 0
	global_load_dwordx4 v[160:163], v[184:185], off offset:3200
	global_load_dwordx4 v[164:167], v[186:187], off offset:3200
	s_setprio 1
	s_waitcnt lgkmcnt(1)
	v_mfma_f32_32x32x16_bf16 v[112:127], v[234:237], v[218:221], v[112:127]
	v_mfma_f32_32x32x16_bf16 v[48:63], v[234:237], v[222:225], v[48:63]
	s_waitcnt lgkmcnt(0)
	v_mfma_f32_32x32x16_bf16 v[96:111], v[238:241], v[218:221], v[96:111]
	v_mfma_f32_32x32x16_bf16 v[32:47], v[238:241], v[222:225], v[32:47]
	ds_read_b128 v[234:237], v205 offset:9280
	ds_read_b128 v[238:241], v205 offset:13888
	s_waitcnt vmcnt(7)
	ds_write_b128 v215, v[226:229] offset:27648
	s_waitcnt vmcnt(6)
	ds_write_b128 v215, v[230:233] offset:64512
	ds_read_b128 v[226:229], v208 offset:96
	ds_read_b128 v[230:233], v208 offset:4704
	s_waitcnt lgkmcnt(5)
	v_mfma_f32_32x32x16_bf16 v[80:95], v[234:237], v[218:221], v[80:95]
	v_mfma_f32_32x32x16_bf16 v[16:31], v[234:237], v[222:225], v[16:31]
	ds_read_b128 v[234:237], v205 offset:96
	s_waitcnt lgkmcnt(5)
	v_mfma_f32_32x32x16_bf16 v[64:79], v[238:241], v[218:221], v[64:79]
	v_mfma_f32_32x32x16_bf16 v[0:15], v[238:241], v[222:225], v[0:15]
	ds_read_b128 v[238:241], v205 offset:4704
	s_setprio 0
	global_load_dwordx4 v[218:221], v[198:199], off offset:3200
	global_load_dwordx4 v[222:225], v[200:201], off offset:3200
	s_setprio 1
	s_waitcnt lgkmcnt(1)
	v_mfma_f32_32x32x16_bf16 v[112:127], v[234:237], v[226:229], v[112:127]
	v_mfma_f32_32x32x16_bf16 v[48:63], v[234:237], v[230:233], v[48:63]
	s_waitcnt lgkmcnt(0)
	v_mfma_f32_32x32x16_bf16 v[96:111], v[238:241], v[226:229], v[96:111]
	v_mfma_f32_32x32x16_bf16 v[32:47], v[238:241], v[230:233], v[32:47]
	ds_read_b128 v[234:237], v205 offset:9312
	ds_read_b128 v[238:241], v205 offset:13920
	s_waitcnt lgkmcnt(0)
	s_barrier
; template <bool trans>
; DI void gemm_core(const GTile& tl, const GTile& nx, bool has_next  , bool chain  , bool pre, u32x4 (&ra)[4], u32x4 (&rb)[4], char* smem, f32x16 (&acc)[2][4]) {
;     ...
;   const int nk = K / 64;
;   if (!pre) { G_LOAD(0); G_STORE(0); G_LOAD(1); }
;   for (int kt = 0; kt < nk; ++kt) {
;     __syncthreads();
;     G_COMPUTE(kt & 1, kt);
;   }
	s_waitcnt vmcnt(7)
	ds_write_b128 v209, v[176:179]
	s_waitcnt vmcnt(6)
	ds_write_b128 v210, v[180:183]
	ds_read_b128 v[176:179], v204 offset:36864
	ds_read_b128 v[180:183], v204 offset:41472
	v_mfma_f32_32x32x16_bf16 v[80:95], v[234:237], v[226:229], v[80:95]
	v_mfma_f32_32x32x16_bf16 v[16:31], v[234:237], v[230:233], v[16:31]
	ds_read_b128 v[234:237], v192
	v_mfma_f32_32x32x16_bf16 v[64:79], v[238:241], v[226:229], v[64:79]
	v_mfma_f32_32x32x16_bf16 v[0:15], v[238:241], v[230:233], v[0:15]
	ds_read_b128 v[238:241], v192 offset:4608
	s_setprio 0
	global_load_dwordx4 v[226:229], v[190:191], off offset:3328
	global_load_dwordx4 v[230:233], v[188:189], off offset:3328
	s_setprio 1
	s_waitcnt lgkmcnt(1)
	v_mfma_f32_32x32x16_bf16 v[112:127], v[234:237], v[176:179], v[112:127]
	v_mfma_f32_32x32x16_bf16 v[48:63], v[234:237], v[180:183], v[48:63]
	s_waitcnt lgkmcnt(0)
	v_mfma_f32_32x32x16_bf16 v[96:111], v[238:241], v[176:179], v[96:111]
	v_mfma_f32_32x32x16_bf16 v[32:47], v[238:241], v[180:183], v[32:47]
	ds_read_b128 v[234:237], v192 offset:9216
	ds_read_b128 v[238:241], v192 offset:13824
	s_waitcnt vmcnt(7)
	ds_write_b128 v212, v[168:171]
	s_waitcnt vmcnt(6)
	ds_write_b128 v211, v[172:175]
	ds_read_b128 v[168:171], v204 offset:36896
	ds_read_b128 v[172:175], v204 offset:41504
	s_waitcnt lgkmcnt(5)
	v_mfma_f32_32x32x16_bf16 v[80:95], v[234:237], v[176:179], v[80:95]
	v_mfma_f32_32x32x16_bf16 v[16:31], v[234:237], v[180:183], v[16:31]
	ds_read_b128 v[234:237], v192 offset:32
	s_waitcnt lgkmcnt(5)
	v_mfma_f32_32x32x16_bf16 v[64:79], v[238:241], v[176:179], v[64:79]
	v_mfma_f32_32x32x16_bf16 v[0:15], v[238:241], v[180:183], v[0:15]
	ds_read_b128 v[238:241], v192 offset:4640
	s_setprio 0
	global_load_dwordx4 v[176:179], v[194:195], off offset:3328
	global_load_dwordx4 v[180:183], v[196:197], off offset:3328
	s_setprio 1
	s_waitcnt lgkmcnt(1)
	v_mfma_f32_32x32x16_bf16 v[112:127], v[234:237], v[168:171], v[112:127]
	v_mfma_f32_32x32x16_bf16 v[48:63], v[234:237], v[172:175], v[48:63]
	s_waitcnt lgkmcnt(0)
	v_mfma_f32_32x32x16_bf16 v[96:111], v[238:241], v[168:171], v[96:111]
	v_mfma_f32_32x32x16_bf16 v[32:47], v[238:241], v[172:175], v[32:47]
	ds_read_b128 v[234:237], v192 offset:9248
	ds_read_b128 v[238:241], v192 offset:13856
	s_waitcnt vmcnt(7)
	ds_write_b128 v214, v[160:163]
	s_waitcnt vmcnt(6)
	ds_write_b128 v213, v[164:167]
	ds_read_b128 v[160:163], v204 offset:36928
	ds_read_b128 v[164:167], v204 offset:41536
	s_waitcnt lgkmcnt(5)
	v_mfma_f32_32x32x16_bf16 v[80:95], v[234:237], v[168:171], v[80:95]
	v_mfma_f32_32x32x16_bf16 v[16:31], v[234:237], v[172:175], v[16:31]
	ds_read_b128 v[234:237], v192 offset:64
	s_waitcnt lgkmcnt(5)
	v_mfma_f32_32x32x16_bf16 v[64:79], v[238:241], v[168:171], v[64:79]
	v_mfma_f32_32x32x16_bf16 v[0:15], v[238:241], v[172:175], v[0:15]
	ds_read_b128 v[238:241], v192 offset:4672
	s_setprio 0
	global_load_dwordx4 v[168:171], v[184:185], off offset:3328
	global_load_dwordx4 v[172:175], v[186:187], off offset:3328
	s_setprio 1
	s_waitcnt lgkmcnt(1)
	v_mfma_f32_32x32x16_bf16 v[112:127], v[234:237], v[160:163], v[112:127]
	v_mfma_f32_32x32x16_bf16 v[48:63], v[234:237], v[164:167], v[48:63]
	s_waitcnt lgkmcnt(0)
	v_mfma_f32_32x32x16_bf16 v[96:111], v[238:241], v[160:163], v[96:111]
	v_mfma_f32_32x32x16_bf16 v[32:47], v[238:241], v[164:167], v[32:47]
	ds_read_b128 v[234:237], v192 offset:9280
	ds_read_b128 v[238:241], v192 offset:13888
	s_waitcnt vmcnt(7)
	ds_write_b128 v217, v[218:221]
	s_waitcnt vmcnt(6)
	ds_write_b128 v216, v[222:225]
	ds_read_b128 v[218:221], v204 offset:36960
	ds_read_b128 v[222:225], v204 offset:41568
	s_waitcnt lgkmcnt(5)
	v_mfma_f32_32x32x16_bf16 v[80:95], v[234:237], v[160:163], v[80:95]
	v_mfma_f32_32x32x16_bf16 v[16:31], v[234:237], v[164:167], v[16:31]
	ds_read_b128 v[234:237], v192 offset:96
	s_waitcnt lgkmcnt(5)
	v_mfma_f32_32x32x16_bf16 v[64:79], v[238:241], v[160:163], v[64:79]
	v_mfma_f32_32x32x16_bf16 v[0:15], v[238:241], v[164:167], v[0:15]
	ds_read_b128 v[238:241], v192 offset:4704
	s_setprio 0
	global_load_dwordx4 v[160:163], v[198:199], off offset:3328
	global_load_dwordx4 v[164:167], v[200:201], off offset:3328
	s_setprio 1
	s_waitcnt lgkmcnt(1)
	v_mfma_f32_32x32x16_bf16 v[112:127], v[234:237], v[218:221], v[112:127]
	v_mfma_f32_32x32x16_bf16 v[48:63], v[234:237], v[222:225], v[48:63]
	s_waitcnt lgkmcnt(0)
	v_mfma_f32_32x32x16_bf16 v[96:111], v[238:241], v[218:221], v[96:111]
	v_mfma_f32_32x32x16_bf16 v[32:47], v[238:241], v[222:225], v[32:47]
	ds_read_b128 v[234:237], v192 offset:9312
	ds_read_b128 v[238:241], v192 offset:13920
	s_waitcnt lgkmcnt(0)
	s_barrier
; template <bool trans>
; DI void gemm_core(const GTile& tl, const GTile& nx, bool has_next  , bool chain  , bool pre, u32x4 (&ra)[4], u32x4 (&rb)[4], char* smem, f32x16 (&acc)[2][4]) {
;     ...
;   const int nk = K / 64;
;   if (!pre) { G_LOAD(0); G_STORE(0); G_LOAD(1); }
;   for (int kt = 0; kt < nk; ++kt) {
;     __syncthreads();
;     G_COMPUTE(kt & 1, kt);
;   }
	s_waitcnt vmcnt(7)
	ds_write_b128 v215, v[226:229]
	s_waitcnt vmcnt(6)
	ds_write_b128 v215, v[230:233] offset:36864
	ds_read_b128 v[226:229], v208
	ds_read_b128 v[230:233], v208 offset:4608
	v_mfma_f32_32x32x16_bf16 v[80:95], v[234:237], v[218:221], v[80:95]
	v_mfma_f32_32x32x16_bf16 v[16:31], v[234:237], v[222:225], v[16:31]
	ds_read_b128 v[234:237], v205
	v_mfma_f32_32x32x16_bf16 v[64:79], v[238:241], v[218:221], v[64:79]
	v_mfma_f32_32x32x16_bf16 v[0:15], v[238:241], v[222:225], v[0:15]
	ds_read_b128 v[238:241], v205 offset:4608
	s_setprio 0
	global_load_dwordx4 v[218:221], v[190:191], off offset:3456
	global_load_dwordx4 v[222:225], v[188:189], off offset:3456
	s_setprio 1
	s_waitcnt lgkmcnt(1)
	v_mfma_f32_32x32x16_bf16 v[112:127], v[234:237], v[226:229], v[112:127]
	v_mfma_f32_32x32x16_bf16 v[48:63], v[234:237], v[230:233], v[48:63]
	s_waitcnt lgkmcnt(0)
	v_mfma_f32_32x32x16_bf16 v[96:111], v[238:241], v[226:229], v[96:111]
	v_mfma_f32_32x32x16_bf16 v[32:47], v[238:241], v[230:233], v[32:47]
	ds_read_b128 v[234:237], v205 offset:9216
	ds_read_b128 v[238:241], v205 offset:13824
	s_waitcnt vmcnt(7)
	ds_write_b128 v215, v[176:179] offset:9216
	s_waitcnt vmcnt(6)
	ds_write_b128 v215, v[180:183] offset:46080
	ds_read_b128 v[176:179], v208 offset:32
	ds_read_b128 v[180:183], v208 offset:4640
	s_waitcnt lgkmcnt(5)
	v_mfma_f32_32x32x16_bf16 v[80:95], v[234:237], v[226:229], v[80:95]
	v_mfma_f32_32x32x16_bf16 v[16:31], v[234:237], v[230:233], v[16:31]
	ds_read_b128 v[234:237], v205 offset:32
	s_waitcnt lgkmcnt(5)
	v_mfma_f32_32x32x16_bf16 v[64:79], v[238:241], v[226:229], v[64:79]
	v_mfma_f32_32x32x16_bf16 v[0:15], v[238:241], v[230:233], v[0:15]
	ds_read_b128 v[238:241], v205 offset:4640
	s_setprio 0
	global_load_dwordx4 v[226:229], v[194:195], off offset:3456
	global_load_dwordx4 v[230:233], v[196:197], off offset:3456
	s_setprio 1
	s_waitcnt lgkmcnt(1)
	v_mfma_f32_32x32x16_bf16 v[112:127], v[234:237], v[176:179], v[112:127]
	v_mfma_f32_32x32x16_bf16 v[48:63], v[234:237], v[180:183], v[48:63]
	s_waitcnt lgkmcnt(0)
	v_mfma_f32_32x32x16_bf16 v[96:111], v[238:241], v[176:179], v[96:111]
	v_mfma_f32_32x32x16_bf16 v[32:47], v[238:241], v[180:183], v[32:47]
	ds_read_b128 v[234:237], v205 offset:9248
	ds_read_b128 v[238:241], v205 offset:13856
	s_waitcnt vmcnt(7)
	ds_write_b128 v215, v[168:171] offset:18432
	s_waitcnt vmcnt(6)
	ds_write_b128 v215, v[172:175] offset:55296
	ds_read_b128 v[168:171], v208 offset:64
	ds_read_b128 v[172:175], v208 offset:4672
	s_waitcnt lgkmcnt(5)
	v_mfma_f32_32x32x16_bf16 v[80:95], v[234:237], v[176:179], v[80:95]
	v_mfma_f32_32x32x16_bf16 v[16:31], v[234:237], v[180:183], v[16:31]
	ds_read_b128 v[234:237], v205 offset:64
	s_waitcnt lgkmcnt(5)
	v_mfma_f32_32x32x16_bf16 v[64:79], v[238:241], v[176:179], v[64:79]
	v_mfma_f32_32x32x16_bf16 v[0:15], v[238:241], v[180:183], v[0:15]
	ds_read_b128 v[238:241], v205 offset:4672
	s_setprio 0
	global_load_dwordx4 v[176:179], v[184:185], off offset:3456
	global_load_dwordx4 v[180:183], v[186:187], off offset:3456
	s_setprio 1
	s_waitcnt lgkmcnt(1)
	v_mfma_f32_32x32x16_bf16 v[112:127], v[234:237], v[168:171], v[112:127]
	v_mfma_f32_32x32x16_bf16 v[48:63], v[234:237], v[172:175], v[48:63]
	s_waitcnt lgkmcnt(0)
	v_mfma_f32_32x32x16_bf16 v[96:111], v[238:241], v[168:171], v[96:111]
	v_mfma_f32_32x32x16_bf16 v[32:47], v[238:241], v[172:175], v[32:47]
	ds_read_b128 v[234:237], v205 offset:9280
	ds_read_b128 v[238:241], v205 offset:13888
	s_waitcnt vmcnt(7)
	ds_write_b128 v215, v[160:163] offset:27648
	s_waitcnt vmcnt(6)
	ds_write_b128 v215, v[164:167] offset:64512
	ds_read_b128 v[160:163], v208 offset:96
	ds_read_b128 v[164:167], v208 offset:4704
	s_waitcnt lgkmcnt(5)
	v_mfma_f32_32x32x16_bf16 v[80:95], v[234:237], v[168:171], v[80:95]
	v_mfma_f32_32x32x16_bf16 v[16:31], v[234:237], v[172:175], v[16:31]
	ds_read_b128 v[234:237], v205 offset:96
	s_waitcnt lgkmcnt(5)
	v_mfma_f32_32x32x16_bf16 v[64:79], v[238:241], v[168:171], v[64:79]
	v_mfma_f32_32x32x16_bf16 v[0:15], v[238:241], v[172:175], v[0:15]
	ds_read_b128 v[238:241], v205 offset:4704
	s_setprio 0
	global_load_dwordx4 v[168:171], v[198:199], off offset:3456
	global_load_dwordx4 v[172:175], v[200:201], off offset:3456
	s_setprio 1
	s_waitcnt lgkmcnt(1)
	v_mfma_f32_32x32x16_bf16 v[112:127], v[234:237], v[160:163], v[112:127]
	v_mfma_f32_32x32x16_bf16 v[48:63], v[234:237], v[164:167], v[48:63]
	s_waitcnt lgkmcnt(0)
	v_mfma_f32_32x32x16_bf16 v[96:111], v[238:241], v[160:163], v[96:111]
	v_mfma_f32_32x32x16_bf16 v[32:47], v[238:241], v[164:167], v[32:47]
	ds_read_b128 v[234:237], v205 offset:9312
	ds_read_b128 v[238:241], v205 offset:13920
	s_waitcnt lgkmcnt(0)
	s_barrier
; template <bool trans>
; DI void gemm_core(const GTile& tl, const GTile& nx, bool has_next  , bool chain  , bool pre, u32x4 (&ra)[4], u32x4 (&rb)[4], char* smem, f32x16 (&acc)[2][4]) {
;     ...
;   const int nk = K / 64;
;   if (!pre) { G_LOAD(0); G_STORE(0); G_LOAD(1); }
;   for (int kt = 0; kt < nk; ++kt) {
;     __syncthreads();
;     G_COMPUTE(kt & 1, kt);
;   }
	s_waitcnt vmcnt(7)
	ds_write_b128 v209, v[218:221]
	s_waitcnt vmcnt(6)
	ds_write_b128 v210, v[222:225]
	ds_read_b128 v[218:221], v204 offset:36864
	ds_read_b128 v[222:225], v204 offset:41472
	v_mfma_f32_32x32x16_bf16 v[80:95], v[234:237], v[160:163], v[80:95]
	v_mfma_f32_32x32x16_bf16 v[16:31], v[234:237], v[164:167], v[16:31]
	ds_read_b128 v[234:237], v192
	v_mfma_f32_32x32x16_bf16 v[64:79], v[238:241], v[160:163], v[64:79]
	v_mfma_f32_32x32x16_bf16 v[0:15], v[238:241], v[164:167], v[0:15]
	ds_read_b128 v[238:241], v192 offset:4608
	s_setprio 0
	global_load_dwordx4 v[160:163], v[190:191], off offset:3584
	global_load_dwordx4 v[164:167], v[188:189], off offset:3584
	s_setprio 1
	s_waitcnt lgkmcnt(1)
	v_mfma_f32_32x32x16_bf16 v[112:127], v[234:237], v[218:221], v[112:127]
	v_mfma_f32_32x32x16_bf16 v[48:63], v[234:237], v[222:225], v[48:63]
	s_waitcnt lgkmcnt(0)
	v_mfma_f32_32x32x16_bf16 v[96:111], v[238:241], v[218:221], v[96:111]
	v_mfma_f32_32x32x16_bf16 v[32:47], v[238:241], v[222:225], v[32:47]
	ds_read_b128 v[234:237], v192 offset:9216
	ds_read_b128 v[238:241], v192 offset:13824
	s_waitcnt vmcnt(7)
	ds_write_b128 v212, v[226:229]
	s_waitcnt vmcnt(6)
	ds_write_b128 v211, v[230:233]
	ds_read_b128 v[226:229], v204 offset:36896
	ds_read_b128 v[230:233], v204 offset:41504
	s_waitcnt lgkmcnt(5)
	v_mfma_f32_32x32x16_bf16 v[80:95], v[234:237], v[218:221], v[80:95]
	v_mfma_f32_32x32x16_bf16 v[16:31], v[234:237], v[222:225], v[16:31]
	ds_read_b128 v[234:237], v192 offset:32
	s_waitcnt lgkmcnt(5)
	v_mfma_f32_32x32x16_bf16 v[64:79], v[238:241], v[218:221], v[64:79]
	v_mfma_f32_32x32x16_bf16 v[0:15], v[238:241], v[222:225], v[0:15]
	ds_read_b128 v[238:241], v192 offset:4640
	s_setprio 0
	global_load_dwordx4 v[218:221], v[194:195], off offset:3584
	global_load_dwordx4 v[222:225], v[196:197], off offset:3584
	s_setprio 1
	s_waitcnt lgkmcnt(1)
	v_mfma_f32_32x32x16_bf16 v[112:127], v[234:237], v[226:229], v[112:127]
	v_mfma_f32_32x32x16_bf16 v[48:63], v[234:237], v[230:233], v[48:63]
	s_waitcnt lgkmcnt(0)
	v_mfma_f32_32x32x16_bf16 v[96:111], v[238:241], v[226:229], v[96:111]
	v_mfma_f32_32x32x16_bf16 v[32:47], v[238:241], v[230:233], v[32:47]
	ds_read_b128 v[234:237], v192 offset:9248
	ds_read_b128 v[238:241], v192 offset:13856
	s_waitcnt vmcnt(7)
	ds_write_b128 v214, v[176:179]
	s_waitcnt vmcnt(6)
	ds_write_b128 v213, v[180:183]
	ds_read_b128 v[176:179], v204 offset:36928
	ds_read_b128 v[180:183], v204 offset:41536
	s_waitcnt lgkmcnt(5)
	v_mfma_f32_32x32x16_bf16 v[80:95], v[234:237], v[226:229], v[80:95]
	v_mfma_f32_32x32x16_bf16 v[16:31], v[234:237], v[230:233], v[16:31]
	ds_read_b128 v[234:237], v192 offset:64
	s_waitcnt lgkmcnt(5)
	v_mfma_f32_32x32x16_bf16 v[64:79], v[238:241], v[226:229], v[64:79]
	v_mfma_f32_32x32x16_bf16 v[0:15], v[238:241], v[230:233], v[0:15]
	ds_read_b128 v[238:241], v192 offset:4672
	s_setprio 0
	global_load_dwordx4 v[226:229], v[184:185], off offset:3584
	global_load_dwordx4 v[230:233], v[186:187], off offset:3584
	s_setprio 1
	s_waitcnt lgkmcnt(1)
	v_mfma_f32_32x32x16_bf16 v[112:127], v[234:237], v[176:179], v[112:127]
	v_mfma_f32_32x32x16_bf16 v[48:63], v[234:237], v[180:183], v[48:63]
	s_waitcnt lgkmcnt(0)
	v_mfma_f32_32x32x16_bf16 v[96:111], v[238:241], v[176:179], v[96:111]
	v_mfma_f32_32x32x16_bf16 v[32:47], v[238:241], v[180:183], v[32:47]
	ds_read_b128 v[234:237], v192 offset:9280
	ds_read_b128 v[238:241], v192 offset:13888
	s_waitcnt vmcnt(7)
	ds_write_b128 v217, v[168:171]
	s_waitcnt vmcnt(6)
	ds_write_b128 v216, v[172:175]
	ds_read_b128 v[168:171], v204 offset:36960
	ds_read_b128 v[172:175], v204 offset:41568
	s_waitcnt lgkmcnt(5)
	v_mfma_f32_32x32x16_bf16 v[80:95], v[234:237], v[176:179], v[80:95]
	v_mfma_f32_32x32x16_bf16 v[16:31], v[234:237], v[180:183], v[16:31]
	ds_read_b128 v[234:237], v192 offset:96
	s_waitcnt lgkmcnt(5)
	v_mfma_f32_32x32x16_bf16 v[64:79], v[238:241], v[176:179], v[64:79]
	v_mfma_f32_32x32x16_bf16 v[0:15], v[238:241], v[180:183], v[0:15]
	ds_read_b128 v[238:241], v192 offset:4704
	s_setprio 0
	global_load_dwordx4 v[176:179], v[198:199], off offset:3584
	global_load_dwordx4 v[180:183], v[200:201], off offset:3584
	s_setprio 1
	s_waitcnt lgkmcnt(1)
	v_mfma_f32_32x32x16_bf16 v[112:127], v[234:237], v[168:171], v[112:127]
	v_mfma_f32_32x32x16_bf16 v[48:63], v[234:237], v[172:175], v[48:63]
	s_waitcnt lgkmcnt(0)
	v_mfma_f32_32x32x16_bf16 v[96:111], v[238:241], v[168:171], v[96:111]
	v_mfma_f32_32x32x16_bf16 v[32:47], v[238:241], v[172:175], v[32:47]
	ds_read_b128 v[234:237], v192 offset:9312
	ds_read_b128 v[238:241], v192 offset:13920
	s_waitcnt lgkmcnt(0)
	s_barrier
; template <bool trans>
; DI void gemm_core(const GTile& tl, const GTile& nx, bool has_next  , bool chain  , bool pre, u32x4 (&ra)[4], u32x4 (&rb)[4], char* smem, f32x16 (&acc)[2][4]) {
;     ...
;   const int nk = K / 64;
;   if (!pre) { G_LOAD(0); G_STORE(0); G_LOAD(1); }
;   for (int kt = 0; kt < nk; ++kt) {
;     __syncthreads();
;     G_COMPUTE(kt & 1, kt);
;   }
	s_waitcnt vmcnt(7)
	ds_write_b128 v215, v[160:163]
	s_waitcnt vmcnt(6)
	ds_write_b128 v215, v[164:167] offset:36864
	ds_read_b128 v[160:163], v208
	ds_read_b128 v[164:167], v208 offset:4608
	v_mfma_f32_32x32x16_bf16 v[80:95], v[234:237], v[168:171], v[80:95]
	v_mfma_f32_32x32x16_bf16 v[16:31], v[234:237], v[172:175], v[16:31]
	ds_read_b128 v[234:237], v205
	v_mfma_f32_32x32x16_bf16 v[64:79], v[238:241], v[168:171], v[64:79]
	v_mfma_f32_32x32x16_bf16 v[0:15], v[238:241], v[172:175], v[0:15]
	ds_read_b128 v[238:241], v205 offset:4608
	s_setprio 0
	global_load_dwordx4 v[168:171], v[190:191], off offset:3712
	global_load_dwordx4 v[172:175], v[188:189], off offset:3712
	s_setprio 1
	s_waitcnt lgkmcnt(1)
	v_mfma_f32_32x32x16_bf16 v[112:127], v[234:237], v[160:163], v[112:127]
	v_mfma_f32_32x32x16_bf16 v[48:63], v[234:237], v[164:167], v[48:63]
	s_waitcnt lgkmcnt(0)
	v_mfma_f32_32x32x16_bf16 v[96:111], v[238:241], v[160:163], v[96:111]
	v_mfma_f32_32x32x16_bf16 v[32:47], v[238:241], v[164:167], v[32:47]
	ds_read_b128 v[234:237], v205 offset:9216
	ds_read_b128 v[238:241], v205 offset:13824
	s_waitcnt vmcnt(7)
	ds_write_b128 v215, v[218:221] offset:9216
	s_waitcnt vmcnt(6)
	ds_write_b128 v215, v[222:225] offset:46080
	ds_read_b128 v[218:221], v208 offset:32
	ds_read_b128 v[222:225], v208 offset:4640
	s_waitcnt lgkmcnt(5)
	v_mfma_f32_32x32x16_bf16 v[80:95], v[234:237], v[160:163], v[80:95]
	v_mfma_f32_32x32x16_bf16 v[16:31], v[234:237], v[164:167], v[16:31]
	ds_read_b128 v[234:237], v205 offset:32
	s_waitcnt lgkmcnt(5)
	v_mfma_f32_32x32x16_bf16 v[64:79], v[238:241], v[160:163], v[64:79]
	v_mfma_f32_32x32x16_bf16 v[0:15], v[238:241], v[164:167], v[0:15]
	ds_read_b128 v[238:241], v205 offset:4640
	s_setprio 0
	global_load_dwordx4 v[160:163], v[194:195], off offset:3712
	global_load_dwordx4 v[164:167], v[196:197], off offset:3712
	s_setprio 1
	s_waitcnt lgkmcnt(1)
	v_mfma_f32_32x32x16_bf16 v[112:127], v[234:237], v[218:221], v[112:127]
	v_mfma_f32_32x32x16_bf16 v[48:63], v[234:237], v[222:225], v[48:63]
	s_waitcnt lgkmcnt(0)
	v_mfma_f32_32x32x16_bf16 v[96:111], v[238:241], v[218:221], v[96:111]
	v_mfma_f32_32x32x16_bf16 v[32:47], v[238:241], v[222:225], v[32:47]
	ds_read_b128 v[234:237], v205 offset:9248
	ds_read_b128 v[238:241], v205 offset:13856
	s_waitcnt vmcnt(7)
	ds_write_b128 v215, v[226:229] offset:18432
	s_waitcnt vmcnt(6)
	ds_write_b128 v215, v[230:233] offset:55296
	ds_read_b128 v[226:229], v208 offset:64
	ds_read_b128 v[230:233], v208 offset:4672
	s_waitcnt lgkmcnt(5)
	v_mfma_f32_32x32x16_bf16 v[80:95], v[234:237], v[218:221], v[80:95]
	v_mfma_f32_32x32x16_bf16 v[16:31], v[234:237], v[222:225], v[16:31]
	ds_read_b128 v[234:237], v205 offset:64
	s_waitcnt lgkmcnt(5)
	v_mfma_f32_32x32x16_bf16 v[64:79], v[238:241], v[218:221], v[64:79]
	v_mfma_f32_32x32x16_bf16 v[0:15], v[238:241], v[222:225], v[0:15]
	ds_read_b128 v[238:241], v205 offset:4672
	s_setprio 0
	global_load_dwordx4 v[218:221], v[184:185], off offset:3712
	global_load_dwordx4 v[222:225], v[186:187], off offset:3712
	s_setprio 1
	s_waitcnt lgkmcnt(1)
	v_mfma_f32_32x32x16_bf16 v[112:127], v[234:237], v[226:229], v[112:127]
	v_mfma_f32_32x32x16_bf16 v[48:63], v[234:237], v[230:233], v[48:63]
	s_waitcnt lgkmcnt(0)
	v_mfma_f32_32x32x16_bf16 v[96:111], v[238:241], v[226:229], v[96:111]
	v_mfma_f32_32x32x16_bf16 v[32:47], v[238:241], v[230:233], v[32:47]
	ds_read_b128 v[234:237], v205 offset:9280
	ds_read_b128 v[238:241], v205 offset:13888
	s_waitcnt vmcnt(7)
	ds_write_b128 v215, v[176:179] offset:27648
	s_waitcnt vmcnt(6)
	ds_write_b128 v215, v[180:183] offset:64512
	ds_read_b128 v[176:179], v208 offset:96
	ds_read_b128 v[180:183], v208 offset:4704
	s_waitcnt lgkmcnt(5)
	v_mfma_f32_32x32x16_bf16 v[80:95], v[234:237], v[226:229], v[80:95]
	v_mfma_f32_32x32x16_bf16 v[16:31], v[234:237], v[230:233], v[16:31]
	ds_read_b128 v[234:237], v205 offset:96
	s_waitcnt lgkmcnt(5)
	v_mfma_f32_32x32x16_bf16 v[64:79], v[238:241], v[226:229], v[64:79]
	v_mfma_f32_32x32x16_bf16 v[0:15], v[238:241], v[230:233], v[0:15]
	ds_read_b128 v[238:241], v205 offset:4704
	s_setprio 0
	global_load_dwordx4 v[226:229], v[198:199], off offset:3712
	global_load_dwordx4 v[230:233], v[200:201], off offset:3712
	s_setprio 1
	s_waitcnt lgkmcnt(1)
	v_mfma_f32_32x32x16_bf16 v[112:127], v[234:237], v[176:179], v[112:127]
	v_mfma_f32_32x32x16_bf16 v[48:63], v[234:237], v[180:183], v[48:63]
	s_waitcnt lgkmcnt(0)
	v_mfma_f32_32x32x16_bf16 v[96:111], v[238:241], v[176:179], v[96:111]
	v_mfma_f32_32x32x16_bf16 v[32:47], v[238:241], v[180:183], v[32:47]
	ds_read_b128 v[234:237], v205 offset:9312
	ds_read_b128 v[238:241], v205 offset:13920
	s_waitcnt lgkmcnt(0)
	s_barrier
; template <bool trans>
; DI void gemm_core(const GTile& tl, const GTile& nx, bool has_next  , bool chain  , bool pre, u32x4 (&ra)[4], u32x4 (&rb)[4], char* smem, f32x16 (&acc)[2][4]) {
;     ...
;   const int nk = K / 64;
;   if (!pre) { G_LOAD(0); G_STORE(0); G_LOAD(1); }
;   for (int kt = 0; kt < nk; ++kt) {
;     __syncthreads();
;     G_COMPUTE(kt & 1, kt);
;   }
	s_waitcnt vmcnt(7)
	ds_write_b128 v209, v[168:171]
	s_waitcnt vmcnt(6)
	ds_write_b128 v210, v[172:175]
	ds_read_b128 v[168:171], v204 offset:36864
	ds_read_b128 v[172:175], v204 offset:41472
	v_mfma_f32_32x32x16_bf16 v[80:95], v[234:237], v[176:179], v[80:95]
	v_mfma_f32_32x32x16_bf16 v[16:31], v[234:237], v[180:183], v[16:31]
	ds_read_b128 v[234:237], v192
	v_mfma_f32_32x32x16_bf16 v[64:79], v[238:241], v[176:179], v[64:79]
	v_mfma_f32_32x32x16_bf16 v[0:15], v[238:241], v[180:183], v[0:15]
	ds_read_b128 v[238:241], v192 offset:4608
	s_setprio 0
	global_load_dwordx4 v[176:179], v[190:191], off offset:3840
	global_load_dwordx4 v[180:183], v[188:189], off offset:3840
	s_setprio 1
	s_waitcnt lgkmcnt(1)
	v_mfma_f32_32x32x16_bf16 v[112:127], v[234:237], v[168:171], v[112:127]
	v_mfma_f32_32x32x16_bf16 v[48:63], v[234:237], v[172:175], v[48:63]
	s_waitcnt lgkmcnt(0)
	v_mfma_f32_32x32x16_bf16 v[96:111], v[238:241], v[168:171], v[96:111]
	v_mfma_f32_32x32x16_bf16 v[32:47], v[238:241], v[172:175], v[32:47]
	ds_read_b128 v[234:237], v192 offset:9216
	ds_read_b128 v[238:241], v192 offset:13824
	s_waitcnt lgkmcnt(1)
	v_mfma_f32_32x32x16_bf16 v[80:95], v[234:237], v[168:171], v[80:95]
	v_mfma_f32_32x32x16_bf16 v[16:31], v[234:237], v[172:175], v[16:31]
	s_waitcnt lgkmcnt(0)
	v_mfma_f32_32x32x16_bf16 v[64:79], v[238:241], v[168:171], v[64:79]
	v_mfma_f32_32x32x16_bf16 v[0:15], v[238:241], v[172:175], v[0:15]
	s_setprio 0
	global_load_dwordx4 v[234:237], v[194:195], off offset:3840
	global_load_dwordx4 v[238:241], v[196:197], off offset:3840
	s_waitcnt vmcnt(9)
	ds_write_b128 v212, v[160:163]
	s_waitcnt vmcnt(8)
	ds_write_b128 v211, v[164:167]
	ds_read_b128 v[160:163], v204 offset:36896
	ds_read_b128 v[164:167], v204 offset:41504
	ds_read_b128 v[168:171], v192 offset:32
	ds_read_b128 v[172:175], v192 offset:4640
	s_setprio 1
	s_waitcnt lgkmcnt(1)
	v_mfma_f32_32x32x16_bf16 v[112:127], v[168:171], v[160:163], v[112:127]
	v_mfma_f32_32x32x16_bf16 v[48:63], v[168:171], v[164:167], v[48:63]
	s_waitcnt lgkmcnt(0)
	v_mfma_f32_32x32x16_bf16 v[96:111], v[172:175], v[160:163], v[96:111]
	v_mfma_f32_32x32x16_bf16 v[32:47], v[172:175], v[164:167], v[32:47]
	ds_read_b128 v[168:171], v192 offset:9248
	ds_read_b128 v[172:175], v192 offset:13856
	s_waitcnt lgkmcnt(1)
	v_mfma_f32_32x32x16_bf16 v[80:95], v[168:171], v[160:163], v[80:95]
	v_mfma_f32_32x32x16_bf16 v[16:31], v[168:171], v[164:167], v[16:31]
	s_waitcnt lgkmcnt(0)
	v_mfma_f32_32x32x16_bf16 v[64:79], v[172:175], v[160:163], v[64:79]
	v_mfma_f32_32x32x16_bf16 v[0:15], v[172:175], v[164:167], v[0:15]
	s_setprio 0
	global_load_dwordx4 v[242:245], v[184:185], off offset:3840
	global_load_dwordx4 v[246:249], v[186:187], off offset:3840
	s_waitcnt vmcnt(9)
	ds_write_b128 v214, v[218:221]
	s_waitcnt vmcnt(8)
	ds_write_b128 v213, v[222:225]
	ds_read_b128 v[160:163], v204 offset:36928
	ds_read_b128 v[164:167], v204 offset:41536
	ds_read_b128 v[168:171], v192 offset:64
	ds_read_b128 v[172:175], v192 offset:4672
	s_setprio 1
	s_waitcnt lgkmcnt(1)
	v_mfma_f32_32x32x16_bf16 v[112:127], v[168:171], v[160:163], v[112:127]
	v_mfma_f32_32x32x16_bf16 v[48:63], v[168:171], v[164:167], v[48:63]
	s_waitcnt lgkmcnt(0)
	v_mfma_f32_32x32x16_bf16 v[96:111], v[172:175], v[160:163], v[96:111]
	v_mfma_f32_32x32x16_bf16 v[32:47], v[172:175], v[164:167], v[32:47]
	ds_read_b128 v[168:171], v192 offset:9280
	ds_read_b128 v[172:175], v192 offset:13888
	s_waitcnt lgkmcnt(1)
	v_mfma_f32_32x32x16_bf16 v[80:95], v[168:171], v[160:163], v[80:95]
	v_mfma_f32_32x32x16_bf16 v[16:31], v[168:171], v[164:167], v[16:31]
	s_waitcnt lgkmcnt(0)
	v_mfma_f32_32x32x16_bf16 v[64:79], v[172:175], v[160:163], v[64:79]
	v_mfma_f32_32x32x16_bf16 v[0:15], v[172:175], v[164:167], v[0:15]
	s_setprio 0
	global_load_dwordx4 v[218:221], v[198:199], off offset:3840
	global_load_dwordx4 v[222:225], v[200:201], off offset:3840
	s_waitcnt vmcnt(9)
	ds_write_b128 v217, v[226:229]
	s_waitcnt vmcnt(8)
	ds_write_b128 v216, v[230:233]
	ds_read_b128 v[160:163], v204 offset:36960
	ds_read_b128 v[164:167], v204 offset:41568
	ds_read_b128 v[168:171], v192 offset:96
	ds_read_b128 v[172:175], v192 offset:4704
	s_setprio 1
	s_waitcnt lgkmcnt(1)
	v_mfma_f32_32x32x16_bf16 v[112:127], v[168:171], v[160:163], v[112:127]
	v_mfma_f32_32x32x16_bf16 v[48:63], v[168:171], v[164:167], v[48:63]
	s_waitcnt lgkmcnt(0)
	v_mfma_f32_32x32x16_bf16 v[96:111], v[172:175], v[160:163], v[96:111]
	v_mfma_f32_32x32x16_bf16 v[32:47], v[172:175], v[164:167], v[32:47]
	ds_read_b128 v[168:171], v192 offset:9312
	ds_read_b128 v[172:175], v192 offset:13920
	s_waitcnt lgkmcnt(1)
	v_mfma_f32_32x32x16_bf16 v[80:95], v[168:171], v[160:163], v[80:95]
	v_mfma_f32_32x32x16_bf16 v[16:31], v[168:171], v[164:167], v[16:31]
	s_waitcnt lgkmcnt(0)
	v_mfma_f32_32x32x16_bf16 v[64:79], v[172:175], v[160:163], v[64:79]
	v_mfma_f32_32x32x16_bf16 v[0:15], v[172:175], v[164:167], v[0:15]
	s_setprio 0
	global_load_dwordx4 v[160:163], v[190:191], off offset:3968
	global_load_dwordx4 v[164:167], v[188:189], off offset:3968
	s_barrier
; template <bool trans>
; DI void gemm_core(const GTile& tl, const GTile& nx, bool has_next  , bool chain  , bool pre, u32x4 (&ra)[4], u32x4 (&rb)[4], char* smem, f32x16 (&acc)[2][4]) {
;     ...
;   const int nk = K / 64;
;   if (!pre) { G_LOAD(0); G_STORE(0); G_LOAD(1); }
;   for (int kt = 0; kt < nk; ++kt) {
;     __syncthreads();
;     G_COMPUTE(kt & 1, kt);
;   }
	s_waitcnt vmcnt(9)
	ds_write_b128 v215, v[176:179]
	s_waitcnt vmcnt(8)
	ds_write_b128 v215, v[180:183] offset:36864
	ds_read_b128 v[168:171], v208
	ds_read_b128 v[172:175], v208 offset:4608
	ds_read_b128 v[176:179], v205
	ds_read_b128 v[180:183], v205 offset:4608
	s_setprio 1
	s_waitcnt lgkmcnt(1)
	v_mfma_f32_32x32x16_bf16 v[112:127], v[176:179], v[168:171], v[112:127]
	v_mfma_f32_32x32x16_bf16 v[48:63], v[176:179], v[172:175], v[48:63]
	s_waitcnt lgkmcnt(0)
	v_mfma_f32_32x32x16_bf16 v[96:111], v[180:183], v[168:171], v[96:111]
	v_mfma_f32_32x32x16_bf16 v[32:47], v[180:183], v[172:175], v[32:47]
	ds_read_b128 v[176:179], v205 offset:9216
	ds_read_b128 v[180:183], v205 offset:13824
	s_waitcnt lgkmcnt(1)
	v_mfma_f32_32x32x16_bf16 v[80:95], v[176:179], v[168:171], v[80:95]
	v_mfma_f32_32x32x16_bf16 v[16:31], v[176:179], v[172:175], v[16:31]
	s_waitcnt lgkmcnt(0)
	v_mfma_f32_32x32x16_bf16 v[64:79], v[180:183], v[168:171], v[64:79]
	v_mfma_f32_32x32x16_bf16 v[0:15], v[180:183], v[172:175], v[0:15]
	s_setprio 0
	global_load_dwordx4 v[168:171], v[194:195], off offset:3968
	global_load_dwordx4 v[172:175], v[196:197], off offset:3968
	s_waitcnt vmcnt(9)
	ds_write_b128 v215, v[234:237] offset:9216
	s_waitcnt vmcnt(8)
	ds_write_b128 v215, v[238:241] offset:46080
	ds_read_b128 v[176:179], v208 offset:32
	ds_read_b128 v[180:183], v208 offset:4640
	ds_read_b128 v[188:191], v205 offset:32
	ds_read_b128 v[194:197], v205 offset:4640
	s_setprio 1
	s_waitcnt lgkmcnt(1)
	v_mfma_f32_32x32x16_bf16 v[112:127], v[188:191], v[176:179], v[112:127]
	v_mfma_f32_32x32x16_bf16 v[48:63], v[188:191], v[180:183], v[48:63]
	s_waitcnt lgkmcnt(0)
	v_mfma_f32_32x32x16_bf16 v[96:111], v[194:197], v[176:179], v[96:111]
	v_mfma_f32_32x32x16_bf16 v[32:47], v[194:197], v[180:183], v[32:47]
	ds_read_b128 v[188:191], v205 offset:9248
	ds_read_b128 v[194:197], v205 offset:13856
	s_waitcnt lgkmcnt(1)
	v_mfma_f32_32x32x16_bf16 v[80:95], v[188:191], v[176:179], v[80:95]
	v_mfma_f32_32x32x16_bf16 v[16:31], v[188:191], v[180:183], v[16:31]
	s_waitcnt lgkmcnt(0)
	v_mfma_f32_32x32x16_bf16 v[64:79], v[194:197], v[176:179], v[64:79]
	v_mfma_f32_32x32x16_bf16 v[0:15], v[194:197], v[180:183], v[0:15]
	s_setprio 0
	global_load_dwordx4 v[176:179], v[184:185], off offset:3968
	global_load_dwordx4 v[180:183], v[186:187], off offset:3968
	s_waitcnt vmcnt(9)
	ds_write_b128 v215, v[242:245] offset:18432
	s_waitcnt vmcnt(8)
	ds_write_b128 v215, v[246:249] offset:55296
	ds_read_b128 v[184:187], v208 offset:64
	ds_read_b128 v[188:191], v208 offset:4672
	ds_read_b128 v[194:197], v205 offset:64
	ds_read_b128 v[226:229], v205 offset:4672
	s_setprio 1
	s_waitcnt lgkmcnt(1)
	v_mfma_f32_32x32x16_bf16 v[112:127], v[194:197], v[184:187], v[112:127]
	v_mfma_f32_32x32x16_bf16 v[48:63], v[194:197], v[188:191], v[48:63]
	s_waitcnt lgkmcnt(0)
	v_mfma_f32_32x32x16_bf16 v[96:111], v[226:229], v[184:187], v[96:111]
	v_mfma_f32_32x32x16_bf16 v[32:47], v[226:229], v[188:191], v[32:47]
	ds_read_b128 v[194:197], v205 offset:9280
	ds_read_b128 v[226:229], v205 offset:13888
	s_waitcnt lgkmcnt(1)
	v_mfma_f32_32x32x16_bf16 v[80:95], v[194:197], v[184:187], v[80:95]
	v_mfma_f32_32x32x16_bf16 v[16:31], v[194:197], v[188:191], v[16:31]
	s_waitcnt lgkmcnt(0)
	v_mfma_f32_32x32x16_bf16 v[64:79], v[226:229], v[184:187], v[64:79]
	v_mfma_f32_32x32x16_bf16 v[0:15], v[226:229], v[188:191], v[0:15]
	s_setprio 0
	global_load_dwordx4 v[184:187], v[198:199], off offset:3968
	global_load_dwordx4 v[188:191], v[200:201], off offset:3968
	s_waitcnt vmcnt(9)
	ds_write_b128 v215, v[218:221] offset:27648
	s_waitcnt vmcnt(8)
	ds_write_b128 v215, v[222:225] offset:64512
	ds_read_b128 v[194:197], v208 offset:96
	ds_read_b128 v[198:201], v208 offset:4704
	ds_read_b128 v[218:221], v205 offset:96
	ds_read_b128 v[222:225], v205 offset:4704
	s_setprio 1
	s_waitcnt lgkmcnt(1)
	v_mfma_f32_32x32x16_bf16 v[112:127], v[218:221], v[194:197], v[112:127]
	v_mfma_f32_32x32x16_bf16 v[48:63], v[218:221], v[198:201], v[48:63]
	s_waitcnt lgkmcnt(0)
	v_mfma_f32_32x32x16_bf16 v[96:111], v[222:225], v[194:197], v[96:111]
	v_mfma_f32_32x32x16_bf16 v[32:47], v[222:225], v[198:201], v[32:47]
	ds_read_b128 v[218:221], v205 offset:9312
	ds_read_b128 v[222:225], v205 offset:13920
	s_waitcnt lgkmcnt(1)
	v_mfma_f32_32x32x16_bf16 v[80:95], v[218:221], v[194:197], v[80:95]
	v_mfma_f32_32x32x16_bf16 v[16:31], v[218:221], v[198:201], v[16:31]
	s_waitcnt lgkmcnt(0)
	v_mfma_f32_32x32x16_bf16 v[64:79], v[222:225], v[194:197], v[64:79]
	v_mfma_f32_32x32x16_bf16 v[0:15], v[222:225], v[198:201], v[0:15]
	s_setprio 0
	s_barrier
; template <bool trans>
; DI void gemm_core(const GTile& tl, const GTile& nx, bool has_next  , bool chain  , bool pre, u32x4 (&ra)[4], u32x4 (&rb)[4], char* smem, f32x16 (&acc)[2][4]) {
;     ...
;   const int nk = K / 64;
;   if (!pre) { G_LOAD(0); G_STORE(0); G_LOAD(1); }
;   for (int kt = 0; kt < nk; ++kt) {
;     __syncthreads();
;     G_COMPUTE(kt & 1, kt);
;   }
	s_waitcnt vmcnt(7)
	ds_write_b128 v209, v[160:163]
	s_waitcnt vmcnt(6)
	ds_write_b128 v210, v[164:167]
	ds_read_b128 v[194:197], v204 offset:36864
	ds_read_b128 v[198:201], v204 offset:41472
	ds_read_b128 v[218:221], v192
	ds_read_b128 v[222:225], v192 offset:4608
	s_setprio 1
	s_waitcnt lgkmcnt(1)
	v_mfma_f32_32x32x16_bf16 v[112:127], v[218:221], v[194:197], v[112:127]
	v_mfma_f32_32x32x16_bf16 v[48:63], v[218:221], v[198:201], v[48:63]
	s_waitcnt lgkmcnt(0)
	v_mfma_f32_32x32x16_bf16 v[96:111], v[222:225], v[194:197], v[96:111]
	v_mfma_f32_32x32x16_bf16 v[32:47], v[222:225], v[198:201], v[32:47]
	ds_read_b128 v[218:221], v192 offset:9216
	ds_read_b128 v[222:225], v192 offset:13824
	s_waitcnt lgkmcnt(1)
	v_mfma_f32_32x32x16_bf16 v[80:95], v[218:221], v[194:197], v[80:95]
	v_mfma_f32_32x32x16_bf16 v[16:31], v[218:221], v[198:201], v[16:31]
	s_waitcnt lgkmcnt(0)
	v_mfma_f32_32x32x16_bf16 v[64:79], v[222:225], v[194:197], v[64:79]
	v_mfma_f32_32x32x16_bf16 v[0:15], v[222:225], v[198:201], v[0:15]
	s_setprio 0
	s_waitcnt vmcnt(5)
	ds_write_b128 v212, v[168:171]
	s_waitcnt vmcnt(4)
	ds_write_b128 v211, v[172:175]
	ds_read_b128 v[194:197], v204 offset:36896
	ds_read_b128 v[198:201], v204 offset:41504
	ds_read_b128 v[218:221], v192 offset:32
	ds_read_b128 v[222:225], v192 offset:4640
	s_setprio 1
	s_waitcnt lgkmcnt(1)
	v_mfma_f32_32x32x16_bf16 v[112:127], v[218:221], v[194:197], v[112:127]
	v_mfma_f32_32x32x16_bf16 v[48:63], v[218:221], v[198:201], v[48:63]
	s_waitcnt lgkmcnt(0)
	v_mfma_f32_32x32x16_bf16 v[96:111], v[222:225], v[194:197], v[96:111]
	v_mfma_f32_32x32x16_bf16 v[32:47], v[222:225], v[198:201], v[32:47]
	ds_read_b128 v[218:221], v192 offset:9248
	ds_read_b128 v[222:225], v192 offset:13856
	s_waitcnt lgkmcnt(1)
	v_mfma_f32_32x32x16_bf16 v[80:95], v[218:221], v[194:197], v[80:95]
	v_mfma_f32_32x32x16_bf16 v[16:31], v[218:221], v[198:201], v[16:31]
	s_waitcnt lgkmcnt(0)
	v_mfma_f32_32x32x16_bf16 v[64:79], v[222:225], v[194:197], v[64:79]
	v_mfma_f32_32x32x16_bf16 v[0:15], v[222:225], v[198:201], v[0:15]
	s_setprio 0
	s_waitcnt vmcnt(3)
	ds_write_b128 v214, v[176:179]
	s_waitcnt vmcnt(2)
	ds_write_b128 v213, v[180:183]
	ds_read_b128 v[194:197], v204 offset:36928
	ds_read_b128 v[198:201], v204 offset:41536
	ds_read_b128 v[210:213], v192 offset:64
	ds_read_b128 v[218:221], v192 offset:4672
	s_setprio 1
	s_waitcnt lgkmcnt(1)
	v_mfma_f32_32x32x16_bf16 v[112:127], v[210:213], v[194:197], v[112:127]
	v_mfma_f32_32x32x16_bf16 v[48:63], v[210:213], v[198:201], v[48:63]
	s_waitcnt lgkmcnt(0)
	v_mfma_f32_32x32x16_bf16 v[96:111], v[218:221], v[194:197], v[96:111]
	v_mfma_f32_32x32x16_bf16 v[32:47], v[218:221], v[198:201], v[32:47]
	ds_read_b128 v[210:213], v192 offset:9280
	ds_read_b128 v[218:221], v192 offset:13888
	s_waitcnt lgkmcnt(1)
	v_mfma_f32_32x32x16_bf16 v[80:95], v[210:213], v[194:197], v[80:95]
	v_mfma_f32_32x32x16_bf16 v[16:31], v[210:213], v[198:201], v[16:31]
	s_waitcnt lgkmcnt(0)
	v_mfma_f32_32x32x16_bf16 v[64:79], v[218:221], v[194:197], v[64:79]
	v_mfma_f32_32x32x16_bf16 v[0:15], v[218:221], v[198:201], v[0:15]
	s_setprio 0
	s_waitcnt vmcnt(1)
	ds_write_b128 v217, v[184:187]
	s_waitcnt vmcnt(0)
	ds_write_b128 v216, v[188:191]
	ds_read_b128 v[194:197], v204 offset:36960
	ds_read_b128 v[198:201], v204 offset:41568
	ds_read_b128 v[210:213], v192 offset:96
	ds_read_b128 v[214:217], v192 offset:4704
	s_setprio 1
	s_waitcnt lgkmcnt(1)
	v_mfma_f32_32x32x16_bf16 v[112:127], v[210:213], v[194:197], v[112:127]
	v_mfma_f32_32x32x16_bf16 v[48:63], v[210:213], v[198:201], v[48:63]
	s_waitcnt lgkmcnt(0)
	v_mfma_f32_32x32x16_bf16 v[96:111], v[214:217], v[194:197], v[96:111]
	v_mfma_f32_32x32x16_bf16 v[32:47], v[214:217], v[198:201], v[32:47]
	ds_read_b128 v[210:213], v192 offset:9312
	ds_read_b128 v[214:217], v192 offset:13920
	s_waitcnt lgkmcnt(1)
	v_mfma_f32_32x32x16_bf16 v[80:95], v[210:213], v[194:197], v[80:95]
	v_mfma_f32_32x32x16_bf16 v[16:31], v[210:213], v[198:201], v[16:31]
	s_waitcnt lgkmcnt(0)
	v_mfma_f32_32x32x16_bf16 v[64:79], v[214:217], v[194:197], v[64:79]
	v_mfma_f32_32x32x16_bf16 v[0:15], v[214:217], v[198:201], v[0:15]
	s_setprio 0
	s_barrier
; template <bool trans>
; DI void gemm_core(const GTile& tl, const GTile& nx, bool has_next  , bool chain  , bool pre, u32x4 (&ra)[4], u32x4 (&rb)[4], char* smem, f32x16 (&acc)[2][4]) {
;     ...
;   for (int kt = 0; kt < nk; ++kt) {
;     __syncthreads();
;     G_COMPUTE(kt & 1, kt);
;   }
;   if (!has_next) __syncthreads();
	ds_read_b128 v[194:197], v208
	ds_read_b128 v[198:201], v208 offset:4608
	ds_read_b128 v[210:213], v205
	ds_read_b128 v[214:217], v205 offset:4608
	s_setprio 1
	s_waitcnt lgkmcnt(1)
	v_mfma_f32_32x32x16_bf16 v[112:127], v[210:213], v[194:197], v[112:127]
	v_mfma_f32_32x32x16_bf16 v[48:63], v[210:213], v[198:201], v[48:63]
	s_waitcnt lgkmcnt(0)
	v_mfma_f32_32x32x16_bf16 v[96:111], v[214:217], v[194:197], v[96:111]
	v_mfma_f32_32x32x16_bf16 v[32:47], v[214:217], v[198:201], v[32:47]
	ds_read_b128 v[210:213], v205 offset:9216
	ds_read_b128 v[214:217], v205 offset:13824
	s_waitcnt lgkmcnt(1)
	v_mfma_f32_32x32x16_bf16 v[80:95], v[210:213], v[194:197], v[80:95]
	v_mfma_f32_32x32x16_bf16 v[16:31], v[210:213], v[198:201], v[16:31]
	s_waitcnt lgkmcnt(0)
	v_mfma_f32_32x32x16_bf16 v[64:79], v[214:217], v[194:197], v[64:79]
	v_mfma_f32_32x32x16_bf16 v[0:15], v[214:217], v[198:201], v[0:15]
	s_setprio 0
	ds_read_b128 v[194:197], v208 offset:32
	ds_read_b128 v[198:201], v208 offset:4640
	ds_read_b128 v[210:213], v205 offset:32
	ds_read_b128 v[214:217], v205 offset:4640
	s_setprio 1
	s_waitcnt lgkmcnt(1)
	v_mfma_f32_32x32x16_bf16 v[112:127], v[210:213], v[194:197], v[112:127]
	v_mfma_f32_32x32x16_bf16 v[48:63], v[210:213], v[198:201], v[48:63]
	s_waitcnt lgkmcnt(0)
	v_mfma_f32_32x32x16_bf16 v[96:111], v[214:217], v[194:197], v[96:111]
	v_mfma_f32_32x32x16_bf16 v[32:47], v[214:217], v[198:201], v[32:47]
	ds_read_b128 v[210:213], v205 offset:9248
	ds_read_b128 v[214:217], v205 offset:13856
	s_waitcnt lgkmcnt(1)
	v_mfma_f32_32x32x16_bf16 v[80:95], v[210:213], v[194:197], v[80:95]
	v_mfma_f32_32x32x16_bf16 v[16:31], v[210:213], v[198:201], v[16:31]
	s_waitcnt lgkmcnt(0)
	v_mfma_f32_32x32x16_bf16 v[64:79], v[214:217], v[194:197], v[64:79]
	v_mfma_f32_32x32x16_bf16 v[0:15], v[214:217], v[198:201], v[0:15]
	s_setprio 0
	ds_read_b128 v[194:197], v208 offset:64
	ds_read_b128 v[198:201], v208 offset:4672
	ds_read_b128 v[210:213], v205 offset:64
	ds_read_b128 v[214:217], v205 offset:4672
	s_setprio 1
	s_waitcnt lgkmcnt(1)
	v_mfma_f32_32x32x16_bf16 v[112:127], v[210:213], v[194:197], v[112:127]
	v_mfma_f32_32x32x16_bf16 v[48:63], v[210:213], v[198:201], v[48:63]
	s_waitcnt lgkmcnt(0)
	v_mfma_f32_32x32x16_bf16 v[96:111], v[214:217], v[194:197], v[96:111]
	v_mfma_f32_32x32x16_bf16 v[32:47], v[214:217], v[198:201], v[32:47]
	ds_read_b128 v[210:213], v205 offset:9280
	ds_read_b128 v[214:217], v205 offset:13888
	s_waitcnt lgkmcnt(1)
	v_mfma_f32_32x32x16_bf16 v[80:95], v[210:213], v[194:197], v[80:95]
	v_mfma_f32_32x32x16_bf16 v[16:31], v[210:213], v[198:201], v[16:31]
	s_waitcnt lgkmcnt(0)
	v_mfma_f32_32x32x16_bf16 v[64:79], v[214:217], v[194:197], v[64:79]
	v_mfma_f32_32x32x16_bf16 v[0:15], v[214:217], v[198:201], v[0:15]
	s_setprio 0
	ds_read_b128 v[194:197], v208 offset:96
	ds_read_b128 v[198:201], v208 offset:4704
	ds_read_b128 v[208:211], v205 offset:96
	ds_read_b128 v[212:215], v205 offset:4704
	s_setprio 1
	s_waitcnt lgkmcnt(1)
	v_mfma_f32_32x32x16_bf16 v[112:127], v[208:211], v[194:197], v[112:127]
	v_mfma_f32_32x32x16_bf16 v[48:63], v[208:211], v[198:201], v[48:63]
	s_waitcnt lgkmcnt(0)
	v_mfma_f32_32x32x16_bf16 v[96:111], v[212:215], v[194:197], v[96:111]
	v_mfma_f32_32x32x16_bf16 v[32:47], v[212:215], v[198:201], v[32:47]
	ds_read_b128 v[208:211], v205 offset:9312
	ds_read_b128 v[212:215], v205 offset:13920
	s_waitcnt lgkmcnt(1)
	v_mfma_f32_32x32x16_bf16 v[80:95], v[208:211], v[194:197], v[80:95]
	v_mfma_f32_32x32x16_bf16 v[16:31], v[208:211], v[198:201], v[16:31]
	s_waitcnt lgkmcnt(0)
	v_mfma_f32_32x32x16_bf16 v[64:79], v[212:215], v[194:197], v[64:79]
	v_mfma_f32_32x32x16_bf16 v[0:15], v[212:215], v[198:201], v[0:15]
	s_setprio 0
	s_andn2_b64 vcc, exec, s[30:31]
	s_cbranch_vccnz .LBB0_884
	s_barrier

;   DI bf16_t* wt_in1() const { return (bf16_t*)(ws + OFF_WT_IN1); }
;   DI bf16_t* h() const { return (bf16_t*)(ws + OFF_H); }
; template <bool trans>
; DI void gemm_core(const GTile& tl, const GTile& nx, bool has_next  , bool chain  , bool pre, u32x4 (&ra)[4], u32x4 (&rb)[4], char* smem, f32x16 (&acc)[2][4]) {
;     ...
;   const int nk = K / 64;
;   if (!pre) { G_LOAD(0); G_STORE(0); G_LOAD(1); }
;   for (int kt = 0; kt < nk; ++kt) {
;     __syncthreads();
;     G_COMPUTE(kt & 1, kt);
;   }
; DI int in1_nt(int t) { return (t >> 6) < 23 ? (t >> 6) : 25; }
; DI void phase_gemm_in1(const Params& p, char* smem) {
;   u32x4 ra[4], rb[4]; bool pre = false;
;   for (int t = blockIdx.x; t < 64 * 24; t += gridDim.x) {
;     const int mt = t & 63, nt = in1_nt(t), tn = t + gridDim.x;
;     const bool has_next = tn < 64 * 24;
;     const GTile tl{p.h(), D, p.wt_in1(), D, D, mt * 256, nt * 256}, nx{p.h(), D, p.wt_in1(), D, D, (tn & 63) * 256, in1_nt(tn) * 256};
.LBB0_890:
	v_lshl_add_u64 v[136:137], s[2:3], 0, v[192:193]
	v_lshl_add_u64 v[138:139], s[16:17], 0, v[192:193]
	s_waitcnt lgkmcnt(0)
	s_barrier
	global_load_dwordx4 v[184:187], v[136:137], off offset:256
	global_load_dwordx4 v[188:191], v[138:139], off offset:256
	s_ashr_i32 s2, s56, 6
	s_lshl_b32 s3, s2, 8
	s_cmp_lt_i32 s2, 23
	s_cselect_b32 s2, s3, 0x1900
	s_and_b32 s3, s49, 0x1f80000
	s_and_b32 s16, s18, 0xc0
	s_lshl_b32 s3, s3, 1
	s_add_u32 s6, s24, s3
	s_addc_u32 s7, s25, 0
	s_ashr_i32 s3, s2, 31
	s_lshl_b64 s[2:3], s[2:3], 12
	s_add_u32 s2, s27, s2
	s_addc_u32 s3, s40, s3
	s_lshr_b32 s17, s18, 1
	v_and_b32_e32 v11, 31, v8
	s_and_b32 s17, s17, 0xfffff80
	v_or_b32_e32 v12, s17, v11
	v_or_b32_e32 v11, s16, v11
	v_add3_u32 v148, 16, v10, v9
	v_lshrrev_b32_e32 v8, 1, v8
	v_mul_u32_u24_e32 v150, 0x90, v11
	v_lshl_add_u64 v[130:131], s[6:7], 0, v[192:193]
	v_lshl_add_u64 v[128:129], s[2:3], 0, v[192:193]
	v_and_b32_e32 v204, 16, v8
	v_add_u32_e32 v192, 0x12000, v148
	v_mul_lo_u32 v149, v12, s54
	v_add3_u32 v152, 16, v150, v204
	v_add_u32_e32 v159, 0x1b000, v148
	ds_write_b128 v192, v[0:3]
	s_waitcnt vmcnt(5)
	ds_write_b128 v159, v[4:7]
	v_add3_u32 v151, 16, v149, v204
	ds_read_b128 v[0:3], v152 offset:36864
	ds_read_b128 v[16:19], v152 offset:41472
	ds_read_b128 v[4:7], v151
	ds_read_b128 v[8:11], v151 offset:4608
	v_lshl_add_u64 v[140:141], v[136:137], 0, s[12:13]
	v_lshl_add_u64 v[142:143], v[138:139], 0, s[12:13]
	v_lshl_add_u64 v[132:133], v[136:137], 0, s[14:15]
	v_lshl_add_u64 v[134:135], v[138:139], 0, s[14:15]
	s_setprio 1
	s_waitcnt lgkmcnt(1)
	v_mfma_f32_32x32x16_bf16 v[96:111], v[0:3], v[4:7], 0
	v_mfma_f32_32x32x16_bf16 v[112:127], v[16:19], v[4:7], 0
	ds_read_b128 v[4:7], v151 offset:9216
	ds_read_b128 v[20:23], v151 offset:13824
	s_waitcnt lgkmcnt(2)
	v_mfma_f32_32x32x16_bf16 v[64:79], v[0:3], v[8:11], 0
	v_mfma_f32_32x32x16_bf16 v[80:95], v[16:19], v[8:11], 0
	s_waitcnt lgkmcnt(1)
	v_mfma_f32_32x32x16_bf16 v[32:47], v[0:3], v[4:7], 0
	v_mfma_f32_32x32x16_bf16 v[48:63], v[16:19], v[4:7], 0
	s_waitcnt lgkmcnt(0)
	v_mfma_f32_32x32x16_bf16 v[0:15], v[0:3], v[20:23], 0
	v_mfma_f32_32x32x16_bf16 v[16:31], v[16:19], v[20:23], 0
	s_setprio 0
	global_load_dwordx4 v[194:197], v[140:141], off offset:256
	global_load_dwordx4 v[198:201], v[142:143], off offset:256
	v_add_u32_e32 v158, 0x14400, v148
	v_add_u32_e32 v157, 0x1d400, v148
	ds_write_b128 v158, v[176:179]
	s_waitcnt vmcnt(6)
	ds_write_b128 v157, v[180:183]
	ds_read_b128 v[144:147], v152 offset:36896
	ds_read_b128 v[176:179], v152 offset:41504
	ds_read_b128 v[180:183], v151 offset:32
	ds_read_b128 v[208:211], v151 offset:4640
	s_setprio 1
	s_waitcnt lgkmcnt(1)
	v_mfma_f32_32x32x16_bf16 v[96:111], v[144:147], v[180:183], v[96:111]
	v_mfma_f32_32x32x16_bf16 v[112:127], v[176:179], v[180:183], v[112:127]
	s_waitcnt lgkmcnt(0)
	v_mfma_f32_32x32x16_bf16 v[64:79], v[144:147], v[208:211], v[64:79]
	v_mfma_f32_32x32x16_bf16 v[80:95], v[176:179], v[208:211], v[80:95]
	ds_read_b128 v[180:183], v151 offset:9248
	ds_read_b128 v[208:211], v151 offset:13856
	s_waitcnt lgkmcnt(1)
	v_mfma_f32_32x32x16_bf16 v[32:47], v[144:147], v[180:183], v[32:47]
	v_mfma_f32_32x32x16_bf16 v[48:63], v[176:179], v[180:183], v[48:63]
	s_waitcnt lgkmcnt(0)
	v_mfma_f32_32x32x16_bf16 v[0:15], v[144:147], v[208:211], v[0:15]
	v_mfma_f32_32x32x16_bf16 v[16:31], v[176:179], v[208:211], v[16:31]
	s_setprio 0
	global_load_dwordx4 v[176:179], v[132:133], off offset:256
	global_load_dwordx4 v[180:183], v[134:135], off offset:256
	v_add_u32_e32 v154, 0x16800, v148
	v_add_u32_e32 v153, 0x1f800, v148
	ds_write_b128 v154, v[168:171]
	s_waitcnt vmcnt(7)
	ds_write_b128 v153, v[172:175]
	ds_read_b128 v[144:147], v152 offset:36928
	ds_read_b128 v[168:171], v152 offset:41536
	ds_read_b128 v[172:175], v151 offset:64
	ds_read_b128 v[208:211], v151 offset:4672
	s_setprio 1
	s_waitcnt lgkmcnt(1)
	v_mfma_f32_32x32x16_bf16 v[96:111], v[144:147], v[172:175], v[96:111]
	v_mfma_f32_32x32x16_bf16 v[112:127], v[168:171], v[172:175], v[112:127]
	s_waitcnt lgkmcnt(0)
	v_mfma_f32_32x32x16_bf16 v[64:79], v[144:147], v[208:211], v[64:79]
	v_mfma_f32_32x32x16_bf16 v[80:95], v[168:171], v[208:211], v[80:95]
	ds_read_b128 v[172:175], v151 offset:9280
	ds_read_b128 v[208:211], v151 offset:13888
	s_waitcnt lgkmcnt(1)
	v_mfma_f32_32x32x16_bf16 v[32:47], v[144:147], v[172:175], v[32:47]
	v_mfma_f32_32x32x16_bf16 v[48:63], v[168:171], v[172:175], v[48:63]
	s_waitcnt lgkmcnt(0)
	v_mfma_f32_32x32x16_bf16 v[0:15], v[144:147], v[208:211], v[0:15]
	v_mfma_f32_32x32x16_bf16 v[16:31], v[168:171], v[208:211], v[16:31]
	s_setprio 0
	v_add_co_u32_e32 v144, vcc, s53, v136
	v_add_u32_e32 v156, 0x18c00, v148
	s_nop 0
	v_addc_co_u32_e32 v145, vcc, 0, v137, vcc
	v_add_co_u32_e32 v146, vcc, s53, v138
	v_add_u32_e32 v155, 0x21c00, v148
	s_nop 0
	v_addc_co_u32_e32 v147, vcc, 0, v139, vcc
	global_load_dwordx4 v[168:171], v[144:145], off offset:256
	global_load_dwordx4 v[172:175], v[146:147], off offset:256
	ds_write_b128 v156, v[160:163]
	s_waitcnt vmcnt(8)
	ds_write_b128 v155, v[164:167]
	ds_read_b128 v[160:163], v152 offset:36960
	ds_read_b128 v[164:167], v152 offset:41568
	ds_read_b128 v[208:211], v151 offset:96
	ds_read_b128 v[212:215], v151 offset:4704
	s_setprio 1
	s_waitcnt lgkmcnt(1)
	v_mfma_f32_32x32x16_bf16 v[96:111], v[160:163], v[208:211], v[96:111]
	v_mfma_f32_32x32x16_bf16 v[112:127], v[164:167], v[208:211], v[112:127]
	s_waitcnt lgkmcnt(0)
	v_mfma_f32_32x32x16_bf16 v[64:79], v[160:163], v[212:215], v[64:79]
	v_mfma_f32_32x32x16_bf16 v[80:95], v[164:167], v[212:215], v[80:95]
	ds_read_b128 v[208:211], v151 offset:9312
	ds_read_b128 v[212:215], v151 offset:13920
	s_waitcnt lgkmcnt(1)
	v_mfma_f32_32x32x16_bf16 v[32:47], v[160:163], v[208:211], v[32:47]
	v_mfma_f32_32x32x16_bf16 v[48:63], v[164:167], v[208:211], v[48:63]
	s_waitcnt lgkmcnt(0)
	v_mfma_f32_32x32x16_bf16 v[0:15], v[160:163], v[212:215], v[0:15]
	v_mfma_f32_32x32x16_bf16 v[16:31], v[164:167], v[212:215], v[16:31]
	s_setprio 0
	global_load_dwordx4 v[160:163], v[136:137], off offset:384
	global_load_dwordx4 v[164:167], v[138:139], off offset:384
	s_barrier
; template <bool trans>
; DI void gemm_core(const GTile& tl, const GTile& nx, bool has_next  , bool chain  , bool pre, u32x4 (&ra)[4], u32x4 (&rb)[4], char* smem, f32x16 (&acc)[2][4]) {
;     ...
;   const int nk = K / 64;
;   if (!pre) { G_LOAD(0); G_STORE(0); G_LOAD(1); }
;   for (int kt = 0; kt < nk; ++kt) {
;     __syncthreads();
;     G_COMPUTE(kt & 1, kt);
;   }
	s_add_i32 s2, 16, 0x12000
	v_add3_u32 v149, s2, v149, v204
	s_add_i32 s2, 16, 0x1b000
	v_add3_u32 v150, s2, v150, v204
	s_waitcnt vmcnt(9)
	ds_write_b128 v148, v[184:187]
	s_waitcnt vmcnt(8)
	ds_write_b128 v148, v[188:191] offset:36864
	ds_read_b128 v[184:187], v150
	ds_read_b128 v[188:191], v150 offset:4608
	ds_read_b128 v[208:211], v149
	ds_read_b128 v[212:215], v149 offset:4608
	s_setprio 1
	s_waitcnt lgkmcnt(1)
	v_mfma_f32_32x32x16_bf16 v[96:111], v[184:187], v[208:211], v[96:111]
	v_mfma_f32_32x32x16_bf16 v[112:127], v[188:191], v[208:211], v[112:127]
	s_waitcnt lgkmcnt(0)
	v_mfma_f32_32x32x16_bf16 v[64:79], v[184:187], v[212:215], v[64:79]
	v_mfma_f32_32x32x16_bf16 v[80:95], v[188:191], v[212:215], v[80:95]
	ds_read_b128 v[208:211], v149 offset:9216
	ds_read_b128 v[212:215], v149 offset:13824
	s_waitcnt lgkmcnt(1)
	v_mfma_f32_32x32x16_bf16 v[32:47], v[184:187], v[208:211], v[32:47]
	v_mfma_f32_32x32x16_bf16 v[48:63], v[188:191], v[208:211], v[48:63]
	s_waitcnt lgkmcnt(0)
	v_mfma_f32_32x32x16_bf16 v[0:15], v[184:187], v[212:215], v[0:15]
	v_mfma_f32_32x32x16_bf16 v[16:31], v[188:191], v[212:215], v[16:31]
	s_setprio 0
	global_load_dwordx4 v[184:187], v[140:141], off offset:384
	global_load_dwordx4 v[188:191], v[142:143], off offset:384
	s_waitcnt vmcnt(9)
	ds_write_b128 v148, v[194:197] offset:9216
	s_waitcnt vmcnt(8)
	ds_write_b128 v148, v[198:201] offset:46080
	ds_read_b128 v[194:197], v150 offset:32
	ds_read_b128 v[198:201], v150 offset:4640
	ds_read_b128 v[208:211], v149 offset:32
	ds_read_b128 v[212:215], v149 offset:4640
	s_setprio 1
	s_waitcnt lgkmcnt(1)
	v_mfma_f32_32x32x16_bf16 v[96:111], v[194:197], v[208:211], v[96:111]
	v_mfma_f32_32x32x16_bf16 v[112:127], v[198:201], v[208:211], v[112:127]
	s_waitcnt lgkmcnt(0)
	v_mfma_f32_32x32x16_bf16 v[64:79], v[194:197], v[212:215], v[64:79]
	v_mfma_f32_32x32x16_bf16 v[80:95], v[198:201], v[212:215], v[80:95]
	ds_read_b128 v[208:211], v149 offset:9248
	ds_read_b128 v[212:215], v149 offset:13856
	s_waitcnt lgkmcnt(1)
	v_mfma_f32_32x32x16_bf16 v[32:47], v[194:197], v[208:211], v[32:47]
	v_mfma_f32_32x32x16_bf16 v[48:63], v[198:201], v[208:211], v[48:63]
	s_waitcnt lgkmcnt(0)
	v_mfma_f32_32x32x16_bf16 v[0:15], v[194:197], v[212:215], v[0:15]
	v_mfma_f32_32x32x16_bf16 v[16:31], v[198:201], v[212:215], v[16:31]
	s_setprio 0
	global_load_dwordx4 v[194:197], v[132:133], off offset:384
	global_load_dwordx4 v[198:201], v[134:135], off offset:384
	s_waitcnt vmcnt(9)
	ds_write_b128 v148, v[176:179] offset:18432
	s_waitcnt vmcnt(8)
	ds_write_b128 v148, v[180:183] offset:55296
	ds_read_b128 v[176:179], v150 offset:64
	ds_read_b128 v[180:183], v150 offset:4672
	ds_read_b128 v[208:211], v149 offset:64
	ds_read_b128 v[212:215], v149 offset:4672
	s_setprio 1
	s_waitcnt lgkmcnt(1)
	v_mfma_f32_32x32x16_bf16 v[96:111], v[176:179], v[208:211], v[96:111]
	v_mfma_f32_32x32x16_bf16 v[112:127], v[180:183], v[208:211], v[112:127]
	s_waitcnt lgkmcnt(0)
	v_mfma_f32_32x32x16_bf16 v[64:79], v[176:179], v[212:215], v[64:79]
	v_mfma_f32_32x32x16_bf16 v[80:95], v[180:183], v[212:215], v[80:95]
	ds_read_b128 v[208:211], v149 offset:9280
	ds_read_b128 v[212:215], v149 offset:13888
	s_waitcnt lgkmcnt(1)
	v_mfma_f32_32x32x16_bf16 v[32:47], v[176:179], v[208:211], v[32:47]
	v_mfma_f32_32x32x16_bf16 v[48:63], v[180:183], v[208:211], v[48:63]
	s_waitcnt lgkmcnt(0)
	v_mfma_f32_32x32x16_bf16 v[0:15], v[176:179], v[212:215], v[0:15]
	v_mfma_f32_32x32x16_bf16 v[16:31], v[180:183], v[212:215], v[16:31]
	s_setprio 0
	global_load_dwordx4 v[176:179], v[144:145], off offset:384
	global_load_dwordx4 v[180:183], v[146:147], off offset:384
	s_waitcnt vmcnt(9)
	ds_write_b128 v148, v[168:171] offset:27648
	s_waitcnt vmcnt(8)
	ds_write_b128 v148, v[172:175] offset:64512
	ds_read_b128 v[168:171], v150 offset:96
	ds_read_b128 v[172:175], v150 offset:4704
	ds_read_b128 v[208:211], v149 offset:96
	ds_read_b128 v[212:215], v149 offset:4704
	s_setprio 1
	s_waitcnt lgkmcnt(1)
	v_mfma_f32_32x32x16_bf16 v[96:111], v[168:171], v[208:211], v[96:111]
	v_mfma_f32_32x32x16_bf16 v[112:127], v[172:175], v[208:211], v[112:127]
	s_waitcnt lgkmcnt(0)
	v_mfma_f32_32x32x16_bf16 v[64:79], v[168:171], v[212:215], v[64:79]
	v_mfma_f32_32x32x16_bf16 v[80:95], v[172:175], v[212:215], v[80:95]
	ds_read_b128 v[208:211], v149 offset:9312
	ds_read_b128 v[212:215], v149 offset:13920
	s_waitcnt lgkmcnt(1)
	v_mfma_f32_32x32x16_bf16 v[32:47], v[168:171], v[208:211], v[32:47]
	v_mfma_f32_32x32x16_bf16 v[48:63], v[172:175], v[208:211], v[48:63]
	s_waitcnt lgkmcnt(0)
	v_mfma_f32_32x32x16_bf16 v[0:15], v[168:171], v[212:215], v[0:15]
	v_mfma_f32_32x32x16_bf16 v[16:31], v[172:175], v[212:215], v[16:31]
	s_setprio 0
	global_load_dwordx4 v[168:171], v[136:137], off offset:512
	global_load_dwordx4 v[172:175], v[138:139], off offset:512
	s_barrier
; template <bool trans>
; DI void gemm_core(const GTile& tl, const GTile& nx, bool has_next  , bool chain  , bool pre, u32x4 (&ra)[4], u32x4 (&rb)[4], char* smem, f32x16 (&acc)[2][4]) {
;     ...
;   const int nk = K / 64;
;   if (!pre) { G_LOAD(0); G_STORE(0); G_LOAD(1); }
;   for (int kt = 0; kt < nk; ++kt) {
;     __syncthreads();
;     G_COMPUTE(kt & 1, kt);
;   }
	s_waitcnt vmcnt(9)
	ds_write_b128 v192, v[160:163]
	s_waitcnt vmcnt(8)
	ds_write_b128 v159, v[164:167]
	ds_read_b128 v[160:163], v152 offset:36864
	ds_read_b128 v[164:167], v152 offset:41472
	ds_read_b128 v[208:211], v151
	ds_read_b128 v[212:215], v151 offset:4608
	s_setprio 1
	s_waitcnt lgkmcnt(1)
	v_mfma_f32_32x32x16_bf16 v[96:111], v[160:163], v[208:211], v[96:111]
	v_mfma_f32_32x32x16_bf16 v[112:127], v[164:167], v[208:211], v[112:127]
	s_waitcnt lgkmcnt(0)
	v_mfma_f32_32x32x16_bf16 v[64:79], v[160:163], v[212:215], v[64:79]
	v_mfma_f32_32x32x16_bf16 v[80:95], v[164:167], v[212:215], v[80:95]
	ds_read_b128 v[208:211], v151 offset:9216
	ds_read_b128 v[212:215], v151 offset:13824
	s_waitcnt vmcnt(7)
	ds_write_b128 v158, v[184:187]
	s_waitcnt vmcnt(6)
	ds_write_b128 v157, v[188:191]
	ds_read_b128 v[184:187], v152 offset:36896
	ds_read_b128 v[188:191], v152 offset:41504
	s_waitcnt lgkmcnt(5)
	v_mfma_f32_32x32x16_bf16 v[32:47], v[160:163], v[208:211], v[32:47]
	v_mfma_f32_32x32x16_bf16 v[48:63], v[164:167], v[208:211], v[48:63]
	ds_read_b128 v[208:211], v151 offset:32
	s_waitcnt lgkmcnt(5)
	v_mfma_f32_32x32x16_bf16 v[0:15], v[160:163], v[212:215], v[0:15]
	v_mfma_f32_32x32x16_bf16 v[16:31], v[164:167], v[212:215], v[16:31]
	ds_read_b128 v[212:215], v151 offset:4640
	s_setprio 0
	global_load_dwordx4 v[160:163], v[140:141], off offset:512
	global_load_dwordx4 v[164:167], v[142:143], off offset:512
	s_setprio 1
	s_waitcnt lgkmcnt(1)
	v_mfma_f32_32x32x16_bf16 v[96:111], v[184:187], v[208:211], v[96:111]
	v_mfma_f32_32x32x16_bf16 v[112:127], v[188:191], v[208:211], v[112:127]
	s_waitcnt lgkmcnt(0)
	v_mfma_f32_32x32x16_bf16 v[64:79], v[184:187], v[212:215], v[64:79]
	v_mfma_f32_32x32x16_bf16 v[80:95], v[188:191], v[212:215], v[80:95]
	ds_read_b128 v[208:211], v151 offset:9248
	ds_read_b128 v[212:215], v151 offset:13856
	s_waitcnt vmcnt(7)
	ds_write_b128 v154, v[194:197]
	s_waitcnt vmcnt(6)
	ds_write_b128 v153, v[198:201]
	ds_read_b128 v[194:197], v152 offset:36928
	ds_read_b128 v[198:201], v152 offset:41536
	s_waitcnt lgkmcnt(5)
	v_mfma_f32_32x32x16_bf16 v[32:47], v[184:187], v[208:211], v[32:47]
	v_mfma_f32_32x32x16_bf16 v[48:63], v[188:191], v[208:211], v[48:63]
	ds_read_b128 v[208:211], v151 offset:64
	s_waitcnt lgkmcnt(5)
	v_mfma_f32_32x32x16_bf16 v[0:15], v[184:187], v[212:215], v[0:15]
	v_mfma_f32_32x32x16_bf16 v[16:31], v[188:191], v[212:215], v[16:31]
	ds_read_b128 v[212:215], v151 offset:4672
	s_setprio 0
	global_load_dwordx4 v[184:187], v[132:133], off offset:512
	global_load_dwordx4 v[188:191], v[134:135], off offset:512
	s_setprio 1
	s_waitcnt lgkmcnt(1)
	v_mfma_f32_32x32x16_bf16 v[96:111], v[194:197], v[208:211], v[96:111]
	v_mfma_f32_32x32x16_bf16 v[112:127], v[198:201], v[208:211], v[112:127]
	s_waitcnt lgkmcnt(0)
	v_mfma_f32_32x32x16_bf16 v[64:79], v[194:197], v[212:215], v[64:79]
	v_mfma_f32_32x32x16_bf16 v[80:95], v[198:201], v[212:215], v[80:95]
	ds_read_b128 v[208:211], v151 offset:9280
	ds_read_b128 v[212:215], v151 offset:13888
	s_waitcnt vmcnt(7)
	ds_write_b128 v156, v[176:179]
	s_waitcnt vmcnt(6)
	ds_write_b128 v155, v[180:183]
	ds_read_b128 v[176:179], v152 offset:36960
	ds_read_b128 v[180:183], v152 offset:41568
	s_waitcnt lgkmcnt(5)
	v_mfma_f32_32x32x16_bf16 v[32:47], v[194:197], v[208:211], v[32:47]
	v_mfma_f32_32x32x16_bf16 v[48:63], v[198:201], v[208:211], v[48:63]
	ds_read_b128 v[208:211], v151 offset:96
	s_waitcnt lgkmcnt(5)
	v_mfma_f32_32x32x16_bf16 v[0:15], v[194:197], v[212:215], v[0:15]
	v_mfma_f32_32x32x16_bf16 v[16:31], v[198:201], v[212:215], v[16:31]
	ds_read_b128 v[212:215], v151 offset:4704
	s_setprio 0
	global_load_dwordx4 v[194:197], v[144:145], off offset:512
	global_load_dwordx4 v[198:201], v[146:147], off offset:512
	s_setprio 1
	s_waitcnt lgkmcnt(1)
	v_mfma_f32_32x32x16_bf16 v[96:111], v[176:179], v[208:211], v[96:111]
	v_mfma_f32_32x32x16_bf16 v[112:127], v[180:183], v[208:211], v[112:127]
	s_waitcnt lgkmcnt(0)
	v_mfma_f32_32x32x16_bf16 v[64:79], v[176:179], v[212:215], v[64:79]
	v_mfma_f32_32x32x16_bf16 v[80:95], v[180:183], v[212:215], v[80:95]
	ds_read_b128 v[208:211], v151 offset:9312
	ds_read_b128 v[212:215], v151 offset:13920
	s_waitcnt lgkmcnt(0)
	s_barrier
	s_waitcnt vmcnt(7)
	ds_write_b128 v148, v[168:171]
	s_waitcnt vmcnt(6)
	ds_write_b128 v148, v[172:175] offset:36864
	ds_read_b128 v[168:171], v150
	ds_read_b128 v[172:175], v150 offset:4608
	v_mfma_f32_32x32x16_bf16 v[32:47], v[176:179], v[208:211], v[32:47]
	v_mfma_f32_32x32x16_bf16 v[48:63], v[180:183], v[208:211], v[48:63]
	ds_read_b128 v[208:211], v149
	v_mfma_f32_32x32x16_bf16 v[0:15], v[176:179], v[212:215], v[0:15]
	v_mfma_f32_32x32x16_bf16 v[16:31], v[180:183], v[212:215], v[16:31]
	ds_read_b128 v[212:215], v149 offset:4608
	s_setprio 0
	global_load_dwordx4 v[176:179], v[136:137], off offset:640
	global_load_dwordx4 v[180:183], v[138:139], off offset:640
	s_setprio 1
	s_waitcnt lgkmcnt(1)
	v_mfma_f32_32x32x16_bf16 v[96:111], v[168:171], v[208:211], v[96:111]
	v_mfma_f32_32x32x16_bf16 v[112:127], v[172:175], v[208:211], v[112:127]
	s_waitcnt lgkmcnt(0)
	v_mfma_f32_32x32x16_bf16 v[64:79], v[168:171], v[212:215], v[64:79]
	v_mfma_f32_32x32x16_bf16 v[80:95], v[172:175], v[212:215], v[80:95]
	ds_read_b128 v[208:211], v149 offset:9216
	ds_read_b128 v[212:215], v149 offset:13824
	s_waitcnt vmcnt(7)
	ds_write_b128 v148, v[160:163] offset:9216
	s_waitcnt vmcnt(6)
	ds_write_b128 v148, v[164:167] offset:46080
	ds_read_b128 v[160:163], v150 offset:32
	ds_read_b128 v[164:167], v150 offset:4640
	s_waitcnt lgkmcnt(5)
	v_mfma_f32_32x32x16_bf16 v[32:47], v[168:171], v[208:211], v[32:47]
	v_mfma_f32_32x32x16_bf16 v[48:63], v[172:175], v[208:211], v[48:63]
	ds_read_b128 v[208:211], v149 offset:32
	s_waitcnt lgkmcnt(5)
; template <bool trans>
; DI void gemm_core(const GTile& tl, const GTile& nx, bool has_next  , bool chain  , bool pre, u32x4 (&ra)[4], u32x4 (&rb)[4], char* smem, f32x16 (&acc)[2][4]) {
;     ...
;   const int nk = K / 64;
;   if (!pre) { G_LOAD(0); G_STORE(0); G_LOAD(1); }
;   for (int kt = 0; kt < nk; ++kt) {
;     __syncthreads();
;     G_COMPUTE(kt & 1, kt);
;   }
	v_mfma_f32_32x32x16_bf16 v[0:15], v[168:171], v[212:215], v[0:15]
	v_mfma_f32_32x32x16_bf16 v[16:31], v[172:175], v[212:215], v[16:31]
	ds_read_b128 v[212:215], v149 offset:4640
	s_setprio 0
	global_load_dwordx4 v[168:171], v[140:141], off offset:640
	global_load_dwordx4 v[172:175], v[142:143], off offset:640
	s_setprio 1
	s_waitcnt lgkmcnt(1)
	v_mfma_f32_32x32x16_bf16 v[96:111], v[160:163], v[208:211], v[96:111]
	v_mfma_f32_32x32x16_bf16 v[112:127], v[164:167], v[208:211], v[112:127]
	s_waitcnt lgkmcnt(0)
	v_mfma_f32_32x32x16_bf16 v[64:79], v[160:163], v[212:215], v[64:79]
	v_mfma_f32_32x32x16_bf16 v[80:95], v[164:167], v[212:215], v[80:95]
	ds_read_b128 v[208:211], v149 offset:9248
	ds_read_b128 v[212:215], v149 offset:13856
	s_waitcnt vmcnt(7)
	ds_write_b128 v148, v[184:187] offset:18432
	s_waitcnt vmcnt(6)
	ds_write_b128 v148, v[188:191] offset:55296
	ds_read_b128 v[184:187], v150 offset:64
	ds_read_b128 v[188:191], v150 offset:4672
	s_waitcnt lgkmcnt(5)
	v_mfma_f32_32x32x16_bf16 v[32:47], v[160:163], v[208:211], v[32:47]
	v_mfma_f32_32x32x16_bf16 v[48:63], v[164:167], v[208:211], v[48:63]
	ds_read_b128 v[208:211], v149 offset:64
	s_waitcnt lgkmcnt(5)
	v_mfma_f32_32x32x16_bf16 v[0:15], v[160:163], v[212:215], v[0:15]
	v_mfma_f32_32x32x16_bf16 v[16:31], v[164:167], v[212:215], v[16:31]
	ds_read_b128 v[212:215], v149 offset:4672
	s_setprio 0
	global_load_dwordx4 v[160:163], v[132:133], off offset:640
	global_load_dwordx4 v[164:167], v[134:135], off offset:640
	s_setprio 1
	s_waitcnt lgkmcnt(1)
	v_mfma_f32_32x32x16_bf16 v[96:111], v[184:187], v[208:211], v[96:111]
	v_mfma_f32_32x32x16_bf16 v[112:127], v[188:191], v[208:211], v[112:127]
	s_waitcnt lgkmcnt(0)
	v_mfma_f32_32x32x16_bf16 v[64:79], v[184:187], v[212:215], v[64:79]
	v_mfma_f32_32x32x16_bf16 v[80:95], v[188:191], v[212:215], v[80:95]
	ds_read_b128 v[208:211], v149 offset:9280
	ds_read_b128 v[212:215], v149 offset:13888
	s_waitcnt vmcnt(7)
	ds_write_b128 v148, v[194:197] offset:27648
	s_waitcnt vmcnt(6)
	ds_write_b128 v148, v[198:201] offset:64512
	ds_read_b128 v[194:197], v150 offset:96
	ds_read_b128 v[198:201], v150 offset:4704
	s_waitcnt lgkmcnt(5)
	v_mfma_f32_32x32x16_bf16 v[32:47], v[184:187], v[208:211], v[32:47]
	v_mfma_f32_32x32x16_bf16 v[48:63], v[188:191], v[208:211], v[48:63]
	ds_read_b128 v[208:211], v149 offset:96
	s_waitcnt lgkmcnt(5)
	v_mfma_f32_32x32x16_bf16 v[0:15], v[184:187], v[212:215], v[0:15]
	v_mfma_f32_32x32x16_bf16 v[16:31], v[188:191], v[212:215], v[16:31]
	ds_read_b128 v[212:215], v149 offset:4704
	s_setprio 0
	global_load_dwordx4 v[184:187], v[144:145], off offset:640
	global_load_dwordx4 v[188:191], v[146:147], off offset:640
	s_setprio 1
	s_waitcnt lgkmcnt(1)
	v_mfma_f32_32x32x16_bf16 v[96:111], v[194:197], v[208:211], v[96:111]
	v_mfma_f32_32x32x16_bf16 v[112:127], v[198:201], v[208:211], v[112:127]
	s_waitcnt lgkmcnt(0)
	v_mfma_f32_32x32x16_bf16 v[64:79], v[194:197], v[212:215], v[64:79]
	v_mfma_f32_32x32x16_bf16 v[80:95], v[198:201], v[212:215], v[80:95]
	ds_read_b128 v[208:211], v149 offset:9312
	ds_read_b128 v[212:215], v149 offset:13920
	s_waitcnt lgkmcnt(0)
	s_barrier
	s_waitcnt vmcnt(7)
	ds_write_b128 v192, v[176:179]
	s_waitcnt vmcnt(6)
	ds_write_b128 v159, v[180:183]
	ds_read_b128 v[176:179], v152 offset:36864
	ds_read_b128 v[180:183], v152 offset:41472
	v_mfma_f32_32x32x16_bf16 v[32:47], v[194:197], v[208:211], v[32:47]
	v_mfma_f32_32x32x16_bf16 v[48:63], v[198:201], v[208:211], v[48:63]
	ds_read_b128 v[208:211], v151
	v_mfma_f32_32x32x16_bf16 v[0:15], v[194:197], v[212:215], v[0:15]
	v_mfma_f32_32x32x16_bf16 v[16:31], v[198:201], v[212:215], v[16:31]
	ds_read_b128 v[212:215], v151 offset:4608
	s_setprio 0
	global_load_dwordx4 v[194:197], v[136:137], off offset:768
	global_load_dwordx4 v[198:201], v[138:139], off offset:768
	s_setprio 1
	s_waitcnt lgkmcnt(1)
	v_mfma_f32_32x32x16_bf16 v[96:111], v[176:179], v[208:211], v[96:111]
	v_mfma_f32_32x32x16_bf16 v[112:127], v[180:183], v[208:211], v[112:127]
	s_waitcnt lgkmcnt(0)
	v_mfma_f32_32x32x16_bf16 v[64:79], v[176:179], v[212:215], v[64:79]
	v_mfma_f32_32x32x16_bf16 v[80:95], v[180:183], v[212:215], v[80:95]
	ds_read_b128 v[208:211], v151 offset:9216
	ds_read_b128 v[212:215], v151 offset:13824
	s_waitcnt vmcnt(7)
	ds_write_b128 v158, v[168:171]
	s_waitcnt vmcnt(6)
	ds_write_b128 v157, v[172:175]
	ds_read_b128 v[168:171], v152 offset:36896
	ds_read_b128 v[172:175], v152 offset:41504
	s_waitcnt lgkmcnt(5)
	v_mfma_f32_32x32x16_bf16 v[32:47], v[176:179], v[208:211], v[32:47]
	v_mfma_f32_32x32x16_bf16 v[48:63], v[180:183], v[208:211], v[48:63]
	ds_read_b128 v[208:211], v151 offset:32
	s_waitcnt lgkmcnt(5)
	v_mfma_f32_32x32x16_bf16 v[0:15], v[176:179], v[212:215], v[0:15]
	v_mfma_f32_32x32x16_bf16 v[16:31], v[180:183], v[212:215], v[16:31]
	ds_read_b128 v[212:215], v151 offset:4640
	s_setprio 0
	global_load_dwordx4 v[176:179], v[140:141], off offset:768
	global_load_dwordx4 v[180:183], v[142:143], off offset:768
	s_setprio 1
	s_waitcnt lgkmcnt(1)
	v_mfma_f32_32x32x16_bf16 v[96:111], v[168:171], v[208:211], v[96:111]
	v_mfma_f32_32x32x16_bf16 v[112:127], v[172:175], v[208:211], v[112:127]
	s_waitcnt lgkmcnt(0)
	v_mfma_f32_32x32x16_bf16 v[64:79], v[168:171], v[212:215], v[64:79]
	v_mfma_f32_32x32x16_bf16 v[80:95], v[172:175], v[212:215], v[80:95]
	ds_read_b128 v[208:211], v151 offset:9248
	ds_read_b128 v[212:215], v151 offset:13856
	s_waitcnt vmcnt(7)
	ds_write_b128 v154, v[160:163]
	s_waitcnt vmcnt(6)
	ds_write_b128 v153, v[164:167]
	ds_read_b128 v[160:163], v152 offset:36928
	ds_read_b128 v[164:167], v152 offset:41536
	s_waitcnt lgkmcnt(5)
; template <bool trans>
; DI void gemm_core(const GTile& tl, const GTile& nx, bool has_next  , bool chain  , bool pre, u32x4 (&ra)[4], u32x4 (&rb)[4], char* smem, f32x16 (&acc)[2][4]) {
;     ...
;   const int nk = K / 64;
;   if (!pre) { G_LOAD(0); G_STORE(0); G_LOAD(1); }
;   for (int kt = 0; kt < nk; ++kt) {
;     __syncthreads();
;     G_COMPUTE(kt & 1, kt);
;   }
	v_mfma_f32_32x32x16_bf16 v[32:47], v[168:171], v[208:211], v[32:47]
	v_mfma_f32_32x32x16_bf16 v[48:63], v[172:175], v[208:211], v[48:63]
	ds_read_b128 v[208:211], v151 offset:64
	s_waitcnt lgkmcnt(5)
	v_mfma_f32_32x32x16_bf16 v[0:15], v[168:171], v[212:215], v[0:15]
	v_mfma_f32_32x32x16_bf16 v[16:31], v[172:175], v[212:215], v[16:31]
	ds_read_b128 v[212:215], v151 offset:4672
	s_setprio 0
	global_load_dwordx4 v[168:171], v[132:133], off offset:768
	global_load_dwordx4 v[172:175], v[134:135], off offset:768
	s_setprio 1
	s_waitcnt lgkmcnt(1)
	v_mfma_f32_32x32x16_bf16 v[96:111], v[160:163], v[208:211], v[96:111]
	v_mfma_f32_32x32x16_bf16 v[112:127], v[164:167], v[208:211], v[112:127]
	s_waitcnt lgkmcnt(0)
	v_mfma_f32_32x32x16_bf16 v[64:79], v[160:163], v[212:215], v[64:79]
	v_mfma_f32_32x32x16_bf16 v[80:95], v[164:167], v[212:215], v[80:95]
	ds_read_b128 v[208:211], v151 offset:9280
	ds_read_b128 v[212:215], v151 offset:13888
	s_waitcnt vmcnt(7)
	ds_write_b128 v156, v[184:187]
	s_waitcnt vmcnt(6)
	ds_write_b128 v155, v[188:191]
	ds_read_b128 v[184:187], v152 offset:36960
	ds_read_b128 v[188:191], v152 offset:41568
	s_waitcnt lgkmcnt(5)
	v_mfma_f32_32x32x16_bf16 v[32:47], v[160:163], v[208:211], v[32:47]
	v_mfma_f32_32x32x16_bf16 v[48:63], v[164:167], v[208:211], v[48:63]
	ds_read_b128 v[208:211], v151 offset:96
	s_waitcnt lgkmcnt(5)
	v_mfma_f32_32x32x16_bf16 v[0:15], v[160:163], v[212:215], v[0:15]
	v_mfma_f32_32x32x16_bf16 v[16:31], v[164:167], v[212:215], v[16:31]
	ds_read_b128 v[212:215], v151 offset:4704
	s_setprio 0
	global_load_dwordx4 v[160:163], v[144:145], off offset:768
	global_load_dwordx4 v[164:167], v[146:147], off offset:768
	s_setprio 1
	s_waitcnt lgkmcnt(1)
	v_mfma_f32_32x32x16_bf16 v[96:111], v[184:187], v[208:211], v[96:111]
	v_mfma_f32_32x32x16_bf16 v[112:127], v[188:191], v[208:211], v[112:127]
	s_waitcnt lgkmcnt(0)
	v_mfma_f32_32x32x16_bf16 v[64:79], v[184:187], v[212:215], v[64:79]
	v_mfma_f32_32x32x16_bf16 v[80:95], v[188:191], v[212:215], v[80:95]
	ds_read_b128 v[208:211], v151 offset:9312
	ds_read_b128 v[212:215], v151 offset:13920
	s_waitcnt lgkmcnt(0)
	s_barrier
	s_waitcnt vmcnt(7)
	ds_write_b128 v148, v[194:197]
	s_waitcnt vmcnt(6)
	ds_write_b128 v148, v[198:201] offset:36864
	ds_read_b128 v[194:197], v150
	ds_read_b128 v[198:201], v150 offset:4608
	v_mfma_f32_32x32x16_bf16 v[32:47], v[184:187], v[208:211], v[32:47]
	v_mfma_f32_32x32x16_bf16 v[48:63], v[188:191], v[208:211], v[48:63]
	ds_read_b128 v[208:211], v149
	v_mfma_f32_32x32x16_bf16 v[0:15], v[184:187], v[212:215], v[0:15]
	v_mfma_f32_32x32x16_bf16 v[16:31], v[188:191], v[212:215], v[16:31]
	ds_read_b128 v[212:215], v149 offset:4608
	s_setprio 0
	global_load_dwordx4 v[184:187], v[136:137], off offset:896
	global_load_dwordx4 v[188:191], v[138:139], off offset:896
	s_setprio 1
	s_waitcnt lgkmcnt(1)
	v_mfma_f32_32x32x16_bf16 v[96:111], v[194:197], v[208:211], v[96:111]
	v_mfma_f32_32x32x16_bf16 v[112:127], v[198:201], v[208:211], v[112:127]
	s_waitcnt lgkmcnt(0)
	v_mfma_f32_32x32x16_bf16 v[64:79], v[194:197], v[212:215], v[64:79]
	v_mfma_f32_32x32x16_bf16 v[80:95], v[198:201], v[212:215], v[80:95]
	ds_read_b128 v[208:211], v149 offset:9216
	ds_read_b128 v[212:215], v149 offset:13824
	s_waitcnt vmcnt(7)
	ds_write_b128 v148, v[176:179] offset:9216
	s_waitcnt vmcnt(6)
	ds_write_b128 v148, v[180:183] offset:46080
	ds_read_b128 v[176:179], v150 offset:32
	ds_read_b128 v[180:183], v150 offset:4640
	s_waitcnt lgkmcnt(5)
	v_mfma_f32_32x32x16_bf16 v[32:47], v[194:197], v[208:211], v[32:47]
	v_mfma_f32_32x32x16_bf16 v[48:63], v[198:201], v[208:211], v[48:63]
	ds_read_b128 v[208:211], v149 offset:32
	s_waitcnt lgkmcnt(5)
	v_mfma_f32_32x32x16_bf16 v[0:15], v[194:197], v[212:215], v[0:15]
	v_mfma_f32_32x32x16_bf16 v[16:31], v[198:201], v[212:215], v[16:31]
	ds_read_b128 v[212:215], v149 offset:4640
	s_setprio 0
	global_load_dwordx4 v[194:197], v[140:141], off offset:896
	global_load_dwordx4 v[198:201], v[142:143], off offset:896
	s_setprio 1
	s_waitcnt lgkmcnt(1)
	v_mfma_f32_32x32x16_bf16 v[96:111], v[176:179], v[208:211], v[96:111]
	v_mfma_f32_32x32x16_bf16 v[112:127], v[180:183], v[208:211], v[112:127]
	s_waitcnt lgkmcnt(0)
	v_mfma_f32_32x32x16_bf16 v[64:79], v[176:179], v[212:215], v[64:79]
	v_mfma_f32_32x32x16_bf16 v[80:95], v[180:183], v[212:215], v[80:95]
	ds_read_b128 v[208:211], v149 offset:9248
	ds_read_b128 v[212:215], v149 offset:13856
	s_waitcnt vmcnt(7)
	ds_write_b128 v148, v[168:171] offset:18432
	s_waitcnt vmcnt(6)
	ds_write_b128 v148, v[172:175] offset:55296
	ds_read_b128 v[168:171], v150 offset:64
	ds_read_b128 v[172:175], v150 offset:4672
	s_waitcnt lgkmcnt(5)
	v_mfma_f32_32x32x16_bf16 v[32:47], v[176:179], v[208:211], v[32:47]
	v_mfma_f32_32x32x16_bf16 v[48:63], v[180:183], v[208:211], v[48:63]
	ds_read_b128 v[208:211], v149 offset:64
	s_waitcnt lgkmcnt(5)
	v_mfma_f32_32x32x16_bf16 v[0:15], v[176:179], v[212:215], v[0:15]
	v_mfma_f32_32x32x16_bf16 v[16:31], v[180:183], v[212:215], v[16:31]
	ds_read_b128 v[212:215], v149 offset:4672
	s_setprio 0
	global_load_dwordx4 v[176:179], v[132:133], off offset:896
	global_load_dwordx4 v[180:183], v[134:135], off offset:896
	s_setprio 1
	s_waitcnt lgkmcnt(1)
	v_mfma_f32_32x32x16_bf16 v[96:111], v[168:171], v[208:211], v[96:111]
	v_mfma_f32_32x32x16_bf16 v[112:127], v[172:175], v[208:211], v[112:127]
	s_waitcnt lgkmcnt(0)
	v_mfma_f32_32x32x16_bf16 v[64:79], v[168:171], v[212:215], v[64:79]
	v_mfma_f32_32x32x16_bf16 v[80:95], v[172:175], v[212:215], v[80:95]
	ds_read_b128 v[208:211], v149 offset:9280
	ds_read_b128 v[212:215], v149 offset:13888
	s_waitcnt vmcnt(7)
	ds_write_b128 v148, v[160:163] offset:27648
	s_waitcnt vmcnt(6)
	ds_write_b128 v148, v[164:167] offset:64512
	ds_read_b128 v[160:163], v150 offset:96
	ds_read_b128 v[164:167], v150 offset:4704
	s_waitcnt lgkmcnt(5)
	v_mfma_f32_32x32x16_bf16 v[32:47], v[168:171], v[208:211], v[32:47]
	v_mfma_f32_32x32x16_bf16 v[48:63], v[172:175], v[208:211], v[48:63]
	ds_read_b128 v[208:211], v149 offset:96
	s_waitcnt lgkmcnt(5)
	v_mfma_f32_32x32x16_bf16 v[0:15], v[168:171], v[212:215], v[0:15]
	v_mfma_f32_32x32x16_bf16 v[16:31], v[172:175], v[212:215], v[16:31]
	ds_read_b128 v[212:215], v149 offset:4704
	s_setprio 0
	global_load_dwordx4 v[168:171], v[144:145], off offset:896
	global_load_dwordx4 v[172:175], v[146:147], off offset:896
	s_setprio 1
	s_waitcnt lgkmcnt(1)
	v_mfma_f32_32x32x16_bf16 v[96:111], v[160:163], v[208:211], v[96:111]
	v_mfma_f32_32x32x16_bf16 v[112:127], v[164:167], v[208:211], v[112:127]
	s_waitcnt lgkmcnt(0)
	v_mfma_f32_32x32x16_bf16 v[64:79], v[160:163], v[212:215], v[64:79]
	v_mfma_f32_32x32x16_bf16 v[80:95], v[164:167], v[212:215], v[80:95]
	ds_read_b128 v[208:211], v149 offset:9312
	ds_read_b128 v[212:215], v149 offset:13920
	s_waitcnt lgkmcnt(0)
	s_barrier
; template <bool trans>
; DI void gemm_core(const GTile& tl, const GTile& nx, bool has_next  , bool chain  , bool pre, u32x4 (&ra)[4], u32x4 (&rb)[4], char* smem, f32x16 (&acc)[2][4]) {
;     ...
;   const int nk = K / 64;
;   if (!pre) { G_LOAD(0); G_STORE(0); G_LOAD(1); }
;   for (int kt = 0; kt < nk; ++kt) {
;     __syncthreads();
;     G_COMPUTE(kt & 1, kt);
;   }
	s_waitcnt vmcnt(7)
	ds_write_b128 v192, v[184:187]
	s_waitcnt vmcnt(6)
	ds_write_b128 v159, v[188:191]
	ds_read_b128 v[184:187], v152 offset:36864
	ds_read_b128 v[188:191], v152 offset:41472
	v_mfma_f32_32x32x16_bf16 v[32:47], v[160:163], v[208:211], v[32:47]
	v_mfma_f32_32x32x16_bf16 v[48:63], v[164:167], v[208:211], v[48:63]
	ds_read_b128 v[208:211], v151
	v_mfma_f32_32x32x16_bf16 v[0:15], v[160:163], v[212:215], v[0:15]
	v_mfma_f32_32x32x16_bf16 v[16:31], v[164:167], v[212:215], v[16:31]
	ds_read_b128 v[212:215], v151 offset:4608
	s_setprio 0
	global_load_dwordx4 v[160:163], v[136:137], off offset:1024
	global_load_dwordx4 v[164:167], v[138:139], off offset:1024
	s_setprio 1
	s_waitcnt lgkmcnt(1)
	v_mfma_f32_32x32x16_bf16 v[96:111], v[184:187], v[208:211], v[96:111]
	v_mfma_f32_32x32x16_bf16 v[112:127], v[188:191], v[208:211], v[112:127]
	s_waitcnt lgkmcnt(0)
	v_mfma_f32_32x32x16_bf16 v[64:79], v[184:187], v[212:215], v[64:79]
	v_mfma_f32_32x32x16_bf16 v[80:95], v[188:191], v[212:215], v[80:95]
	ds_read_b128 v[208:211], v151 offset:9216
	ds_read_b128 v[212:215], v151 offset:13824
	s_waitcnt vmcnt(7)
	ds_write_b128 v158, v[194:197]
	s_waitcnt vmcnt(6)
	ds_write_b128 v157, v[198:201]
	ds_read_b128 v[194:197], v152 offset:36896
	ds_read_b128 v[198:201], v152 offset:41504
	s_waitcnt lgkmcnt(5)
	v_mfma_f32_32x32x16_bf16 v[32:47], v[184:187], v[208:211], v[32:47]
	v_mfma_f32_32x32x16_bf16 v[48:63], v[188:191], v[208:211], v[48:63]
	ds_read_b128 v[208:211], v151 offset:32
	s_waitcnt lgkmcnt(5)
	v_mfma_f32_32x32x16_bf16 v[0:15], v[184:187], v[212:215], v[0:15]
	v_mfma_f32_32x32x16_bf16 v[16:31], v[188:191], v[212:215], v[16:31]
	ds_read_b128 v[212:215], v151 offset:4640
	s_setprio 0
	global_load_dwordx4 v[184:187], v[140:141], off offset:1024
	global_load_dwordx4 v[188:191], v[142:143], off offset:1024
	s_setprio 1
	s_waitcnt lgkmcnt(1)
	v_mfma_f32_32x32x16_bf16 v[96:111], v[194:197], v[208:211], v[96:111]
	v_mfma_f32_32x32x16_bf16 v[112:127], v[198:201], v[208:211], v[112:127]
	s_waitcnt lgkmcnt(0)
	v_mfma_f32_32x32x16_bf16 v[64:79], v[194:197], v[212:215], v[64:79]
	v_mfma_f32_32x32x16_bf16 v[80:95], v[198:201], v[212:215], v[80:95]
	ds_read_b128 v[208:211], v151 offset:9248
	ds_read_b128 v[212:215], v151 offset:13856
	s_waitcnt vmcnt(7)
	ds_write_b128 v154, v[176:179]
	s_waitcnt vmcnt(6)
	ds_write_b128 v153, v[180:183]
	ds_read_b128 v[176:179], v152 offset:36928
	ds_read_b128 v[180:183], v152 offset:41536
	s_waitcnt lgkmcnt(5)
	v_mfma_f32_32x32x16_bf16 v[32:47], v[194:197], v[208:211], v[32:47]
	v_mfma_f32_32x32x16_bf16 v[48:63], v[198:201], v[208:211], v[48:63]
	ds_read_b128 v[208:211], v151 offset:64
	s_waitcnt lgkmcnt(5)
	v_mfma_f32_32x32x16_bf16 v[0:15], v[194:197], v[212:215], v[0:15]
	v_mfma_f32_32x32x16_bf16 v[16:31], v[198:201], v[212:215], v[16:31]
	ds_read_b128 v[212:215], v151 offset:4672
	s_setprio 0
	global_load_dwordx4 v[194:197], v[132:133], off offset:1024
	global_load_dwordx4 v[198:201], v[134:135], off offset:1024
	s_setprio 1
	s_waitcnt lgkmcnt(1)
	v_mfma_f32_32x32x16_bf16 v[96:111], v[176:179], v[208:211], v[96:111]
	v_mfma_f32_32x32x16_bf16 v[112:127], v[180:183], v[208:211], v[112:127]
	s_waitcnt lgkmcnt(0)
	v_mfma_f32_32x32x16_bf16 v[64:79], v[176:179], v[212:215], v[64:79]
	v_mfma_f32_32x32x16_bf16 v[80:95], v[180:183], v[212:215], v[80:95]
	ds_read_b128 v[208:211], v151 offset:9280
	ds_read_b128 v[212:215], v151 offset:13888
	s_waitcnt vmcnt(7)
	ds_write_b128 v156, v[168:171]
	s_waitcnt vmcnt(6)
	ds_write_b128 v155, v[172:175]
	ds_read_b128 v[168:171], v152 offset:36960
	ds_read_b128 v[172:175], v152 offset:41568
	s_waitcnt lgkmcnt(5)
	v_mfma_f32_32x32x16_bf16 v[32:47], v[176:179], v[208:211], v[32:47]
	v_mfma_f32_32x32x16_bf16 v[48:63], v[180:183], v[208:211], v[48:63]
	ds_read_b128 v[208:211], v151 offset:96
	s_waitcnt lgkmcnt(5)
	v_mfma_f32_32x32x16_bf16 v[0:15], v[176:179], v[212:215], v[0:15]
	v_mfma_f32_32x32x16_bf16 v[16:31], v[180:183], v[212:215], v[16:31]
	ds_read_b128 v[212:215], v151 offset:4704
	s_setprio 0
	global_load_dwordx4 v[176:179], v[144:145], off offset:1024
	global_load_dwordx4 v[180:183], v[146:147], off offset:1024
	s_setprio 1
	s_waitcnt lgkmcnt(1)
	v_mfma_f32_32x32x16_bf16 v[96:111], v[168:171], v[208:211], v[96:111]
	v_mfma_f32_32x32x16_bf16 v[112:127], v[172:175], v[208:211], v[112:127]
	s_waitcnt lgkmcnt(0)
	v_mfma_f32_32x32x16_bf16 v[64:79], v[168:171], v[212:215], v[64:79]
	v_mfma_f32_32x32x16_bf16 v[80:95], v[172:175], v[212:215], v[80:95]
	ds_read_b128 v[208:211], v151 offset:9312
	ds_read_b128 v[212:215], v151 offset:13920
	s_waitcnt lgkmcnt(0)
	s_barrier
; template <bool trans>
; DI void gemm_core(const GTile& tl, const GTile& nx, bool has_next  , bool chain  , bool pre, u32x4 (&ra)[4], u32x4 (&rb)[4], char* smem, f32x16 (&acc)[2][4]) {
;     ...
;   const int nk = K / 64;
;   if (!pre) { G_LOAD(0); G_STORE(0); G_LOAD(1); }
;   for (int kt = 0; kt < nk; ++kt) {
;     __syncthreads();
;     G_COMPUTE(kt & 1, kt);
;   }
	s_waitcnt vmcnt(7)
	ds_write_b128 v148, v[160:163]
	s_waitcnt vmcnt(6)
	ds_write_b128 v148, v[164:167] offset:36864
	ds_read_b128 v[160:163], v150
	ds_read_b128 v[164:167], v150 offset:4608
	v_mfma_f32_32x32x16_bf16 v[32:47], v[168:171], v[208:211], v[32:47]
	v_mfma_f32_32x32x16_bf16 v[48:63], v[172:175], v[208:211], v[48:63]
	ds_read_b128 v[208:211], v149
	v_mfma_f32_32x32x16_bf16 v[0:15], v[168:171], v[212:215], v[0:15]
	v_mfma_f32_32x32x16_bf16 v[16:31], v[172:175], v[212:215], v[16:31]
	ds_read_b128 v[212:215], v149 offset:4608
	s_setprio 0
	global_load_dwordx4 v[168:171], v[136:137], off offset:1152
	global_load_dwordx4 v[172:175], v[138:139], off offset:1152
	s_setprio 1
	s_waitcnt lgkmcnt(1)
	v_mfma_f32_32x32x16_bf16 v[96:111], v[160:163], v[208:211], v[96:111]
	v_mfma_f32_32x32x16_bf16 v[112:127], v[164:167], v[208:211], v[112:127]
	s_waitcnt lgkmcnt(0)
	v_mfma_f32_32x32x16_bf16 v[64:79], v[160:163], v[212:215], v[64:79]
	v_mfma_f32_32x32x16_bf16 v[80:95], v[164:167], v[212:215], v[80:95]
	ds_read_b128 v[208:211], v149 offset:9216
	ds_read_b128 v[212:215], v149 offset:13824
	s_waitcnt vmcnt(7)
	ds_write_b128 v148, v[184:187] offset:9216
	s_waitcnt vmcnt(6)
	ds_write_b128 v148, v[188:191] offset:46080
	ds_read_b128 v[184:187], v150 offset:32
	ds_read_b128 v[188:191], v150 offset:4640
	s_waitcnt lgkmcnt(5)
	v_mfma_f32_32x32x16_bf16 v[32:47], v[160:163], v[208:211], v[32:47]
	v_mfma_f32_32x32x16_bf16 v[48:63], v[164:167], v[208:211], v[48:63]
	ds_read_b128 v[208:211], v149 offset:32
	s_waitcnt lgkmcnt(5)
	v_mfma_f32_32x32x16_bf16 v[0:15], v[160:163], v[212:215], v[0:15]
	v_mfma_f32_32x32x16_bf16 v[16:31], v[164:167], v[212:215], v[16:31]
	ds_read_b128 v[212:215], v149 offset:4640
	s_setprio 0
	global_load_dwordx4 v[160:163], v[140:141], off offset:1152
	global_load_dwordx4 v[164:167], v[142:143], off offset:1152
	s_setprio 1
	s_waitcnt lgkmcnt(1)
	v_mfma_f32_32x32x16_bf16 v[96:111], v[184:187], v[208:211], v[96:111]
	v_mfma_f32_32x32x16_bf16 v[112:127], v[188:191], v[208:211], v[112:127]
	s_waitcnt lgkmcnt(0)
	v_mfma_f32_32x32x16_bf16 v[64:79], v[184:187], v[212:215], v[64:79]
	v_mfma_f32_32x32x16_bf16 v[80:95], v[188:191], v[212:215], v[80:95]
	ds_read_b128 v[208:211], v149 offset:9248
	ds_read_b128 v[212:215], v149 offset:13856
	s_waitcnt vmcnt(7)
	ds_write_b128 v148, v[194:197] offset:18432
	s_waitcnt vmcnt(6)
	ds_write_b128 v148, v[198:201] offset:55296
	ds_read_b128 v[194:197], v150 offset:64
	ds_read_b128 v[198:201], v150 offset:4672
	s_waitcnt lgkmcnt(5)
	v_mfma_f32_32x32x16_bf16 v[32:47], v[184:187], v[208:211], v[32:47]
	v_mfma_f32_32x32x16_bf16 v[48:63], v[188:191], v[208:211], v[48:63]
	ds_read_b128 v[208:211], v149 offset:64
	s_waitcnt lgkmcnt(5)
	v_mfma_f32_32x32x16_bf16 v[0:15], v[184:187], v[212:215], v[0:15]
	v_mfma_f32_32x32x16_bf16 v[16:31], v[188:191], v[212:215], v[16:31]
	ds_read_b128 v[212:215], v149 offset:4672
	s_setprio 0
	global_load_dwordx4 v[184:187], v[132:133], off offset:1152
	global_load_dwordx4 v[188:191], v[134:135], off offset:1152
	s_setprio 1
	s_waitcnt lgkmcnt(1)
	v_mfma_f32_32x32x16_bf16 v[96:111], v[194:197], v[208:211], v[96:111]
	v_mfma_f32_32x32x16_bf16 v[112:127], v[198:201], v[208:211], v[112:127]
	s_waitcnt lgkmcnt(0)
	v_mfma_f32_32x32x16_bf16 v[64:79], v[194:197], v[212:215], v[64:79]
	v_mfma_f32_32x32x16_bf16 v[80:95], v[198:201], v[212:215], v[80:95]
	ds_read_b128 v[208:211], v149 offset:9280
	ds_read_b128 v[212:215], v149 offset:13888
	s_waitcnt vmcnt(7)
	ds_write_b128 v148, v[176:179] offset:27648
	s_waitcnt vmcnt(6)
	ds_write_b128 v148, v[180:183] offset:64512
	ds_read_b128 v[176:179], v150 offset:96
	ds_read_b128 v[180:183], v150 offset:4704
	s_waitcnt lgkmcnt(5)
	v_mfma_f32_32x32x16_bf16 v[32:47], v[194:197], v[208:211], v[32:47]
	v_mfma_f32_32x32x16_bf16 v[48:63], v[198:201], v[208:211], v[48:63]
	ds_read_b128 v[208:211], v149 offset:96
	s_waitcnt lgkmcnt(5)
	v_mfma_f32_32x32x16_bf16 v[0:15], v[194:197], v[212:215], v[0:15]
	v_mfma_f32_32x32x16_bf16 v[16:31], v[198:201], v[212:215], v[16:31]
	ds_read_b128 v[212:215], v149 offset:4704
	s_setprio 0
	global_load_dwordx4 v[194:197], v[144:145], off offset:1152
	global_load_dwordx4 v[198:201], v[146:147], off offset:1152
	s_setprio 1
	s_waitcnt lgkmcnt(1)
	v_mfma_f32_32x32x16_bf16 v[96:111], v[176:179], v[208:211], v[96:111]
	v_mfma_f32_32x32x16_bf16 v[112:127], v[180:183], v[208:211], v[112:127]
	s_waitcnt lgkmcnt(0)
	v_mfma_f32_32x32x16_bf16 v[64:79], v[176:179], v[212:215], v[64:79]
	v_mfma_f32_32x32x16_bf16 v[80:95], v[180:183], v[212:215], v[80:95]
	ds_read_b128 v[208:211], v149 offset:9312
	ds_read_b128 v[212:215], v149 offset:13920
	s_waitcnt lgkmcnt(0)
	s_barrier
; template <bool trans>
; DI void gemm_core(const GTile& tl, const GTile& nx, bool has_next  , bool chain  , bool pre, u32x4 (&ra)[4], u32x4 (&rb)[4], char* smem, f32x16 (&acc)[2][4]) {
;     ...
;   const int nk = K / 64;
;   if (!pre) { G_LOAD(0); G_STORE(0); G_LOAD(1); }
;   for (int kt = 0; kt < nk; ++kt) {
;     __syncthreads();
;     G_COMPUTE(kt & 1, kt);
;   }
	s_waitcnt vmcnt(7)
	ds_write_b128 v192, v[168:171]
	s_waitcnt vmcnt(6)
	ds_write_b128 v159, v[172:175]
	ds_read_b128 v[168:171], v152 offset:36864
	ds_read_b128 v[172:175], v152 offset:41472
	v_mfma_f32_32x32x16_bf16 v[32:47], v[176:179], v[208:211], v[32:47]
	v_mfma_f32_32x32x16_bf16 v[48:63], v[180:183], v[208:211], v[48:63]
	ds_read_b128 v[208:211], v151
	v_mfma_f32_32x32x16_bf16 v[0:15], v[176:179], v[212:215], v[0:15]
	v_mfma_f32_32x32x16_bf16 v[16:31], v[180:183], v[212:215], v[16:31]
	ds_read_b128 v[212:215], v151 offset:4608
	s_setprio 0
	global_load_dwordx4 v[176:179], v[136:137], off offset:1280
	global_load_dwordx4 v[180:183], v[138:139], off offset:1280
	s_setprio 1
	s_waitcnt lgkmcnt(1)
	v_mfma_f32_32x32x16_bf16 v[96:111], v[168:171], v[208:211], v[96:111]
	v_mfma_f32_32x32x16_bf16 v[112:127], v[172:175], v[208:211], v[112:127]
	s_waitcnt lgkmcnt(0)
	v_mfma_f32_32x32x16_bf16 v[64:79], v[168:171], v[212:215], v[64:79]
	v_mfma_f32_32x32x16_bf16 v[80:95], v[172:175], v[212:215], v[80:95]
	ds_read_b128 v[208:211], v151 offset:9216
	ds_read_b128 v[212:215], v151 offset:13824
	s_waitcnt vmcnt(7)
	ds_write_b128 v158, v[160:163]
	s_waitcnt vmcnt(6)
	ds_write_b128 v157, v[164:167]
	ds_read_b128 v[160:163], v152 offset:36896
	ds_read_b128 v[164:167], v152 offset:41504
	s_waitcnt lgkmcnt(5)
	v_mfma_f32_32x32x16_bf16 v[32:47], v[168:171], v[208:211], v[32:47]
	v_mfma_f32_32x32x16_bf16 v[48:63], v[172:175], v[208:211], v[48:63]
	ds_read_b128 v[208:211], v151 offset:32
	s_waitcnt lgkmcnt(5)
	v_mfma_f32_32x32x16_bf16 v[0:15], v[168:171], v[212:215], v[0:15]
	v_mfma_f32_32x32x16_bf16 v[16:31], v[172:175], v[212:215], v[16:31]
	ds_read_b128 v[212:215], v151 offset:4640
	s_setprio 0
	global_load_dwordx4 v[168:171], v[140:141], off offset:1280
	global_load_dwordx4 v[172:175], v[142:143], off offset:1280
	s_setprio 1
	s_waitcnt lgkmcnt(1)
	v_mfma_f32_32x32x16_bf16 v[96:111], v[160:163], v[208:211], v[96:111]
	v_mfma_f32_32x32x16_bf16 v[112:127], v[164:167], v[208:211], v[112:127]
	s_waitcnt lgkmcnt(0)
	v_mfma_f32_32x32x16_bf16 v[64:79], v[160:163], v[212:215], v[64:79]
	v_mfma_f32_32x32x16_bf16 v[80:95], v[164:167], v[212:215], v[80:95]
	ds_read_b128 v[208:211], v151 offset:9248
	ds_read_b128 v[212:215], v151 offset:13856
	s_waitcnt vmcnt(7)
	ds_write_b128 v154, v[184:187]
	s_waitcnt vmcnt(6)
	ds_write_b128 v153, v[188:191]
	ds_read_b128 v[184:187], v152 offset:36928
	ds_read_b128 v[188:191], v152 offset:41536
	s_waitcnt lgkmcnt(5)
	v_mfma_f32_32x32x16_bf16 v[32:47], v[160:163], v[208:211], v[32:47]
	v_mfma_f32_32x32x16_bf16 v[48:63], v[164:167], v[208:211], v[48:63]
	ds_read_b128 v[208:211], v151 offset:64
	s_waitcnt lgkmcnt(5)
	v_mfma_f32_32x32x16_bf16 v[0:15], v[160:163], v[212:215], v[0:15]
	v_mfma_f32_32x32x16_bf16 v[16:31], v[164:167], v[212:215], v[16:31]
	ds_read_b128 v[212:215], v151 offset:4672
	s_setprio 0
	global_load_dwordx4 v[160:163], v[132:133], off offset:1280
	global_load_dwordx4 v[164:167], v[134:135], off offset:1280
	s_setprio 1
	s_waitcnt lgkmcnt(1)
	v_mfma_f32_32x32x16_bf16 v[96:111], v[184:187], v[208:211], v[96:111]
	v_mfma_f32_32x32x16_bf16 v[112:127], v[188:191], v[208:211], v[112:127]
	s_waitcnt lgkmcnt(0)
	v_mfma_f32_32x32x16_bf16 v[64:79], v[184:187], v[212:215], v[64:79]
	v_mfma_f32_32x32x16_bf16 v[80:95], v[188:191], v[212:215], v[80:95]
	ds_read_b128 v[208:211], v151 offset:9280
	ds_read_b128 v[212:215], v151 offset:13888
	s_waitcnt vmcnt(7)
	ds_write_b128 v156, v[194:197]
	s_waitcnt vmcnt(6)
	ds_write_b128 v155, v[198:201]
	ds_read_b128 v[194:197], v152 offset:36960
	ds_read_b128 v[198:201], v152 offset:41568
	s_waitcnt lgkmcnt(5)
	v_mfma_f32_32x32x16_bf16 v[32:47], v[184:187], v[208:211], v[32:47]
	v_mfma_f32_32x32x16_bf16 v[48:63], v[188:191], v[208:211], v[48:63]
	ds_read_b128 v[208:211], v151 offset:96
	s_waitcnt lgkmcnt(5)
	v_mfma_f32_32x32x16_bf16 v[0:15], v[184:187], v[212:215], v[0:15]
	v_mfma_f32_32x32x16_bf16 v[16:31], v[188:191], v[212:215], v[16:31]
	ds_read_b128 v[212:215], v151 offset:4704
	s_setprio 0
	global_load_dwordx4 v[184:187], v[144:145], off offset:1280
	global_load_dwordx4 v[188:191], v[146:147], off offset:1280
	s_setprio 1
	s_waitcnt lgkmcnt(1)
	v_mfma_f32_32x32x16_bf16 v[96:111], v[194:197], v[208:211], v[96:111]
	v_mfma_f32_32x32x16_bf16 v[112:127], v[198:201], v[208:211], v[112:127]
	s_waitcnt lgkmcnt(0)
	v_mfma_f32_32x32x16_bf16 v[64:79], v[194:197], v[212:215], v[64:79]
	v_mfma_f32_32x32x16_bf16 v[80:95], v[198:201], v[212:215], v[80:95]
	ds_read_b128 v[208:211], v151 offset:9312
	ds_read_b128 v[212:215], v151 offset:13920
	s_waitcnt lgkmcnt(0)
	s_barrier
; template <bool trans>
; DI void gemm_core(const GTile& tl, const GTile& nx, bool has_next  , bool chain  , bool pre, u32x4 (&ra)[4], u32x4 (&rb)[4], char* smem, f32x16 (&acc)[2][4]) {
;     ...
;   const int nk = K / 64;
;   if (!pre) { G_LOAD(0); G_STORE(0); G_LOAD(1); }
;   for (int kt = 0; kt < nk; ++kt) {
;     __syncthreads();
;     G_COMPUTE(kt & 1, kt);
;   }
	s_waitcnt vmcnt(7)
	ds_write_b128 v148, v[176:179]
	s_waitcnt vmcnt(6)
	ds_write_b128 v148, v[180:183] offset:36864
	ds_read_b128 v[176:179], v150
	ds_read_b128 v[180:183], v150 offset:4608
	v_mfma_f32_32x32x16_bf16 v[32:47], v[194:197], v[208:211], v[32:47]
	v_mfma_f32_32x32x16_bf16 v[48:63], v[198:201], v[208:211], v[48:63]
	ds_read_b128 v[208:211], v149
	v_mfma_f32_32x32x16_bf16 v[0:15], v[194:197], v[212:215], v[0:15]
	v_mfma_f32_32x32x16_bf16 v[16:31], v[198:201], v[212:215], v[16:31]
	ds_read_b128 v[212:215], v149 offset:4608
	s_setprio 0
	global_load_dwordx4 v[194:197], v[136:137], off offset:1408
	global_load_dwordx4 v[198:201], v[138:139], off offset:1408
	s_setprio 1
	s_waitcnt lgkmcnt(1)
	v_mfma_f32_32x32x16_bf16 v[96:111], v[176:179], v[208:211], v[96:111]
	v_mfma_f32_32x32x16_bf16 v[112:127], v[180:183], v[208:211], v[112:127]
	s_waitcnt lgkmcnt(0)
	v_mfma_f32_32x32x16_bf16 v[64:79], v[176:179], v[212:215], v[64:79]
	v_mfma_f32_32x32x16_bf16 v[80:95], v[180:183], v[212:215], v[80:95]
	ds_read_b128 v[208:211], v149 offset:9216
	ds_read_b128 v[212:215], v149 offset:13824
	s_waitcnt vmcnt(7)
	ds_write_b128 v148, v[168:171] offset:9216
	s_waitcnt vmcnt(6)
	ds_write_b128 v148, v[172:175] offset:46080
	ds_read_b128 v[168:171], v150 offset:32
	ds_read_b128 v[172:175], v150 offset:4640
	s_waitcnt lgkmcnt(5)
	v_mfma_f32_32x32x16_bf16 v[32:47], v[176:179], v[208:211], v[32:47]
	v_mfma_f32_32x32x16_bf16 v[48:63], v[180:183], v[208:211], v[48:63]
	ds_read_b128 v[208:211], v149 offset:32
	s_waitcnt lgkmcnt(5)
	v_mfma_f32_32x32x16_bf16 v[0:15], v[176:179], v[212:215], v[0:15]
	v_mfma_f32_32x32x16_bf16 v[16:31], v[180:183], v[212:215], v[16:31]
	ds_read_b128 v[212:215], v149 offset:4640
	s_setprio 0
	global_load_dwordx4 v[176:179], v[140:141], off offset:1408
	global_load_dwordx4 v[180:183], v[142:143], off offset:1408
	s_setprio 1
	s_waitcnt lgkmcnt(1)
	v_mfma_f32_32x32x16_bf16 v[96:111], v[168:171], v[208:211], v[96:111]
	v_mfma_f32_32x32x16_bf16 v[112:127], v[172:175], v[208:211], v[112:127]
	s_waitcnt lgkmcnt(0)
	v_mfma_f32_32x32x16_bf16 v[64:79], v[168:171], v[212:215], v[64:79]
	v_mfma_f32_32x32x16_bf16 v[80:95], v[172:175], v[212:215], v[80:95]
	ds_read_b128 v[208:211], v149 offset:9248
	ds_read_b128 v[212:215], v149 offset:13856
	s_waitcnt vmcnt(7)
	ds_write_b128 v148, v[160:163] offset:18432
	s_waitcnt vmcnt(6)
	ds_write_b128 v148, v[164:167] offset:55296
	ds_read_b128 v[160:163], v150 offset:64
	ds_read_b128 v[164:167], v150 offset:4672
	s_waitcnt lgkmcnt(5)
	v_mfma_f32_32x32x16_bf16 v[32:47], v[168:171], v[208:211], v[32:47]
	v_mfma_f32_32x32x16_bf16 v[48:63], v[172:175], v[208:211], v[48:63]
	ds_read_b128 v[208:211], v149 offset:64
	s_waitcnt lgkmcnt(5)
	v_mfma_f32_32x32x16_bf16 v[0:15], v[168:171], v[212:215], v[0:15]
	v_mfma_f32_32x32x16_bf16 v[16:31], v[172:175], v[212:215], v[16:31]
	ds_read_b128 v[212:215], v149 offset:4672
	s_setprio 0
	global_load_dwordx4 v[168:171], v[132:133], off offset:1408
	global_load_dwordx4 v[172:175], v[134:135], off offset:1408
	s_setprio 1
	s_waitcnt lgkmcnt(1)
	v_mfma_f32_32x32x16_bf16 v[96:111], v[160:163], v[208:211], v[96:111]
	v_mfma_f32_32x32x16_bf16 v[112:127], v[164:167], v[208:211], v[112:127]
	s_waitcnt lgkmcnt(0)
	v_mfma_f32_32x32x16_bf16 v[64:79], v[160:163], v[212:215], v[64:79]
	v_mfma_f32_32x32x16_bf16 v[80:95], v[164:167], v[212:215], v[80:95]
	ds_read_b128 v[208:211], v149 offset:9280
	ds_read_b128 v[212:215], v149 offset:13888
	s_waitcnt vmcnt(7)
	ds_write_b128 v148, v[184:187] offset:27648
	s_waitcnt vmcnt(6)
	ds_write_b128 v148, v[188:191] offset:64512
	ds_read_b128 v[184:187], v150 offset:96
	ds_read_b128 v[188:191], v150 offset:4704
	s_waitcnt lgkmcnt(5)
	v_mfma_f32_32x32x16_bf16 v[32:47], v[160:163], v[208:211], v[32:47]
	v_mfma_f32_32x32x16_bf16 v[48:63], v[164:167], v[208:211], v[48:63]
	ds_read_b128 v[208:211], v149 offset:96
	s_waitcnt lgkmcnt(5)
	v_mfma_f32_32x32x16_bf16 v[0:15], v[160:163], v[212:215], v[0:15]
	v_mfma_f32_32x32x16_bf16 v[16:31], v[164:167], v[212:215], v[16:31]
	ds_read_b128 v[212:215], v149 offset:4704
	s_setprio 0
	global_load_dwordx4 v[160:163], v[144:145], off offset:1408
	global_load_dwordx4 v[164:167], v[146:147], off offset:1408
	s_setprio 1
	s_waitcnt lgkmcnt(1)
	v_mfma_f32_32x32x16_bf16 v[96:111], v[184:187], v[208:211], v[96:111]
	v_mfma_f32_32x32x16_bf16 v[112:127], v[188:191], v[208:211], v[112:127]
	s_waitcnt lgkmcnt(0)
	v_mfma_f32_32x32x16_bf16 v[64:79], v[184:187], v[212:215], v[64:79]
	v_mfma_f32_32x32x16_bf16 v[80:95], v[188:191], v[212:215], v[80:95]
	ds_read_b128 v[208:211], v149 offset:9312
	ds_read_b128 v[212:215], v149 offset:13920
	s_waitcnt lgkmcnt(0)
	s_barrier
; template <bool trans>
; DI void gemm_core(const GTile& tl, const GTile& nx, bool has_next  , bool chain  , bool pre, u32x4 (&ra)[4], u32x4 (&rb)[4], char* smem, f32x16 (&acc)[2][4]) {
;     ...
;   const int nk = K / 64;
;   if (!pre) { G_LOAD(0); G_STORE(0); G_LOAD(1); }
;   for (int kt = 0; kt < nk; ++kt) {
;     __syncthreads();
;     G_COMPUTE(kt & 1, kt);
;   }
	s_waitcnt vmcnt(7)
	ds_write_b128 v192, v[194:197]
	s_waitcnt vmcnt(6)
	ds_write_b128 v159, v[198:201]
	ds_read_b128 v[194:197], v152 offset:36864
	ds_read_b128 v[198:201], v152 offset:41472
	v_mfma_f32_32x32x16_bf16 v[32:47], v[184:187], v[208:211], v[32:47]
	v_mfma_f32_32x32x16_bf16 v[48:63], v[188:191], v[208:211], v[48:63]
	ds_read_b128 v[208:211], v151
	v_mfma_f32_32x32x16_bf16 v[0:15], v[184:187], v[212:215], v[0:15]
	v_mfma_f32_32x32x16_bf16 v[16:31], v[188:191], v[212:215], v[16:31]
	ds_read_b128 v[212:215], v151 offset:4608
	s_setprio 0
	global_load_dwordx4 v[184:187], v[136:137], off offset:1536
	global_load_dwordx4 v[188:191], v[138:139], off offset:1536
	s_setprio 1
	s_waitcnt lgkmcnt(1)
	v_mfma_f32_32x32x16_bf16 v[96:111], v[194:197], v[208:211], v[96:111]
	v_mfma_f32_32x32x16_bf16 v[112:127], v[198:201], v[208:211], v[112:127]
	s_waitcnt lgkmcnt(0)
	v_mfma_f32_32x32x16_bf16 v[64:79], v[194:197], v[212:215], v[64:79]
	v_mfma_f32_32x32x16_bf16 v[80:95], v[198:201], v[212:215], v[80:95]
	ds_read_b128 v[208:211], v151 offset:9216
	ds_read_b128 v[212:215], v151 offset:13824
	s_waitcnt vmcnt(7)
	ds_write_b128 v158, v[176:179]
	s_waitcnt vmcnt(6)
	ds_write_b128 v157, v[180:183]
	ds_read_b128 v[176:179], v152 offset:36896
	ds_read_b128 v[180:183], v152 offset:41504
	s_waitcnt lgkmcnt(5)
	v_mfma_f32_32x32x16_bf16 v[32:47], v[194:197], v[208:211], v[32:47]
	v_mfma_f32_32x32x16_bf16 v[48:63], v[198:201], v[208:211], v[48:63]
	ds_read_b128 v[208:211], v151 offset:32
	s_waitcnt lgkmcnt(5)
	v_mfma_f32_32x32x16_bf16 v[0:15], v[194:197], v[212:215], v[0:15]
	v_mfma_f32_32x32x16_bf16 v[16:31], v[198:201], v[212:215], v[16:31]
	ds_read_b128 v[212:215], v151 offset:4640
	s_setprio 0
	global_load_dwordx4 v[194:197], v[140:141], off offset:1536
	global_load_dwordx4 v[198:201], v[142:143], off offset:1536
	s_setprio 1
	s_waitcnt lgkmcnt(1)
	v_mfma_f32_32x32x16_bf16 v[96:111], v[176:179], v[208:211], v[96:111]
	v_mfma_f32_32x32x16_bf16 v[112:127], v[180:183], v[208:211], v[112:127]
	s_waitcnt lgkmcnt(0)
	v_mfma_f32_32x32x16_bf16 v[64:79], v[176:179], v[212:215], v[64:79]
	v_mfma_f32_32x32x16_bf16 v[80:95], v[180:183], v[212:215], v[80:95]
	ds_read_b128 v[208:211], v151 offset:9248
	ds_read_b128 v[212:215], v151 offset:13856
	s_waitcnt vmcnt(7)
	ds_write_b128 v154, v[168:171]
	s_waitcnt vmcnt(6)
	ds_write_b128 v153, v[172:175]
	ds_read_b128 v[168:171], v152 offset:36928
	ds_read_b128 v[172:175], v152 offset:41536
	s_waitcnt lgkmcnt(5)
	v_mfma_f32_32x32x16_bf16 v[32:47], v[176:179], v[208:211], v[32:47]
	v_mfma_f32_32x32x16_bf16 v[48:63], v[180:183], v[208:211], v[48:63]
	ds_read_b128 v[208:211], v151 offset:64
	s_waitcnt lgkmcnt(5)
	v_mfma_f32_32x32x16_bf16 v[0:15], v[176:179], v[212:215], v[0:15]
	v_mfma_f32_32x32x16_bf16 v[16:31], v[180:183], v[212:215], v[16:31]
	ds_read_b128 v[212:215], v151 offset:4672
	s_setprio 0
	global_load_dwordx4 v[176:179], v[132:133], off offset:1536
	global_load_dwordx4 v[180:183], v[134:135], off offset:1536
	s_setprio 1
	s_waitcnt lgkmcnt(1)
	v_mfma_f32_32x32x16_bf16 v[96:111], v[168:171], v[208:211], v[96:111]
	v_mfma_f32_32x32x16_bf16 v[112:127], v[172:175], v[208:211], v[112:127]
	s_waitcnt lgkmcnt(0)
	v_mfma_f32_32x32x16_bf16 v[64:79], v[168:171], v[212:215], v[64:79]
	v_mfma_f32_32x32x16_bf16 v[80:95], v[172:175], v[212:215], v[80:95]
	ds_read_b128 v[208:211], v151 offset:9280
	ds_read_b128 v[212:215], v151 offset:13888
	s_waitcnt vmcnt(7)
	ds_write_b128 v156, v[160:163]
	s_waitcnt vmcnt(6)
	ds_write_b128 v155, v[164:167]
	ds_read_b128 v[160:163], v152 offset:36960
	ds_read_b128 v[164:167], v152 offset:41568
	s_waitcnt lgkmcnt(5)
	v_mfma_f32_32x32x16_bf16 v[32:47], v[168:171], v[208:211], v[32:47]
	v_mfma_f32_32x32x16_bf16 v[48:63], v[172:175], v[208:211], v[48:63]
	ds_read_b128 v[208:211], v151 offset:96
	s_waitcnt lgkmcnt(5)
	v_mfma_f32_32x32x16_bf16 v[0:15], v[168:171], v[212:215], v[0:15]
	v_mfma_f32_32x32x16_bf16 v[16:31], v[172:175], v[212:215], v[16:31]
	ds_read_b128 v[212:215], v151 offset:4704
	s_setprio 0
	global_load_dwordx4 v[168:171], v[144:145], off offset:1536
	global_load_dwordx4 v[172:175], v[146:147], off offset:1536
	s_setprio 1
	s_waitcnt lgkmcnt(1)
	v_mfma_f32_32x32x16_bf16 v[96:111], v[160:163], v[208:211], v[96:111]
	v_mfma_f32_32x32x16_bf16 v[112:127], v[164:167], v[208:211], v[112:127]
	s_waitcnt lgkmcnt(0)
	v_mfma_f32_32x32x16_bf16 v[64:79], v[160:163], v[212:215], v[64:79]
	v_mfma_f32_32x32x16_bf16 v[80:95], v[164:167], v[212:215], v[80:95]
	ds_read_b128 v[208:211], v151 offset:9312
	ds_read_b128 v[212:215], v151 offset:13920
	s_waitcnt lgkmcnt(0)
	s_barrier
; template <bool trans>
; DI void gemm_core(const GTile& tl, const GTile& nx, bool has_next  , bool chain  , bool pre, u32x4 (&ra)[4], u32x4 (&rb)[4], char* smem, f32x16 (&acc)[2][4]) {
;     ...
;   const int nk = K / 64;
;   if (!pre) { G_LOAD(0); G_STORE(0); G_LOAD(1); }
;   for (int kt = 0; kt < nk; ++kt) {
;     __syncthreads();
;     G_COMPUTE(kt & 1, kt);
;   }
	s_waitcnt vmcnt(7)
	ds_write_b128 v148, v[184:187]
	s_waitcnt vmcnt(6)
	ds_write_b128 v148, v[188:191] offset:36864
	ds_read_b128 v[184:187], v150
	ds_read_b128 v[188:191], v150 offset:4608
	v_mfma_f32_32x32x16_bf16 v[32:47], v[160:163], v[208:211], v[32:47]
	v_mfma_f32_32x32x16_bf16 v[48:63], v[164:167], v[208:211], v[48:63]
	ds_read_b128 v[208:211], v149
	v_mfma_f32_32x32x16_bf16 v[0:15], v[160:163], v[212:215], v[0:15]
	v_mfma_f32_32x32x16_bf16 v[16:31], v[164:167], v[212:215], v[16:31]
	ds_read_b128 v[212:215], v149 offset:4608
	s_setprio 0
	global_load_dwordx4 v[160:163], v[136:137], off offset:1664
	global_load_dwordx4 v[164:167], v[138:139], off offset:1664
	s_setprio 1
	s_waitcnt lgkmcnt(1)
	v_mfma_f32_32x32x16_bf16 v[96:111], v[184:187], v[208:211], v[96:111]
	v_mfma_f32_32x32x16_bf16 v[112:127], v[188:191], v[208:211], v[112:127]
	s_waitcnt lgkmcnt(0)
	v_mfma_f32_32x32x16_bf16 v[64:79], v[184:187], v[212:215], v[64:79]
	v_mfma_f32_32x32x16_bf16 v[80:95], v[188:191], v[212:215], v[80:95]
	ds_read_b128 v[208:211], v149 offset:9216
	ds_read_b128 v[212:215], v149 offset:13824
	s_waitcnt vmcnt(7)
	ds_write_b128 v148, v[194:197] offset:9216
	s_waitcnt vmcnt(6)
	ds_write_b128 v148, v[198:201] offset:46080
	ds_read_b128 v[194:197], v150 offset:32
	ds_read_b128 v[198:201], v150 offset:4640
	s_waitcnt lgkmcnt(5)
	v_mfma_f32_32x32x16_bf16 v[32:47], v[184:187], v[208:211], v[32:47]
	v_mfma_f32_32x32x16_bf16 v[48:63], v[188:191], v[208:211], v[48:63]
	ds_read_b128 v[208:211], v149 offset:32
	s_waitcnt lgkmcnt(5)
	v_mfma_f32_32x32x16_bf16 v[0:15], v[184:187], v[212:215], v[0:15]
	v_mfma_f32_32x32x16_bf16 v[16:31], v[188:191], v[212:215], v[16:31]
	ds_read_b128 v[212:215], v149 offset:4640
	s_setprio 0
	global_load_dwordx4 v[184:187], v[140:141], off offset:1664
	global_load_dwordx4 v[188:191], v[142:143], off offset:1664
	s_setprio 1
	s_waitcnt lgkmcnt(1)
	v_mfma_f32_32x32x16_bf16 v[96:111], v[194:197], v[208:211], v[96:111]
	v_mfma_f32_32x32x16_bf16 v[112:127], v[198:201], v[208:211], v[112:127]
	s_waitcnt lgkmcnt(0)
	v_mfma_f32_32x32x16_bf16 v[64:79], v[194:197], v[212:215], v[64:79]
	v_mfma_f32_32x32x16_bf16 v[80:95], v[198:201], v[212:215], v[80:95]
	ds_read_b128 v[208:211], v149 offset:9248
	ds_read_b128 v[212:215], v149 offset:13856
	s_waitcnt vmcnt(7)
	ds_write_b128 v148, v[176:179] offset:18432
	s_waitcnt vmcnt(6)
	ds_write_b128 v148, v[180:183] offset:55296
	ds_read_b128 v[176:179], v150 offset:64
	ds_read_b128 v[180:183], v150 offset:4672
	s_waitcnt lgkmcnt(5)
	v_mfma_f32_32x32x16_bf16 v[32:47], v[194:197], v[208:211], v[32:47]
	v_mfma_f32_32x32x16_bf16 v[48:63], v[198:201], v[208:211], v[48:63]
	ds_read_b128 v[208:211], v149 offset:64
	s_waitcnt lgkmcnt(5)
	v_mfma_f32_32x32x16_bf16 v[0:15], v[194:197], v[212:215], v[0:15]
	v_mfma_f32_32x32x16_bf16 v[16:31], v[198:201], v[212:215], v[16:31]
	ds_read_b128 v[212:215], v149 offset:4672
	s_setprio 0
	global_load_dwordx4 v[194:197], v[132:133], off offset:1664
	global_load_dwordx4 v[198:201], v[134:135], off offset:1664
	s_setprio 1
	s_waitcnt lgkmcnt(1)
	v_mfma_f32_32x32x16_bf16 v[96:111], v[176:179], v[208:211], v[96:111]
	v_mfma_f32_32x32x16_bf16 v[112:127], v[180:183], v[208:211], v[112:127]
	s_waitcnt lgkmcnt(0)
	v_mfma_f32_32x32x16_bf16 v[64:79], v[176:179], v[212:215], v[64:79]
	v_mfma_f32_32x32x16_bf16 v[80:95], v[180:183], v[212:215], v[80:95]
	ds_read_b128 v[208:211], v149 offset:9280
	ds_read_b128 v[212:215], v149 offset:13888
	s_waitcnt vmcnt(7)
	ds_write_b128 v148, v[168:171] offset:27648
	s_waitcnt vmcnt(6)
	ds_write_b128 v148, v[172:175] offset:64512
	ds_read_b128 v[168:171], v150 offset:96
	ds_read_b128 v[172:175], v150 offset:4704
	s_waitcnt lgkmcnt(5)
	v_mfma_f32_32x32x16_bf16 v[32:47], v[176:179], v[208:211], v[32:47]
	v_mfma_f32_32x32x16_bf16 v[48:63], v[180:183], v[208:211], v[48:63]
	ds_read_b128 v[208:211], v149 offset:96
	s_waitcnt lgkmcnt(5)
	v_mfma_f32_32x32x16_bf16 v[0:15], v[176:179], v[212:215], v[0:15]
	v_mfma_f32_32x32x16_bf16 v[16:31], v[180:183], v[212:215], v[16:31]
	ds_read_b128 v[212:215], v149 offset:4704
	s_setprio 0
	global_load_dwordx4 v[176:179], v[144:145], off offset:1664
	global_load_dwordx4 v[180:183], v[146:147], off offset:1664
	s_setprio 1
	s_waitcnt lgkmcnt(1)
	v_mfma_f32_32x32x16_bf16 v[96:111], v[168:171], v[208:211], v[96:111]
	v_mfma_f32_32x32x16_bf16 v[112:127], v[172:175], v[208:211], v[112:127]
	s_waitcnt lgkmcnt(0)
	v_mfma_f32_32x32x16_bf16 v[64:79], v[168:171], v[212:215], v[64:79]
	v_mfma_f32_32x32x16_bf16 v[80:95], v[172:175], v[212:215], v[80:95]
	ds_read_b128 v[208:211], v149 offset:9312
	ds_read_b128 v[212:215], v149 offset:13920
	s_waitcnt lgkmcnt(0)
	s_barrier
; template <bool trans>
; DI void gemm_core(const GTile& tl, const GTile& nx, bool has_next  , bool chain  , bool pre, u32x4 (&ra)[4], u32x4 (&rb)[4], char* smem, f32x16 (&acc)[2][4]) {
;     ...
;   const int nk = K / 64;
;   if (!pre) { G_LOAD(0); G_STORE(0); G_LOAD(1); }
;   for (int kt = 0; kt < nk; ++kt) {
;     __syncthreads();
;     G_COMPUTE(kt & 1, kt);
;   }
	s_waitcnt vmcnt(7)
	ds_write_b128 v192, v[160:163]
	s_waitcnt vmcnt(6)
	ds_write_b128 v159, v[164:167]
	ds_read_b128 v[160:163], v152 offset:36864
	ds_read_b128 v[164:167], v152 offset:41472
	v_mfma_f32_32x32x16_bf16 v[32:47], v[168:171], v[208:211], v[32:47]
	v_mfma_f32_32x32x16_bf16 v[48:63], v[172:175], v[208:211], v[48:63]
	ds_read_b128 v[208:211], v151
	v_mfma_f32_32x32x16_bf16 v[0:15], v[168:171], v[212:215], v[0:15]
	v_mfma_f32_32x32x16_bf16 v[16:31], v[172:175], v[212:215], v[16:31]
	ds_read_b128 v[212:215], v151 offset:4608
	s_setprio 0
	global_load_dwordx4 v[168:171], v[136:137], off offset:1792
	global_load_dwordx4 v[172:175], v[138:139], off offset:1792
	s_setprio 1
	s_waitcnt lgkmcnt(1)
	v_mfma_f32_32x32x16_bf16 v[96:111], v[160:163], v[208:211], v[96:111]
	v_mfma_f32_32x32x16_bf16 v[112:127], v[164:167], v[208:211], v[112:127]
	s_waitcnt lgkmcnt(0)
	v_mfma_f32_32x32x16_bf16 v[64:79], v[160:163], v[212:215], v[64:79]
	v_mfma_f32_32x32x16_bf16 v[80:95], v[164:167], v[212:215], v[80:95]
	ds_read_b128 v[208:211], v151 offset:9216
	ds_read_b128 v[212:215], v151 offset:13824
	s_waitcnt vmcnt(7)
	ds_write_b128 v158, v[184:187]
	s_waitcnt vmcnt(6)
	ds_write_b128 v157, v[188:191]
	ds_read_b128 v[184:187], v152 offset:36896
	ds_read_b128 v[188:191], v152 offset:41504
	s_waitcnt lgkmcnt(5)
	v_mfma_f32_32x32x16_bf16 v[32:47], v[160:163], v[208:211], v[32:47]
	v_mfma_f32_32x32x16_bf16 v[48:63], v[164:167], v[208:211], v[48:63]
	ds_read_b128 v[208:211], v151 offset:32
	s_waitcnt lgkmcnt(5)
	v_mfma_f32_32x32x16_bf16 v[0:15], v[160:163], v[212:215], v[0:15]
	v_mfma_f32_32x32x16_bf16 v[16:31], v[164:167], v[212:215], v[16:31]
	ds_read_b128 v[212:215], v151 offset:4640
	s_setprio 0
	global_load_dwordx4 v[160:163], v[140:141], off offset:1792
	global_load_dwordx4 v[164:167], v[142:143], off offset:1792
	s_setprio 1
	s_waitcnt lgkmcnt(1)
	v_mfma_f32_32x32x16_bf16 v[96:111], v[184:187], v[208:211], v[96:111]
	v_mfma_f32_32x32x16_bf16 v[112:127], v[188:191], v[208:211], v[112:127]
	s_waitcnt lgkmcnt(0)
	v_mfma_f32_32x32x16_bf16 v[64:79], v[184:187], v[212:215], v[64:79]
	v_mfma_f32_32x32x16_bf16 v[80:95], v[188:191], v[212:215], v[80:95]
	ds_read_b128 v[208:211], v151 offset:9248
	ds_read_b128 v[212:215], v151 offset:13856
	s_waitcnt vmcnt(7)
	ds_write_b128 v154, v[194:197]
	s_waitcnt vmcnt(6)
	ds_write_b128 v153, v[198:201]
	ds_read_b128 v[194:197], v152 offset:36928
	ds_read_b128 v[198:201], v152 offset:41536
	s_waitcnt lgkmcnt(5)
	v_mfma_f32_32x32x16_bf16 v[32:47], v[184:187], v[208:211], v[32:47]
	v_mfma_f32_32x32x16_bf16 v[48:63], v[188:191], v[208:211], v[48:63]
	ds_read_b128 v[208:211], v151 offset:64
	s_waitcnt lgkmcnt(5)
	v_mfma_f32_32x32x16_bf16 v[0:15], v[184:187], v[212:215], v[0:15]
	v_mfma_f32_32x32x16_bf16 v[16:31], v[188:191], v[212:215], v[16:31]
	ds_read_b128 v[212:215], v151 offset:4672
	s_setprio 0
	global_load_dwordx4 v[184:187], v[132:133], off offset:1792
	global_load_dwordx4 v[188:191], v[134:135], off offset:1792
	s_setprio 1
	s_waitcnt lgkmcnt(1)
	v_mfma_f32_32x32x16_bf16 v[96:111], v[194:197], v[208:211], v[96:111]
	v_mfma_f32_32x32x16_bf16 v[112:127], v[198:201], v[208:211], v[112:127]
	s_waitcnt lgkmcnt(0)
	v_mfma_f32_32x32x16_bf16 v[64:79], v[194:197], v[212:215], v[64:79]
	v_mfma_f32_32x32x16_bf16 v[80:95], v[198:201], v[212:215], v[80:95]
	ds_read_b128 v[208:211], v151 offset:9280
	ds_read_b128 v[212:215], v151 offset:13888
	s_waitcnt vmcnt(7)
	ds_write_b128 v156, v[176:179]
	s_waitcnt vmcnt(6)
	ds_write_b128 v155, v[180:183]
	ds_read_b128 v[176:179], v152 offset:36960
	ds_read_b128 v[180:183], v152 offset:41568
	s_waitcnt lgkmcnt(5)
	v_mfma_f32_32x32x16_bf16 v[32:47], v[194:197], v[208:211], v[32:47]
	v_mfma_f32_32x32x16_bf16 v[48:63], v[198:201], v[208:211], v[48:63]
	ds_read_b128 v[208:211], v151 offset:96
	s_waitcnt lgkmcnt(5)
	v_mfma_f32_32x32x16_bf16 v[0:15], v[194:197], v[212:215], v[0:15]
	v_mfma_f32_32x32x16_bf16 v[16:31], v[198:201], v[212:215], v[16:31]
	ds_read_b128 v[212:215], v151 offset:4704
	s_setprio 0
	global_load_dwordx4 v[194:197], v[144:145], off offset:1792
	global_load_dwordx4 v[198:201], v[146:147], off offset:1792
	s_setprio 1
	s_waitcnt lgkmcnt(1)
	v_mfma_f32_32x32x16_bf16 v[96:111], v[176:179], v[208:211], v[96:111]
	v_mfma_f32_32x32x16_bf16 v[112:127], v[180:183], v[208:211], v[112:127]
	s_waitcnt lgkmcnt(0)
	v_mfma_f32_32x32x16_bf16 v[64:79], v[176:179], v[212:215], v[64:79]
	v_mfma_f32_32x32x16_bf16 v[80:95], v[180:183], v[212:215], v[80:95]
	ds_read_b128 v[208:211], v151 offset:9312
	ds_read_b128 v[212:215], v151 offset:13920
	s_waitcnt lgkmcnt(0)
	s_barrier
; template <bool trans>
; DI void gemm_core(const GTile& tl, const GTile& nx, bool has_next  , bool chain  , bool pre, u32x4 (&ra)[4], u32x4 (&rb)[4], char* smem, f32x16 (&acc)[2][4]) {
;     ...
;   const int nk = K / 64;
;   if (!pre) { G_LOAD(0); G_STORE(0); G_LOAD(1); }
;   for (int kt = 0; kt < nk; ++kt) {
;     __syncthreads();
;     G_COMPUTE(kt & 1, kt);
;   }
	s_waitcnt vmcnt(7)
	ds_write_b128 v148, v[168:171]
	s_waitcnt vmcnt(6)
	ds_write_b128 v148, v[172:175] offset:36864
	ds_read_b128 v[168:171], v150
	ds_read_b128 v[172:175], v150 offset:4608
	v_mfma_f32_32x32x16_bf16 v[32:47], v[176:179], v[208:211], v[32:47]
	v_mfma_f32_32x32x16_bf16 v[48:63], v[180:183], v[208:211], v[48:63]
	ds_read_b128 v[208:211], v149
	v_mfma_f32_32x32x16_bf16 v[0:15], v[176:179], v[212:215], v[0:15]
	v_mfma_f32_32x32x16_bf16 v[16:31], v[180:183], v[212:215], v[16:31]
	ds_read_b128 v[212:215], v149 offset:4608
	s_setprio 0
	global_load_dwordx4 v[176:179], v[136:137], off offset:1920
	global_load_dwordx4 v[180:183], v[138:139], off offset:1920
	s_setprio 1
	s_waitcnt lgkmcnt(1)
	v_mfma_f32_32x32x16_bf16 v[96:111], v[168:171], v[208:211], v[96:111]
	v_mfma_f32_32x32x16_bf16 v[112:127], v[172:175], v[208:211], v[112:127]
	s_waitcnt lgkmcnt(0)
	v_mfma_f32_32x32x16_bf16 v[64:79], v[168:171], v[212:215], v[64:79]
	v_mfma_f32_32x32x16_bf16 v[80:95], v[172:175], v[212:215], v[80:95]
	ds_read_b128 v[208:211], v149 offset:9216
	ds_read_b128 v[212:215], v149 offset:13824
	s_waitcnt vmcnt(7)
	ds_write_b128 v148, v[160:163] offset:9216
	s_waitcnt vmcnt(6)
	ds_write_b128 v148, v[164:167] offset:46080
	ds_read_b128 v[160:163], v150 offset:32
	ds_read_b128 v[164:167], v150 offset:4640
	s_waitcnt lgkmcnt(5)
	v_mfma_f32_32x32x16_bf16 v[32:47], v[168:171], v[208:211], v[32:47]
	v_mfma_f32_32x32x16_bf16 v[48:63], v[172:175], v[208:211], v[48:63]
	ds_read_b128 v[208:211], v149 offset:32
	s_waitcnt lgkmcnt(5)
	v_mfma_f32_32x32x16_bf16 v[0:15], v[168:171], v[212:215], v[0:15]
	v_mfma_f32_32x32x16_bf16 v[16:31], v[172:175], v[212:215], v[16:31]
	ds_read_b128 v[212:215], v149 offset:4640
	s_setprio 0
	global_load_dwordx4 v[168:171], v[140:141], off offset:1920
	global_load_dwordx4 v[172:175], v[142:143], off offset:1920
	s_setprio 1
	s_waitcnt lgkmcnt(1)
	v_mfma_f32_32x32x16_bf16 v[96:111], v[160:163], v[208:211], v[96:111]
	v_mfma_f32_32x32x16_bf16 v[112:127], v[164:167], v[208:211], v[112:127]
	s_waitcnt lgkmcnt(0)
	v_mfma_f32_32x32x16_bf16 v[64:79], v[160:163], v[212:215], v[64:79]
	v_mfma_f32_32x32x16_bf16 v[80:95], v[164:167], v[212:215], v[80:95]
	ds_read_b128 v[208:211], v149 offset:9248
	ds_read_b128 v[212:215], v149 offset:13856
	s_waitcnt vmcnt(7)
	ds_write_b128 v148, v[184:187] offset:18432
	s_waitcnt vmcnt(6)
	ds_write_b128 v148, v[188:191] offset:55296
	ds_read_b128 v[184:187], v150 offset:64
	ds_read_b128 v[188:191], v150 offset:4672
	s_waitcnt lgkmcnt(5)
	v_mfma_f32_32x32x16_bf16 v[32:47], v[160:163], v[208:211], v[32:47]
	v_mfma_f32_32x32x16_bf16 v[48:63], v[164:167], v[208:211], v[48:63]
	ds_read_b128 v[208:211], v149 offset:64
	s_waitcnt lgkmcnt(5)
	v_mfma_f32_32x32x16_bf16 v[0:15], v[160:163], v[212:215], v[0:15]
	v_mfma_f32_32x32x16_bf16 v[16:31], v[164:167], v[212:215], v[16:31]
	ds_read_b128 v[212:215], v149 offset:4672
	s_setprio 0
	global_load_dwordx4 v[160:163], v[132:133], off offset:1920
	global_load_dwordx4 v[164:167], v[134:135], off offset:1920
	s_setprio 1
	s_waitcnt lgkmcnt(1)
	v_mfma_f32_32x32x16_bf16 v[96:111], v[184:187], v[208:211], v[96:111]
	v_mfma_f32_32x32x16_bf16 v[112:127], v[188:191], v[208:211], v[112:127]
	s_waitcnt lgkmcnt(0)
	v_mfma_f32_32x32x16_bf16 v[64:79], v[184:187], v[212:215], v[64:79]
	v_mfma_f32_32x32x16_bf16 v[80:95], v[188:191], v[212:215], v[80:95]
	ds_read_b128 v[208:211], v149 offset:9280
	ds_read_b128 v[212:215], v149 offset:13888
	s_waitcnt vmcnt(7)
	ds_write_b128 v148, v[194:197] offset:27648
	s_waitcnt vmcnt(6)
	ds_write_b128 v148, v[198:201] offset:64512
	ds_read_b128 v[194:197], v150 offset:96
	ds_read_b128 v[198:201], v150 offset:4704
	s_waitcnt lgkmcnt(5)
	v_mfma_f32_32x32x16_bf16 v[32:47], v[184:187], v[208:211], v[32:47]
	v_mfma_f32_32x32x16_bf16 v[48:63], v[188:191], v[208:211], v[48:63]
	ds_read_b128 v[208:211], v149 offset:96
	s_waitcnt lgkmcnt(5)
	v_mfma_f32_32x32x16_bf16 v[0:15], v[184:187], v[212:215], v[0:15]
	v_mfma_f32_32x32x16_bf16 v[16:31], v[188:191], v[212:215], v[16:31]
	ds_read_b128 v[212:215], v149 offset:4704
	s_setprio 0
	global_load_dwordx4 v[184:187], v[144:145], off offset:1920
	global_load_dwordx4 v[188:191], v[146:147], off offset:1920
	s_setprio 1
	s_waitcnt lgkmcnt(1)
	v_mfma_f32_32x32x16_bf16 v[96:111], v[194:197], v[208:211], v[96:111]
	v_mfma_f32_32x32x16_bf16 v[112:127], v[198:201], v[208:211], v[112:127]
	s_waitcnt lgkmcnt(0)
	v_mfma_f32_32x32x16_bf16 v[64:79], v[194:197], v[212:215], v[64:79]
	v_mfma_f32_32x32x16_bf16 v[80:95], v[198:201], v[212:215], v[80:95]
	ds_read_b128 v[208:211], v149 offset:9312
	ds_read_b128 v[212:215], v149 offset:13920
	s_waitcnt lgkmcnt(0)
	s_barrier
; template <bool trans>
; DI void gemm_core(const GTile& tl, const GTile& nx, bool has_next  , bool chain  , bool pre, u32x4 (&ra)[4], u32x4 (&rb)[4], char* smem, f32x16 (&acc)[2][4]) {
;     ...
;   const int nk = K / 64;
;   if (!pre) { G_LOAD(0); G_STORE(0); G_LOAD(1); }
;   for (int kt = 0; kt < nk; ++kt) {
;     __syncthreads();
;     G_COMPUTE(kt & 1, kt);
;   }
	s_waitcnt vmcnt(7)
	ds_write_b128 v192, v[176:179]
	s_waitcnt vmcnt(6)
	ds_write_b128 v159, v[180:183]
	ds_read_b128 v[176:179], v152 offset:36864
	ds_read_b128 v[180:183], v152 offset:41472
	v_mfma_f32_32x32x16_bf16 v[32:47], v[194:197], v[208:211], v[32:47]
	v_mfma_f32_32x32x16_bf16 v[48:63], v[198:201], v[208:211], v[48:63]
	ds_read_b128 v[208:211], v151
	v_mfma_f32_32x32x16_bf16 v[0:15], v[194:197], v[212:215], v[0:15]
	v_mfma_f32_32x32x16_bf16 v[16:31], v[198:201], v[212:215], v[16:31]
	ds_read_b128 v[212:215], v151 offset:4608
	s_setprio 0
	global_load_dwordx4 v[194:197], v[136:137], off offset:2048
	global_load_dwordx4 v[198:201], v[138:139], off offset:2048
	s_setprio 1
	s_waitcnt lgkmcnt(1)
	v_mfma_f32_32x32x16_bf16 v[96:111], v[176:179], v[208:211], v[96:111]
	v_mfma_f32_32x32x16_bf16 v[112:127], v[180:183], v[208:211], v[112:127]
	s_waitcnt lgkmcnt(0)
	v_mfma_f32_32x32x16_bf16 v[64:79], v[176:179], v[212:215], v[64:79]
	v_mfma_f32_32x32x16_bf16 v[80:95], v[180:183], v[212:215], v[80:95]
	ds_read_b128 v[208:211], v151 offset:9216
	ds_read_b128 v[212:215], v151 offset:13824
	s_waitcnt vmcnt(7)
	ds_write_b128 v158, v[168:171]
	s_waitcnt vmcnt(6)
	ds_write_b128 v157, v[172:175]
	ds_read_b128 v[168:171], v152 offset:36896
	ds_read_b128 v[172:175], v152 offset:41504
	s_waitcnt lgkmcnt(5)
	v_mfma_f32_32x32x16_bf16 v[32:47], v[176:179], v[208:211], v[32:47]
	v_mfma_f32_32x32x16_bf16 v[48:63], v[180:183], v[208:211], v[48:63]
	ds_read_b128 v[208:211], v151 offset:32
	s_waitcnt lgkmcnt(5)
	v_mfma_f32_32x32x16_bf16 v[0:15], v[176:179], v[212:215], v[0:15]
	v_mfma_f32_32x32x16_bf16 v[16:31], v[180:183], v[212:215], v[16:31]
	ds_read_b128 v[212:215], v151 offset:4640
	s_setprio 0
	global_load_dwordx4 v[176:179], v[140:141], off offset:2048
	global_load_dwordx4 v[180:183], v[142:143], off offset:2048
	s_setprio 1
	s_waitcnt lgkmcnt(1)
	v_mfma_f32_32x32x16_bf16 v[96:111], v[168:171], v[208:211], v[96:111]
	v_mfma_f32_32x32x16_bf16 v[112:127], v[172:175], v[208:211], v[112:127]
	s_waitcnt lgkmcnt(0)
	v_mfma_f32_32x32x16_bf16 v[64:79], v[168:171], v[212:215], v[64:79]
	v_mfma_f32_32x32x16_bf16 v[80:95], v[172:175], v[212:215], v[80:95]
	ds_read_b128 v[208:211], v151 offset:9248
	ds_read_b128 v[212:215], v151 offset:13856
	s_waitcnt vmcnt(7)
	ds_write_b128 v154, v[160:163]
	s_waitcnt vmcnt(6)
	ds_write_b128 v153, v[164:167]
	ds_read_b128 v[160:163], v152 offset:36928
	ds_read_b128 v[164:167], v152 offset:41536
	s_waitcnt lgkmcnt(5)
	v_mfma_f32_32x32x16_bf16 v[32:47], v[168:171], v[208:211], v[32:47]
	v_mfma_f32_32x32x16_bf16 v[48:63], v[172:175], v[208:211], v[48:63]
	ds_read_b128 v[208:211], v151 offset:64
	s_waitcnt lgkmcnt(5)
	v_mfma_f32_32x32x16_bf16 v[0:15], v[168:171], v[212:215], v[0:15]
	v_mfma_f32_32x32x16_bf16 v[16:31], v[172:175], v[212:215], v[16:31]
	ds_read_b128 v[212:215], v151 offset:4672
	s_setprio 0
	global_load_dwordx4 v[168:171], v[132:133], off offset:2048
	global_load_dwordx4 v[172:175], v[134:135], off offset:2048
	s_setprio 1
	s_waitcnt lgkmcnt(1)
	v_mfma_f32_32x32x16_bf16 v[96:111], v[160:163], v[208:211], v[96:111]
	v_mfma_f32_32x32x16_bf16 v[112:127], v[164:167], v[208:211], v[112:127]
	s_waitcnt lgkmcnt(0)
	v_mfma_f32_32x32x16_bf16 v[64:79], v[160:163], v[212:215], v[64:79]
	v_mfma_f32_32x32x16_bf16 v[80:95], v[164:167], v[212:215], v[80:95]
	ds_read_b128 v[208:211], v151 offset:9280
	ds_read_b128 v[212:215], v151 offset:13888
	s_waitcnt vmcnt(7)
	ds_write_b128 v156, v[184:187]
	s_waitcnt vmcnt(6)
	ds_write_b128 v155, v[188:191]
	ds_read_b128 v[184:187], v152 offset:36960
	ds_read_b128 v[188:191], v152 offset:41568
	s_waitcnt lgkmcnt(5)
	v_mfma_f32_32x32x16_bf16 v[32:47], v[160:163], v[208:211], v[32:47]
	v_mfma_f32_32x32x16_bf16 v[48:63], v[164:167], v[208:211], v[48:63]
	ds_read_b128 v[208:211], v151 offset:96
	s_waitcnt lgkmcnt(5)
	v_mfma_f32_32x32x16_bf16 v[0:15], v[160:163], v[212:215], v[0:15]
	v_mfma_f32_32x32x16_bf16 v[16:31], v[164:167], v[212:215], v[16:31]
	ds_read_b128 v[212:215], v151 offset:4704
	s_setprio 0
	global_load_dwordx4 v[160:163], v[144:145], off offset:2048
	global_load_dwordx4 v[164:167], v[146:147], off offset:2048
	s_setprio 1
	s_waitcnt lgkmcnt(1)
	v_mfma_f32_32x32x16_bf16 v[96:111], v[184:187], v[208:211], v[96:111]
	v_mfma_f32_32x32x16_bf16 v[112:127], v[188:191], v[208:211], v[112:127]
	s_waitcnt lgkmcnt(0)
	v_mfma_f32_32x32x16_bf16 v[64:79], v[184:187], v[212:215], v[64:79]
	v_mfma_f32_32x32x16_bf16 v[80:95], v[188:191], v[212:215], v[80:95]
	ds_read_b128 v[208:211], v151 offset:9312
	ds_read_b128 v[212:215], v151 offset:13920
	s_waitcnt lgkmcnt(0)
	s_barrier
; template <bool trans>
; DI void gemm_core(const GTile& tl, const GTile& nx, bool has_next  , bool chain  , bool pre, u32x4 (&ra)[4], u32x4 (&rb)[4], char* smem, f32x16 (&acc)[2][4]) {
;     ...
;   const int nk = K / 64;
;   if (!pre) { G_LOAD(0); G_STORE(0); G_LOAD(1); }
;   for (int kt = 0; kt < nk; ++kt) {
;     __syncthreads();
;     G_COMPUTE(kt & 1, kt);
;   }
	s_waitcnt vmcnt(7)
	ds_write_b128 v148, v[194:197]
	s_waitcnt vmcnt(6)
	ds_write_b128 v148, v[198:201] offset:36864
	ds_read_b128 v[194:197], v150
	ds_read_b128 v[198:201], v150 offset:4608
	v_mfma_f32_32x32x16_bf16 v[32:47], v[184:187], v[208:211], v[32:47]
	v_mfma_f32_32x32x16_bf16 v[48:63], v[188:191], v[208:211], v[48:63]
	ds_read_b128 v[208:211], v149
	v_mfma_f32_32x32x16_bf16 v[0:15], v[184:187], v[212:215], v[0:15]
	v_mfma_f32_32x32x16_bf16 v[16:31], v[188:191], v[212:215], v[16:31]
	ds_read_b128 v[212:215], v149 offset:4608
	s_setprio 0
	global_load_dwordx4 v[184:187], v[136:137], off offset:2176
	global_load_dwordx4 v[188:191], v[138:139], off offset:2176
	s_setprio 1
	s_waitcnt lgkmcnt(1)
	v_mfma_f32_32x32x16_bf16 v[96:111], v[194:197], v[208:211], v[96:111]
	v_mfma_f32_32x32x16_bf16 v[112:127], v[198:201], v[208:211], v[112:127]
	s_waitcnt lgkmcnt(0)
	v_mfma_f32_32x32x16_bf16 v[64:79], v[194:197], v[212:215], v[64:79]
	v_mfma_f32_32x32x16_bf16 v[80:95], v[198:201], v[212:215], v[80:95]
	ds_read_b128 v[208:211], v149 offset:9216
	ds_read_b128 v[212:215], v149 offset:13824
	s_waitcnt vmcnt(7)
	ds_write_b128 v148, v[176:179] offset:9216
	s_waitcnt vmcnt(6)
	ds_write_b128 v148, v[180:183] offset:46080
	ds_read_b128 v[176:179], v150 offset:32
	ds_read_b128 v[180:183], v150 offset:4640
	s_waitcnt lgkmcnt(5)
	v_mfma_f32_32x32x16_bf16 v[32:47], v[194:197], v[208:211], v[32:47]
	v_mfma_f32_32x32x16_bf16 v[48:63], v[198:201], v[208:211], v[48:63]
	ds_read_b128 v[208:211], v149 offset:32
	s_waitcnt lgkmcnt(5)
	v_mfma_f32_32x32x16_bf16 v[0:15], v[194:197], v[212:215], v[0:15]
	v_mfma_f32_32x32x16_bf16 v[16:31], v[198:201], v[212:215], v[16:31]
	ds_read_b128 v[212:215], v149 offset:4640
	s_setprio 0
	global_load_dwordx4 v[194:197], v[140:141], off offset:2176
	global_load_dwordx4 v[198:201], v[142:143], off offset:2176
	s_setprio 1
	s_waitcnt lgkmcnt(1)
	v_mfma_f32_32x32x16_bf16 v[96:111], v[176:179], v[208:211], v[96:111]
	v_mfma_f32_32x32x16_bf16 v[112:127], v[180:183], v[208:211], v[112:127]
	s_waitcnt lgkmcnt(0)
	v_mfma_f32_32x32x16_bf16 v[64:79], v[176:179], v[212:215], v[64:79]
	v_mfma_f32_32x32x16_bf16 v[80:95], v[180:183], v[212:215], v[80:95]
	ds_read_b128 v[208:211], v149 offset:9248
	ds_read_b128 v[212:215], v149 offset:13856
	s_waitcnt vmcnt(7)
	ds_write_b128 v148, v[168:171] offset:18432
	s_waitcnt vmcnt(6)
	ds_write_b128 v148, v[172:175] offset:55296
	ds_read_b128 v[168:171], v150 offset:64
	ds_read_b128 v[172:175], v150 offset:4672
	s_waitcnt lgkmcnt(5)
	v_mfma_f32_32x32x16_bf16 v[32:47], v[176:179], v[208:211], v[32:47]
	v_mfma_f32_32x32x16_bf16 v[48:63], v[180:183], v[208:211], v[48:63]
	ds_read_b128 v[208:211], v149 offset:64
	s_waitcnt lgkmcnt(5)
	v_mfma_f32_32x32x16_bf16 v[0:15], v[176:179], v[212:215], v[0:15]
	v_mfma_f32_32x32x16_bf16 v[16:31], v[180:183], v[212:215], v[16:31]
	ds_read_b128 v[212:215], v149 offset:4672
	s_setprio 0
	global_load_dwordx4 v[176:179], v[132:133], off offset:2176
	global_load_dwordx4 v[180:183], v[134:135], off offset:2176
	s_setprio 1
	s_waitcnt lgkmcnt(1)
	v_mfma_f32_32x32x16_bf16 v[96:111], v[168:171], v[208:211], v[96:111]
	v_mfma_f32_32x32x16_bf16 v[112:127], v[172:175], v[208:211], v[112:127]
	s_waitcnt lgkmcnt(0)
	v_mfma_f32_32x32x16_bf16 v[64:79], v[168:171], v[212:215], v[64:79]
	v_mfma_f32_32x32x16_bf16 v[80:95], v[172:175], v[212:215], v[80:95]
	ds_read_b128 v[208:211], v149 offset:9280
	ds_read_b128 v[212:215], v149 offset:13888
	s_waitcnt vmcnt(7)
	ds_write_b128 v148, v[160:163] offset:27648
	s_waitcnt vmcnt(6)
	ds_write_b128 v148, v[164:167] offset:64512
	ds_read_b128 v[160:163], v150 offset:96
	ds_read_b128 v[164:167], v150 offset:4704
	s_waitcnt lgkmcnt(5)
	v_mfma_f32_32x32x16_bf16 v[32:47], v[168:171], v[208:211], v[32:47]
	v_mfma_f32_32x32x16_bf16 v[48:63], v[172:175], v[208:211], v[48:63]
	ds_read_b128 v[208:211], v149 offset:96
	s_waitcnt lgkmcnt(5)
	v_mfma_f32_32x32x16_bf16 v[0:15], v[168:171], v[212:215], v[0:15]
	v_mfma_f32_32x32x16_bf16 v[16:31], v[172:175], v[212:215], v[16:31]
	ds_read_b128 v[212:215], v149 offset:4704
	s_setprio 0
	global_load_dwordx4 v[168:171], v[144:145], off offset:2176
	global_load_dwordx4 v[172:175], v[146:147], off offset:2176
	s_setprio 1
	s_waitcnt lgkmcnt(1)
	v_mfma_f32_32x32x16_bf16 v[96:111], v[160:163], v[208:211], v[96:111]
	v_mfma_f32_32x32x16_bf16 v[112:127], v[164:167], v[208:211], v[112:127]
	s_waitcnt lgkmcnt(0)
	v_mfma_f32_32x32x16_bf16 v[64:79], v[160:163], v[212:215], v[64:79]
	v_mfma_f32_32x32x16_bf16 v[80:95], v[164:167], v[212:215], v[80:95]
	ds_read_b128 v[208:211], v149 offset:9312
	ds_read_b128 v[212:215], v149 offset:13920
	s_waitcnt lgkmcnt(0)
	s_barrier
; template <bool trans>
; DI void gemm_core(const GTile& tl, const GTile& nx, bool has_next  , bool chain  , bool pre, u32x4 (&ra)[4], u32x4 (&rb)[4], char* smem, f32x16 (&acc)[2][4]) {
;     ...
;   const int nk = K / 64;
;   if (!pre) { G_LOAD(0); G_STORE(0); G_LOAD(1); }
;   for (int kt = 0; kt < nk; ++kt) {
;     __syncthreads();
;     G_COMPUTE(kt & 1, kt);
;   }
	s_waitcnt vmcnt(7)
	ds_write_b128 v192, v[184:187]
	s_waitcnt vmcnt(6)
	ds_write_b128 v159, v[188:191]
	ds_read_b128 v[184:187], v152 offset:36864
	ds_read_b128 v[188:191], v152 offset:41472
	v_mfma_f32_32x32x16_bf16 v[32:47], v[160:163], v[208:211], v[32:47]
	v_mfma_f32_32x32x16_bf16 v[48:63], v[164:167], v[208:211], v[48:63]
	ds_read_b128 v[208:211], v151
	v_mfma_f32_32x32x16_bf16 v[0:15], v[160:163], v[212:215], v[0:15]
	v_mfma_f32_32x32x16_bf16 v[16:31], v[164:167], v[212:215], v[16:31]
	ds_read_b128 v[212:215], v151 offset:4608
	s_setprio 0
	global_load_dwordx4 v[160:163], v[136:137], off offset:2304
	global_load_dwordx4 v[164:167], v[138:139], off offset:2304
	s_setprio 1
	s_waitcnt lgkmcnt(1)
	v_mfma_f32_32x32x16_bf16 v[96:111], v[184:187], v[208:211], v[96:111]
	v_mfma_f32_32x32x16_bf16 v[112:127], v[188:191], v[208:211], v[112:127]
	s_waitcnt lgkmcnt(0)
	v_mfma_f32_32x32x16_bf16 v[64:79], v[184:187], v[212:215], v[64:79]
	v_mfma_f32_32x32x16_bf16 v[80:95], v[188:191], v[212:215], v[80:95]
	ds_read_b128 v[208:211], v151 offset:9216
	ds_read_b128 v[212:215], v151 offset:13824
	s_waitcnt vmcnt(7)
	ds_write_b128 v158, v[194:197]
	s_waitcnt vmcnt(6)
	ds_write_b128 v157, v[198:201]
	ds_read_b128 v[194:197], v152 offset:36896
	ds_read_b128 v[198:201], v152 offset:41504
	s_waitcnt lgkmcnt(5)
	v_mfma_f32_32x32x16_bf16 v[32:47], v[184:187], v[208:211], v[32:47]
	v_mfma_f32_32x32x16_bf16 v[48:63], v[188:191], v[208:211], v[48:63]
	ds_read_b128 v[208:211], v151 offset:32
	s_waitcnt lgkmcnt(5)
	v_mfma_f32_32x32x16_bf16 v[0:15], v[184:187], v[212:215], v[0:15]
	v_mfma_f32_32x32x16_bf16 v[16:31], v[188:191], v[212:215], v[16:31]
	ds_read_b128 v[212:215], v151 offset:4640
	s_setprio 0
	global_load_dwordx4 v[184:187], v[140:141], off offset:2304
	global_load_dwordx4 v[188:191], v[142:143], off offset:2304
	s_setprio 1
	s_waitcnt lgkmcnt(1)
	v_mfma_f32_32x32x16_bf16 v[96:111], v[194:197], v[208:211], v[96:111]
	v_mfma_f32_32x32x16_bf16 v[112:127], v[198:201], v[208:211], v[112:127]
	s_waitcnt lgkmcnt(0)
	v_mfma_f32_32x32x16_bf16 v[64:79], v[194:197], v[212:215], v[64:79]
	v_mfma_f32_32x32x16_bf16 v[80:95], v[198:201], v[212:215], v[80:95]
	ds_read_b128 v[208:211], v151 offset:9248
	ds_read_b128 v[212:215], v151 offset:13856
	s_waitcnt vmcnt(7)
	ds_write_b128 v154, v[176:179]
	s_waitcnt vmcnt(6)
	ds_write_b128 v153, v[180:183]
	ds_read_b128 v[176:179], v152 offset:36928
	ds_read_b128 v[180:183], v152 offset:41536
	s_waitcnt lgkmcnt(5)
	v_mfma_f32_32x32x16_bf16 v[32:47], v[194:197], v[208:211], v[32:47]
	v_mfma_f32_32x32x16_bf16 v[48:63], v[198:201], v[208:211], v[48:63]
	ds_read_b128 v[208:211], v151 offset:64
	s_waitcnt lgkmcnt(5)
	v_mfma_f32_32x32x16_bf16 v[0:15], v[194:197], v[212:215], v[0:15]
	v_mfma_f32_32x32x16_bf16 v[16:31], v[198:201], v[212:215], v[16:31]
	ds_read_b128 v[212:215], v151 offset:4672
	s_setprio 0
	global_load_dwordx4 v[194:197], v[132:133], off offset:2304
	global_load_dwordx4 v[198:201], v[134:135], off offset:2304
	s_setprio 1
	s_waitcnt lgkmcnt(1)
	v_mfma_f32_32x32x16_bf16 v[96:111], v[176:179], v[208:211], v[96:111]
	v_mfma_f32_32x32x16_bf16 v[112:127], v[180:183], v[208:211], v[112:127]
	s_waitcnt lgkmcnt(0)
	v_mfma_f32_32x32x16_bf16 v[64:79], v[176:179], v[212:215], v[64:79]
	v_mfma_f32_32x32x16_bf16 v[80:95], v[180:183], v[212:215], v[80:95]
	ds_read_b128 v[208:211], v151 offset:9280
	ds_read_b128 v[212:215], v151 offset:13888
	s_waitcnt vmcnt(7)
	ds_write_b128 v156, v[168:171]
	s_waitcnt vmcnt(6)
	ds_write_b128 v155, v[172:175]
	ds_read_b128 v[168:171], v152 offset:36960
	ds_read_b128 v[172:175], v152 offset:41568
	s_waitcnt lgkmcnt(5)
	v_mfma_f32_32x32x16_bf16 v[32:47], v[176:179], v[208:211], v[32:47]
	v_mfma_f32_32x32x16_bf16 v[48:63], v[180:183], v[208:211], v[48:63]
	ds_read_b128 v[208:211], v151 offset:96
	s_waitcnt lgkmcnt(5)
	v_mfma_f32_32x32x16_bf16 v[0:15], v[176:179], v[212:215], v[0:15]
	v_mfma_f32_32x32x16_bf16 v[16:31], v[180:183], v[212:215], v[16:31]
	ds_read_b128 v[212:215], v151 offset:4704
	s_setprio 0
	global_load_dwordx4 v[176:179], v[144:145], off offset:2304
	global_load_dwordx4 v[180:183], v[146:147], off offset:2304
	s_setprio 1
	s_waitcnt lgkmcnt(1)
	v_mfma_f32_32x32x16_bf16 v[96:111], v[168:171], v[208:211], v[96:111]
	v_mfma_f32_32x32x16_bf16 v[112:127], v[172:175], v[208:211], v[112:127]
	s_waitcnt lgkmcnt(0)
	v_mfma_f32_32x32x16_bf16 v[64:79], v[168:171], v[212:215], v[64:79]
	v_mfma_f32_32x32x16_bf16 v[80:95], v[172:175], v[212:215], v[80:95]
	ds_read_b128 v[208:211], v151 offset:9312
	ds_read_b128 v[212:215], v151 offset:13920
	s_waitcnt lgkmcnt(0)
	s_barrier
; template <bool trans>
; DI void gemm_core(const GTile& tl, const GTile& nx, bool has_next  , bool chain  , bool pre, u32x4 (&ra)[4], u32x4 (&rb)[4], char* smem, f32x16 (&acc)[2][4]) {
;     ...
;   const int nk = K / 64;
;   if (!pre) { G_LOAD(0); G_STORE(0); G_LOAD(1); }
;   for (int kt = 0; kt < nk; ++kt) {
;     __syncthreads();
;     G_COMPUTE(kt & 1, kt);
;   }
	s_waitcnt vmcnt(7)
	ds_write_b128 v148, v[160:163]
	s_waitcnt vmcnt(6)
	ds_write_b128 v148, v[164:167] offset:36864
	ds_read_b128 v[160:163], v150
	ds_read_b128 v[164:167], v150 offset:4608
	v_mfma_f32_32x32x16_bf16 v[32:47], v[168:171], v[208:211], v[32:47]
	v_mfma_f32_32x32x16_bf16 v[48:63], v[172:175], v[208:211], v[48:63]
	ds_read_b128 v[208:211], v149
	v_mfma_f32_32x32x16_bf16 v[0:15], v[168:171], v[212:215], v[0:15]
	v_mfma_f32_32x32x16_bf16 v[16:31], v[172:175], v[212:215], v[16:31]
	ds_read_b128 v[212:215], v149 offset:4608
	s_setprio 0
	global_load_dwordx4 v[168:171], v[136:137], off offset:2432
	global_load_dwordx4 v[172:175], v[138:139], off offset:2432
	s_setprio 1
	s_waitcnt lgkmcnt(1)
	v_mfma_f32_32x32x16_bf16 v[96:111], v[160:163], v[208:211], v[96:111]
	v_mfma_f32_32x32x16_bf16 v[112:127], v[164:167], v[208:211], v[112:127]
	s_waitcnt lgkmcnt(0)
	v_mfma_f32_32x32x16_bf16 v[64:79], v[160:163], v[212:215], v[64:79]
	v_mfma_f32_32x32x16_bf16 v[80:95], v[164:167], v[212:215], v[80:95]
	ds_read_b128 v[208:211], v149 offset:9216
	ds_read_b128 v[212:215], v149 offset:13824
	s_waitcnt vmcnt(7)
	ds_write_b128 v148, v[184:187] offset:9216
	s_waitcnt vmcnt(6)
	ds_write_b128 v148, v[188:191] offset:46080
	ds_read_b128 v[184:187], v150 offset:32
	ds_read_b128 v[188:191], v150 offset:4640
	s_waitcnt lgkmcnt(5)
	v_mfma_f32_32x32x16_bf16 v[32:47], v[160:163], v[208:211], v[32:47]
	v_mfma_f32_32x32x16_bf16 v[48:63], v[164:167], v[208:211], v[48:63]
	ds_read_b128 v[208:211], v149 offset:32
	s_waitcnt lgkmcnt(5)
	v_mfma_f32_32x32x16_bf16 v[0:15], v[160:163], v[212:215], v[0:15]
	v_mfma_f32_32x32x16_bf16 v[16:31], v[164:167], v[212:215], v[16:31]
	ds_read_b128 v[212:215], v149 offset:4640
	s_setprio 0
	global_load_dwordx4 v[160:163], v[140:141], off offset:2432
	global_load_dwordx4 v[164:167], v[142:143], off offset:2432
	s_setprio 1
	s_waitcnt lgkmcnt(1)
	v_mfma_f32_32x32x16_bf16 v[96:111], v[184:187], v[208:211], v[96:111]
	v_mfma_f32_32x32x16_bf16 v[112:127], v[188:191], v[208:211], v[112:127]
	s_waitcnt lgkmcnt(0)
	v_mfma_f32_32x32x16_bf16 v[64:79], v[184:187], v[212:215], v[64:79]
	v_mfma_f32_32x32x16_bf16 v[80:95], v[188:191], v[212:215], v[80:95]
	ds_read_b128 v[208:211], v149 offset:9248
	ds_read_b128 v[212:215], v149 offset:13856
	s_waitcnt vmcnt(7)
	ds_write_b128 v148, v[194:197] offset:18432
	s_waitcnt vmcnt(6)
	ds_write_b128 v148, v[198:201] offset:55296
	ds_read_b128 v[194:197], v150 offset:64
	ds_read_b128 v[198:201], v150 offset:4672
	s_waitcnt lgkmcnt(5)
	v_mfma_f32_32x32x16_bf16 v[32:47], v[184:187], v[208:211], v[32:47]
	v_mfma_f32_32x32x16_bf16 v[48:63], v[188:191], v[208:211], v[48:63]
	ds_read_b128 v[208:211], v149 offset:64
	s_waitcnt lgkmcnt(5)
	v_mfma_f32_32x32x16_bf16 v[0:15], v[184:187], v[212:215], v[0:15]
	v_mfma_f32_32x32x16_bf16 v[16:31], v[188:191], v[212:215], v[16:31]
	ds_read_b128 v[212:215], v149 offset:4672
	s_setprio 0
	global_load_dwordx4 v[184:187], v[132:133], off offset:2432
	global_load_dwordx4 v[188:191], v[134:135], off offset:2432
	s_setprio 1
	s_waitcnt lgkmcnt(1)
	v_mfma_f32_32x32x16_bf16 v[96:111], v[194:197], v[208:211], v[96:111]
	v_mfma_f32_32x32x16_bf16 v[112:127], v[198:201], v[208:211], v[112:127]
	s_waitcnt lgkmcnt(0)
	v_mfma_f32_32x32x16_bf16 v[64:79], v[194:197], v[212:215], v[64:79]
	v_mfma_f32_32x32x16_bf16 v[80:95], v[198:201], v[212:215], v[80:95]
	ds_read_b128 v[208:211], v149 offset:9280
	ds_read_b128 v[212:215], v149 offset:13888
	s_waitcnt vmcnt(7)
	ds_write_b128 v148, v[176:179] offset:27648
	s_waitcnt vmcnt(6)
	ds_write_b128 v148, v[180:183] offset:64512
	ds_read_b128 v[176:179], v150 offset:96
	ds_read_b128 v[180:183], v150 offset:4704
	s_waitcnt lgkmcnt(5)
	v_mfma_f32_32x32x16_bf16 v[32:47], v[194:197], v[208:211], v[32:47]
	v_mfma_f32_32x32x16_bf16 v[48:63], v[198:201], v[208:211], v[48:63]
	ds_read_b128 v[208:211], v149 offset:96
	s_waitcnt lgkmcnt(5)
	v_mfma_f32_32x32x16_bf16 v[0:15], v[194:197], v[212:215], v[0:15]
	v_mfma_f32_32x32x16_bf16 v[16:31], v[198:201], v[212:215], v[16:31]
	ds_read_b128 v[212:215], v149 offset:4704
	s_setprio 0
	global_load_dwordx4 v[194:197], v[144:145], off offset:2432
	global_load_dwordx4 v[198:201], v[146:147], off offset:2432
	s_setprio 1
	s_waitcnt lgkmcnt(1)
	v_mfma_f32_32x32x16_bf16 v[96:111], v[176:179], v[208:211], v[96:111]
	v_mfma_f32_32x32x16_bf16 v[112:127], v[180:183], v[208:211], v[112:127]
	s_waitcnt lgkmcnt(0)
	v_mfma_f32_32x32x16_bf16 v[64:79], v[176:179], v[212:215], v[64:79]
	v_mfma_f32_32x32x16_bf16 v[80:95], v[180:183], v[212:215], v[80:95]
	ds_read_b128 v[208:211], v149 offset:9312
	ds_read_b128 v[212:215], v149 offset:13920
	s_waitcnt lgkmcnt(0)
	s_barrier
; template <bool trans>
; DI void gemm_core(const GTile& tl, const GTile& nx, bool has_next  , bool chain  , bool pre, u32x4 (&ra)[4], u32x4 (&rb)[4], char* smem, f32x16 (&acc)[2][4]) {
;     ...
;   const int nk = K / 64;
;   if (!pre) { G_LOAD(0); G_STORE(0); G_LOAD(1); }
;   for (int kt = 0; kt < nk; ++kt) {
;     __syncthreads();
;     G_COMPUTE(kt & 1, kt);
;   }
	s_waitcnt vmcnt(7)
	ds_write_b128 v192, v[168:171]
	s_waitcnt vmcnt(6)
	ds_write_b128 v159, v[172:175]
	ds_read_b128 v[168:171], v152 offset:36864
	ds_read_b128 v[172:175], v152 offset:41472
	v_mfma_f32_32x32x16_bf16 v[32:47], v[176:179], v[208:211], v[32:47]
	v_mfma_f32_32x32x16_bf16 v[48:63], v[180:183], v[208:211], v[48:63]
	ds_read_b128 v[208:211], v151
	v_mfma_f32_32x32x16_bf16 v[0:15], v[176:179], v[212:215], v[0:15]
	v_mfma_f32_32x32x16_bf16 v[16:31], v[180:183], v[212:215], v[16:31]
	ds_read_b128 v[212:215], v151 offset:4608
	s_setprio 0
	global_load_dwordx4 v[176:179], v[136:137], off offset:2560
	global_load_dwordx4 v[180:183], v[138:139], off offset:2560
	s_setprio 1
	s_waitcnt lgkmcnt(1)
	v_mfma_f32_32x32x16_bf16 v[96:111], v[168:171], v[208:211], v[96:111]
	v_mfma_f32_32x32x16_bf16 v[112:127], v[172:175], v[208:211], v[112:127]
	s_waitcnt lgkmcnt(0)
	v_mfma_f32_32x32x16_bf16 v[64:79], v[168:171], v[212:215], v[64:79]
	v_mfma_f32_32x32x16_bf16 v[80:95], v[172:175], v[212:215], v[80:95]
	ds_read_b128 v[208:211], v151 offset:9216
	ds_read_b128 v[212:215], v151 offset:13824
	s_waitcnt vmcnt(7)
	ds_write_b128 v158, v[160:163]
	s_waitcnt vmcnt(6)
	ds_write_b128 v157, v[164:167]
	ds_read_b128 v[160:163], v152 offset:36896
	ds_read_b128 v[164:167], v152 offset:41504
	s_waitcnt lgkmcnt(5)
	v_mfma_f32_32x32x16_bf16 v[32:47], v[168:171], v[208:211], v[32:47]
	v_mfma_f32_32x32x16_bf16 v[48:63], v[172:175], v[208:211], v[48:63]
	ds_read_b128 v[208:211], v151 offset:32
	s_waitcnt lgkmcnt(5)
	v_mfma_f32_32x32x16_bf16 v[0:15], v[168:171], v[212:215], v[0:15]
	v_mfma_f32_32x32x16_bf16 v[16:31], v[172:175], v[212:215], v[16:31]
	ds_read_b128 v[212:215], v151 offset:4640
	s_setprio 0
	global_load_dwordx4 v[168:171], v[140:141], off offset:2560
	global_load_dwordx4 v[172:175], v[142:143], off offset:2560
	s_setprio 1
	s_waitcnt lgkmcnt(1)
	v_mfma_f32_32x32x16_bf16 v[96:111], v[160:163], v[208:211], v[96:111]
	v_mfma_f32_32x32x16_bf16 v[112:127], v[164:167], v[208:211], v[112:127]
	s_waitcnt lgkmcnt(0)
	v_mfma_f32_32x32x16_bf16 v[64:79], v[160:163], v[212:215], v[64:79]
	v_mfma_f32_32x32x16_bf16 v[80:95], v[164:167], v[212:215], v[80:95]
	ds_read_b128 v[208:211], v151 offset:9248
	ds_read_b128 v[212:215], v151 offset:13856
	s_waitcnt vmcnt(7)
	ds_write_b128 v154, v[184:187]
	s_waitcnt vmcnt(6)
	ds_write_b128 v153, v[188:191]
	ds_read_b128 v[184:187], v152 offset:36928
	ds_read_b128 v[188:191], v152 offset:41536
	s_waitcnt lgkmcnt(5)
	v_mfma_f32_32x32x16_bf16 v[32:47], v[160:163], v[208:211], v[32:47]
	v_mfma_f32_32x32x16_bf16 v[48:63], v[164:167], v[208:211], v[48:63]
	ds_read_b128 v[208:211], v151 offset:64
	s_waitcnt lgkmcnt(5)
	v_mfma_f32_32x32x16_bf16 v[0:15], v[160:163], v[212:215], v[0:15]
	v_mfma_f32_32x32x16_bf16 v[16:31], v[164:167], v[212:215], v[16:31]
	ds_read_b128 v[212:215], v151 offset:4672
	s_setprio 0
	global_load_dwordx4 v[160:163], v[132:133], off offset:2560
	global_load_dwordx4 v[164:167], v[134:135], off offset:2560
	s_setprio 1
	s_waitcnt lgkmcnt(1)
	v_mfma_f32_32x32x16_bf16 v[96:111], v[184:187], v[208:211], v[96:111]
	v_mfma_f32_32x32x16_bf16 v[112:127], v[188:191], v[208:211], v[112:127]
	s_waitcnt lgkmcnt(0)
	v_mfma_f32_32x32x16_bf16 v[64:79], v[184:187], v[212:215], v[64:79]
	v_mfma_f32_32x32x16_bf16 v[80:95], v[188:191], v[212:215], v[80:95]
	ds_read_b128 v[208:211], v151 offset:9280
	ds_read_b128 v[212:215], v151 offset:13888
	s_waitcnt vmcnt(7)
	ds_write_b128 v156, v[194:197]
	s_waitcnt vmcnt(6)
	ds_write_b128 v155, v[198:201]
	ds_read_b128 v[194:197], v152 offset:36960
	ds_read_b128 v[198:201], v152 offset:41568
	s_waitcnt lgkmcnt(5)
	v_mfma_f32_32x32x16_bf16 v[32:47], v[184:187], v[208:211], v[32:47]
	v_mfma_f32_32x32x16_bf16 v[48:63], v[188:191], v[208:211], v[48:63]
	ds_read_b128 v[208:211], v151 offset:96
	s_waitcnt lgkmcnt(5)
	v_mfma_f32_32x32x16_bf16 v[0:15], v[184:187], v[212:215], v[0:15]
	v_mfma_f32_32x32x16_bf16 v[16:31], v[188:191], v[212:215], v[16:31]
	ds_read_b128 v[212:215], v151 offset:4704
	s_setprio 0
	global_load_dwordx4 v[184:187], v[144:145], off offset:2560
	global_load_dwordx4 v[188:191], v[146:147], off offset:2560
	s_setprio 1
	s_waitcnt lgkmcnt(1)
	v_mfma_f32_32x32x16_bf16 v[96:111], v[194:197], v[208:211], v[96:111]
	v_mfma_f32_32x32x16_bf16 v[112:127], v[198:201], v[208:211], v[112:127]
	s_waitcnt lgkmcnt(0)
	v_mfma_f32_32x32x16_bf16 v[64:79], v[194:197], v[212:215], v[64:79]
	v_mfma_f32_32x32x16_bf16 v[80:95], v[198:201], v[212:215], v[80:95]
	ds_read_b128 v[208:211], v151 offset:9312
	ds_read_b128 v[212:215], v151 offset:13920
	s_waitcnt lgkmcnt(0)
	s_barrier
; template <bool trans>
; DI void gemm_core(const GTile& tl, const GTile& nx, bool has_next  , bool chain  , bool pre, u32x4 (&ra)[4], u32x4 (&rb)[4], char* smem, f32x16 (&acc)[2][4]) {
;     ...
;   const int nk = K / 64;
;   if (!pre) { G_LOAD(0); G_STORE(0); G_LOAD(1); }
;   for (int kt = 0; kt < nk; ++kt) {
;     __syncthreads();
;     G_COMPUTE(kt & 1, kt);
;   }
	s_waitcnt vmcnt(7)
	ds_write_b128 v148, v[176:179]
	s_waitcnt vmcnt(6)
	ds_write_b128 v148, v[180:183] offset:36864
	ds_read_b128 v[176:179], v150
	ds_read_b128 v[180:183], v150 offset:4608
	v_mfma_f32_32x32x16_bf16 v[32:47], v[194:197], v[208:211], v[32:47]
	v_mfma_f32_32x32x16_bf16 v[48:63], v[198:201], v[208:211], v[48:63]
	ds_read_b128 v[208:211], v149
	v_mfma_f32_32x32x16_bf16 v[0:15], v[194:197], v[212:215], v[0:15]
	v_mfma_f32_32x32x16_bf16 v[16:31], v[198:201], v[212:215], v[16:31]
	ds_read_b128 v[212:215], v149 offset:4608
	s_setprio 0
	global_load_dwordx4 v[194:197], v[136:137], off offset:2688
	global_load_dwordx4 v[198:201], v[138:139], off offset:2688
	s_setprio 1
	s_waitcnt lgkmcnt(1)
	v_mfma_f32_32x32x16_bf16 v[96:111], v[176:179], v[208:211], v[96:111]
	v_mfma_f32_32x32x16_bf16 v[112:127], v[180:183], v[208:211], v[112:127]
	s_waitcnt lgkmcnt(0)
	v_mfma_f32_32x32x16_bf16 v[64:79], v[176:179], v[212:215], v[64:79]
	v_mfma_f32_32x32x16_bf16 v[80:95], v[180:183], v[212:215], v[80:95]
	ds_read_b128 v[208:211], v149 offset:9216
	ds_read_b128 v[212:215], v149 offset:13824
	s_waitcnt vmcnt(7)
	ds_write_b128 v148, v[168:171] offset:9216
	s_waitcnt vmcnt(6)
	ds_write_b128 v148, v[172:175] offset:46080
	ds_read_b128 v[168:171], v150 offset:32
	ds_read_b128 v[172:175], v150 offset:4640
	s_waitcnt lgkmcnt(5)
	v_mfma_f32_32x32x16_bf16 v[32:47], v[176:179], v[208:211], v[32:47]
	v_mfma_f32_32x32x16_bf16 v[48:63], v[180:183], v[208:211], v[48:63]
	ds_read_b128 v[208:211], v149 offset:32
	s_waitcnt lgkmcnt(5)
	v_mfma_f32_32x32x16_bf16 v[0:15], v[176:179], v[212:215], v[0:15]
	v_mfma_f32_32x32x16_bf16 v[16:31], v[180:183], v[212:215], v[16:31]
	ds_read_b128 v[212:215], v149 offset:4640
	s_setprio 0
	global_load_dwordx4 v[176:179], v[140:141], off offset:2688
	global_load_dwordx4 v[180:183], v[142:143], off offset:2688
	s_setprio 1
	s_waitcnt lgkmcnt(1)
	v_mfma_f32_32x32x16_bf16 v[96:111], v[168:171], v[208:211], v[96:111]
	v_mfma_f32_32x32x16_bf16 v[112:127], v[172:175], v[208:211], v[112:127]
	s_waitcnt lgkmcnt(0)
	v_mfma_f32_32x32x16_bf16 v[64:79], v[168:171], v[212:215], v[64:79]
	v_mfma_f32_32x32x16_bf16 v[80:95], v[172:175], v[212:215], v[80:95]
	ds_read_b128 v[208:211], v149 offset:9248
	ds_read_b128 v[212:215], v149 offset:13856
	s_waitcnt vmcnt(7)
	ds_write_b128 v148, v[160:163] offset:18432
	s_waitcnt vmcnt(6)
	ds_write_b128 v148, v[164:167] offset:55296
	ds_read_b128 v[160:163], v150 offset:64
	ds_read_b128 v[164:167], v150 offset:4672
	s_waitcnt lgkmcnt(5)
	v_mfma_f32_32x32x16_bf16 v[32:47], v[168:171], v[208:211], v[32:47]
	v_mfma_f32_32x32x16_bf16 v[48:63], v[172:175], v[208:211], v[48:63]
	ds_read_b128 v[208:211], v149 offset:64
	s_waitcnt lgkmcnt(5)
	v_mfma_f32_32x32x16_bf16 v[0:15], v[168:171], v[212:215], v[0:15]
	v_mfma_f32_32x32x16_bf16 v[16:31], v[172:175], v[212:215], v[16:31]
	ds_read_b128 v[212:215], v149 offset:4672
	s_setprio 0
	global_load_dwordx4 v[168:171], v[132:133], off offset:2688
	global_load_dwordx4 v[172:175], v[134:135], off offset:2688
	s_setprio 1
	s_waitcnt lgkmcnt(1)
	v_mfma_f32_32x32x16_bf16 v[96:111], v[160:163], v[208:211], v[96:111]
	v_mfma_f32_32x32x16_bf16 v[112:127], v[164:167], v[208:211], v[112:127]
	s_waitcnt lgkmcnt(0)
	v_mfma_f32_32x32x16_bf16 v[64:79], v[160:163], v[212:215], v[64:79]
	v_mfma_f32_32x32x16_bf16 v[80:95], v[164:167], v[212:215], v[80:95]
	ds_read_b128 v[208:211], v149 offset:9280
	ds_read_b128 v[212:215], v149 offset:13888
	s_waitcnt vmcnt(7)
	ds_write_b128 v148, v[184:187] offset:27648
	s_waitcnt vmcnt(6)
	ds_write_b128 v148, v[188:191] offset:64512
	ds_read_b128 v[184:187], v150 offset:96
	ds_read_b128 v[188:191], v150 offset:4704
	s_waitcnt lgkmcnt(5)
	v_mfma_f32_32x32x16_bf16 v[32:47], v[160:163], v[208:211], v[32:47]
	v_mfma_f32_32x32x16_bf16 v[48:63], v[164:167], v[208:211], v[48:63]
	ds_read_b128 v[208:211], v149 offset:96
	s_waitcnt lgkmcnt(5)
	v_mfma_f32_32x32x16_bf16 v[0:15], v[160:163], v[212:215], v[0:15]
	v_mfma_f32_32x32x16_bf16 v[16:31], v[164:167], v[212:215], v[16:31]
	ds_read_b128 v[212:215], v149 offset:4704
	s_setprio 0
	global_load_dwordx4 v[160:163], v[144:145], off offset:2688
	global_load_dwordx4 v[164:167], v[146:147], off offset:2688
	s_setprio 1
	s_waitcnt lgkmcnt(1)
	v_mfma_f32_32x32x16_bf16 v[96:111], v[184:187], v[208:211], v[96:111]
	v_mfma_f32_32x32x16_bf16 v[112:127], v[188:191], v[208:211], v[112:127]
	s_waitcnt lgkmcnt(0)
	v_mfma_f32_32x32x16_bf16 v[64:79], v[184:187], v[212:215], v[64:79]
	v_mfma_f32_32x32x16_bf16 v[80:95], v[188:191], v[212:215], v[80:95]
	ds_read_b128 v[208:211], v149 offset:9312
	ds_read_b128 v[212:215], v149 offset:13920
	s_waitcnt lgkmcnt(0)
	s_barrier
; template <bool trans>
; DI void gemm_core(const GTile& tl, const GTile& nx, bool has_next  , bool chain  , bool pre, u32x4 (&ra)[4], u32x4 (&rb)[4], char* smem, f32x16 (&acc)[2][4]) {
;     ...
;   const int nk = K / 64;
;   if (!pre) { G_LOAD(0); G_STORE(0); G_LOAD(1); }
;   for (int kt = 0; kt < nk; ++kt) {
;     __syncthreads();
;     G_COMPUTE(kt & 1, kt);
;   }
	s_waitcnt vmcnt(7)
	ds_write_b128 v192, v[194:197]
	s_waitcnt vmcnt(6)
	ds_write_b128 v159, v[198:201]
	ds_read_b128 v[194:197], v152 offset:36864
	ds_read_b128 v[198:201], v152 offset:41472
	v_mfma_f32_32x32x16_bf16 v[32:47], v[184:187], v[208:211], v[32:47]
	v_mfma_f32_32x32x16_bf16 v[48:63], v[188:191], v[208:211], v[48:63]
	ds_read_b128 v[208:211], v151
	v_mfma_f32_32x32x16_bf16 v[0:15], v[184:187], v[212:215], v[0:15]
	v_mfma_f32_32x32x16_bf16 v[16:31], v[188:191], v[212:215], v[16:31]
	ds_read_b128 v[212:215], v151 offset:4608
	s_setprio 0
	global_load_dwordx4 v[184:187], v[136:137], off offset:2816
	global_load_dwordx4 v[188:191], v[138:139], off offset:2816
	s_setprio 1
	s_waitcnt lgkmcnt(1)
	v_mfma_f32_32x32x16_bf16 v[96:111], v[194:197], v[208:211], v[96:111]
	v_mfma_f32_32x32x16_bf16 v[112:127], v[198:201], v[208:211], v[112:127]
	s_waitcnt lgkmcnt(0)
	v_mfma_f32_32x32x16_bf16 v[64:79], v[194:197], v[212:215], v[64:79]
	v_mfma_f32_32x32x16_bf16 v[80:95], v[198:201], v[212:215], v[80:95]
	ds_read_b128 v[208:211], v151 offset:9216
	ds_read_b128 v[212:215], v151 offset:13824
	s_waitcnt vmcnt(7)
	ds_write_b128 v158, v[176:179]
	s_waitcnt vmcnt(6)
	ds_write_b128 v157, v[180:183]
	ds_read_b128 v[176:179], v152 offset:36896
	ds_read_b128 v[180:183], v152 offset:41504
	s_waitcnt lgkmcnt(5)
	v_mfma_f32_32x32x16_bf16 v[32:47], v[194:197], v[208:211], v[32:47]
	v_mfma_f32_32x32x16_bf16 v[48:63], v[198:201], v[208:211], v[48:63]
	ds_read_b128 v[208:211], v151 offset:32
	s_waitcnt lgkmcnt(5)
	v_mfma_f32_32x32x16_bf16 v[0:15], v[194:197], v[212:215], v[0:15]
	v_mfma_f32_32x32x16_bf16 v[16:31], v[198:201], v[212:215], v[16:31]
	ds_read_b128 v[212:215], v151 offset:4640
	s_setprio 0
	global_load_dwordx4 v[194:197], v[140:141], off offset:2816
	global_load_dwordx4 v[198:201], v[142:143], off offset:2816
	s_setprio 1
	s_waitcnt lgkmcnt(1)
	v_mfma_f32_32x32x16_bf16 v[96:111], v[176:179], v[208:211], v[96:111]
	v_mfma_f32_32x32x16_bf16 v[112:127], v[180:183], v[208:211], v[112:127]
	s_waitcnt lgkmcnt(0)
	v_mfma_f32_32x32x16_bf16 v[64:79], v[176:179], v[212:215], v[64:79]
	v_mfma_f32_32x32x16_bf16 v[80:95], v[180:183], v[212:215], v[80:95]
	ds_read_b128 v[208:211], v151 offset:9248
	ds_read_b128 v[212:215], v151 offset:13856
	s_waitcnt vmcnt(7)
	ds_write_b128 v154, v[168:171]
	s_waitcnt vmcnt(6)
	ds_write_b128 v153, v[172:175]
	ds_read_b128 v[168:171], v152 offset:36928
	ds_read_b128 v[172:175], v152 offset:41536
	s_waitcnt lgkmcnt(5)
	v_mfma_f32_32x32x16_bf16 v[32:47], v[176:179], v[208:211], v[32:47]
	v_mfma_f32_32x32x16_bf16 v[48:63], v[180:183], v[208:211], v[48:63]
	ds_read_b128 v[208:211], v151 offset:64
	s_waitcnt lgkmcnt(5)
	v_mfma_f32_32x32x16_bf16 v[0:15], v[176:179], v[212:215], v[0:15]
	v_mfma_f32_32x32x16_bf16 v[16:31], v[180:183], v[212:215], v[16:31]
	ds_read_b128 v[212:215], v151 offset:4672
	s_setprio 0
	global_load_dwordx4 v[176:179], v[132:133], off offset:2816
	global_load_dwordx4 v[180:183], v[134:135], off offset:2816
	s_setprio 1
	s_waitcnt lgkmcnt(1)
	v_mfma_f32_32x32x16_bf16 v[96:111], v[168:171], v[208:211], v[96:111]
	v_mfma_f32_32x32x16_bf16 v[112:127], v[172:175], v[208:211], v[112:127]
	s_waitcnt lgkmcnt(0)
	v_mfma_f32_32x32x16_bf16 v[64:79], v[168:171], v[212:215], v[64:79]
	v_mfma_f32_32x32x16_bf16 v[80:95], v[172:175], v[212:215], v[80:95]
	ds_read_b128 v[208:211], v151 offset:9280
	ds_read_b128 v[212:215], v151 offset:13888
	s_waitcnt vmcnt(7)
	ds_write_b128 v156, v[160:163]
	s_waitcnt vmcnt(6)
	ds_write_b128 v155, v[164:167]
	ds_read_b128 v[160:163], v152 offset:36960
	ds_read_b128 v[164:167], v152 offset:41568
	s_waitcnt lgkmcnt(5)
	v_mfma_f32_32x32x16_bf16 v[32:47], v[168:171], v[208:211], v[32:47]
	v_mfma_f32_32x32x16_bf16 v[48:63], v[172:175], v[208:211], v[48:63]
	ds_read_b128 v[208:211], v151 offset:96
	s_waitcnt lgkmcnt(5)
	v_mfma_f32_32x32x16_bf16 v[0:15], v[168:171], v[212:215], v[0:15]
	v_mfma_f32_32x32x16_bf16 v[16:31], v[172:175], v[212:215], v[16:31]
	ds_read_b128 v[212:215], v151 offset:4704
	s_setprio 0
	global_load_dwordx4 v[168:171], v[144:145], off offset:2816
	global_load_dwordx4 v[172:175], v[146:147], off offset:2816
	s_setprio 1
	s_waitcnt lgkmcnt(1)
	v_mfma_f32_32x32x16_bf16 v[96:111], v[160:163], v[208:211], v[96:111]
	v_mfma_f32_32x32x16_bf16 v[112:127], v[164:167], v[208:211], v[112:127]
	s_waitcnt lgkmcnt(0)
	v_mfma_f32_32x32x16_bf16 v[64:79], v[160:163], v[212:215], v[64:79]
	v_mfma_f32_32x32x16_bf16 v[80:95], v[164:167], v[212:215], v[80:95]
	ds_read_b128 v[208:211], v151 offset:9312
	ds_read_b128 v[212:215], v151 offset:13920
	s_waitcnt lgkmcnt(0)
	s_barrier
; template <bool trans>
; DI void gemm_core(const GTile& tl, const GTile& nx, bool has_next  , bool chain  , bool pre, u32x4 (&ra)[4], u32x4 (&rb)[4], char* smem, f32x16 (&acc)[2][4]) {
;     ...
;   const int nk = K / 64;
;   if (!pre) { G_LOAD(0); G_STORE(0); G_LOAD(1); }
;   for (int kt = 0; kt < nk; ++kt) {
;     __syncthreads();
;     G_COMPUTE(kt & 1, kt);
;   }
	s_waitcnt vmcnt(7)
	ds_write_b128 v148, v[184:187]
	s_waitcnt vmcnt(6)
	ds_write_b128 v148, v[188:191] offset:36864
	ds_read_b128 v[184:187], v150
	ds_read_b128 v[188:191], v150 offset:4608
	v_mfma_f32_32x32x16_bf16 v[32:47], v[160:163], v[208:211], v[32:47]
	v_mfma_f32_32x32x16_bf16 v[48:63], v[164:167], v[208:211], v[48:63]
	ds_read_b128 v[208:211], v149
	v_mfma_f32_32x32x16_bf16 v[0:15], v[160:163], v[212:215], v[0:15]
	v_mfma_f32_32x32x16_bf16 v[16:31], v[164:167], v[212:215], v[16:31]
	ds_read_b128 v[212:215], v149 offset:4608
	s_setprio 0
	global_load_dwordx4 v[160:163], v[136:137], off offset:2944
	global_load_dwordx4 v[164:167], v[138:139], off offset:2944
	s_setprio 1
	s_waitcnt lgkmcnt(1)
	v_mfma_f32_32x32x16_bf16 v[96:111], v[184:187], v[208:211], v[96:111]
	v_mfma_f32_32x32x16_bf16 v[112:127], v[188:191], v[208:211], v[112:127]
	s_waitcnt lgkmcnt(0)
	v_mfma_f32_32x32x16_bf16 v[64:79], v[184:187], v[212:215], v[64:79]
	v_mfma_f32_32x32x16_bf16 v[80:95], v[188:191], v[212:215], v[80:95]
	ds_read_b128 v[208:211], v149 offset:9216
	ds_read_b128 v[212:215], v149 offset:13824
	s_waitcnt vmcnt(7)
	ds_write_b128 v148, v[194:197] offset:9216
	s_waitcnt vmcnt(6)
	ds_write_b128 v148, v[198:201] offset:46080
	ds_read_b128 v[194:197], v150 offset:32
	ds_read_b128 v[198:201], v150 offset:4640
	s_waitcnt lgkmcnt(5)
	v_mfma_f32_32x32x16_bf16 v[32:47], v[184:187], v[208:211], v[32:47]
	v_mfma_f32_32x32x16_bf16 v[48:63], v[188:191], v[208:211], v[48:63]
	ds_read_b128 v[208:211], v149 offset:32
	s_waitcnt lgkmcnt(5)
	v_mfma_f32_32x32x16_bf16 v[0:15], v[184:187], v[212:215], v[0:15]
	v_mfma_f32_32x32x16_bf16 v[16:31], v[188:191], v[212:215], v[16:31]
	ds_read_b128 v[212:215], v149 offset:4640
	s_setprio 0
	global_load_dwordx4 v[184:187], v[140:141], off offset:2944
	global_load_dwordx4 v[188:191], v[142:143], off offset:2944
	s_setprio 1
	s_waitcnt lgkmcnt(1)
	v_mfma_f32_32x32x16_bf16 v[96:111], v[194:197], v[208:211], v[96:111]
	v_mfma_f32_32x32x16_bf16 v[112:127], v[198:201], v[208:211], v[112:127]
	s_waitcnt lgkmcnt(0)
	v_mfma_f32_32x32x16_bf16 v[64:79], v[194:197], v[212:215], v[64:79]
	v_mfma_f32_32x32x16_bf16 v[80:95], v[198:201], v[212:215], v[80:95]
	ds_read_b128 v[208:211], v149 offset:9248
	ds_read_b128 v[212:215], v149 offset:13856
	s_waitcnt vmcnt(7)
	ds_write_b128 v148, v[176:179] offset:18432
	s_waitcnt vmcnt(6)
	ds_write_b128 v148, v[180:183] offset:55296
	ds_read_b128 v[176:179], v150 offset:64
	ds_read_b128 v[180:183], v150 offset:4672
	s_waitcnt lgkmcnt(5)
	v_mfma_f32_32x32x16_bf16 v[32:47], v[194:197], v[208:211], v[32:47]
	v_mfma_f32_32x32x16_bf16 v[48:63], v[198:201], v[208:211], v[48:63]
	ds_read_b128 v[208:211], v149 offset:64
	s_waitcnt lgkmcnt(5)
	v_mfma_f32_32x32x16_bf16 v[0:15], v[194:197], v[212:215], v[0:15]
	v_mfma_f32_32x32x16_bf16 v[16:31], v[198:201], v[212:215], v[16:31]
	ds_read_b128 v[212:215], v149 offset:4672
	s_setprio 0
	global_load_dwordx4 v[194:197], v[132:133], off offset:2944
	global_load_dwordx4 v[198:201], v[134:135], off offset:2944
	s_setprio 1
	s_waitcnt lgkmcnt(1)
	v_mfma_f32_32x32x16_bf16 v[96:111], v[176:179], v[208:211], v[96:111]
	v_mfma_f32_32x32x16_bf16 v[112:127], v[180:183], v[208:211], v[112:127]
	s_waitcnt lgkmcnt(0)
	v_mfma_f32_32x32x16_bf16 v[64:79], v[176:179], v[212:215], v[64:79]
	v_mfma_f32_32x32x16_bf16 v[80:95], v[180:183], v[212:215], v[80:95]
	ds_read_b128 v[208:211], v149 offset:9280
	ds_read_b128 v[212:215], v149 offset:13888
	s_waitcnt vmcnt(7)
	ds_write_b128 v148, v[168:171] offset:27648
	s_waitcnt vmcnt(6)
	ds_write_b128 v148, v[172:175] offset:64512
	ds_read_b128 v[168:171], v150 offset:96
	ds_read_b128 v[172:175], v150 offset:4704
	s_waitcnt lgkmcnt(5)
	v_mfma_f32_32x32x16_bf16 v[32:47], v[176:179], v[208:211], v[32:47]
	v_mfma_f32_32x32x16_bf16 v[48:63], v[180:183], v[208:211], v[48:63]
	ds_read_b128 v[208:211], v149 offset:96
	s_waitcnt lgkmcnt(5)
	v_mfma_f32_32x32x16_bf16 v[0:15], v[176:179], v[212:215], v[0:15]
	v_mfma_f32_32x32x16_bf16 v[16:31], v[180:183], v[212:215], v[16:31]
	ds_read_b128 v[212:215], v149 offset:4704
	s_setprio 0
	global_load_dwordx4 v[176:179], v[144:145], off offset:2944
	global_load_dwordx4 v[180:183], v[146:147], off offset:2944
	s_setprio 1
	s_waitcnt lgkmcnt(1)
	v_mfma_f32_32x32x16_bf16 v[96:111], v[168:171], v[208:211], v[96:111]
	v_mfma_f32_32x32x16_bf16 v[112:127], v[172:175], v[208:211], v[112:127]
	s_waitcnt lgkmcnt(0)
	v_mfma_f32_32x32x16_bf16 v[64:79], v[168:171], v[212:215], v[64:79]
	v_mfma_f32_32x32x16_bf16 v[80:95], v[172:175], v[212:215], v[80:95]
	ds_read_b128 v[208:211], v149 offset:9312
	ds_read_b128 v[212:215], v149 offset:13920
	s_waitcnt lgkmcnt(0)
	s_barrier
; template <bool trans>
; DI void gemm_core(const GTile& tl, const GTile& nx, bool has_next  , bool chain  , bool pre, u32x4 (&ra)[4], u32x4 (&rb)[4], char* smem, f32x16 (&acc)[2][4]) {
;     ...
;   const int nk = K / 64;
;   if (!pre) { G_LOAD(0); G_STORE(0); G_LOAD(1); }
;   for (int kt = 0; kt < nk; ++kt) {
;     __syncthreads();
;     G_COMPUTE(kt & 1, kt);
;   }
	s_waitcnt vmcnt(7)
	ds_write_b128 v192, v[160:163]
	s_waitcnt vmcnt(6)
	ds_write_b128 v159, v[164:167]
	ds_read_b128 v[160:163], v152 offset:36864
	ds_read_b128 v[164:167], v152 offset:41472
	v_mfma_f32_32x32x16_bf16 v[32:47], v[168:171], v[208:211], v[32:47]
	v_mfma_f32_32x32x16_bf16 v[48:63], v[172:175], v[208:211], v[48:63]
	ds_read_b128 v[208:211], v151
	v_mfma_f32_32x32x16_bf16 v[0:15], v[168:171], v[212:215], v[0:15]
	v_mfma_f32_32x32x16_bf16 v[16:31], v[172:175], v[212:215], v[16:31]
	ds_read_b128 v[212:215], v151 offset:4608
	s_setprio 0
	global_load_dwordx4 v[168:171], v[136:137], off offset:3072
	global_load_dwordx4 v[172:175], v[138:139], off offset:3072
	s_setprio 1
	s_waitcnt lgkmcnt(1)
	v_mfma_f32_32x32x16_bf16 v[96:111], v[160:163], v[208:211], v[96:111]
	v_mfma_f32_32x32x16_bf16 v[112:127], v[164:167], v[208:211], v[112:127]
	s_waitcnt lgkmcnt(0)
	v_mfma_f32_32x32x16_bf16 v[64:79], v[160:163], v[212:215], v[64:79]
	v_mfma_f32_32x32x16_bf16 v[80:95], v[164:167], v[212:215], v[80:95]
	ds_read_b128 v[208:211], v151 offset:9216
	ds_read_b128 v[212:215], v151 offset:13824
	s_waitcnt vmcnt(7)
	ds_write_b128 v158, v[184:187]
	s_waitcnt vmcnt(6)
	ds_write_b128 v157, v[188:191]
	ds_read_b128 v[184:187], v152 offset:36896
	ds_read_b128 v[188:191], v152 offset:41504
	s_waitcnt lgkmcnt(5)
	v_mfma_f32_32x32x16_bf16 v[32:47], v[160:163], v[208:211], v[32:47]
	v_mfma_f32_32x32x16_bf16 v[48:63], v[164:167], v[208:211], v[48:63]
	ds_read_b128 v[208:211], v151 offset:32
	s_waitcnt lgkmcnt(5)
	v_mfma_f32_32x32x16_bf16 v[0:15], v[160:163], v[212:215], v[0:15]
	v_mfma_f32_32x32x16_bf16 v[16:31], v[164:167], v[212:215], v[16:31]
	ds_read_b128 v[212:215], v151 offset:4640
	s_setprio 0
	global_load_dwordx4 v[160:163], v[140:141], off offset:3072
	global_load_dwordx4 v[164:167], v[142:143], off offset:3072
	s_setprio 1
	s_waitcnt lgkmcnt(1)
	v_mfma_f32_32x32x16_bf16 v[96:111], v[184:187], v[208:211], v[96:111]
	v_mfma_f32_32x32x16_bf16 v[112:127], v[188:191], v[208:211], v[112:127]
	s_waitcnt lgkmcnt(0)
	v_mfma_f32_32x32x16_bf16 v[64:79], v[184:187], v[212:215], v[64:79]
	v_mfma_f32_32x32x16_bf16 v[80:95], v[188:191], v[212:215], v[80:95]
	ds_read_b128 v[208:211], v151 offset:9248
	ds_read_b128 v[212:215], v151 offset:13856
	s_waitcnt vmcnt(7)
	ds_write_b128 v154, v[194:197]
	s_waitcnt vmcnt(6)
	ds_write_b128 v153, v[198:201]
	ds_read_b128 v[194:197], v152 offset:36928
	ds_read_b128 v[198:201], v152 offset:41536
	s_waitcnt lgkmcnt(5)
	v_mfma_f32_32x32x16_bf16 v[32:47], v[184:187], v[208:211], v[32:47]
	v_mfma_f32_32x32x16_bf16 v[48:63], v[188:191], v[208:211], v[48:63]
	ds_read_b128 v[208:211], v151 offset:64
	s_waitcnt lgkmcnt(5)
	v_mfma_f32_32x32x16_bf16 v[0:15], v[184:187], v[212:215], v[0:15]
	v_mfma_f32_32x32x16_bf16 v[16:31], v[188:191], v[212:215], v[16:31]
	ds_read_b128 v[212:215], v151 offset:4672
	s_setprio 0
	global_load_dwordx4 v[184:187], v[132:133], off offset:3072
	global_load_dwordx4 v[188:191], v[134:135], off offset:3072
	s_setprio 1
	s_waitcnt lgkmcnt(1)
	v_mfma_f32_32x32x16_bf16 v[96:111], v[194:197], v[208:211], v[96:111]
	v_mfma_f32_32x32x16_bf16 v[112:127], v[198:201], v[208:211], v[112:127]
	s_waitcnt lgkmcnt(0)
	v_mfma_f32_32x32x16_bf16 v[64:79], v[194:197], v[212:215], v[64:79]
	v_mfma_f32_32x32x16_bf16 v[80:95], v[198:201], v[212:215], v[80:95]
	ds_read_b128 v[208:211], v151 offset:9280
	ds_read_b128 v[212:215], v151 offset:13888
	s_waitcnt vmcnt(7)
	ds_write_b128 v156, v[176:179]
	s_waitcnt vmcnt(6)
	ds_write_b128 v155, v[180:183]
	ds_read_b128 v[176:179], v152 offset:36960
	ds_read_b128 v[180:183], v152 offset:41568
	s_waitcnt lgkmcnt(5)
	v_mfma_f32_32x32x16_bf16 v[32:47], v[194:197], v[208:211], v[32:47]
	v_mfma_f32_32x32x16_bf16 v[48:63], v[198:201], v[208:211], v[48:63]
	ds_read_b128 v[208:211], v151 offset:96
	s_waitcnt lgkmcnt(5)
	v_mfma_f32_32x32x16_bf16 v[0:15], v[194:197], v[212:215], v[0:15]
	v_mfma_f32_32x32x16_bf16 v[16:31], v[198:201], v[212:215], v[16:31]
	ds_read_b128 v[212:215], v151 offset:4704
	s_setprio 0
	global_load_dwordx4 v[194:197], v[144:145], off offset:3072
	global_load_dwordx4 v[198:201], v[146:147], off offset:3072
	s_setprio 1
	s_waitcnt lgkmcnt(1)
	v_mfma_f32_32x32x16_bf16 v[96:111], v[176:179], v[208:211], v[96:111]
	v_mfma_f32_32x32x16_bf16 v[112:127], v[180:183], v[208:211], v[112:127]
	s_waitcnt lgkmcnt(0)
	v_mfma_f32_32x32x16_bf16 v[64:79], v[176:179], v[212:215], v[64:79]
	v_mfma_f32_32x32x16_bf16 v[80:95], v[180:183], v[212:215], v[80:95]
	ds_read_b128 v[208:211], v151 offset:9312
	ds_read_b128 v[212:215], v151 offset:13920
	s_waitcnt lgkmcnt(0)
	s_barrier
; template <bool trans>
; DI void gemm_core(const GTile& tl, const GTile& nx, bool has_next  , bool chain  , bool pre, u32x4 (&ra)[4], u32x4 (&rb)[4], char* smem, f32x16 (&acc)[2][4]) {
;     ...
;   const int nk = K / 64;
;   if (!pre) { G_LOAD(0); G_STORE(0); G_LOAD(1); }
;   for (int kt = 0; kt < nk; ++kt) {
;     __syncthreads();
;     G_COMPUTE(kt & 1, kt);
;   }
	s_waitcnt vmcnt(7)
	ds_write_b128 v148, v[168:171]
	s_waitcnt vmcnt(6)
	ds_write_b128 v148, v[172:175] offset:36864
	ds_read_b128 v[168:171], v150
	ds_read_b128 v[172:175], v150 offset:4608
	v_mfma_f32_32x32x16_bf16 v[32:47], v[176:179], v[208:211], v[32:47]
	v_mfma_f32_32x32x16_bf16 v[48:63], v[180:183], v[208:211], v[48:63]
	ds_read_b128 v[208:211], v149
	v_mfma_f32_32x32x16_bf16 v[0:15], v[176:179], v[212:215], v[0:15]
	v_mfma_f32_32x32x16_bf16 v[16:31], v[180:183], v[212:215], v[16:31]
	ds_read_b128 v[212:215], v149 offset:4608
	s_setprio 0
	global_load_dwordx4 v[176:179], v[136:137], off offset:3200
	global_load_dwordx4 v[180:183], v[138:139], off offset:3200
	s_setprio 1
	s_waitcnt lgkmcnt(1)
	v_mfma_f32_32x32x16_bf16 v[96:111], v[168:171], v[208:211], v[96:111]
	v_mfma_f32_32x32x16_bf16 v[112:127], v[172:175], v[208:211], v[112:127]
	s_waitcnt lgkmcnt(0)
	v_mfma_f32_32x32x16_bf16 v[64:79], v[168:171], v[212:215], v[64:79]
	v_mfma_f32_32x32x16_bf16 v[80:95], v[172:175], v[212:215], v[80:95]
	ds_read_b128 v[208:211], v149 offset:9216
	ds_read_b128 v[212:215], v149 offset:13824
	s_waitcnt vmcnt(7)
	ds_write_b128 v148, v[160:163] offset:9216
	s_waitcnt vmcnt(6)
	ds_write_b128 v148, v[164:167] offset:46080
	ds_read_b128 v[160:163], v150 offset:32
	ds_read_b128 v[164:167], v150 offset:4640
	s_waitcnt lgkmcnt(5)
	v_mfma_f32_32x32x16_bf16 v[32:47], v[168:171], v[208:211], v[32:47]
	v_mfma_f32_32x32x16_bf16 v[48:63], v[172:175], v[208:211], v[48:63]
	ds_read_b128 v[208:211], v149 offset:32
	s_waitcnt lgkmcnt(5)
	v_mfma_f32_32x32x16_bf16 v[0:15], v[168:171], v[212:215], v[0:15]
	v_mfma_f32_32x32x16_bf16 v[16:31], v[172:175], v[212:215], v[16:31]
	ds_read_b128 v[212:215], v149 offset:4640
	s_setprio 0
	global_load_dwordx4 v[168:171], v[140:141], off offset:3200
	global_load_dwordx4 v[172:175], v[142:143], off offset:3200
	s_setprio 1
	s_waitcnt lgkmcnt(1)
	v_mfma_f32_32x32x16_bf16 v[96:111], v[160:163], v[208:211], v[96:111]
	v_mfma_f32_32x32x16_bf16 v[112:127], v[164:167], v[208:211], v[112:127]
	s_waitcnt lgkmcnt(0)
	v_mfma_f32_32x32x16_bf16 v[64:79], v[160:163], v[212:215], v[64:79]
	v_mfma_f32_32x32x16_bf16 v[80:95], v[164:167], v[212:215], v[80:95]
	ds_read_b128 v[208:211], v149 offset:9248
	ds_read_b128 v[212:215], v149 offset:13856
	s_waitcnt vmcnt(7)
	ds_write_b128 v148, v[184:187] offset:18432
	s_waitcnt vmcnt(6)
	ds_write_b128 v148, v[188:191] offset:55296
	ds_read_b128 v[184:187], v150 offset:64
	ds_read_b128 v[188:191], v150 offset:4672
	s_waitcnt lgkmcnt(5)
	v_mfma_f32_32x32x16_bf16 v[32:47], v[160:163], v[208:211], v[32:47]
	v_mfma_f32_32x32x16_bf16 v[48:63], v[164:167], v[208:211], v[48:63]
	ds_read_b128 v[208:211], v149 offset:64
	s_waitcnt lgkmcnt(5)
	v_mfma_f32_32x32x16_bf16 v[0:15], v[160:163], v[212:215], v[0:15]
	v_mfma_f32_32x32x16_bf16 v[16:31], v[164:167], v[212:215], v[16:31]
	ds_read_b128 v[212:215], v149 offset:4672
	s_setprio 0
	global_load_dwordx4 v[160:163], v[132:133], off offset:3200
	global_load_dwordx4 v[164:167], v[134:135], off offset:3200
	s_setprio 1
	s_waitcnt lgkmcnt(1)
	v_mfma_f32_32x32x16_bf16 v[96:111], v[184:187], v[208:211], v[96:111]
	v_mfma_f32_32x32x16_bf16 v[112:127], v[188:191], v[208:211], v[112:127]
	s_waitcnt lgkmcnt(0)
	v_mfma_f32_32x32x16_bf16 v[64:79], v[184:187], v[212:215], v[64:79]
	v_mfma_f32_32x32x16_bf16 v[80:95], v[188:191], v[212:215], v[80:95]
	ds_read_b128 v[208:211], v149 offset:9280
	ds_read_b128 v[212:215], v149 offset:13888
	s_waitcnt vmcnt(7)
	ds_write_b128 v148, v[194:197] offset:27648
	s_waitcnt vmcnt(6)
	ds_write_b128 v148, v[198:201] offset:64512
	ds_read_b128 v[194:197], v150 offset:96
	ds_read_b128 v[198:201], v150 offset:4704
	s_waitcnt lgkmcnt(5)
	v_mfma_f32_32x32x16_bf16 v[32:47], v[184:187], v[208:211], v[32:47]
	v_mfma_f32_32x32x16_bf16 v[48:63], v[188:191], v[208:211], v[48:63]
	ds_read_b128 v[208:211], v149 offset:96
	s_waitcnt lgkmcnt(5)
	v_mfma_f32_32x32x16_bf16 v[0:15], v[184:187], v[212:215], v[0:15]
	v_mfma_f32_32x32x16_bf16 v[16:31], v[188:191], v[212:215], v[16:31]
	ds_read_b128 v[212:215], v149 offset:4704
	s_setprio 0
	global_load_dwordx4 v[184:187], v[144:145], off offset:3200
	global_load_dwordx4 v[188:191], v[146:147], off offset:3200
	s_setprio 1
	s_waitcnt lgkmcnt(1)
	v_mfma_f32_32x32x16_bf16 v[96:111], v[194:197], v[208:211], v[96:111]
	v_mfma_f32_32x32x16_bf16 v[112:127], v[198:201], v[208:211], v[112:127]
	s_waitcnt lgkmcnt(0)
	v_mfma_f32_32x32x16_bf16 v[64:79], v[194:197], v[212:215], v[64:79]
	v_mfma_f32_32x32x16_bf16 v[80:95], v[198:201], v[212:215], v[80:95]
	ds_read_b128 v[208:211], v149 offset:9312
	ds_read_b128 v[212:215], v149 offset:13920
	s_waitcnt lgkmcnt(0)
	s_barrier
; template <bool trans>
; DI void gemm_core(const GTile& tl, const GTile& nx, bool has_next  , bool chain  , bool pre, u32x4 (&ra)[4], u32x4 (&rb)[4], char* smem, f32x16 (&acc)[2][4]) {
;     ...
;   const int nk = K / 64;
;   if (!pre) { G_LOAD(0); G_STORE(0); G_LOAD(1); }
;   for (int kt = 0; kt < nk; ++kt) {
;     __syncthreads();
;     G_COMPUTE(kt & 1, kt);
;   }
	s_waitcnt vmcnt(7)
	ds_write_b128 v192, v[176:179]
	s_waitcnt vmcnt(6)
	ds_write_b128 v159, v[180:183]
	ds_read_b128 v[176:179], v152 offset:36864
	ds_read_b128 v[180:183], v152 offset:41472
	v_mfma_f32_32x32x16_bf16 v[32:47], v[194:197], v[208:211], v[32:47]
	v_mfma_f32_32x32x16_bf16 v[48:63], v[198:201], v[208:211], v[48:63]
	ds_read_b128 v[208:211], v151
	v_mfma_f32_32x32x16_bf16 v[0:15], v[194:197], v[212:215], v[0:15]
	v_mfma_f32_32x32x16_bf16 v[16:31], v[198:201], v[212:215], v[16:31]
	ds_read_b128 v[212:215], v151 offset:4608
	s_setprio 0
	global_load_dwordx4 v[194:197], v[136:137], off offset:3328
	global_load_dwordx4 v[198:201], v[138:139], off offset:3328
	s_setprio 1
	s_waitcnt lgkmcnt(1)
	v_mfma_f32_32x32x16_bf16 v[96:111], v[176:179], v[208:211], v[96:111]
	v_mfma_f32_32x32x16_bf16 v[112:127], v[180:183], v[208:211], v[112:127]
	s_waitcnt lgkmcnt(0)
	v_mfma_f32_32x32x16_bf16 v[64:79], v[176:179], v[212:215], v[64:79]
	v_mfma_f32_32x32x16_bf16 v[80:95], v[180:183], v[212:215], v[80:95]
	ds_read_b128 v[208:211], v151 offset:9216
	ds_read_b128 v[212:215], v151 offset:13824
	s_waitcnt vmcnt(7)
	ds_write_b128 v158, v[168:171]
	s_waitcnt vmcnt(6)
	ds_write_b128 v157, v[172:175]
	ds_read_b128 v[168:171], v152 offset:36896
	ds_read_b128 v[172:175], v152 offset:41504
	s_waitcnt lgkmcnt(5)
	v_mfma_f32_32x32x16_bf16 v[32:47], v[176:179], v[208:211], v[32:47]
	v_mfma_f32_32x32x16_bf16 v[48:63], v[180:183], v[208:211], v[48:63]
	ds_read_b128 v[208:211], v151 offset:32
	s_waitcnt lgkmcnt(5)
	v_mfma_f32_32x32x16_bf16 v[0:15], v[176:179], v[212:215], v[0:15]
	v_mfma_f32_32x32x16_bf16 v[16:31], v[180:183], v[212:215], v[16:31]
	ds_read_b128 v[212:215], v151 offset:4640
	s_setprio 0
	global_load_dwordx4 v[176:179], v[140:141], off offset:3328
	global_load_dwordx4 v[180:183], v[142:143], off offset:3328
	s_setprio 1
	s_waitcnt lgkmcnt(1)
	v_mfma_f32_32x32x16_bf16 v[96:111], v[168:171], v[208:211], v[96:111]
	v_mfma_f32_32x32x16_bf16 v[112:127], v[172:175], v[208:211], v[112:127]
	s_waitcnt lgkmcnt(0)
	v_mfma_f32_32x32x16_bf16 v[64:79], v[168:171], v[212:215], v[64:79]
	v_mfma_f32_32x32x16_bf16 v[80:95], v[172:175], v[212:215], v[80:95]
	ds_read_b128 v[208:211], v151 offset:9248
	ds_read_b128 v[212:215], v151 offset:13856
	s_waitcnt vmcnt(7)
	ds_write_b128 v154, v[160:163]
	s_waitcnt vmcnt(6)
	ds_write_b128 v153, v[164:167]
	ds_read_b128 v[160:163], v152 offset:36928
	ds_read_b128 v[164:167], v152 offset:41536
	s_waitcnt lgkmcnt(5)
	v_mfma_f32_32x32x16_bf16 v[32:47], v[168:171], v[208:211], v[32:47]
	v_mfma_f32_32x32x16_bf16 v[48:63], v[172:175], v[208:211], v[48:63]
	ds_read_b128 v[208:211], v151 offset:64
	s_waitcnt lgkmcnt(5)
	v_mfma_f32_32x32x16_bf16 v[0:15], v[168:171], v[212:215], v[0:15]
	v_mfma_f32_32x32x16_bf16 v[16:31], v[172:175], v[212:215], v[16:31]
	ds_read_b128 v[212:215], v151 offset:4672
	s_setprio 0
	global_load_dwordx4 v[168:171], v[132:133], off offset:3328
	global_load_dwordx4 v[172:175], v[134:135], off offset:3328
	s_setprio 1
	s_waitcnt lgkmcnt(1)
	v_mfma_f32_32x32x16_bf16 v[96:111], v[160:163], v[208:211], v[96:111]
	v_mfma_f32_32x32x16_bf16 v[112:127], v[164:167], v[208:211], v[112:127]
	s_waitcnt lgkmcnt(0)
	v_mfma_f32_32x32x16_bf16 v[64:79], v[160:163], v[212:215], v[64:79]
	v_mfma_f32_32x32x16_bf16 v[80:95], v[164:167], v[212:215], v[80:95]
	ds_read_b128 v[208:211], v151 offset:9280
	ds_read_b128 v[212:215], v151 offset:13888
	s_waitcnt vmcnt(7)
	ds_write_b128 v156, v[184:187]
	s_waitcnt vmcnt(6)
	ds_write_b128 v155, v[188:191]
	ds_read_b128 v[184:187], v152 offset:36960
	ds_read_b128 v[188:191], v152 offset:41568
	s_waitcnt lgkmcnt(5)
	v_mfma_f32_32x32x16_bf16 v[32:47], v[160:163], v[208:211], v[32:47]
	v_mfma_f32_32x32x16_bf16 v[48:63], v[164:167], v[208:211], v[48:63]
	ds_read_b128 v[208:211], v151 offset:96
	s_waitcnt lgkmcnt(5)
	v_mfma_f32_32x32x16_bf16 v[0:15], v[160:163], v[212:215], v[0:15]
	v_mfma_f32_32x32x16_bf16 v[16:31], v[164:167], v[212:215], v[16:31]
	ds_read_b128 v[212:215], v151 offset:4704
	s_setprio 0
	global_load_dwordx4 v[160:163], v[144:145], off offset:3328
	global_load_dwordx4 v[164:167], v[146:147], off offset:3328
	s_setprio 1
	s_waitcnt lgkmcnt(1)
	v_mfma_f32_32x32x16_bf16 v[96:111], v[184:187], v[208:211], v[96:111]
	v_mfma_f32_32x32x16_bf16 v[112:127], v[188:191], v[208:211], v[112:127]
	s_waitcnt lgkmcnt(0)
	v_mfma_f32_32x32x16_bf16 v[64:79], v[184:187], v[212:215], v[64:79]
	v_mfma_f32_32x32x16_bf16 v[80:95], v[188:191], v[212:215], v[80:95]
	ds_read_b128 v[208:211], v151 offset:9312
	ds_read_b128 v[212:215], v151 offset:13920
	s_waitcnt lgkmcnt(0)
	s_barrier
; template <bool trans>
; DI void gemm_core(const GTile& tl, const GTile& nx, bool has_next  , bool chain  , bool pre, u32x4 (&ra)[4], u32x4 (&rb)[4], char* smem, f32x16 (&acc)[2][4]) {
;     ...
;   const int nk = K / 64;
;   if (!pre) { G_LOAD(0); G_STORE(0); G_LOAD(1); }
;   for (int kt = 0; kt < nk; ++kt) {
;     __syncthreads();
;     G_COMPUTE(kt & 1, kt);
;   }
	s_waitcnt vmcnt(7)
	ds_write_b128 v148, v[194:197]
	s_waitcnt vmcnt(6)
	ds_write_b128 v148, v[198:201] offset:36864
	ds_read_b128 v[194:197], v150
	ds_read_b128 v[198:201], v150 offset:4608
	v_mfma_f32_32x32x16_bf16 v[32:47], v[184:187], v[208:211], v[32:47]
	v_mfma_f32_32x32x16_bf16 v[48:63], v[188:191], v[208:211], v[48:63]
	ds_read_b128 v[208:211], v149
	v_mfma_f32_32x32x16_bf16 v[0:15], v[184:187], v[212:215], v[0:15]
	v_mfma_f32_32x32x16_bf16 v[16:31], v[188:191], v[212:215], v[16:31]
	ds_read_b128 v[212:215], v149 offset:4608
	s_setprio 0
	global_load_dwordx4 v[184:187], v[136:137], off offset:3456
	global_load_dwordx4 v[188:191], v[138:139], off offset:3456
	s_setprio 1
	s_waitcnt lgkmcnt(1)
	v_mfma_f32_32x32x16_bf16 v[96:111], v[194:197], v[208:211], v[96:111]
	v_mfma_f32_32x32x16_bf16 v[112:127], v[198:201], v[208:211], v[112:127]
	s_waitcnt lgkmcnt(0)
	v_mfma_f32_32x32x16_bf16 v[64:79], v[194:197], v[212:215], v[64:79]
	v_mfma_f32_32x32x16_bf16 v[80:95], v[198:201], v[212:215], v[80:95]
	ds_read_b128 v[208:211], v149 offset:9216
	ds_read_b128 v[212:215], v149 offset:13824
	s_waitcnt vmcnt(7)
	ds_write_b128 v148, v[176:179] offset:9216
	s_waitcnt vmcnt(6)
	ds_write_b128 v148, v[180:183] offset:46080
	ds_read_b128 v[176:179], v150 offset:32
	ds_read_b128 v[180:183], v150 offset:4640
	s_waitcnt lgkmcnt(5)
	v_mfma_f32_32x32x16_bf16 v[32:47], v[194:197], v[208:211], v[32:47]
	v_mfma_f32_32x32x16_bf16 v[48:63], v[198:201], v[208:211], v[48:63]
	ds_read_b128 v[208:211], v149 offset:32
	s_waitcnt lgkmcnt(5)
	v_mfma_f32_32x32x16_bf16 v[0:15], v[194:197], v[212:215], v[0:15]
	v_mfma_f32_32x32x16_bf16 v[16:31], v[198:201], v[212:215], v[16:31]
	ds_read_b128 v[212:215], v149 offset:4640
	s_setprio 0
	global_load_dwordx4 v[194:197], v[140:141], off offset:3456
	global_load_dwordx4 v[198:201], v[142:143], off offset:3456
	s_setprio 1
	s_waitcnt lgkmcnt(1)
	v_mfma_f32_32x32x16_bf16 v[96:111], v[176:179], v[208:211], v[96:111]
	v_mfma_f32_32x32x16_bf16 v[112:127], v[180:183], v[208:211], v[112:127]
	s_waitcnt lgkmcnt(0)
	v_mfma_f32_32x32x16_bf16 v[64:79], v[176:179], v[212:215], v[64:79]
	v_mfma_f32_32x32x16_bf16 v[80:95], v[180:183], v[212:215], v[80:95]
	ds_read_b128 v[208:211], v149 offset:9248
	ds_read_b128 v[212:215], v149 offset:13856
	s_waitcnt vmcnt(7)
	ds_write_b128 v148, v[168:171] offset:18432
	s_waitcnt vmcnt(6)
	ds_write_b128 v148, v[172:175] offset:55296
	ds_read_b128 v[168:171], v150 offset:64
	ds_read_b128 v[172:175], v150 offset:4672
	s_waitcnt lgkmcnt(5)
	v_mfma_f32_32x32x16_bf16 v[32:47], v[176:179], v[208:211], v[32:47]
	v_mfma_f32_32x32x16_bf16 v[48:63], v[180:183], v[208:211], v[48:63]
	ds_read_b128 v[208:211], v149 offset:64
	s_waitcnt lgkmcnt(5)
	v_mfma_f32_32x32x16_bf16 v[0:15], v[176:179], v[212:215], v[0:15]
	v_mfma_f32_32x32x16_bf16 v[16:31], v[180:183], v[212:215], v[16:31]
	ds_read_b128 v[212:215], v149 offset:4672
	s_setprio 0
	global_load_dwordx4 v[176:179], v[132:133], off offset:3456
	global_load_dwordx4 v[180:183], v[134:135], off offset:3456
	s_setprio 1
	s_waitcnt lgkmcnt(1)
	v_mfma_f32_32x32x16_bf16 v[96:111], v[168:171], v[208:211], v[96:111]
	v_mfma_f32_32x32x16_bf16 v[112:127], v[172:175], v[208:211], v[112:127]
	s_waitcnt lgkmcnt(0)
	v_mfma_f32_32x32x16_bf16 v[64:79], v[168:171], v[212:215], v[64:79]
	v_mfma_f32_32x32x16_bf16 v[80:95], v[172:175], v[212:215], v[80:95]
	ds_read_b128 v[208:211], v149 offset:9280
	ds_read_b128 v[212:215], v149 offset:13888
	s_waitcnt vmcnt(7)
	ds_write_b128 v148, v[160:163] offset:27648
	s_waitcnt vmcnt(6)
	ds_write_b128 v148, v[164:167] offset:64512
	ds_read_b128 v[160:163], v150 offset:96
	ds_read_b128 v[164:167], v150 offset:4704
	s_waitcnt lgkmcnt(5)
	v_mfma_f32_32x32x16_bf16 v[32:47], v[168:171], v[208:211], v[32:47]
	v_mfma_f32_32x32x16_bf16 v[48:63], v[172:175], v[208:211], v[48:63]
	ds_read_b128 v[208:211], v149 offset:96
	s_waitcnt lgkmcnt(5)
	v_mfma_f32_32x32x16_bf16 v[0:15], v[168:171], v[212:215], v[0:15]
	v_mfma_f32_32x32x16_bf16 v[16:31], v[172:175], v[212:215], v[16:31]
	ds_read_b128 v[212:215], v149 offset:4704
	s_setprio 0
	global_load_dwordx4 v[168:171], v[144:145], off offset:3456
	global_load_dwordx4 v[172:175], v[146:147], off offset:3456
	s_setprio 1
	s_waitcnt lgkmcnt(1)
	v_mfma_f32_32x32x16_bf16 v[96:111], v[160:163], v[208:211], v[96:111]
	v_mfma_f32_32x32x16_bf16 v[112:127], v[164:167], v[208:211], v[112:127]
	s_waitcnt lgkmcnt(0)
	v_mfma_f32_32x32x16_bf16 v[64:79], v[160:163], v[212:215], v[64:79]
	v_mfma_f32_32x32x16_bf16 v[80:95], v[164:167], v[212:215], v[80:95]
	ds_read_b128 v[208:211], v149 offset:9312
	ds_read_b128 v[212:215], v149 offset:13920
	s_waitcnt lgkmcnt(0)
	s_barrier
; template <bool trans>
; DI void gemm_core(const GTile& tl, const GTile& nx, bool has_next  , bool chain  , bool pre, u32x4 (&ra)[4], u32x4 (&rb)[4], char* smem, f32x16 (&acc)[2][4]) {
;     ...
;   const int nk = K / 64;
;   if (!pre) { G_LOAD(0); G_STORE(0); G_LOAD(1); }
;   for (int kt = 0; kt < nk; ++kt) {
;     __syncthreads();
;     G_COMPUTE(kt & 1, kt);
;   }
	s_waitcnt vmcnt(7)
	ds_write_b128 v192, v[184:187]
	s_waitcnt vmcnt(6)
	ds_write_b128 v159, v[188:191]
	ds_read_b128 v[184:187], v152 offset:36864
	ds_read_b128 v[188:191], v152 offset:41472
	v_mfma_f32_32x32x16_bf16 v[32:47], v[160:163], v[208:211], v[32:47]
	v_mfma_f32_32x32x16_bf16 v[48:63], v[164:167], v[208:211], v[48:63]
	ds_read_b128 v[208:211], v151
	v_mfma_f32_32x32x16_bf16 v[0:15], v[160:163], v[212:215], v[0:15]
	v_mfma_f32_32x32x16_bf16 v[16:31], v[164:167], v[212:215], v[16:31]
	ds_read_b128 v[212:215], v151 offset:4608
	s_setprio 0
	global_load_dwordx4 v[160:163], v[136:137], off offset:3584
	global_load_dwordx4 v[164:167], v[138:139], off offset:3584
	s_setprio 1
	s_waitcnt lgkmcnt(1)
	v_mfma_f32_32x32x16_bf16 v[96:111], v[184:187], v[208:211], v[96:111]
	v_mfma_f32_32x32x16_bf16 v[112:127], v[188:191], v[208:211], v[112:127]
	s_waitcnt lgkmcnt(0)
	v_mfma_f32_32x32x16_bf16 v[64:79], v[184:187], v[212:215], v[64:79]
	v_mfma_f32_32x32x16_bf16 v[80:95], v[188:191], v[212:215], v[80:95]
	ds_read_b128 v[208:211], v151 offset:9216
	ds_read_b128 v[212:215], v151 offset:13824
	s_waitcnt vmcnt(7)
	ds_write_b128 v158, v[194:197]
	s_waitcnt vmcnt(6)
	ds_write_b128 v157, v[198:201]
	ds_read_b128 v[194:197], v152 offset:36896
	ds_read_b128 v[198:201], v152 offset:41504
	s_waitcnt lgkmcnt(5)
	v_mfma_f32_32x32x16_bf16 v[32:47], v[184:187], v[208:211], v[32:47]
	v_mfma_f32_32x32x16_bf16 v[48:63], v[188:191], v[208:211], v[48:63]
	ds_read_b128 v[208:211], v151 offset:32
	s_waitcnt lgkmcnt(5)
	v_mfma_f32_32x32x16_bf16 v[0:15], v[184:187], v[212:215], v[0:15]
	v_mfma_f32_32x32x16_bf16 v[16:31], v[188:191], v[212:215], v[16:31]
	ds_read_b128 v[212:215], v151 offset:4640
	s_setprio 0
	global_load_dwordx4 v[184:187], v[140:141], off offset:3584
	global_load_dwordx4 v[188:191], v[142:143], off offset:3584
	s_setprio 1
	s_waitcnt lgkmcnt(1)
	v_mfma_f32_32x32x16_bf16 v[96:111], v[194:197], v[208:211], v[96:111]
	v_mfma_f32_32x32x16_bf16 v[112:127], v[198:201], v[208:211], v[112:127]
	s_waitcnt lgkmcnt(0)
	v_mfma_f32_32x32x16_bf16 v[64:79], v[194:197], v[212:215], v[64:79]
	v_mfma_f32_32x32x16_bf16 v[80:95], v[198:201], v[212:215], v[80:95]
	ds_read_b128 v[208:211], v151 offset:9248
	ds_read_b128 v[212:215], v151 offset:13856
	s_waitcnt vmcnt(7)
	ds_write_b128 v154, v[176:179]
	s_waitcnt vmcnt(6)
	ds_write_b128 v153, v[180:183]
	ds_read_b128 v[176:179], v152 offset:36928
	ds_read_b128 v[180:183], v152 offset:41536
	s_waitcnt lgkmcnt(5)
	v_mfma_f32_32x32x16_bf16 v[32:47], v[194:197], v[208:211], v[32:47]
	v_mfma_f32_32x32x16_bf16 v[48:63], v[198:201], v[208:211], v[48:63]
	ds_read_b128 v[208:211], v151 offset:64
	s_waitcnt lgkmcnt(5)
	v_mfma_f32_32x32x16_bf16 v[0:15], v[194:197], v[212:215], v[0:15]
	v_mfma_f32_32x32x16_bf16 v[16:31], v[198:201], v[212:215], v[16:31]
	ds_read_b128 v[212:215], v151 offset:4672
	s_setprio 0
	global_load_dwordx4 v[194:197], v[132:133], off offset:3584
	global_load_dwordx4 v[198:201], v[134:135], off offset:3584
	s_setprio 1
	s_waitcnt lgkmcnt(1)
	v_mfma_f32_32x32x16_bf16 v[96:111], v[176:179], v[208:211], v[96:111]
	v_mfma_f32_32x32x16_bf16 v[112:127], v[180:183], v[208:211], v[112:127]
	s_waitcnt lgkmcnt(0)
	v_mfma_f32_32x32x16_bf16 v[64:79], v[176:179], v[212:215], v[64:79]
	v_mfma_f32_32x32x16_bf16 v[80:95], v[180:183], v[212:215], v[80:95]
	ds_read_b128 v[208:211], v151 offset:9280
	ds_read_b128 v[212:215], v151 offset:13888
	s_waitcnt vmcnt(7)
	ds_write_b128 v156, v[168:171]
	s_waitcnt vmcnt(6)
	ds_write_b128 v155, v[172:175]
	ds_read_b128 v[168:171], v152 offset:36960
	ds_read_b128 v[172:175], v152 offset:41568
	s_waitcnt lgkmcnt(5)
	v_mfma_f32_32x32x16_bf16 v[32:47], v[176:179], v[208:211], v[32:47]
	v_mfma_f32_32x32x16_bf16 v[48:63], v[180:183], v[208:211], v[48:63]
	ds_read_b128 v[208:211], v151 offset:96
	s_waitcnt lgkmcnt(5)
	v_mfma_f32_32x32x16_bf16 v[0:15], v[176:179], v[212:215], v[0:15]
	v_mfma_f32_32x32x16_bf16 v[16:31], v[180:183], v[212:215], v[16:31]
	ds_read_b128 v[212:215], v151 offset:4704
	s_setprio 0
	global_load_dwordx4 v[176:179], v[144:145], off offset:3584
	global_load_dwordx4 v[180:183], v[146:147], off offset:3584
	s_setprio 1
	s_waitcnt lgkmcnt(1)
	v_mfma_f32_32x32x16_bf16 v[96:111], v[168:171], v[208:211], v[96:111]
	v_mfma_f32_32x32x16_bf16 v[112:127], v[172:175], v[208:211], v[112:127]
	s_waitcnt lgkmcnt(0)
	v_mfma_f32_32x32x16_bf16 v[64:79], v[168:171], v[212:215], v[64:79]
	v_mfma_f32_32x32x16_bf16 v[80:95], v[172:175], v[212:215], v[80:95]
	ds_read_b128 v[208:211], v151 offset:9312
	ds_read_b128 v[212:215], v151 offset:13920
	s_waitcnt lgkmcnt(0)
	s_barrier
; template <bool trans>
; DI void gemm_core(const GTile& tl, const GTile& nx, bool has_next  , bool chain  , bool pre, u32x4 (&ra)[4], u32x4 (&rb)[4], char* smem, f32x16 (&acc)[2][4]) {
;     ...
;   const int nk = K / 64;
;   if (!pre) { G_LOAD(0); G_STORE(0); G_LOAD(1); }
;   for (int kt = 0; kt < nk; ++kt) {
;     __syncthreads();
;     G_COMPUTE(kt & 1, kt);
;   }
	s_waitcnt vmcnt(7)
	ds_write_b128 v148, v[160:163]
	s_waitcnt vmcnt(6)
	ds_write_b128 v148, v[164:167] offset:36864
	ds_read_b128 v[160:163], v150
	ds_read_b128 v[164:167], v150 offset:4608
	v_mfma_f32_32x32x16_bf16 v[32:47], v[168:171], v[208:211], v[32:47]
	v_mfma_f32_32x32x16_bf16 v[48:63], v[172:175], v[208:211], v[48:63]
	ds_read_b128 v[208:211], v149
	v_mfma_f32_32x32x16_bf16 v[0:15], v[168:171], v[212:215], v[0:15]
	v_mfma_f32_32x32x16_bf16 v[16:31], v[172:175], v[212:215], v[16:31]
	ds_read_b128 v[212:215], v149 offset:4608
	s_setprio 0
	global_load_dwordx4 v[168:171], v[136:137], off offset:3712
	global_load_dwordx4 v[172:175], v[138:139], off offset:3712
	s_setprio 1
	s_waitcnt lgkmcnt(1)
	v_mfma_f32_32x32x16_bf16 v[96:111], v[160:163], v[208:211], v[96:111]
	v_mfma_f32_32x32x16_bf16 v[112:127], v[164:167], v[208:211], v[112:127]
	s_waitcnt lgkmcnt(0)
	v_mfma_f32_32x32x16_bf16 v[64:79], v[160:163], v[212:215], v[64:79]
	v_mfma_f32_32x32x16_bf16 v[80:95], v[164:167], v[212:215], v[80:95]
	ds_read_b128 v[208:211], v149 offset:9216
	ds_read_b128 v[212:215], v149 offset:13824
	s_waitcnt vmcnt(7)
	ds_write_b128 v148, v[184:187] offset:9216
	s_waitcnt vmcnt(6)
	ds_write_b128 v148, v[188:191] offset:46080
	ds_read_b128 v[184:187], v150 offset:32
	ds_read_b128 v[188:191], v150 offset:4640
	s_waitcnt lgkmcnt(5)
	v_mfma_f32_32x32x16_bf16 v[32:47], v[160:163], v[208:211], v[32:47]
	v_mfma_f32_32x32x16_bf16 v[48:63], v[164:167], v[208:211], v[48:63]
	ds_read_b128 v[208:211], v149 offset:32
	s_waitcnt lgkmcnt(5)
	v_mfma_f32_32x32x16_bf16 v[0:15], v[160:163], v[212:215], v[0:15]
	v_mfma_f32_32x32x16_bf16 v[16:31], v[164:167], v[212:215], v[16:31]
	ds_read_b128 v[212:215], v149 offset:4640
	s_setprio 0
	global_load_dwordx4 v[160:163], v[140:141], off offset:3712
	global_load_dwordx4 v[164:167], v[142:143], off offset:3712
	s_setprio 1
	s_waitcnt lgkmcnt(1)
	v_mfma_f32_32x32x16_bf16 v[96:111], v[184:187], v[208:211], v[96:111]
	v_mfma_f32_32x32x16_bf16 v[112:127], v[188:191], v[208:211], v[112:127]
	s_waitcnt lgkmcnt(0)
	v_mfma_f32_32x32x16_bf16 v[64:79], v[184:187], v[212:215], v[64:79]
	v_mfma_f32_32x32x16_bf16 v[80:95], v[188:191], v[212:215], v[80:95]
	ds_read_b128 v[208:211], v149 offset:9248
	ds_read_b128 v[212:215], v149 offset:13856
	s_waitcnt vmcnt(7)
	ds_write_b128 v148, v[194:197] offset:18432
	s_waitcnt vmcnt(6)
	ds_write_b128 v148, v[198:201] offset:55296
	ds_read_b128 v[194:197], v150 offset:64
	ds_read_b128 v[198:201], v150 offset:4672
	s_waitcnt lgkmcnt(5)
	v_mfma_f32_32x32x16_bf16 v[32:47], v[184:187], v[208:211], v[32:47]
	v_mfma_f32_32x32x16_bf16 v[48:63], v[188:191], v[208:211], v[48:63]
	ds_read_b128 v[208:211], v149 offset:64
	s_waitcnt lgkmcnt(5)
	v_mfma_f32_32x32x16_bf16 v[0:15], v[184:187], v[212:215], v[0:15]
	v_mfma_f32_32x32x16_bf16 v[16:31], v[188:191], v[212:215], v[16:31]
	ds_read_b128 v[212:215], v149 offset:4672
	s_setprio 0
	global_load_dwordx4 v[184:187], v[132:133], off offset:3712
	global_load_dwordx4 v[188:191], v[134:135], off offset:3712
	s_setprio 1
	s_waitcnt lgkmcnt(1)
	v_mfma_f32_32x32x16_bf16 v[96:111], v[194:197], v[208:211], v[96:111]
	v_mfma_f32_32x32x16_bf16 v[112:127], v[198:201], v[208:211], v[112:127]
	s_waitcnt lgkmcnt(0)
	v_mfma_f32_32x32x16_bf16 v[64:79], v[194:197], v[212:215], v[64:79]
	v_mfma_f32_32x32x16_bf16 v[80:95], v[198:201], v[212:215], v[80:95]
	ds_read_b128 v[208:211], v149 offset:9280
	ds_read_b128 v[212:215], v149 offset:13888
	s_waitcnt vmcnt(7)
	ds_write_b128 v148, v[176:179] offset:27648
	s_waitcnt vmcnt(6)
	ds_write_b128 v148, v[180:183] offset:64512
	ds_read_b128 v[176:179], v150 offset:96
	ds_read_b128 v[180:183], v150 offset:4704
	s_waitcnt lgkmcnt(5)
	v_mfma_f32_32x32x16_bf16 v[32:47], v[194:197], v[208:211], v[32:47]
	v_mfma_f32_32x32x16_bf16 v[48:63], v[198:201], v[208:211], v[48:63]
	ds_read_b128 v[208:211], v149 offset:96
	s_waitcnt lgkmcnt(5)
	v_mfma_f32_32x32x16_bf16 v[0:15], v[194:197], v[212:215], v[0:15]
	v_mfma_f32_32x32x16_bf16 v[16:31], v[198:201], v[212:215], v[16:31]
	ds_read_b128 v[212:215], v149 offset:4704
	s_setprio 0
	global_load_dwordx4 v[194:197], v[144:145], off offset:3712
	global_load_dwordx4 v[198:201], v[146:147], off offset:3712
	s_setprio 1
	s_waitcnt lgkmcnt(1)
	v_mfma_f32_32x32x16_bf16 v[96:111], v[176:179], v[208:211], v[96:111]
	v_mfma_f32_32x32x16_bf16 v[112:127], v[180:183], v[208:211], v[112:127]
	s_waitcnt lgkmcnt(0)
	v_mfma_f32_32x32x16_bf16 v[64:79], v[176:179], v[212:215], v[64:79]
	v_mfma_f32_32x32x16_bf16 v[80:95], v[180:183], v[212:215], v[80:95]
	ds_read_b128 v[208:211], v149 offset:9312
	ds_read_b128 v[212:215], v149 offset:13920
	s_waitcnt lgkmcnt(0)
	s_barrier
; template <bool trans>
; DI void gemm_core(const GTile& tl, const GTile& nx, bool has_next  , bool chain  , bool pre, u32x4 (&ra)[4], u32x4 (&rb)[4], char* smem, f32x16 (&acc)[2][4]) {
;     ...
;   const int nk = K / 64;
;   if (!pre) { G_LOAD(0); G_STORE(0); G_LOAD(1); }
;   for (int kt = 0; kt < nk; ++kt) {
;     __syncthreads();
;     G_COMPUTE(kt & 1, kt);
;   }
	s_waitcnt vmcnt(7)
	ds_write_b128 v192, v[168:171]
	s_waitcnt vmcnt(6)
	ds_write_b128 v159, v[172:175]
	ds_read_b128 v[168:171], v152 offset:36864
	ds_read_b128 v[172:175], v152 offset:41472
	v_mfma_f32_32x32x16_bf16 v[32:47], v[176:179], v[208:211], v[32:47]
	v_mfma_f32_32x32x16_bf16 v[48:63], v[180:183], v[208:211], v[48:63]
	ds_read_b128 v[208:211], v151
	v_mfma_f32_32x32x16_bf16 v[0:15], v[176:179], v[212:215], v[0:15]
	v_mfma_f32_32x32x16_bf16 v[16:31], v[180:183], v[212:215], v[16:31]
	ds_read_b128 v[212:215], v151 offset:4608
	s_setprio 0
	global_load_dwordx4 v[176:179], v[136:137], off offset:3840
	global_load_dwordx4 v[180:183], v[138:139], off offset:3840
	s_setprio 1
	s_waitcnt lgkmcnt(1)
	v_mfma_f32_32x32x16_bf16 v[96:111], v[168:171], v[208:211], v[96:111]
	v_mfma_f32_32x32x16_bf16 v[112:127], v[172:175], v[208:211], v[112:127]
	s_waitcnt lgkmcnt(0)
	v_mfma_f32_32x32x16_bf16 v[64:79], v[168:171], v[212:215], v[64:79]
	v_mfma_f32_32x32x16_bf16 v[80:95], v[172:175], v[212:215], v[80:95]
	ds_read_b128 v[208:211], v151 offset:9216
	ds_read_b128 v[212:215], v151 offset:13824
	s_waitcnt lgkmcnt(1)
	v_mfma_f32_32x32x16_bf16 v[32:47], v[168:171], v[208:211], v[32:47]
	v_mfma_f32_32x32x16_bf16 v[48:63], v[172:175], v[208:211], v[48:63]
	s_waitcnt lgkmcnt(0)
	v_mfma_f32_32x32x16_bf16 v[0:15], v[168:171], v[212:215], v[0:15]
	v_mfma_f32_32x32x16_bf16 v[16:31], v[172:175], v[212:215], v[16:31]
	s_setprio 0
	global_load_dwordx4 v[208:211], v[140:141], off offset:3840
	global_load_dwordx4 v[212:215], v[142:143], off offset:3840
	s_waitcnt vmcnt(9)
	ds_write_b128 v158, v[160:163]
	s_waitcnt vmcnt(8)
	ds_write_b128 v157, v[164:167]
	ds_read_b128 v[160:163], v152 offset:36896
	ds_read_b128 v[164:167], v152 offset:41504
	ds_read_b128 v[168:171], v151 offset:32
	ds_read_b128 v[172:175], v151 offset:4640
	s_setprio 1
	s_waitcnt lgkmcnt(1)
	v_mfma_f32_32x32x16_bf16 v[96:111], v[160:163], v[168:171], v[96:111]
	v_mfma_f32_32x32x16_bf16 v[112:127], v[164:167], v[168:171], v[112:127]
	s_waitcnt lgkmcnt(0)
	v_mfma_f32_32x32x16_bf16 v[64:79], v[160:163], v[172:175], v[64:79]
	v_mfma_f32_32x32x16_bf16 v[80:95], v[164:167], v[172:175], v[80:95]
	ds_read_b128 v[168:171], v151 offset:9248
	ds_read_b128 v[172:175], v151 offset:13856
	s_waitcnt lgkmcnt(1)
	v_mfma_f32_32x32x16_bf16 v[32:47], v[160:163], v[168:171], v[32:47]
	v_mfma_f32_32x32x16_bf16 v[48:63], v[164:167], v[168:171], v[48:63]
	s_waitcnt lgkmcnt(0)
	v_mfma_f32_32x32x16_bf16 v[0:15], v[160:163], v[172:175], v[0:15]
	v_mfma_f32_32x32x16_bf16 v[16:31], v[164:167], v[172:175], v[16:31]
	s_setprio 0
	global_load_dwordx4 v[216:219], v[132:133], off offset:3840
	global_load_dwordx4 v[220:223], v[134:135], off offset:3840
	s_waitcnt vmcnt(9)
	ds_write_b128 v154, v[184:187]
	s_waitcnt vmcnt(8)
	ds_write_b128 v153, v[188:191]
	ds_read_b128 v[160:163], v152 offset:36928
	ds_read_b128 v[164:167], v152 offset:41536
	ds_read_b128 v[168:171], v151 offset:64
	ds_read_b128 v[172:175], v151 offset:4672
	s_setprio 1
	s_waitcnt lgkmcnt(1)
	v_mfma_f32_32x32x16_bf16 v[96:111], v[160:163], v[168:171], v[96:111]
	v_mfma_f32_32x32x16_bf16 v[112:127], v[164:167], v[168:171], v[112:127]
	s_waitcnt lgkmcnt(0)
	v_mfma_f32_32x32x16_bf16 v[64:79], v[160:163], v[172:175], v[64:79]
	v_mfma_f32_32x32x16_bf16 v[80:95], v[164:167], v[172:175], v[80:95]
	ds_read_b128 v[168:171], v151 offset:9280
	ds_read_b128 v[172:175], v151 offset:13888
	s_waitcnt lgkmcnt(1)
	v_mfma_f32_32x32x16_bf16 v[32:47], v[160:163], v[168:171], v[32:47]
	v_mfma_f32_32x32x16_bf16 v[48:63], v[164:167], v[168:171], v[48:63]
	s_waitcnt lgkmcnt(0)
	v_mfma_f32_32x32x16_bf16 v[0:15], v[160:163], v[172:175], v[0:15]
	v_mfma_f32_32x32x16_bf16 v[16:31], v[164:167], v[172:175], v[16:31]
	s_setprio 0
	global_load_dwordx4 v[224:227], v[144:145], off offset:3840
	global_load_dwordx4 v[228:231], v[146:147], off offset:3840
	s_waitcnt vmcnt(9)
	ds_write_b128 v156, v[194:197]
	s_waitcnt vmcnt(8)
	ds_write_b128 v155, v[198:201]
	ds_read_b128 v[160:163], v152 offset:36960
	ds_read_b128 v[164:167], v152 offset:41568
	ds_read_b128 v[168:171], v151 offset:96
	ds_read_b128 v[172:175], v151 offset:4704
	s_setprio 1
	s_waitcnt lgkmcnt(1)
	v_mfma_f32_32x32x16_bf16 v[96:111], v[160:163], v[168:171], v[96:111]
	v_mfma_f32_32x32x16_bf16 v[112:127], v[164:167], v[168:171], v[112:127]
	s_waitcnt lgkmcnt(0)
	v_mfma_f32_32x32x16_bf16 v[64:79], v[160:163], v[172:175], v[64:79]
	v_mfma_f32_32x32x16_bf16 v[80:95], v[164:167], v[172:175], v[80:95]
	ds_read_b128 v[168:171], v151 offset:9312
	ds_read_b128 v[172:175], v151 offset:13920
	s_waitcnt lgkmcnt(1)
	v_mfma_f32_32x32x16_bf16 v[32:47], v[160:163], v[168:171], v[32:47]
	v_mfma_f32_32x32x16_bf16 v[48:63], v[164:167], v[168:171], v[48:63]
	s_waitcnt lgkmcnt(0)
	v_mfma_f32_32x32x16_bf16 v[0:15], v[160:163], v[172:175], v[0:15]
	v_mfma_f32_32x32x16_bf16 v[16:31], v[164:167], v[172:175], v[16:31]
	s_setprio 0
	global_load_dwordx4 v[160:163], v[136:137], off offset:3968
	global_load_dwordx4 v[164:167], v[138:139], off offset:3968
	s_barrier
; template <bool trans>
; DI void gemm_core(const GTile& tl, const GTile& nx, bool has_next  , bool chain  , bool pre, u32x4 (&ra)[4], u32x4 (&rb)[4], char* smem, f32x16 (&acc)[2][4]) {
;     ...
;   const int nk = K / 64;
;   if (!pre) { G_LOAD(0); G_STORE(0); G_LOAD(1); }
;   for (int kt = 0; kt < nk; ++kt) {
;     __syncthreads();
;     G_COMPUTE(kt & 1, kt);
;   }
;   if (!has_next) __syncthreads();
	s_waitcnt vmcnt(9)
	ds_write_b128 v148, v[176:179]
	s_waitcnt vmcnt(8)
	ds_write_b128 v148, v[180:183] offset:36864
	ds_read_b128 v[136:139], v150
	ds_read_b128 v[168:171], v150 offset:4608
	ds_read_b128 v[172:175], v149
	ds_read_b128 v[176:179], v149 offset:4608
	s_setprio 1
	s_waitcnt lgkmcnt(1)
	v_mfma_f32_32x32x16_bf16 v[96:111], v[136:139], v[172:175], v[96:111]
	v_mfma_f32_32x32x16_bf16 v[112:127], v[168:171], v[172:175], v[112:127]
	s_waitcnt lgkmcnt(0)
	v_mfma_f32_32x32x16_bf16 v[64:79], v[136:139], v[176:179], v[64:79]
	v_mfma_f32_32x32x16_bf16 v[80:95], v[168:171], v[176:179], v[80:95]
	ds_read_b128 v[172:175], v149 offset:9216
	ds_read_b128 v[176:179], v149 offset:13824
	s_waitcnt lgkmcnt(1)
	v_mfma_f32_32x32x16_bf16 v[32:47], v[136:139], v[172:175], v[32:47]
	v_mfma_f32_32x32x16_bf16 v[48:63], v[168:171], v[172:175], v[48:63]
	s_waitcnt lgkmcnt(0)
	v_mfma_f32_32x32x16_bf16 v[0:15], v[136:139], v[176:179], v[0:15]
	v_mfma_f32_32x32x16_bf16 v[16:31], v[168:171], v[176:179], v[16:31]
	s_setprio 0
	global_load_dwordx4 v[168:171], v[140:141], off offset:3968
	global_load_dwordx4 v[172:175], v[142:143], off offset:3968
	s_waitcnt vmcnt(9)
	ds_write_b128 v148, v[208:211] offset:9216
	s_waitcnt vmcnt(8)
	ds_write_b128 v148, v[212:215] offset:46080
	ds_read_b128 v[136:139], v150 offset:32
	ds_read_b128 v[140:143], v150 offset:4640
	ds_read_b128 v[176:179], v149 offset:32
	ds_read_b128 v[180:183], v149 offset:4640
	s_setprio 1
	s_waitcnt lgkmcnt(1)
	v_mfma_f32_32x32x16_bf16 v[96:111], v[136:139], v[176:179], v[96:111]
	v_mfma_f32_32x32x16_bf16 v[112:127], v[140:143], v[176:179], v[112:127]
	s_waitcnt lgkmcnt(0)
	v_mfma_f32_32x32x16_bf16 v[64:79], v[136:139], v[180:183], v[64:79]
	v_mfma_f32_32x32x16_bf16 v[80:95], v[140:143], v[180:183], v[80:95]
	ds_read_b128 v[176:179], v149 offset:9248
	ds_read_b128 v[180:183], v149 offset:13856
	s_waitcnt lgkmcnt(1)
	v_mfma_f32_32x32x16_bf16 v[32:47], v[136:139], v[176:179], v[32:47]
	v_mfma_f32_32x32x16_bf16 v[48:63], v[140:143], v[176:179], v[48:63]
	s_waitcnt lgkmcnt(0)
	v_mfma_f32_32x32x16_bf16 v[0:15], v[136:139], v[180:183], v[0:15]
	v_mfma_f32_32x32x16_bf16 v[16:31], v[140:143], v[180:183], v[16:31]
	s_setprio 0
	global_load_dwordx4 v[176:179], v[132:133], off offset:3968
	global_load_dwordx4 v[180:183], v[134:135], off offset:3968
	s_waitcnt vmcnt(9)
	ds_write_b128 v148, v[216:219] offset:18432
	s_waitcnt vmcnt(8)
	ds_write_b128 v148, v[220:223] offset:55296
	ds_read_b128 v[132:135], v150 offset:64
	ds_read_b128 v[136:139], v150 offset:4672
	ds_read_b128 v[140:143], v149 offset:64
	ds_read_b128 v[184:187], v149 offset:4672
	s_setprio 1
	s_waitcnt lgkmcnt(1)
	v_mfma_f32_32x32x16_bf16 v[96:111], v[132:135], v[140:143], v[96:111]
	v_mfma_f32_32x32x16_bf16 v[112:127], v[136:139], v[140:143], v[112:127]
	s_waitcnt lgkmcnt(0)
	v_mfma_f32_32x32x16_bf16 v[64:79], v[132:135], v[184:187], v[64:79]
	v_mfma_f32_32x32x16_bf16 v[80:95], v[136:139], v[184:187], v[80:95]
	ds_read_b128 v[140:143], v149 offset:9280
	ds_read_b128 v[184:187], v149 offset:13888
	s_waitcnt lgkmcnt(1)
	v_mfma_f32_32x32x16_bf16 v[32:47], v[132:135], v[140:143], v[32:47]
	v_mfma_f32_32x32x16_bf16 v[48:63], v[136:139], v[140:143], v[48:63]
	s_waitcnt lgkmcnt(0)
	v_mfma_f32_32x32x16_bf16 v[0:15], v[132:135], v[184:187], v[0:15]
	v_mfma_f32_32x32x16_bf16 v[16:31], v[136:139], v[184:187], v[16:31]
	s_setprio 0
	global_load_dwordx4 v[184:187], v[144:145], off offset:3968
	global_load_dwordx4 v[188:191], v[146:147], off offset:3968
	s_waitcnt vmcnt(9)
	ds_write_b128 v148, v[224:227] offset:27648
	s_waitcnt vmcnt(8)
	ds_write_b128 v148, v[228:231] offset:64512
	ds_read_b128 v[132:135], v150 offset:96
	ds_read_b128 v[136:139], v150 offset:4704
	ds_read_b128 v[140:143], v149 offset:96
	ds_read_b128 v[144:147], v149 offset:4704
	s_setprio 1
	s_waitcnt lgkmcnt(1)
	v_mfma_f32_32x32x16_bf16 v[96:111], v[132:135], v[140:143], v[96:111]
	v_mfma_f32_32x32x16_bf16 v[112:127], v[136:139], v[140:143], v[112:127]
	s_waitcnt lgkmcnt(0)
	v_mfma_f32_32x32x16_bf16 v[64:79], v[132:135], v[144:147], v[64:79]
	v_mfma_f32_32x32x16_bf16 v[80:95], v[136:139], v[144:147], v[80:95]
	ds_read_b128 v[140:143], v149 offset:9312
	ds_read_b128 v[144:147], v149 offset:13920
	s_waitcnt lgkmcnt(1)
	v_mfma_f32_32x32x16_bf16 v[32:47], v[132:135], v[140:143], v[32:47]
	v_mfma_f32_32x32x16_bf16 v[48:63], v[136:139], v[140:143], v[48:63]
	s_waitcnt lgkmcnt(0)
	v_mfma_f32_32x32x16_bf16 v[0:15], v[132:135], v[144:147], v[0:15]
	v_mfma_f32_32x32x16_bf16 v[16:31], v[136:139], v[144:147], v[16:31]
	s_setprio 0
	v_cndmask_b32_e64 v132, 0, 1, s[34:35]
	v_cmp_ne_u32_e64 s[6:7], 1, v132
	s_andn2_b64 vcc, exec, s[34:35]
	s_barrier
	s_waitcnt vmcnt(7)
	ds_write_b128 v192, v[160:163]
	s_waitcnt vmcnt(6)
	ds_write_b128 v159, v[164:167]
	s_cbranch_vccnz .LBB0_892
	global_load_dwordx4 v[160:163], v[130:131], off
	global_load_dwordx4 v[164:167], v[128:129], off
